# x-update row rebalance: waves that finish a sample row take 5 prompt rows, their three sibling waves 9 (was 8+sample / 8)
# baseline (speedup 1.0000x reference)
.LBB0_446:
	s_waitcnt lgkmcnt(0)
	v_cndmask_b32_e64 v0, 0, 1, s[24:25]
	v_cmp_ne_u32_e64 s[0:1], 1, v0
	s_andn2_b64 vcc, exec, s[24:25]
	s_nop 0
	v_writelane_b32 v235, s0, 52
	s_barrier
	s_nop 0
	v_writelane_b32 v235, s1, 53
	v_mbcnt_lo_u32_b32 v0, -1, 0
	v_mbcnt_hi_u32_b32 v0, -1, v0
	s_cbranch_vccnz .LBB0_465
	v_lshlrev_b32_e32 v2, 3, v0
	v_ashrrev_i32_e32 v3, 31, v2
	v_readlane_b32 s4, v235, 4
	v_lshlrev_b64 v[4:5], 1, v[2:3]
	v_lshlrev_b64 v[2:3], 2, v[2:3]
	v_readlane_b32 s5, v235, 5
	v_readlane_b32 s6, v235, 6
	v_readlane_b32 s7, v235, 7
	v_readlane_b32 s8, v235, 8
	v_readlane_b32 s9, v235, 9
	v_readlane_b32 s10, v235, 10
	v_readlane_b32 s11, v235, 11
	v_readlane_b32 s12, v235, 12
	v_readlane_b32 s13, v235, 13
	v_readlane_b32 s14, v235, 14
	v_readlane_b32 s15, v235, 15
	v_readlane_b32 s16, v235, 16
	v_readlane_b32 s17, v235, 17
	v_readlane_b32 s18, v235, 18
	v_readlane_b32 s19, v235, 19
	v_lshl_add_u64 v[60:61], s[86:87], 0, v[4:5]
	v_lshl_add_u64 v[62:63], s[90:91], 0, v[2:3]
	v_lshl_add_u64 v[64:65], s[54:55], 0, v[4:5]
	v_lshl_add_u64 v[66:67], s[14:15], 0, v[2:3]
	s_mov_b32 s1, 0
	v_cmp_eq_u32_e64 s[4:5], 0, v0
	s_mov_b64 s[6:7], 0x200000
	s_mov_b64 s[8:9], 0x200800
	s_mov_b64 s[10:11], 0x400000
	s_mov_b64 s[12:13], 0x400800
	s_mov_b64 s[14:15], 0x600000
	s_mov_b64 s[16:17], 0x600800
	s_mov_b64 s[18:19], 0x800000
	s_mov_b32 s48, 0x800000
	s_mov_b64 s[20:21], 0x800800
	s_mov_b64 s[22:23], 0xa00000
	s_mov_b64 s[24:25], 0xa00800
	s_mov_b64 s[26:27], 0xc00000
	s_mov_b64 s[28:29], 0xc00800
	s_mov_b64 s[34:35], 0xe00000
	s_mov_b64 s[36:37], 0xe00800
	v_mov_b32_e32 v104, 0
	v_mov_b32_e32 v105, 0x358637bd
	s_mov_b32 s40, s80
	v_mbcnt_lo_u32_b32 v176, -1, 0
	v_mbcnt_hi_u32_b32 v176, -1, v176
	v_readlane_b32 s98, v235, 49
	v_readlane_b32 s99, v235, 20
	v_readlane_b32 s100, v235, 14
	v_readlane_b32 s101, v235, 15
	s_nop 3
	s_lshr_b32 vcc_lo, s98, 3
	s_and_b32 vcc_hi, vcc_lo, 7
	s_lshr_b32 vcc_lo, vcc_lo, 3
	s_lshl_b32 vcc_lo, vcc_lo, 3
	s_add_i32 vcc_lo, vcc_lo, s99
	s_lshl_b32 s98, vcc_hi, 8
	s_add_i32 s98, s98, vcc_lo
	s_mov_b32 s99, s98
	v_mov_b32_e32 v183, s99
	v_lshlrev_b32_e32 v177, 4, v176
	s_lshl_b32 s99, s99, 11
	v_add_u32_e32 v177, s99, v177
	v_add_u32_e32 v178, 0x1800000, v177
	v_add_u32_e32 v179, 0x9e00000, v177
	v_lshlrev_b32_e32 v180, 5, v176
	global_load_dwordx4 v[128:131], v180, s[100:101]
	global_load_dwordx4 v[132:135], v180, s[100:101] offset:16
	global_load_dwordx4 v[136:139], v180, s[100:101] offset:2048
	global_load_dwordx4 v[140:143], v180, s[100:101] offset:2064
	v_mov_b32_e32 v182, 0x358637bd
	s_and_b32 vcc_lo, s98, 3
	s_cmp_eq_u32 vcc_lo, 0
	s_cbranch_scc1 .Lmyxupd_heavy_0
	global_load_dwordx4 v[0:3], v178, s[78:79]
	global_load_dwordx4 v[4:7], v178, s[78:79] offset:1024
	global_load_dwordx4 v[8:11], v179, s[78:79]
	global_load_dwordx4 v[12:15], v179, s[78:79] offset:1024
	v_add_u32_e32 v178, 0x400000, v178
	v_add_u32_e32 v179, 0x400000, v179
	global_load_dwordx4 v[16:19], v178, s[78:79]
	global_load_dwordx4 v[20:23], v178, s[78:79] offset:1024
	global_load_dwordx4 v[24:27], v179, s[78:79]
	global_load_dwordx4 v[28:31], v179, s[78:79] offset:1024
	v_add_u32_e32 v178, 0x400000, v178
	v_add_u32_e32 v179, 0x400000, v179
	global_load_dwordx4 v[32:35], v178, s[78:79]
	global_load_dwordx4 v[36:39], v178, s[78:79] offset:1024
	global_load_dwordx4 v[40:43], v179, s[78:79]
	global_load_dwordx4 v[44:47], v179, s[78:79] offset:1024
	v_add_u32_e32 v178, 0x400000, v178
	v_add_u32_e32 v179, 0x400000, v179
	global_load_dwordx4 v[48:51], v178, s[78:79]
	global_load_dwordx4 v[52:55], v178, s[78:79] offset:1024
	global_load_dwordx4 v[56:59], v179, s[78:79]
	global_load_dwordx4 v[60:63], v179, s[78:79] offset:1024
	v_add_u32_e32 v178, 0x400000, v178
	v_add_u32_e32 v179, 0x400000, v179
	global_load_dwordx4 v[64:67], v178, s[78:79]
	global_load_dwordx4 v[68:71], v178, s[78:79] offset:1024
	global_load_dwordx4 v[72:75], v179, s[78:79]
	global_load_dwordx4 v[76:79], v179, s[78:79] offset:1024
	v_add_u32_e32 v178, 0x400000, v178
	v_add_u32_e32 v179, 0x400000, v179
	global_load_dwordx4 v[80:83], v178, s[78:79]
	global_load_dwordx4 v[84:87], v178, s[78:79] offset:1024
	global_load_dwordx4 v[88:91], v179, s[78:79]
	global_load_dwordx4 v[92:95], v179, s[78:79] offset:1024
	v_add_u32_e32 v178, 0x400000, v178
	v_add_u32_e32 v179, 0x400000, v179
	global_load_dwordx4 v[96:99], v178, s[78:79]
	global_load_dwordx4 v[100:103], v178, s[78:79] offset:1024
	global_load_dwordx4 v[104:107], v179, s[78:79]
	global_load_dwordx4 v[108:111], v179, s[78:79] offset:1024
	v_add_u32_e32 v178, 0x400000, v178
	v_add_u32_e32 v179, 0x400000, v179
	global_load_dwordx4 v[112:115], v178, s[78:79]
	global_load_dwordx4 v[116:119], v178, s[78:79] offset:1024
	global_load_dwordx4 v[120:123], v179, s[78:79]
	global_load_dwordx4 v[124:127], v179, s[78:79] offset:1024
	v_lshlrev_b32_e32 v237, 2, v183
	v_add_u32_e32 v237, 0x10000, v237
	v_mov_b32_e32 v179, s98
	s_waitcnt vmcnt(28)
	v_lshlrev_b32_e32 v144, 16, v0
	v_and_b32_e32 v145, 0xffff0000, v0
	v_lshlrev_b32_e32 v146, 16, v1
	v_and_b32_e32 v147, 0xffff0000, v1
	v_lshlrev_b32_e32 v148, 16, v2
	v_and_b32_e32 v149, 0xffff0000, v2
	v_lshlrev_b32_e32 v150, 16, v3
	v_and_b32_e32 v151, 0xffff0000, v3
	v_lshlrev_b32_e32 v152, 16, v4
	v_and_b32_e32 v153, 0xffff0000, v4
	v_lshlrev_b32_e32 v154, 16, v5
	v_and_b32_e32 v155, 0xffff0000, v5
	v_lshlrev_b32_e32 v156, 16, v6
	v_and_b32_e32 v157, 0xffff0000, v6
	v_lshlrev_b32_e32 v158, 16, v7
	v_and_b32_e32 v159, 0xffff0000, v7
	v_lshlrev_b32_e32 v160, 16, v8
	v_and_b32_e32 v161, 0xffff0000, v8
	v_lshlrev_b32_e32 v162, 16, v9
	v_and_b32_e32 v163, 0xffff0000, v9
	v_lshlrev_b32_e32 v164, 16, v10
	v_and_b32_e32 v165, 0xffff0000, v10
	v_lshlrev_b32_e32 v166, 16, v11
	v_and_b32_e32 v167, 0xffff0000, v11
	v_lshlrev_b32_e32 v168, 16, v12
	v_and_b32_e32 v169, 0xffff0000, v12
	v_lshlrev_b32_e32 v170, 16, v13
	v_and_b32_e32 v171, 0xffff0000, v13
	v_lshlrev_b32_e32 v172, 16, v14
	v_and_b32_e32 v173, 0xffff0000, v14
	v_lshlrev_b32_e32 v174, 16, v15
	v_and_b32_e32 v175, 0xffff0000, v15
	v_pk_mul_f32 v[252:253], v[160:161], v[160:161]
	v_pk_mul_f32 v[254:255], v[162:163], v[162:163]
	v_pk_fma_f32 v[252:253], v[164:165], v[164:165], v[252:253]
	v_pk_fma_f32 v[254:255], v[166:167], v[166:167], v[254:255]
	v_pk_fma_f32 v[252:253], v[168:169], v[168:169], v[252:253]
	v_pk_fma_f32 v[254:255], v[170:171], v[170:171], v[254:255]
	v_pk_fma_f32 v[252:253], v[172:173], v[172:173], v[252:253]
	v_pk_fma_f32 v[254:255], v[174:175], v[174:175], v[254:255]
	v_pk_add_f32 v[252:253], v[252:253], v[254:255]
	s_nop 0
	v_add_f32_e32 v183, v252, v253
	s_nop 1
	v_add_f32_dpp v183, v183, v183 quad_perm:[1,0,3,2] row_mask:0xf bank_mask:0xf bound_ctrl:1
	s_nop 1
	v_add_f32_dpp v183, v183, v183 quad_perm:[2,3,0,1] row_mask:0xf bank_mask:0xf bound_ctrl:1
	s_nop 1
	v_add_f32_dpp v183, v183, v183 row_half_mirror row_mask:0xf bank_mask:0xf bound_ctrl:1
	s_nop 1
	v_add_f32_dpp v183, v183, v183 row_mirror row_mask:0xf bank_mask:0xf bound_ctrl:1
	s_nop 1
	v_readlane_b32 s98, v183, 0
	v_readlane_b32 s99, v183, 16
	v_readlane_b32 s100, v183, 32
	v_readlane_b32 s101, v183, 48
	s_nop 1
	v_mov_b32_e32 v183, s98
	v_add_f32_e32 v183, s99, v183
	v_add_f32_e32 v183, s100, v183
	v_add_f32_e32 v183, s101, v183
	v_fmamk_f32 v183, v183, 0x3a800000, v182
	v_cmp_gt_f32_e32 vcc, 0x800000, v183
	v_mul_f32_e32 v181, 0x4b800000, v183
	s_nop 1
	v_cndmask_b32_e32 v183, v183, v181, vcc
	v_rsq_f32_e32 v183, v183
	s_nop 0
	v_mul_f32_e32 v181, 0x45800000, v183
	v_cndmask_b32_e32 v184, v183, v181, vcc
	v_mov_b32_e32 v185, v184
	v_pk_mul_f32 v[160:161], v[160:161], v[184:185]
	v_pk_mul_f32 v[162:163], v[162:163], v[184:185]
	v_pk_mul_f32 v[164:165], v[164:165], v[184:185]
	v_pk_mul_f32 v[166:167], v[166:167], v[184:185]
	v_pk_mul_f32 v[168:169], v[168:169], v[184:185]
	v_pk_mul_f32 v[170:171], v[170:171], v[184:185]
	v_pk_mul_f32 v[172:173], v[172:173], v[184:185]
	v_pk_mul_f32 v[174:175], v[174:175], v[184:185]
	v_pk_fma_f32 v[144:145], v[160:161], v[128:129], v[144:145]
	v_pk_fma_f32 v[146:147], v[162:163], v[130:131], v[146:147]
	v_pk_fma_f32 v[148:149], v[164:165], v[132:133], v[148:149]
	v_pk_fma_f32 v[150:151], v[166:167], v[134:135], v[150:151]
	v_pk_fma_f32 v[152:153], v[168:169], v[136:137], v[152:153]
	v_pk_fma_f32 v[154:155], v[170:171], v[138:139], v[154:155]
	v_pk_fma_f32 v[156:157], v[172:173], v[140:141], v[156:157]
	v_pk_fma_f32 v[158:159], v[174:175], v[142:143], v[158:159]
	v_pk_mul_f32 v[252:253], v[144:145], v[144:145]
	v_pk_mul_f32 v[254:255], v[146:147], v[146:147]
	v_pk_fma_f32 v[252:253], v[148:149], v[148:149], v[252:253]
	v_pk_fma_f32 v[254:255], v[150:151], v[150:151], v[254:255]
	v_pk_fma_f32 v[252:253], v[152:153], v[152:153], v[252:253]
	v_pk_fma_f32 v[254:255], v[154:155], v[154:155], v[254:255]
	v_pk_fma_f32 v[252:253], v[156:157], v[156:157], v[252:253]
	v_pk_fma_f32 v[254:255], v[158:159], v[158:159], v[254:255]
	v_pk_add_f32 v[252:253], v[252:253], v[254:255]
	s_nop 0
	v_add_f32_e32 v183, v252, v253
	s_nop 1
	v_add_f32_dpp v183, v183, v183 quad_perm:[1,0,3,2] row_mask:0xf bank_mask:0xf bound_ctrl:1
	s_nop 1
	v_add_f32_dpp v183, v183, v183 quad_perm:[2,3,0,1] row_mask:0xf bank_mask:0xf bound_ctrl:1
	s_nop 1
	v_add_f32_dpp v183, v183, v183 row_half_mirror row_mask:0xf bank_mask:0xf bound_ctrl:1
	s_nop 1
	v_add_f32_dpp v183, v183, v183 row_mirror row_mask:0xf bank_mask:0xf bound_ctrl:1
	s_nop 1
	v_readlane_b32 s98, v183, 0
	v_readlane_b32 s99, v183, 16
	v_readlane_b32 s100, v183, 32
	v_readlane_b32 s101, v183, 48
	s_nop 1
	v_mov_b32_e32 v183, s98
	v_add_f32_e32 v183, s99, v183
	v_add_f32_e32 v183, s100, v183
	v_add_f32_e32 v183, s101, v183
	v_fmamk_f32 v183, v183, 0x3a800000, v182
	v_cmp_gt_f32_e32 vcc, 0x800000, v183
	v_mul_f32_e32 v181, 0x4b800000, v183
	s_nop 1
	v_cndmask_b32_e32 v183, v183, v181, vcc
	v_rsq_f32_e32 v183, v183
	s_nop 0
	v_mul_f32_e32 v181, 0x45800000, v183
	v_cndmask_b32_e32 v184, v183, v181, vcc
	v_mov_b32_e32 v185, v184
	v_cvt_pk_bf16_f32 v0, v144, v145
	v_cvt_pk_bf16_f32 v1, v146, v147
	v_cvt_pk_bf16_f32 v2, v148, v149
	v_cvt_pk_bf16_f32 v3, v150, v151
	v_cvt_pk_bf16_f32 v4, v152, v153
	v_cvt_pk_bf16_f32 v5, v154, v155
	v_cvt_pk_bf16_f32 v6, v156, v157
	v_cvt_pk_bf16_f32 v7, v158, v159
	v_add_u32_e32 v181, 0x1800000, v177
	global_store_dwordx4 v181, v[0:3], s[78:79]
	global_store_dwordx4 v181, v[4:7], s[78:79] offset:1024
	v_add_u32_e32 v236, 0x0, v237
	s_mov_b64 exec, 1
	global_store_dword v236, v184, s[78:79]
	s_mov_b64 exec, -1
	s_waitcnt vmcnt(24)
	v_lshlrev_b32_e32 v144, 16, v16
	v_and_b32_e32 v145, 0xffff0000, v16
	v_lshlrev_b32_e32 v146, 16, v17
	v_and_b32_e32 v147, 0xffff0000, v17
	v_lshlrev_b32_e32 v148, 16, v18
	v_and_b32_e32 v149, 0xffff0000, v18
	v_lshlrev_b32_e32 v150, 16, v19
	v_and_b32_e32 v151, 0xffff0000, v19
	v_lshlrev_b32_e32 v152, 16, v20
	v_and_b32_e32 v153, 0xffff0000, v20
	v_lshlrev_b32_e32 v154, 16, v21
	v_and_b32_e32 v155, 0xffff0000, v21
	v_lshlrev_b32_e32 v156, 16, v22
	v_and_b32_e32 v157, 0xffff0000, v22
	v_lshlrev_b32_e32 v158, 16, v23
	v_and_b32_e32 v159, 0xffff0000, v23
	v_lshlrev_b32_e32 v160, 16, v24
	v_and_b32_e32 v161, 0xffff0000, v24
	v_lshlrev_b32_e32 v162, 16, v25
	v_and_b32_e32 v163, 0xffff0000, v25
	v_lshlrev_b32_e32 v164, 16, v26
	v_and_b32_e32 v165, 0xffff0000, v26
	v_lshlrev_b32_e32 v166, 16, v27
	v_and_b32_e32 v167, 0xffff0000, v27
	v_lshlrev_b32_e32 v168, 16, v28
	v_and_b32_e32 v169, 0xffff0000, v28
	v_lshlrev_b32_e32 v170, 16, v29
	v_and_b32_e32 v171, 0xffff0000, v29
	v_lshlrev_b32_e32 v172, 16, v30
	v_and_b32_e32 v173, 0xffff0000, v30
	v_lshlrev_b32_e32 v174, 16, v31
	v_and_b32_e32 v175, 0xffff0000, v31
	v_pk_mul_f32 v[252:253], v[160:161], v[160:161]
	v_pk_mul_f32 v[254:255], v[162:163], v[162:163]
	v_pk_fma_f32 v[252:253], v[164:165], v[164:165], v[252:253]
	v_pk_fma_f32 v[254:255], v[166:167], v[166:167], v[254:255]
	v_pk_fma_f32 v[252:253], v[168:169], v[168:169], v[252:253]
	v_pk_fma_f32 v[254:255], v[170:171], v[170:171], v[254:255]
	v_pk_fma_f32 v[252:253], v[172:173], v[172:173], v[252:253]
	v_pk_fma_f32 v[254:255], v[174:175], v[174:175], v[254:255]
	v_pk_add_f32 v[252:253], v[252:253], v[254:255]
	s_nop 0
	v_add_f32_e32 v183, v252, v253
	s_nop 1
	v_add_f32_dpp v183, v183, v183 quad_perm:[1,0,3,2] row_mask:0xf bank_mask:0xf bound_ctrl:1
	s_nop 1
	v_add_f32_dpp v183, v183, v183 quad_perm:[2,3,0,1] row_mask:0xf bank_mask:0xf bound_ctrl:1
	s_nop 1
	v_add_f32_dpp v183, v183, v183 row_half_mirror row_mask:0xf bank_mask:0xf bound_ctrl:1
	s_nop 1
	v_add_f32_dpp v183, v183, v183 row_mirror row_mask:0xf bank_mask:0xf bound_ctrl:1
	s_nop 1
	v_readlane_b32 s98, v183, 0
	v_readlane_b32 s99, v183, 16
	v_readlane_b32 s100, v183, 32
	v_readlane_b32 s101, v183, 48
	s_nop 1
	v_mov_b32_e32 v183, s98
	v_add_f32_e32 v183, s99, v183
	v_add_f32_e32 v183, s100, v183
	v_add_f32_e32 v183, s101, v183
	v_fmamk_f32 v183, v183, 0x3a800000, v182
	v_cmp_gt_f32_e32 vcc, 0x800000, v183
	v_mul_f32_e32 v181, 0x4b800000, v183
	s_nop 1
	v_cndmask_b32_e32 v183, v183, v181, vcc
	v_rsq_f32_e32 v183, v183
	s_nop 0
	v_mul_f32_e32 v181, 0x45800000, v183
	v_cndmask_b32_e32 v184, v183, v181, vcc
	v_mov_b32_e32 v185, v184
	v_pk_mul_f32 v[160:161], v[160:161], v[184:185]
	v_pk_mul_f32 v[162:163], v[162:163], v[184:185]
	v_pk_mul_f32 v[164:165], v[164:165], v[184:185]
	v_pk_mul_f32 v[166:167], v[166:167], v[184:185]
	v_pk_mul_f32 v[168:169], v[168:169], v[184:185]
	v_pk_mul_f32 v[170:171], v[170:171], v[184:185]
	v_pk_mul_f32 v[172:173], v[172:173], v[184:185]
	v_pk_mul_f32 v[174:175], v[174:175], v[184:185]
	v_pk_fma_f32 v[144:145], v[160:161], v[128:129], v[144:145]
	v_pk_fma_f32 v[146:147], v[162:163], v[130:131], v[146:147]
	v_pk_fma_f32 v[148:149], v[164:165], v[132:133], v[148:149]
	v_pk_fma_f32 v[150:151], v[166:167], v[134:135], v[150:151]
	v_pk_fma_f32 v[152:153], v[168:169], v[136:137], v[152:153]
	v_pk_fma_f32 v[154:155], v[170:171], v[138:139], v[154:155]
	v_pk_fma_f32 v[156:157], v[172:173], v[140:141], v[156:157]
	v_pk_fma_f32 v[158:159], v[174:175], v[142:143], v[158:159]
	v_pk_mul_f32 v[252:253], v[144:145], v[144:145]
	v_pk_mul_f32 v[254:255], v[146:147], v[146:147]
	v_pk_fma_f32 v[252:253], v[148:149], v[148:149], v[252:253]
	v_pk_fma_f32 v[254:255], v[150:151], v[150:151], v[254:255]
	v_pk_fma_f32 v[252:253], v[152:153], v[152:153], v[252:253]
	v_pk_fma_f32 v[254:255], v[154:155], v[154:155], v[254:255]
	v_pk_fma_f32 v[252:253], v[156:157], v[156:157], v[252:253]
	v_pk_fma_f32 v[254:255], v[158:159], v[158:159], v[254:255]
	v_pk_add_f32 v[252:253], v[252:253], v[254:255]
	s_nop 0
	v_add_f32_e32 v183, v252, v253
	s_nop 1
	v_add_f32_dpp v183, v183, v183 quad_perm:[1,0,3,2] row_mask:0xf bank_mask:0xf bound_ctrl:1
	s_nop 1
	v_add_f32_dpp v183, v183, v183 quad_perm:[2,3,0,1] row_mask:0xf bank_mask:0xf bound_ctrl:1
	s_nop 1
	v_add_f32_dpp v183, v183, v183 row_half_mirror row_mask:0xf bank_mask:0xf bound_ctrl:1
	s_nop 1
	v_add_f32_dpp v183, v183, v183 row_mirror row_mask:0xf bank_mask:0xf bound_ctrl:1
	s_nop 1
	v_readlane_b32 s98, v183, 0
	v_readlane_b32 s99, v183, 16
	v_readlane_b32 s100, v183, 32
	v_readlane_b32 s101, v183, 48
	s_nop 1
	v_mov_b32_e32 v183, s98
	v_add_f32_e32 v183, s99, v183
	v_add_f32_e32 v183, s100, v183
	v_add_f32_e32 v183, s101, v183
	v_fmamk_f32 v183, v183, 0x3a800000, v182
	v_cmp_gt_f32_e32 vcc, 0x800000, v183
	v_mul_f32_e32 v181, 0x4b800000, v183
	s_nop 1
	v_cndmask_b32_e32 v183, v183, v181, vcc
	v_rsq_f32_e32 v183, v183
	s_nop 0
	v_mul_f32_e32 v181, 0x45800000, v183
	v_cndmask_b32_e32 v184, v183, v181, vcc
	v_mov_b32_e32 v185, v184
	v_cvt_pk_bf16_f32 v16, v144, v145
	v_cvt_pk_bf16_f32 v17, v146, v147
	v_cvt_pk_bf16_f32 v18, v148, v149
	v_cvt_pk_bf16_f32 v19, v150, v151
	v_cvt_pk_bf16_f32 v20, v152, v153
	v_cvt_pk_bf16_f32 v21, v154, v155
	v_cvt_pk_bf16_f32 v22, v156, v157
	v_cvt_pk_bf16_f32 v23, v158, v159
	v_add_u32_e32 v181, 0x1c00000, v177
	global_store_dwordx4 v181, v[16:19], s[78:79]
	global_store_dwordx4 v181, v[20:23], s[78:79] offset:1024
	v_add_u32_e32 v236, 0x2000, v237
	s_mov_b64 exec, 1
	global_store_dword v236, v184, s[78:79]
	s_mov_b64 exec, -1
	s_waitcnt vmcnt(20)
	v_lshlrev_b32_e32 v144, 16, v32
	v_and_b32_e32 v145, 0xffff0000, v32
	v_lshlrev_b32_e32 v146, 16, v33
	v_and_b32_e32 v147, 0xffff0000, v33
	v_lshlrev_b32_e32 v148, 16, v34
	v_and_b32_e32 v149, 0xffff0000, v34
	v_lshlrev_b32_e32 v150, 16, v35
	v_and_b32_e32 v151, 0xffff0000, v35
	v_lshlrev_b32_e32 v152, 16, v36
	v_and_b32_e32 v153, 0xffff0000, v36
	v_lshlrev_b32_e32 v154, 16, v37
	v_and_b32_e32 v155, 0xffff0000, v37
	v_lshlrev_b32_e32 v156, 16, v38
	v_and_b32_e32 v157, 0xffff0000, v38
	v_lshlrev_b32_e32 v158, 16, v39
	v_and_b32_e32 v159, 0xffff0000, v39
	v_lshlrev_b32_e32 v160, 16, v40
	v_and_b32_e32 v161, 0xffff0000, v40
	v_lshlrev_b32_e32 v162, 16, v41
	v_and_b32_e32 v163, 0xffff0000, v41
	v_lshlrev_b32_e32 v164, 16, v42
	v_and_b32_e32 v165, 0xffff0000, v42
	v_lshlrev_b32_e32 v166, 16, v43
	v_and_b32_e32 v167, 0xffff0000, v43
	v_lshlrev_b32_e32 v168, 16, v44
	v_and_b32_e32 v169, 0xffff0000, v44
	v_lshlrev_b32_e32 v170, 16, v45
	v_and_b32_e32 v171, 0xffff0000, v45
	v_lshlrev_b32_e32 v172, 16, v46
	v_and_b32_e32 v173, 0xffff0000, v46
	v_lshlrev_b32_e32 v174, 16, v47
	v_and_b32_e32 v175, 0xffff0000, v47
	v_pk_mul_f32 v[252:253], v[160:161], v[160:161]
	v_pk_mul_f32 v[254:255], v[162:163], v[162:163]
	v_pk_fma_f32 v[252:253], v[164:165], v[164:165], v[252:253]
	v_pk_fma_f32 v[254:255], v[166:167], v[166:167], v[254:255]
	v_pk_fma_f32 v[252:253], v[168:169], v[168:169], v[252:253]
	v_pk_fma_f32 v[254:255], v[170:171], v[170:171], v[254:255]
	v_pk_fma_f32 v[252:253], v[172:173], v[172:173], v[252:253]
	v_pk_fma_f32 v[254:255], v[174:175], v[174:175], v[254:255]
	v_pk_add_f32 v[252:253], v[252:253], v[254:255]
	s_nop 0
	v_add_f32_e32 v183, v252, v253
	s_nop 1
	v_add_f32_dpp v183, v183, v183 quad_perm:[1,0,3,2] row_mask:0xf bank_mask:0xf bound_ctrl:1
	s_nop 1
	v_add_f32_dpp v183, v183, v183 quad_perm:[2,3,0,1] row_mask:0xf bank_mask:0xf bound_ctrl:1
	s_nop 1
	v_add_f32_dpp v183, v183, v183 row_half_mirror row_mask:0xf bank_mask:0xf bound_ctrl:1
	s_nop 1
	v_add_f32_dpp v183, v183, v183 row_mirror row_mask:0xf bank_mask:0xf bound_ctrl:1
	s_nop 1
	v_readlane_b32 s98, v183, 0
	v_readlane_b32 s99, v183, 16
	v_readlane_b32 s100, v183, 32
	v_readlane_b32 s101, v183, 48
	s_nop 1
	v_mov_b32_e32 v183, s98
	v_add_f32_e32 v183, s99, v183
	v_add_f32_e32 v183, s100, v183
	v_add_f32_e32 v183, s101, v183
	v_fmamk_f32 v183, v183, 0x3a800000, v182
	v_cmp_gt_f32_e32 vcc, 0x800000, v183
	v_mul_f32_e32 v181, 0x4b800000, v183
	s_nop 1
	v_cndmask_b32_e32 v183, v183, v181, vcc
	v_rsq_f32_e32 v183, v183
	s_nop 0
	v_mul_f32_e32 v181, 0x45800000, v183
	v_cndmask_b32_e32 v184, v183, v181, vcc
	v_mov_b32_e32 v185, v184
	v_pk_mul_f32 v[160:161], v[160:161], v[184:185]
	v_pk_mul_f32 v[162:163], v[162:163], v[184:185]
	v_pk_mul_f32 v[164:165], v[164:165], v[184:185]
	v_pk_mul_f32 v[166:167], v[166:167], v[184:185]
	v_pk_mul_f32 v[168:169], v[168:169], v[184:185]
	v_pk_mul_f32 v[170:171], v[170:171], v[184:185]
	v_pk_mul_f32 v[172:173], v[172:173], v[184:185]
	v_pk_mul_f32 v[174:175], v[174:175], v[184:185]
	v_pk_fma_f32 v[144:145], v[160:161], v[128:129], v[144:145]
	v_pk_fma_f32 v[146:147], v[162:163], v[130:131], v[146:147]
	v_pk_fma_f32 v[148:149], v[164:165], v[132:133], v[148:149]
	v_pk_fma_f32 v[150:151], v[166:167], v[134:135], v[150:151]
	v_pk_fma_f32 v[152:153], v[168:169], v[136:137], v[152:153]
	v_pk_fma_f32 v[154:155], v[170:171], v[138:139], v[154:155]
	v_pk_fma_f32 v[156:157], v[172:173], v[140:141], v[156:157]
	v_pk_fma_f32 v[158:159], v[174:175], v[142:143], v[158:159]
	v_pk_mul_f32 v[252:253], v[144:145], v[144:145]
	v_pk_mul_f32 v[254:255], v[146:147], v[146:147]
	v_pk_fma_f32 v[252:253], v[148:149], v[148:149], v[252:253]
	v_pk_fma_f32 v[254:255], v[150:151], v[150:151], v[254:255]
	v_pk_fma_f32 v[252:253], v[152:153], v[152:153], v[252:253]
	v_pk_fma_f32 v[254:255], v[154:155], v[154:155], v[254:255]
	v_pk_fma_f32 v[252:253], v[156:157], v[156:157], v[252:253]
	v_pk_fma_f32 v[254:255], v[158:159], v[158:159], v[254:255]
	v_pk_add_f32 v[252:253], v[252:253], v[254:255]
	s_nop 0
	v_add_f32_e32 v183, v252, v253
	s_nop 1
	v_add_f32_dpp v183, v183, v183 quad_perm:[1,0,3,2] row_mask:0xf bank_mask:0xf bound_ctrl:1
	s_nop 1
	v_add_f32_dpp v183, v183, v183 quad_perm:[2,3,0,1] row_mask:0xf bank_mask:0xf bound_ctrl:1
	s_nop 1
	v_add_f32_dpp v183, v183, v183 row_half_mirror row_mask:0xf bank_mask:0xf bound_ctrl:1
	s_nop 1
	v_add_f32_dpp v183, v183, v183 row_mirror row_mask:0xf bank_mask:0xf bound_ctrl:1
	s_nop 1
	v_readlane_b32 s98, v183, 0
	v_readlane_b32 s99, v183, 16
	v_readlane_b32 s100, v183, 32
	v_readlane_b32 s101, v183, 48
	s_nop 1
	v_mov_b32_e32 v183, s98
	v_add_f32_e32 v183, s99, v183
	v_add_f32_e32 v183, s100, v183
	v_add_f32_e32 v183, s101, v183
	v_fmamk_f32 v183, v183, 0x3a800000, v182
	v_cmp_gt_f32_e32 vcc, 0x800000, v183
	v_mul_f32_e32 v181, 0x4b800000, v183
	s_nop 1
	v_cndmask_b32_e32 v183, v183, v181, vcc
	v_rsq_f32_e32 v183, v183
	s_nop 0
	v_mul_f32_e32 v181, 0x45800000, v183
	v_cndmask_b32_e32 v184, v183, v181, vcc
	v_mov_b32_e32 v185, v184
	v_cvt_pk_bf16_f32 v32, v144, v145
	v_cvt_pk_bf16_f32 v33, v146, v147
	v_cvt_pk_bf16_f32 v34, v148, v149
	v_cvt_pk_bf16_f32 v35, v150, v151
	v_cvt_pk_bf16_f32 v36, v152, v153
	v_cvt_pk_bf16_f32 v37, v154, v155
	v_cvt_pk_bf16_f32 v38, v156, v157
	v_cvt_pk_bf16_f32 v39, v158, v159
	v_add_u32_e32 v181, 0x2000000, v177
	global_store_dwordx4 v181, v[32:35], s[78:79]
	global_store_dwordx4 v181, v[36:39], s[78:79] offset:1024
	v_add_u32_e32 v236, 0x4000, v237
	s_mov_b64 exec, 1
	global_store_dword v236, v184, s[78:79]
	s_mov_b64 exec, -1
	s_waitcnt vmcnt(16)
	v_lshlrev_b32_e32 v144, 16, v48
	v_and_b32_e32 v145, 0xffff0000, v48
	v_lshlrev_b32_e32 v146, 16, v49
	v_and_b32_e32 v147, 0xffff0000, v49
	v_lshlrev_b32_e32 v148, 16, v50
	v_and_b32_e32 v149, 0xffff0000, v50
	v_lshlrev_b32_e32 v150, 16, v51
	v_and_b32_e32 v151, 0xffff0000, v51
	v_lshlrev_b32_e32 v152, 16, v52
	v_and_b32_e32 v153, 0xffff0000, v52
	v_lshlrev_b32_e32 v154, 16, v53
	v_and_b32_e32 v155, 0xffff0000, v53
	v_lshlrev_b32_e32 v156, 16, v54
	v_and_b32_e32 v157, 0xffff0000, v54
	v_lshlrev_b32_e32 v158, 16, v55
	v_and_b32_e32 v159, 0xffff0000, v55
	v_lshlrev_b32_e32 v160, 16, v56
	v_and_b32_e32 v161, 0xffff0000, v56
	v_lshlrev_b32_e32 v162, 16, v57
	v_and_b32_e32 v163, 0xffff0000, v57
	v_lshlrev_b32_e32 v164, 16, v58
	v_and_b32_e32 v165, 0xffff0000, v58
	v_lshlrev_b32_e32 v166, 16, v59
	v_and_b32_e32 v167, 0xffff0000, v59
	v_lshlrev_b32_e32 v168, 16, v60
	v_and_b32_e32 v169, 0xffff0000, v60
	v_lshlrev_b32_e32 v170, 16, v61
	v_and_b32_e32 v171, 0xffff0000, v61
	v_lshlrev_b32_e32 v172, 16, v62
	v_and_b32_e32 v173, 0xffff0000, v62
	v_lshlrev_b32_e32 v174, 16, v63
	v_and_b32_e32 v175, 0xffff0000, v63
	v_pk_mul_f32 v[252:253], v[160:161], v[160:161]
	v_pk_mul_f32 v[254:255], v[162:163], v[162:163]
	v_pk_fma_f32 v[252:253], v[164:165], v[164:165], v[252:253]
	v_pk_fma_f32 v[254:255], v[166:167], v[166:167], v[254:255]
	v_pk_fma_f32 v[252:253], v[168:169], v[168:169], v[252:253]
	v_pk_fma_f32 v[254:255], v[170:171], v[170:171], v[254:255]
	v_pk_fma_f32 v[252:253], v[172:173], v[172:173], v[252:253]
	v_pk_fma_f32 v[254:255], v[174:175], v[174:175], v[254:255]
	v_pk_add_f32 v[252:253], v[252:253], v[254:255]
	s_nop 0
	v_add_f32_e32 v183, v252, v253
	s_nop 1
	v_add_f32_dpp v183, v183, v183 quad_perm:[1,0,3,2] row_mask:0xf bank_mask:0xf bound_ctrl:1
	s_nop 1
	v_add_f32_dpp v183, v183, v183 quad_perm:[2,3,0,1] row_mask:0xf bank_mask:0xf bound_ctrl:1
	s_nop 1
	v_add_f32_dpp v183, v183, v183 row_half_mirror row_mask:0xf bank_mask:0xf bound_ctrl:1
	s_nop 1
	v_add_f32_dpp v183, v183, v183 row_mirror row_mask:0xf bank_mask:0xf bound_ctrl:1
	s_nop 1
	v_readlane_b32 s98, v183, 0
	v_readlane_b32 s99, v183, 16
	v_readlane_b32 s100, v183, 32
	v_readlane_b32 s101, v183, 48
	s_nop 1
	v_mov_b32_e32 v183, s98
	v_add_f32_e32 v183, s99, v183
	v_add_f32_e32 v183, s100, v183
	v_add_f32_e32 v183, s101, v183
	v_fmamk_f32 v183, v183, 0x3a800000, v182
	v_cmp_gt_f32_e32 vcc, 0x800000, v183
	v_mul_f32_e32 v181, 0x4b800000, v183
	s_nop 1
	v_cndmask_b32_e32 v183, v183, v181, vcc
	v_rsq_f32_e32 v183, v183
	s_nop 0
	v_mul_f32_e32 v181, 0x45800000, v183
	v_cndmask_b32_e32 v184, v183, v181, vcc
	v_mov_b32_e32 v185, v184
	v_pk_mul_f32 v[160:161], v[160:161], v[184:185]
	v_pk_mul_f32 v[162:163], v[162:163], v[184:185]
	v_pk_mul_f32 v[164:165], v[164:165], v[184:185]
	v_pk_mul_f32 v[166:167], v[166:167], v[184:185]
	v_pk_mul_f32 v[168:169], v[168:169], v[184:185]
	v_pk_mul_f32 v[170:171], v[170:171], v[184:185]
	v_pk_mul_f32 v[172:173], v[172:173], v[184:185]
	v_pk_mul_f32 v[174:175], v[174:175], v[184:185]
	v_pk_fma_f32 v[144:145], v[160:161], v[128:129], v[144:145]
	v_pk_fma_f32 v[146:147], v[162:163], v[130:131], v[146:147]
	v_pk_fma_f32 v[148:149], v[164:165], v[132:133], v[148:149]
	v_pk_fma_f32 v[150:151], v[166:167], v[134:135], v[150:151]
	v_pk_fma_f32 v[152:153], v[168:169], v[136:137], v[152:153]
	v_pk_fma_f32 v[154:155], v[170:171], v[138:139], v[154:155]
	v_pk_fma_f32 v[156:157], v[172:173], v[140:141], v[156:157]
	v_pk_fma_f32 v[158:159], v[174:175], v[142:143], v[158:159]
	v_pk_mul_f32 v[252:253], v[144:145], v[144:145]
	v_pk_mul_f32 v[254:255], v[146:147], v[146:147]
	v_pk_fma_f32 v[252:253], v[148:149], v[148:149], v[252:253]
	v_pk_fma_f32 v[254:255], v[150:151], v[150:151], v[254:255]
	v_pk_fma_f32 v[252:253], v[152:153], v[152:153], v[252:253]
	v_pk_fma_f32 v[254:255], v[154:155], v[154:155], v[254:255]
	v_pk_fma_f32 v[252:253], v[156:157], v[156:157], v[252:253]
	v_pk_fma_f32 v[254:255], v[158:159], v[158:159], v[254:255]
	v_pk_add_f32 v[252:253], v[252:253], v[254:255]
	s_nop 0
	v_add_f32_e32 v183, v252, v253
	s_nop 1
	v_add_f32_dpp v183, v183, v183 quad_perm:[1,0,3,2] row_mask:0xf bank_mask:0xf bound_ctrl:1
	s_nop 1
	v_add_f32_dpp v183, v183, v183 quad_perm:[2,3,0,1] row_mask:0xf bank_mask:0xf bound_ctrl:1
	s_nop 1
	v_add_f32_dpp v183, v183, v183 row_half_mirror row_mask:0xf bank_mask:0xf bound_ctrl:1
	s_nop 1
	v_add_f32_dpp v183, v183, v183 row_mirror row_mask:0xf bank_mask:0xf bound_ctrl:1
	s_nop 1
	v_readlane_b32 s98, v183, 0
	v_readlane_b32 s99, v183, 16
	v_readlane_b32 s100, v183, 32
	v_readlane_b32 s101, v183, 48
	s_nop 1
	v_mov_b32_e32 v183, s98
	v_add_f32_e32 v183, s99, v183
	v_add_f32_e32 v183, s100, v183
	v_add_f32_e32 v183, s101, v183
	v_fmamk_f32 v183, v183, 0x3a800000, v182
	v_cmp_gt_f32_e32 vcc, 0x800000, v183
	v_mul_f32_e32 v181, 0x4b800000, v183
	s_nop 1
	v_cndmask_b32_e32 v183, v183, v181, vcc
	v_rsq_f32_e32 v183, v183
	s_nop 0
	v_mul_f32_e32 v181, 0x45800000, v183
	v_cndmask_b32_e32 v184, v183, v181, vcc
	v_mov_b32_e32 v185, v184
	v_cvt_pk_bf16_f32 v48, v144, v145
	v_cvt_pk_bf16_f32 v49, v146, v147
	v_cvt_pk_bf16_f32 v50, v148, v149
	v_cvt_pk_bf16_f32 v51, v150, v151
	v_cvt_pk_bf16_f32 v52, v152, v153
	v_cvt_pk_bf16_f32 v53, v154, v155
	v_cvt_pk_bf16_f32 v54, v156, v157
	v_cvt_pk_bf16_f32 v55, v158, v159
	v_add_u32_e32 v181, 0x2400000, v177
	global_store_dwordx4 v181, v[48:51], s[78:79]
	global_store_dwordx4 v181, v[52:55], s[78:79] offset:1024
	v_add_u32_e32 v236, 0x6000, v237
	s_mov_b64 exec, 1
	global_store_dword v236, v184, s[78:79]
	s_mov_b64 exec, -1
	s_waitcnt vmcnt(12)
	v_lshlrev_b32_e32 v144, 16, v64
	v_and_b32_e32 v145, 0xffff0000, v64
	v_lshlrev_b32_e32 v146, 16, v65
	v_and_b32_e32 v147, 0xffff0000, v65
	v_lshlrev_b32_e32 v148, 16, v66
	v_and_b32_e32 v149, 0xffff0000, v66
	v_lshlrev_b32_e32 v150, 16, v67
	v_and_b32_e32 v151, 0xffff0000, v67
	v_lshlrev_b32_e32 v152, 16, v68
	v_and_b32_e32 v153, 0xffff0000, v68
	v_lshlrev_b32_e32 v154, 16, v69
	v_and_b32_e32 v155, 0xffff0000, v69
	v_lshlrev_b32_e32 v156, 16, v70
	v_and_b32_e32 v157, 0xffff0000, v70
	v_lshlrev_b32_e32 v158, 16, v71
	v_and_b32_e32 v159, 0xffff0000, v71
	v_lshlrev_b32_e32 v160, 16, v72
	v_and_b32_e32 v161, 0xffff0000, v72
	v_lshlrev_b32_e32 v162, 16, v73
	v_and_b32_e32 v163, 0xffff0000, v73
	v_lshlrev_b32_e32 v164, 16, v74
	v_and_b32_e32 v165, 0xffff0000, v74
	v_lshlrev_b32_e32 v166, 16, v75
	v_and_b32_e32 v167, 0xffff0000, v75
	v_lshlrev_b32_e32 v168, 16, v76
	v_and_b32_e32 v169, 0xffff0000, v76
	v_lshlrev_b32_e32 v170, 16, v77
	v_and_b32_e32 v171, 0xffff0000, v77
	v_lshlrev_b32_e32 v172, 16, v78
	v_and_b32_e32 v173, 0xffff0000, v78
	v_lshlrev_b32_e32 v174, 16, v79
	v_and_b32_e32 v175, 0xffff0000, v79
	v_pk_mul_f32 v[252:253], v[160:161], v[160:161]
	v_pk_mul_f32 v[254:255], v[162:163], v[162:163]
	v_pk_fma_f32 v[252:253], v[164:165], v[164:165], v[252:253]
	v_pk_fma_f32 v[254:255], v[166:167], v[166:167], v[254:255]
	v_pk_fma_f32 v[252:253], v[168:169], v[168:169], v[252:253]
	v_pk_fma_f32 v[254:255], v[170:171], v[170:171], v[254:255]
	v_pk_fma_f32 v[252:253], v[172:173], v[172:173], v[252:253]
	v_pk_fma_f32 v[254:255], v[174:175], v[174:175], v[254:255]
	v_pk_add_f32 v[252:253], v[252:253], v[254:255]
	s_nop 0
	v_add_f32_e32 v183, v252, v253
	s_nop 1
	v_add_f32_dpp v183, v183, v183 quad_perm:[1,0,3,2] row_mask:0xf bank_mask:0xf bound_ctrl:1
	s_nop 1
	v_add_f32_dpp v183, v183, v183 quad_perm:[2,3,0,1] row_mask:0xf bank_mask:0xf bound_ctrl:1
	s_nop 1
	v_add_f32_dpp v183, v183, v183 row_half_mirror row_mask:0xf bank_mask:0xf bound_ctrl:1
	s_nop 1
	v_add_f32_dpp v183, v183, v183 row_mirror row_mask:0xf bank_mask:0xf bound_ctrl:1
	s_nop 1
	v_readlane_b32 s98, v183, 0
	v_readlane_b32 s99, v183, 16
	v_readlane_b32 s100, v183, 32
	v_readlane_b32 s101, v183, 48
	s_nop 1
	v_mov_b32_e32 v183, s98
	v_add_f32_e32 v183, s99, v183
	v_add_f32_e32 v183, s100, v183
	v_add_f32_e32 v183, s101, v183
	v_fmamk_f32 v183, v183, 0x3a800000, v182
	v_cmp_gt_f32_e32 vcc, 0x800000, v183
	v_mul_f32_e32 v181, 0x4b800000, v183
	s_nop 1
	v_cndmask_b32_e32 v183, v183, v181, vcc
	v_rsq_f32_e32 v183, v183
	s_nop 0
	v_mul_f32_e32 v181, 0x45800000, v183
	v_cndmask_b32_e32 v184, v183, v181, vcc
	v_mov_b32_e32 v185, v184
	v_pk_mul_f32 v[160:161], v[160:161], v[184:185]
	v_pk_mul_f32 v[162:163], v[162:163], v[184:185]
	v_pk_mul_f32 v[164:165], v[164:165], v[184:185]
	v_pk_mul_f32 v[166:167], v[166:167], v[184:185]
	v_pk_mul_f32 v[168:169], v[168:169], v[184:185]
	v_pk_mul_f32 v[170:171], v[170:171], v[184:185]
	v_pk_mul_f32 v[172:173], v[172:173], v[184:185]
	v_pk_mul_f32 v[174:175], v[174:175], v[184:185]
	v_pk_fma_f32 v[144:145], v[160:161], v[128:129], v[144:145]
	v_pk_fma_f32 v[146:147], v[162:163], v[130:131], v[146:147]
	v_pk_fma_f32 v[148:149], v[164:165], v[132:133], v[148:149]
	v_pk_fma_f32 v[150:151], v[166:167], v[134:135], v[150:151]
	v_pk_fma_f32 v[152:153], v[168:169], v[136:137], v[152:153]
	v_pk_fma_f32 v[154:155], v[170:171], v[138:139], v[154:155]
	v_pk_fma_f32 v[156:157], v[172:173], v[140:141], v[156:157]
	v_pk_fma_f32 v[158:159], v[174:175], v[142:143], v[158:159]
	v_pk_mul_f32 v[252:253], v[144:145], v[144:145]
	v_pk_mul_f32 v[254:255], v[146:147], v[146:147]
	v_pk_fma_f32 v[252:253], v[148:149], v[148:149], v[252:253]
	v_pk_fma_f32 v[254:255], v[150:151], v[150:151], v[254:255]
	v_pk_fma_f32 v[252:253], v[152:153], v[152:153], v[252:253]
	v_pk_fma_f32 v[254:255], v[154:155], v[154:155], v[254:255]
	v_pk_fma_f32 v[252:253], v[156:157], v[156:157], v[252:253]
	v_pk_fma_f32 v[254:255], v[158:159], v[158:159], v[254:255]
	v_pk_add_f32 v[252:253], v[252:253], v[254:255]
	s_nop 0
	v_add_f32_e32 v183, v252, v253
	s_nop 1
	v_add_f32_dpp v183, v183, v183 quad_perm:[1,0,3,2] row_mask:0xf bank_mask:0xf bound_ctrl:1
	s_nop 1
	v_add_f32_dpp v183, v183, v183 quad_perm:[2,3,0,1] row_mask:0xf bank_mask:0xf bound_ctrl:1
	s_nop 1
	v_add_f32_dpp v183, v183, v183 row_half_mirror row_mask:0xf bank_mask:0xf bound_ctrl:1
	s_nop 1
	v_add_f32_dpp v183, v183, v183 row_mirror row_mask:0xf bank_mask:0xf bound_ctrl:1
	s_nop 1
	v_readlane_b32 s98, v183, 0
	v_readlane_b32 s99, v183, 16
	v_readlane_b32 s100, v183, 32
	v_readlane_b32 s101, v183, 48
	s_nop 1
	v_mov_b32_e32 v183, s98
	v_add_f32_e32 v183, s99, v183
	v_add_f32_e32 v183, s100, v183
	v_add_f32_e32 v183, s101, v183
	v_fmamk_f32 v183, v183, 0x3a800000, v182
	v_cmp_gt_f32_e32 vcc, 0x800000, v183
	v_mul_f32_e32 v181, 0x4b800000, v183
	s_nop 1
	v_cndmask_b32_e32 v183, v183, v181, vcc
	v_rsq_f32_e32 v183, v183
	s_nop 0
	v_mul_f32_e32 v181, 0x45800000, v183
	v_cndmask_b32_e32 v184, v183, v181, vcc
	v_mov_b32_e32 v185, v184
	v_cvt_pk_bf16_f32 v64, v144, v145
	v_cvt_pk_bf16_f32 v65, v146, v147
	v_cvt_pk_bf16_f32 v66, v148, v149
	v_cvt_pk_bf16_f32 v67, v150, v151
	v_cvt_pk_bf16_f32 v68, v152, v153
	v_cvt_pk_bf16_f32 v69, v154, v155
	v_cvt_pk_bf16_f32 v70, v156, v157
	v_cvt_pk_bf16_f32 v71, v158, v159
	v_add_u32_e32 v181, 0x2800000, v177
	global_store_dwordx4 v181, v[64:67], s[78:79]
	global_store_dwordx4 v181, v[68:71], s[78:79] offset:1024
	v_add_u32_e32 v236, 0x8000, v237
	s_mov_b64 exec, 1
	global_store_dword v236, v184, s[78:79]
	s_mov_b64 exec, -1
	s_waitcnt vmcnt(8)
	v_lshlrev_b32_e32 v144, 16, v80
	v_and_b32_e32 v145, 0xffff0000, v80
	v_lshlrev_b32_e32 v146, 16, v81
	v_and_b32_e32 v147, 0xffff0000, v81
	v_lshlrev_b32_e32 v148, 16, v82
	v_and_b32_e32 v149, 0xffff0000, v82
	v_lshlrev_b32_e32 v150, 16, v83
	v_and_b32_e32 v151, 0xffff0000, v83
	v_lshlrev_b32_e32 v152, 16, v84
	v_and_b32_e32 v153, 0xffff0000, v84
	v_lshlrev_b32_e32 v154, 16, v85
	v_and_b32_e32 v155, 0xffff0000, v85
	v_lshlrev_b32_e32 v156, 16, v86
	v_and_b32_e32 v157, 0xffff0000, v86
	v_lshlrev_b32_e32 v158, 16, v87
	v_and_b32_e32 v159, 0xffff0000, v87
	v_lshlrev_b32_e32 v160, 16, v88
	v_and_b32_e32 v161, 0xffff0000, v88
	v_lshlrev_b32_e32 v162, 16, v89
	v_and_b32_e32 v163, 0xffff0000, v89
	v_lshlrev_b32_e32 v164, 16, v90
	v_and_b32_e32 v165, 0xffff0000, v90
	v_lshlrev_b32_e32 v166, 16, v91
	v_and_b32_e32 v167, 0xffff0000, v91
	v_lshlrev_b32_e32 v168, 16, v92
	v_and_b32_e32 v169, 0xffff0000, v92
	v_lshlrev_b32_e32 v170, 16, v93
	v_and_b32_e32 v171, 0xffff0000, v93
	v_lshlrev_b32_e32 v172, 16, v94
	v_and_b32_e32 v173, 0xffff0000, v94
	v_lshlrev_b32_e32 v174, 16, v95
	v_and_b32_e32 v175, 0xffff0000, v95
	v_pk_mul_f32 v[252:253], v[160:161], v[160:161]
	v_pk_mul_f32 v[254:255], v[162:163], v[162:163]
	v_pk_fma_f32 v[252:253], v[164:165], v[164:165], v[252:253]
	v_pk_fma_f32 v[254:255], v[166:167], v[166:167], v[254:255]
	v_pk_fma_f32 v[252:253], v[168:169], v[168:169], v[252:253]
	v_pk_fma_f32 v[254:255], v[170:171], v[170:171], v[254:255]
	v_pk_fma_f32 v[252:253], v[172:173], v[172:173], v[252:253]
	v_pk_fma_f32 v[254:255], v[174:175], v[174:175], v[254:255]
	v_pk_add_f32 v[252:253], v[252:253], v[254:255]
	s_nop 0
	v_add_f32_e32 v183, v252, v253
	s_nop 1
	v_add_f32_dpp v183, v183, v183 quad_perm:[1,0,3,2] row_mask:0xf bank_mask:0xf bound_ctrl:1
	s_nop 1
	v_add_f32_dpp v183, v183, v183 quad_perm:[2,3,0,1] row_mask:0xf bank_mask:0xf bound_ctrl:1
	s_nop 1
	v_add_f32_dpp v183, v183, v183 row_half_mirror row_mask:0xf bank_mask:0xf bound_ctrl:1
	s_nop 1
	v_add_f32_dpp v183, v183, v183 row_mirror row_mask:0xf bank_mask:0xf bound_ctrl:1
	s_nop 1
	v_readlane_b32 s98, v183, 0
	v_readlane_b32 s99, v183, 16
	v_readlane_b32 s100, v183, 32
	v_readlane_b32 s101, v183, 48
	s_nop 1
	v_mov_b32_e32 v183, s98
	v_add_f32_e32 v183, s99, v183
	v_add_f32_e32 v183, s100, v183
	v_add_f32_e32 v183, s101, v183
	v_fmamk_f32 v183, v183, 0x3a800000, v182
	v_cmp_gt_f32_e32 vcc, 0x800000, v183
	v_mul_f32_e32 v181, 0x4b800000, v183
	s_nop 1
	v_cndmask_b32_e32 v183, v183, v181, vcc
	v_rsq_f32_e32 v183, v183
	s_nop 0
	v_mul_f32_e32 v181, 0x45800000, v183
	v_cndmask_b32_e32 v184, v183, v181, vcc
	v_mov_b32_e32 v185, v184
	v_pk_mul_f32 v[160:161], v[160:161], v[184:185]
	v_pk_mul_f32 v[162:163], v[162:163], v[184:185]
	v_pk_mul_f32 v[164:165], v[164:165], v[184:185]
	v_pk_mul_f32 v[166:167], v[166:167], v[184:185]
	v_pk_mul_f32 v[168:169], v[168:169], v[184:185]
	v_pk_mul_f32 v[170:171], v[170:171], v[184:185]
	v_pk_mul_f32 v[172:173], v[172:173], v[184:185]
	v_pk_mul_f32 v[174:175], v[174:175], v[184:185]
	v_pk_fma_f32 v[144:145], v[160:161], v[128:129], v[144:145]
	v_pk_fma_f32 v[146:147], v[162:163], v[130:131], v[146:147]
	v_pk_fma_f32 v[148:149], v[164:165], v[132:133], v[148:149]
	v_pk_fma_f32 v[150:151], v[166:167], v[134:135], v[150:151]
	v_pk_fma_f32 v[152:153], v[168:169], v[136:137], v[152:153]
	v_pk_fma_f32 v[154:155], v[170:171], v[138:139], v[154:155]
	v_pk_fma_f32 v[156:157], v[172:173], v[140:141], v[156:157]
	v_pk_fma_f32 v[158:159], v[174:175], v[142:143], v[158:159]
	v_pk_mul_f32 v[252:253], v[144:145], v[144:145]
	v_pk_mul_f32 v[254:255], v[146:147], v[146:147]
	v_pk_fma_f32 v[252:253], v[148:149], v[148:149], v[252:253]
	v_pk_fma_f32 v[254:255], v[150:151], v[150:151], v[254:255]
	v_pk_fma_f32 v[252:253], v[152:153], v[152:153], v[252:253]
	v_pk_fma_f32 v[254:255], v[154:155], v[154:155], v[254:255]
	v_pk_fma_f32 v[252:253], v[156:157], v[156:157], v[252:253]
	v_pk_fma_f32 v[254:255], v[158:159], v[158:159], v[254:255]
	v_pk_add_f32 v[252:253], v[252:253], v[254:255]
	s_nop 0
	v_add_f32_e32 v183, v252, v253
	s_nop 1
	v_add_f32_dpp v183, v183, v183 quad_perm:[1,0,3,2] row_mask:0xf bank_mask:0xf bound_ctrl:1
	s_nop 1
	v_add_f32_dpp v183, v183, v183 quad_perm:[2,3,0,1] row_mask:0xf bank_mask:0xf bound_ctrl:1
	s_nop 1
	v_add_f32_dpp v183, v183, v183 row_half_mirror row_mask:0xf bank_mask:0xf bound_ctrl:1
	s_nop 1
	v_add_f32_dpp v183, v183, v183 row_mirror row_mask:0xf bank_mask:0xf bound_ctrl:1
	s_nop 1
	v_readlane_b32 s98, v183, 0
	v_readlane_b32 s99, v183, 16
	v_readlane_b32 s100, v183, 32
	v_readlane_b32 s101, v183, 48
	s_nop 1
	v_mov_b32_e32 v183, s98
	v_add_f32_e32 v183, s99, v183
	v_add_f32_e32 v183, s100, v183
	v_add_f32_e32 v183, s101, v183
	v_fmamk_f32 v183, v183, 0x3a800000, v182
	v_cmp_gt_f32_e32 vcc, 0x800000, v183
	v_mul_f32_e32 v181, 0x4b800000, v183
	s_nop 1
	v_cndmask_b32_e32 v183, v183, v181, vcc
	v_rsq_f32_e32 v183, v183
	s_nop 0
	v_mul_f32_e32 v181, 0x45800000, v183
	v_cndmask_b32_e32 v184, v183, v181, vcc
	v_mov_b32_e32 v185, v184
	v_cvt_pk_bf16_f32 v80, v144, v145
	v_cvt_pk_bf16_f32 v81, v146, v147
	v_cvt_pk_bf16_f32 v82, v148, v149
	v_cvt_pk_bf16_f32 v83, v150, v151
	v_cvt_pk_bf16_f32 v84, v152, v153
	v_cvt_pk_bf16_f32 v85, v154, v155
	v_cvt_pk_bf16_f32 v86, v156, v157
	v_cvt_pk_bf16_f32 v87, v158, v159
	v_add_u32_e32 v181, 0x2c00000, v177
	global_store_dwordx4 v181, v[80:83], s[78:79]
	global_store_dwordx4 v181, v[84:87], s[78:79] offset:1024
	v_add_u32_e32 v236, 0xa000, v237
	s_mov_b64 exec, 1
	global_store_dword v236, v184, s[78:79]
	s_mov_b64 exec, -1
	s_waitcnt vmcnt(4)
	v_lshlrev_b32_e32 v144, 16, v96
	v_and_b32_e32 v145, 0xffff0000, v96
	v_lshlrev_b32_e32 v146, 16, v97
	v_and_b32_e32 v147, 0xffff0000, v97
	v_lshlrev_b32_e32 v148, 16, v98
	v_and_b32_e32 v149, 0xffff0000, v98
	v_lshlrev_b32_e32 v150, 16, v99
	v_and_b32_e32 v151, 0xffff0000, v99
	v_lshlrev_b32_e32 v152, 16, v100
	v_and_b32_e32 v153, 0xffff0000, v100
	v_lshlrev_b32_e32 v154, 16, v101
	v_and_b32_e32 v155, 0xffff0000, v101
	v_lshlrev_b32_e32 v156, 16, v102
	v_and_b32_e32 v157, 0xffff0000, v102
	v_lshlrev_b32_e32 v158, 16, v103
	v_and_b32_e32 v159, 0xffff0000, v103
	v_lshlrev_b32_e32 v160, 16, v104
	v_and_b32_e32 v161, 0xffff0000, v104
	v_lshlrev_b32_e32 v162, 16, v105
	v_and_b32_e32 v163, 0xffff0000, v105
	v_lshlrev_b32_e32 v164, 16, v106
	v_and_b32_e32 v165, 0xffff0000, v106
	v_lshlrev_b32_e32 v166, 16, v107
	v_and_b32_e32 v167, 0xffff0000, v107
	v_lshlrev_b32_e32 v168, 16, v108
	v_and_b32_e32 v169, 0xffff0000, v108
	v_lshlrev_b32_e32 v170, 16, v109
	v_and_b32_e32 v171, 0xffff0000, v109
	v_lshlrev_b32_e32 v172, 16, v110
	v_and_b32_e32 v173, 0xffff0000, v110
	v_lshlrev_b32_e32 v174, 16, v111
	v_and_b32_e32 v175, 0xffff0000, v111
	v_pk_mul_f32 v[252:253], v[160:161], v[160:161]
	v_pk_mul_f32 v[254:255], v[162:163], v[162:163]
	v_pk_fma_f32 v[252:253], v[164:165], v[164:165], v[252:253]
	v_pk_fma_f32 v[254:255], v[166:167], v[166:167], v[254:255]
	v_pk_fma_f32 v[252:253], v[168:169], v[168:169], v[252:253]
	v_pk_fma_f32 v[254:255], v[170:171], v[170:171], v[254:255]
	v_pk_fma_f32 v[252:253], v[172:173], v[172:173], v[252:253]
	v_pk_fma_f32 v[254:255], v[174:175], v[174:175], v[254:255]
	v_pk_add_f32 v[252:253], v[252:253], v[254:255]
	s_nop 0
	v_add_f32_e32 v183, v252, v253
	s_nop 1
	v_add_f32_dpp v183, v183, v183 quad_perm:[1,0,3,2] row_mask:0xf bank_mask:0xf bound_ctrl:1
	s_nop 1
	v_add_f32_dpp v183, v183, v183 quad_perm:[2,3,0,1] row_mask:0xf bank_mask:0xf bound_ctrl:1
	s_nop 1
	v_add_f32_dpp v183, v183, v183 row_half_mirror row_mask:0xf bank_mask:0xf bound_ctrl:1
	s_nop 1
	v_add_f32_dpp v183, v183, v183 row_mirror row_mask:0xf bank_mask:0xf bound_ctrl:1
	s_nop 1
	v_readlane_b32 s98, v183, 0
	v_readlane_b32 s99, v183, 16
	v_readlane_b32 s100, v183, 32
	v_readlane_b32 s101, v183, 48
	s_nop 1
	v_mov_b32_e32 v183, s98
	v_add_f32_e32 v183, s99, v183
	v_add_f32_e32 v183, s100, v183
	v_add_f32_e32 v183, s101, v183
	v_fmamk_f32 v183, v183, 0x3a800000, v182
	v_cmp_gt_f32_e32 vcc, 0x800000, v183
	v_mul_f32_e32 v181, 0x4b800000, v183
	s_nop 1
	v_cndmask_b32_e32 v183, v183, v181, vcc
	v_rsq_f32_e32 v183, v183
	s_nop 0
	v_mul_f32_e32 v181, 0x45800000, v183
	v_cndmask_b32_e32 v184, v183, v181, vcc
	v_mov_b32_e32 v185, v184
	v_pk_mul_f32 v[160:161], v[160:161], v[184:185]
	v_pk_mul_f32 v[162:163], v[162:163], v[184:185]
	v_pk_mul_f32 v[164:165], v[164:165], v[184:185]
	v_pk_mul_f32 v[166:167], v[166:167], v[184:185]
	v_pk_mul_f32 v[168:169], v[168:169], v[184:185]
	v_pk_mul_f32 v[170:171], v[170:171], v[184:185]
	v_pk_mul_f32 v[172:173], v[172:173], v[184:185]
	v_pk_mul_f32 v[174:175], v[174:175], v[184:185]
	v_pk_fma_f32 v[144:145], v[160:161], v[128:129], v[144:145]
	v_pk_fma_f32 v[146:147], v[162:163], v[130:131], v[146:147]
	v_pk_fma_f32 v[148:149], v[164:165], v[132:133], v[148:149]
	v_pk_fma_f32 v[150:151], v[166:167], v[134:135], v[150:151]
	v_pk_fma_f32 v[152:153], v[168:169], v[136:137], v[152:153]
	v_pk_fma_f32 v[154:155], v[170:171], v[138:139], v[154:155]
	v_pk_fma_f32 v[156:157], v[172:173], v[140:141], v[156:157]
	v_pk_fma_f32 v[158:159], v[174:175], v[142:143], v[158:159]
	v_pk_mul_f32 v[252:253], v[144:145], v[144:145]
	v_pk_mul_f32 v[254:255], v[146:147], v[146:147]
	v_pk_fma_f32 v[252:253], v[148:149], v[148:149], v[252:253]
	v_pk_fma_f32 v[254:255], v[150:151], v[150:151], v[254:255]
	v_pk_fma_f32 v[252:253], v[152:153], v[152:153], v[252:253]
	v_pk_fma_f32 v[254:255], v[154:155], v[154:155], v[254:255]
	v_pk_fma_f32 v[252:253], v[156:157], v[156:157], v[252:253]
	v_pk_fma_f32 v[254:255], v[158:159], v[158:159], v[254:255]
	v_pk_add_f32 v[252:253], v[252:253], v[254:255]
	s_nop 0
	v_add_f32_e32 v183, v252, v253
	s_nop 1
	v_add_f32_dpp v183, v183, v183 quad_perm:[1,0,3,2] row_mask:0xf bank_mask:0xf bound_ctrl:1
	s_nop 1
	v_add_f32_dpp v183, v183, v183 quad_perm:[2,3,0,1] row_mask:0xf bank_mask:0xf bound_ctrl:1
	s_nop 1
	v_add_f32_dpp v183, v183, v183 row_half_mirror row_mask:0xf bank_mask:0xf bound_ctrl:1
	s_nop 1
	v_add_f32_dpp v183, v183, v183 row_mirror row_mask:0xf bank_mask:0xf bound_ctrl:1
	s_nop 1
	v_readlane_b32 s98, v183, 0
	v_readlane_b32 s99, v183, 16
	v_readlane_b32 s100, v183, 32
	v_readlane_b32 s101, v183, 48
	s_nop 1
	v_mov_b32_e32 v183, s98
	v_add_f32_e32 v183, s99, v183
	v_add_f32_e32 v183, s100, v183
	v_add_f32_e32 v183, s101, v183
	v_fmamk_f32 v183, v183, 0x3a800000, v182
	v_cmp_gt_f32_e32 vcc, 0x800000, v183
	v_mul_f32_e32 v181, 0x4b800000, v183
	s_nop 1
	v_cndmask_b32_e32 v183, v183, v181, vcc
	v_rsq_f32_e32 v183, v183
	s_nop 0
	v_mul_f32_e32 v181, 0x45800000, v183
	v_cndmask_b32_e32 v184, v183, v181, vcc
	v_mov_b32_e32 v185, v184
	v_cvt_pk_bf16_f32 v96, v144, v145
	v_cvt_pk_bf16_f32 v97, v146, v147
	v_cvt_pk_bf16_f32 v98, v148, v149
	v_cvt_pk_bf16_f32 v99, v150, v151
	v_cvt_pk_bf16_f32 v100, v152, v153
	v_cvt_pk_bf16_f32 v101, v154, v155
	v_cvt_pk_bf16_f32 v102, v156, v157
	v_cvt_pk_bf16_f32 v103, v158, v159
	v_add_u32_e32 v181, 0x3000000, v177
	global_store_dwordx4 v181, v[96:99], s[78:79]
	global_store_dwordx4 v181, v[100:103], s[78:79] offset:1024
	v_add_u32_e32 v236, 0xc000, v237
	s_mov_b64 exec, 1
	global_store_dword v236, v184, s[78:79]
	s_mov_b64 exec, -1
	s_waitcnt vmcnt(0)
	v_lshlrev_b32_e32 v144, 16, v112
	v_and_b32_e32 v145, 0xffff0000, v112
	v_lshlrev_b32_e32 v146, 16, v113
	v_and_b32_e32 v147, 0xffff0000, v113
	v_lshlrev_b32_e32 v148, 16, v114
	v_and_b32_e32 v149, 0xffff0000, v114
	v_lshlrev_b32_e32 v150, 16, v115
	v_and_b32_e32 v151, 0xffff0000, v115
	v_lshlrev_b32_e32 v152, 16, v116
	v_and_b32_e32 v153, 0xffff0000, v116
	v_lshlrev_b32_e32 v154, 16, v117
	v_and_b32_e32 v155, 0xffff0000, v117
	v_lshlrev_b32_e32 v156, 16, v118
	v_and_b32_e32 v157, 0xffff0000, v118
	v_lshlrev_b32_e32 v158, 16, v119
	v_and_b32_e32 v159, 0xffff0000, v119
	v_lshlrev_b32_e32 v160, 16, v120
	v_and_b32_e32 v161, 0xffff0000, v120
	v_lshlrev_b32_e32 v162, 16, v121
	v_and_b32_e32 v163, 0xffff0000, v121
	v_lshlrev_b32_e32 v164, 16, v122
	v_and_b32_e32 v165, 0xffff0000, v122
	v_lshlrev_b32_e32 v166, 16, v123
	v_and_b32_e32 v167, 0xffff0000, v123
	v_lshlrev_b32_e32 v168, 16, v124
	v_and_b32_e32 v169, 0xffff0000, v124
	v_lshlrev_b32_e32 v170, 16, v125
	v_and_b32_e32 v171, 0xffff0000, v125
	v_lshlrev_b32_e32 v172, 16, v126
	v_and_b32_e32 v173, 0xffff0000, v126
	v_lshlrev_b32_e32 v174, 16, v127
	v_and_b32_e32 v175, 0xffff0000, v127
	v_pk_mul_f32 v[252:253], v[160:161], v[160:161]
	v_pk_mul_f32 v[254:255], v[162:163], v[162:163]
	v_pk_fma_f32 v[252:253], v[164:165], v[164:165], v[252:253]
	v_pk_fma_f32 v[254:255], v[166:167], v[166:167], v[254:255]
	v_pk_fma_f32 v[252:253], v[168:169], v[168:169], v[252:253]
	v_pk_fma_f32 v[254:255], v[170:171], v[170:171], v[254:255]
	v_pk_fma_f32 v[252:253], v[172:173], v[172:173], v[252:253]
	v_pk_fma_f32 v[254:255], v[174:175], v[174:175], v[254:255]
	v_pk_add_f32 v[252:253], v[252:253], v[254:255]
	s_nop 0
	v_add_f32_e32 v183, v252, v253
	s_nop 1
	v_add_f32_dpp v183, v183, v183 quad_perm:[1,0,3,2] row_mask:0xf bank_mask:0xf bound_ctrl:1
	s_nop 1
	v_add_f32_dpp v183, v183, v183 quad_perm:[2,3,0,1] row_mask:0xf bank_mask:0xf bound_ctrl:1
	s_nop 1
	v_add_f32_dpp v183, v183, v183 row_half_mirror row_mask:0xf bank_mask:0xf bound_ctrl:1
	s_nop 1
	v_add_f32_dpp v183, v183, v183 row_mirror row_mask:0xf bank_mask:0xf bound_ctrl:1
	s_nop 1
	v_readlane_b32 s98, v183, 0
	v_readlane_b32 s99, v183, 16
	v_readlane_b32 s100, v183, 32
	v_readlane_b32 s101, v183, 48
	s_nop 1
	v_mov_b32_e32 v183, s98
	v_add_f32_e32 v183, s99, v183
	v_add_f32_e32 v183, s100, v183
	v_add_f32_e32 v183, s101, v183
	v_fmamk_f32 v183, v183, 0x3a800000, v182
	v_cmp_gt_f32_e32 vcc, 0x800000, v183
	v_mul_f32_e32 v181, 0x4b800000, v183
	s_nop 1
	v_cndmask_b32_e32 v183, v183, v181, vcc
	v_rsq_f32_e32 v183, v183
	s_nop 0
	v_mul_f32_e32 v181, 0x45800000, v183
	v_cndmask_b32_e32 v184, v183, v181, vcc
	v_mov_b32_e32 v185, v184
	v_pk_mul_f32 v[160:161], v[160:161], v[184:185]
	v_pk_mul_f32 v[162:163], v[162:163], v[184:185]
	v_pk_mul_f32 v[164:165], v[164:165], v[184:185]
	v_pk_mul_f32 v[166:167], v[166:167], v[184:185]
	v_pk_mul_f32 v[168:169], v[168:169], v[184:185]
	v_pk_mul_f32 v[170:171], v[170:171], v[184:185]
	v_pk_mul_f32 v[172:173], v[172:173], v[184:185]
	v_pk_mul_f32 v[174:175], v[174:175], v[184:185]
	v_pk_fma_f32 v[144:145], v[160:161], v[128:129], v[144:145]
	v_pk_fma_f32 v[146:147], v[162:163], v[130:131], v[146:147]
	v_pk_fma_f32 v[148:149], v[164:165], v[132:133], v[148:149]
	v_pk_fma_f32 v[150:151], v[166:167], v[134:135], v[150:151]
	v_pk_fma_f32 v[152:153], v[168:169], v[136:137], v[152:153]
	v_pk_fma_f32 v[154:155], v[170:171], v[138:139], v[154:155]
	v_pk_fma_f32 v[156:157], v[172:173], v[140:141], v[156:157]
	v_pk_fma_f32 v[158:159], v[174:175], v[142:143], v[158:159]
	v_pk_mul_f32 v[252:253], v[144:145], v[144:145]
	v_pk_mul_f32 v[254:255], v[146:147], v[146:147]
	v_pk_fma_f32 v[252:253], v[148:149], v[148:149], v[252:253]
	v_pk_fma_f32 v[254:255], v[150:151], v[150:151], v[254:255]
	v_pk_fma_f32 v[252:253], v[152:153], v[152:153], v[252:253]
	v_pk_fma_f32 v[254:255], v[154:155], v[154:155], v[254:255]
	v_pk_fma_f32 v[252:253], v[156:157], v[156:157], v[252:253]
	v_pk_fma_f32 v[254:255], v[158:159], v[158:159], v[254:255]
	v_pk_add_f32 v[252:253], v[252:253], v[254:255]
	s_nop 0
	v_add_f32_e32 v183, v252, v253
	s_nop 1
	v_add_f32_dpp v183, v183, v183 quad_perm:[1,0,3,2] row_mask:0xf bank_mask:0xf bound_ctrl:1
	s_nop 1
	v_add_f32_dpp v183, v183, v183 quad_perm:[2,3,0,1] row_mask:0xf bank_mask:0xf bound_ctrl:1
	s_nop 1
	v_add_f32_dpp v183, v183, v183 row_half_mirror row_mask:0xf bank_mask:0xf bound_ctrl:1
	s_nop 1
	v_add_f32_dpp v183, v183, v183 row_mirror row_mask:0xf bank_mask:0xf bound_ctrl:1
	s_nop 1
	v_readlane_b32 s98, v183, 0
	v_readlane_b32 s99, v183, 16
	v_readlane_b32 s100, v183, 32
	v_readlane_b32 s101, v183, 48
	s_nop 1
	v_mov_b32_e32 v183, s98
	v_add_f32_e32 v183, s99, v183
	v_add_f32_e32 v183, s100, v183
	v_add_f32_e32 v183, s101, v183
	v_fmamk_f32 v183, v183, 0x3a800000, v182
	v_cmp_gt_f32_e32 vcc, 0x800000, v183
	v_mul_f32_e32 v181, 0x4b800000, v183
	s_nop 1
	v_cndmask_b32_e32 v183, v183, v181, vcc
	v_rsq_f32_e32 v183, v183
	s_nop 0
	v_mul_f32_e32 v181, 0x45800000, v183
	v_cndmask_b32_e32 v184, v183, v181, vcc
	v_mov_b32_e32 v185, v184
	v_cvt_pk_bf16_f32 v112, v144, v145
	v_cvt_pk_bf16_f32 v113, v146, v147
	v_cvt_pk_bf16_f32 v114, v148, v149
	v_cvt_pk_bf16_f32 v115, v150, v151
	v_cvt_pk_bf16_f32 v116, v152, v153
	v_cvt_pk_bf16_f32 v117, v154, v155
	v_cvt_pk_bf16_f32 v118, v156, v157
	v_cvt_pk_bf16_f32 v119, v158, v159
	v_add_u32_e32 v181, 0x3400000, v177
	global_store_dwordx4 v181, v[112:115], s[78:79]
	global_store_dwordx4 v181, v[116:119], s[78:79] offset:1024
	v_add_u32_e32 v236, 0xe000, v237
	s_mov_b64 exec, 1
	global_store_dword v236, v184, s[78:79]
	s_mov_b64 exec, -1
	v_readfirstlane_b32 s98, v179
	s_nop 3
	s_and_b32 s99, s98, 3
	s_add_i32 s100, s99, 4
	s_lshl_b32 s100, s100, 11
	s_sub_i32 s100, s100, s99
	s_lshl_b32 s101, s100, 11
	v_add_u32_e32 v177, s101, v177
	s_lshl_b32 s101, s100, 2
	v_add_u32_e32 v237, s101, v237
	v_add_u32_e32 v181, 0x1800000, v177
	global_load_dwordx4 v[0:3], v181, s[78:79]
	global_load_dwordx4 v[4:7], v181, s[78:79] offset:1024
	v_add_u32_e32 v181, 0x9e00000, v177
	global_load_dwordx4 v[8:11], v181, s[78:79]
	global_load_dwordx4 v[12:15], v181, s[78:79] offset:1024
	s_waitcnt vmcnt(0)
	v_lshlrev_b32_e32 v144, 16, v0
	v_and_b32_e32 v145, 0xffff0000, v0
	v_lshlrev_b32_e32 v146, 16, v1
	v_and_b32_e32 v147, 0xffff0000, v1
	v_lshlrev_b32_e32 v148, 16, v2
	v_and_b32_e32 v149, 0xffff0000, v2
	v_lshlrev_b32_e32 v150, 16, v3
	v_and_b32_e32 v151, 0xffff0000, v3
	v_lshlrev_b32_e32 v152, 16, v4
	v_and_b32_e32 v153, 0xffff0000, v4
	v_lshlrev_b32_e32 v154, 16, v5
	v_and_b32_e32 v155, 0xffff0000, v5
	v_lshlrev_b32_e32 v156, 16, v6
	v_and_b32_e32 v157, 0xffff0000, v6
	v_lshlrev_b32_e32 v158, 16, v7
	v_and_b32_e32 v159, 0xffff0000, v7
	v_lshlrev_b32_e32 v160, 16, v8
	v_and_b32_e32 v161, 0xffff0000, v8
	v_lshlrev_b32_e32 v162, 16, v9
	v_and_b32_e32 v163, 0xffff0000, v9
	v_lshlrev_b32_e32 v164, 16, v10
	v_and_b32_e32 v165, 0xffff0000, v10
	v_lshlrev_b32_e32 v166, 16, v11
	v_and_b32_e32 v167, 0xffff0000, v11
	v_lshlrev_b32_e32 v168, 16, v12
	v_and_b32_e32 v169, 0xffff0000, v12
	v_lshlrev_b32_e32 v170, 16, v13
	v_and_b32_e32 v171, 0xffff0000, v13
	v_lshlrev_b32_e32 v172, 16, v14
	v_and_b32_e32 v173, 0xffff0000, v14
	v_lshlrev_b32_e32 v174, 16, v15
	v_and_b32_e32 v175, 0xffff0000, v15
	v_pk_mul_f32 v[252:253], v[160:161], v[160:161]
	v_pk_mul_f32 v[254:255], v[162:163], v[162:163]
	v_pk_fma_f32 v[252:253], v[164:165], v[164:165], v[252:253]
	v_pk_fma_f32 v[254:255], v[166:167], v[166:167], v[254:255]
	v_pk_fma_f32 v[252:253], v[168:169], v[168:169], v[252:253]
	v_pk_fma_f32 v[254:255], v[170:171], v[170:171], v[254:255]
	v_pk_fma_f32 v[252:253], v[172:173], v[172:173], v[252:253]
	v_pk_fma_f32 v[254:255], v[174:175], v[174:175], v[254:255]
	v_pk_add_f32 v[252:253], v[252:253], v[254:255]
	s_nop 0
	v_add_f32_e32 v183, v252, v253
	s_nop 1
	v_add_f32_dpp v183, v183, v183 quad_perm:[1,0,3,2] row_mask:0xf bank_mask:0xf bound_ctrl:1
	s_nop 1
	v_add_f32_dpp v183, v183, v183 quad_perm:[2,3,0,1] row_mask:0xf bank_mask:0xf bound_ctrl:1
	s_nop 1
	v_add_f32_dpp v183, v183, v183 row_half_mirror row_mask:0xf bank_mask:0xf bound_ctrl:1
	s_nop 1
	v_add_f32_dpp v183, v183, v183 row_mirror row_mask:0xf bank_mask:0xf bound_ctrl:1
	s_nop 1
	v_readlane_b32 s98, v183, 0
	v_readlane_b32 s99, v183, 16
	v_readlane_b32 s100, v183, 32
	v_readlane_b32 s101, v183, 48
	s_nop 1
	v_mov_b32_e32 v183, s98
	v_add_f32_e32 v183, s99, v183
	v_add_f32_e32 v183, s100, v183
	v_add_f32_e32 v183, s101, v183
	v_fmamk_f32 v183, v183, 0x3a800000, v182
	v_cmp_gt_f32_e32 vcc, 0x800000, v183
	v_mul_f32_e32 v181, 0x4b800000, v183
	s_nop 1
	v_cndmask_b32_e32 v183, v183, v181, vcc
	v_rsq_f32_e32 v183, v183
	s_nop 0
	v_mul_f32_e32 v181, 0x45800000, v183
	v_cndmask_b32_e32 v184, v183, v181, vcc
	v_mov_b32_e32 v185, v184
	v_pk_mul_f32 v[160:161], v[160:161], v[184:185]
	v_pk_mul_f32 v[162:163], v[162:163], v[184:185]
	v_pk_mul_f32 v[164:165], v[164:165], v[184:185]
	v_pk_mul_f32 v[166:167], v[166:167], v[184:185]
	v_pk_mul_f32 v[168:169], v[168:169], v[184:185]
	v_pk_mul_f32 v[170:171], v[170:171], v[184:185]
	v_pk_mul_f32 v[172:173], v[172:173], v[184:185]
	v_pk_mul_f32 v[174:175], v[174:175], v[184:185]
	v_pk_fma_f32 v[144:145], v[160:161], v[128:129], v[144:145]
	v_pk_fma_f32 v[146:147], v[162:163], v[130:131], v[146:147]
	v_pk_fma_f32 v[148:149], v[164:165], v[132:133], v[148:149]
	v_pk_fma_f32 v[150:151], v[166:167], v[134:135], v[150:151]
	v_pk_fma_f32 v[152:153], v[168:169], v[136:137], v[152:153]
	v_pk_fma_f32 v[154:155], v[170:171], v[138:139], v[154:155]
	v_pk_fma_f32 v[156:157], v[172:173], v[140:141], v[156:157]
	v_pk_fma_f32 v[158:159], v[174:175], v[142:143], v[158:159]
	v_pk_mul_f32 v[252:253], v[144:145], v[144:145]
	v_pk_mul_f32 v[254:255], v[146:147], v[146:147]
	v_pk_fma_f32 v[252:253], v[148:149], v[148:149], v[252:253]
	v_pk_fma_f32 v[254:255], v[150:151], v[150:151], v[254:255]
	v_pk_fma_f32 v[252:253], v[152:153], v[152:153], v[252:253]
	v_pk_fma_f32 v[254:255], v[154:155], v[154:155], v[254:255]
	v_pk_fma_f32 v[252:253], v[156:157], v[156:157], v[252:253]
	v_pk_fma_f32 v[254:255], v[158:159], v[158:159], v[254:255]
	v_pk_add_f32 v[252:253], v[252:253], v[254:255]
	s_nop 0
	v_add_f32_e32 v183, v252, v253
	s_nop 1
	v_add_f32_dpp v183, v183, v183 quad_perm:[1,0,3,2] row_mask:0xf bank_mask:0xf bound_ctrl:1
	s_nop 1
	v_add_f32_dpp v183, v183, v183 quad_perm:[2,3,0,1] row_mask:0xf bank_mask:0xf bound_ctrl:1
	s_nop 1
	v_add_f32_dpp v183, v183, v183 row_half_mirror row_mask:0xf bank_mask:0xf bound_ctrl:1
	s_nop 1
	v_add_f32_dpp v183, v183, v183 row_mirror row_mask:0xf bank_mask:0xf bound_ctrl:1
	s_nop 1
	v_readlane_b32 s98, v183, 0
	v_readlane_b32 s99, v183, 16
	v_readlane_b32 s100, v183, 32
	v_readlane_b32 s101, v183, 48
	s_nop 1
	v_mov_b32_e32 v183, s98
	v_add_f32_e32 v183, s99, v183
	v_add_f32_e32 v183, s100, v183
	v_add_f32_e32 v183, s101, v183
	v_fmamk_f32 v183, v183, 0x3a800000, v182
	v_cmp_gt_f32_e32 vcc, 0x800000, v183
	v_mul_f32_e32 v181, 0x4b800000, v183
	s_nop 1
	v_cndmask_b32_e32 v183, v183, v181, vcc
	v_rsq_f32_e32 v183, v183
	s_nop 0
	v_mul_f32_e32 v181, 0x45800000, v183
	v_cndmask_b32_e32 v184, v183, v181, vcc
	v_mov_b32_e32 v185, v184
	v_cvt_pk_bf16_f32 v0, v144, v145
	v_cvt_pk_bf16_f32 v1, v146, v147
	v_cvt_pk_bf16_f32 v2, v148, v149
	v_cvt_pk_bf16_f32 v3, v150, v151
	v_cvt_pk_bf16_f32 v4, v152, v153
	v_cvt_pk_bf16_f32 v5, v154, v155
	v_cvt_pk_bf16_f32 v6, v156, v157
	v_cvt_pk_bf16_f32 v7, v158, v159
	v_add_u32_e32 v181, 0x1800000, v177
	global_store_dwordx4 v181, v[0:3], s[78:79]
	global_store_dwordx4 v181, v[4:7], s[78:79] offset:1024
	v_add_u32_e32 v236, 0x0, v237
	s_mov_b64 exec, 1
	global_store_dword v236, v184, s[78:79]
	s_mov_b64 exec, -1
	s_branch .Lmyxupd_done_0
.Lmyxupd_heavy_0:
	global_load_dwordx4 v[0:3], v178, s[78:79]
	global_load_dwordx4 v[4:7], v178, s[78:79] offset:1024
	global_load_dwordx4 v[8:11], v179, s[78:79]
	global_load_dwordx4 v[12:15], v179, s[78:79] offset:1024
	v_add_u32_e32 v178, 0x400000, v178
	v_add_u32_e32 v179, 0x400000, v179
	global_load_dwordx4 v[16:19], v178, s[78:79]
	global_load_dwordx4 v[20:23], v178, s[78:79] offset:1024
	global_load_dwordx4 v[24:27], v179, s[78:79]
	global_load_dwordx4 v[28:31], v179, s[78:79] offset:1024
	v_add_u32_e32 v178, 0x400000, v178
	v_add_u32_e32 v179, 0x400000, v179
	global_load_dwordx4 v[32:35], v178, s[78:79]
	global_load_dwordx4 v[36:39], v178, s[78:79] offset:1024
	global_load_dwordx4 v[40:43], v179, s[78:79]
	global_load_dwordx4 v[44:47], v179, s[78:79] offset:1024
	v_add_u32_e32 v178, 0x400000, v178
	v_add_u32_e32 v179, 0x400000, v179
	global_load_dwordx4 v[48:51], v178, s[78:79]
	global_load_dwordx4 v[52:55], v178, s[78:79] offset:1024
	global_load_dwordx4 v[56:59], v179, s[78:79]
	global_load_dwordx4 v[60:63], v179, s[78:79] offset:1024
	v_add_u32_e32 v178, 0x400000, v178
	v_add_u32_e32 v179, 0x400000, v179
	global_load_dwordx4 v[64:67], v178, s[78:79]
	global_load_dwordx4 v[68:71], v178, s[78:79] offset:1024
	global_load_dwordx4 v[72:75], v179, s[78:79]
	global_load_dwordx4 v[76:79], v179, s[78:79] offset:1024
	v_lshlrev_b32_e32 v237, 2, v183
	v_add_u32_e32 v237, 0x10000, v237
	v_mov_b32_e32 v179, s98
	s_waitcnt vmcnt(16)
	v_lshlrev_b32_e32 v144, 16, v0
	v_and_b32_e32 v145, 0xffff0000, v0
	v_lshlrev_b32_e32 v146, 16, v1
	v_and_b32_e32 v147, 0xffff0000, v1
	v_lshlrev_b32_e32 v148, 16, v2
	v_and_b32_e32 v149, 0xffff0000, v2
	v_lshlrev_b32_e32 v150, 16, v3
	v_and_b32_e32 v151, 0xffff0000, v3
	v_lshlrev_b32_e32 v152, 16, v4
	v_and_b32_e32 v153, 0xffff0000, v4
	v_lshlrev_b32_e32 v154, 16, v5
	v_and_b32_e32 v155, 0xffff0000, v5
	v_lshlrev_b32_e32 v156, 16, v6
	v_and_b32_e32 v157, 0xffff0000, v6
	v_lshlrev_b32_e32 v158, 16, v7
	v_and_b32_e32 v159, 0xffff0000, v7
	v_lshlrev_b32_e32 v160, 16, v8
	v_and_b32_e32 v161, 0xffff0000, v8
	v_lshlrev_b32_e32 v162, 16, v9
	v_and_b32_e32 v163, 0xffff0000, v9
	v_lshlrev_b32_e32 v164, 16, v10
	v_and_b32_e32 v165, 0xffff0000, v10
	v_lshlrev_b32_e32 v166, 16, v11
	v_and_b32_e32 v167, 0xffff0000, v11
	v_lshlrev_b32_e32 v168, 16, v12
	v_and_b32_e32 v169, 0xffff0000, v12
	v_lshlrev_b32_e32 v170, 16, v13
	v_and_b32_e32 v171, 0xffff0000, v13
	v_lshlrev_b32_e32 v172, 16, v14
	v_and_b32_e32 v173, 0xffff0000, v14
	v_lshlrev_b32_e32 v174, 16, v15
	v_and_b32_e32 v175, 0xffff0000, v15
	v_pk_mul_f32 v[252:253], v[160:161], v[160:161]
	v_pk_mul_f32 v[254:255], v[162:163], v[162:163]
	v_pk_fma_f32 v[252:253], v[164:165], v[164:165], v[252:253]
	v_pk_fma_f32 v[254:255], v[166:167], v[166:167], v[254:255]
	v_pk_fma_f32 v[252:253], v[168:169], v[168:169], v[252:253]
	v_pk_fma_f32 v[254:255], v[170:171], v[170:171], v[254:255]
	v_pk_fma_f32 v[252:253], v[172:173], v[172:173], v[252:253]
	v_pk_fma_f32 v[254:255], v[174:175], v[174:175], v[254:255]
	v_pk_add_f32 v[252:253], v[252:253], v[254:255]
	s_nop 0
	v_add_f32_e32 v183, v252, v253
	s_nop 1
	v_add_f32_dpp v183, v183, v183 quad_perm:[1,0,3,2] row_mask:0xf bank_mask:0xf bound_ctrl:1
	s_nop 1
	v_add_f32_dpp v183, v183, v183 quad_perm:[2,3,0,1] row_mask:0xf bank_mask:0xf bound_ctrl:1
	s_nop 1
	v_add_f32_dpp v183, v183, v183 row_half_mirror row_mask:0xf bank_mask:0xf bound_ctrl:1
	s_nop 1
	v_add_f32_dpp v183, v183, v183 row_mirror row_mask:0xf bank_mask:0xf bound_ctrl:1
	s_nop 1
	v_readlane_b32 s98, v183, 0
	v_readlane_b32 s99, v183, 16
	v_readlane_b32 s100, v183, 32
	v_readlane_b32 s101, v183, 48
	s_nop 1
	v_mov_b32_e32 v183, s98
	v_add_f32_e32 v183, s99, v183
	v_add_f32_e32 v183, s100, v183
	v_add_f32_e32 v183, s101, v183
	v_fmamk_f32 v183, v183, 0x3a800000, v182
	v_cmp_gt_f32_e32 vcc, 0x800000, v183
	v_mul_f32_e32 v181, 0x4b800000, v183
	s_nop 1
	v_cndmask_b32_e32 v183, v183, v181, vcc
	v_rsq_f32_e32 v183, v183
	s_nop 0
	v_mul_f32_e32 v181, 0x45800000, v183
	v_cndmask_b32_e32 v184, v183, v181, vcc
	v_mov_b32_e32 v185, v184
	v_pk_mul_f32 v[160:161], v[160:161], v[184:185]
	v_pk_mul_f32 v[162:163], v[162:163], v[184:185]
	v_pk_mul_f32 v[164:165], v[164:165], v[184:185]
	v_pk_mul_f32 v[166:167], v[166:167], v[184:185]
	v_pk_mul_f32 v[168:169], v[168:169], v[184:185]
	v_pk_mul_f32 v[170:171], v[170:171], v[184:185]
	v_pk_mul_f32 v[172:173], v[172:173], v[184:185]
	v_pk_mul_f32 v[174:175], v[174:175], v[184:185]
	v_pk_fma_f32 v[144:145], v[160:161], v[128:129], v[144:145]
	v_pk_fma_f32 v[146:147], v[162:163], v[130:131], v[146:147]
	v_pk_fma_f32 v[148:149], v[164:165], v[132:133], v[148:149]
	v_pk_fma_f32 v[150:151], v[166:167], v[134:135], v[150:151]
	v_pk_fma_f32 v[152:153], v[168:169], v[136:137], v[152:153]
	v_pk_fma_f32 v[154:155], v[170:171], v[138:139], v[154:155]
	v_pk_fma_f32 v[156:157], v[172:173], v[140:141], v[156:157]
	v_pk_fma_f32 v[158:159], v[174:175], v[142:143], v[158:159]
	v_pk_mul_f32 v[252:253], v[144:145], v[144:145]
	v_pk_mul_f32 v[254:255], v[146:147], v[146:147]
	v_pk_fma_f32 v[252:253], v[148:149], v[148:149], v[252:253]
	v_pk_fma_f32 v[254:255], v[150:151], v[150:151], v[254:255]
	v_pk_fma_f32 v[252:253], v[152:153], v[152:153], v[252:253]
	v_pk_fma_f32 v[254:255], v[154:155], v[154:155], v[254:255]
	v_pk_fma_f32 v[252:253], v[156:157], v[156:157], v[252:253]
	v_pk_fma_f32 v[254:255], v[158:159], v[158:159], v[254:255]
	v_pk_add_f32 v[252:253], v[252:253], v[254:255]
	s_nop 0
	v_add_f32_e32 v183, v252, v253
	s_nop 1
	v_add_f32_dpp v183, v183, v183 quad_perm:[1,0,3,2] row_mask:0xf bank_mask:0xf bound_ctrl:1
	s_nop 1
	v_add_f32_dpp v183, v183, v183 quad_perm:[2,3,0,1] row_mask:0xf bank_mask:0xf bound_ctrl:1
	s_nop 1
	v_add_f32_dpp v183, v183, v183 row_half_mirror row_mask:0xf bank_mask:0xf bound_ctrl:1
	s_nop 1
	v_add_f32_dpp v183, v183, v183 row_mirror row_mask:0xf bank_mask:0xf bound_ctrl:1
	s_nop 1
	v_readlane_b32 s98, v183, 0
	v_readlane_b32 s99, v183, 16
	v_readlane_b32 s100, v183, 32
	v_readlane_b32 s101, v183, 48
	s_nop 1
	v_mov_b32_e32 v183, s98
	v_add_f32_e32 v183, s99, v183
	v_add_f32_e32 v183, s100, v183
	v_add_f32_e32 v183, s101, v183
	v_fmamk_f32 v183, v183, 0x3a800000, v182
	v_cmp_gt_f32_e32 vcc, 0x800000, v183
	v_mul_f32_e32 v181, 0x4b800000, v183
	s_nop 1
	v_cndmask_b32_e32 v183, v183, v181, vcc
	v_rsq_f32_e32 v183, v183
	s_nop 0
	v_mul_f32_e32 v181, 0x45800000, v183
	v_cndmask_b32_e32 v184, v183, v181, vcc
	v_mov_b32_e32 v185, v184
	v_cvt_pk_bf16_f32 v0, v144, v145
	v_cvt_pk_bf16_f32 v1, v146, v147
	v_cvt_pk_bf16_f32 v2, v148, v149
	v_cvt_pk_bf16_f32 v3, v150, v151
	v_cvt_pk_bf16_f32 v4, v152, v153
	v_cvt_pk_bf16_f32 v5, v154, v155
	v_cvt_pk_bf16_f32 v6, v156, v157
	v_cvt_pk_bf16_f32 v7, v158, v159
	v_add_u32_e32 v181, 0x1800000, v177
	global_store_dwordx4 v181, v[0:3], s[78:79]
	global_store_dwordx4 v181, v[4:7], s[78:79] offset:1024
	v_add_u32_e32 v236, 0x0, v237
	s_mov_b64 exec, 1
	global_store_dword v236, v184, s[78:79]
	s_mov_b64 exec, -1
	s_waitcnt vmcnt(12)
	v_lshlrev_b32_e32 v144, 16, v16
	v_and_b32_e32 v145, 0xffff0000, v16
	v_lshlrev_b32_e32 v146, 16, v17
	v_and_b32_e32 v147, 0xffff0000, v17
	v_lshlrev_b32_e32 v148, 16, v18
	v_and_b32_e32 v149, 0xffff0000, v18
	v_lshlrev_b32_e32 v150, 16, v19
	v_and_b32_e32 v151, 0xffff0000, v19
	v_lshlrev_b32_e32 v152, 16, v20
	v_and_b32_e32 v153, 0xffff0000, v20
	v_lshlrev_b32_e32 v154, 16, v21
	v_and_b32_e32 v155, 0xffff0000, v21
	v_lshlrev_b32_e32 v156, 16, v22
	v_and_b32_e32 v157, 0xffff0000, v22
	v_lshlrev_b32_e32 v158, 16, v23
	v_and_b32_e32 v159, 0xffff0000, v23
	v_lshlrev_b32_e32 v160, 16, v24
	v_and_b32_e32 v161, 0xffff0000, v24
	v_lshlrev_b32_e32 v162, 16, v25
	v_and_b32_e32 v163, 0xffff0000, v25
	v_lshlrev_b32_e32 v164, 16, v26
	v_and_b32_e32 v165, 0xffff0000, v26
	v_lshlrev_b32_e32 v166, 16, v27
	v_and_b32_e32 v167, 0xffff0000, v27
	v_lshlrev_b32_e32 v168, 16, v28
	v_and_b32_e32 v169, 0xffff0000, v28
	v_lshlrev_b32_e32 v170, 16, v29
	v_and_b32_e32 v171, 0xffff0000, v29
	v_lshlrev_b32_e32 v172, 16, v30
	v_and_b32_e32 v173, 0xffff0000, v30
	v_lshlrev_b32_e32 v174, 16, v31
	v_and_b32_e32 v175, 0xffff0000, v31
	v_pk_mul_f32 v[252:253], v[160:161], v[160:161]
	v_pk_mul_f32 v[254:255], v[162:163], v[162:163]
	v_pk_fma_f32 v[252:253], v[164:165], v[164:165], v[252:253]
	v_pk_fma_f32 v[254:255], v[166:167], v[166:167], v[254:255]
	v_pk_fma_f32 v[252:253], v[168:169], v[168:169], v[252:253]
	v_pk_fma_f32 v[254:255], v[170:171], v[170:171], v[254:255]
	v_pk_fma_f32 v[252:253], v[172:173], v[172:173], v[252:253]
	v_pk_fma_f32 v[254:255], v[174:175], v[174:175], v[254:255]
	v_pk_add_f32 v[252:253], v[252:253], v[254:255]
	s_nop 0
	v_add_f32_e32 v183, v252, v253
	s_nop 1
	v_add_f32_dpp v183, v183, v183 quad_perm:[1,0,3,2] row_mask:0xf bank_mask:0xf bound_ctrl:1
	s_nop 1
	v_add_f32_dpp v183, v183, v183 quad_perm:[2,3,0,1] row_mask:0xf bank_mask:0xf bound_ctrl:1
	s_nop 1
	v_add_f32_dpp v183, v183, v183 row_half_mirror row_mask:0xf bank_mask:0xf bound_ctrl:1
	s_nop 1
	v_add_f32_dpp v183, v183, v183 row_mirror row_mask:0xf bank_mask:0xf bound_ctrl:1
	s_nop 1
	v_readlane_b32 s98, v183, 0
	v_readlane_b32 s99, v183, 16
	v_readlane_b32 s100, v183, 32
	v_readlane_b32 s101, v183, 48
	s_nop 1
	v_mov_b32_e32 v183, s98
	v_add_f32_e32 v183, s99, v183
	v_add_f32_e32 v183, s100, v183
	v_add_f32_e32 v183, s101, v183
	v_fmamk_f32 v183, v183, 0x3a800000, v182
	v_cmp_gt_f32_e32 vcc, 0x800000, v183
	v_mul_f32_e32 v181, 0x4b800000, v183
	s_nop 1
	v_cndmask_b32_e32 v183, v183, v181, vcc
	v_rsq_f32_e32 v183, v183
	s_nop 0
	v_mul_f32_e32 v181, 0x45800000, v183
	v_cndmask_b32_e32 v184, v183, v181, vcc
	v_mov_b32_e32 v185, v184
	v_pk_mul_f32 v[160:161], v[160:161], v[184:185]
	v_pk_mul_f32 v[162:163], v[162:163], v[184:185]
	v_pk_mul_f32 v[164:165], v[164:165], v[184:185]
	v_pk_mul_f32 v[166:167], v[166:167], v[184:185]
	v_pk_mul_f32 v[168:169], v[168:169], v[184:185]
	v_pk_mul_f32 v[170:171], v[170:171], v[184:185]
	v_pk_mul_f32 v[172:173], v[172:173], v[184:185]
	v_pk_mul_f32 v[174:175], v[174:175], v[184:185]
	v_pk_fma_f32 v[144:145], v[160:161], v[128:129], v[144:145]
	v_pk_fma_f32 v[146:147], v[162:163], v[130:131], v[146:147]
	v_pk_fma_f32 v[148:149], v[164:165], v[132:133], v[148:149]
	v_pk_fma_f32 v[150:151], v[166:167], v[134:135], v[150:151]
	v_pk_fma_f32 v[152:153], v[168:169], v[136:137], v[152:153]
	v_pk_fma_f32 v[154:155], v[170:171], v[138:139], v[154:155]
	v_pk_fma_f32 v[156:157], v[172:173], v[140:141], v[156:157]
	v_pk_fma_f32 v[158:159], v[174:175], v[142:143], v[158:159]
	v_pk_mul_f32 v[252:253], v[144:145], v[144:145]
	v_pk_mul_f32 v[254:255], v[146:147], v[146:147]
	v_pk_fma_f32 v[252:253], v[148:149], v[148:149], v[252:253]
	v_pk_fma_f32 v[254:255], v[150:151], v[150:151], v[254:255]
	v_pk_fma_f32 v[252:253], v[152:153], v[152:153], v[252:253]
	v_pk_fma_f32 v[254:255], v[154:155], v[154:155], v[254:255]
	v_pk_fma_f32 v[252:253], v[156:157], v[156:157], v[252:253]
	v_pk_fma_f32 v[254:255], v[158:159], v[158:159], v[254:255]
	v_pk_add_f32 v[252:253], v[252:253], v[254:255]
	s_nop 0
	v_add_f32_e32 v183, v252, v253
	s_nop 1
	v_add_f32_dpp v183, v183, v183 quad_perm:[1,0,3,2] row_mask:0xf bank_mask:0xf bound_ctrl:1
	s_nop 1
	v_add_f32_dpp v183, v183, v183 quad_perm:[2,3,0,1] row_mask:0xf bank_mask:0xf bound_ctrl:1
	s_nop 1
	v_add_f32_dpp v183, v183, v183 row_half_mirror row_mask:0xf bank_mask:0xf bound_ctrl:1
	s_nop 1
	v_add_f32_dpp v183, v183, v183 row_mirror row_mask:0xf bank_mask:0xf bound_ctrl:1
	s_nop 1
	v_readlane_b32 s98, v183, 0
	v_readlane_b32 s99, v183, 16
	v_readlane_b32 s100, v183, 32
	v_readlane_b32 s101, v183, 48
	s_nop 1
	v_mov_b32_e32 v183, s98
	v_add_f32_e32 v183, s99, v183
	v_add_f32_e32 v183, s100, v183
	v_add_f32_e32 v183, s101, v183
	v_fmamk_f32 v183, v183, 0x3a800000, v182
	v_cmp_gt_f32_e32 vcc, 0x800000, v183
	v_mul_f32_e32 v181, 0x4b800000, v183
	s_nop 1
	v_cndmask_b32_e32 v183, v183, v181, vcc
	v_rsq_f32_e32 v183, v183
	s_nop 0
	v_mul_f32_e32 v181, 0x45800000, v183
	v_cndmask_b32_e32 v184, v183, v181, vcc
	v_mov_b32_e32 v185, v184
	v_cvt_pk_bf16_f32 v16, v144, v145
	v_cvt_pk_bf16_f32 v17, v146, v147
	v_cvt_pk_bf16_f32 v18, v148, v149
	v_cvt_pk_bf16_f32 v19, v150, v151
	v_cvt_pk_bf16_f32 v20, v152, v153
	v_cvt_pk_bf16_f32 v21, v154, v155
	v_cvt_pk_bf16_f32 v22, v156, v157
	v_cvt_pk_bf16_f32 v23, v158, v159
	v_add_u32_e32 v181, 0x1c00000, v177
	global_store_dwordx4 v181, v[16:19], s[78:79]
	global_store_dwordx4 v181, v[20:23], s[78:79] offset:1024
	v_add_u32_e32 v236, 0x2000, v237
	s_mov_b64 exec, 1
	global_store_dword v236, v184, s[78:79]
	s_mov_b64 exec, -1
	s_waitcnt vmcnt(8)
	v_lshlrev_b32_e32 v144, 16, v32
	v_and_b32_e32 v145, 0xffff0000, v32
	v_lshlrev_b32_e32 v146, 16, v33
	v_and_b32_e32 v147, 0xffff0000, v33
	v_lshlrev_b32_e32 v148, 16, v34
	v_and_b32_e32 v149, 0xffff0000, v34
	v_lshlrev_b32_e32 v150, 16, v35
	v_and_b32_e32 v151, 0xffff0000, v35
	v_lshlrev_b32_e32 v152, 16, v36
	v_and_b32_e32 v153, 0xffff0000, v36
	v_lshlrev_b32_e32 v154, 16, v37
	v_and_b32_e32 v155, 0xffff0000, v37
	v_lshlrev_b32_e32 v156, 16, v38
	v_and_b32_e32 v157, 0xffff0000, v38
	v_lshlrev_b32_e32 v158, 16, v39
	v_and_b32_e32 v159, 0xffff0000, v39
	v_lshlrev_b32_e32 v160, 16, v40
	v_and_b32_e32 v161, 0xffff0000, v40
	v_lshlrev_b32_e32 v162, 16, v41
	v_and_b32_e32 v163, 0xffff0000, v41
	v_lshlrev_b32_e32 v164, 16, v42
	v_and_b32_e32 v165, 0xffff0000, v42
	v_lshlrev_b32_e32 v166, 16, v43
	v_and_b32_e32 v167, 0xffff0000, v43
	v_lshlrev_b32_e32 v168, 16, v44
	v_and_b32_e32 v169, 0xffff0000, v44
	v_lshlrev_b32_e32 v170, 16, v45
	v_and_b32_e32 v171, 0xffff0000, v45
	v_lshlrev_b32_e32 v172, 16, v46
	v_and_b32_e32 v173, 0xffff0000, v46
	v_lshlrev_b32_e32 v174, 16, v47
	v_and_b32_e32 v175, 0xffff0000, v47
	v_pk_mul_f32 v[252:253], v[160:161], v[160:161]
	v_pk_mul_f32 v[254:255], v[162:163], v[162:163]
	v_pk_fma_f32 v[252:253], v[164:165], v[164:165], v[252:253]
	v_pk_fma_f32 v[254:255], v[166:167], v[166:167], v[254:255]
	v_pk_fma_f32 v[252:253], v[168:169], v[168:169], v[252:253]
	v_pk_fma_f32 v[254:255], v[170:171], v[170:171], v[254:255]
	v_pk_fma_f32 v[252:253], v[172:173], v[172:173], v[252:253]
	v_pk_fma_f32 v[254:255], v[174:175], v[174:175], v[254:255]
	v_pk_add_f32 v[252:253], v[252:253], v[254:255]
	s_nop 0
	v_add_f32_e32 v183, v252, v253
	s_nop 1
	v_add_f32_dpp v183, v183, v183 quad_perm:[1,0,3,2] row_mask:0xf bank_mask:0xf bound_ctrl:1
	s_nop 1
	v_add_f32_dpp v183, v183, v183 quad_perm:[2,3,0,1] row_mask:0xf bank_mask:0xf bound_ctrl:1
	s_nop 1
	v_add_f32_dpp v183, v183, v183 row_half_mirror row_mask:0xf bank_mask:0xf bound_ctrl:1
	s_nop 1
	v_add_f32_dpp v183, v183, v183 row_mirror row_mask:0xf bank_mask:0xf bound_ctrl:1
	s_nop 1
	v_readlane_b32 s98, v183, 0
	v_readlane_b32 s99, v183, 16
	v_readlane_b32 s100, v183, 32
	v_readlane_b32 s101, v183, 48
	s_nop 1
	v_mov_b32_e32 v183, s98
	v_add_f32_e32 v183, s99, v183
	v_add_f32_e32 v183, s100, v183
	v_add_f32_e32 v183, s101, v183
	v_fmamk_f32 v183, v183, 0x3a800000, v182
	v_cmp_gt_f32_e32 vcc, 0x800000, v183
	v_mul_f32_e32 v181, 0x4b800000, v183
	s_nop 1
	v_cndmask_b32_e32 v183, v183, v181, vcc
	v_rsq_f32_e32 v183, v183
	s_nop 0
	v_mul_f32_e32 v181, 0x45800000, v183
	v_cndmask_b32_e32 v184, v183, v181, vcc
	v_mov_b32_e32 v185, v184
	v_pk_mul_f32 v[160:161], v[160:161], v[184:185]
	v_pk_mul_f32 v[162:163], v[162:163], v[184:185]
	v_pk_mul_f32 v[164:165], v[164:165], v[184:185]
	v_pk_mul_f32 v[166:167], v[166:167], v[184:185]
	v_pk_mul_f32 v[168:169], v[168:169], v[184:185]
	v_pk_mul_f32 v[170:171], v[170:171], v[184:185]
	v_pk_mul_f32 v[172:173], v[172:173], v[184:185]
	v_pk_mul_f32 v[174:175], v[174:175], v[184:185]
	v_pk_fma_f32 v[144:145], v[160:161], v[128:129], v[144:145]
	v_pk_fma_f32 v[146:147], v[162:163], v[130:131], v[146:147]
	v_pk_fma_f32 v[148:149], v[164:165], v[132:133], v[148:149]
	v_pk_fma_f32 v[150:151], v[166:167], v[134:135], v[150:151]
	v_pk_fma_f32 v[152:153], v[168:169], v[136:137], v[152:153]
	v_pk_fma_f32 v[154:155], v[170:171], v[138:139], v[154:155]
	v_pk_fma_f32 v[156:157], v[172:173], v[140:141], v[156:157]
	v_pk_fma_f32 v[158:159], v[174:175], v[142:143], v[158:159]
	v_pk_mul_f32 v[252:253], v[144:145], v[144:145]
	v_pk_mul_f32 v[254:255], v[146:147], v[146:147]
	v_pk_fma_f32 v[252:253], v[148:149], v[148:149], v[252:253]
	v_pk_fma_f32 v[254:255], v[150:151], v[150:151], v[254:255]
	v_pk_fma_f32 v[252:253], v[152:153], v[152:153], v[252:253]
	v_pk_fma_f32 v[254:255], v[154:155], v[154:155], v[254:255]
	v_pk_fma_f32 v[252:253], v[156:157], v[156:157], v[252:253]
	v_pk_fma_f32 v[254:255], v[158:159], v[158:159], v[254:255]
	v_pk_add_f32 v[252:253], v[252:253], v[254:255]
	s_nop 0
	v_add_f32_e32 v183, v252, v253
	s_nop 1
	v_add_f32_dpp v183, v183, v183 quad_perm:[1,0,3,2] row_mask:0xf bank_mask:0xf bound_ctrl:1
	s_nop 1
	v_add_f32_dpp v183, v183, v183 quad_perm:[2,3,0,1] row_mask:0xf bank_mask:0xf bound_ctrl:1
	s_nop 1
	v_add_f32_dpp v183, v183, v183 row_half_mirror row_mask:0xf bank_mask:0xf bound_ctrl:1
	s_nop 1
	v_add_f32_dpp v183, v183, v183 row_mirror row_mask:0xf bank_mask:0xf bound_ctrl:1
	s_nop 1
	v_readlane_b32 s98, v183, 0
	v_readlane_b32 s99, v183, 16
	v_readlane_b32 s100, v183, 32
	v_readlane_b32 s101, v183, 48
	s_nop 1
	v_mov_b32_e32 v183, s98
	v_add_f32_e32 v183, s99, v183
	v_add_f32_e32 v183, s100, v183
	v_add_f32_e32 v183, s101, v183
	v_fmamk_f32 v183, v183, 0x3a800000, v182
	v_cmp_gt_f32_e32 vcc, 0x800000, v183
	v_mul_f32_e32 v181, 0x4b800000, v183
	s_nop 1
	v_cndmask_b32_e32 v183, v183, v181, vcc
	v_rsq_f32_e32 v183, v183
	s_nop 0
	v_mul_f32_e32 v181, 0x45800000, v183
	v_cndmask_b32_e32 v184, v183, v181, vcc
	v_mov_b32_e32 v185, v184
	v_cvt_pk_bf16_f32 v32, v144, v145
	v_cvt_pk_bf16_f32 v33, v146, v147
	v_cvt_pk_bf16_f32 v34, v148, v149
	v_cvt_pk_bf16_f32 v35, v150, v151
	v_cvt_pk_bf16_f32 v36, v152, v153
	v_cvt_pk_bf16_f32 v37, v154, v155
	v_cvt_pk_bf16_f32 v38, v156, v157
	v_cvt_pk_bf16_f32 v39, v158, v159
	v_add_u32_e32 v181, 0x2000000, v177
	global_store_dwordx4 v181, v[32:35], s[78:79]
	global_store_dwordx4 v181, v[36:39], s[78:79] offset:1024
	v_add_u32_e32 v236, 0x4000, v237
	s_mov_b64 exec, 1
	global_store_dword v236, v184, s[78:79]
	s_mov_b64 exec, -1
	s_waitcnt vmcnt(4)
	v_lshlrev_b32_e32 v144, 16, v48
	v_and_b32_e32 v145, 0xffff0000, v48
	v_lshlrev_b32_e32 v146, 16, v49
	v_and_b32_e32 v147, 0xffff0000, v49
	v_lshlrev_b32_e32 v148, 16, v50
	v_and_b32_e32 v149, 0xffff0000, v50
	v_lshlrev_b32_e32 v150, 16, v51
	v_and_b32_e32 v151, 0xffff0000, v51
	v_lshlrev_b32_e32 v152, 16, v52
	v_and_b32_e32 v153, 0xffff0000, v52
	v_lshlrev_b32_e32 v154, 16, v53
	v_and_b32_e32 v155, 0xffff0000, v53
	v_lshlrev_b32_e32 v156, 16, v54
	v_and_b32_e32 v157, 0xffff0000, v54
	v_lshlrev_b32_e32 v158, 16, v55
	v_and_b32_e32 v159, 0xffff0000, v55
	v_lshlrev_b32_e32 v160, 16, v56
	v_and_b32_e32 v161, 0xffff0000, v56
	v_lshlrev_b32_e32 v162, 16, v57
	v_and_b32_e32 v163, 0xffff0000, v57
	v_lshlrev_b32_e32 v164, 16, v58
	v_and_b32_e32 v165, 0xffff0000, v58
	v_lshlrev_b32_e32 v166, 16, v59
	v_and_b32_e32 v167, 0xffff0000, v59
	v_lshlrev_b32_e32 v168, 16, v60
	v_and_b32_e32 v169, 0xffff0000, v60
	v_lshlrev_b32_e32 v170, 16, v61
	v_and_b32_e32 v171, 0xffff0000, v61
	v_lshlrev_b32_e32 v172, 16, v62
	v_and_b32_e32 v173, 0xffff0000, v62
	v_lshlrev_b32_e32 v174, 16, v63
	v_and_b32_e32 v175, 0xffff0000, v63
	v_pk_mul_f32 v[252:253], v[160:161], v[160:161]
	v_pk_mul_f32 v[254:255], v[162:163], v[162:163]
	v_pk_fma_f32 v[252:253], v[164:165], v[164:165], v[252:253]
	v_pk_fma_f32 v[254:255], v[166:167], v[166:167], v[254:255]
	v_pk_fma_f32 v[252:253], v[168:169], v[168:169], v[252:253]
	v_pk_fma_f32 v[254:255], v[170:171], v[170:171], v[254:255]
	v_pk_fma_f32 v[252:253], v[172:173], v[172:173], v[252:253]
	v_pk_fma_f32 v[254:255], v[174:175], v[174:175], v[254:255]
	v_pk_add_f32 v[252:253], v[252:253], v[254:255]
	s_nop 0
	v_add_f32_e32 v183, v252, v253
	s_nop 1
	v_add_f32_dpp v183, v183, v183 quad_perm:[1,0,3,2] row_mask:0xf bank_mask:0xf bound_ctrl:1
	s_nop 1
	v_add_f32_dpp v183, v183, v183 quad_perm:[2,3,0,1] row_mask:0xf bank_mask:0xf bound_ctrl:1
	s_nop 1
	v_add_f32_dpp v183, v183, v183 row_half_mirror row_mask:0xf bank_mask:0xf bound_ctrl:1
	s_nop 1
	v_add_f32_dpp v183, v183, v183 row_mirror row_mask:0xf bank_mask:0xf bound_ctrl:1
	s_nop 1
	v_readlane_b32 s98, v183, 0
	v_readlane_b32 s99, v183, 16
	v_readlane_b32 s100, v183, 32
	v_readlane_b32 s101, v183, 48
	s_nop 1
	v_mov_b32_e32 v183, s98
	v_add_f32_e32 v183, s99, v183
	v_add_f32_e32 v183, s100, v183
	v_add_f32_e32 v183, s101, v183
	v_fmamk_f32 v183, v183, 0x3a800000, v182
	v_cmp_gt_f32_e32 vcc, 0x800000, v183
	v_mul_f32_e32 v181, 0x4b800000, v183
	s_nop 1
	v_cndmask_b32_e32 v183, v183, v181, vcc
	v_rsq_f32_e32 v183, v183
	s_nop 0
	v_mul_f32_e32 v181, 0x45800000, v183
	v_cndmask_b32_e32 v184, v183, v181, vcc
	v_mov_b32_e32 v185, v184
	v_pk_mul_f32 v[160:161], v[160:161], v[184:185]
	v_pk_mul_f32 v[162:163], v[162:163], v[184:185]
	v_pk_mul_f32 v[164:165], v[164:165], v[184:185]
	v_pk_mul_f32 v[166:167], v[166:167], v[184:185]
	v_pk_mul_f32 v[168:169], v[168:169], v[184:185]
	v_pk_mul_f32 v[170:171], v[170:171], v[184:185]
	v_pk_mul_f32 v[172:173], v[172:173], v[184:185]
	v_pk_mul_f32 v[174:175], v[174:175], v[184:185]
	v_pk_fma_f32 v[144:145], v[160:161], v[128:129], v[144:145]
	v_pk_fma_f32 v[146:147], v[162:163], v[130:131], v[146:147]
	v_pk_fma_f32 v[148:149], v[164:165], v[132:133], v[148:149]
	v_pk_fma_f32 v[150:151], v[166:167], v[134:135], v[150:151]
	v_pk_fma_f32 v[152:153], v[168:169], v[136:137], v[152:153]
	v_pk_fma_f32 v[154:155], v[170:171], v[138:139], v[154:155]
	v_pk_fma_f32 v[156:157], v[172:173], v[140:141], v[156:157]
	v_pk_fma_f32 v[158:159], v[174:175], v[142:143], v[158:159]
	v_pk_mul_f32 v[252:253], v[144:145], v[144:145]
	v_pk_mul_f32 v[254:255], v[146:147], v[146:147]
	v_pk_fma_f32 v[252:253], v[148:149], v[148:149], v[252:253]
	v_pk_fma_f32 v[254:255], v[150:151], v[150:151], v[254:255]
	v_pk_fma_f32 v[252:253], v[152:153], v[152:153], v[252:253]
	v_pk_fma_f32 v[254:255], v[154:155], v[154:155], v[254:255]
	v_pk_fma_f32 v[252:253], v[156:157], v[156:157], v[252:253]
	v_pk_fma_f32 v[254:255], v[158:159], v[158:159], v[254:255]
	v_pk_add_f32 v[252:253], v[252:253], v[254:255]
	s_nop 0
	v_add_f32_e32 v183, v252, v253
	s_nop 1
	v_add_f32_dpp v183, v183, v183 quad_perm:[1,0,3,2] row_mask:0xf bank_mask:0xf bound_ctrl:1
	s_nop 1
	v_add_f32_dpp v183, v183, v183 quad_perm:[2,3,0,1] row_mask:0xf bank_mask:0xf bound_ctrl:1
	s_nop 1
	v_add_f32_dpp v183, v183, v183 row_half_mirror row_mask:0xf bank_mask:0xf bound_ctrl:1
	s_nop 1
	v_add_f32_dpp v183, v183, v183 row_mirror row_mask:0xf bank_mask:0xf bound_ctrl:1
	s_nop 1
	v_readlane_b32 s98, v183, 0
	v_readlane_b32 s99, v183, 16
	v_readlane_b32 s100, v183, 32
	v_readlane_b32 s101, v183, 48
	s_nop 1
	v_mov_b32_e32 v183, s98
	v_add_f32_e32 v183, s99, v183
	v_add_f32_e32 v183, s100, v183
	v_add_f32_e32 v183, s101, v183
	v_fmamk_f32 v183, v183, 0x3a800000, v182
	v_cmp_gt_f32_e32 vcc, 0x800000, v183
	v_mul_f32_e32 v181, 0x4b800000, v183
	s_nop 1
	v_cndmask_b32_e32 v183, v183, v181, vcc
	v_rsq_f32_e32 v183, v183
	s_nop 0
	v_mul_f32_e32 v181, 0x45800000, v183
	v_cndmask_b32_e32 v184, v183, v181, vcc
	v_mov_b32_e32 v185, v184
	v_cvt_pk_bf16_f32 v48, v144, v145
	v_cvt_pk_bf16_f32 v49, v146, v147
	v_cvt_pk_bf16_f32 v50, v148, v149
	v_cvt_pk_bf16_f32 v51, v150, v151
	v_cvt_pk_bf16_f32 v52, v152, v153
	v_cvt_pk_bf16_f32 v53, v154, v155
	v_cvt_pk_bf16_f32 v54, v156, v157
	v_cvt_pk_bf16_f32 v55, v158, v159
	v_add_u32_e32 v181, 0x2400000, v177
	global_store_dwordx4 v181, v[48:51], s[78:79]
	global_store_dwordx4 v181, v[52:55], s[78:79] offset:1024
	v_add_u32_e32 v236, 0x6000, v237
	s_mov_b64 exec, 1
	global_store_dword v236, v184, s[78:79]
	s_mov_b64 exec, -1
	s_waitcnt vmcnt(0)
	v_lshlrev_b32_e32 v144, 16, v64
	v_and_b32_e32 v145, 0xffff0000, v64
	v_lshlrev_b32_e32 v146, 16, v65
	v_and_b32_e32 v147, 0xffff0000, v65
	v_lshlrev_b32_e32 v148, 16, v66
	v_and_b32_e32 v149, 0xffff0000, v66
	v_lshlrev_b32_e32 v150, 16, v67
	v_and_b32_e32 v151, 0xffff0000, v67
	v_lshlrev_b32_e32 v152, 16, v68
	v_and_b32_e32 v153, 0xffff0000, v68
	v_lshlrev_b32_e32 v154, 16, v69
	v_and_b32_e32 v155, 0xffff0000, v69
	v_lshlrev_b32_e32 v156, 16, v70
	v_and_b32_e32 v157, 0xffff0000, v70
	v_lshlrev_b32_e32 v158, 16, v71
	v_and_b32_e32 v159, 0xffff0000, v71
	v_lshlrev_b32_e32 v160, 16, v72
	v_and_b32_e32 v161, 0xffff0000, v72
	v_lshlrev_b32_e32 v162, 16, v73
	v_and_b32_e32 v163, 0xffff0000, v73
	v_lshlrev_b32_e32 v164, 16, v74
	v_and_b32_e32 v165, 0xffff0000, v74
	v_lshlrev_b32_e32 v166, 16, v75
	v_and_b32_e32 v167, 0xffff0000, v75
	v_lshlrev_b32_e32 v168, 16, v76
	v_and_b32_e32 v169, 0xffff0000, v76
	v_lshlrev_b32_e32 v170, 16, v77
	v_and_b32_e32 v171, 0xffff0000, v77
	v_lshlrev_b32_e32 v172, 16, v78
	v_and_b32_e32 v173, 0xffff0000, v78
	v_lshlrev_b32_e32 v174, 16, v79
	v_and_b32_e32 v175, 0xffff0000, v79
	v_pk_mul_f32 v[252:253], v[160:161], v[160:161]
	v_pk_mul_f32 v[254:255], v[162:163], v[162:163]
	v_pk_fma_f32 v[252:253], v[164:165], v[164:165], v[252:253]
	v_pk_fma_f32 v[254:255], v[166:167], v[166:167], v[254:255]
	v_pk_fma_f32 v[252:253], v[168:169], v[168:169], v[252:253]
	v_pk_fma_f32 v[254:255], v[170:171], v[170:171], v[254:255]
	v_pk_fma_f32 v[252:253], v[172:173], v[172:173], v[252:253]
	v_pk_fma_f32 v[254:255], v[174:175], v[174:175], v[254:255]
	v_pk_add_f32 v[252:253], v[252:253], v[254:255]
	s_nop 0
	v_add_f32_e32 v183, v252, v253
	s_nop 1
	v_add_f32_dpp v183, v183, v183 quad_perm:[1,0,3,2] row_mask:0xf bank_mask:0xf bound_ctrl:1
	s_nop 1
	v_add_f32_dpp v183, v183, v183 quad_perm:[2,3,0,1] row_mask:0xf bank_mask:0xf bound_ctrl:1
	s_nop 1
	v_add_f32_dpp v183, v183, v183 row_half_mirror row_mask:0xf bank_mask:0xf bound_ctrl:1
	s_nop 1
	v_add_f32_dpp v183, v183, v183 row_mirror row_mask:0xf bank_mask:0xf bound_ctrl:1
	s_nop 1
	v_readlane_b32 s98, v183, 0
	v_readlane_b32 s99, v183, 16
	v_readlane_b32 s100, v183, 32
	v_readlane_b32 s101, v183, 48
	s_nop 1
	v_mov_b32_e32 v183, s98
	v_add_f32_e32 v183, s99, v183
	v_add_f32_e32 v183, s100, v183
	v_add_f32_e32 v183, s101, v183
	v_fmamk_f32 v183, v183, 0x3a800000, v182
	v_cmp_gt_f32_e32 vcc, 0x800000, v183
	v_mul_f32_e32 v181, 0x4b800000, v183
	s_nop 1
	v_cndmask_b32_e32 v183, v183, v181, vcc
	v_rsq_f32_e32 v183, v183
	s_nop 0
	v_mul_f32_e32 v181, 0x45800000, v183
	v_cndmask_b32_e32 v184, v183, v181, vcc
	v_mov_b32_e32 v185, v184
	v_pk_mul_f32 v[160:161], v[160:161], v[184:185]
	v_pk_mul_f32 v[162:163], v[162:163], v[184:185]
	v_pk_mul_f32 v[164:165], v[164:165], v[184:185]
	v_pk_mul_f32 v[166:167], v[166:167], v[184:185]
	v_pk_mul_f32 v[168:169], v[168:169], v[184:185]
	v_pk_mul_f32 v[170:171], v[170:171], v[184:185]
	v_pk_mul_f32 v[172:173], v[172:173], v[184:185]
	v_pk_mul_f32 v[174:175], v[174:175], v[184:185]
	v_pk_fma_f32 v[144:145], v[160:161], v[128:129], v[144:145]
	v_pk_fma_f32 v[146:147], v[162:163], v[130:131], v[146:147]
	v_pk_fma_f32 v[148:149], v[164:165], v[132:133], v[148:149]
	v_pk_fma_f32 v[150:151], v[166:167], v[134:135], v[150:151]
	v_pk_fma_f32 v[152:153], v[168:169], v[136:137], v[152:153]
	v_pk_fma_f32 v[154:155], v[170:171], v[138:139], v[154:155]
	v_pk_fma_f32 v[156:157], v[172:173], v[140:141], v[156:157]
	v_pk_fma_f32 v[158:159], v[174:175], v[142:143], v[158:159]
	v_pk_mul_f32 v[252:253], v[144:145], v[144:145]
	v_pk_mul_f32 v[254:255], v[146:147], v[146:147]
	v_pk_fma_f32 v[252:253], v[148:149], v[148:149], v[252:253]
	v_pk_fma_f32 v[254:255], v[150:151], v[150:151], v[254:255]
	v_pk_fma_f32 v[252:253], v[152:153], v[152:153], v[252:253]
	v_pk_fma_f32 v[254:255], v[154:155], v[154:155], v[254:255]
	v_pk_fma_f32 v[252:253], v[156:157], v[156:157], v[252:253]
	v_pk_fma_f32 v[254:255], v[158:159], v[158:159], v[254:255]
	v_pk_add_f32 v[252:253], v[252:253], v[254:255]
	s_nop 0
	v_add_f32_e32 v183, v252, v253
	s_nop 1
	v_add_f32_dpp v183, v183, v183 quad_perm:[1,0,3,2] row_mask:0xf bank_mask:0xf bound_ctrl:1
	s_nop 1
	v_add_f32_dpp v183, v183, v183 quad_perm:[2,3,0,1] row_mask:0xf bank_mask:0xf bound_ctrl:1
	s_nop 1
	v_add_f32_dpp v183, v183, v183 row_half_mirror row_mask:0xf bank_mask:0xf bound_ctrl:1
	s_nop 1
	v_add_f32_dpp v183, v183, v183 row_mirror row_mask:0xf bank_mask:0xf bound_ctrl:1
	s_nop 1
	v_readlane_b32 s98, v183, 0
	v_readlane_b32 s99, v183, 16
	v_readlane_b32 s100, v183, 32
	v_readlane_b32 s101, v183, 48
	s_nop 1
	v_mov_b32_e32 v183, s98
	v_add_f32_e32 v183, s99, v183
	v_add_f32_e32 v183, s100, v183
	v_add_f32_e32 v183, s101, v183
	v_fmamk_f32 v183, v183, 0x3a800000, v182
	v_cmp_gt_f32_e32 vcc, 0x800000, v183
	v_mul_f32_e32 v181, 0x4b800000, v183
	s_nop 1
	v_cndmask_b32_e32 v183, v183, v181, vcc
	v_rsq_f32_e32 v183, v183
	s_nop 0
	v_mul_f32_e32 v181, 0x45800000, v183
	v_cndmask_b32_e32 v184, v183, v181, vcc
	v_mov_b32_e32 v185, v184
	v_cvt_pk_bf16_f32 v64, v144, v145
	v_cvt_pk_bf16_f32 v65, v146, v147
	v_cvt_pk_bf16_f32 v66, v148, v149
	v_cvt_pk_bf16_f32 v67, v150, v151
	v_cvt_pk_bf16_f32 v68, v152, v153
	v_cvt_pk_bf16_f32 v69, v154, v155
	v_cvt_pk_bf16_f32 v70, v156, v157
	v_cvt_pk_bf16_f32 v71, v158, v159
	v_add_u32_e32 v181, 0x2800000, v177
	global_store_dwordx4 v181, v[64:67], s[78:79]
	global_store_dwordx4 v181, v[68:71], s[78:79] offset:1024
	v_add_u32_e32 v236, 0x8000, v237
	s_mov_b64 exec, 1
	global_store_dword v236, v184, s[78:79]
	s_mov_b64 exec, -1
	v_readfirstlane_b32 s98, v179
	s_nop 3
	s_and_b32 s99, s98, 3
	s_cmp_lg_u32 s99, 0
	s_cbranch_scc1 .Lmyxupd_done_0
	v_lshrrev_b32_e32 v179, 2, v179
	v_lshlrev_b32_e32 v177, 4, v176
	v_lshl_add_u32 v177, v179, 11, v177
	v_lshlrev_b32_e32 v237, 2, v179
	v_add_u32_e32 v237, 0x10000, v237
	v_add_u32_e32 v181, 0x3800000, v177
	global_load_dwordx4 v[240:243], v181, s[78:79]
	global_load_dwordx4 v[244:247], v181, s[78:79] offset:1024
	v_lshl_add_u32 v183, v179, 12, v180
	v_add_u32_e32 v183, 0xbf00000, v183
	v_add_u32_e32 v181, 0x0, v183
	global_load_dwordx4 v[0:3], v181, s[78:79]
	global_load_dwordx4 v[4:7], v181, s[78:79] offset:16
	global_load_dwordx4 v[8:11], v181, s[78:79] offset:2048
	global_load_dwordx4 v[12:15], v181, s[78:79] offset:2064
	v_add_u32_e32 v181, 0x200000, v183
	global_load_dwordx4 v[16:19], v181, s[78:79]
	global_load_dwordx4 v[20:23], v181, s[78:79] offset:16
	global_load_dwordx4 v[24:27], v181, s[78:79] offset:2048
	global_load_dwordx4 v[28:31], v181, s[78:79] offset:2064
	v_add_u32_e32 v181, 0x400000, v183
	global_load_dwordx4 v[32:35], v181, s[78:79]
	global_load_dwordx4 v[36:39], v181, s[78:79] offset:16
	global_load_dwordx4 v[40:43], v181, s[78:79] offset:2048
	global_load_dwordx4 v[44:47], v181, s[78:79] offset:2064
	v_add_u32_e32 v181, 0x600000, v183
	global_load_dwordx4 v[48:51], v181, s[78:79]
	global_load_dwordx4 v[52:55], v181, s[78:79] offset:16
	global_load_dwordx4 v[56:59], v181, s[78:79] offset:2048
	global_load_dwordx4 v[60:63], v181, s[78:79] offset:2064
	v_add_u32_e32 v181, 0x800000, v183
	global_load_dwordx4 v[64:67], v181, s[78:79]
	global_load_dwordx4 v[68:71], v181, s[78:79] offset:16
	global_load_dwordx4 v[72:75], v181, s[78:79] offset:2048
	global_load_dwordx4 v[76:79], v181, s[78:79] offset:2064
	v_add_u32_e32 v181, 0xa00000, v183
	global_load_dwordx4 v[80:83], v181, s[78:79]
	global_load_dwordx4 v[84:87], v181, s[78:79] offset:16
	global_load_dwordx4 v[88:91], v181, s[78:79] offset:2048
	global_load_dwordx4 v[92:95], v181, s[78:79] offset:2064
	v_add_u32_e32 v181, 0xc00000, v183
	global_load_dwordx4 v[96:99], v181, s[78:79]
	global_load_dwordx4 v[100:103], v181, s[78:79] offset:16
	global_load_dwordx4 v[104:107], v181, s[78:79] offset:2048
	global_load_dwordx4 v[108:111], v181, s[78:79] offset:2064
	v_add_u32_e32 v181, 0xe00000, v183
	global_load_dwordx4 v[112:115], v181, s[78:79]
	global_load_dwordx4 v[116:119], v181, s[78:79] offset:16
	global_load_dwordx4 v[120:123], v181, s[78:79] offset:2048
	global_load_dwordx4 v[124:127], v181, s[78:79] offset:2064
	s_waitcnt vmcnt(28)
	v_pk_add_f32 v[160:161], v[0:1], 0 op_sel_hi:[1,0]
	v_pk_add_f32 v[162:163], v[2:3], 0 op_sel_hi:[1,0]
	v_pk_add_f32 v[164:165], v[4:5], 0 op_sel_hi:[1,0]
	v_pk_add_f32 v[166:167], v[6:7], 0 op_sel_hi:[1,0]
	v_pk_add_f32 v[168:169], v[8:9], 0 op_sel_hi:[1,0]
	v_pk_add_f32 v[170:171], v[10:11], 0 op_sel_hi:[1,0]
	v_pk_add_f32 v[172:173], v[12:13], 0 op_sel_hi:[1,0]
	v_pk_add_f32 v[174:175], v[14:15], 0 op_sel_hi:[1,0]
	s_waitcnt vmcnt(24)
	v_pk_add_f32 v[160:161], v[160:161], v[16:17]
	v_pk_add_f32 v[162:163], v[162:163], v[18:19]
	v_pk_add_f32 v[164:165], v[164:165], v[20:21]
	v_pk_add_f32 v[166:167], v[166:167], v[22:23]
	v_pk_add_f32 v[168:169], v[168:169], v[24:25]
	v_pk_add_f32 v[170:171], v[170:171], v[26:27]
	v_pk_add_f32 v[172:173], v[172:173], v[28:29]
	v_pk_add_f32 v[174:175], v[174:175], v[30:31]
	s_waitcnt vmcnt(20)
	v_pk_add_f32 v[160:161], v[160:161], v[32:33]
	v_pk_add_f32 v[162:163], v[162:163], v[34:35]
	v_pk_add_f32 v[164:165], v[164:165], v[36:37]
	v_pk_add_f32 v[166:167], v[166:167], v[38:39]
	v_pk_add_f32 v[168:169], v[168:169], v[40:41]
	v_pk_add_f32 v[170:171], v[170:171], v[42:43]
	v_pk_add_f32 v[172:173], v[172:173], v[44:45]
	v_pk_add_f32 v[174:175], v[174:175], v[46:47]
	s_waitcnt vmcnt(16)
	v_pk_add_f32 v[160:161], v[160:161], v[48:49]
	v_pk_add_f32 v[162:163], v[162:163], v[50:51]
	v_pk_add_f32 v[164:165], v[164:165], v[52:53]
	v_pk_add_f32 v[166:167], v[166:167], v[54:55]
	v_pk_add_f32 v[168:169], v[168:169], v[56:57]
	v_pk_add_f32 v[170:171], v[170:171], v[58:59]
	v_pk_add_f32 v[172:173], v[172:173], v[60:61]
	v_pk_add_f32 v[174:175], v[174:175], v[62:63]
	s_waitcnt vmcnt(12)
	v_pk_add_f32 v[160:161], v[160:161], v[64:65]
	v_pk_add_f32 v[162:163], v[162:163], v[66:67]
	v_pk_add_f32 v[164:165], v[164:165], v[68:69]
	v_pk_add_f32 v[166:167], v[166:167], v[70:71]
	v_pk_add_f32 v[168:169], v[168:169], v[72:73]
	v_pk_add_f32 v[170:171], v[170:171], v[74:75]
	v_pk_add_f32 v[172:173], v[172:173], v[76:77]
	v_pk_add_f32 v[174:175], v[174:175], v[78:79]
	s_waitcnt vmcnt(8)
	v_pk_add_f32 v[160:161], v[160:161], v[80:81]
	v_pk_add_f32 v[162:163], v[162:163], v[82:83]
	v_pk_add_f32 v[164:165], v[164:165], v[84:85]
	v_pk_add_f32 v[166:167], v[166:167], v[86:87]
	v_pk_add_f32 v[168:169], v[168:169], v[88:89]
	v_pk_add_f32 v[170:171], v[170:171], v[90:91]
	v_pk_add_f32 v[172:173], v[172:173], v[92:93]
	v_pk_add_f32 v[174:175], v[174:175], v[94:95]
	s_waitcnt vmcnt(4)
	v_pk_add_f32 v[160:161], v[160:161], v[96:97]
	v_pk_add_f32 v[162:163], v[162:163], v[98:99]
	v_pk_add_f32 v[164:165], v[164:165], v[100:101]
	v_pk_add_f32 v[166:167], v[166:167], v[102:103]
	v_pk_add_f32 v[168:169], v[168:169], v[104:105]
	v_pk_add_f32 v[170:171], v[170:171], v[106:107]
	v_pk_add_f32 v[172:173], v[172:173], v[108:109]
	v_pk_add_f32 v[174:175], v[174:175], v[110:111]
	s_waitcnt vmcnt(0)
	v_pk_add_f32 v[160:161], v[160:161], v[112:113]
	v_pk_add_f32 v[162:163], v[162:163], v[114:115]
	v_pk_add_f32 v[164:165], v[164:165], v[116:117]
	v_pk_add_f32 v[166:167], v[166:167], v[118:119]
	v_pk_add_f32 v[168:169], v[168:169], v[120:121]
	v_pk_add_f32 v[170:171], v[170:171], v[122:123]
	v_pk_add_f32 v[172:173], v[172:173], v[124:125]
	v_pk_add_f32 v[174:175], v[174:175], v[126:127]
	v_lshlrev_b32_e32 v144, 16, v240
	v_and_b32_e32 v145, 0xffff0000, v240
	v_lshlrev_b32_e32 v146, 16, v241
	v_and_b32_e32 v147, 0xffff0000, v241
	v_lshlrev_b32_e32 v148, 16, v242
	v_and_b32_e32 v149, 0xffff0000, v242
	v_lshlrev_b32_e32 v150, 16, v243
	v_and_b32_e32 v151, 0xffff0000, v243
	v_lshlrev_b32_e32 v152, 16, v244
	v_and_b32_e32 v153, 0xffff0000, v244
	v_lshlrev_b32_e32 v154, 16, v245
	v_and_b32_e32 v155, 0xffff0000, v245
	v_lshlrev_b32_e32 v156, 16, v246
	v_and_b32_e32 v157, 0xffff0000, v246
	v_lshlrev_b32_e32 v158, 16, v247
	v_and_b32_e32 v159, 0xffff0000, v247
	v_pk_mul_f32 v[252:253], v[160:161], v[160:161]
	v_pk_mul_f32 v[254:255], v[162:163], v[162:163]
	v_pk_fma_f32 v[252:253], v[164:165], v[164:165], v[252:253]
	v_pk_fma_f32 v[254:255], v[166:167], v[166:167], v[254:255]
	v_pk_fma_f32 v[252:253], v[168:169], v[168:169], v[252:253]
	v_pk_fma_f32 v[254:255], v[170:171], v[170:171], v[254:255]
	v_pk_fma_f32 v[252:253], v[172:173], v[172:173], v[252:253]
	v_pk_fma_f32 v[254:255], v[174:175], v[174:175], v[254:255]
	v_pk_add_f32 v[252:253], v[252:253], v[254:255]
	s_nop 0
	v_add_f32_e32 v183, v252, v253
	s_nop 1
	v_add_f32_dpp v183, v183, v183 quad_perm:[1,0,3,2] row_mask:0xf bank_mask:0xf bound_ctrl:1
	s_nop 1
	v_add_f32_dpp v183, v183, v183 quad_perm:[2,3,0,1] row_mask:0xf bank_mask:0xf bound_ctrl:1
	s_nop 1
	v_add_f32_dpp v183, v183, v183 row_half_mirror row_mask:0xf bank_mask:0xf bound_ctrl:1
	s_nop 1
	v_add_f32_dpp v183, v183, v183 row_mirror row_mask:0xf bank_mask:0xf bound_ctrl:1
	s_nop 1
	v_readlane_b32 s98, v183, 0
	v_readlane_b32 s99, v183, 16
	v_readlane_b32 s100, v183, 32
	v_readlane_b32 s101, v183, 48
	s_nop 1
	v_mov_b32_e32 v183, s98
	v_add_f32_e32 v183, s99, v183
	v_add_f32_e32 v183, s100, v183
	v_add_f32_e32 v183, s101, v183
	v_fmamk_f32 v183, v183, 0x3a800000, v182
	v_cmp_gt_f32_e32 vcc, 0x800000, v183
	v_mul_f32_e32 v181, 0x4b800000, v183
	s_nop 1
	v_cndmask_b32_e32 v183, v183, v181, vcc
	v_rsq_f32_e32 v183, v183
	s_nop 0
	v_mul_f32_e32 v181, 0x45800000, v183
	v_cndmask_b32_e32 v184, v183, v181, vcc
	v_mov_b32_e32 v185, v184
	v_pk_mul_f32 v[160:161], v[160:161], v[184:185]
	v_pk_mul_f32 v[162:163], v[162:163], v[184:185]
	v_pk_mul_f32 v[164:165], v[164:165], v[184:185]
	v_pk_mul_f32 v[166:167], v[166:167], v[184:185]
	v_pk_mul_f32 v[168:169], v[168:169], v[184:185]
	v_pk_mul_f32 v[170:171], v[170:171], v[184:185]
	v_pk_mul_f32 v[172:173], v[172:173], v[184:185]
	v_pk_mul_f32 v[174:175], v[174:175], v[184:185]
	v_pk_fma_f32 v[144:145], v[160:161], v[128:129], v[144:145]
	v_pk_fma_f32 v[146:147], v[162:163], v[130:131], v[146:147]
	v_pk_fma_f32 v[148:149], v[164:165], v[132:133], v[148:149]
	v_pk_fma_f32 v[150:151], v[166:167], v[134:135], v[150:151]
	v_pk_fma_f32 v[152:153], v[168:169], v[136:137], v[152:153]
	v_pk_fma_f32 v[154:155], v[170:171], v[138:139], v[154:155]
	v_pk_fma_f32 v[156:157], v[172:173], v[140:141], v[156:157]
	v_pk_fma_f32 v[158:159], v[174:175], v[142:143], v[158:159]
	v_pk_mul_f32 v[252:253], v[144:145], v[144:145]
	v_pk_mul_f32 v[254:255], v[146:147], v[146:147]
	v_pk_fma_f32 v[252:253], v[148:149], v[148:149], v[252:253]
	v_pk_fma_f32 v[254:255], v[150:151], v[150:151], v[254:255]
	v_pk_fma_f32 v[252:253], v[152:153], v[152:153], v[252:253]
	v_pk_fma_f32 v[254:255], v[154:155], v[154:155], v[254:255]
	v_pk_fma_f32 v[252:253], v[156:157], v[156:157], v[252:253]
	v_pk_fma_f32 v[254:255], v[158:159], v[158:159], v[254:255]
	v_pk_add_f32 v[252:253], v[252:253], v[254:255]
	s_nop 0
	v_add_f32_e32 v183, v252, v253
	s_nop 1
	v_add_f32_dpp v183, v183, v183 quad_perm:[1,0,3,2] row_mask:0xf bank_mask:0xf bound_ctrl:1
	s_nop 1
	v_add_f32_dpp v183, v183, v183 quad_perm:[2,3,0,1] row_mask:0xf bank_mask:0xf bound_ctrl:1
	s_nop 1
	v_add_f32_dpp v183, v183, v183 row_half_mirror row_mask:0xf bank_mask:0xf bound_ctrl:1
	s_nop 1
	v_add_f32_dpp v183, v183, v183 row_mirror row_mask:0xf bank_mask:0xf bound_ctrl:1
	s_nop 1
	v_readlane_b32 s98, v183, 0
	v_readlane_b32 s99, v183, 16
	v_readlane_b32 s100, v183, 32
	v_readlane_b32 s101, v183, 48
	s_nop 1
	v_mov_b32_e32 v183, s98
	v_add_f32_e32 v183, s99, v183
	v_add_f32_e32 v183, s100, v183
	v_add_f32_e32 v183, s101, v183
	v_fmamk_f32 v183, v183, 0x3a800000, v182
	v_cmp_gt_f32_e32 vcc, 0x800000, v183
	v_mul_f32_e32 v181, 0x4b800000, v183
	s_nop 1
	v_cndmask_b32_e32 v183, v183, v181, vcc
	v_rsq_f32_e32 v183, v183
	s_nop 0
	v_mul_f32_e32 v181, 0x45800000, v183
	v_cndmask_b32_e32 v184, v183, v181, vcc
	v_mov_b32_e32 v185, v184
	v_cvt_pk_bf16_f32 v0, v144, v145
	v_cvt_pk_bf16_f32 v1, v146, v147
	v_cvt_pk_bf16_f32 v2, v148, v149
	v_cvt_pk_bf16_f32 v3, v150, v151
	v_cvt_pk_bf16_f32 v4, v152, v153
	v_cvt_pk_bf16_f32 v5, v154, v155
	v_cvt_pk_bf16_f32 v6, v156, v157
	v_cvt_pk_bf16_f32 v7, v158, v159
	v_add_u32_e32 v181, 0x3800000, v177
	global_store_dwordx4 v181, v[0:3], s[78:79]
	global_store_dwordx4 v181, v[4:7], s[78:79] offset:1024
	v_add_u32_e32 v236, 0x10000, v237
	s_mov_b64 exec, 1
	global_store_dword v236, v184, s[78:79]
	s_mov_b64 exec, -1

.LBB0_721:
	v_readlane_b32 s0, v235, 52
	v_readlane_b32 s1, v235, 53
	s_and_b64 vcc, exec, s[0:1]
	s_waitcnt lgkmcnt(0)
	s_barrier
	v_mbcnt_lo_u32_b32 v0, -1, 0
	v_mbcnt_hi_u32_b32 v0, -1, v0
	v_writelane_b32 v234, s93, 4
	s_cbranch_vccnz .LBB0_741
	v_readlane_b32 s4, v235, 4
	v_readlane_b32 s8, v235, 8
	v_readlane_b32 s9, v235, 9
	v_readlane_b32 s6, v235, 6
	v_readlane_b32 s7, v235, 7
	v_readlane_b32 s12, v235, 12
	v_readlane_b32 s13, v235, 13
	v_readlane_b32 s8, v235, 61
	v_readlane_b32 s10, v235, 10
	v_readlane_b32 s6, v235, 0
	v_readlane_b32 s9, v235, 62
	s_mov_b32 s12, s8
	s_ashr_i32 s13, s8, 31
	v_lshlrev_b32_e32 v2, 3, v0
	v_readlane_b32 s11, v235, 11
	s_lshl_b32 s6, s6, 4
	s_add_i32 s0, s8, 0xffffc000
	s_lshl_b64 s[8:9], s[12:13], 2
	s_mov_b32 s10, s12
	v_ashrrev_i32_e32 v3, 31, v2
	v_readlane_b32 s5, v235, 5
	v_readlane_b32 s14, v235, 14
	v_readlane_b32 s15, v235, 15
	v_readlane_b32 s16, v235, 16
	v_readlane_b32 s17, v235, 17
	v_readlane_b32 s18, v235, 18
	v_readlane_b32 s19, v235, 19
	v_readlane_b32 s7, v235, 1
	s_add_u32 s80, s8, 0x10000
	v_writelane_b32 v235, s10, 61
	v_lshlrev_b64 v[4:5], 1, v[2:3]
	v_lshlrev_b64 v[2:3], 2, v[2:3]
	s_addc_u32 s14, s9, 0
	s_ashr_i32 s7, s6, 31
	v_writelane_b32 v235, s11, 62
	s_lshl_b64 s[10:11], s[12:13], 11
	v_lshl_add_u64 v[152:153], s[86:87], 0, v[4:5]
	v_lshl_add_u64 v[154:155], s[90:91], 0, v[2:3]
	v_lshl_add_u64 v[156:157], s[54:55], 0, v[4:5]
	v_lshl_add_u64 v[158:159], s[18:19], 0, v[2:3]
	s_mov_b32 s1, 0
	v_cmp_eq_u32_e64 s[4:5], 0, v0
	s_lshl_b64 s[8:9], s[6:7], 2
	v_lshl_add_u64 v[160:161], s[10:11], 0, v[4:5]
	s_lshl_b64 s[10:11], s[6:7], 11
	s_mov_b64 s[24:25], 0x600000
	s_mov_b64 s[26:27], 0x600800
	s_mov_b64 s[28:29], 0x800000
	s_mov_b32 s7, 0x800000
	s_mov_b64 s[36:37], 0x800800
	s_mov_b64 s[38:39], 0xa00000
	s_mov_b64 s[40:41], 0xa00800
	s_mov_b64 s[42:43], 0xc00000
	s_mov_b64 s[44:45], 0xc00800
	s_mov_b64 s[46:47], 0xe00000
	s_mov_b64 s[48:49], 0xe00800
	s_mov_b64 s[50:51], 0x1000000
	s_mov_b32 s15, 0x1000000
	s_mov_b64 s[12:13], 0x1000800
	s_mov_b64 s[82:83], 0x1200000
	s_mov_b32 s16, 0x1200000
	s_mov_b64 s[90:91], 0x1200800
	s_mov_b64 s[20:21], 0x1400000
	s_mov_b32 s17, 0x1400000
	s_mov_b64 s[22:23], 0x1400800
	v_mov_b32_e32 v215, 0
	v_mov_b32_e32 v216, 0x358637bd
	v_mbcnt_lo_u32_b32 v176, -1, 0
	v_mbcnt_hi_u32_b32 v176, -1, v176
	v_readlane_b32 s98, v235, 49
	v_readlane_b32 s99, v235, 20
	v_readlane_b32 s100, v235, 18
	v_readlane_b32 s101, v235, 19
	s_nop 3
	s_lshr_b32 vcc_lo, s98, 3
	s_and_b32 vcc_hi, vcc_lo, 7
	s_lshr_b32 vcc_lo, vcc_lo, 3
	s_lshl_b32 vcc_lo, vcc_lo, 3
	s_add_i32 vcc_lo, vcc_lo, s99
	s_lshl_b32 s98, vcc_hi, 8
	s_add_i32 s98, s98, vcc_lo
	s_mov_b32 s99, s98
	v_mov_b32_e32 v183, s99
	v_lshlrev_b32_e32 v177, 4, v176
	s_lshl_b32 s99, s99, 11
	v_add_u32_e32 v177, s99, v177
	v_add_u32_e32 v178, 0x1800000, v177
	v_add_u32_e32 v179, 0x9e00000, v177
	v_lshlrev_b32_e32 v180, 5, v176
	global_load_dwordx4 v[128:131], v180, s[100:101]
	global_load_dwordx4 v[132:135], v180, s[100:101] offset:16
	global_load_dwordx4 v[136:139], v180, s[100:101] offset:2048
	global_load_dwordx4 v[140:143], v180, s[100:101] offset:2064
	v_mov_b32_e32 v182, 0x358637bd
	s_and_b32 vcc_lo, s98, 3
	s_cmp_eq_u32 vcc_lo, 0
	s_cbranch_scc1 .Lmyxupd_heavy_1
	global_load_dwordx4 v[0:3], v178, s[78:79]
	global_load_dwordx4 v[4:7], v178, s[78:79] offset:1024
	global_load_dwordx4 v[8:11], v179, s[78:79]
	global_load_dwordx4 v[12:15], v179, s[78:79] offset:1024
	v_add_u32_e32 v178, 0x400000, v178
	v_add_u32_e32 v179, 0x400000, v179
	global_load_dwordx4 v[16:19], v178, s[78:79]
	global_load_dwordx4 v[20:23], v178, s[78:79] offset:1024
	global_load_dwordx4 v[24:27], v179, s[78:79]
	global_load_dwordx4 v[28:31], v179, s[78:79] offset:1024
	v_add_u32_e32 v178, 0x400000, v178
	v_add_u32_e32 v179, 0x400000, v179
	global_load_dwordx4 v[32:35], v178, s[78:79]
	global_load_dwordx4 v[36:39], v178, s[78:79] offset:1024
	global_load_dwordx4 v[40:43], v179, s[78:79]
	global_load_dwordx4 v[44:47], v179, s[78:79] offset:1024
	v_add_u32_e32 v178, 0x400000, v178
	v_add_u32_e32 v179, 0x400000, v179
	global_load_dwordx4 v[48:51], v178, s[78:79]
	global_load_dwordx4 v[52:55], v178, s[78:79] offset:1024
	global_load_dwordx4 v[56:59], v179, s[78:79]
	global_load_dwordx4 v[60:63], v179, s[78:79] offset:1024
	v_add_u32_e32 v178, 0x400000, v178
	v_add_u32_e32 v179, 0x400000, v179
	global_load_dwordx4 v[64:67], v178, s[78:79]
	global_load_dwordx4 v[68:71], v178, s[78:79] offset:1024
	global_load_dwordx4 v[72:75], v179, s[78:79]
	global_load_dwordx4 v[76:79], v179, s[78:79] offset:1024
	v_add_u32_e32 v178, 0x400000, v178
	v_add_u32_e32 v179, 0x400000, v179
	global_load_dwordx4 v[80:83], v178, s[78:79]
	global_load_dwordx4 v[84:87], v178, s[78:79] offset:1024
	global_load_dwordx4 v[88:91], v179, s[78:79]
	global_load_dwordx4 v[92:95], v179, s[78:79] offset:1024
	v_add_u32_e32 v178, 0x400000, v178
	v_add_u32_e32 v179, 0x400000, v179
	global_load_dwordx4 v[96:99], v178, s[78:79]
	global_load_dwordx4 v[100:103], v178, s[78:79] offset:1024
	global_load_dwordx4 v[104:107], v179, s[78:79]
	global_load_dwordx4 v[108:111], v179, s[78:79] offset:1024
	v_add_u32_e32 v178, 0x400000, v178
	v_add_u32_e32 v179, 0x400000, v179
	global_load_dwordx4 v[112:115], v178, s[78:79]
	global_load_dwordx4 v[116:119], v178, s[78:79] offset:1024
	global_load_dwordx4 v[120:123], v179, s[78:79]
	global_load_dwordx4 v[124:127], v179, s[78:79] offset:1024
	v_lshlrev_b32_e32 v237, 2, v183
	v_add_u32_e32 v237, 0x10000, v237
	v_mov_b32_e32 v179, s98
	s_waitcnt vmcnt(28)
	v_lshlrev_b32_e32 v144, 16, v0
	v_and_b32_e32 v145, 0xffff0000, v0
	v_lshlrev_b32_e32 v146, 16, v1
	v_and_b32_e32 v147, 0xffff0000, v1
	v_lshlrev_b32_e32 v148, 16, v2
	v_and_b32_e32 v149, 0xffff0000, v2
	v_lshlrev_b32_e32 v150, 16, v3
	v_and_b32_e32 v151, 0xffff0000, v3
	v_lshlrev_b32_e32 v152, 16, v4
	v_and_b32_e32 v153, 0xffff0000, v4
	v_lshlrev_b32_e32 v154, 16, v5
	v_and_b32_e32 v155, 0xffff0000, v5
	v_lshlrev_b32_e32 v156, 16, v6
	v_and_b32_e32 v157, 0xffff0000, v6
	v_lshlrev_b32_e32 v158, 16, v7
	v_and_b32_e32 v159, 0xffff0000, v7
	v_lshlrev_b32_e32 v160, 16, v8
	v_and_b32_e32 v161, 0xffff0000, v8
	v_lshlrev_b32_e32 v162, 16, v9
	v_and_b32_e32 v163, 0xffff0000, v9
	v_lshlrev_b32_e32 v164, 16, v10
	v_and_b32_e32 v165, 0xffff0000, v10
	v_lshlrev_b32_e32 v166, 16, v11
	v_and_b32_e32 v167, 0xffff0000, v11
	v_lshlrev_b32_e32 v168, 16, v12
	v_and_b32_e32 v169, 0xffff0000, v12
	v_lshlrev_b32_e32 v170, 16, v13
	v_and_b32_e32 v171, 0xffff0000, v13
	v_lshlrev_b32_e32 v172, 16, v14
	v_and_b32_e32 v173, 0xffff0000, v14
	v_lshlrev_b32_e32 v174, 16, v15
	v_and_b32_e32 v175, 0xffff0000, v15
	v_pk_mul_f32 v[252:253], v[160:161], v[160:161]
	v_pk_mul_f32 v[254:255], v[162:163], v[162:163]
	v_pk_fma_f32 v[252:253], v[164:165], v[164:165], v[252:253]
	v_pk_fma_f32 v[254:255], v[166:167], v[166:167], v[254:255]
	v_pk_fma_f32 v[252:253], v[168:169], v[168:169], v[252:253]
	v_pk_fma_f32 v[254:255], v[170:171], v[170:171], v[254:255]
	v_pk_fma_f32 v[252:253], v[172:173], v[172:173], v[252:253]
	v_pk_fma_f32 v[254:255], v[174:175], v[174:175], v[254:255]
	v_pk_add_f32 v[252:253], v[252:253], v[254:255]
	s_nop 0
	v_add_f32_e32 v183, v252, v253
	s_nop 1
	v_add_f32_dpp v183, v183, v183 quad_perm:[1,0,3,2] row_mask:0xf bank_mask:0xf bound_ctrl:1
	s_nop 1
	v_add_f32_dpp v183, v183, v183 quad_perm:[2,3,0,1] row_mask:0xf bank_mask:0xf bound_ctrl:1
	s_nop 1
	v_add_f32_dpp v183, v183, v183 row_half_mirror row_mask:0xf bank_mask:0xf bound_ctrl:1
	s_nop 1
	v_add_f32_dpp v183, v183, v183 row_mirror row_mask:0xf bank_mask:0xf bound_ctrl:1
	s_nop 1
	v_readlane_b32 s98, v183, 0
	v_readlane_b32 s99, v183, 16
	v_readlane_b32 s100, v183, 32
	v_readlane_b32 s101, v183, 48
	s_nop 1
	v_mov_b32_e32 v183, s98
	v_add_f32_e32 v183, s99, v183
	v_add_f32_e32 v183, s100, v183
	v_add_f32_e32 v183, s101, v183
	v_fmamk_f32 v183, v183, 0x3a800000, v182
	v_cmp_gt_f32_e32 vcc, 0x800000, v183
	v_mul_f32_e32 v181, 0x4b800000, v183
	s_nop 1
	v_cndmask_b32_e32 v183, v183, v181, vcc
	v_rsq_f32_e32 v183, v183
	s_nop 0
	v_mul_f32_e32 v181, 0x45800000, v183
	v_cndmask_b32_e32 v184, v183, v181, vcc
	v_mov_b32_e32 v185, v184
	v_pk_mul_f32 v[160:161], v[160:161], v[184:185]
	v_pk_mul_f32 v[162:163], v[162:163], v[184:185]
	v_pk_mul_f32 v[164:165], v[164:165], v[184:185]
	v_pk_mul_f32 v[166:167], v[166:167], v[184:185]
	v_pk_mul_f32 v[168:169], v[168:169], v[184:185]
	v_pk_mul_f32 v[170:171], v[170:171], v[184:185]
	v_pk_mul_f32 v[172:173], v[172:173], v[184:185]
	v_pk_mul_f32 v[174:175], v[174:175], v[184:185]
	v_pk_fma_f32 v[144:145], v[160:161], v[128:129], v[144:145]
	v_pk_fma_f32 v[146:147], v[162:163], v[130:131], v[146:147]
	v_pk_fma_f32 v[148:149], v[164:165], v[132:133], v[148:149]
	v_pk_fma_f32 v[150:151], v[166:167], v[134:135], v[150:151]
	v_pk_fma_f32 v[152:153], v[168:169], v[136:137], v[152:153]
	v_pk_fma_f32 v[154:155], v[170:171], v[138:139], v[154:155]
	v_pk_fma_f32 v[156:157], v[172:173], v[140:141], v[156:157]
	v_pk_fma_f32 v[158:159], v[174:175], v[142:143], v[158:159]
	v_pk_mul_f32 v[252:253], v[144:145], v[144:145]
	v_pk_mul_f32 v[254:255], v[146:147], v[146:147]
	v_pk_fma_f32 v[252:253], v[148:149], v[148:149], v[252:253]
	v_pk_fma_f32 v[254:255], v[150:151], v[150:151], v[254:255]
	v_pk_fma_f32 v[252:253], v[152:153], v[152:153], v[252:253]
	v_pk_fma_f32 v[254:255], v[154:155], v[154:155], v[254:255]
	v_pk_fma_f32 v[252:253], v[156:157], v[156:157], v[252:253]
	v_pk_fma_f32 v[254:255], v[158:159], v[158:159], v[254:255]
	v_pk_add_f32 v[252:253], v[252:253], v[254:255]
	s_nop 0
	v_add_f32_e32 v183, v252, v253
	s_nop 1
	v_add_f32_dpp v183, v183, v183 quad_perm:[1,0,3,2] row_mask:0xf bank_mask:0xf bound_ctrl:1
	s_nop 1
	v_add_f32_dpp v183, v183, v183 quad_perm:[2,3,0,1] row_mask:0xf bank_mask:0xf bound_ctrl:1
	s_nop 1
	v_add_f32_dpp v183, v183, v183 row_half_mirror row_mask:0xf bank_mask:0xf bound_ctrl:1
	s_nop 1
	v_add_f32_dpp v183, v183, v183 row_mirror row_mask:0xf bank_mask:0xf bound_ctrl:1
	s_nop 1
	v_readlane_b32 s98, v183, 0
	v_readlane_b32 s99, v183, 16
	v_readlane_b32 s100, v183, 32
	v_readlane_b32 s101, v183, 48
	s_nop 1
	v_mov_b32_e32 v183, s98
	v_add_f32_e32 v183, s99, v183
	v_add_f32_e32 v183, s100, v183
	v_add_f32_e32 v183, s101, v183
	v_fmamk_f32 v183, v183, 0x3a800000, v182
	v_cmp_gt_f32_e32 vcc, 0x800000, v183
	v_mul_f32_e32 v181, 0x4b800000, v183
	s_nop 1
	v_cndmask_b32_e32 v183, v183, v181, vcc
	v_rsq_f32_e32 v183, v183
	s_nop 0
	v_mul_f32_e32 v181, 0x45800000, v183
	v_cndmask_b32_e32 v184, v183, v181, vcc
	v_mov_b32_e32 v185, v184
	v_cvt_pk_bf16_f32 v0, v144, v145
	v_cvt_pk_bf16_f32 v1, v146, v147
	v_cvt_pk_bf16_f32 v2, v148, v149
	v_cvt_pk_bf16_f32 v3, v150, v151
	v_cvt_pk_bf16_f32 v4, v152, v153
	v_cvt_pk_bf16_f32 v5, v154, v155
	v_cvt_pk_bf16_f32 v6, v156, v157
	v_cvt_pk_bf16_f32 v7, v158, v159
	v_add_u32_e32 v181, 0x1800000, v177
	global_store_dwordx4 v181, v[0:3], s[78:79]
	global_store_dwordx4 v181, v[4:7], s[78:79] offset:1024
	v_add_u32_e32 v236, 0x0, v237
	s_mov_b64 exec, 1
	global_store_dword v236, v184, s[78:79]
	s_mov_b64 exec, -1
	s_waitcnt vmcnt(24)
	v_lshlrev_b32_e32 v144, 16, v16
	v_and_b32_e32 v145, 0xffff0000, v16
	v_lshlrev_b32_e32 v146, 16, v17
	v_and_b32_e32 v147, 0xffff0000, v17
	v_lshlrev_b32_e32 v148, 16, v18
	v_and_b32_e32 v149, 0xffff0000, v18
	v_lshlrev_b32_e32 v150, 16, v19
	v_and_b32_e32 v151, 0xffff0000, v19
	v_lshlrev_b32_e32 v152, 16, v20
	v_and_b32_e32 v153, 0xffff0000, v20
	v_lshlrev_b32_e32 v154, 16, v21
	v_and_b32_e32 v155, 0xffff0000, v21
	v_lshlrev_b32_e32 v156, 16, v22
	v_and_b32_e32 v157, 0xffff0000, v22
	v_lshlrev_b32_e32 v158, 16, v23
	v_and_b32_e32 v159, 0xffff0000, v23
	v_lshlrev_b32_e32 v160, 16, v24
	v_and_b32_e32 v161, 0xffff0000, v24
	v_lshlrev_b32_e32 v162, 16, v25
	v_and_b32_e32 v163, 0xffff0000, v25
	v_lshlrev_b32_e32 v164, 16, v26
	v_and_b32_e32 v165, 0xffff0000, v26
	v_lshlrev_b32_e32 v166, 16, v27
	v_and_b32_e32 v167, 0xffff0000, v27
	v_lshlrev_b32_e32 v168, 16, v28
	v_and_b32_e32 v169, 0xffff0000, v28
	v_lshlrev_b32_e32 v170, 16, v29
	v_and_b32_e32 v171, 0xffff0000, v29
	v_lshlrev_b32_e32 v172, 16, v30
	v_and_b32_e32 v173, 0xffff0000, v30
	v_lshlrev_b32_e32 v174, 16, v31
	v_and_b32_e32 v175, 0xffff0000, v31
	v_pk_mul_f32 v[252:253], v[160:161], v[160:161]
	v_pk_mul_f32 v[254:255], v[162:163], v[162:163]
	v_pk_fma_f32 v[252:253], v[164:165], v[164:165], v[252:253]
	v_pk_fma_f32 v[254:255], v[166:167], v[166:167], v[254:255]
	v_pk_fma_f32 v[252:253], v[168:169], v[168:169], v[252:253]
	v_pk_fma_f32 v[254:255], v[170:171], v[170:171], v[254:255]
	v_pk_fma_f32 v[252:253], v[172:173], v[172:173], v[252:253]
	v_pk_fma_f32 v[254:255], v[174:175], v[174:175], v[254:255]
	v_pk_add_f32 v[252:253], v[252:253], v[254:255]
	s_nop 0
	v_add_f32_e32 v183, v252, v253
	s_nop 1
	v_add_f32_dpp v183, v183, v183 quad_perm:[1,0,3,2] row_mask:0xf bank_mask:0xf bound_ctrl:1
	s_nop 1
	v_add_f32_dpp v183, v183, v183 quad_perm:[2,3,0,1] row_mask:0xf bank_mask:0xf bound_ctrl:1
	s_nop 1
	v_add_f32_dpp v183, v183, v183 row_half_mirror row_mask:0xf bank_mask:0xf bound_ctrl:1
	s_nop 1
	v_add_f32_dpp v183, v183, v183 row_mirror row_mask:0xf bank_mask:0xf bound_ctrl:1
	s_nop 1
	v_readlane_b32 s98, v183, 0
	v_readlane_b32 s99, v183, 16
	v_readlane_b32 s100, v183, 32
	v_readlane_b32 s101, v183, 48
	s_nop 1
	v_mov_b32_e32 v183, s98
	v_add_f32_e32 v183, s99, v183
	v_add_f32_e32 v183, s100, v183
	v_add_f32_e32 v183, s101, v183
	v_fmamk_f32 v183, v183, 0x3a800000, v182
	v_cmp_gt_f32_e32 vcc, 0x800000, v183
	v_mul_f32_e32 v181, 0x4b800000, v183
	s_nop 1
	v_cndmask_b32_e32 v183, v183, v181, vcc
	v_rsq_f32_e32 v183, v183
	s_nop 0
	v_mul_f32_e32 v181, 0x45800000, v183
	v_cndmask_b32_e32 v184, v183, v181, vcc
	v_mov_b32_e32 v185, v184
	v_pk_mul_f32 v[160:161], v[160:161], v[184:185]
	v_pk_mul_f32 v[162:163], v[162:163], v[184:185]
	v_pk_mul_f32 v[164:165], v[164:165], v[184:185]
	v_pk_mul_f32 v[166:167], v[166:167], v[184:185]
	v_pk_mul_f32 v[168:169], v[168:169], v[184:185]
	v_pk_mul_f32 v[170:171], v[170:171], v[184:185]
	v_pk_mul_f32 v[172:173], v[172:173], v[184:185]
	v_pk_mul_f32 v[174:175], v[174:175], v[184:185]
	v_pk_fma_f32 v[144:145], v[160:161], v[128:129], v[144:145]
	v_pk_fma_f32 v[146:147], v[162:163], v[130:131], v[146:147]
	v_pk_fma_f32 v[148:149], v[164:165], v[132:133], v[148:149]
	v_pk_fma_f32 v[150:151], v[166:167], v[134:135], v[150:151]
	v_pk_fma_f32 v[152:153], v[168:169], v[136:137], v[152:153]
	v_pk_fma_f32 v[154:155], v[170:171], v[138:139], v[154:155]
	v_pk_fma_f32 v[156:157], v[172:173], v[140:141], v[156:157]
	v_pk_fma_f32 v[158:159], v[174:175], v[142:143], v[158:159]
	v_pk_mul_f32 v[252:253], v[144:145], v[144:145]
	v_pk_mul_f32 v[254:255], v[146:147], v[146:147]
	v_pk_fma_f32 v[252:253], v[148:149], v[148:149], v[252:253]
	v_pk_fma_f32 v[254:255], v[150:151], v[150:151], v[254:255]
	v_pk_fma_f32 v[252:253], v[152:153], v[152:153], v[252:253]
	v_pk_fma_f32 v[254:255], v[154:155], v[154:155], v[254:255]
	v_pk_fma_f32 v[252:253], v[156:157], v[156:157], v[252:253]
	v_pk_fma_f32 v[254:255], v[158:159], v[158:159], v[254:255]
	v_pk_add_f32 v[252:253], v[252:253], v[254:255]
	s_nop 0
	v_add_f32_e32 v183, v252, v253
	s_nop 1
	v_add_f32_dpp v183, v183, v183 quad_perm:[1,0,3,2] row_mask:0xf bank_mask:0xf bound_ctrl:1
	s_nop 1
	v_add_f32_dpp v183, v183, v183 quad_perm:[2,3,0,1] row_mask:0xf bank_mask:0xf bound_ctrl:1
	s_nop 1
	v_add_f32_dpp v183, v183, v183 row_half_mirror row_mask:0xf bank_mask:0xf bound_ctrl:1
	s_nop 1
	v_add_f32_dpp v183, v183, v183 row_mirror row_mask:0xf bank_mask:0xf bound_ctrl:1
	s_nop 1
	v_readlane_b32 s98, v183, 0
	v_readlane_b32 s99, v183, 16
	v_readlane_b32 s100, v183, 32
	v_readlane_b32 s101, v183, 48
	s_nop 1
	v_mov_b32_e32 v183, s98
	v_add_f32_e32 v183, s99, v183
	v_add_f32_e32 v183, s100, v183
	v_add_f32_e32 v183, s101, v183
	v_fmamk_f32 v183, v183, 0x3a800000, v182
	v_cmp_gt_f32_e32 vcc, 0x800000, v183
	v_mul_f32_e32 v181, 0x4b800000, v183
	s_nop 1
	v_cndmask_b32_e32 v183, v183, v181, vcc
	v_rsq_f32_e32 v183, v183
	s_nop 0
	v_mul_f32_e32 v181, 0x45800000, v183
	v_cndmask_b32_e32 v184, v183, v181, vcc
	v_mov_b32_e32 v185, v184
	v_cvt_pk_bf16_f32 v16, v144, v145
	v_cvt_pk_bf16_f32 v17, v146, v147
	v_cvt_pk_bf16_f32 v18, v148, v149
	v_cvt_pk_bf16_f32 v19, v150, v151
	v_cvt_pk_bf16_f32 v20, v152, v153
	v_cvt_pk_bf16_f32 v21, v154, v155
	v_cvt_pk_bf16_f32 v22, v156, v157
	v_cvt_pk_bf16_f32 v23, v158, v159
	v_add_u32_e32 v181, 0x1c00000, v177
	global_store_dwordx4 v181, v[16:19], s[78:79]
	global_store_dwordx4 v181, v[20:23], s[78:79] offset:1024
	v_add_u32_e32 v236, 0x2000, v237
	s_mov_b64 exec, 1
	global_store_dword v236, v184, s[78:79]
	s_mov_b64 exec, -1
	s_waitcnt vmcnt(20)
	v_lshlrev_b32_e32 v144, 16, v32
	v_and_b32_e32 v145, 0xffff0000, v32
	v_lshlrev_b32_e32 v146, 16, v33
	v_and_b32_e32 v147, 0xffff0000, v33
	v_lshlrev_b32_e32 v148, 16, v34
	v_and_b32_e32 v149, 0xffff0000, v34
	v_lshlrev_b32_e32 v150, 16, v35
	v_and_b32_e32 v151, 0xffff0000, v35
	v_lshlrev_b32_e32 v152, 16, v36
	v_and_b32_e32 v153, 0xffff0000, v36
	v_lshlrev_b32_e32 v154, 16, v37
	v_and_b32_e32 v155, 0xffff0000, v37
	v_lshlrev_b32_e32 v156, 16, v38
	v_and_b32_e32 v157, 0xffff0000, v38
	v_lshlrev_b32_e32 v158, 16, v39
	v_and_b32_e32 v159, 0xffff0000, v39
	v_lshlrev_b32_e32 v160, 16, v40
	v_and_b32_e32 v161, 0xffff0000, v40
	v_lshlrev_b32_e32 v162, 16, v41
	v_and_b32_e32 v163, 0xffff0000, v41
	v_lshlrev_b32_e32 v164, 16, v42
	v_and_b32_e32 v165, 0xffff0000, v42
	v_lshlrev_b32_e32 v166, 16, v43
	v_and_b32_e32 v167, 0xffff0000, v43
	v_lshlrev_b32_e32 v168, 16, v44
	v_and_b32_e32 v169, 0xffff0000, v44
	v_lshlrev_b32_e32 v170, 16, v45
	v_and_b32_e32 v171, 0xffff0000, v45
	v_lshlrev_b32_e32 v172, 16, v46
	v_and_b32_e32 v173, 0xffff0000, v46
	v_lshlrev_b32_e32 v174, 16, v47
	v_and_b32_e32 v175, 0xffff0000, v47
	v_pk_mul_f32 v[252:253], v[160:161], v[160:161]
	v_pk_mul_f32 v[254:255], v[162:163], v[162:163]
	v_pk_fma_f32 v[252:253], v[164:165], v[164:165], v[252:253]
	v_pk_fma_f32 v[254:255], v[166:167], v[166:167], v[254:255]
	v_pk_fma_f32 v[252:253], v[168:169], v[168:169], v[252:253]
	v_pk_fma_f32 v[254:255], v[170:171], v[170:171], v[254:255]
	v_pk_fma_f32 v[252:253], v[172:173], v[172:173], v[252:253]
	v_pk_fma_f32 v[254:255], v[174:175], v[174:175], v[254:255]
	v_pk_add_f32 v[252:253], v[252:253], v[254:255]
	s_nop 0
	v_add_f32_e32 v183, v252, v253
	s_nop 1
	v_add_f32_dpp v183, v183, v183 quad_perm:[1,0,3,2] row_mask:0xf bank_mask:0xf bound_ctrl:1
	s_nop 1
	v_add_f32_dpp v183, v183, v183 quad_perm:[2,3,0,1] row_mask:0xf bank_mask:0xf bound_ctrl:1
	s_nop 1
	v_add_f32_dpp v183, v183, v183 row_half_mirror row_mask:0xf bank_mask:0xf bound_ctrl:1
	s_nop 1
	v_add_f32_dpp v183, v183, v183 row_mirror row_mask:0xf bank_mask:0xf bound_ctrl:1
	s_nop 1
	v_readlane_b32 s98, v183, 0
	v_readlane_b32 s99, v183, 16
	v_readlane_b32 s100, v183, 32
	v_readlane_b32 s101, v183, 48
	s_nop 1
	v_mov_b32_e32 v183, s98
	v_add_f32_e32 v183, s99, v183
	v_add_f32_e32 v183, s100, v183
	v_add_f32_e32 v183, s101, v183
	v_fmamk_f32 v183, v183, 0x3a800000, v182
	v_cmp_gt_f32_e32 vcc, 0x800000, v183
	v_mul_f32_e32 v181, 0x4b800000, v183
	s_nop 1
	v_cndmask_b32_e32 v183, v183, v181, vcc
	v_rsq_f32_e32 v183, v183
	s_nop 0
	v_mul_f32_e32 v181, 0x45800000, v183
	v_cndmask_b32_e32 v184, v183, v181, vcc
	v_mov_b32_e32 v185, v184
	v_pk_mul_f32 v[160:161], v[160:161], v[184:185]
	v_pk_mul_f32 v[162:163], v[162:163], v[184:185]
	v_pk_mul_f32 v[164:165], v[164:165], v[184:185]
	v_pk_mul_f32 v[166:167], v[166:167], v[184:185]
	v_pk_mul_f32 v[168:169], v[168:169], v[184:185]
	v_pk_mul_f32 v[170:171], v[170:171], v[184:185]
	v_pk_mul_f32 v[172:173], v[172:173], v[184:185]
	v_pk_mul_f32 v[174:175], v[174:175], v[184:185]
	v_pk_fma_f32 v[144:145], v[160:161], v[128:129], v[144:145]
	v_pk_fma_f32 v[146:147], v[162:163], v[130:131], v[146:147]
	v_pk_fma_f32 v[148:149], v[164:165], v[132:133], v[148:149]
	v_pk_fma_f32 v[150:151], v[166:167], v[134:135], v[150:151]
	v_pk_fma_f32 v[152:153], v[168:169], v[136:137], v[152:153]
	v_pk_fma_f32 v[154:155], v[170:171], v[138:139], v[154:155]
	v_pk_fma_f32 v[156:157], v[172:173], v[140:141], v[156:157]
	v_pk_fma_f32 v[158:159], v[174:175], v[142:143], v[158:159]
	v_pk_mul_f32 v[252:253], v[144:145], v[144:145]
	v_pk_mul_f32 v[254:255], v[146:147], v[146:147]
	v_pk_fma_f32 v[252:253], v[148:149], v[148:149], v[252:253]
	v_pk_fma_f32 v[254:255], v[150:151], v[150:151], v[254:255]
	v_pk_fma_f32 v[252:253], v[152:153], v[152:153], v[252:253]
	v_pk_fma_f32 v[254:255], v[154:155], v[154:155], v[254:255]
	v_pk_fma_f32 v[252:253], v[156:157], v[156:157], v[252:253]
	v_pk_fma_f32 v[254:255], v[158:159], v[158:159], v[254:255]
	v_pk_add_f32 v[252:253], v[252:253], v[254:255]
	s_nop 0
	v_add_f32_e32 v183, v252, v253
	s_nop 1
	v_add_f32_dpp v183, v183, v183 quad_perm:[1,0,3,2] row_mask:0xf bank_mask:0xf bound_ctrl:1
	s_nop 1
	v_add_f32_dpp v183, v183, v183 quad_perm:[2,3,0,1] row_mask:0xf bank_mask:0xf bound_ctrl:1
	s_nop 1
	v_add_f32_dpp v183, v183, v183 row_half_mirror row_mask:0xf bank_mask:0xf bound_ctrl:1
	s_nop 1
	v_add_f32_dpp v183, v183, v183 row_mirror row_mask:0xf bank_mask:0xf bound_ctrl:1
	s_nop 1
	v_readlane_b32 s98, v183, 0
	v_readlane_b32 s99, v183, 16
	v_readlane_b32 s100, v183, 32
	v_readlane_b32 s101, v183, 48
	s_nop 1
	v_mov_b32_e32 v183, s98
	v_add_f32_e32 v183, s99, v183
	v_add_f32_e32 v183, s100, v183
	v_add_f32_e32 v183, s101, v183
	v_fmamk_f32 v183, v183, 0x3a800000, v182
	v_cmp_gt_f32_e32 vcc, 0x800000, v183
	v_mul_f32_e32 v181, 0x4b800000, v183
	s_nop 1
	v_cndmask_b32_e32 v183, v183, v181, vcc
	v_rsq_f32_e32 v183, v183
	s_nop 0
	v_mul_f32_e32 v181, 0x45800000, v183
	v_cndmask_b32_e32 v184, v183, v181, vcc
	v_mov_b32_e32 v185, v184
	v_cvt_pk_bf16_f32 v32, v144, v145
	v_cvt_pk_bf16_f32 v33, v146, v147
	v_cvt_pk_bf16_f32 v34, v148, v149
	v_cvt_pk_bf16_f32 v35, v150, v151
	v_cvt_pk_bf16_f32 v36, v152, v153
	v_cvt_pk_bf16_f32 v37, v154, v155
	v_cvt_pk_bf16_f32 v38, v156, v157
	v_cvt_pk_bf16_f32 v39, v158, v159
	v_add_u32_e32 v181, 0x2000000, v177
	global_store_dwordx4 v181, v[32:35], s[78:79]
	global_store_dwordx4 v181, v[36:39], s[78:79] offset:1024
	v_add_u32_e32 v236, 0x4000, v237
	s_mov_b64 exec, 1
	global_store_dword v236, v184, s[78:79]
	s_mov_b64 exec, -1
	s_waitcnt vmcnt(16)
	v_lshlrev_b32_e32 v144, 16, v48
	v_and_b32_e32 v145, 0xffff0000, v48
	v_lshlrev_b32_e32 v146, 16, v49
	v_and_b32_e32 v147, 0xffff0000, v49
	v_lshlrev_b32_e32 v148, 16, v50
	v_and_b32_e32 v149, 0xffff0000, v50
	v_lshlrev_b32_e32 v150, 16, v51
	v_and_b32_e32 v151, 0xffff0000, v51
	v_lshlrev_b32_e32 v152, 16, v52
	v_and_b32_e32 v153, 0xffff0000, v52
	v_lshlrev_b32_e32 v154, 16, v53
	v_and_b32_e32 v155, 0xffff0000, v53
	v_lshlrev_b32_e32 v156, 16, v54
	v_and_b32_e32 v157, 0xffff0000, v54
	v_lshlrev_b32_e32 v158, 16, v55
	v_and_b32_e32 v159, 0xffff0000, v55
	v_lshlrev_b32_e32 v160, 16, v56
	v_and_b32_e32 v161, 0xffff0000, v56
	v_lshlrev_b32_e32 v162, 16, v57
	v_and_b32_e32 v163, 0xffff0000, v57
	v_lshlrev_b32_e32 v164, 16, v58
	v_and_b32_e32 v165, 0xffff0000, v58
	v_lshlrev_b32_e32 v166, 16, v59
	v_and_b32_e32 v167, 0xffff0000, v59
	v_lshlrev_b32_e32 v168, 16, v60
	v_and_b32_e32 v169, 0xffff0000, v60
	v_lshlrev_b32_e32 v170, 16, v61
	v_and_b32_e32 v171, 0xffff0000, v61
	v_lshlrev_b32_e32 v172, 16, v62
	v_and_b32_e32 v173, 0xffff0000, v62
	v_lshlrev_b32_e32 v174, 16, v63
	v_and_b32_e32 v175, 0xffff0000, v63
	v_pk_mul_f32 v[252:253], v[160:161], v[160:161]
	v_pk_mul_f32 v[254:255], v[162:163], v[162:163]
	v_pk_fma_f32 v[252:253], v[164:165], v[164:165], v[252:253]
	v_pk_fma_f32 v[254:255], v[166:167], v[166:167], v[254:255]
	v_pk_fma_f32 v[252:253], v[168:169], v[168:169], v[252:253]
	v_pk_fma_f32 v[254:255], v[170:171], v[170:171], v[254:255]
	v_pk_fma_f32 v[252:253], v[172:173], v[172:173], v[252:253]
	v_pk_fma_f32 v[254:255], v[174:175], v[174:175], v[254:255]
	v_pk_add_f32 v[252:253], v[252:253], v[254:255]
	s_nop 0
	v_add_f32_e32 v183, v252, v253
	s_nop 1
	v_add_f32_dpp v183, v183, v183 quad_perm:[1,0,3,2] row_mask:0xf bank_mask:0xf bound_ctrl:1
	s_nop 1
	v_add_f32_dpp v183, v183, v183 quad_perm:[2,3,0,1] row_mask:0xf bank_mask:0xf bound_ctrl:1
	s_nop 1
	v_add_f32_dpp v183, v183, v183 row_half_mirror row_mask:0xf bank_mask:0xf bound_ctrl:1
	s_nop 1
	v_add_f32_dpp v183, v183, v183 row_mirror row_mask:0xf bank_mask:0xf bound_ctrl:1
	s_nop 1
	v_readlane_b32 s98, v183, 0
	v_readlane_b32 s99, v183, 16
	v_readlane_b32 s100, v183, 32
	v_readlane_b32 s101, v183, 48
	s_nop 1
	v_mov_b32_e32 v183, s98
	v_add_f32_e32 v183, s99, v183
	v_add_f32_e32 v183, s100, v183
	v_add_f32_e32 v183, s101, v183
	v_fmamk_f32 v183, v183, 0x3a800000, v182
	v_cmp_gt_f32_e32 vcc, 0x800000, v183
	v_mul_f32_e32 v181, 0x4b800000, v183
	s_nop 1
	v_cndmask_b32_e32 v183, v183, v181, vcc
	v_rsq_f32_e32 v183, v183
	s_nop 0
	v_mul_f32_e32 v181, 0x45800000, v183
	v_cndmask_b32_e32 v184, v183, v181, vcc
	v_mov_b32_e32 v185, v184
	v_pk_mul_f32 v[160:161], v[160:161], v[184:185]
	v_pk_mul_f32 v[162:163], v[162:163], v[184:185]
	v_pk_mul_f32 v[164:165], v[164:165], v[184:185]
	v_pk_mul_f32 v[166:167], v[166:167], v[184:185]
	v_pk_mul_f32 v[168:169], v[168:169], v[184:185]
	v_pk_mul_f32 v[170:171], v[170:171], v[184:185]
	v_pk_mul_f32 v[172:173], v[172:173], v[184:185]
	v_pk_mul_f32 v[174:175], v[174:175], v[184:185]
	v_pk_fma_f32 v[144:145], v[160:161], v[128:129], v[144:145]
	v_pk_fma_f32 v[146:147], v[162:163], v[130:131], v[146:147]
	v_pk_fma_f32 v[148:149], v[164:165], v[132:133], v[148:149]
	v_pk_fma_f32 v[150:151], v[166:167], v[134:135], v[150:151]
	v_pk_fma_f32 v[152:153], v[168:169], v[136:137], v[152:153]
	v_pk_fma_f32 v[154:155], v[170:171], v[138:139], v[154:155]
	v_pk_fma_f32 v[156:157], v[172:173], v[140:141], v[156:157]
	v_pk_fma_f32 v[158:159], v[174:175], v[142:143], v[158:159]
	v_pk_mul_f32 v[252:253], v[144:145], v[144:145]
	v_pk_mul_f32 v[254:255], v[146:147], v[146:147]
	v_pk_fma_f32 v[252:253], v[148:149], v[148:149], v[252:253]
	v_pk_fma_f32 v[254:255], v[150:151], v[150:151], v[254:255]
	v_pk_fma_f32 v[252:253], v[152:153], v[152:153], v[252:253]
	v_pk_fma_f32 v[254:255], v[154:155], v[154:155], v[254:255]
	v_pk_fma_f32 v[252:253], v[156:157], v[156:157], v[252:253]
	v_pk_fma_f32 v[254:255], v[158:159], v[158:159], v[254:255]
	v_pk_add_f32 v[252:253], v[252:253], v[254:255]
	s_nop 0
	v_add_f32_e32 v183, v252, v253
	s_nop 1
	v_add_f32_dpp v183, v183, v183 quad_perm:[1,0,3,2] row_mask:0xf bank_mask:0xf bound_ctrl:1
	s_nop 1
	v_add_f32_dpp v183, v183, v183 quad_perm:[2,3,0,1] row_mask:0xf bank_mask:0xf bound_ctrl:1
	s_nop 1
	v_add_f32_dpp v183, v183, v183 row_half_mirror row_mask:0xf bank_mask:0xf bound_ctrl:1
	s_nop 1
	v_add_f32_dpp v183, v183, v183 row_mirror row_mask:0xf bank_mask:0xf bound_ctrl:1
	s_nop 1
	v_readlane_b32 s98, v183, 0
	v_readlane_b32 s99, v183, 16
	v_readlane_b32 s100, v183, 32
	v_readlane_b32 s101, v183, 48
	s_nop 1
	v_mov_b32_e32 v183, s98
	v_add_f32_e32 v183, s99, v183
	v_add_f32_e32 v183, s100, v183
	v_add_f32_e32 v183, s101, v183
	v_fmamk_f32 v183, v183, 0x3a800000, v182
	v_cmp_gt_f32_e32 vcc, 0x800000, v183
	v_mul_f32_e32 v181, 0x4b800000, v183
	s_nop 1
	v_cndmask_b32_e32 v183, v183, v181, vcc
	v_rsq_f32_e32 v183, v183
	s_nop 0
	v_mul_f32_e32 v181, 0x45800000, v183
	v_cndmask_b32_e32 v184, v183, v181, vcc
	v_mov_b32_e32 v185, v184
	v_cvt_pk_bf16_f32 v48, v144, v145
	v_cvt_pk_bf16_f32 v49, v146, v147
	v_cvt_pk_bf16_f32 v50, v148, v149
	v_cvt_pk_bf16_f32 v51, v150, v151
	v_cvt_pk_bf16_f32 v52, v152, v153
	v_cvt_pk_bf16_f32 v53, v154, v155
	v_cvt_pk_bf16_f32 v54, v156, v157
	v_cvt_pk_bf16_f32 v55, v158, v159
	v_add_u32_e32 v181, 0x2400000, v177
	global_store_dwordx4 v181, v[48:51], s[78:79]
	global_store_dwordx4 v181, v[52:55], s[78:79] offset:1024
	v_add_u32_e32 v236, 0x6000, v237
	s_mov_b64 exec, 1
	global_store_dword v236, v184, s[78:79]
	s_mov_b64 exec, -1
	s_waitcnt vmcnt(12)
	v_lshlrev_b32_e32 v144, 16, v64
	v_and_b32_e32 v145, 0xffff0000, v64
	v_lshlrev_b32_e32 v146, 16, v65
	v_and_b32_e32 v147, 0xffff0000, v65
	v_lshlrev_b32_e32 v148, 16, v66
	v_and_b32_e32 v149, 0xffff0000, v66
	v_lshlrev_b32_e32 v150, 16, v67
	v_and_b32_e32 v151, 0xffff0000, v67
	v_lshlrev_b32_e32 v152, 16, v68
	v_and_b32_e32 v153, 0xffff0000, v68
	v_lshlrev_b32_e32 v154, 16, v69
	v_and_b32_e32 v155, 0xffff0000, v69
	v_lshlrev_b32_e32 v156, 16, v70
	v_and_b32_e32 v157, 0xffff0000, v70
	v_lshlrev_b32_e32 v158, 16, v71
	v_and_b32_e32 v159, 0xffff0000, v71
	v_lshlrev_b32_e32 v160, 16, v72
	v_and_b32_e32 v161, 0xffff0000, v72
	v_lshlrev_b32_e32 v162, 16, v73
	v_and_b32_e32 v163, 0xffff0000, v73
	v_lshlrev_b32_e32 v164, 16, v74
	v_and_b32_e32 v165, 0xffff0000, v74
	v_lshlrev_b32_e32 v166, 16, v75
	v_and_b32_e32 v167, 0xffff0000, v75
	v_lshlrev_b32_e32 v168, 16, v76
	v_and_b32_e32 v169, 0xffff0000, v76
	v_lshlrev_b32_e32 v170, 16, v77
	v_and_b32_e32 v171, 0xffff0000, v77
	v_lshlrev_b32_e32 v172, 16, v78
	v_and_b32_e32 v173, 0xffff0000, v78
	v_lshlrev_b32_e32 v174, 16, v79
	v_and_b32_e32 v175, 0xffff0000, v79
	v_pk_mul_f32 v[252:253], v[160:161], v[160:161]
	v_pk_mul_f32 v[254:255], v[162:163], v[162:163]
	v_pk_fma_f32 v[252:253], v[164:165], v[164:165], v[252:253]
	v_pk_fma_f32 v[254:255], v[166:167], v[166:167], v[254:255]
	v_pk_fma_f32 v[252:253], v[168:169], v[168:169], v[252:253]
	v_pk_fma_f32 v[254:255], v[170:171], v[170:171], v[254:255]
	v_pk_fma_f32 v[252:253], v[172:173], v[172:173], v[252:253]
	v_pk_fma_f32 v[254:255], v[174:175], v[174:175], v[254:255]
	v_pk_add_f32 v[252:253], v[252:253], v[254:255]
	s_nop 0
	v_add_f32_e32 v183, v252, v253
	s_nop 1
	v_add_f32_dpp v183, v183, v183 quad_perm:[1,0,3,2] row_mask:0xf bank_mask:0xf bound_ctrl:1
	s_nop 1
	v_add_f32_dpp v183, v183, v183 quad_perm:[2,3,0,1] row_mask:0xf bank_mask:0xf bound_ctrl:1
	s_nop 1
	v_add_f32_dpp v183, v183, v183 row_half_mirror row_mask:0xf bank_mask:0xf bound_ctrl:1
	s_nop 1
	v_add_f32_dpp v183, v183, v183 row_mirror row_mask:0xf bank_mask:0xf bound_ctrl:1
	s_nop 1
	v_readlane_b32 s98, v183, 0
	v_readlane_b32 s99, v183, 16
	v_readlane_b32 s100, v183, 32
	v_readlane_b32 s101, v183, 48
	s_nop 1
	v_mov_b32_e32 v183, s98
	v_add_f32_e32 v183, s99, v183
	v_add_f32_e32 v183, s100, v183
	v_add_f32_e32 v183, s101, v183
	v_fmamk_f32 v183, v183, 0x3a800000, v182
	v_cmp_gt_f32_e32 vcc, 0x800000, v183
	v_mul_f32_e32 v181, 0x4b800000, v183
	s_nop 1
	v_cndmask_b32_e32 v183, v183, v181, vcc
	v_rsq_f32_e32 v183, v183
	s_nop 0
	v_mul_f32_e32 v181, 0x45800000, v183
	v_cndmask_b32_e32 v184, v183, v181, vcc
	v_mov_b32_e32 v185, v184
	v_pk_mul_f32 v[160:161], v[160:161], v[184:185]
	v_pk_mul_f32 v[162:163], v[162:163], v[184:185]
	v_pk_mul_f32 v[164:165], v[164:165], v[184:185]
	v_pk_mul_f32 v[166:167], v[166:167], v[184:185]
	v_pk_mul_f32 v[168:169], v[168:169], v[184:185]
	v_pk_mul_f32 v[170:171], v[170:171], v[184:185]
	v_pk_mul_f32 v[172:173], v[172:173], v[184:185]
	v_pk_mul_f32 v[174:175], v[174:175], v[184:185]
	v_pk_fma_f32 v[144:145], v[160:161], v[128:129], v[144:145]
	v_pk_fma_f32 v[146:147], v[162:163], v[130:131], v[146:147]
	v_pk_fma_f32 v[148:149], v[164:165], v[132:133], v[148:149]
	v_pk_fma_f32 v[150:151], v[166:167], v[134:135], v[150:151]
	v_pk_fma_f32 v[152:153], v[168:169], v[136:137], v[152:153]
	v_pk_fma_f32 v[154:155], v[170:171], v[138:139], v[154:155]
	v_pk_fma_f32 v[156:157], v[172:173], v[140:141], v[156:157]
	v_pk_fma_f32 v[158:159], v[174:175], v[142:143], v[158:159]
	v_pk_mul_f32 v[252:253], v[144:145], v[144:145]
	v_pk_mul_f32 v[254:255], v[146:147], v[146:147]
	v_pk_fma_f32 v[252:253], v[148:149], v[148:149], v[252:253]
	v_pk_fma_f32 v[254:255], v[150:151], v[150:151], v[254:255]
	v_pk_fma_f32 v[252:253], v[152:153], v[152:153], v[252:253]
	v_pk_fma_f32 v[254:255], v[154:155], v[154:155], v[254:255]
	v_pk_fma_f32 v[252:253], v[156:157], v[156:157], v[252:253]
	v_pk_fma_f32 v[254:255], v[158:159], v[158:159], v[254:255]
	v_pk_add_f32 v[252:253], v[252:253], v[254:255]
	s_nop 0
	v_add_f32_e32 v183, v252, v253
	s_nop 1
	v_add_f32_dpp v183, v183, v183 quad_perm:[1,0,3,2] row_mask:0xf bank_mask:0xf bound_ctrl:1
	s_nop 1
	v_add_f32_dpp v183, v183, v183 quad_perm:[2,3,0,1] row_mask:0xf bank_mask:0xf bound_ctrl:1
	s_nop 1
	v_add_f32_dpp v183, v183, v183 row_half_mirror row_mask:0xf bank_mask:0xf bound_ctrl:1
	s_nop 1
	v_add_f32_dpp v183, v183, v183 row_mirror row_mask:0xf bank_mask:0xf bound_ctrl:1
	s_nop 1
	v_readlane_b32 s98, v183, 0
	v_readlane_b32 s99, v183, 16
	v_readlane_b32 s100, v183, 32
	v_readlane_b32 s101, v183, 48
	s_nop 1
	v_mov_b32_e32 v183, s98
	v_add_f32_e32 v183, s99, v183
	v_add_f32_e32 v183, s100, v183
	v_add_f32_e32 v183, s101, v183
	v_fmamk_f32 v183, v183, 0x3a800000, v182
	v_cmp_gt_f32_e32 vcc, 0x800000, v183
	v_mul_f32_e32 v181, 0x4b800000, v183
	s_nop 1
	v_cndmask_b32_e32 v183, v183, v181, vcc
	v_rsq_f32_e32 v183, v183
	s_nop 0
	v_mul_f32_e32 v181, 0x45800000, v183
	v_cndmask_b32_e32 v184, v183, v181, vcc
	v_mov_b32_e32 v185, v184
	v_cvt_pk_bf16_f32 v64, v144, v145
	v_cvt_pk_bf16_f32 v65, v146, v147
	v_cvt_pk_bf16_f32 v66, v148, v149
	v_cvt_pk_bf16_f32 v67, v150, v151
	v_cvt_pk_bf16_f32 v68, v152, v153
	v_cvt_pk_bf16_f32 v69, v154, v155
	v_cvt_pk_bf16_f32 v70, v156, v157
	v_cvt_pk_bf16_f32 v71, v158, v159
	v_add_u32_e32 v181, 0x2800000, v177
	global_store_dwordx4 v181, v[64:67], s[78:79]
	global_store_dwordx4 v181, v[68:71], s[78:79] offset:1024
	v_add_u32_e32 v236, 0x8000, v237
	s_mov_b64 exec, 1
	global_store_dword v236, v184, s[78:79]
	s_mov_b64 exec, -1
	s_waitcnt vmcnt(8)
	v_lshlrev_b32_e32 v144, 16, v80
	v_and_b32_e32 v145, 0xffff0000, v80
	v_lshlrev_b32_e32 v146, 16, v81
	v_and_b32_e32 v147, 0xffff0000, v81
	v_lshlrev_b32_e32 v148, 16, v82
	v_and_b32_e32 v149, 0xffff0000, v82
	v_lshlrev_b32_e32 v150, 16, v83
	v_and_b32_e32 v151, 0xffff0000, v83
	v_lshlrev_b32_e32 v152, 16, v84
	v_and_b32_e32 v153, 0xffff0000, v84
	v_lshlrev_b32_e32 v154, 16, v85
	v_and_b32_e32 v155, 0xffff0000, v85
	v_lshlrev_b32_e32 v156, 16, v86
	v_and_b32_e32 v157, 0xffff0000, v86
	v_lshlrev_b32_e32 v158, 16, v87
	v_and_b32_e32 v159, 0xffff0000, v87
	v_lshlrev_b32_e32 v160, 16, v88
	v_and_b32_e32 v161, 0xffff0000, v88
	v_lshlrev_b32_e32 v162, 16, v89
	v_and_b32_e32 v163, 0xffff0000, v89
	v_lshlrev_b32_e32 v164, 16, v90
	v_and_b32_e32 v165, 0xffff0000, v90
	v_lshlrev_b32_e32 v166, 16, v91
	v_and_b32_e32 v167, 0xffff0000, v91
	v_lshlrev_b32_e32 v168, 16, v92
	v_and_b32_e32 v169, 0xffff0000, v92
	v_lshlrev_b32_e32 v170, 16, v93
	v_and_b32_e32 v171, 0xffff0000, v93
	v_lshlrev_b32_e32 v172, 16, v94
	v_and_b32_e32 v173, 0xffff0000, v94
	v_lshlrev_b32_e32 v174, 16, v95
	v_and_b32_e32 v175, 0xffff0000, v95
	v_pk_mul_f32 v[252:253], v[160:161], v[160:161]
	v_pk_mul_f32 v[254:255], v[162:163], v[162:163]
	v_pk_fma_f32 v[252:253], v[164:165], v[164:165], v[252:253]
	v_pk_fma_f32 v[254:255], v[166:167], v[166:167], v[254:255]
	v_pk_fma_f32 v[252:253], v[168:169], v[168:169], v[252:253]
	v_pk_fma_f32 v[254:255], v[170:171], v[170:171], v[254:255]
	v_pk_fma_f32 v[252:253], v[172:173], v[172:173], v[252:253]
	v_pk_fma_f32 v[254:255], v[174:175], v[174:175], v[254:255]
	v_pk_add_f32 v[252:253], v[252:253], v[254:255]
	s_nop 0
	v_add_f32_e32 v183, v252, v253
	s_nop 1
	v_add_f32_dpp v183, v183, v183 quad_perm:[1,0,3,2] row_mask:0xf bank_mask:0xf bound_ctrl:1
	s_nop 1
	v_add_f32_dpp v183, v183, v183 quad_perm:[2,3,0,1] row_mask:0xf bank_mask:0xf bound_ctrl:1
	s_nop 1
	v_add_f32_dpp v183, v183, v183 row_half_mirror row_mask:0xf bank_mask:0xf bound_ctrl:1
	s_nop 1
	v_add_f32_dpp v183, v183, v183 row_mirror row_mask:0xf bank_mask:0xf bound_ctrl:1
	s_nop 1
	v_readlane_b32 s98, v183, 0
	v_readlane_b32 s99, v183, 16
	v_readlane_b32 s100, v183, 32
	v_readlane_b32 s101, v183, 48
	s_nop 1
	v_mov_b32_e32 v183, s98
	v_add_f32_e32 v183, s99, v183
	v_add_f32_e32 v183, s100, v183
	v_add_f32_e32 v183, s101, v183
	v_fmamk_f32 v183, v183, 0x3a800000, v182
	v_cmp_gt_f32_e32 vcc, 0x800000, v183
	v_mul_f32_e32 v181, 0x4b800000, v183
	s_nop 1
	v_cndmask_b32_e32 v183, v183, v181, vcc
	v_rsq_f32_e32 v183, v183
	s_nop 0
	v_mul_f32_e32 v181, 0x45800000, v183
	v_cndmask_b32_e32 v184, v183, v181, vcc
	v_mov_b32_e32 v185, v184
	v_pk_mul_f32 v[160:161], v[160:161], v[184:185]
	v_pk_mul_f32 v[162:163], v[162:163], v[184:185]
	v_pk_mul_f32 v[164:165], v[164:165], v[184:185]
	v_pk_mul_f32 v[166:167], v[166:167], v[184:185]
	v_pk_mul_f32 v[168:169], v[168:169], v[184:185]
	v_pk_mul_f32 v[170:171], v[170:171], v[184:185]
	v_pk_mul_f32 v[172:173], v[172:173], v[184:185]
	v_pk_mul_f32 v[174:175], v[174:175], v[184:185]
	v_pk_fma_f32 v[144:145], v[160:161], v[128:129], v[144:145]
	v_pk_fma_f32 v[146:147], v[162:163], v[130:131], v[146:147]
	v_pk_fma_f32 v[148:149], v[164:165], v[132:133], v[148:149]
	v_pk_fma_f32 v[150:151], v[166:167], v[134:135], v[150:151]
	v_pk_fma_f32 v[152:153], v[168:169], v[136:137], v[152:153]
	v_pk_fma_f32 v[154:155], v[170:171], v[138:139], v[154:155]
	v_pk_fma_f32 v[156:157], v[172:173], v[140:141], v[156:157]
	v_pk_fma_f32 v[158:159], v[174:175], v[142:143], v[158:159]
	v_pk_mul_f32 v[252:253], v[144:145], v[144:145]
	v_pk_mul_f32 v[254:255], v[146:147], v[146:147]
	v_pk_fma_f32 v[252:253], v[148:149], v[148:149], v[252:253]
	v_pk_fma_f32 v[254:255], v[150:151], v[150:151], v[254:255]
	v_pk_fma_f32 v[252:253], v[152:153], v[152:153], v[252:253]
	v_pk_fma_f32 v[254:255], v[154:155], v[154:155], v[254:255]
	v_pk_fma_f32 v[252:253], v[156:157], v[156:157], v[252:253]
	v_pk_fma_f32 v[254:255], v[158:159], v[158:159], v[254:255]
	v_pk_add_f32 v[252:253], v[252:253], v[254:255]
	s_nop 0
	v_add_f32_e32 v183, v252, v253
	s_nop 1
	v_add_f32_dpp v183, v183, v183 quad_perm:[1,0,3,2] row_mask:0xf bank_mask:0xf bound_ctrl:1
	s_nop 1
	v_add_f32_dpp v183, v183, v183 quad_perm:[2,3,0,1] row_mask:0xf bank_mask:0xf bound_ctrl:1
	s_nop 1
	v_add_f32_dpp v183, v183, v183 row_half_mirror row_mask:0xf bank_mask:0xf bound_ctrl:1
	s_nop 1
	v_add_f32_dpp v183, v183, v183 row_mirror row_mask:0xf bank_mask:0xf bound_ctrl:1
	s_nop 1
	v_readlane_b32 s98, v183, 0
	v_readlane_b32 s99, v183, 16
	v_readlane_b32 s100, v183, 32
	v_readlane_b32 s101, v183, 48
	s_nop 1
	v_mov_b32_e32 v183, s98
	v_add_f32_e32 v183, s99, v183
	v_add_f32_e32 v183, s100, v183
	v_add_f32_e32 v183, s101, v183
	v_fmamk_f32 v183, v183, 0x3a800000, v182
	v_cmp_gt_f32_e32 vcc, 0x800000, v183
	v_mul_f32_e32 v181, 0x4b800000, v183
	s_nop 1
	v_cndmask_b32_e32 v183, v183, v181, vcc
	v_rsq_f32_e32 v183, v183
	s_nop 0
	v_mul_f32_e32 v181, 0x45800000, v183
	v_cndmask_b32_e32 v184, v183, v181, vcc
	v_mov_b32_e32 v185, v184
	v_cvt_pk_bf16_f32 v80, v144, v145
	v_cvt_pk_bf16_f32 v81, v146, v147
	v_cvt_pk_bf16_f32 v82, v148, v149
	v_cvt_pk_bf16_f32 v83, v150, v151
	v_cvt_pk_bf16_f32 v84, v152, v153
	v_cvt_pk_bf16_f32 v85, v154, v155
	v_cvt_pk_bf16_f32 v86, v156, v157
	v_cvt_pk_bf16_f32 v87, v158, v159
	v_add_u32_e32 v181, 0x2c00000, v177
	global_store_dwordx4 v181, v[80:83], s[78:79]
	global_store_dwordx4 v181, v[84:87], s[78:79] offset:1024
	v_add_u32_e32 v236, 0xa000, v237
	s_mov_b64 exec, 1
	global_store_dword v236, v184, s[78:79]
	s_mov_b64 exec, -1
	s_waitcnt vmcnt(4)
	v_lshlrev_b32_e32 v144, 16, v96
	v_and_b32_e32 v145, 0xffff0000, v96
	v_lshlrev_b32_e32 v146, 16, v97
	v_and_b32_e32 v147, 0xffff0000, v97
	v_lshlrev_b32_e32 v148, 16, v98
	v_and_b32_e32 v149, 0xffff0000, v98
	v_lshlrev_b32_e32 v150, 16, v99
	v_and_b32_e32 v151, 0xffff0000, v99
	v_lshlrev_b32_e32 v152, 16, v100
	v_and_b32_e32 v153, 0xffff0000, v100
	v_lshlrev_b32_e32 v154, 16, v101
	v_and_b32_e32 v155, 0xffff0000, v101
	v_lshlrev_b32_e32 v156, 16, v102
	v_and_b32_e32 v157, 0xffff0000, v102
	v_lshlrev_b32_e32 v158, 16, v103
	v_and_b32_e32 v159, 0xffff0000, v103
	v_lshlrev_b32_e32 v160, 16, v104
	v_and_b32_e32 v161, 0xffff0000, v104
	v_lshlrev_b32_e32 v162, 16, v105
	v_and_b32_e32 v163, 0xffff0000, v105
	v_lshlrev_b32_e32 v164, 16, v106
	v_and_b32_e32 v165, 0xffff0000, v106
	v_lshlrev_b32_e32 v166, 16, v107
	v_and_b32_e32 v167, 0xffff0000, v107
	v_lshlrev_b32_e32 v168, 16, v108
	v_and_b32_e32 v169, 0xffff0000, v108
	v_lshlrev_b32_e32 v170, 16, v109
	v_and_b32_e32 v171, 0xffff0000, v109
	v_lshlrev_b32_e32 v172, 16, v110
	v_and_b32_e32 v173, 0xffff0000, v110
	v_lshlrev_b32_e32 v174, 16, v111
	v_and_b32_e32 v175, 0xffff0000, v111
	v_pk_mul_f32 v[252:253], v[160:161], v[160:161]
	v_pk_mul_f32 v[254:255], v[162:163], v[162:163]
	v_pk_fma_f32 v[252:253], v[164:165], v[164:165], v[252:253]
	v_pk_fma_f32 v[254:255], v[166:167], v[166:167], v[254:255]
	v_pk_fma_f32 v[252:253], v[168:169], v[168:169], v[252:253]
	v_pk_fma_f32 v[254:255], v[170:171], v[170:171], v[254:255]
	v_pk_fma_f32 v[252:253], v[172:173], v[172:173], v[252:253]
	v_pk_fma_f32 v[254:255], v[174:175], v[174:175], v[254:255]
	v_pk_add_f32 v[252:253], v[252:253], v[254:255]
	s_nop 0
	v_add_f32_e32 v183, v252, v253
	s_nop 1
	v_add_f32_dpp v183, v183, v183 quad_perm:[1,0,3,2] row_mask:0xf bank_mask:0xf bound_ctrl:1
	s_nop 1
	v_add_f32_dpp v183, v183, v183 quad_perm:[2,3,0,1] row_mask:0xf bank_mask:0xf bound_ctrl:1
	s_nop 1
	v_add_f32_dpp v183, v183, v183 row_half_mirror row_mask:0xf bank_mask:0xf bound_ctrl:1
	s_nop 1
	v_add_f32_dpp v183, v183, v183 row_mirror row_mask:0xf bank_mask:0xf bound_ctrl:1
	s_nop 1
	v_readlane_b32 s98, v183, 0
	v_readlane_b32 s99, v183, 16
	v_readlane_b32 s100, v183, 32
	v_readlane_b32 s101, v183, 48
	s_nop 1
	v_mov_b32_e32 v183, s98
	v_add_f32_e32 v183, s99, v183
	v_add_f32_e32 v183, s100, v183
	v_add_f32_e32 v183, s101, v183
	v_fmamk_f32 v183, v183, 0x3a800000, v182
	v_cmp_gt_f32_e32 vcc, 0x800000, v183
	v_mul_f32_e32 v181, 0x4b800000, v183
	s_nop 1
	v_cndmask_b32_e32 v183, v183, v181, vcc
	v_rsq_f32_e32 v183, v183
	s_nop 0
	v_mul_f32_e32 v181, 0x45800000, v183
	v_cndmask_b32_e32 v184, v183, v181, vcc
	v_mov_b32_e32 v185, v184
	v_pk_mul_f32 v[160:161], v[160:161], v[184:185]
	v_pk_mul_f32 v[162:163], v[162:163], v[184:185]
	v_pk_mul_f32 v[164:165], v[164:165], v[184:185]
	v_pk_mul_f32 v[166:167], v[166:167], v[184:185]
	v_pk_mul_f32 v[168:169], v[168:169], v[184:185]
	v_pk_mul_f32 v[170:171], v[170:171], v[184:185]
	v_pk_mul_f32 v[172:173], v[172:173], v[184:185]
	v_pk_mul_f32 v[174:175], v[174:175], v[184:185]
	v_pk_fma_f32 v[144:145], v[160:161], v[128:129], v[144:145]
	v_pk_fma_f32 v[146:147], v[162:163], v[130:131], v[146:147]
	v_pk_fma_f32 v[148:149], v[164:165], v[132:133], v[148:149]
	v_pk_fma_f32 v[150:151], v[166:167], v[134:135], v[150:151]
	v_pk_fma_f32 v[152:153], v[168:169], v[136:137], v[152:153]
	v_pk_fma_f32 v[154:155], v[170:171], v[138:139], v[154:155]
	v_pk_fma_f32 v[156:157], v[172:173], v[140:141], v[156:157]
	v_pk_fma_f32 v[158:159], v[174:175], v[142:143], v[158:159]
	v_pk_mul_f32 v[252:253], v[144:145], v[144:145]
	v_pk_mul_f32 v[254:255], v[146:147], v[146:147]
	v_pk_fma_f32 v[252:253], v[148:149], v[148:149], v[252:253]
	v_pk_fma_f32 v[254:255], v[150:151], v[150:151], v[254:255]
	v_pk_fma_f32 v[252:253], v[152:153], v[152:153], v[252:253]
	v_pk_fma_f32 v[254:255], v[154:155], v[154:155], v[254:255]
	v_pk_fma_f32 v[252:253], v[156:157], v[156:157], v[252:253]
	v_pk_fma_f32 v[254:255], v[158:159], v[158:159], v[254:255]
	v_pk_add_f32 v[252:253], v[252:253], v[254:255]
	s_nop 0
	v_add_f32_e32 v183, v252, v253
	s_nop 1
	v_add_f32_dpp v183, v183, v183 quad_perm:[1,0,3,2] row_mask:0xf bank_mask:0xf bound_ctrl:1
	s_nop 1
	v_add_f32_dpp v183, v183, v183 quad_perm:[2,3,0,1] row_mask:0xf bank_mask:0xf bound_ctrl:1
	s_nop 1
	v_add_f32_dpp v183, v183, v183 row_half_mirror row_mask:0xf bank_mask:0xf bound_ctrl:1
	s_nop 1
	v_add_f32_dpp v183, v183, v183 row_mirror row_mask:0xf bank_mask:0xf bound_ctrl:1
	s_nop 1
	v_readlane_b32 s98, v183, 0
	v_readlane_b32 s99, v183, 16
	v_readlane_b32 s100, v183, 32
	v_readlane_b32 s101, v183, 48
	s_nop 1
	v_mov_b32_e32 v183, s98
	v_add_f32_e32 v183, s99, v183
	v_add_f32_e32 v183, s100, v183
	v_add_f32_e32 v183, s101, v183
	v_fmamk_f32 v183, v183, 0x3a800000, v182
	v_cmp_gt_f32_e32 vcc, 0x800000, v183
	v_mul_f32_e32 v181, 0x4b800000, v183
	s_nop 1
	v_cndmask_b32_e32 v183, v183, v181, vcc
	v_rsq_f32_e32 v183, v183
	s_nop 0
	v_mul_f32_e32 v181, 0x45800000, v183
	v_cndmask_b32_e32 v184, v183, v181, vcc
	v_mov_b32_e32 v185, v184
	v_cvt_pk_bf16_f32 v96, v144, v145
	v_cvt_pk_bf16_f32 v97, v146, v147
	v_cvt_pk_bf16_f32 v98, v148, v149
	v_cvt_pk_bf16_f32 v99, v150, v151
	v_cvt_pk_bf16_f32 v100, v152, v153
	v_cvt_pk_bf16_f32 v101, v154, v155
	v_cvt_pk_bf16_f32 v102, v156, v157
	v_cvt_pk_bf16_f32 v103, v158, v159
	v_add_u32_e32 v181, 0x3000000, v177
	global_store_dwordx4 v181, v[96:99], s[78:79]
	global_store_dwordx4 v181, v[100:103], s[78:79] offset:1024
	v_add_u32_e32 v236, 0xc000, v237
	s_mov_b64 exec, 1
	global_store_dword v236, v184, s[78:79]
	s_mov_b64 exec, -1
	s_waitcnt vmcnt(0)
	v_lshlrev_b32_e32 v144, 16, v112
	v_and_b32_e32 v145, 0xffff0000, v112
	v_lshlrev_b32_e32 v146, 16, v113
	v_and_b32_e32 v147, 0xffff0000, v113
	v_lshlrev_b32_e32 v148, 16, v114
	v_and_b32_e32 v149, 0xffff0000, v114
	v_lshlrev_b32_e32 v150, 16, v115
	v_and_b32_e32 v151, 0xffff0000, v115
	v_lshlrev_b32_e32 v152, 16, v116
	v_and_b32_e32 v153, 0xffff0000, v116
	v_lshlrev_b32_e32 v154, 16, v117
	v_and_b32_e32 v155, 0xffff0000, v117
	v_lshlrev_b32_e32 v156, 16, v118
	v_and_b32_e32 v157, 0xffff0000, v118
	v_lshlrev_b32_e32 v158, 16, v119
	v_and_b32_e32 v159, 0xffff0000, v119
	v_lshlrev_b32_e32 v160, 16, v120
	v_and_b32_e32 v161, 0xffff0000, v120
	v_lshlrev_b32_e32 v162, 16, v121
	v_and_b32_e32 v163, 0xffff0000, v121
	v_lshlrev_b32_e32 v164, 16, v122
	v_and_b32_e32 v165, 0xffff0000, v122
	v_lshlrev_b32_e32 v166, 16, v123
	v_and_b32_e32 v167, 0xffff0000, v123
	v_lshlrev_b32_e32 v168, 16, v124
	v_and_b32_e32 v169, 0xffff0000, v124
	v_lshlrev_b32_e32 v170, 16, v125
	v_and_b32_e32 v171, 0xffff0000, v125
	v_lshlrev_b32_e32 v172, 16, v126
	v_and_b32_e32 v173, 0xffff0000, v126
	v_lshlrev_b32_e32 v174, 16, v127
	v_and_b32_e32 v175, 0xffff0000, v127
	v_pk_mul_f32 v[252:253], v[160:161], v[160:161]
	v_pk_mul_f32 v[254:255], v[162:163], v[162:163]
	v_pk_fma_f32 v[252:253], v[164:165], v[164:165], v[252:253]
	v_pk_fma_f32 v[254:255], v[166:167], v[166:167], v[254:255]
	v_pk_fma_f32 v[252:253], v[168:169], v[168:169], v[252:253]
	v_pk_fma_f32 v[254:255], v[170:171], v[170:171], v[254:255]
	v_pk_fma_f32 v[252:253], v[172:173], v[172:173], v[252:253]
	v_pk_fma_f32 v[254:255], v[174:175], v[174:175], v[254:255]
	v_pk_add_f32 v[252:253], v[252:253], v[254:255]
	s_nop 0
	v_add_f32_e32 v183, v252, v253
	s_nop 1
	v_add_f32_dpp v183, v183, v183 quad_perm:[1,0,3,2] row_mask:0xf bank_mask:0xf bound_ctrl:1
	s_nop 1
	v_add_f32_dpp v183, v183, v183 quad_perm:[2,3,0,1] row_mask:0xf bank_mask:0xf bound_ctrl:1
	s_nop 1
	v_add_f32_dpp v183, v183, v183 row_half_mirror row_mask:0xf bank_mask:0xf bound_ctrl:1
	s_nop 1
	v_add_f32_dpp v183, v183, v183 row_mirror row_mask:0xf bank_mask:0xf bound_ctrl:1
	s_nop 1
	v_readlane_b32 s98, v183, 0
	v_readlane_b32 s99, v183, 16
	v_readlane_b32 s100, v183, 32
	v_readlane_b32 s101, v183, 48
	s_nop 1
	v_mov_b32_e32 v183, s98
	v_add_f32_e32 v183, s99, v183
	v_add_f32_e32 v183, s100, v183
	v_add_f32_e32 v183, s101, v183
	v_fmamk_f32 v183, v183, 0x3a800000, v182
	v_cmp_gt_f32_e32 vcc, 0x800000, v183
	v_mul_f32_e32 v181, 0x4b800000, v183
	s_nop 1
	v_cndmask_b32_e32 v183, v183, v181, vcc
	v_rsq_f32_e32 v183, v183
	s_nop 0
	v_mul_f32_e32 v181, 0x45800000, v183
	v_cndmask_b32_e32 v184, v183, v181, vcc
	v_mov_b32_e32 v185, v184
	v_pk_mul_f32 v[160:161], v[160:161], v[184:185]
	v_pk_mul_f32 v[162:163], v[162:163], v[184:185]
	v_pk_mul_f32 v[164:165], v[164:165], v[184:185]
	v_pk_mul_f32 v[166:167], v[166:167], v[184:185]
	v_pk_mul_f32 v[168:169], v[168:169], v[184:185]
	v_pk_mul_f32 v[170:171], v[170:171], v[184:185]
	v_pk_mul_f32 v[172:173], v[172:173], v[184:185]
	v_pk_mul_f32 v[174:175], v[174:175], v[184:185]
	v_pk_fma_f32 v[144:145], v[160:161], v[128:129], v[144:145]
	v_pk_fma_f32 v[146:147], v[162:163], v[130:131], v[146:147]
	v_pk_fma_f32 v[148:149], v[164:165], v[132:133], v[148:149]
	v_pk_fma_f32 v[150:151], v[166:167], v[134:135], v[150:151]
	v_pk_fma_f32 v[152:153], v[168:169], v[136:137], v[152:153]
	v_pk_fma_f32 v[154:155], v[170:171], v[138:139], v[154:155]
	v_pk_fma_f32 v[156:157], v[172:173], v[140:141], v[156:157]
	v_pk_fma_f32 v[158:159], v[174:175], v[142:143], v[158:159]
	v_pk_mul_f32 v[252:253], v[144:145], v[144:145]
	v_pk_mul_f32 v[254:255], v[146:147], v[146:147]
	v_pk_fma_f32 v[252:253], v[148:149], v[148:149], v[252:253]
	v_pk_fma_f32 v[254:255], v[150:151], v[150:151], v[254:255]
	v_pk_fma_f32 v[252:253], v[152:153], v[152:153], v[252:253]
	v_pk_fma_f32 v[254:255], v[154:155], v[154:155], v[254:255]
	v_pk_fma_f32 v[252:253], v[156:157], v[156:157], v[252:253]
	v_pk_fma_f32 v[254:255], v[158:159], v[158:159], v[254:255]
	v_pk_add_f32 v[252:253], v[252:253], v[254:255]
	s_nop 0
	v_add_f32_e32 v183, v252, v253
	s_nop 1
	v_add_f32_dpp v183, v183, v183 quad_perm:[1,0,3,2] row_mask:0xf bank_mask:0xf bound_ctrl:1
	s_nop 1
	v_add_f32_dpp v183, v183, v183 quad_perm:[2,3,0,1] row_mask:0xf bank_mask:0xf bound_ctrl:1
	s_nop 1
	v_add_f32_dpp v183, v183, v183 row_half_mirror row_mask:0xf bank_mask:0xf bound_ctrl:1
	s_nop 1
	v_add_f32_dpp v183, v183, v183 row_mirror row_mask:0xf bank_mask:0xf bound_ctrl:1
	s_nop 1
	v_readlane_b32 s98, v183, 0
	v_readlane_b32 s99, v183, 16
	v_readlane_b32 s100, v183, 32
	v_readlane_b32 s101, v183, 48
	s_nop 1
	v_mov_b32_e32 v183, s98
	v_add_f32_e32 v183, s99, v183
	v_add_f32_e32 v183, s100, v183
	v_add_f32_e32 v183, s101, v183
	v_fmamk_f32 v183, v183, 0x3a800000, v182
	v_cmp_gt_f32_e32 vcc, 0x800000, v183
	v_mul_f32_e32 v181, 0x4b800000, v183
	s_nop 1
	v_cndmask_b32_e32 v183, v183, v181, vcc
	v_rsq_f32_e32 v183, v183
	s_nop 0
	v_mul_f32_e32 v181, 0x45800000, v183
	v_cndmask_b32_e32 v184, v183, v181, vcc
	v_mov_b32_e32 v185, v184
	v_cvt_pk_bf16_f32 v112, v144, v145
	v_cvt_pk_bf16_f32 v113, v146, v147
	v_cvt_pk_bf16_f32 v114, v148, v149
	v_cvt_pk_bf16_f32 v115, v150, v151
	v_cvt_pk_bf16_f32 v116, v152, v153
	v_cvt_pk_bf16_f32 v117, v154, v155
	v_cvt_pk_bf16_f32 v118, v156, v157
	v_cvt_pk_bf16_f32 v119, v158, v159
	v_add_u32_e32 v181, 0x3400000, v177
	global_store_dwordx4 v181, v[112:115], s[78:79]
	global_store_dwordx4 v181, v[116:119], s[78:79] offset:1024
	v_add_u32_e32 v236, 0xe000, v237
	s_mov_b64 exec, 1
	global_store_dword v236, v184, s[78:79]
	s_mov_b64 exec, -1
	v_readfirstlane_b32 s98, v179
	s_nop 3
	s_and_b32 s99, s98, 3
	s_add_i32 s100, s99, 4
	s_lshl_b32 s100, s100, 11
	s_sub_i32 s100, s100, s99
	s_lshl_b32 s101, s100, 11
	v_add_u32_e32 v177, s101, v177
	s_lshl_b32 s101, s100, 2
	v_add_u32_e32 v237, s101, v237
	v_add_u32_e32 v181, 0x1800000, v177
	global_load_dwordx4 v[0:3], v181, s[78:79]
	global_load_dwordx4 v[4:7], v181, s[78:79] offset:1024
	v_add_u32_e32 v181, 0x9e00000, v177
	global_load_dwordx4 v[8:11], v181, s[78:79]
	global_load_dwordx4 v[12:15], v181, s[78:79] offset:1024
	s_waitcnt vmcnt(0)
	v_lshlrev_b32_e32 v144, 16, v0
	v_and_b32_e32 v145, 0xffff0000, v0
	v_lshlrev_b32_e32 v146, 16, v1
	v_and_b32_e32 v147, 0xffff0000, v1
	v_lshlrev_b32_e32 v148, 16, v2
	v_and_b32_e32 v149, 0xffff0000, v2
	v_lshlrev_b32_e32 v150, 16, v3
	v_and_b32_e32 v151, 0xffff0000, v3
	v_lshlrev_b32_e32 v152, 16, v4
	v_and_b32_e32 v153, 0xffff0000, v4
	v_lshlrev_b32_e32 v154, 16, v5
	v_and_b32_e32 v155, 0xffff0000, v5
	v_lshlrev_b32_e32 v156, 16, v6
	v_and_b32_e32 v157, 0xffff0000, v6
	v_lshlrev_b32_e32 v158, 16, v7
	v_and_b32_e32 v159, 0xffff0000, v7
	v_lshlrev_b32_e32 v160, 16, v8
	v_and_b32_e32 v161, 0xffff0000, v8
	v_lshlrev_b32_e32 v162, 16, v9
	v_and_b32_e32 v163, 0xffff0000, v9
	v_lshlrev_b32_e32 v164, 16, v10
	v_and_b32_e32 v165, 0xffff0000, v10
	v_lshlrev_b32_e32 v166, 16, v11
	v_and_b32_e32 v167, 0xffff0000, v11
	v_lshlrev_b32_e32 v168, 16, v12
	v_and_b32_e32 v169, 0xffff0000, v12
	v_lshlrev_b32_e32 v170, 16, v13
	v_and_b32_e32 v171, 0xffff0000, v13
	v_lshlrev_b32_e32 v172, 16, v14
	v_and_b32_e32 v173, 0xffff0000, v14
	v_lshlrev_b32_e32 v174, 16, v15
	v_and_b32_e32 v175, 0xffff0000, v15
	v_pk_mul_f32 v[252:253], v[160:161], v[160:161]
	v_pk_mul_f32 v[254:255], v[162:163], v[162:163]
	v_pk_fma_f32 v[252:253], v[164:165], v[164:165], v[252:253]
	v_pk_fma_f32 v[254:255], v[166:167], v[166:167], v[254:255]
	v_pk_fma_f32 v[252:253], v[168:169], v[168:169], v[252:253]
	v_pk_fma_f32 v[254:255], v[170:171], v[170:171], v[254:255]
	v_pk_fma_f32 v[252:253], v[172:173], v[172:173], v[252:253]
	v_pk_fma_f32 v[254:255], v[174:175], v[174:175], v[254:255]
	v_pk_add_f32 v[252:253], v[252:253], v[254:255]
	s_nop 0
	v_add_f32_e32 v183, v252, v253
	s_nop 1
	v_add_f32_dpp v183, v183, v183 quad_perm:[1,0,3,2] row_mask:0xf bank_mask:0xf bound_ctrl:1
	s_nop 1
	v_add_f32_dpp v183, v183, v183 quad_perm:[2,3,0,1] row_mask:0xf bank_mask:0xf bound_ctrl:1
	s_nop 1
	v_add_f32_dpp v183, v183, v183 row_half_mirror row_mask:0xf bank_mask:0xf bound_ctrl:1
	s_nop 1
	v_add_f32_dpp v183, v183, v183 row_mirror row_mask:0xf bank_mask:0xf bound_ctrl:1
	s_nop 1
	v_readlane_b32 s98, v183, 0
	v_readlane_b32 s99, v183, 16
	v_readlane_b32 s100, v183, 32
	v_readlane_b32 s101, v183, 48
	s_nop 1
	v_mov_b32_e32 v183, s98
	v_add_f32_e32 v183, s99, v183
	v_add_f32_e32 v183, s100, v183
	v_add_f32_e32 v183, s101, v183
	v_fmamk_f32 v183, v183, 0x3a800000, v182
	v_cmp_gt_f32_e32 vcc, 0x800000, v183
	v_mul_f32_e32 v181, 0x4b800000, v183
	s_nop 1
	v_cndmask_b32_e32 v183, v183, v181, vcc
	v_rsq_f32_e32 v183, v183
	s_nop 0
	v_mul_f32_e32 v181, 0x45800000, v183
	v_cndmask_b32_e32 v184, v183, v181, vcc
	v_mov_b32_e32 v185, v184
	v_pk_mul_f32 v[160:161], v[160:161], v[184:185]
	v_pk_mul_f32 v[162:163], v[162:163], v[184:185]
	v_pk_mul_f32 v[164:165], v[164:165], v[184:185]
	v_pk_mul_f32 v[166:167], v[166:167], v[184:185]
	v_pk_mul_f32 v[168:169], v[168:169], v[184:185]
	v_pk_mul_f32 v[170:171], v[170:171], v[184:185]
	v_pk_mul_f32 v[172:173], v[172:173], v[184:185]
	v_pk_mul_f32 v[174:175], v[174:175], v[184:185]
	v_pk_fma_f32 v[144:145], v[160:161], v[128:129], v[144:145]
	v_pk_fma_f32 v[146:147], v[162:163], v[130:131], v[146:147]
	v_pk_fma_f32 v[148:149], v[164:165], v[132:133], v[148:149]
	v_pk_fma_f32 v[150:151], v[166:167], v[134:135], v[150:151]
	v_pk_fma_f32 v[152:153], v[168:169], v[136:137], v[152:153]
	v_pk_fma_f32 v[154:155], v[170:171], v[138:139], v[154:155]
	v_pk_fma_f32 v[156:157], v[172:173], v[140:141], v[156:157]
	v_pk_fma_f32 v[158:159], v[174:175], v[142:143], v[158:159]
	v_pk_mul_f32 v[252:253], v[144:145], v[144:145]
	v_pk_mul_f32 v[254:255], v[146:147], v[146:147]
	v_pk_fma_f32 v[252:253], v[148:149], v[148:149], v[252:253]
	v_pk_fma_f32 v[254:255], v[150:151], v[150:151], v[254:255]
	v_pk_fma_f32 v[252:253], v[152:153], v[152:153], v[252:253]
	v_pk_fma_f32 v[254:255], v[154:155], v[154:155], v[254:255]
	v_pk_fma_f32 v[252:253], v[156:157], v[156:157], v[252:253]
	v_pk_fma_f32 v[254:255], v[158:159], v[158:159], v[254:255]
	v_pk_add_f32 v[252:253], v[252:253], v[254:255]
	s_nop 0
	v_add_f32_e32 v183, v252, v253
	s_nop 1
	v_add_f32_dpp v183, v183, v183 quad_perm:[1,0,3,2] row_mask:0xf bank_mask:0xf bound_ctrl:1
	s_nop 1
	v_add_f32_dpp v183, v183, v183 quad_perm:[2,3,0,1] row_mask:0xf bank_mask:0xf bound_ctrl:1
	s_nop 1
	v_add_f32_dpp v183, v183, v183 row_half_mirror row_mask:0xf bank_mask:0xf bound_ctrl:1
	s_nop 1
	v_add_f32_dpp v183, v183, v183 row_mirror row_mask:0xf bank_mask:0xf bound_ctrl:1
	s_nop 1
	v_readlane_b32 s98, v183, 0
	v_readlane_b32 s99, v183, 16
	v_readlane_b32 s100, v183, 32
	v_readlane_b32 s101, v183, 48
	s_nop 1
	v_mov_b32_e32 v183, s98
	v_add_f32_e32 v183, s99, v183
	v_add_f32_e32 v183, s100, v183
	v_add_f32_e32 v183, s101, v183
	v_fmamk_f32 v183, v183, 0x3a800000, v182
	v_cmp_gt_f32_e32 vcc, 0x800000, v183
	v_mul_f32_e32 v181, 0x4b800000, v183
	s_nop 1
	v_cndmask_b32_e32 v183, v183, v181, vcc
	v_rsq_f32_e32 v183, v183
	s_nop 0
	v_mul_f32_e32 v181, 0x45800000, v183
	v_cndmask_b32_e32 v184, v183, v181, vcc
	v_mov_b32_e32 v185, v184
	v_cvt_pk_bf16_f32 v0, v144, v145
	v_cvt_pk_bf16_f32 v1, v146, v147
	v_cvt_pk_bf16_f32 v2, v148, v149
	v_cvt_pk_bf16_f32 v3, v150, v151
	v_cvt_pk_bf16_f32 v4, v152, v153
	v_cvt_pk_bf16_f32 v5, v154, v155
	v_cvt_pk_bf16_f32 v6, v156, v157
	v_cvt_pk_bf16_f32 v7, v158, v159
	v_add_u32_e32 v181, 0x1800000, v177
	global_store_dwordx4 v181, v[0:3], s[78:79]
	global_store_dwordx4 v181, v[4:7], s[78:79] offset:1024
	v_add_u32_e32 v236, 0x0, v237
	s_mov_b64 exec, 1
	global_store_dword v236, v184, s[78:79]
	s_mov_b64 exec, -1
	s_branch .Lmyxupd_done_1
.Lmyxupd_heavy_1:
	global_load_dwordx4 v[0:3], v178, s[78:79]
	global_load_dwordx4 v[4:7], v178, s[78:79] offset:1024
	global_load_dwordx4 v[8:11], v179, s[78:79]
	global_load_dwordx4 v[12:15], v179, s[78:79] offset:1024
	v_add_u32_e32 v178, 0x400000, v178
	v_add_u32_e32 v179, 0x400000, v179
	global_load_dwordx4 v[16:19], v178, s[78:79]
	global_load_dwordx4 v[20:23], v178, s[78:79] offset:1024
	global_load_dwordx4 v[24:27], v179, s[78:79]
	global_load_dwordx4 v[28:31], v179, s[78:79] offset:1024
	v_add_u32_e32 v178, 0x400000, v178
	v_add_u32_e32 v179, 0x400000, v179
	global_load_dwordx4 v[32:35], v178, s[78:79]
	global_load_dwordx4 v[36:39], v178, s[78:79] offset:1024
	global_load_dwordx4 v[40:43], v179, s[78:79]
	global_load_dwordx4 v[44:47], v179, s[78:79] offset:1024
	v_add_u32_e32 v178, 0x400000, v178
	v_add_u32_e32 v179, 0x400000, v179
	global_load_dwordx4 v[48:51], v178, s[78:79]
	global_load_dwordx4 v[52:55], v178, s[78:79] offset:1024
	global_load_dwordx4 v[56:59], v179, s[78:79]
	global_load_dwordx4 v[60:63], v179, s[78:79] offset:1024
	v_add_u32_e32 v178, 0x400000, v178
	v_add_u32_e32 v179, 0x400000, v179
	global_load_dwordx4 v[64:67], v178, s[78:79]
	global_load_dwordx4 v[68:71], v178, s[78:79] offset:1024
	global_load_dwordx4 v[72:75], v179, s[78:79]
	global_load_dwordx4 v[76:79], v179, s[78:79] offset:1024
	v_lshlrev_b32_e32 v237, 2, v183
	v_add_u32_e32 v237, 0x10000, v237
	v_mov_b32_e32 v179, s98
	s_waitcnt vmcnt(16)
	v_lshlrev_b32_e32 v144, 16, v0
	v_and_b32_e32 v145, 0xffff0000, v0
	v_lshlrev_b32_e32 v146, 16, v1
	v_and_b32_e32 v147, 0xffff0000, v1
	v_lshlrev_b32_e32 v148, 16, v2
	v_and_b32_e32 v149, 0xffff0000, v2
	v_lshlrev_b32_e32 v150, 16, v3
	v_and_b32_e32 v151, 0xffff0000, v3
	v_lshlrev_b32_e32 v152, 16, v4
	v_and_b32_e32 v153, 0xffff0000, v4
	v_lshlrev_b32_e32 v154, 16, v5
	v_and_b32_e32 v155, 0xffff0000, v5
	v_lshlrev_b32_e32 v156, 16, v6
	v_and_b32_e32 v157, 0xffff0000, v6
	v_lshlrev_b32_e32 v158, 16, v7
	v_and_b32_e32 v159, 0xffff0000, v7
	v_lshlrev_b32_e32 v160, 16, v8
	v_and_b32_e32 v161, 0xffff0000, v8
	v_lshlrev_b32_e32 v162, 16, v9
	v_and_b32_e32 v163, 0xffff0000, v9
	v_lshlrev_b32_e32 v164, 16, v10
	v_and_b32_e32 v165, 0xffff0000, v10
	v_lshlrev_b32_e32 v166, 16, v11
	v_and_b32_e32 v167, 0xffff0000, v11
	v_lshlrev_b32_e32 v168, 16, v12
	v_and_b32_e32 v169, 0xffff0000, v12
	v_lshlrev_b32_e32 v170, 16, v13
	v_and_b32_e32 v171, 0xffff0000, v13
	v_lshlrev_b32_e32 v172, 16, v14
	v_and_b32_e32 v173, 0xffff0000, v14
	v_lshlrev_b32_e32 v174, 16, v15
	v_and_b32_e32 v175, 0xffff0000, v15
	v_pk_mul_f32 v[252:253], v[160:161], v[160:161]
	v_pk_mul_f32 v[254:255], v[162:163], v[162:163]
	v_pk_fma_f32 v[252:253], v[164:165], v[164:165], v[252:253]
	v_pk_fma_f32 v[254:255], v[166:167], v[166:167], v[254:255]
	v_pk_fma_f32 v[252:253], v[168:169], v[168:169], v[252:253]
	v_pk_fma_f32 v[254:255], v[170:171], v[170:171], v[254:255]
	v_pk_fma_f32 v[252:253], v[172:173], v[172:173], v[252:253]
	v_pk_fma_f32 v[254:255], v[174:175], v[174:175], v[254:255]
	v_pk_add_f32 v[252:253], v[252:253], v[254:255]
	s_nop 0
	v_add_f32_e32 v183, v252, v253
	s_nop 1
	v_add_f32_dpp v183, v183, v183 quad_perm:[1,0,3,2] row_mask:0xf bank_mask:0xf bound_ctrl:1
	s_nop 1
	v_add_f32_dpp v183, v183, v183 quad_perm:[2,3,0,1] row_mask:0xf bank_mask:0xf bound_ctrl:1
	s_nop 1
	v_add_f32_dpp v183, v183, v183 row_half_mirror row_mask:0xf bank_mask:0xf bound_ctrl:1
	s_nop 1
	v_add_f32_dpp v183, v183, v183 row_mirror row_mask:0xf bank_mask:0xf bound_ctrl:1
	s_nop 1
	v_readlane_b32 s98, v183, 0
	v_readlane_b32 s99, v183, 16
	v_readlane_b32 s100, v183, 32
	v_readlane_b32 s101, v183, 48
	s_nop 1
	v_mov_b32_e32 v183, s98
	v_add_f32_e32 v183, s99, v183
	v_add_f32_e32 v183, s100, v183
	v_add_f32_e32 v183, s101, v183
	v_fmamk_f32 v183, v183, 0x3a800000, v182
	v_cmp_gt_f32_e32 vcc, 0x800000, v183
	v_mul_f32_e32 v181, 0x4b800000, v183
	s_nop 1
	v_cndmask_b32_e32 v183, v183, v181, vcc
	v_rsq_f32_e32 v183, v183
	s_nop 0
	v_mul_f32_e32 v181, 0x45800000, v183
	v_cndmask_b32_e32 v184, v183, v181, vcc
	v_mov_b32_e32 v185, v184
	v_pk_mul_f32 v[160:161], v[160:161], v[184:185]
	v_pk_mul_f32 v[162:163], v[162:163], v[184:185]
	v_pk_mul_f32 v[164:165], v[164:165], v[184:185]
	v_pk_mul_f32 v[166:167], v[166:167], v[184:185]
	v_pk_mul_f32 v[168:169], v[168:169], v[184:185]
	v_pk_mul_f32 v[170:171], v[170:171], v[184:185]
	v_pk_mul_f32 v[172:173], v[172:173], v[184:185]
	v_pk_mul_f32 v[174:175], v[174:175], v[184:185]
	v_pk_fma_f32 v[144:145], v[160:161], v[128:129], v[144:145]
	v_pk_fma_f32 v[146:147], v[162:163], v[130:131], v[146:147]
	v_pk_fma_f32 v[148:149], v[164:165], v[132:133], v[148:149]
	v_pk_fma_f32 v[150:151], v[166:167], v[134:135], v[150:151]
	v_pk_fma_f32 v[152:153], v[168:169], v[136:137], v[152:153]
	v_pk_fma_f32 v[154:155], v[170:171], v[138:139], v[154:155]
	v_pk_fma_f32 v[156:157], v[172:173], v[140:141], v[156:157]
	v_pk_fma_f32 v[158:159], v[174:175], v[142:143], v[158:159]
	v_pk_mul_f32 v[252:253], v[144:145], v[144:145]
	v_pk_mul_f32 v[254:255], v[146:147], v[146:147]
	v_pk_fma_f32 v[252:253], v[148:149], v[148:149], v[252:253]
	v_pk_fma_f32 v[254:255], v[150:151], v[150:151], v[254:255]
	v_pk_fma_f32 v[252:253], v[152:153], v[152:153], v[252:253]
	v_pk_fma_f32 v[254:255], v[154:155], v[154:155], v[254:255]
	v_pk_fma_f32 v[252:253], v[156:157], v[156:157], v[252:253]
	v_pk_fma_f32 v[254:255], v[158:159], v[158:159], v[254:255]
	v_pk_add_f32 v[252:253], v[252:253], v[254:255]
	s_nop 0
	v_add_f32_e32 v183, v252, v253
	s_nop 1
	v_add_f32_dpp v183, v183, v183 quad_perm:[1,0,3,2] row_mask:0xf bank_mask:0xf bound_ctrl:1
	s_nop 1
	v_add_f32_dpp v183, v183, v183 quad_perm:[2,3,0,1] row_mask:0xf bank_mask:0xf bound_ctrl:1
	s_nop 1
	v_add_f32_dpp v183, v183, v183 row_half_mirror row_mask:0xf bank_mask:0xf bound_ctrl:1
	s_nop 1
	v_add_f32_dpp v183, v183, v183 row_mirror row_mask:0xf bank_mask:0xf bound_ctrl:1
	s_nop 1
	v_readlane_b32 s98, v183, 0
	v_readlane_b32 s99, v183, 16
	v_readlane_b32 s100, v183, 32
	v_readlane_b32 s101, v183, 48
	s_nop 1
	v_mov_b32_e32 v183, s98
	v_add_f32_e32 v183, s99, v183
	v_add_f32_e32 v183, s100, v183
	v_add_f32_e32 v183, s101, v183
	v_fmamk_f32 v183, v183, 0x3a800000, v182
	v_cmp_gt_f32_e32 vcc, 0x800000, v183
	v_mul_f32_e32 v181, 0x4b800000, v183
	s_nop 1
	v_cndmask_b32_e32 v183, v183, v181, vcc
	v_rsq_f32_e32 v183, v183
	s_nop 0
	v_mul_f32_e32 v181, 0x45800000, v183
	v_cndmask_b32_e32 v184, v183, v181, vcc
	v_mov_b32_e32 v185, v184
	v_cvt_pk_bf16_f32 v0, v144, v145
	v_cvt_pk_bf16_f32 v1, v146, v147
	v_cvt_pk_bf16_f32 v2, v148, v149
	v_cvt_pk_bf16_f32 v3, v150, v151
	v_cvt_pk_bf16_f32 v4, v152, v153
	v_cvt_pk_bf16_f32 v5, v154, v155
	v_cvt_pk_bf16_f32 v6, v156, v157
	v_cvt_pk_bf16_f32 v7, v158, v159
	v_add_u32_e32 v181, 0x1800000, v177
	global_store_dwordx4 v181, v[0:3], s[78:79]
	global_store_dwordx4 v181, v[4:7], s[78:79] offset:1024
	v_add_u32_e32 v236, 0x0, v237
	s_mov_b64 exec, 1
	global_store_dword v236, v184, s[78:79]
	s_mov_b64 exec, -1
	s_waitcnt vmcnt(12)
	v_lshlrev_b32_e32 v144, 16, v16
	v_and_b32_e32 v145, 0xffff0000, v16
	v_lshlrev_b32_e32 v146, 16, v17
	v_and_b32_e32 v147, 0xffff0000, v17
	v_lshlrev_b32_e32 v148, 16, v18
	v_and_b32_e32 v149, 0xffff0000, v18
	v_lshlrev_b32_e32 v150, 16, v19
	v_and_b32_e32 v151, 0xffff0000, v19
	v_lshlrev_b32_e32 v152, 16, v20
	v_and_b32_e32 v153, 0xffff0000, v20
	v_lshlrev_b32_e32 v154, 16, v21
	v_and_b32_e32 v155, 0xffff0000, v21
	v_lshlrev_b32_e32 v156, 16, v22
	v_and_b32_e32 v157, 0xffff0000, v22
	v_lshlrev_b32_e32 v158, 16, v23
	v_and_b32_e32 v159, 0xffff0000, v23
	v_lshlrev_b32_e32 v160, 16, v24
	v_and_b32_e32 v161, 0xffff0000, v24
	v_lshlrev_b32_e32 v162, 16, v25
	v_and_b32_e32 v163, 0xffff0000, v25
	v_lshlrev_b32_e32 v164, 16, v26
	v_and_b32_e32 v165, 0xffff0000, v26
	v_lshlrev_b32_e32 v166, 16, v27
	v_and_b32_e32 v167, 0xffff0000, v27
	v_lshlrev_b32_e32 v168, 16, v28
	v_and_b32_e32 v169, 0xffff0000, v28
	v_lshlrev_b32_e32 v170, 16, v29
	v_and_b32_e32 v171, 0xffff0000, v29
	v_lshlrev_b32_e32 v172, 16, v30
	v_and_b32_e32 v173, 0xffff0000, v30
	v_lshlrev_b32_e32 v174, 16, v31
	v_and_b32_e32 v175, 0xffff0000, v31
	v_pk_mul_f32 v[252:253], v[160:161], v[160:161]
	v_pk_mul_f32 v[254:255], v[162:163], v[162:163]
	v_pk_fma_f32 v[252:253], v[164:165], v[164:165], v[252:253]
	v_pk_fma_f32 v[254:255], v[166:167], v[166:167], v[254:255]
	v_pk_fma_f32 v[252:253], v[168:169], v[168:169], v[252:253]
	v_pk_fma_f32 v[254:255], v[170:171], v[170:171], v[254:255]
	v_pk_fma_f32 v[252:253], v[172:173], v[172:173], v[252:253]
	v_pk_fma_f32 v[254:255], v[174:175], v[174:175], v[254:255]
	v_pk_add_f32 v[252:253], v[252:253], v[254:255]
	s_nop 0
	v_add_f32_e32 v183, v252, v253
	s_nop 1
	v_add_f32_dpp v183, v183, v183 quad_perm:[1,0,3,2] row_mask:0xf bank_mask:0xf bound_ctrl:1
	s_nop 1
	v_add_f32_dpp v183, v183, v183 quad_perm:[2,3,0,1] row_mask:0xf bank_mask:0xf bound_ctrl:1
	s_nop 1
	v_add_f32_dpp v183, v183, v183 row_half_mirror row_mask:0xf bank_mask:0xf bound_ctrl:1
	s_nop 1
	v_add_f32_dpp v183, v183, v183 row_mirror row_mask:0xf bank_mask:0xf bound_ctrl:1
	s_nop 1
	v_readlane_b32 s98, v183, 0
	v_readlane_b32 s99, v183, 16
	v_readlane_b32 s100, v183, 32
	v_readlane_b32 s101, v183, 48
	s_nop 1
	v_mov_b32_e32 v183, s98
	v_add_f32_e32 v183, s99, v183
	v_add_f32_e32 v183, s100, v183
	v_add_f32_e32 v183, s101, v183
	v_fmamk_f32 v183, v183, 0x3a800000, v182
	v_cmp_gt_f32_e32 vcc, 0x800000, v183
	v_mul_f32_e32 v181, 0x4b800000, v183
	s_nop 1
	v_cndmask_b32_e32 v183, v183, v181, vcc
	v_rsq_f32_e32 v183, v183
	s_nop 0
	v_mul_f32_e32 v181, 0x45800000, v183
	v_cndmask_b32_e32 v184, v183, v181, vcc
	v_mov_b32_e32 v185, v184
	v_pk_mul_f32 v[160:161], v[160:161], v[184:185]
	v_pk_mul_f32 v[162:163], v[162:163], v[184:185]
	v_pk_mul_f32 v[164:165], v[164:165], v[184:185]
	v_pk_mul_f32 v[166:167], v[166:167], v[184:185]
	v_pk_mul_f32 v[168:169], v[168:169], v[184:185]
	v_pk_mul_f32 v[170:171], v[170:171], v[184:185]
	v_pk_mul_f32 v[172:173], v[172:173], v[184:185]
	v_pk_mul_f32 v[174:175], v[174:175], v[184:185]
	v_pk_fma_f32 v[144:145], v[160:161], v[128:129], v[144:145]
	v_pk_fma_f32 v[146:147], v[162:163], v[130:131], v[146:147]
	v_pk_fma_f32 v[148:149], v[164:165], v[132:133], v[148:149]
	v_pk_fma_f32 v[150:151], v[166:167], v[134:135], v[150:151]
	v_pk_fma_f32 v[152:153], v[168:169], v[136:137], v[152:153]
	v_pk_fma_f32 v[154:155], v[170:171], v[138:139], v[154:155]
	v_pk_fma_f32 v[156:157], v[172:173], v[140:141], v[156:157]
	v_pk_fma_f32 v[158:159], v[174:175], v[142:143], v[158:159]
	v_pk_mul_f32 v[252:253], v[144:145], v[144:145]
	v_pk_mul_f32 v[254:255], v[146:147], v[146:147]
	v_pk_fma_f32 v[252:253], v[148:149], v[148:149], v[252:253]
	v_pk_fma_f32 v[254:255], v[150:151], v[150:151], v[254:255]
	v_pk_fma_f32 v[252:253], v[152:153], v[152:153], v[252:253]
	v_pk_fma_f32 v[254:255], v[154:155], v[154:155], v[254:255]
	v_pk_fma_f32 v[252:253], v[156:157], v[156:157], v[252:253]
	v_pk_fma_f32 v[254:255], v[158:159], v[158:159], v[254:255]
	v_pk_add_f32 v[252:253], v[252:253], v[254:255]
	s_nop 0
	v_add_f32_e32 v183, v252, v253
	s_nop 1
	v_add_f32_dpp v183, v183, v183 quad_perm:[1,0,3,2] row_mask:0xf bank_mask:0xf bound_ctrl:1
	s_nop 1
	v_add_f32_dpp v183, v183, v183 quad_perm:[2,3,0,1] row_mask:0xf bank_mask:0xf bound_ctrl:1
	s_nop 1
	v_add_f32_dpp v183, v183, v183 row_half_mirror row_mask:0xf bank_mask:0xf bound_ctrl:1
	s_nop 1
	v_add_f32_dpp v183, v183, v183 row_mirror row_mask:0xf bank_mask:0xf bound_ctrl:1
	s_nop 1
	v_readlane_b32 s98, v183, 0
	v_readlane_b32 s99, v183, 16
	v_readlane_b32 s100, v183, 32
	v_readlane_b32 s101, v183, 48
	s_nop 1
	v_mov_b32_e32 v183, s98
	v_add_f32_e32 v183, s99, v183
	v_add_f32_e32 v183, s100, v183
	v_add_f32_e32 v183, s101, v183
	v_fmamk_f32 v183, v183, 0x3a800000, v182
	v_cmp_gt_f32_e32 vcc, 0x800000, v183
	v_mul_f32_e32 v181, 0x4b800000, v183
	s_nop 1
	v_cndmask_b32_e32 v183, v183, v181, vcc
	v_rsq_f32_e32 v183, v183
	s_nop 0
	v_mul_f32_e32 v181, 0x45800000, v183
	v_cndmask_b32_e32 v184, v183, v181, vcc
	v_mov_b32_e32 v185, v184
	v_cvt_pk_bf16_f32 v16, v144, v145
	v_cvt_pk_bf16_f32 v17, v146, v147
	v_cvt_pk_bf16_f32 v18, v148, v149
	v_cvt_pk_bf16_f32 v19, v150, v151
	v_cvt_pk_bf16_f32 v20, v152, v153
	v_cvt_pk_bf16_f32 v21, v154, v155
	v_cvt_pk_bf16_f32 v22, v156, v157
	v_cvt_pk_bf16_f32 v23, v158, v159
	v_add_u32_e32 v181, 0x1c00000, v177
	global_store_dwordx4 v181, v[16:19], s[78:79]
	global_store_dwordx4 v181, v[20:23], s[78:79] offset:1024
	v_add_u32_e32 v236, 0x2000, v237
	s_mov_b64 exec, 1
	global_store_dword v236, v184, s[78:79]
	s_mov_b64 exec, -1
	s_waitcnt vmcnt(8)
	v_lshlrev_b32_e32 v144, 16, v32
	v_and_b32_e32 v145, 0xffff0000, v32
	v_lshlrev_b32_e32 v146, 16, v33
	v_and_b32_e32 v147, 0xffff0000, v33
	v_lshlrev_b32_e32 v148, 16, v34
	v_and_b32_e32 v149, 0xffff0000, v34
	v_lshlrev_b32_e32 v150, 16, v35
	v_and_b32_e32 v151, 0xffff0000, v35
	v_lshlrev_b32_e32 v152, 16, v36
	v_and_b32_e32 v153, 0xffff0000, v36
	v_lshlrev_b32_e32 v154, 16, v37
	v_and_b32_e32 v155, 0xffff0000, v37
	v_lshlrev_b32_e32 v156, 16, v38
	v_and_b32_e32 v157, 0xffff0000, v38
	v_lshlrev_b32_e32 v158, 16, v39
	v_and_b32_e32 v159, 0xffff0000, v39
	v_lshlrev_b32_e32 v160, 16, v40
	v_and_b32_e32 v161, 0xffff0000, v40
	v_lshlrev_b32_e32 v162, 16, v41
	v_and_b32_e32 v163, 0xffff0000, v41
	v_lshlrev_b32_e32 v164, 16, v42
	v_and_b32_e32 v165, 0xffff0000, v42
	v_lshlrev_b32_e32 v166, 16, v43
	v_and_b32_e32 v167, 0xffff0000, v43
	v_lshlrev_b32_e32 v168, 16, v44
	v_and_b32_e32 v169, 0xffff0000, v44
	v_lshlrev_b32_e32 v170, 16, v45
	v_and_b32_e32 v171, 0xffff0000, v45
	v_lshlrev_b32_e32 v172, 16, v46
	v_and_b32_e32 v173, 0xffff0000, v46
	v_lshlrev_b32_e32 v174, 16, v47
	v_and_b32_e32 v175, 0xffff0000, v47
	v_pk_mul_f32 v[252:253], v[160:161], v[160:161]
	v_pk_mul_f32 v[254:255], v[162:163], v[162:163]
	v_pk_fma_f32 v[252:253], v[164:165], v[164:165], v[252:253]
	v_pk_fma_f32 v[254:255], v[166:167], v[166:167], v[254:255]
	v_pk_fma_f32 v[252:253], v[168:169], v[168:169], v[252:253]
	v_pk_fma_f32 v[254:255], v[170:171], v[170:171], v[254:255]
	v_pk_fma_f32 v[252:253], v[172:173], v[172:173], v[252:253]
	v_pk_fma_f32 v[254:255], v[174:175], v[174:175], v[254:255]
	v_pk_add_f32 v[252:253], v[252:253], v[254:255]
	s_nop 0
	v_add_f32_e32 v183, v252, v253
	s_nop 1
	v_add_f32_dpp v183, v183, v183 quad_perm:[1,0,3,2] row_mask:0xf bank_mask:0xf bound_ctrl:1
	s_nop 1
	v_add_f32_dpp v183, v183, v183 quad_perm:[2,3,0,1] row_mask:0xf bank_mask:0xf bound_ctrl:1
	s_nop 1
	v_add_f32_dpp v183, v183, v183 row_half_mirror row_mask:0xf bank_mask:0xf bound_ctrl:1
	s_nop 1
	v_add_f32_dpp v183, v183, v183 row_mirror row_mask:0xf bank_mask:0xf bound_ctrl:1
	s_nop 1
	v_readlane_b32 s98, v183, 0
	v_readlane_b32 s99, v183, 16
	v_readlane_b32 s100, v183, 32
	v_readlane_b32 s101, v183, 48
	s_nop 1
	v_mov_b32_e32 v183, s98
	v_add_f32_e32 v183, s99, v183
	v_add_f32_e32 v183, s100, v183
	v_add_f32_e32 v183, s101, v183
	v_fmamk_f32 v183, v183, 0x3a800000, v182
	v_cmp_gt_f32_e32 vcc, 0x800000, v183
	v_mul_f32_e32 v181, 0x4b800000, v183
	s_nop 1
	v_cndmask_b32_e32 v183, v183, v181, vcc
	v_rsq_f32_e32 v183, v183
	s_nop 0
	v_mul_f32_e32 v181, 0x45800000, v183
	v_cndmask_b32_e32 v184, v183, v181, vcc
	v_mov_b32_e32 v185, v184
	v_pk_mul_f32 v[160:161], v[160:161], v[184:185]
	v_pk_mul_f32 v[162:163], v[162:163], v[184:185]
	v_pk_mul_f32 v[164:165], v[164:165], v[184:185]
	v_pk_mul_f32 v[166:167], v[166:167], v[184:185]
	v_pk_mul_f32 v[168:169], v[168:169], v[184:185]
	v_pk_mul_f32 v[170:171], v[170:171], v[184:185]
	v_pk_mul_f32 v[172:173], v[172:173], v[184:185]
	v_pk_mul_f32 v[174:175], v[174:175], v[184:185]
	v_pk_fma_f32 v[144:145], v[160:161], v[128:129], v[144:145]
	v_pk_fma_f32 v[146:147], v[162:163], v[130:131], v[146:147]
	v_pk_fma_f32 v[148:149], v[164:165], v[132:133], v[148:149]
	v_pk_fma_f32 v[150:151], v[166:167], v[134:135], v[150:151]
	v_pk_fma_f32 v[152:153], v[168:169], v[136:137], v[152:153]
	v_pk_fma_f32 v[154:155], v[170:171], v[138:139], v[154:155]
	v_pk_fma_f32 v[156:157], v[172:173], v[140:141], v[156:157]
	v_pk_fma_f32 v[158:159], v[174:175], v[142:143], v[158:159]
	v_pk_mul_f32 v[252:253], v[144:145], v[144:145]
	v_pk_mul_f32 v[254:255], v[146:147], v[146:147]
	v_pk_fma_f32 v[252:253], v[148:149], v[148:149], v[252:253]
	v_pk_fma_f32 v[254:255], v[150:151], v[150:151], v[254:255]
	v_pk_fma_f32 v[252:253], v[152:153], v[152:153], v[252:253]
	v_pk_fma_f32 v[254:255], v[154:155], v[154:155], v[254:255]
	v_pk_fma_f32 v[252:253], v[156:157], v[156:157], v[252:253]
	v_pk_fma_f32 v[254:255], v[158:159], v[158:159], v[254:255]
	v_pk_add_f32 v[252:253], v[252:253], v[254:255]
	s_nop 0
	v_add_f32_e32 v183, v252, v253
	s_nop 1
	v_add_f32_dpp v183, v183, v183 quad_perm:[1,0,3,2] row_mask:0xf bank_mask:0xf bound_ctrl:1
	s_nop 1
	v_add_f32_dpp v183, v183, v183 quad_perm:[2,3,0,1] row_mask:0xf bank_mask:0xf bound_ctrl:1
	s_nop 1
	v_add_f32_dpp v183, v183, v183 row_half_mirror row_mask:0xf bank_mask:0xf bound_ctrl:1
	s_nop 1
	v_add_f32_dpp v183, v183, v183 row_mirror row_mask:0xf bank_mask:0xf bound_ctrl:1
	s_nop 1
	v_readlane_b32 s98, v183, 0
	v_readlane_b32 s99, v183, 16
	v_readlane_b32 s100, v183, 32
	v_readlane_b32 s101, v183, 48
	s_nop 1
	v_mov_b32_e32 v183, s98
	v_add_f32_e32 v183, s99, v183
	v_add_f32_e32 v183, s100, v183
	v_add_f32_e32 v183, s101, v183
	v_fmamk_f32 v183, v183, 0x3a800000, v182
	v_cmp_gt_f32_e32 vcc, 0x800000, v183
	v_mul_f32_e32 v181, 0x4b800000, v183
	s_nop 1
	v_cndmask_b32_e32 v183, v183, v181, vcc
	v_rsq_f32_e32 v183, v183
	s_nop 0
	v_mul_f32_e32 v181, 0x45800000, v183
	v_cndmask_b32_e32 v184, v183, v181, vcc
	v_mov_b32_e32 v185, v184
	v_cvt_pk_bf16_f32 v32, v144, v145
	v_cvt_pk_bf16_f32 v33, v146, v147
	v_cvt_pk_bf16_f32 v34, v148, v149
	v_cvt_pk_bf16_f32 v35, v150, v151
	v_cvt_pk_bf16_f32 v36, v152, v153
	v_cvt_pk_bf16_f32 v37, v154, v155
	v_cvt_pk_bf16_f32 v38, v156, v157
	v_cvt_pk_bf16_f32 v39, v158, v159
	v_add_u32_e32 v181, 0x2000000, v177
	global_store_dwordx4 v181, v[32:35], s[78:79]
	global_store_dwordx4 v181, v[36:39], s[78:79] offset:1024
	v_add_u32_e32 v236, 0x4000, v237
	s_mov_b64 exec, 1
	global_store_dword v236, v184, s[78:79]
	s_mov_b64 exec, -1
	s_waitcnt vmcnt(4)
	v_lshlrev_b32_e32 v144, 16, v48
	v_and_b32_e32 v145, 0xffff0000, v48
	v_lshlrev_b32_e32 v146, 16, v49
	v_and_b32_e32 v147, 0xffff0000, v49
	v_lshlrev_b32_e32 v148, 16, v50
	v_and_b32_e32 v149, 0xffff0000, v50
	v_lshlrev_b32_e32 v150, 16, v51
	v_and_b32_e32 v151, 0xffff0000, v51
	v_lshlrev_b32_e32 v152, 16, v52
	v_and_b32_e32 v153, 0xffff0000, v52
	v_lshlrev_b32_e32 v154, 16, v53
	v_and_b32_e32 v155, 0xffff0000, v53
	v_lshlrev_b32_e32 v156, 16, v54
	v_and_b32_e32 v157, 0xffff0000, v54
	v_lshlrev_b32_e32 v158, 16, v55
	v_and_b32_e32 v159, 0xffff0000, v55
	v_lshlrev_b32_e32 v160, 16, v56
	v_and_b32_e32 v161, 0xffff0000, v56
	v_lshlrev_b32_e32 v162, 16, v57
	v_and_b32_e32 v163, 0xffff0000, v57
	v_lshlrev_b32_e32 v164, 16, v58
	v_and_b32_e32 v165, 0xffff0000, v58
	v_lshlrev_b32_e32 v166, 16, v59
	v_and_b32_e32 v167, 0xffff0000, v59
	v_lshlrev_b32_e32 v168, 16, v60
	v_and_b32_e32 v169, 0xffff0000, v60
	v_lshlrev_b32_e32 v170, 16, v61
	v_and_b32_e32 v171, 0xffff0000, v61
	v_lshlrev_b32_e32 v172, 16, v62
	v_and_b32_e32 v173, 0xffff0000, v62
	v_lshlrev_b32_e32 v174, 16, v63
	v_and_b32_e32 v175, 0xffff0000, v63
	v_pk_mul_f32 v[252:253], v[160:161], v[160:161]
	v_pk_mul_f32 v[254:255], v[162:163], v[162:163]
	v_pk_fma_f32 v[252:253], v[164:165], v[164:165], v[252:253]
	v_pk_fma_f32 v[254:255], v[166:167], v[166:167], v[254:255]
	v_pk_fma_f32 v[252:253], v[168:169], v[168:169], v[252:253]
	v_pk_fma_f32 v[254:255], v[170:171], v[170:171], v[254:255]
	v_pk_fma_f32 v[252:253], v[172:173], v[172:173], v[252:253]
	v_pk_fma_f32 v[254:255], v[174:175], v[174:175], v[254:255]
	v_pk_add_f32 v[252:253], v[252:253], v[254:255]
	s_nop 0
	v_add_f32_e32 v183, v252, v253
	s_nop 1
	v_add_f32_dpp v183, v183, v183 quad_perm:[1,0,3,2] row_mask:0xf bank_mask:0xf bound_ctrl:1
	s_nop 1
	v_add_f32_dpp v183, v183, v183 quad_perm:[2,3,0,1] row_mask:0xf bank_mask:0xf bound_ctrl:1
	s_nop 1
	v_add_f32_dpp v183, v183, v183 row_half_mirror row_mask:0xf bank_mask:0xf bound_ctrl:1
	s_nop 1
	v_add_f32_dpp v183, v183, v183 row_mirror row_mask:0xf bank_mask:0xf bound_ctrl:1
	s_nop 1
	v_readlane_b32 s98, v183, 0
	v_readlane_b32 s99, v183, 16
	v_readlane_b32 s100, v183, 32
	v_readlane_b32 s101, v183, 48
	s_nop 1
	v_mov_b32_e32 v183, s98
	v_add_f32_e32 v183, s99, v183
	v_add_f32_e32 v183, s100, v183
	v_add_f32_e32 v183, s101, v183
	v_fmamk_f32 v183, v183, 0x3a800000, v182
	v_cmp_gt_f32_e32 vcc, 0x800000, v183
	v_mul_f32_e32 v181, 0x4b800000, v183
	s_nop 1
	v_cndmask_b32_e32 v183, v183, v181, vcc
	v_rsq_f32_e32 v183, v183
	s_nop 0
	v_mul_f32_e32 v181, 0x45800000, v183
	v_cndmask_b32_e32 v184, v183, v181, vcc
	v_mov_b32_e32 v185, v184
	v_pk_mul_f32 v[160:161], v[160:161], v[184:185]
	v_pk_mul_f32 v[162:163], v[162:163], v[184:185]
	v_pk_mul_f32 v[164:165], v[164:165], v[184:185]
	v_pk_mul_f32 v[166:167], v[166:167], v[184:185]
	v_pk_mul_f32 v[168:169], v[168:169], v[184:185]
	v_pk_mul_f32 v[170:171], v[170:171], v[184:185]
	v_pk_mul_f32 v[172:173], v[172:173], v[184:185]
	v_pk_mul_f32 v[174:175], v[174:175], v[184:185]
	v_pk_fma_f32 v[144:145], v[160:161], v[128:129], v[144:145]
	v_pk_fma_f32 v[146:147], v[162:163], v[130:131], v[146:147]
	v_pk_fma_f32 v[148:149], v[164:165], v[132:133], v[148:149]
	v_pk_fma_f32 v[150:151], v[166:167], v[134:135], v[150:151]
	v_pk_fma_f32 v[152:153], v[168:169], v[136:137], v[152:153]
	v_pk_fma_f32 v[154:155], v[170:171], v[138:139], v[154:155]
	v_pk_fma_f32 v[156:157], v[172:173], v[140:141], v[156:157]
	v_pk_fma_f32 v[158:159], v[174:175], v[142:143], v[158:159]
	v_pk_mul_f32 v[252:253], v[144:145], v[144:145]
	v_pk_mul_f32 v[254:255], v[146:147], v[146:147]
	v_pk_fma_f32 v[252:253], v[148:149], v[148:149], v[252:253]
	v_pk_fma_f32 v[254:255], v[150:151], v[150:151], v[254:255]
	v_pk_fma_f32 v[252:253], v[152:153], v[152:153], v[252:253]
	v_pk_fma_f32 v[254:255], v[154:155], v[154:155], v[254:255]
	v_pk_fma_f32 v[252:253], v[156:157], v[156:157], v[252:253]
	v_pk_fma_f32 v[254:255], v[158:159], v[158:159], v[254:255]
	v_pk_add_f32 v[252:253], v[252:253], v[254:255]
	s_nop 0
	v_add_f32_e32 v183, v252, v253
	s_nop 1
	v_add_f32_dpp v183, v183, v183 quad_perm:[1,0,3,2] row_mask:0xf bank_mask:0xf bound_ctrl:1
	s_nop 1
	v_add_f32_dpp v183, v183, v183 quad_perm:[2,3,0,1] row_mask:0xf bank_mask:0xf bound_ctrl:1
	s_nop 1
	v_add_f32_dpp v183, v183, v183 row_half_mirror row_mask:0xf bank_mask:0xf bound_ctrl:1
	s_nop 1
	v_add_f32_dpp v183, v183, v183 row_mirror row_mask:0xf bank_mask:0xf bound_ctrl:1
	s_nop 1
	v_readlane_b32 s98, v183, 0
	v_readlane_b32 s99, v183, 16
	v_readlane_b32 s100, v183, 32
	v_readlane_b32 s101, v183, 48
	s_nop 1
	v_mov_b32_e32 v183, s98
	v_add_f32_e32 v183, s99, v183
	v_add_f32_e32 v183, s100, v183
	v_add_f32_e32 v183, s101, v183
	v_fmamk_f32 v183, v183, 0x3a800000, v182
	v_cmp_gt_f32_e32 vcc, 0x800000, v183
	v_mul_f32_e32 v181, 0x4b800000, v183
	s_nop 1
	v_cndmask_b32_e32 v183, v183, v181, vcc
	v_rsq_f32_e32 v183, v183
	s_nop 0
	v_mul_f32_e32 v181, 0x45800000, v183
	v_cndmask_b32_e32 v184, v183, v181, vcc
	v_mov_b32_e32 v185, v184
	v_cvt_pk_bf16_f32 v48, v144, v145
	v_cvt_pk_bf16_f32 v49, v146, v147
	v_cvt_pk_bf16_f32 v50, v148, v149
	v_cvt_pk_bf16_f32 v51, v150, v151
	v_cvt_pk_bf16_f32 v52, v152, v153
	v_cvt_pk_bf16_f32 v53, v154, v155
	v_cvt_pk_bf16_f32 v54, v156, v157
	v_cvt_pk_bf16_f32 v55, v158, v159
	v_add_u32_e32 v181, 0x2400000, v177
	global_store_dwordx4 v181, v[48:51], s[78:79]
	global_store_dwordx4 v181, v[52:55], s[78:79] offset:1024
	v_add_u32_e32 v236, 0x6000, v237
	s_mov_b64 exec, 1
	global_store_dword v236, v184, s[78:79]
	s_mov_b64 exec, -1
	s_waitcnt vmcnt(0)
	v_lshlrev_b32_e32 v144, 16, v64
	v_and_b32_e32 v145, 0xffff0000, v64
	v_lshlrev_b32_e32 v146, 16, v65
	v_and_b32_e32 v147, 0xffff0000, v65
	v_lshlrev_b32_e32 v148, 16, v66
	v_and_b32_e32 v149, 0xffff0000, v66
	v_lshlrev_b32_e32 v150, 16, v67
	v_and_b32_e32 v151, 0xffff0000, v67
	v_lshlrev_b32_e32 v152, 16, v68
	v_and_b32_e32 v153, 0xffff0000, v68
	v_lshlrev_b32_e32 v154, 16, v69
	v_and_b32_e32 v155, 0xffff0000, v69
	v_lshlrev_b32_e32 v156, 16, v70
	v_and_b32_e32 v157, 0xffff0000, v70
	v_lshlrev_b32_e32 v158, 16, v71
	v_and_b32_e32 v159, 0xffff0000, v71
	v_lshlrev_b32_e32 v160, 16, v72
	v_and_b32_e32 v161, 0xffff0000, v72
	v_lshlrev_b32_e32 v162, 16, v73
	v_and_b32_e32 v163, 0xffff0000, v73
	v_lshlrev_b32_e32 v164, 16, v74
	v_and_b32_e32 v165, 0xffff0000, v74
	v_lshlrev_b32_e32 v166, 16, v75
	v_and_b32_e32 v167, 0xffff0000, v75
	v_lshlrev_b32_e32 v168, 16, v76
	v_and_b32_e32 v169, 0xffff0000, v76
	v_lshlrev_b32_e32 v170, 16, v77
	v_and_b32_e32 v171, 0xffff0000, v77
	v_lshlrev_b32_e32 v172, 16, v78
	v_and_b32_e32 v173, 0xffff0000, v78
	v_lshlrev_b32_e32 v174, 16, v79
	v_and_b32_e32 v175, 0xffff0000, v79
	v_pk_mul_f32 v[252:253], v[160:161], v[160:161]
	v_pk_mul_f32 v[254:255], v[162:163], v[162:163]
	v_pk_fma_f32 v[252:253], v[164:165], v[164:165], v[252:253]
	v_pk_fma_f32 v[254:255], v[166:167], v[166:167], v[254:255]
	v_pk_fma_f32 v[252:253], v[168:169], v[168:169], v[252:253]
	v_pk_fma_f32 v[254:255], v[170:171], v[170:171], v[254:255]
	v_pk_fma_f32 v[252:253], v[172:173], v[172:173], v[252:253]
	v_pk_fma_f32 v[254:255], v[174:175], v[174:175], v[254:255]
	v_pk_add_f32 v[252:253], v[252:253], v[254:255]
	s_nop 0
	v_add_f32_e32 v183, v252, v253
	s_nop 1
	v_add_f32_dpp v183, v183, v183 quad_perm:[1,0,3,2] row_mask:0xf bank_mask:0xf bound_ctrl:1
	s_nop 1
	v_add_f32_dpp v183, v183, v183 quad_perm:[2,3,0,1] row_mask:0xf bank_mask:0xf bound_ctrl:1
	s_nop 1
	v_add_f32_dpp v183, v183, v183 row_half_mirror row_mask:0xf bank_mask:0xf bound_ctrl:1
	s_nop 1
	v_add_f32_dpp v183, v183, v183 row_mirror row_mask:0xf bank_mask:0xf bound_ctrl:1
	s_nop 1
	v_readlane_b32 s98, v183, 0
	v_readlane_b32 s99, v183, 16
	v_readlane_b32 s100, v183, 32
	v_readlane_b32 s101, v183, 48
	s_nop 1
	v_mov_b32_e32 v183, s98
	v_add_f32_e32 v183, s99, v183
	v_add_f32_e32 v183, s100, v183
	v_add_f32_e32 v183, s101, v183
	v_fmamk_f32 v183, v183, 0x3a800000, v182
	v_cmp_gt_f32_e32 vcc, 0x800000, v183
	v_mul_f32_e32 v181, 0x4b800000, v183
	s_nop 1
	v_cndmask_b32_e32 v183, v183, v181, vcc
	v_rsq_f32_e32 v183, v183
	s_nop 0
	v_mul_f32_e32 v181, 0x45800000, v183
	v_cndmask_b32_e32 v184, v183, v181, vcc
	v_mov_b32_e32 v185, v184
	v_pk_mul_f32 v[160:161], v[160:161], v[184:185]
	v_pk_mul_f32 v[162:163], v[162:163], v[184:185]
	v_pk_mul_f32 v[164:165], v[164:165], v[184:185]
	v_pk_mul_f32 v[166:167], v[166:167], v[184:185]
	v_pk_mul_f32 v[168:169], v[168:169], v[184:185]
	v_pk_mul_f32 v[170:171], v[170:171], v[184:185]
	v_pk_mul_f32 v[172:173], v[172:173], v[184:185]
	v_pk_mul_f32 v[174:175], v[174:175], v[184:185]
	v_pk_fma_f32 v[144:145], v[160:161], v[128:129], v[144:145]
	v_pk_fma_f32 v[146:147], v[162:163], v[130:131], v[146:147]
	v_pk_fma_f32 v[148:149], v[164:165], v[132:133], v[148:149]
	v_pk_fma_f32 v[150:151], v[166:167], v[134:135], v[150:151]
	v_pk_fma_f32 v[152:153], v[168:169], v[136:137], v[152:153]
	v_pk_fma_f32 v[154:155], v[170:171], v[138:139], v[154:155]
	v_pk_fma_f32 v[156:157], v[172:173], v[140:141], v[156:157]
	v_pk_fma_f32 v[158:159], v[174:175], v[142:143], v[158:159]
	v_pk_mul_f32 v[252:253], v[144:145], v[144:145]
	v_pk_mul_f32 v[254:255], v[146:147], v[146:147]
	v_pk_fma_f32 v[252:253], v[148:149], v[148:149], v[252:253]
	v_pk_fma_f32 v[254:255], v[150:151], v[150:151], v[254:255]
	v_pk_fma_f32 v[252:253], v[152:153], v[152:153], v[252:253]
	v_pk_fma_f32 v[254:255], v[154:155], v[154:155], v[254:255]
	v_pk_fma_f32 v[252:253], v[156:157], v[156:157], v[252:253]
	v_pk_fma_f32 v[254:255], v[158:159], v[158:159], v[254:255]
	v_pk_add_f32 v[252:253], v[252:253], v[254:255]
	s_nop 0
	v_add_f32_e32 v183, v252, v253
	s_nop 1
	v_add_f32_dpp v183, v183, v183 quad_perm:[1,0,3,2] row_mask:0xf bank_mask:0xf bound_ctrl:1
	s_nop 1
	v_add_f32_dpp v183, v183, v183 quad_perm:[2,3,0,1] row_mask:0xf bank_mask:0xf bound_ctrl:1
	s_nop 1
	v_add_f32_dpp v183, v183, v183 row_half_mirror row_mask:0xf bank_mask:0xf bound_ctrl:1
	s_nop 1
	v_add_f32_dpp v183, v183, v183 row_mirror row_mask:0xf bank_mask:0xf bound_ctrl:1
	s_nop 1
	v_readlane_b32 s98, v183, 0
	v_readlane_b32 s99, v183, 16
	v_readlane_b32 s100, v183, 32
	v_readlane_b32 s101, v183, 48
	s_nop 1
	v_mov_b32_e32 v183, s98
	v_add_f32_e32 v183, s99, v183
	v_add_f32_e32 v183, s100, v183
	v_add_f32_e32 v183, s101, v183
	v_fmamk_f32 v183, v183, 0x3a800000, v182
	v_cmp_gt_f32_e32 vcc, 0x800000, v183
	v_mul_f32_e32 v181, 0x4b800000, v183
	s_nop 1
	v_cndmask_b32_e32 v183, v183, v181, vcc
	v_rsq_f32_e32 v183, v183
	s_nop 0
	v_mul_f32_e32 v181, 0x45800000, v183
	v_cndmask_b32_e32 v184, v183, v181, vcc
	v_mov_b32_e32 v185, v184
	v_cvt_pk_bf16_f32 v64, v144, v145
	v_cvt_pk_bf16_f32 v65, v146, v147
	v_cvt_pk_bf16_f32 v66, v148, v149
	v_cvt_pk_bf16_f32 v67, v150, v151
	v_cvt_pk_bf16_f32 v68, v152, v153
	v_cvt_pk_bf16_f32 v69, v154, v155
	v_cvt_pk_bf16_f32 v70, v156, v157
	v_cvt_pk_bf16_f32 v71, v158, v159
	v_add_u32_e32 v181, 0x2800000, v177
	global_store_dwordx4 v181, v[64:67], s[78:79]
	global_store_dwordx4 v181, v[68:71], s[78:79] offset:1024
	v_add_u32_e32 v236, 0x8000, v237
	s_mov_b64 exec, 1
	global_store_dword v236, v184, s[78:79]
	s_mov_b64 exec, -1
	v_readfirstlane_b32 s98, v179
	s_nop 3
	s_and_b32 s99, s98, 3
	s_cmp_lg_u32 s99, 0
	s_cbranch_scc1 .Lmyxupd_done_1
	v_lshrrev_b32_e32 v179, 2, v179
	v_lshlrev_b32_e32 v177, 4, v176
	v_lshl_add_u32 v177, v179, 11, v177
	v_lshlrev_b32_e32 v237, 2, v179
	v_add_u32_e32 v237, 0x10000, v237
	v_add_u32_e32 v181, 0x3800000, v177
	global_load_dwordx4 v[240:243], v181, s[78:79]
	global_load_dwordx4 v[244:247], v181, s[78:79] offset:1024
	v_lshl_add_u32 v183, v179, 12, v180
	v_add_u32_e32 v183, 0xbf00000, v183
	v_add_u32_e32 v181, 0x0, v183
	global_load_dwordx4 v[0:3], v181, s[78:79]
	global_load_dwordx4 v[4:7], v181, s[78:79] offset:16
	global_load_dwordx4 v[8:11], v181, s[78:79] offset:2048
	global_load_dwordx4 v[12:15], v181, s[78:79] offset:2064
	v_add_u32_e32 v181, 0x200000, v183
	global_load_dwordx4 v[16:19], v181, s[78:79]
	global_load_dwordx4 v[20:23], v181, s[78:79] offset:16
	global_load_dwordx4 v[24:27], v181, s[78:79] offset:2048
	global_load_dwordx4 v[28:31], v181, s[78:79] offset:2064
	v_add_u32_e32 v181, 0x400000, v183
	global_load_dwordx4 v[32:35], v181, s[78:79]
	global_load_dwordx4 v[36:39], v181, s[78:79] offset:16
	global_load_dwordx4 v[40:43], v181, s[78:79] offset:2048
	global_load_dwordx4 v[44:47], v181, s[78:79] offset:2064
	v_add_u32_e32 v181, 0x600000, v183
	global_load_dwordx4 v[48:51], v181, s[78:79]
	global_load_dwordx4 v[52:55], v181, s[78:79] offset:16
	global_load_dwordx4 v[56:59], v181, s[78:79] offset:2048
	global_load_dwordx4 v[60:63], v181, s[78:79] offset:2064
	v_add_u32_e32 v181, 0x800000, v183
	global_load_dwordx4 v[64:67], v181, s[78:79]
	global_load_dwordx4 v[68:71], v181, s[78:79] offset:16
	global_load_dwordx4 v[72:75], v181, s[78:79] offset:2048
	global_load_dwordx4 v[76:79], v181, s[78:79] offset:2064
	v_add_u32_e32 v181, 0xa00000, v183
	global_load_dwordx4 v[80:83], v181, s[78:79]
	global_load_dwordx4 v[84:87], v181, s[78:79] offset:16
	global_load_dwordx4 v[88:91], v181, s[78:79] offset:2048
	global_load_dwordx4 v[92:95], v181, s[78:79] offset:2064
	v_add_u32_e32 v181, 0xc00000, v183
	global_load_dwordx4 v[96:99], v181, s[78:79]
	global_load_dwordx4 v[100:103], v181, s[78:79] offset:16
	global_load_dwordx4 v[104:107], v181, s[78:79] offset:2048
	global_load_dwordx4 v[108:111], v181, s[78:79] offset:2064
	v_add_u32_e32 v181, 0xe00000, v183
	global_load_dwordx4 v[112:115], v181, s[78:79]
	global_load_dwordx4 v[116:119], v181, s[78:79] offset:16
	global_load_dwordx4 v[120:123], v181, s[78:79] offset:2048
	global_load_dwordx4 v[124:127], v181, s[78:79] offset:2064
	s_waitcnt vmcnt(28)
	v_pk_add_f32 v[160:161], v[0:1], 0 op_sel_hi:[1,0]
	v_pk_add_f32 v[162:163], v[2:3], 0 op_sel_hi:[1,0]
	v_pk_add_f32 v[164:165], v[4:5], 0 op_sel_hi:[1,0]
	v_pk_add_f32 v[166:167], v[6:7], 0 op_sel_hi:[1,0]
	v_pk_add_f32 v[168:169], v[8:9], 0 op_sel_hi:[1,0]
	v_pk_add_f32 v[170:171], v[10:11], 0 op_sel_hi:[1,0]
	v_pk_add_f32 v[172:173], v[12:13], 0 op_sel_hi:[1,0]
	v_pk_add_f32 v[174:175], v[14:15], 0 op_sel_hi:[1,0]
	s_waitcnt vmcnt(24)
	v_pk_add_f32 v[160:161], v[160:161], v[16:17]
	v_pk_add_f32 v[162:163], v[162:163], v[18:19]
	v_pk_add_f32 v[164:165], v[164:165], v[20:21]
	v_pk_add_f32 v[166:167], v[166:167], v[22:23]
	v_pk_add_f32 v[168:169], v[168:169], v[24:25]
	v_pk_add_f32 v[170:171], v[170:171], v[26:27]
	v_pk_add_f32 v[172:173], v[172:173], v[28:29]
	v_pk_add_f32 v[174:175], v[174:175], v[30:31]
	s_waitcnt vmcnt(20)
	v_pk_add_f32 v[160:161], v[160:161], v[32:33]
	v_pk_add_f32 v[162:163], v[162:163], v[34:35]
	v_pk_add_f32 v[164:165], v[164:165], v[36:37]
	v_pk_add_f32 v[166:167], v[166:167], v[38:39]
	v_pk_add_f32 v[168:169], v[168:169], v[40:41]
	v_pk_add_f32 v[170:171], v[170:171], v[42:43]
	v_pk_add_f32 v[172:173], v[172:173], v[44:45]
	v_pk_add_f32 v[174:175], v[174:175], v[46:47]
	v_add_u32_e32 v181, 0x1000000, v183
	global_load_dwordx4 v[0:3], v181, s[78:79]
	global_load_dwordx4 v[4:7], v181, s[78:79] offset:16
	global_load_dwordx4 v[8:11], v181, s[78:79] offset:2048
	global_load_dwordx4 v[12:15], v181, s[78:79] offset:2064
	v_add_u32_e32 v181, 0x1200000, v183
	global_load_dwordx4 v[16:19], v181, s[78:79]
	global_load_dwordx4 v[20:23], v181, s[78:79] offset:16
	global_load_dwordx4 v[24:27], v181, s[78:79] offset:2048
	global_load_dwordx4 v[28:31], v181, s[78:79] offset:2064
	v_add_u32_e32 v181, 0x1400000, v183
	global_load_dwordx4 v[32:35], v181, s[78:79]
	global_load_dwordx4 v[36:39], v181, s[78:79] offset:16
	global_load_dwordx4 v[40:43], v181, s[78:79] offset:2048
	global_load_dwordx4 v[44:47], v181, s[78:79] offset:2064
	s_waitcnt vmcnt(28)
	v_pk_add_f32 v[160:161], v[160:161], v[48:49]
	v_pk_add_f32 v[162:163], v[162:163], v[50:51]
	v_pk_add_f32 v[164:165], v[164:165], v[52:53]
	v_pk_add_f32 v[166:167], v[166:167], v[54:55]
	v_pk_add_f32 v[168:169], v[168:169], v[56:57]
	v_pk_add_f32 v[170:171], v[170:171], v[58:59]
	v_pk_add_f32 v[172:173], v[172:173], v[60:61]
	v_pk_add_f32 v[174:175], v[174:175], v[62:63]
	s_waitcnt vmcnt(24)
	v_pk_add_f32 v[160:161], v[160:161], v[64:65]
	v_pk_add_f32 v[162:163], v[162:163], v[66:67]
	v_pk_add_f32 v[164:165], v[164:165], v[68:69]
	v_pk_add_f32 v[166:167], v[166:167], v[70:71]
	v_pk_add_f32 v[168:169], v[168:169], v[72:73]
	v_pk_add_f32 v[170:171], v[170:171], v[74:75]
	v_pk_add_f32 v[172:173], v[172:173], v[76:77]
	v_pk_add_f32 v[174:175], v[174:175], v[78:79]
	s_waitcnt vmcnt(20)
	v_pk_add_f32 v[160:161], v[160:161], v[80:81]
	v_pk_add_f32 v[162:163], v[162:163], v[82:83]
	v_pk_add_f32 v[164:165], v[164:165], v[84:85]
	v_pk_add_f32 v[166:167], v[166:167], v[86:87]
	v_pk_add_f32 v[168:169], v[168:169], v[88:89]
	v_pk_add_f32 v[170:171], v[170:171], v[90:91]
	v_pk_add_f32 v[172:173], v[172:173], v[92:93]
	v_pk_add_f32 v[174:175], v[174:175], v[94:95]
	s_waitcnt vmcnt(16)
	v_pk_add_f32 v[160:161], v[160:161], v[96:97]
	v_pk_add_f32 v[162:163], v[162:163], v[98:99]
	v_pk_add_f32 v[164:165], v[164:165], v[100:101]
	v_pk_add_f32 v[166:167], v[166:167], v[102:103]
	v_pk_add_f32 v[168:169], v[168:169], v[104:105]
	v_pk_add_f32 v[170:171], v[170:171], v[106:107]
	v_pk_add_f32 v[172:173], v[172:173], v[108:109]
	v_pk_add_f32 v[174:175], v[174:175], v[110:111]
	s_waitcnt vmcnt(12)
	v_pk_add_f32 v[160:161], v[160:161], v[112:113]
	v_pk_add_f32 v[162:163], v[162:163], v[114:115]
	v_pk_add_f32 v[164:165], v[164:165], v[116:117]
	v_pk_add_f32 v[166:167], v[166:167], v[118:119]
	v_pk_add_f32 v[168:169], v[168:169], v[120:121]
	v_pk_add_f32 v[170:171], v[170:171], v[122:123]
	v_pk_add_f32 v[172:173], v[172:173], v[124:125]
	v_pk_add_f32 v[174:175], v[174:175], v[126:127]
	v_lshlrev_b32_e32 v144, 16, v240
	v_and_b32_e32 v145, 0xffff0000, v240
	v_lshlrev_b32_e32 v146, 16, v241
	v_and_b32_e32 v147, 0xffff0000, v241
	v_lshlrev_b32_e32 v148, 16, v242
	v_and_b32_e32 v149, 0xffff0000, v242
	v_lshlrev_b32_e32 v150, 16, v243
	v_and_b32_e32 v151, 0xffff0000, v243
	v_lshlrev_b32_e32 v152, 16, v244
	v_and_b32_e32 v153, 0xffff0000, v244
	v_lshlrev_b32_e32 v154, 16, v245
	v_and_b32_e32 v155, 0xffff0000, v245
	v_lshlrev_b32_e32 v156, 16, v246
	v_and_b32_e32 v157, 0xffff0000, v246
	v_lshlrev_b32_e32 v158, 16, v247
	v_and_b32_e32 v159, 0xffff0000, v247
	s_waitcnt vmcnt(8)
	v_pk_add_f32 v[160:161], v[160:161], v[0:1]
	v_pk_add_f32 v[162:163], v[162:163], v[2:3]
	v_pk_add_f32 v[164:165], v[164:165], v[4:5]
	v_pk_add_f32 v[166:167], v[166:167], v[6:7]
	v_pk_add_f32 v[168:169], v[168:169], v[8:9]
	v_pk_add_f32 v[170:171], v[170:171], v[10:11]
	v_pk_add_f32 v[172:173], v[172:173], v[12:13]
	v_pk_add_f32 v[174:175], v[174:175], v[14:15]
	s_waitcnt vmcnt(4)
	v_pk_add_f32 v[160:161], v[160:161], v[16:17]
	v_pk_add_f32 v[162:163], v[162:163], v[18:19]
	v_pk_add_f32 v[164:165], v[164:165], v[20:21]
	v_pk_add_f32 v[166:167], v[166:167], v[22:23]
	v_pk_add_f32 v[168:169], v[168:169], v[24:25]
	v_pk_add_f32 v[170:171], v[170:171], v[26:27]
	v_pk_add_f32 v[172:173], v[172:173], v[28:29]
	v_pk_add_f32 v[174:175], v[174:175], v[30:31]
	s_waitcnt vmcnt(0)
	v_pk_add_f32 v[160:161], v[160:161], v[32:33]
	v_pk_add_f32 v[162:163], v[162:163], v[34:35]
	v_pk_add_f32 v[164:165], v[164:165], v[36:37]
	v_pk_add_f32 v[166:167], v[166:167], v[38:39]
	v_pk_add_f32 v[168:169], v[168:169], v[40:41]
	v_pk_add_f32 v[170:171], v[170:171], v[42:43]
	v_pk_add_f32 v[172:173], v[172:173], v[44:45]
	v_pk_add_f32 v[174:175], v[174:175], v[46:47]
	v_pk_mul_f32 v[252:253], v[160:161], v[160:161]
	v_pk_mul_f32 v[254:255], v[162:163], v[162:163]
	v_pk_fma_f32 v[252:253], v[164:165], v[164:165], v[252:253]
	v_pk_fma_f32 v[254:255], v[166:167], v[166:167], v[254:255]
	v_pk_fma_f32 v[252:253], v[168:169], v[168:169], v[252:253]
	v_pk_fma_f32 v[254:255], v[170:171], v[170:171], v[254:255]
	v_pk_fma_f32 v[252:253], v[172:173], v[172:173], v[252:253]
	v_pk_fma_f32 v[254:255], v[174:175], v[174:175], v[254:255]
	v_pk_add_f32 v[252:253], v[252:253], v[254:255]
	s_nop 0
	v_add_f32_e32 v183, v252, v253
	s_nop 1
	v_add_f32_dpp v183, v183, v183 quad_perm:[1,0,3,2] row_mask:0xf bank_mask:0xf bound_ctrl:1
	s_nop 1
	v_add_f32_dpp v183, v183, v183 quad_perm:[2,3,0,1] row_mask:0xf bank_mask:0xf bound_ctrl:1
	s_nop 1
	v_add_f32_dpp v183, v183, v183 row_half_mirror row_mask:0xf bank_mask:0xf bound_ctrl:1
	s_nop 1
	v_add_f32_dpp v183, v183, v183 row_mirror row_mask:0xf bank_mask:0xf bound_ctrl:1
	s_nop 1
	v_readlane_b32 s98, v183, 0
	v_readlane_b32 s99, v183, 16
	v_readlane_b32 s100, v183, 32
	v_readlane_b32 s101, v183, 48
	s_nop 1
	v_mov_b32_e32 v183, s98
	v_add_f32_e32 v183, s99, v183
	v_add_f32_e32 v183, s100, v183
	v_add_f32_e32 v183, s101, v183
	v_fmamk_f32 v183, v183, 0x3a800000, v182
	v_cmp_gt_f32_e32 vcc, 0x800000, v183
	v_mul_f32_e32 v181, 0x4b800000, v183
	s_nop 1
	v_cndmask_b32_e32 v183, v183, v181, vcc
	v_rsq_f32_e32 v183, v183
	s_nop 0
	v_mul_f32_e32 v181, 0x45800000, v183
	v_cndmask_b32_e32 v184, v183, v181, vcc
	v_mov_b32_e32 v185, v184
	v_pk_mul_f32 v[160:161], v[160:161], v[184:185]
	v_pk_mul_f32 v[162:163], v[162:163], v[184:185]
	v_pk_mul_f32 v[164:165], v[164:165], v[184:185]
	v_pk_mul_f32 v[166:167], v[166:167], v[184:185]
	v_pk_mul_f32 v[168:169], v[168:169], v[184:185]
	v_pk_mul_f32 v[170:171], v[170:171], v[184:185]
	v_pk_mul_f32 v[172:173], v[172:173], v[184:185]
	v_pk_mul_f32 v[174:175], v[174:175], v[184:185]
	v_pk_fma_f32 v[144:145], v[160:161], v[128:129], v[144:145]
	v_pk_fma_f32 v[146:147], v[162:163], v[130:131], v[146:147]
	v_pk_fma_f32 v[148:149], v[164:165], v[132:133], v[148:149]
	v_pk_fma_f32 v[150:151], v[166:167], v[134:135], v[150:151]
	v_pk_fma_f32 v[152:153], v[168:169], v[136:137], v[152:153]
	v_pk_fma_f32 v[154:155], v[170:171], v[138:139], v[154:155]
	v_pk_fma_f32 v[156:157], v[172:173], v[140:141], v[156:157]
	v_pk_fma_f32 v[158:159], v[174:175], v[142:143], v[158:159]
	v_pk_mul_f32 v[252:253], v[144:145], v[144:145]
	v_pk_mul_f32 v[254:255], v[146:147], v[146:147]
	v_pk_fma_f32 v[252:253], v[148:149], v[148:149], v[252:253]
	v_pk_fma_f32 v[254:255], v[150:151], v[150:151], v[254:255]
	v_pk_fma_f32 v[252:253], v[152:153], v[152:153], v[252:253]
	v_pk_fma_f32 v[254:255], v[154:155], v[154:155], v[254:255]
	v_pk_fma_f32 v[252:253], v[156:157], v[156:157], v[252:253]
	v_pk_fma_f32 v[254:255], v[158:159], v[158:159], v[254:255]
	v_pk_add_f32 v[252:253], v[252:253], v[254:255]
	s_nop 0
	v_add_f32_e32 v183, v252, v253
	s_nop 1
	v_add_f32_dpp v183, v183, v183 quad_perm:[1,0,3,2] row_mask:0xf bank_mask:0xf bound_ctrl:1
	s_nop 1
	v_add_f32_dpp v183, v183, v183 quad_perm:[2,3,0,1] row_mask:0xf bank_mask:0xf bound_ctrl:1
	s_nop 1
	v_add_f32_dpp v183, v183, v183 row_half_mirror row_mask:0xf bank_mask:0xf bound_ctrl:1
	s_nop 1
	v_add_f32_dpp v183, v183, v183 row_mirror row_mask:0xf bank_mask:0xf bound_ctrl:1
	s_nop 1
	v_readlane_b32 s98, v183, 0
	v_readlane_b32 s99, v183, 16
	v_readlane_b32 s100, v183, 32
	v_readlane_b32 s101, v183, 48
	s_nop 1
	v_mov_b32_e32 v183, s98
	v_add_f32_e32 v183, s99, v183
	v_add_f32_e32 v183, s100, v183
	v_add_f32_e32 v183, s101, v183
	v_fmamk_f32 v183, v183, 0x3a800000, v182
	v_cmp_gt_f32_e32 vcc, 0x800000, v183
	v_mul_f32_e32 v181, 0x4b800000, v183
	s_nop 1
	v_cndmask_b32_e32 v183, v183, v181, vcc
	v_rsq_f32_e32 v183, v183
	s_nop 0
	v_mul_f32_e32 v181, 0x45800000, v183
	v_cndmask_b32_e32 v184, v183, v181, vcc
	v_mov_b32_e32 v185, v184
	v_cvt_pk_bf16_f32 v0, v144, v145
	v_cvt_pk_bf16_f32 v1, v146, v147
	v_cvt_pk_bf16_f32 v2, v148, v149
	v_cvt_pk_bf16_f32 v3, v150, v151
	v_cvt_pk_bf16_f32 v4, v152, v153
	v_cvt_pk_bf16_f32 v5, v154, v155
	v_cvt_pk_bf16_f32 v6, v156, v157
	v_cvt_pk_bf16_f32 v7, v158, v159
	v_add_u32_e32 v181, 0x3800000, v177
	global_store_dwordx4 v181, v[0:3], s[78:79]
	global_store_dwordx4 v181, v[4:7], s[78:79] offset:1024
	v_add_u32_e32 v236, 0x10000, v237
	s_mov_b64 exec, 1
	global_store_dword v236, v184, s[78:79]
	s_mov_b64 exec, -1

.LBB0_880:
	s_or_b64 exec, exec, s[8:9]
	v_cvt_f32_u32_e32 v4, v2
	s_waitcnt vmcnt(0)
	v_readfirstlane_b32 s6, v3
	v_sub_u32_e32 v3, 0, v2
	v_rcp_iflag_f32_e32 v4, v4
	v_add_u32_e32 v5, s6, v1
	v_mul_f32_e32 v4, 0x4f7ffffe, v4
	v_cvt_u32_f32_e32 v4, v4
	v_mul_lo_u32 v1, v3, v4
	v_mul_hi_u32 v1, v4, v1
	v_add_u32_e32 v1, v4, v1
	v_mul_hi_u32 v1, v5, v1
	v_mul_lo_u32 v3, v1, v2
	v_sub_u32_e32 v3, v5, v3
	v_add_u32_e32 v4, 1, v1
	v_cmp_ge_u32_e32 vcc, v3, v2
	s_nop 1
	v_cndmask_b32_e32 v1, v1, v4, vcc
	v_sub_u32_e32 v4, v3, v2
	v_cndmask_b32_e32 v3, v3, v4, vcc
	v_add_u32_e32 v4, 1, v1
	v_cmp_ge_u32_e32 vcc, v3, v2
	v_add_u32_e32 v3, 1, v5
	s_nop 0
	v_cndmask_b32_e32 v1, v1, v4, vcc
	v_mul_lo_u32 v4, v2, v1
	v_add_u32_e32 v2, v4, v2
	v_cmp_ne_u32_e32 vcc, v3, v2
	s_and_saveexec_b64 s[6:7], vcc
	s_xor_b64 s[6:7], exec, s[6:7]
	s_cbranch_execz .LBB0_894
	s_waitcnt lgkmcnt(0)
	v_mov_b32_e32 v0, 0x3500
	global_load_dword v0, v0, s[78:79] sc1
	s_add_u32 s10, s78, 0x3500
	s_addc_u32 s11, s79, 0
	s_waitcnt vmcnt(0)
	v_cmp_eq_u32_e32 vcc, v0, v1
	s_cmp_lt_u32 s2, 16
	s_cbranch_scc0 ATB1_26317
	v_readfirstlane_b32 s100, v1
	s_mov_b64 vcc, 0
ATB1_26317:
	s_and_saveexec_b64 s[8:9], vcc
	s_cbranch_execz .LBB0_893
	s_mov_b32 s22, 1
	s_mov_b64 s[12:13], 0
	v_mov_b32_e32 v0, 0
	s_branch .LBB0_884

.LBB0_897:
	s_or_b64 exec, exec, s[8:9]
	s_waitcnt vmcnt(0)
	v_readfirstlane_b32 s6, v2
	v_cvt_f32_u32_e32 v2, v0
	v_sub_u32_e32 v3, 0, v0
	v_add_u32_e32 v1, s6, v1
	s_add_u32 s6, s78, 0x3500
	v_rcp_iflag_f32_e32 v2, v2
	s_addc_u32 s7, s79, 0
	s_mov_b64 s[10:11], -1
	v_mul_f32_e32 v2, 0x4f7ffffe, v2
	v_cvt_u32_f32_e32 v2, v2
	v_mul_lo_u32 v3, v3, v2
	v_mul_hi_u32 v3, v2, v3
	v_add_u32_e32 v2, v2, v3
	v_mul_hi_u32 v2, v1, v2
	v_mul_lo_u32 v3, v2, v0
	v_sub_u32_e32 v3, v1, v3
	v_cmp_ge_u32_e32 vcc, v3, v0
	v_add_u32_e32 v4, 1, v2
	v_add_u32_e32 v1, 1, v1
	v_cndmask_b32_e32 v2, v2, v4, vcc
	v_sub_u32_e32 v4, v3, v0
	v_cndmask_b32_e32 v3, v3, v4, vcc
	v_cmp_ge_u32_e32 vcc, v3, v0
	v_add_u32_e32 v3, 1, v2
	s_nop 0
	v_cndmask_b32_e32 v2, v2, v3, vcc
	v_mul_lo_u32 v3, v0, v2
	v_add_u32_e32 v0, v3, v0
	v_cmp_ne_u32_e32 vcc, v1, v0
	v_mov_b64_e32 v[0:1], s[6:7]
	s_and_saveexec_b64 s[8:9], vcc
	s_cbranch_execz .LBB0_909
	v_mov_b32_e32 v0, 0
	global_load_dword v1, v0, s[6:7] sc1
	s_mov_b64 s[14:15], 0
	s_waitcnt vmcnt(0)
	v_cmp_eq_u32_e32 vcc, v1, v2
	s_cmp_lt_u32 s2, 16
	s_cbranch_scc0 ATB1_26457
	v_readfirstlane_b32 s100, v2
	s_mov_b64 vcc, 0
ATB1_26457:
	s_and_saveexec_b64 s[12:13], vcc
	s_cbranch_execz .LBB0_908
	s_add_u32 s10, s78, 0x200
	s_addc_u32 s11, s79, 0
	s_mov_b32 s24, 1
	s_branch .LBB0_901

.LBB0_1154:
	v_readlane_b32 s0, v235, 52
	v_readlane_b32 s1, v235, 53
	s_and_b64 vcc, exec, s[0:1]
	s_waitcnt lgkmcnt(0)
	s_barrier
	v_mbcnt_lo_u32_b32 v0, -1, 0
	v_mbcnt_hi_u32_b32 v0, -1, v0
	s_cbranch_vccnz .LBB0_1174
	v_lshlrev_b32_e32 v2, 3, v0
	v_ashrrev_i32_e32 v3, 31, v2
	v_readlane_b32 s4, v235, 4
	v_lshlrev_b64 v[4:5], 1, v[2:3]
	v_lshlrev_b64 v[2:3], 2, v[2:3]
	v_readlane_b32 s14, v235, 14
	v_readlane_b32 s15, v235, 15
	v_lshl_add_u64 v[62:63], s[90:91], 0, v[2:3]
	v_readlane_b32 s5, v235, 5
	v_readlane_b32 s6, v235, 6
	v_readlane_b32 s7, v235, 7
	v_readlane_b32 s8, v235, 8
	v_readlane_b32 s9, v235, 9
	v_readlane_b32 s10, v235, 10
	v_readlane_b32 s11, v235, 11
	v_readlane_b32 s12, v235, 12
	v_readlane_b32 s13, v235, 13
	v_readlane_b32 s16, v235, 16
	v_readlane_b32 s17, v235, 17
	v_readlane_b32 s18, v235, 18
	v_readlane_b32 s19, v235, 19
	v_lshl_add_u64 v[2:3], s[14:15], 0, v[2:3]
	s_mov_b64 s[0:1], 0x1000
	v_lshl_add_u64 v[60:61], s[86:87], 0, v[4:5]
	v_lshl_add_u64 v[64:65], s[54:55], 0, v[4:5]
	v_lshl_add_u64 v[66:67], v[2:3], 0, s[0:1]
	s_mov_b32 s1, 0
	v_cmp_eq_u32_e64 s[12:13], 0, v0
	s_mov_b64 s[4:5], 0x200000
	s_mov_b64 s[6:7], 0x200800
	s_mov_b64 s[8:9], 0x400000
	s_mov_b64 s[10:11], 0x400800
	s_mov_b64 s[14:15], 0x600000
	s_mov_b64 s[16:17], 0x600800
	s_mov_b64 s[18:19], 0x800000
	s_mov_b32 s48, 0x800000
	s_mov_b64 s[20:21], 0x800800
	s_mov_b64 s[22:23], 0xa00000
	s_mov_b64 s[24:25], 0xa00800
	s_mov_b64 s[26:27], 0xc00000
	s_mov_b64 s[28:29], 0xc00800
	s_mov_b64 s[36:37], 0xe00000
	s_mov_b64 s[38:39], 0xe00800
	v_mov_b32_e32 v104, 0
	v_mov_b32_e32 v105, 0x358637bd
	v_readlane_b32 s42, v235, 61
	v_readlane_b32 s43, v235, 62
	v_mbcnt_lo_u32_b32 v176, -1, 0
	v_mbcnt_hi_u32_b32 v176, -1, v176
	v_readlane_b32 s98, v235, 49
	v_readlane_b32 s99, v235, 20
	v_readlane_b32 s100, v235, 14
	v_readlane_b32 s101, v235, 15
	s_nop 3
	s_lshr_b32 vcc_lo, s98, 3
	s_and_b32 vcc_hi, vcc_lo, 7
	s_lshr_b32 vcc_lo, vcc_lo, 3
	s_lshl_b32 vcc_lo, vcc_lo, 3
	s_add_i32 vcc_lo, vcc_lo, s99
	s_lshl_b32 s98, vcc_hi, 8
	s_add_i32 s98, s98, vcc_lo
	s_mov_b32 s99, s98
	v_mov_b32_e32 v183, s99
	v_lshlrev_b32_e32 v177, 4, v176
	s_lshl_b32 s99, s99, 11
	v_add_u32_e32 v177, s99, v177
	v_add_u32_e32 v178, 0x1800000, v177
	v_add_u32_e32 v179, 0x9e00000, v177
	v_lshlrev_b32_e32 v180, 5, v176
	v_add_u32_e32 v181, 0x1000, v180
	global_load_dwordx4 v[128:131], v181, s[100:101]
	global_load_dwordx4 v[132:135], v181, s[100:101] offset:16
	global_load_dwordx4 v[136:139], v181, s[100:101] offset:2048
	global_load_dwordx4 v[140:143], v181, s[100:101] offset:2064
	v_mov_b32_e32 v182, 0x358637bd
	s_and_b32 vcc_lo, s98, 3
	s_cmp_eq_u32 vcc_lo, 0
	s_cbranch_scc1 .Lmyxupd_heavy_2
	global_load_dwordx4 v[0:3], v178, s[78:79]
	global_load_dwordx4 v[4:7], v178, s[78:79] offset:1024
	global_load_dwordx4 v[8:11], v179, s[78:79]
	global_load_dwordx4 v[12:15], v179, s[78:79] offset:1024
	v_add_u32_e32 v178, 0x400000, v178
	v_add_u32_e32 v179, 0x400000, v179
	global_load_dwordx4 v[16:19], v178, s[78:79]
	global_load_dwordx4 v[20:23], v178, s[78:79] offset:1024
	global_load_dwordx4 v[24:27], v179, s[78:79]
	global_load_dwordx4 v[28:31], v179, s[78:79] offset:1024
	v_add_u32_e32 v178, 0x400000, v178
	v_add_u32_e32 v179, 0x400000, v179
	global_load_dwordx4 v[32:35], v178, s[78:79]
	global_load_dwordx4 v[36:39], v178, s[78:79] offset:1024
	global_load_dwordx4 v[40:43], v179, s[78:79]
	global_load_dwordx4 v[44:47], v179, s[78:79] offset:1024
	v_add_u32_e32 v178, 0x400000, v178
	v_add_u32_e32 v179, 0x400000, v179
	global_load_dwordx4 v[48:51], v178, s[78:79]
	global_load_dwordx4 v[52:55], v178, s[78:79] offset:1024
	global_load_dwordx4 v[56:59], v179, s[78:79]
	global_load_dwordx4 v[60:63], v179, s[78:79] offset:1024
	v_add_u32_e32 v178, 0x400000, v178
	v_add_u32_e32 v179, 0x400000, v179
	global_load_dwordx4 v[64:67], v178, s[78:79]
	global_load_dwordx4 v[68:71], v178, s[78:79] offset:1024
	global_load_dwordx4 v[72:75], v179, s[78:79]
	global_load_dwordx4 v[76:79], v179, s[78:79] offset:1024
	v_add_u32_e32 v178, 0x400000, v178
	v_add_u32_e32 v179, 0x400000, v179
	global_load_dwordx4 v[80:83], v178, s[78:79]
	global_load_dwordx4 v[84:87], v178, s[78:79] offset:1024
	global_load_dwordx4 v[88:91], v179, s[78:79]
	global_load_dwordx4 v[92:95], v179, s[78:79] offset:1024
	v_add_u32_e32 v178, 0x400000, v178
	v_add_u32_e32 v179, 0x400000, v179
	global_load_dwordx4 v[96:99], v178, s[78:79]
	global_load_dwordx4 v[100:103], v178, s[78:79] offset:1024
	global_load_dwordx4 v[104:107], v179, s[78:79]
	global_load_dwordx4 v[108:111], v179, s[78:79] offset:1024
	v_add_u32_e32 v178, 0x400000, v178
	v_add_u32_e32 v179, 0x400000, v179
	global_load_dwordx4 v[112:115], v178, s[78:79]
	global_load_dwordx4 v[116:119], v178, s[78:79] offset:1024
	global_load_dwordx4 v[120:123], v179, s[78:79]
	global_load_dwordx4 v[124:127], v179, s[78:79] offset:1024
	v_lshlrev_b32_e32 v237, 2, v183
	v_add_u32_e32 v237, 0x10000, v237
	v_mov_b32_e32 v179, s98
	s_waitcnt vmcnt(28)
	v_lshlrev_b32_e32 v144, 16, v0
	v_and_b32_e32 v145, 0xffff0000, v0
	v_lshlrev_b32_e32 v146, 16, v1
	v_and_b32_e32 v147, 0xffff0000, v1
	v_lshlrev_b32_e32 v148, 16, v2
	v_and_b32_e32 v149, 0xffff0000, v2
	v_lshlrev_b32_e32 v150, 16, v3
	v_and_b32_e32 v151, 0xffff0000, v3
	v_lshlrev_b32_e32 v152, 16, v4
	v_and_b32_e32 v153, 0xffff0000, v4
	v_lshlrev_b32_e32 v154, 16, v5
	v_and_b32_e32 v155, 0xffff0000, v5
	v_lshlrev_b32_e32 v156, 16, v6
	v_and_b32_e32 v157, 0xffff0000, v6
	v_lshlrev_b32_e32 v158, 16, v7
	v_and_b32_e32 v159, 0xffff0000, v7
	v_lshlrev_b32_e32 v160, 16, v8
	v_and_b32_e32 v161, 0xffff0000, v8
	v_lshlrev_b32_e32 v162, 16, v9
	v_and_b32_e32 v163, 0xffff0000, v9
	v_lshlrev_b32_e32 v164, 16, v10
	v_and_b32_e32 v165, 0xffff0000, v10
	v_lshlrev_b32_e32 v166, 16, v11
	v_and_b32_e32 v167, 0xffff0000, v11
	v_lshlrev_b32_e32 v168, 16, v12
	v_and_b32_e32 v169, 0xffff0000, v12
	v_lshlrev_b32_e32 v170, 16, v13
	v_and_b32_e32 v171, 0xffff0000, v13
	v_lshlrev_b32_e32 v172, 16, v14
	v_and_b32_e32 v173, 0xffff0000, v14
	v_lshlrev_b32_e32 v174, 16, v15
	v_and_b32_e32 v175, 0xffff0000, v15
	v_pk_mul_f32 v[252:253], v[160:161], v[160:161]
	v_pk_mul_f32 v[254:255], v[162:163], v[162:163]
	v_pk_fma_f32 v[252:253], v[164:165], v[164:165], v[252:253]
	v_pk_fma_f32 v[254:255], v[166:167], v[166:167], v[254:255]
	v_pk_fma_f32 v[252:253], v[168:169], v[168:169], v[252:253]
	v_pk_fma_f32 v[254:255], v[170:171], v[170:171], v[254:255]
	v_pk_fma_f32 v[252:253], v[172:173], v[172:173], v[252:253]
	v_pk_fma_f32 v[254:255], v[174:175], v[174:175], v[254:255]
	v_pk_add_f32 v[252:253], v[252:253], v[254:255]
	s_nop 0
	v_add_f32_e32 v183, v252, v253
	s_nop 1
	v_add_f32_dpp v183, v183, v183 quad_perm:[1,0,3,2] row_mask:0xf bank_mask:0xf bound_ctrl:1
	s_nop 1
	v_add_f32_dpp v183, v183, v183 quad_perm:[2,3,0,1] row_mask:0xf bank_mask:0xf bound_ctrl:1
	s_nop 1
	v_add_f32_dpp v183, v183, v183 row_half_mirror row_mask:0xf bank_mask:0xf bound_ctrl:1
	s_nop 1
	v_add_f32_dpp v183, v183, v183 row_mirror row_mask:0xf bank_mask:0xf bound_ctrl:1
	s_nop 1
	v_readlane_b32 s98, v183, 0
	v_readlane_b32 s99, v183, 16
	v_readlane_b32 s100, v183, 32
	v_readlane_b32 s101, v183, 48
	s_nop 1
	v_mov_b32_e32 v183, s98
	v_add_f32_e32 v183, s99, v183
	v_add_f32_e32 v183, s100, v183
	v_add_f32_e32 v183, s101, v183
	v_fmamk_f32 v183, v183, 0x3a800000, v182
	v_cmp_gt_f32_e32 vcc, 0x800000, v183
	v_mul_f32_e32 v181, 0x4b800000, v183
	s_nop 1
	v_cndmask_b32_e32 v183, v183, v181, vcc
	v_rsq_f32_e32 v183, v183
	s_nop 0
	v_mul_f32_e32 v181, 0x45800000, v183
	v_cndmask_b32_e32 v184, v183, v181, vcc
	v_mov_b32_e32 v185, v184
	v_pk_mul_f32 v[160:161], v[160:161], v[184:185]
	v_pk_mul_f32 v[162:163], v[162:163], v[184:185]
	v_pk_mul_f32 v[164:165], v[164:165], v[184:185]
	v_pk_mul_f32 v[166:167], v[166:167], v[184:185]
	v_pk_mul_f32 v[168:169], v[168:169], v[184:185]
	v_pk_mul_f32 v[170:171], v[170:171], v[184:185]
	v_pk_mul_f32 v[172:173], v[172:173], v[184:185]
	v_pk_mul_f32 v[174:175], v[174:175], v[184:185]
	v_pk_fma_f32 v[144:145], v[160:161], v[128:129], v[144:145]
	v_pk_fma_f32 v[146:147], v[162:163], v[130:131], v[146:147]
	v_pk_fma_f32 v[148:149], v[164:165], v[132:133], v[148:149]
	v_pk_fma_f32 v[150:151], v[166:167], v[134:135], v[150:151]
	v_pk_fma_f32 v[152:153], v[168:169], v[136:137], v[152:153]
	v_pk_fma_f32 v[154:155], v[170:171], v[138:139], v[154:155]
	v_pk_fma_f32 v[156:157], v[172:173], v[140:141], v[156:157]
	v_pk_fma_f32 v[158:159], v[174:175], v[142:143], v[158:159]
	v_pk_mul_f32 v[252:253], v[144:145], v[144:145]
	v_pk_mul_f32 v[254:255], v[146:147], v[146:147]
	v_pk_fma_f32 v[252:253], v[148:149], v[148:149], v[252:253]
	v_pk_fma_f32 v[254:255], v[150:151], v[150:151], v[254:255]
	v_pk_fma_f32 v[252:253], v[152:153], v[152:153], v[252:253]
	v_pk_fma_f32 v[254:255], v[154:155], v[154:155], v[254:255]
	v_pk_fma_f32 v[252:253], v[156:157], v[156:157], v[252:253]
	v_pk_fma_f32 v[254:255], v[158:159], v[158:159], v[254:255]
	v_pk_add_f32 v[252:253], v[252:253], v[254:255]
	s_nop 0
	v_add_f32_e32 v183, v252, v253
	s_nop 1
	v_add_f32_dpp v183, v183, v183 quad_perm:[1,0,3,2] row_mask:0xf bank_mask:0xf bound_ctrl:1
	s_nop 1
	v_add_f32_dpp v183, v183, v183 quad_perm:[2,3,0,1] row_mask:0xf bank_mask:0xf bound_ctrl:1
	s_nop 1
	v_add_f32_dpp v183, v183, v183 row_half_mirror row_mask:0xf bank_mask:0xf bound_ctrl:1
	s_nop 1
	v_add_f32_dpp v183, v183, v183 row_mirror row_mask:0xf bank_mask:0xf bound_ctrl:1
	s_nop 1
	v_readlane_b32 s98, v183, 0
	v_readlane_b32 s99, v183, 16
	v_readlane_b32 s100, v183, 32
	v_readlane_b32 s101, v183, 48
	s_nop 1
	v_mov_b32_e32 v183, s98
	v_add_f32_e32 v183, s99, v183
	v_add_f32_e32 v183, s100, v183
	v_add_f32_e32 v183, s101, v183
	v_fmamk_f32 v183, v183, 0x3a800000, v182
	v_cmp_gt_f32_e32 vcc, 0x800000, v183
	v_mul_f32_e32 v181, 0x4b800000, v183
	s_nop 1
	v_cndmask_b32_e32 v183, v183, v181, vcc
	v_rsq_f32_e32 v183, v183
	s_nop 0
	v_mul_f32_e32 v181, 0x45800000, v183
	v_cndmask_b32_e32 v184, v183, v181, vcc
	v_mov_b32_e32 v185, v184
	v_cvt_pk_bf16_f32 v0, v144, v145
	v_cvt_pk_bf16_f32 v1, v146, v147
	v_cvt_pk_bf16_f32 v2, v148, v149
	v_cvt_pk_bf16_f32 v3, v150, v151
	v_cvt_pk_bf16_f32 v4, v152, v153
	v_cvt_pk_bf16_f32 v5, v154, v155
	v_cvt_pk_bf16_f32 v6, v156, v157
	v_cvt_pk_bf16_f32 v7, v158, v159
	v_add_u32_e32 v181, 0x1800000, v177
	global_store_dwordx4 v181, v[0:3], s[78:79]
	global_store_dwordx4 v181, v[4:7], s[78:79] offset:1024
	v_add_u32_e32 v236, 0x0, v237
	s_mov_b64 exec, 1
	global_store_dword v236, v184, s[78:79]
	s_mov_b64 exec, -1
	s_waitcnt vmcnt(24)
	v_lshlrev_b32_e32 v144, 16, v16
	v_and_b32_e32 v145, 0xffff0000, v16
	v_lshlrev_b32_e32 v146, 16, v17
	v_and_b32_e32 v147, 0xffff0000, v17
	v_lshlrev_b32_e32 v148, 16, v18
	v_and_b32_e32 v149, 0xffff0000, v18
	v_lshlrev_b32_e32 v150, 16, v19
	v_and_b32_e32 v151, 0xffff0000, v19
	v_lshlrev_b32_e32 v152, 16, v20
	v_and_b32_e32 v153, 0xffff0000, v20
	v_lshlrev_b32_e32 v154, 16, v21
	v_and_b32_e32 v155, 0xffff0000, v21
	v_lshlrev_b32_e32 v156, 16, v22
	v_and_b32_e32 v157, 0xffff0000, v22
	v_lshlrev_b32_e32 v158, 16, v23
	v_and_b32_e32 v159, 0xffff0000, v23
	v_lshlrev_b32_e32 v160, 16, v24
	v_and_b32_e32 v161, 0xffff0000, v24
	v_lshlrev_b32_e32 v162, 16, v25
	v_and_b32_e32 v163, 0xffff0000, v25
	v_lshlrev_b32_e32 v164, 16, v26
	v_and_b32_e32 v165, 0xffff0000, v26
	v_lshlrev_b32_e32 v166, 16, v27
	v_and_b32_e32 v167, 0xffff0000, v27
	v_lshlrev_b32_e32 v168, 16, v28
	v_and_b32_e32 v169, 0xffff0000, v28
	v_lshlrev_b32_e32 v170, 16, v29
	v_and_b32_e32 v171, 0xffff0000, v29
	v_lshlrev_b32_e32 v172, 16, v30
	v_and_b32_e32 v173, 0xffff0000, v30
	v_lshlrev_b32_e32 v174, 16, v31
	v_and_b32_e32 v175, 0xffff0000, v31
	v_pk_mul_f32 v[252:253], v[160:161], v[160:161]
	v_pk_mul_f32 v[254:255], v[162:163], v[162:163]
	v_pk_fma_f32 v[252:253], v[164:165], v[164:165], v[252:253]
	v_pk_fma_f32 v[254:255], v[166:167], v[166:167], v[254:255]
	v_pk_fma_f32 v[252:253], v[168:169], v[168:169], v[252:253]
	v_pk_fma_f32 v[254:255], v[170:171], v[170:171], v[254:255]
	v_pk_fma_f32 v[252:253], v[172:173], v[172:173], v[252:253]
	v_pk_fma_f32 v[254:255], v[174:175], v[174:175], v[254:255]
	v_pk_add_f32 v[252:253], v[252:253], v[254:255]
	s_nop 0
	v_add_f32_e32 v183, v252, v253
	s_nop 1
	v_add_f32_dpp v183, v183, v183 quad_perm:[1,0,3,2] row_mask:0xf bank_mask:0xf bound_ctrl:1
	s_nop 1
	v_add_f32_dpp v183, v183, v183 quad_perm:[2,3,0,1] row_mask:0xf bank_mask:0xf bound_ctrl:1
	s_nop 1
	v_add_f32_dpp v183, v183, v183 row_half_mirror row_mask:0xf bank_mask:0xf bound_ctrl:1
	s_nop 1
	v_add_f32_dpp v183, v183, v183 row_mirror row_mask:0xf bank_mask:0xf bound_ctrl:1
	s_nop 1
	v_readlane_b32 s98, v183, 0
	v_readlane_b32 s99, v183, 16
	v_readlane_b32 s100, v183, 32
	v_readlane_b32 s101, v183, 48
	s_nop 1
	v_mov_b32_e32 v183, s98
	v_add_f32_e32 v183, s99, v183
	v_add_f32_e32 v183, s100, v183
	v_add_f32_e32 v183, s101, v183
	v_fmamk_f32 v183, v183, 0x3a800000, v182
	v_cmp_gt_f32_e32 vcc, 0x800000, v183
	v_mul_f32_e32 v181, 0x4b800000, v183
	s_nop 1
	v_cndmask_b32_e32 v183, v183, v181, vcc
	v_rsq_f32_e32 v183, v183
	s_nop 0
	v_mul_f32_e32 v181, 0x45800000, v183
	v_cndmask_b32_e32 v184, v183, v181, vcc
	v_mov_b32_e32 v185, v184
	v_pk_mul_f32 v[160:161], v[160:161], v[184:185]
	v_pk_mul_f32 v[162:163], v[162:163], v[184:185]
	v_pk_mul_f32 v[164:165], v[164:165], v[184:185]
	v_pk_mul_f32 v[166:167], v[166:167], v[184:185]
	v_pk_mul_f32 v[168:169], v[168:169], v[184:185]
	v_pk_mul_f32 v[170:171], v[170:171], v[184:185]
	v_pk_mul_f32 v[172:173], v[172:173], v[184:185]
	v_pk_mul_f32 v[174:175], v[174:175], v[184:185]
	v_pk_fma_f32 v[144:145], v[160:161], v[128:129], v[144:145]
	v_pk_fma_f32 v[146:147], v[162:163], v[130:131], v[146:147]
	v_pk_fma_f32 v[148:149], v[164:165], v[132:133], v[148:149]
	v_pk_fma_f32 v[150:151], v[166:167], v[134:135], v[150:151]
	v_pk_fma_f32 v[152:153], v[168:169], v[136:137], v[152:153]
	v_pk_fma_f32 v[154:155], v[170:171], v[138:139], v[154:155]
	v_pk_fma_f32 v[156:157], v[172:173], v[140:141], v[156:157]
	v_pk_fma_f32 v[158:159], v[174:175], v[142:143], v[158:159]
	v_pk_mul_f32 v[252:253], v[144:145], v[144:145]
	v_pk_mul_f32 v[254:255], v[146:147], v[146:147]
	v_pk_fma_f32 v[252:253], v[148:149], v[148:149], v[252:253]
	v_pk_fma_f32 v[254:255], v[150:151], v[150:151], v[254:255]
	v_pk_fma_f32 v[252:253], v[152:153], v[152:153], v[252:253]
	v_pk_fma_f32 v[254:255], v[154:155], v[154:155], v[254:255]
	v_pk_fma_f32 v[252:253], v[156:157], v[156:157], v[252:253]
	v_pk_fma_f32 v[254:255], v[158:159], v[158:159], v[254:255]
	v_pk_add_f32 v[252:253], v[252:253], v[254:255]
	s_nop 0
	v_add_f32_e32 v183, v252, v253
	s_nop 1
	v_add_f32_dpp v183, v183, v183 quad_perm:[1,0,3,2] row_mask:0xf bank_mask:0xf bound_ctrl:1
	s_nop 1
	v_add_f32_dpp v183, v183, v183 quad_perm:[2,3,0,1] row_mask:0xf bank_mask:0xf bound_ctrl:1
	s_nop 1
	v_add_f32_dpp v183, v183, v183 row_half_mirror row_mask:0xf bank_mask:0xf bound_ctrl:1
	s_nop 1
	v_add_f32_dpp v183, v183, v183 row_mirror row_mask:0xf bank_mask:0xf bound_ctrl:1
	s_nop 1
	v_readlane_b32 s98, v183, 0
	v_readlane_b32 s99, v183, 16
	v_readlane_b32 s100, v183, 32
	v_readlane_b32 s101, v183, 48
	s_nop 1
	v_mov_b32_e32 v183, s98
	v_add_f32_e32 v183, s99, v183
	v_add_f32_e32 v183, s100, v183
	v_add_f32_e32 v183, s101, v183
	v_fmamk_f32 v183, v183, 0x3a800000, v182
	v_cmp_gt_f32_e32 vcc, 0x800000, v183
	v_mul_f32_e32 v181, 0x4b800000, v183
	s_nop 1
	v_cndmask_b32_e32 v183, v183, v181, vcc
	v_rsq_f32_e32 v183, v183
	s_nop 0
	v_mul_f32_e32 v181, 0x45800000, v183
	v_cndmask_b32_e32 v184, v183, v181, vcc
	v_mov_b32_e32 v185, v184
	v_cvt_pk_bf16_f32 v16, v144, v145
	v_cvt_pk_bf16_f32 v17, v146, v147
	v_cvt_pk_bf16_f32 v18, v148, v149
	v_cvt_pk_bf16_f32 v19, v150, v151
	v_cvt_pk_bf16_f32 v20, v152, v153
	v_cvt_pk_bf16_f32 v21, v154, v155
	v_cvt_pk_bf16_f32 v22, v156, v157
	v_cvt_pk_bf16_f32 v23, v158, v159
	v_add_u32_e32 v181, 0x1c00000, v177
	global_store_dwordx4 v181, v[16:19], s[78:79]
	global_store_dwordx4 v181, v[20:23], s[78:79] offset:1024
	v_add_u32_e32 v236, 0x2000, v237
	s_mov_b64 exec, 1
	global_store_dword v236, v184, s[78:79]
	s_mov_b64 exec, -1
	s_waitcnt vmcnt(20)
	v_lshlrev_b32_e32 v144, 16, v32
	v_and_b32_e32 v145, 0xffff0000, v32
	v_lshlrev_b32_e32 v146, 16, v33
	v_and_b32_e32 v147, 0xffff0000, v33
	v_lshlrev_b32_e32 v148, 16, v34
	v_and_b32_e32 v149, 0xffff0000, v34
	v_lshlrev_b32_e32 v150, 16, v35
	v_and_b32_e32 v151, 0xffff0000, v35
	v_lshlrev_b32_e32 v152, 16, v36
	v_and_b32_e32 v153, 0xffff0000, v36
	v_lshlrev_b32_e32 v154, 16, v37
	v_and_b32_e32 v155, 0xffff0000, v37
	v_lshlrev_b32_e32 v156, 16, v38
	v_and_b32_e32 v157, 0xffff0000, v38
	v_lshlrev_b32_e32 v158, 16, v39
	v_and_b32_e32 v159, 0xffff0000, v39
	v_lshlrev_b32_e32 v160, 16, v40
	v_and_b32_e32 v161, 0xffff0000, v40
	v_lshlrev_b32_e32 v162, 16, v41
	v_and_b32_e32 v163, 0xffff0000, v41
	v_lshlrev_b32_e32 v164, 16, v42
	v_and_b32_e32 v165, 0xffff0000, v42
	v_lshlrev_b32_e32 v166, 16, v43
	v_and_b32_e32 v167, 0xffff0000, v43
	v_lshlrev_b32_e32 v168, 16, v44
	v_and_b32_e32 v169, 0xffff0000, v44
	v_lshlrev_b32_e32 v170, 16, v45
	v_and_b32_e32 v171, 0xffff0000, v45
	v_lshlrev_b32_e32 v172, 16, v46
	v_and_b32_e32 v173, 0xffff0000, v46
	v_lshlrev_b32_e32 v174, 16, v47
	v_and_b32_e32 v175, 0xffff0000, v47
	v_pk_mul_f32 v[252:253], v[160:161], v[160:161]
	v_pk_mul_f32 v[254:255], v[162:163], v[162:163]
	v_pk_fma_f32 v[252:253], v[164:165], v[164:165], v[252:253]
	v_pk_fma_f32 v[254:255], v[166:167], v[166:167], v[254:255]
	v_pk_fma_f32 v[252:253], v[168:169], v[168:169], v[252:253]
	v_pk_fma_f32 v[254:255], v[170:171], v[170:171], v[254:255]
	v_pk_fma_f32 v[252:253], v[172:173], v[172:173], v[252:253]
	v_pk_fma_f32 v[254:255], v[174:175], v[174:175], v[254:255]
	v_pk_add_f32 v[252:253], v[252:253], v[254:255]
	s_nop 0
	v_add_f32_e32 v183, v252, v253
	s_nop 1
	v_add_f32_dpp v183, v183, v183 quad_perm:[1,0,3,2] row_mask:0xf bank_mask:0xf bound_ctrl:1
	s_nop 1
	v_add_f32_dpp v183, v183, v183 quad_perm:[2,3,0,1] row_mask:0xf bank_mask:0xf bound_ctrl:1
	s_nop 1
	v_add_f32_dpp v183, v183, v183 row_half_mirror row_mask:0xf bank_mask:0xf bound_ctrl:1
	s_nop 1
	v_add_f32_dpp v183, v183, v183 row_mirror row_mask:0xf bank_mask:0xf bound_ctrl:1
	s_nop 1
	v_readlane_b32 s98, v183, 0
	v_readlane_b32 s99, v183, 16
	v_readlane_b32 s100, v183, 32
	v_readlane_b32 s101, v183, 48
	s_nop 1
	v_mov_b32_e32 v183, s98
	v_add_f32_e32 v183, s99, v183
	v_add_f32_e32 v183, s100, v183
	v_add_f32_e32 v183, s101, v183
	v_fmamk_f32 v183, v183, 0x3a800000, v182
	v_cmp_gt_f32_e32 vcc, 0x800000, v183
	v_mul_f32_e32 v181, 0x4b800000, v183
	s_nop 1
	v_cndmask_b32_e32 v183, v183, v181, vcc
	v_rsq_f32_e32 v183, v183
	s_nop 0
	v_mul_f32_e32 v181, 0x45800000, v183
	v_cndmask_b32_e32 v184, v183, v181, vcc
	v_mov_b32_e32 v185, v184
	v_pk_mul_f32 v[160:161], v[160:161], v[184:185]
	v_pk_mul_f32 v[162:163], v[162:163], v[184:185]
	v_pk_mul_f32 v[164:165], v[164:165], v[184:185]
	v_pk_mul_f32 v[166:167], v[166:167], v[184:185]
	v_pk_mul_f32 v[168:169], v[168:169], v[184:185]
	v_pk_mul_f32 v[170:171], v[170:171], v[184:185]
	v_pk_mul_f32 v[172:173], v[172:173], v[184:185]
	v_pk_mul_f32 v[174:175], v[174:175], v[184:185]
	v_pk_fma_f32 v[144:145], v[160:161], v[128:129], v[144:145]
	v_pk_fma_f32 v[146:147], v[162:163], v[130:131], v[146:147]
	v_pk_fma_f32 v[148:149], v[164:165], v[132:133], v[148:149]
	v_pk_fma_f32 v[150:151], v[166:167], v[134:135], v[150:151]
	v_pk_fma_f32 v[152:153], v[168:169], v[136:137], v[152:153]
	v_pk_fma_f32 v[154:155], v[170:171], v[138:139], v[154:155]
	v_pk_fma_f32 v[156:157], v[172:173], v[140:141], v[156:157]
	v_pk_fma_f32 v[158:159], v[174:175], v[142:143], v[158:159]
	v_pk_mul_f32 v[252:253], v[144:145], v[144:145]
	v_pk_mul_f32 v[254:255], v[146:147], v[146:147]
	v_pk_fma_f32 v[252:253], v[148:149], v[148:149], v[252:253]
	v_pk_fma_f32 v[254:255], v[150:151], v[150:151], v[254:255]
	v_pk_fma_f32 v[252:253], v[152:153], v[152:153], v[252:253]
	v_pk_fma_f32 v[254:255], v[154:155], v[154:155], v[254:255]
	v_pk_fma_f32 v[252:253], v[156:157], v[156:157], v[252:253]
	v_pk_fma_f32 v[254:255], v[158:159], v[158:159], v[254:255]
	v_pk_add_f32 v[252:253], v[252:253], v[254:255]
	s_nop 0
	v_add_f32_e32 v183, v252, v253
	s_nop 1
	v_add_f32_dpp v183, v183, v183 quad_perm:[1,0,3,2] row_mask:0xf bank_mask:0xf bound_ctrl:1
	s_nop 1
	v_add_f32_dpp v183, v183, v183 quad_perm:[2,3,0,1] row_mask:0xf bank_mask:0xf bound_ctrl:1
	s_nop 1
	v_add_f32_dpp v183, v183, v183 row_half_mirror row_mask:0xf bank_mask:0xf bound_ctrl:1
	s_nop 1
	v_add_f32_dpp v183, v183, v183 row_mirror row_mask:0xf bank_mask:0xf bound_ctrl:1
	s_nop 1
	v_readlane_b32 s98, v183, 0
	v_readlane_b32 s99, v183, 16
	v_readlane_b32 s100, v183, 32
	v_readlane_b32 s101, v183, 48
	s_nop 1
	v_mov_b32_e32 v183, s98
	v_add_f32_e32 v183, s99, v183
	v_add_f32_e32 v183, s100, v183
	v_add_f32_e32 v183, s101, v183
	v_fmamk_f32 v183, v183, 0x3a800000, v182
	v_cmp_gt_f32_e32 vcc, 0x800000, v183
	v_mul_f32_e32 v181, 0x4b800000, v183
	s_nop 1
	v_cndmask_b32_e32 v183, v183, v181, vcc
	v_rsq_f32_e32 v183, v183
	s_nop 0
	v_mul_f32_e32 v181, 0x45800000, v183
	v_cndmask_b32_e32 v184, v183, v181, vcc
	v_mov_b32_e32 v185, v184
	v_cvt_pk_bf16_f32 v32, v144, v145
	v_cvt_pk_bf16_f32 v33, v146, v147
	v_cvt_pk_bf16_f32 v34, v148, v149
	v_cvt_pk_bf16_f32 v35, v150, v151
	v_cvt_pk_bf16_f32 v36, v152, v153
	v_cvt_pk_bf16_f32 v37, v154, v155
	v_cvt_pk_bf16_f32 v38, v156, v157
	v_cvt_pk_bf16_f32 v39, v158, v159
	v_add_u32_e32 v181, 0x2000000, v177
	global_store_dwordx4 v181, v[32:35], s[78:79]
	global_store_dwordx4 v181, v[36:39], s[78:79] offset:1024
	v_add_u32_e32 v236, 0x4000, v237
	s_mov_b64 exec, 1
	global_store_dword v236, v184, s[78:79]
	s_mov_b64 exec, -1
	s_waitcnt vmcnt(16)
	v_lshlrev_b32_e32 v144, 16, v48
	v_and_b32_e32 v145, 0xffff0000, v48
	v_lshlrev_b32_e32 v146, 16, v49
	v_and_b32_e32 v147, 0xffff0000, v49
	v_lshlrev_b32_e32 v148, 16, v50
	v_and_b32_e32 v149, 0xffff0000, v50
	v_lshlrev_b32_e32 v150, 16, v51
	v_and_b32_e32 v151, 0xffff0000, v51
	v_lshlrev_b32_e32 v152, 16, v52
	v_and_b32_e32 v153, 0xffff0000, v52
	v_lshlrev_b32_e32 v154, 16, v53
	v_and_b32_e32 v155, 0xffff0000, v53
	v_lshlrev_b32_e32 v156, 16, v54
	v_and_b32_e32 v157, 0xffff0000, v54
	v_lshlrev_b32_e32 v158, 16, v55
	v_and_b32_e32 v159, 0xffff0000, v55
	v_lshlrev_b32_e32 v160, 16, v56
	v_and_b32_e32 v161, 0xffff0000, v56
	v_lshlrev_b32_e32 v162, 16, v57
	v_and_b32_e32 v163, 0xffff0000, v57
	v_lshlrev_b32_e32 v164, 16, v58
	v_and_b32_e32 v165, 0xffff0000, v58
	v_lshlrev_b32_e32 v166, 16, v59
	v_and_b32_e32 v167, 0xffff0000, v59
	v_lshlrev_b32_e32 v168, 16, v60
	v_and_b32_e32 v169, 0xffff0000, v60
	v_lshlrev_b32_e32 v170, 16, v61
	v_and_b32_e32 v171, 0xffff0000, v61
	v_lshlrev_b32_e32 v172, 16, v62
	v_and_b32_e32 v173, 0xffff0000, v62
	v_lshlrev_b32_e32 v174, 16, v63
	v_and_b32_e32 v175, 0xffff0000, v63
	v_pk_mul_f32 v[252:253], v[160:161], v[160:161]
	v_pk_mul_f32 v[254:255], v[162:163], v[162:163]
	v_pk_fma_f32 v[252:253], v[164:165], v[164:165], v[252:253]
	v_pk_fma_f32 v[254:255], v[166:167], v[166:167], v[254:255]
	v_pk_fma_f32 v[252:253], v[168:169], v[168:169], v[252:253]
	v_pk_fma_f32 v[254:255], v[170:171], v[170:171], v[254:255]
	v_pk_fma_f32 v[252:253], v[172:173], v[172:173], v[252:253]
	v_pk_fma_f32 v[254:255], v[174:175], v[174:175], v[254:255]
	v_pk_add_f32 v[252:253], v[252:253], v[254:255]
	s_nop 0
	v_add_f32_e32 v183, v252, v253
	s_nop 1
	v_add_f32_dpp v183, v183, v183 quad_perm:[1,0,3,2] row_mask:0xf bank_mask:0xf bound_ctrl:1
	s_nop 1
	v_add_f32_dpp v183, v183, v183 quad_perm:[2,3,0,1] row_mask:0xf bank_mask:0xf bound_ctrl:1
	s_nop 1
	v_add_f32_dpp v183, v183, v183 row_half_mirror row_mask:0xf bank_mask:0xf bound_ctrl:1
	s_nop 1
	v_add_f32_dpp v183, v183, v183 row_mirror row_mask:0xf bank_mask:0xf bound_ctrl:1
	s_nop 1
	v_readlane_b32 s98, v183, 0
	v_readlane_b32 s99, v183, 16
	v_readlane_b32 s100, v183, 32
	v_readlane_b32 s101, v183, 48
	s_nop 1
	v_mov_b32_e32 v183, s98
	v_add_f32_e32 v183, s99, v183
	v_add_f32_e32 v183, s100, v183
	v_add_f32_e32 v183, s101, v183
	v_fmamk_f32 v183, v183, 0x3a800000, v182
	v_cmp_gt_f32_e32 vcc, 0x800000, v183
	v_mul_f32_e32 v181, 0x4b800000, v183
	s_nop 1
	v_cndmask_b32_e32 v183, v183, v181, vcc
	v_rsq_f32_e32 v183, v183
	s_nop 0
	v_mul_f32_e32 v181, 0x45800000, v183
	v_cndmask_b32_e32 v184, v183, v181, vcc
	v_mov_b32_e32 v185, v184
	v_pk_mul_f32 v[160:161], v[160:161], v[184:185]
	v_pk_mul_f32 v[162:163], v[162:163], v[184:185]
	v_pk_mul_f32 v[164:165], v[164:165], v[184:185]
	v_pk_mul_f32 v[166:167], v[166:167], v[184:185]
	v_pk_mul_f32 v[168:169], v[168:169], v[184:185]
	v_pk_mul_f32 v[170:171], v[170:171], v[184:185]
	v_pk_mul_f32 v[172:173], v[172:173], v[184:185]
	v_pk_mul_f32 v[174:175], v[174:175], v[184:185]
	v_pk_fma_f32 v[144:145], v[160:161], v[128:129], v[144:145]
	v_pk_fma_f32 v[146:147], v[162:163], v[130:131], v[146:147]
	v_pk_fma_f32 v[148:149], v[164:165], v[132:133], v[148:149]
	v_pk_fma_f32 v[150:151], v[166:167], v[134:135], v[150:151]
	v_pk_fma_f32 v[152:153], v[168:169], v[136:137], v[152:153]
	v_pk_fma_f32 v[154:155], v[170:171], v[138:139], v[154:155]
	v_pk_fma_f32 v[156:157], v[172:173], v[140:141], v[156:157]
	v_pk_fma_f32 v[158:159], v[174:175], v[142:143], v[158:159]
	v_pk_mul_f32 v[252:253], v[144:145], v[144:145]
	v_pk_mul_f32 v[254:255], v[146:147], v[146:147]
	v_pk_fma_f32 v[252:253], v[148:149], v[148:149], v[252:253]
	v_pk_fma_f32 v[254:255], v[150:151], v[150:151], v[254:255]
	v_pk_fma_f32 v[252:253], v[152:153], v[152:153], v[252:253]
	v_pk_fma_f32 v[254:255], v[154:155], v[154:155], v[254:255]
	v_pk_fma_f32 v[252:253], v[156:157], v[156:157], v[252:253]
	v_pk_fma_f32 v[254:255], v[158:159], v[158:159], v[254:255]
	v_pk_add_f32 v[252:253], v[252:253], v[254:255]
	s_nop 0
	v_add_f32_e32 v183, v252, v253
	s_nop 1
	v_add_f32_dpp v183, v183, v183 quad_perm:[1,0,3,2] row_mask:0xf bank_mask:0xf bound_ctrl:1
	s_nop 1
	v_add_f32_dpp v183, v183, v183 quad_perm:[2,3,0,1] row_mask:0xf bank_mask:0xf bound_ctrl:1
	s_nop 1
	v_add_f32_dpp v183, v183, v183 row_half_mirror row_mask:0xf bank_mask:0xf bound_ctrl:1
	s_nop 1
	v_add_f32_dpp v183, v183, v183 row_mirror row_mask:0xf bank_mask:0xf bound_ctrl:1
	s_nop 1
	v_readlane_b32 s98, v183, 0
	v_readlane_b32 s99, v183, 16
	v_readlane_b32 s100, v183, 32
	v_readlane_b32 s101, v183, 48
	s_nop 1
	v_mov_b32_e32 v183, s98
	v_add_f32_e32 v183, s99, v183
	v_add_f32_e32 v183, s100, v183
	v_add_f32_e32 v183, s101, v183
	v_fmamk_f32 v183, v183, 0x3a800000, v182
	v_cmp_gt_f32_e32 vcc, 0x800000, v183
	v_mul_f32_e32 v181, 0x4b800000, v183
	s_nop 1
	v_cndmask_b32_e32 v183, v183, v181, vcc
	v_rsq_f32_e32 v183, v183
	s_nop 0
	v_mul_f32_e32 v181, 0x45800000, v183
	v_cndmask_b32_e32 v184, v183, v181, vcc
	v_mov_b32_e32 v185, v184
	v_cvt_pk_bf16_f32 v48, v144, v145
	v_cvt_pk_bf16_f32 v49, v146, v147
	v_cvt_pk_bf16_f32 v50, v148, v149
	v_cvt_pk_bf16_f32 v51, v150, v151
	v_cvt_pk_bf16_f32 v52, v152, v153
	v_cvt_pk_bf16_f32 v53, v154, v155
	v_cvt_pk_bf16_f32 v54, v156, v157
	v_cvt_pk_bf16_f32 v55, v158, v159
	v_add_u32_e32 v181, 0x2400000, v177
	global_store_dwordx4 v181, v[48:51], s[78:79]
	global_store_dwordx4 v181, v[52:55], s[78:79] offset:1024
	v_add_u32_e32 v236, 0x6000, v237
	s_mov_b64 exec, 1
	global_store_dword v236, v184, s[78:79]
	s_mov_b64 exec, -1
	s_waitcnt vmcnt(12)
	v_lshlrev_b32_e32 v144, 16, v64
	v_and_b32_e32 v145, 0xffff0000, v64
	v_lshlrev_b32_e32 v146, 16, v65
	v_and_b32_e32 v147, 0xffff0000, v65
	v_lshlrev_b32_e32 v148, 16, v66
	v_and_b32_e32 v149, 0xffff0000, v66
	v_lshlrev_b32_e32 v150, 16, v67
	v_and_b32_e32 v151, 0xffff0000, v67
	v_lshlrev_b32_e32 v152, 16, v68
	v_and_b32_e32 v153, 0xffff0000, v68
	v_lshlrev_b32_e32 v154, 16, v69
	v_and_b32_e32 v155, 0xffff0000, v69
	v_lshlrev_b32_e32 v156, 16, v70
	v_and_b32_e32 v157, 0xffff0000, v70
	v_lshlrev_b32_e32 v158, 16, v71
	v_and_b32_e32 v159, 0xffff0000, v71
	v_lshlrev_b32_e32 v160, 16, v72
	v_and_b32_e32 v161, 0xffff0000, v72
	v_lshlrev_b32_e32 v162, 16, v73
	v_and_b32_e32 v163, 0xffff0000, v73
	v_lshlrev_b32_e32 v164, 16, v74
	v_and_b32_e32 v165, 0xffff0000, v74
	v_lshlrev_b32_e32 v166, 16, v75
	v_and_b32_e32 v167, 0xffff0000, v75
	v_lshlrev_b32_e32 v168, 16, v76
	v_and_b32_e32 v169, 0xffff0000, v76
	v_lshlrev_b32_e32 v170, 16, v77
	v_and_b32_e32 v171, 0xffff0000, v77
	v_lshlrev_b32_e32 v172, 16, v78
	v_and_b32_e32 v173, 0xffff0000, v78
	v_lshlrev_b32_e32 v174, 16, v79
	v_and_b32_e32 v175, 0xffff0000, v79
	v_pk_mul_f32 v[252:253], v[160:161], v[160:161]
	v_pk_mul_f32 v[254:255], v[162:163], v[162:163]
	v_pk_fma_f32 v[252:253], v[164:165], v[164:165], v[252:253]
	v_pk_fma_f32 v[254:255], v[166:167], v[166:167], v[254:255]
	v_pk_fma_f32 v[252:253], v[168:169], v[168:169], v[252:253]
	v_pk_fma_f32 v[254:255], v[170:171], v[170:171], v[254:255]
	v_pk_fma_f32 v[252:253], v[172:173], v[172:173], v[252:253]
	v_pk_fma_f32 v[254:255], v[174:175], v[174:175], v[254:255]
	v_pk_add_f32 v[252:253], v[252:253], v[254:255]
	s_nop 0
	v_add_f32_e32 v183, v252, v253
	s_nop 1
	v_add_f32_dpp v183, v183, v183 quad_perm:[1,0,3,2] row_mask:0xf bank_mask:0xf bound_ctrl:1
	s_nop 1
	v_add_f32_dpp v183, v183, v183 quad_perm:[2,3,0,1] row_mask:0xf bank_mask:0xf bound_ctrl:1
	s_nop 1
	v_add_f32_dpp v183, v183, v183 row_half_mirror row_mask:0xf bank_mask:0xf bound_ctrl:1
	s_nop 1
	v_add_f32_dpp v183, v183, v183 row_mirror row_mask:0xf bank_mask:0xf bound_ctrl:1
	s_nop 1
	v_readlane_b32 s98, v183, 0
	v_readlane_b32 s99, v183, 16
	v_readlane_b32 s100, v183, 32
	v_readlane_b32 s101, v183, 48
	s_nop 1
	v_mov_b32_e32 v183, s98
	v_add_f32_e32 v183, s99, v183
	v_add_f32_e32 v183, s100, v183
	v_add_f32_e32 v183, s101, v183
	v_fmamk_f32 v183, v183, 0x3a800000, v182
	v_cmp_gt_f32_e32 vcc, 0x800000, v183
	v_mul_f32_e32 v181, 0x4b800000, v183
	s_nop 1
	v_cndmask_b32_e32 v183, v183, v181, vcc
	v_rsq_f32_e32 v183, v183
	s_nop 0
	v_mul_f32_e32 v181, 0x45800000, v183
	v_cndmask_b32_e32 v184, v183, v181, vcc
	v_mov_b32_e32 v185, v184
	v_pk_mul_f32 v[160:161], v[160:161], v[184:185]
	v_pk_mul_f32 v[162:163], v[162:163], v[184:185]
	v_pk_mul_f32 v[164:165], v[164:165], v[184:185]
	v_pk_mul_f32 v[166:167], v[166:167], v[184:185]
	v_pk_mul_f32 v[168:169], v[168:169], v[184:185]
	v_pk_mul_f32 v[170:171], v[170:171], v[184:185]
	v_pk_mul_f32 v[172:173], v[172:173], v[184:185]
	v_pk_mul_f32 v[174:175], v[174:175], v[184:185]
	v_pk_fma_f32 v[144:145], v[160:161], v[128:129], v[144:145]
	v_pk_fma_f32 v[146:147], v[162:163], v[130:131], v[146:147]
	v_pk_fma_f32 v[148:149], v[164:165], v[132:133], v[148:149]
	v_pk_fma_f32 v[150:151], v[166:167], v[134:135], v[150:151]
	v_pk_fma_f32 v[152:153], v[168:169], v[136:137], v[152:153]
	v_pk_fma_f32 v[154:155], v[170:171], v[138:139], v[154:155]
	v_pk_fma_f32 v[156:157], v[172:173], v[140:141], v[156:157]
	v_pk_fma_f32 v[158:159], v[174:175], v[142:143], v[158:159]
	v_pk_mul_f32 v[252:253], v[144:145], v[144:145]
	v_pk_mul_f32 v[254:255], v[146:147], v[146:147]
	v_pk_fma_f32 v[252:253], v[148:149], v[148:149], v[252:253]
	v_pk_fma_f32 v[254:255], v[150:151], v[150:151], v[254:255]
	v_pk_fma_f32 v[252:253], v[152:153], v[152:153], v[252:253]
	v_pk_fma_f32 v[254:255], v[154:155], v[154:155], v[254:255]
	v_pk_fma_f32 v[252:253], v[156:157], v[156:157], v[252:253]
	v_pk_fma_f32 v[254:255], v[158:159], v[158:159], v[254:255]
	v_pk_add_f32 v[252:253], v[252:253], v[254:255]
	s_nop 0
	v_add_f32_e32 v183, v252, v253
	s_nop 1
	v_add_f32_dpp v183, v183, v183 quad_perm:[1,0,3,2] row_mask:0xf bank_mask:0xf bound_ctrl:1
	s_nop 1
	v_add_f32_dpp v183, v183, v183 quad_perm:[2,3,0,1] row_mask:0xf bank_mask:0xf bound_ctrl:1
	s_nop 1
	v_add_f32_dpp v183, v183, v183 row_half_mirror row_mask:0xf bank_mask:0xf bound_ctrl:1
	s_nop 1
	v_add_f32_dpp v183, v183, v183 row_mirror row_mask:0xf bank_mask:0xf bound_ctrl:1
	s_nop 1
	v_readlane_b32 s98, v183, 0
	v_readlane_b32 s99, v183, 16
	v_readlane_b32 s100, v183, 32
	v_readlane_b32 s101, v183, 48
	s_nop 1
	v_mov_b32_e32 v183, s98
	v_add_f32_e32 v183, s99, v183
	v_add_f32_e32 v183, s100, v183
	v_add_f32_e32 v183, s101, v183
	v_fmamk_f32 v183, v183, 0x3a800000, v182
	v_cmp_gt_f32_e32 vcc, 0x800000, v183
	v_mul_f32_e32 v181, 0x4b800000, v183
	s_nop 1
	v_cndmask_b32_e32 v183, v183, v181, vcc
	v_rsq_f32_e32 v183, v183
	s_nop 0
	v_mul_f32_e32 v181, 0x45800000, v183
	v_cndmask_b32_e32 v184, v183, v181, vcc
	v_mov_b32_e32 v185, v184
	v_cvt_pk_bf16_f32 v64, v144, v145
	v_cvt_pk_bf16_f32 v65, v146, v147
	v_cvt_pk_bf16_f32 v66, v148, v149
	v_cvt_pk_bf16_f32 v67, v150, v151
	v_cvt_pk_bf16_f32 v68, v152, v153
	v_cvt_pk_bf16_f32 v69, v154, v155
	v_cvt_pk_bf16_f32 v70, v156, v157
	v_cvt_pk_bf16_f32 v71, v158, v159
	v_add_u32_e32 v181, 0x2800000, v177
	global_store_dwordx4 v181, v[64:67], s[78:79]
	global_store_dwordx4 v181, v[68:71], s[78:79] offset:1024
	v_add_u32_e32 v236, 0x8000, v237
	s_mov_b64 exec, 1
	global_store_dword v236, v184, s[78:79]
	s_mov_b64 exec, -1
	s_waitcnt vmcnt(8)
	v_lshlrev_b32_e32 v144, 16, v80
	v_and_b32_e32 v145, 0xffff0000, v80
	v_lshlrev_b32_e32 v146, 16, v81
	v_and_b32_e32 v147, 0xffff0000, v81
	v_lshlrev_b32_e32 v148, 16, v82
	v_and_b32_e32 v149, 0xffff0000, v82
	v_lshlrev_b32_e32 v150, 16, v83
	v_and_b32_e32 v151, 0xffff0000, v83
	v_lshlrev_b32_e32 v152, 16, v84
	v_and_b32_e32 v153, 0xffff0000, v84
	v_lshlrev_b32_e32 v154, 16, v85
	v_and_b32_e32 v155, 0xffff0000, v85
	v_lshlrev_b32_e32 v156, 16, v86
	v_and_b32_e32 v157, 0xffff0000, v86
	v_lshlrev_b32_e32 v158, 16, v87
	v_and_b32_e32 v159, 0xffff0000, v87
	v_lshlrev_b32_e32 v160, 16, v88
	v_and_b32_e32 v161, 0xffff0000, v88
	v_lshlrev_b32_e32 v162, 16, v89
	v_and_b32_e32 v163, 0xffff0000, v89
	v_lshlrev_b32_e32 v164, 16, v90
	v_and_b32_e32 v165, 0xffff0000, v90
	v_lshlrev_b32_e32 v166, 16, v91
	v_and_b32_e32 v167, 0xffff0000, v91
	v_lshlrev_b32_e32 v168, 16, v92
	v_and_b32_e32 v169, 0xffff0000, v92
	v_lshlrev_b32_e32 v170, 16, v93
	v_and_b32_e32 v171, 0xffff0000, v93
	v_lshlrev_b32_e32 v172, 16, v94
	v_and_b32_e32 v173, 0xffff0000, v94
	v_lshlrev_b32_e32 v174, 16, v95
	v_and_b32_e32 v175, 0xffff0000, v95
	v_pk_mul_f32 v[252:253], v[160:161], v[160:161]
	v_pk_mul_f32 v[254:255], v[162:163], v[162:163]
	v_pk_fma_f32 v[252:253], v[164:165], v[164:165], v[252:253]
	v_pk_fma_f32 v[254:255], v[166:167], v[166:167], v[254:255]
	v_pk_fma_f32 v[252:253], v[168:169], v[168:169], v[252:253]
	v_pk_fma_f32 v[254:255], v[170:171], v[170:171], v[254:255]
	v_pk_fma_f32 v[252:253], v[172:173], v[172:173], v[252:253]
	v_pk_fma_f32 v[254:255], v[174:175], v[174:175], v[254:255]
	v_pk_add_f32 v[252:253], v[252:253], v[254:255]
	s_nop 0
	v_add_f32_e32 v183, v252, v253
	s_nop 1
	v_add_f32_dpp v183, v183, v183 quad_perm:[1,0,3,2] row_mask:0xf bank_mask:0xf bound_ctrl:1
	s_nop 1
	v_add_f32_dpp v183, v183, v183 quad_perm:[2,3,0,1] row_mask:0xf bank_mask:0xf bound_ctrl:1
	s_nop 1
	v_add_f32_dpp v183, v183, v183 row_half_mirror row_mask:0xf bank_mask:0xf bound_ctrl:1
	s_nop 1
	v_add_f32_dpp v183, v183, v183 row_mirror row_mask:0xf bank_mask:0xf bound_ctrl:1
	s_nop 1
	v_readlane_b32 s98, v183, 0
	v_readlane_b32 s99, v183, 16
	v_readlane_b32 s100, v183, 32
	v_readlane_b32 s101, v183, 48
	s_nop 1
	v_mov_b32_e32 v183, s98
	v_add_f32_e32 v183, s99, v183
	v_add_f32_e32 v183, s100, v183
	v_add_f32_e32 v183, s101, v183
	v_fmamk_f32 v183, v183, 0x3a800000, v182
	v_cmp_gt_f32_e32 vcc, 0x800000, v183
	v_mul_f32_e32 v181, 0x4b800000, v183
	s_nop 1
	v_cndmask_b32_e32 v183, v183, v181, vcc
	v_rsq_f32_e32 v183, v183
	s_nop 0
	v_mul_f32_e32 v181, 0x45800000, v183
	v_cndmask_b32_e32 v184, v183, v181, vcc
	v_mov_b32_e32 v185, v184
	v_pk_mul_f32 v[160:161], v[160:161], v[184:185]
	v_pk_mul_f32 v[162:163], v[162:163], v[184:185]
	v_pk_mul_f32 v[164:165], v[164:165], v[184:185]
	v_pk_mul_f32 v[166:167], v[166:167], v[184:185]
	v_pk_mul_f32 v[168:169], v[168:169], v[184:185]
	v_pk_mul_f32 v[170:171], v[170:171], v[184:185]
	v_pk_mul_f32 v[172:173], v[172:173], v[184:185]
	v_pk_mul_f32 v[174:175], v[174:175], v[184:185]
	v_pk_fma_f32 v[144:145], v[160:161], v[128:129], v[144:145]
	v_pk_fma_f32 v[146:147], v[162:163], v[130:131], v[146:147]
	v_pk_fma_f32 v[148:149], v[164:165], v[132:133], v[148:149]
	v_pk_fma_f32 v[150:151], v[166:167], v[134:135], v[150:151]
	v_pk_fma_f32 v[152:153], v[168:169], v[136:137], v[152:153]
	v_pk_fma_f32 v[154:155], v[170:171], v[138:139], v[154:155]
	v_pk_fma_f32 v[156:157], v[172:173], v[140:141], v[156:157]
	v_pk_fma_f32 v[158:159], v[174:175], v[142:143], v[158:159]
	v_pk_mul_f32 v[252:253], v[144:145], v[144:145]
	v_pk_mul_f32 v[254:255], v[146:147], v[146:147]
	v_pk_fma_f32 v[252:253], v[148:149], v[148:149], v[252:253]
	v_pk_fma_f32 v[254:255], v[150:151], v[150:151], v[254:255]
	v_pk_fma_f32 v[252:253], v[152:153], v[152:153], v[252:253]
	v_pk_fma_f32 v[254:255], v[154:155], v[154:155], v[254:255]
	v_pk_fma_f32 v[252:253], v[156:157], v[156:157], v[252:253]
	v_pk_fma_f32 v[254:255], v[158:159], v[158:159], v[254:255]
	v_pk_add_f32 v[252:253], v[252:253], v[254:255]
	s_nop 0
	v_add_f32_e32 v183, v252, v253
	s_nop 1
	v_add_f32_dpp v183, v183, v183 quad_perm:[1,0,3,2] row_mask:0xf bank_mask:0xf bound_ctrl:1
	s_nop 1
	v_add_f32_dpp v183, v183, v183 quad_perm:[2,3,0,1] row_mask:0xf bank_mask:0xf bound_ctrl:1
	s_nop 1
	v_add_f32_dpp v183, v183, v183 row_half_mirror row_mask:0xf bank_mask:0xf bound_ctrl:1
	s_nop 1
	v_add_f32_dpp v183, v183, v183 row_mirror row_mask:0xf bank_mask:0xf bound_ctrl:1
	s_nop 1
	v_readlane_b32 s98, v183, 0
	v_readlane_b32 s99, v183, 16
	v_readlane_b32 s100, v183, 32
	v_readlane_b32 s101, v183, 48
	s_nop 1
	v_mov_b32_e32 v183, s98
	v_add_f32_e32 v183, s99, v183
	v_add_f32_e32 v183, s100, v183
	v_add_f32_e32 v183, s101, v183
	v_fmamk_f32 v183, v183, 0x3a800000, v182
	v_cmp_gt_f32_e32 vcc, 0x800000, v183
	v_mul_f32_e32 v181, 0x4b800000, v183
	s_nop 1
	v_cndmask_b32_e32 v183, v183, v181, vcc
	v_rsq_f32_e32 v183, v183
	s_nop 0
	v_mul_f32_e32 v181, 0x45800000, v183
	v_cndmask_b32_e32 v184, v183, v181, vcc
	v_mov_b32_e32 v185, v184
	v_cvt_pk_bf16_f32 v80, v144, v145
	v_cvt_pk_bf16_f32 v81, v146, v147
	v_cvt_pk_bf16_f32 v82, v148, v149
	v_cvt_pk_bf16_f32 v83, v150, v151
	v_cvt_pk_bf16_f32 v84, v152, v153
	v_cvt_pk_bf16_f32 v85, v154, v155
	v_cvt_pk_bf16_f32 v86, v156, v157
	v_cvt_pk_bf16_f32 v87, v158, v159
	v_add_u32_e32 v181, 0x2c00000, v177
	global_store_dwordx4 v181, v[80:83], s[78:79]
	global_store_dwordx4 v181, v[84:87], s[78:79] offset:1024
	v_add_u32_e32 v236, 0xa000, v237
	s_mov_b64 exec, 1
	global_store_dword v236, v184, s[78:79]
	s_mov_b64 exec, -1
	s_waitcnt vmcnt(4)
	v_lshlrev_b32_e32 v144, 16, v96
	v_and_b32_e32 v145, 0xffff0000, v96
	v_lshlrev_b32_e32 v146, 16, v97
	v_and_b32_e32 v147, 0xffff0000, v97
	v_lshlrev_b32_e32 v148, 16, v98
	v_and_b32_e32 v149, 0xffff0000, v98
	v_lshlrev_b32_e32 v150, 16, v99
	v_and_b32_e32 v151, 0xffff0000, v99
	v_lshlrev_b32_e32 v152, 16, v100
	v_and_b32_e32 v153, 0xffff0000, v100
	v_lshlrev_b32_e32 v154, 16, v101
	v_and_b32_e32 v155, 0xffff0000, v101
	v_lshlrev_b32_e32 v156, 16, v102
	v_and_b32_e32 v157, 0xffff0000, v102
	v_lshlrev_b32_e32 v158, 16, v103
	v_and_b32_e32 v159, 0xffff0000, v103
	v_lshlrev_b32_e32 v160, 16, v104
	v_and_b32_e32 v161, 0xffff0000, v104
	v_lshlrev_b32_e32 v162, 16, v105
	v_and_b32_e32 v163, 0xffff0000, v105
	v_lshlrev_b32_e32 v164, 16, v106
	v_and_b32_e32 v165, 0xffff0000, v106
	v_lshlrev_b32_e32 v166, 16, v107
	v_and_b32_e32 v167, 0xffff0000, v107
	v_lshlrev_b32_e32 v168, 16, v108
	v_and_b32_e32 v169, 0xffff0000, v108
	v_lshlrev_b32_e32 v170, 16, v109
	v_and_b32_e32 v171, 0xffff0000, v109
	v_lshlrev_b32_e32 v172, 16, v110
	v_and_b32_e32 v173, 0xffff0000, v110
	v_lshlrev_b32_e32 v174, 16, v111
	v_and_b32_e32 v175, 0xffff0000, v111
	v_pk_mul_f32 v[252:253], v[160:161], v[160:161]
	v_pk_mul_f32 v[254:255], v[162:163], v[162:163]
	v_pk_fma_f32 v[252:253], v[164:165], v[164:165], v[252:253]
	v_pk_fma_f32 v[254:255], v[166:167], v[166:167], v[254:255]
	v_pk_fma_f32 v[252:253], v[168:169], v[168:169], v[252:253]
	v_pk_fma_f32 v[254:255], v[170:171], v[170:171], v[254:255]
	v_pk_fma_f32 v[252:253], v[172:173], v[172:173], v[252:253]
	v_pk_fma_f32 v[254:255], v[174:175], v[174:175], v[254:255]
	v_pk_add_f32 v[252:253], v[252:253], v[254:255]
	s_nop 0
	v_add_f32_e32 v183, v252, v253
	s_nop 1
	v_add_f32_dpp v183, v183, v183 quad_perm:[1,0,3,2] row_mask:0xf bank_mask:0xf bound_ctrl:1
	s_nop 1
	v_add_f32_dpp v183, v183, v183 quad_perm:[2,3,0,1] row_mask:0xf bank_mask:0xf bound_ctrl:1
	s_nop 1
	v_add_f32_dpp v183, v183, v183 row_half_mirror row_mask:0xf bank_mask:0xf bound_ctrl:1
	s_nop 1
	v_add_f32_dpp v183, v183, v183 row_mirror row_mask:0xf bank_mask:0xf bound_ctrl:1
	s_nop 1
	v_readlane_b32 s98, v183, 0
	v_readlane_b32 s99, v183, 16
	v_readlane_b32 s100, v183, 32
	v_readlane_b32 s101, v183, 48
	s_nop 1
	v_mov_b32_e32 v183, s98
	v_add_f32_e32 v183, s99, v183
	v_add_f32_e32 v183, s100, v183
	v_add_f32_e32 v183, s101, v183
	v_fmamk_f32 v183, v183, 0x3a800000, v182
	v_cmp_gt_f32_e32 vcc, 0x800000, v183
	v_mul_f32_e32 v181, 0x4b800000, v183
	s_nop 1
	v_cndmask_b32_e32 v183, v183, v181, vcc
	v_rsq_f32_e32 v183, v183
	s_nop 0
	v_mul_f32_e32 v181, 0x45800000, v183
	v_cndmask_b32_e32 v184, v183, v181, vcc
	v_mov_b32_e32 v185, v184
	v_pk_mul_f32 v[160:161], v[160:161], v[184:185]
	v_pk_mul_f32 v[162:163], v[162:163], v[184:185]
	v_pk_mul_f32 v[164:165], v[164:165], v[184:185]
	v_pk_mul_f32 v[166:167], v[166:167], v[184:185]
	v_pk_mul_f32 v[168:169], v[168:169], v[184:185]
	v_pk_mul_f32 v[170:171], v[170:171], v[184:185]
	v_pk_mul_f32 v[172:173], v[172:173], v[184:185]
	v_pk_mul_f32 v[174:175], v[174:175], v[184:185]
	v_pk_fma_f32 v[144:145], v[160:161], v[128:129], v[144:145]
	v_pk_fma_f32 v[146:147], v[162:163], v[130:131], v[146:147]
	v_pk_fma_f32 v[148:149], v[164:165], v[132:133], v[148:149]
	v_pk_fma_f32 v[150:151], v[166:167], v[134:135], v[150:151]
	v_pk_fma_f32 v[152:153], v[168:169], v[136:137], v[152:153]
	v_pk_fma_f32 v[154:155], v[170:171], v[138:139], v[154:155]
	v_pk_fma_f32 v[156:157], v[172:173], v[140:141], v[156:157]
	v_pk_fma_f32 v[158:159], v[174:175], v[142:143], v[158:159]
	v_pk_mul_f32 v[252:253], v[144:145], v[144:145]
	v_pk_mul_f32 v[254:255], v[146:147], v[146:147]
	v_pk_fma_f32 v[252:253], v[148:149], v[148:149], v[252:253]
	v_pk_fma_f32 v[254:255], v[150:151], v[150:151], v[254:255]
	v_pk_fma_f32 v[252:253], v[152:153], v[152:153], v[252:253]
	v_pk_fma_f32 v[254:255], v[154:155], v[154:155], v[254:255]
	v_pk_fma_f32 v[252:253], v[156:157], v[156:157], v[252:253]
	v_pk_fma_f32 v[254:255], v[158:159], v[158:159], v[254:255]
	v_pk_add_f32 v[252:253], v[252:253], v[254:255]
	s_nop 0
	v_add_f32_e32 v183, v252, v253
	s_nop 1
	v_add_f32_dpp v183, v183, v183 quad_perm:[1,0,3,2] row_mask:0xf bank_mask:0xf bound_ctrl:1
	s_nop 1
	v_add_f32_dpp v183, v183, v183 quad_perm:[2,3,0,1] row_mask:0xf bank_mask:0xf bound_ctrl:1
	s_nop 1
	v_add_f32_dpp v183, v183, v183 row_half_mirror row_mask:0xf bank_mask:0xf bound_ctrl:1
	s_nop 1
	v_add_f32_dpp v183, v183, v183 row_mirror row_mask:0xf bank_mask:0xf bound_ctrl:1
	s_nop 1
	v_readlane_b32 s98, v183, 0
	v_readlane_b32 s99, v183, 16
	v_readlane_b32 s100, v183, 32
	v_readlane_b32 s101, v183, 48
	s_nop 1
	v_mov_b32_e32 v183, s98
	v_add_f32_e32 v183, s99, v183
	v_add_f32_e32 v183, s100, v183
	v_add_f32_e32 v183, s101, v183
	v_fmamk_f32 v183, v183, 0x3a800000, v182
	v_cmp_gt_f32_e32 vcc, 0x800000, v183
	v_mul_f32_e32 v181, 0x4b800000, v183
	s_nop 1
	v_cndmask_b32_e32 v183, v183, v181, vcc
	v_rsq_f32_e32 v183, v183
	s_nop 0
	v_mul_f32_e32 v181, 0x45800000, v183
	v_cndmask_b32_e32 v184, v183, v181, vcc
	v_mov_b32_e32 v185, v184
	v_cvt_pk_bf16_f32 v96, v144, v145
	v_cvt_pk_bf16_f32 v97, v146, v147
	v_cvt_pk_bf16_f32 v98, v148, v149
	v_cvt_pk_bf16_f32 v99, v150, v151
	v_cvt_pk_bf16_f32 v100, v152, v153
	v_cvt_pk_bf16_f32 v101, v154, v155
	v_cvt_pk_bf16_f32 v102, v156, v157
	v_cvt_pk_bf16_f32 v103, v158, v159
	v_add_u32_e32 v181, 0x3000000, v177
	global_store_dwordx4 v181, v[96:99], s[78:79]
	global_store_dwordx4 v181, v[100:103], s[78:79] offset:1024
	v_add_u32_e32 v236, 0xc000, v237
	s_mov_b64 exec, 1
	global_store_dword v236, v184, s[78:79]
	s_mov_b64 exec, -1
	s_waitcnt vmcnt(0)
	v_lshlrev_b32_e32 v144, 16, v112
	v_and_b32_e32 v145, 0xffff0000, v112
	v_lshlrev_b32_e32 v146, 16, v113
	v_and_b32_e32 v147, 0xffff0000, v113
	v_lshlrev_b32_e32 v148, 16, v114
	v_and_b32_e32 v149, 0xffff0000, v114
	v_lshlrev_b32_e32 v150, 16, v115
	v_and_b32_e32 v151, 0xffff0000, v115
	v_lshlrev_b32_e32 v152, 16, v116
	v_and_b32_e32 v153, 0xffff0000, v116
	v_lshlrev_b32_e32 v154, 16, v117
	v_and_b32_e32 v155, 0xffff0000, v117
	v_lshlrev_b32_e32 v156, 16, v118
	v_and_b32_e32 v157, 0xffff0000, v118
	v_lshlrev_b32_e32 v158, 16, v119
	v_and_b32_e32 v159, 0xffff0000, v119
	v_lshlrev_b32_e32 v160, 16, v120
	v_and_b32_e32 v161, 0xffff0000, v120
	v_lshlrev_b32_e32 v162, 16, v121
	v_and_b32_e32 v163, 0xffff0000, v121
	v_lshlrev_b32_e32 v164, 16, v122
	v_and_b32_e32 v165, 0xffff0000, v122
	v_lshlrev_b32_e32 v166, 16, v123
	v_and_b32_e32 v167, 0xffff0000, v123
	v_lshlrev_b32_e32 v168, 16, v124
	v_and_b32_e32 v169, 0xffff0000, v124
	v_lshlrev_b32_e32 v170, 16, v125
	v_and_b32_e32 v171, 0xffff0000, v125
	v_lshlrev_b32_e32 v172, 16, v126
	v_and_b32_e32 v173, 0xffff0000, v126
	v_lshlrev_b32_e32 v174, 16, v127
	v_and_b32_e32 v175, 0xffff0000, v127
	v_pk_mul_f32 v[252:253], v[160:161], v[160:161]
	v_pk_mul_f32 v[254:255], v[162:163], v[162:163]
	v_pk_fma_f32 v[252:253], v[164:165], v[164:165], v[252:253]
	v_pk_fma_f32 v[254:255], v[166:167], v[166:167], v[254:255]
	v_pk_fma_f32 v[252:253], v[168:169], v[168:169], v[252:253]
	v_pk_fma_f32 v[254:255], v[170:171], v[170:171], v[254:255]
	v_pk_fma_f32 v[252:253], v[172:173], v[172:173], v[252:253]
	v_pk_fma_f32 v[254:255], v[174:175], v[174:175], v[254:255]
	v_pk_add_f32 v[252:253], v[252:253], v[254:255]
	s_nop 0
	v_add_f32_e32 v183, v252, v253
	s_nop 1
	v_add_f32_dpp v183, v183, v183 quad_perm:[1,0,3,2] row_mask:0xf bank_mask:0xf bound_ctrl:1
	s_nop 1
	v_add_f32_dpp v183, v183, v183 quad_perm:[2,3,0,1] row_mask:0xf bank_mask:0xf bound_ctrl:1
	s_nop 1
	v_add_f32_dpp v183, v183, v183 row_half_mirror row_mask:0xf bank_mask:0xf bound_ctrl:1
	s_nop 1
	v_add_f32_dpp v183, v183, v183 row_mirror row_mask:0xf bank_mask:0xf bound_ctrl:1
	s_nop 1
	v_readlane_b32 s98, v183, 0
	v_readlane_b32 s99, v183, 16
	v_readlane_b32 s100, v183, 32
	v_readlane_b32 s101, v183, 48
	s_nop 1
	v_mov_b32_e32 v183, s98
	v_add_f32_e32 v183, s99, v183
	v_add_f32_e32 v183, s100, v183
	v_add_f32_e32 v183, s101, v183
	v_fmamk_f32 v183, v183, 0x3a800000, v182
	v_cmp_gt_f32_e32 vcc, 0x800000, v183
	v_mul_f32_e32 v181, 0x4b800000, v183
	s_nop 1
	v_cndmask_b32_e32 v183, v183, v181, vcc
	v_rsq_f32_e32 v183, v183
	s_nop 0
	v_mul_f32_e32 v181, 0x45800000, v183
	v_cndmask_b32_e32 v184, v183, v181, vcc
	v_mov_b32_e32 v185, v184
	v_pk_mul_f32 v[160:161], v[160:161], v[184:185]
	v_pk_mul_f32 v[162:163], v[162:163], v[184:185]
	v_pk_mul_f32 v[164:165], v[164:165], v[184:185]
	v_pk_mul_f32 v[166:167], v[166:167], v[184:185]
	v_pk_mul_f32 v[168:169], v[168:169], v[184:185]
	v_pk_mul_f32 v[170:171], v[170:171], v[184:185]
	v_pk_mul_f32 v[172:173], v[172:173], v[184:185]
	v_pk_mul_f32 v[174:175], v[174:175], v[184:185]
	v_pk_fma_f32 v[144:145], v[160:161], v[128:129], v[144:145]
	v_pk_fma_f32 v[146:147], v[162:163], v[130:131], v[146:147]
	v_pk_fma_f32 v[148:149], v[164:165], v[132:133], v[148:149]
	v_pk_fma_f32 v[150:151], v[166:167], v[134:135], v[150:151]
	v_pk_fma_f32 v[152:153], v[168:169], v[136:137], v[152:153]
	v_pk_fma_f32 v[154:155], v[170:171], v[138:139], v[154:155]
	v_pk_fma_f32 v[156:157], v[172:173], v[140:141], v[156:157]
	v_pk_fma_f32 v[158:159], v[174:175], v[142:143], v[158:159]
	v_pk_mul_f32 v[252:253], v[144:145], v[144:145]
	v_pk_mul_f32 v[254:255], v[146:147], v[146:147]
	v_pk_fma_f32 v[252:253], v[148:149], v[148:149], v[252:253]
	v_pk_fma_f32 v[254:255], v[150:151], v[150:151], v[254:255]
	v_pk_fma_f32 v[252:253], v[152:153], v[152:153], v[252:253]
	v_pk_fma_f32 v[254:255], v[154:155], v[154:155], v[254:255]
	v_pk_fma_f32 v[252:253], v[156:157], v[156:157], v[252:253]
	v_pk_fma_f32 v[254:255], v[158:159], v[158:159], v[254:255]
	v_pk_add_f32 v[252:253], v[252:253], v[254:255]
	s_nop 0
	v_add_f32_e32 v183, v252, v253
	s_nop 1
	v_add_f32_dpp v183, v183, v183 quad_perm:[1,0,3,2] row_mask:0xf bank_mask:0xf bound_ctrl:1
	s_nop 1
	v_add_f32_dpp v183, v183, v183 quad_perm:[2,3,0,1] row_mask:0xf bank_mask:0xf bound_ctrl:1
	s_nop 1
	v_add_f32_dpp v183, v183, v183 row_half_mirror row_mask:0xf bank_mask:0xf bound_ctrl:1
	s_nop 1
	v_add_f32_dpp v183, v183, v183 row_mirror row_mask:0xf bank_mask:0xf bound_ctrl:1
	s_nop 1
	v_readlane_b32 s98, v183, 0
	v_readlane_b32 s99, v183, 16
	v_readlane_b32 s100, v183, 32
	v_readlane_b32 s101, v183, 48
	s_nop 1
	v_mov_b32_e32 v183, s98
	v_add_f32_e32 v183, s99, v183
	v_add_f32_e32 v183, s100, v183
	v_add_f32_e32 v183, s101, v183
	v_fmamk_f32 v183, v183, 0x3a800000, v182
	v_cmp_gt_f32_e32 vcc, 0x800000, v183
	v_mul_f32_e32 v181, 0x4b800000, v183
	s_nop 1
	v_cndmask_b32_e32 v183, v183, v181, vcc
	v_rsq_f32_e32 v183, v183
	s_nop 0
	v_mul_f32_e32 v181, 0x45800000, v183
	v_cndmask_b32_e32 v184, v183, v181, vcc
	v_mov_b32_e32 v185, v184
	v_cvt_pk_bf16_f32 v112, v144, v145
	v_cvt_pk_bf16_f32 v113, v146, v147
	v_cvt_pk_bf16_f32 v114, v148, v149
	v_cvt_pk_bf16_f32 v115, v150, v151
	v_cvt_pk_bf16_f32 v116, v152, v153
	v_cvt_pk_bf16_f32 v117, v154, v155
	v_cvt_pk_bf16_f32 v118, v156, v157
	v_cvt_pk_bf16_f32 v119, v158, v159
	v_add_u32_e32 v181, 0x3400000, v177
	global_store_dwordx4 v181, v[112:115], s[78:79]
	global_store_dwordx4 v181, v[116:119], s[78:79] offset:1024
	v_add_u32_e32 v236, 0xe000, v237
	s_mov_b64 exec, 1
	global_store_dword v236, v184, s[78:79]
	s_mov_b64 exec, -1
	v_readfirstlane_b32 s98, v179
	s_nop 3
	s_and_b32 s99, s98, 3
	s_add_i32 s100, s99, 4
	s_lshl_b32 s100, s100, 11
	s_sub_i32 s100, s100, s99
	s_lshl_b32 s101, s100, 11
	v_add_u32_e32 v177, s101, v177
	s_lshl_b32 s101, s100, 2
	v_add_u32_e32 v237, s101, v237
	v_add_u32_e32 v181, 0x1800000, v177
	global_load_dwordx4 v[0:3], v181, s[78:79]
	global_load_dwordx4 v[4:7], v181, s[78:79] offset:1024
	v_add_u32_e32 v181, 0x9e00000, v177
	global_load_dwordx4 v[8:11], v181, s[78:79]
	global_load_dwordx4 v[12:15], v181, s[78:79] offset:1024
	s_waitcnt vmcnt(0)
	v_lshlrev_b32_e32 v144, 16, v0
	v_and_b32_e32 v145, 0xffff0000, v0
	v_lshlrev_b32_e32 v146, 16, v1
	v_and_b32_e32 v147, 0xffff0000, v1
	v_lshlrev_b32_e32 v148, 16, v2
	v_and_b32_e32 v149, 0xffff0000, v2
	v_lshlrev_b32_e32 v150, 16, v3
	v_and_b32_e32 v151, 0xffff0000, v3
	v_lshlrev_b32_e32 v152, 16, v4
	v_and_b32_e32 v153, 0xffff0000, v4
	v_lshlrev_b32_e32 v154, 16, v5
	v_and_b32_e32 v155, 0xffff0000, v5
	v_lshlrev_b32_e32 v156, 16, v6
	v_and_b32_e32 v157, 0xffff0000, v6
	v_lshlrev_b32_e32 v158, 16, v7
	v_and_b32_e32 v159, 0xffff0000, v7
	v_lshlrev_b32_e32 v160, 16, v8
	v_and_b32_e32 v161, 0xffff0000, v8
	v_lshlrev_b32_e32 v162, 16, v9
	v_and_b32_e32 v163, 0xffff0000, v9
	v_lshlrev_b32_e32 v164, 16, v10
	v_and_b32_e32 v165, 0xffff0000, v10
	v_lshlrev_b32_e32 v166, 16, v11
	v_and_b32_e32 v167, 0xffff0000, v11
	v_lshlrev_b32_e32 v168, 16, v12
	v_and_b32_e32 v169, 0xffff0000, v12
	v_lshlrev_b32_e32 v170, 16, v13
	v_and_b32_e32 v171, 0xffff0000, v13
	v_lshlrev_b32_e32 v172, 16, v14
	v_and_b32_e32 v173, 0xffff0000, v14
	v_lshlrev_b32_e32 v174, 16, v15
	v_and_b32_e32 v175, 0xffff0000, v15
	v_pk_mul_f32 v[252:253], v[160:161], v[160:161]
	v_pk_mul_f32 v[254:255], v[162:163], v[162:163]
	v_pk_fma_f32 v[252:253], v[164:165], v[164:165], v[252:253]
	v_pk_fma_f32 v[254:255], v[166:167], v[166:167], v[254:255]
	v_pk_fma_f32 v[252:253], v[168:169], v[168:169], v[252:253]
	v_pk_fma_f32 v[254:255], v[170:171], v[170:171], v[254:255]
	v_pk_fma_f32 v[252:253], v[172:173], v[172:173], v[252:253]
	v_pk_fma_f32 v[254:255], v[174:175], v[174:175], v[254:255]
	v_pk_add_f32 v[252:253], v[252:253], v[254:255]
	s_nop 0
	v_add_f32_e32 v183, v252, v253
	s_nop 1
	v_add_f32_dpp v183, v183, v183 quad_perm:[1,0,3,2] row_mask:0xf bank_mask:0xf bound_ctrl:1
	s_nop 1
	v_add_f32_dpp v183, v183, v183 quad_perm:[2,3,0,1] row_mask:0xf bank_mask:0xf bound_ctrl:1
	s_nop 1
	v_add_f32_dpp v183, v183, v183 row_half_mirror row_mask:0xf bank_mask:0xf bound_ctrl:1
	s_nop 1
	v_add_f32_dpp v183, v183, v183 row_mirror row_mask:0xf bank_mask:0xf bound_ctrl:1
	s_nop 1
	v_readlane_b32 s98, v183, 0
	v_readlane_b32 s99, v183, 16
	v_readlane_b32 s100, v183, 32
	v_readlane_b32 s101, v183, 48
	s_nop 1
	v_mov_b32_e32 v183, s98
	v_add_f32_e32 v183, s99, v183
	v_add_f32_e32 v183, s100, v183
	v_add_f32_e32 v183, s101, v183
	v_fmamk_f32 v183, v183, 0x3a800000, v182
	v_cmp_gt_f32_e32 vcc, 0x800000, v183
	v_mul_f32_e32 v181, 0x4b800000, v183
	s_nop 1
	v_cndmask_b32_e32 v183, v183, v181, vcc
	v_rsq_f32_e32 v183, v183
	s_nop 0
	v_mul_f32_e32 v181, 0x45800000, v183
	v_cndmask_b32_e32 v184, v183, v181, vcc
	v_mov_b32_e32 v185, v184
	v_pk_mul_f32 v[160:161], v[160:161], v[184:185]
	v_pk_mul_f32 v[162:163], v[162:163], v[184:185]
	v_pk_mul_f32 v[164:165], v[164:165], v[184:185]
	v_pk_mul_f32 v[166:167], v[166:167], v[184:185]
	v_pk_mul_f32 v[168:169], v[168:169], v[184:185]
	v_pk_mul_f32 v[170:171], v[170:171], v[184:185]
	v_pk_mul_f32 v[172:173], v[172:173], v[184:185]
	v_pk_mul_f32 v[174:175], v[174:175], v[184:185]
	v_pk_fma_f32 v[144:145], v[160:161], v[128:129], v[144:145]
	v_pk_fma_f32 v[146:147], v[162:163], v[130:131], v[146:147]
	v_pk_fma_f32 v[148:149], v[164:165], v[132:133], v[148:149]
	v_pk_fma_f32 v[150:151], v[166:167], v[134:135], v[150:151]
	v_pk_fma_f32 v[152:153], v[168:169], v[136:137], v[152:153]
	v_pk_fma_f32 v[154:155], v[170:171], v[138:139], v[154:155]
	v_pk_fma_f32 v[156:157], v[172:173], v[140:141], v[156:157]
	v_pk_fma_f32 v[158:159], v[174:175], v[142:143], v[158:159]
	v_pk_mul_f32 v[252:253], v[144:145], v[144:145]
	v_pk_mul_f32 v[254:255], v[146:147], v[146:147]
	v_pk_fma_f32 v[252:253], v[148:149], v[148:149], v[252:253]
	v_pk_fma_f32 v[254:255], v[150:151], v[150:151], v[254:255]
	v_pk_fma_f32 v[252:253], v[152:153], v[152:153], v[252:253]
	v_pk_fma_f32 v[254:255], v[154:155], v[154:155], v[254:255]
	v_pk_fma_f32 v[252:253], v[156:157], v[156:157], v[252:253]
	v_pk_fma_f32 v[254:255], v[158:159], v[158:159], v[254:255]
	v_pk_add_f32 v[252:253], v[252:253], v[254:255]
	s_nop 0
	v_add_f32_e32 v183, v252, v253
	s_nop 1
	v_add_f32_dpp v183, v183, v183 quad_perm:[1,0,3,2] row_mask:0xf bank_mask:0xf bound_ctrl:1
	s_nop 1
	v_add_f32_dpp v183, v183, v183 quad_perm:[2,3,0,1] row_mask:0xf bank_mask:0xf bound_ctrl:1
	s_nop 1
	v_add_f32_dpp v183, v183, v183 row_half_mirror row_mask:0xf bank_mask:0xf bound_ctrl:1
	s_nop 1
	v_add_f32_dpp v183, v183, v183 row_mirror row_mask:0xf bank_mask:0xf bound_ctrl:1
	s_nop 1
	v_readlane_b32 s98, v183, 0
	v_readlane_b32 s99, v183, 16
	v_readlane_b32 s100, v183, 32
	v_readlane_b32 s101, v183, 48
	s_nop 1
	v_mov_b32_e32 v183, s98
	v_add_f32_e32 v183, s99, v183
	v_add_f32_e32 v183, s100, v183
	v_add_f32_e32 v183, s101, v183
	v_fmamk_f32 v183, v183, 0x3a800000, v182
	v_cmp_gt_f32_e32 vcc, 0x800000, v183
	v_mul_f32_e32 v181, 0x4b800000, v183
	s_nop 1
	v_cndmask_b32_e32 v183, v183, v181, vcc
	v_rsq_f32_e32 v183, v183
	s_nop 0
	v_mul_f32_e32 v181, 0x45800000, v183
	v_cndmask_b32_e32 v184, v183, v181, vcc
	v_mov_b32_e32 v185, v184
	v_cvt_pk_bf16_f32 v0, v144, v145
	v_cvt_pk_bf16_f32 v1, v146, v147
	v_cvt_pk_bf16_f32 v2, v148, v149
	v_cvt_pk_bf16_f32 v3, v150, v151
	v_cvt_pk_bf16_f32 v4, v152, v153
	v_cvt_pk_bf16_f32 v5, v154, v155
	v_cvt_pk_bf16_f32 v6, v156, v157
	v_cvt_pk_bf16_f32 v7, v158, v159
	v_add_u32_e32 v181, 0x1800000, v177
	global_store_dwordx4 v181, v[0:3], s[78:79]
	global_store_dwordx4 v181, v[4:7], s[78:79] offset:1024
	v_add_u32_e32 v236, 0x0, v237
	s_mov_b64 exec, 1
	global_store_dword v236, v184, s[78:79]
	s_mov_b64 exec, -1
	s_branch .Lmyxupd_done_2

.LBB0_1430:
	v_readlane_b32 s0, v235, 52
	v_readlane_b32 s1, v235, 53
	s_and_b64 vcc, exec, s[0:1]
	s_waitcnt lgkmcnt(0)
	s_barrier
	v_mbcnt_lo_u32_b32 v0, -1, 0
	v_mbcnt_hi_u32_b32 v0, -1, v0
	s_cbranch_vccnz .LBB0_1450
	v_lshlrev_b32_e32 v2, 3, v0
	v_readlane_b32 s4, v235, 4
	v_ashrrev_i32_e32 v3, 31, v2
	v_readlane_b32 s6, v235, 6
	v_readlane_b32 s7, v235, 7
	v_lshlrev_b64 v[4:5], 1, v[2:3]
	v_lshlrev_b64 v[2:3], 2, v[2:3]
	v_readlane_b32 s5, v235, 5
	v_readlane_b32 s10, v235, 10
	v_readlane_b32 s11, v235, 11
	v_readlane_b32 s18, v235, 18
	v_readlane_b32 s19, v235, 19
	v_readlane_b32 s6, v235, 61
	v_lshl_add_u64 v[154:155], s[90:91], 0, v[2:3]
	v_readlane_b32 s8, v235, 8
	v_lshl_add_u64 v[2:3], s[18:19], 0, v[2:3]
	s_mov_b64 s[0:1], 0x1000
	v_readlane_b32 s4, v235, 0
	v_readlane_b32 s7, v235, 62
	s_mov_b32 s10, s6
	s_ashr_i32 s11, s6, 31
	v_readlane_b32 s9, v235, 9
	v_lshl_add_u64 v[158:159], v[2:3], 0, s[0:1]
	s_lshl_b32 s4, s4, 4
	s_add_i32 s0, s6, 0xffffc000
	s_lshl_b64 s[6:7], s[10:11], 2
	s_mov_b32 s8, s10
	v_readlane_b32 s12, v235, 12
	v_readlane_b32 s13, v235, 13
	v_readlane_b32 s14, v235, 14
	v_readlane_b32 s15, v235, 15
	v_readlane_b32 s16, v235, 16
	v_readlane_b32 s17, v235, 17
	v_readlane_b32 s5, v235, 1
	s_add_u32 s80, s6, 0x10000
	v_writelane_b32 v235, s8, 61
	s_addc_u32 s12, s7, 0
	s_ashr_i32 s5, s4, 31
	v_writelane_b32 v235, s9, 62
	s_lshl_b64 s[8:9], s[10:11], 11
	v_lshl_add_u64 v[152:153], s[86:87], 0, v[4:5]
	v_lshl_add_u64 v[156:157], s[54:55], 0, v[4:5]
	s_mov_b32 s1, 0
	v_cmp_eq_u32_e64 s[16:17], 0, v0
	s_lshl_b64 s[6:7], s[4:5], 2
	v_lshl_add_u64 v[160:161], s[8:9], 0, v[4:5]
	s_lshl_b64 s[8:9], s[4:5], 11
	s_mov_b64 s[20:21], 0x600000
	s_mov_b64 s[22:23], 0x600800
	s_mov_b64 s[24:25], 0x800000
	s_mov_b32 s5, 0x800000
	s_mov_b64 s[26:27], 0x800800
	s_mov_b64 s[28:29], 0xa00000
	s_mov_b64 s[36:37], 0xa00800
	s_mov_b64 s[38:39], 0xc00000
	s_mov_b64 s[40:41], 0xc00800
	s_mov_b64 s[42:43], 0xe00000
	s_mov_b64 s[44:45], 0xe00800
	s_mov_b64 s[46:47], 0x1000000
	s_mov_b32 s13, 0x1000000
	s_mov_b64 s[48:49], 0x1000800
	s_mov_b64 s[50:51], 0x1200000
	s_mov_b32 s14, 0x1200000
	s_mov_b64 s[10:11], 0x1200800
	s_mov_b64 s[82:83], 0x1400000
	s_mov_b32 s15, 0x1400000
	s_mov_b64 s[90:91], 0x1400800
	v_mov_b32_e32 v215, 0
	v_mov_b32_e32 v216, 0x358637bd
	v_mbcnt_lo_u32_b32 v176, -1, 0
	v_mbcnt_hi_u32_b32 v176, -1, v176
	v_readlane_b32 s98, v235, 49
	v_readlane_b32 s99, v235, 20
	v_readlane_b32 s100, v235, 18
	v_readlane_b32 s101, v235, 19
	s_nop 3
	s_lshr_b32 vcc_lo, s98, 3
	s_and_b32 vcc_hi, vcc_lo, 7
	s_lshr_b32 vcc_lo, vcc_lo, 3
	s_lshl_b32 vcc_lo, vcc_lo, 3
	s_add_i32 vcc_lo, vcc_lo, s99
	s_lshl_b32 s98, vcc_hi, 8
	s_add_i32 s98, s98, vcc_lo
	s_mov_b32 s99, s98
	v_mov_b32_e32 v183, s99
	v_lshlrev_b32_e32 v177, 4, v176
	s_lshl_b32 s99, s99, 11
	v_add_u32_e32 v177, s99, v177
	v_add_u32_e32 v178, 0x1800000, v177
	v_add_u32_e32 v179, 0x9e00000, v177
	v_lshlrev_b32_e32 v180, 5, v176
	v_add_u32_e32 v181, 0x1000, v180
	global_load_dwordx4 v[128:131], v181, s[100:101]
	global_load_dwordx4 v[132:135], v181, s[100:101] offset:16
	global_load_dwordx4 v[136:139], v181, s[100:101] offset:2048
	global_load_dwordx4 v[140:143], v181, s[100:101] offset:2064
	v_mov_b32_e32 v182, 0x358637bd
	s_and_b32 vcc_lo, s98, 3
	s_cmp_eq_u32 vcc_lo, 0
	s_cbranch_scc1 .Lmyxupd_heavy_3
	global_load_dwordx4 v[0:3], v178, s[78:79]
	global_load_dwordx4 v[4:7], v178, s[78:79] offset:1024
	global_load_dwordx4 v[8:11], v179, s[78:79]
	global_load_dwordx4 v[12:15], v179, s[78:79] offset:1024
	v_add_u32_e32 v178, 0x400000, v178
	v_add_u32_e32 v179, 0x400000, v179
	global_load_dwordx4 v[16:19], v178, s[78:79]
	global_load_dwordx4 v[20:23], v178, s[78:79] offset:1024
	global_load_dwordx4 v[24:27], v179, s[78:79]
	global_load_dwordx4 v[28:31], v179, s[78:79] offset:1024
	v_add_u32_e32 v178, 0x400000, v178
	v_add_u32_e32 v179, 0x400000, v179
	global_load_dwordx4 v[32:35], v178, s[78:79]
	global_load_dwordx4 v[36:39], v178, s[78:79] offset:1024
	global_load_dwordx4 v[40:43], v179, s[78:79]
	global_load_dwordx4 v[44:47], v179, s[78:79] offset:1024
	v_add_u32_e32 v178, 0x400000, v178
	v_add_u32_e32 v179, 0x400000, v179
	global_load_dwordx4 v[48:51], v178, s[78:79]
	global_load_dwordx4 v[52:55], v178, s[78:79] offset:1024
	global_load_dwordx4 v[56:59], v179, s[78:79]
	global_load_dwordx4 v[60:63], v179, s[78:79] offset:1024
	v_add_u32_e32 v178, 0x400000, v178
	v_add_u32_e32 v179, 0x400000, v179
	global_load_dwordx4 v[64:67], v178, s[78:79]
	global_load_dwordx4 v[68:71], v178, s[78:79] offset:1024
	global_load_dwordx4 v[72:75], v179, s[78:79]
	global_load_dwordx4 v[76:79], v179, s[78:79] offset:1024
	v_add_u32_e32 v178, 0x400000, v178
	v_add_u32_e32 v179, 0x400000, v179
	global_load_dwordx4 v[80:83], v178, s[78:79]
	global_load_dwordx4 v[84:87], v178, s[78:79] offset:1024
	global_load_dwordx4 v[88:91], v179, s[78:79]
	global_load_dwordx4 v[92:95], v179, s[78:79] offset:1024
	v_add_u32_e32 v178, 0x400000, v178
	v_add_u32_e32 v179, 0x400000, v179
	global_load_dwordx4 v[96:99], v178, s[78:79]
	global_load_dwordx4 v[100:103], v178, s[78:79] offset:1024
	global_load_dwordx4 v[104:107], v179, s[78:79]
	global_load_dwordx4 v[108:111], v179, s[78:79] offset:1024
	v_add_u32_e32 v178, 0x400000, v178
	v_add_u32_e32 v179, 0x400000, v179
	global_load_dwordx4 v[112:115], v178, s[78:79]
	global_load_dwordx4 v[116:119], v178, s[78:79] offset:1024
	global_load_dwordx4 v[120:123], v179, s[78:79]
	global_load_dwordx4 v[124:127], v179, s[78:79] offset:1024
	v_lshlrev_b32_e32 v237, 2, v183
	v_add_u32_e32 v237, 0x10000, v237
	v_mov_b32_e32 v179, s98
	s_waitcnt vmcnt(28)
	v_lshlrev_b32_e32 v144, 16, v0
	v_and_b32_e32 v145, 0xffff0000, v0
	v_lshlrev_b32_e32 v146, 16, v1
	v_and_b32_e32 v147, 0xffff0000, v1
	v_lshlrev_b32_e32 v148, 16, v2
	v_and_b32_e32 v149, 0xffff0000, v2
	v_lshlrev_b32_e32 v150, 16, v3
	v_and_b32_e32 v151, 0xffff0000, v3
	v_lshlrev_b32_e32 v152, 16, v4
	v_and_b32_e32 v153, 0xffff0000, v4
	v_lshlrev_b32_e32 v154, 16, v5
	v_and_b32_e32 v155, 0xffff0000, v5
	v_lshlrev_b32_e32 v156, 16, v6
	v_and_b32_e32 v157, 0xffff0000, v6
	v_lshlrev_b32_e32 v158, 16, v7
	v_and_b32_e32 v159, 0xffff0000, v7
	v_lshlrev_b32_e32 v160, 16, v8
	v_and_b32_e32 v161, 0xffff0000, v8
	v_lshlrev_b32_e32 v162, 16, v9
	v_and_b32_e32 v163, 0xffff0000, v9
	v_lshlrev_b32_e32 v164, 16, v10
	v_and_b32_e32 v165, 0xffff0000, v10
	v_lshlrev_b32_e32 v166, 16, v11
	v_and_b32_e32 v167, 0xffff0000, v11
	v_lshlrev_b32_e32 v168, 16, v12
	v_and_b32_e32 v169, 0xffff0000, v12
	v_lshlrev_b32_e32 v170, 16, v13
	v_and_b32_e32 v171, 0xffff0000, v13
	v_lshlrev_b32_e32 v172, 16, v14
	v_and_b32_e32 v173, 0xffff0000, v14
	v_lshlrev_b32_e32 v174, 16, v15
	v_and_b32_e32 v175, 0xffff0000, v15
	v_pk_mul_f32 v[252:253], v[160:161], v[160:161]
	v_pk_mul_f32 v[254:255], v[162:163], v[162:163]
	v_pk_fma_f32 v[252:253], v[164:165], v[164:165], v[252:253]
	v_pk_fma_f32 v[254:255], v[166:167], v[166:167], v[254:255]
	v_pk_fma_f32 v[252:253], v[168:169], v[168:169], v[252:253]
	v_pk_fma_f32 v[254:255], v[170:171], v[170:171], v[254:255]
	v_pk_fma_f32 v[252:253], v[172:173], v[172:173], v[252:253]
	v_pk_fma_f32 v[254:255], v[174:175], v[174:175], v[254:255]
	v_pk_add_f32 v[252:253], v[252:253], v[254:255]
	s_nop 0
	v_add_f32_e32 v183, v252, v253
	s_nop 1
	v_add_f32_dpp v183, v183, v183 quad_perm:[1,0,3,2] row_mask:0xf bank_mask:0xf bound_ctrl:1
	s_nop 1
	v_add_f32_dpp v183, v183, v183 quad_perm:[2,3,0,1] row_mask:0xf bank_mask:0xf bound_ctrl:1
	s_nop 1
	v_add_f32_dpp v183, v183, v183 row_half_mirror row_mask:0xf bank_mask:0xf bound_ctrl:1
	s_nop 1
	v_add_f32_dpp v183, v183, v183 row_mirror row_mask:0xf bank_mask:0xf bound_ctrl:1
	s_nop 1
	v_readlane_b32 s98, v183, 0
	v_readlane_b32 s99, v183, 16
	v_readlane_b32 s100, v183, 32
	v_readlane_b32 s101, v183, 48
	s_nop 1
	v_mov_b32_e32 v183, s98
	v_add_f32_e32 v183, s99, v183
	v_add_f32_e32 v183, s100, v183
	v_add_f32_e32 v183, s101, v183
	v_fmamk_f32 v183, v183, 0x3a800000, v182
	v_cmp_gt_f32_e32 vcc, 0x800000, v183
	v_mul_f32_e32 v181, 0x4b800000, v183
	s_nop 1
	v_cndmask_b32_e32 v183, v183, v181, vcc
	v_rsq_f32_e32 v183, v183
	s_nop 0
	v_mul_f32_e32 v181, 0x45800000, v183
	v_cndmask_b32_e32 v184, v183, v181, vcc
	v_mov_b32_e32 v185, v184
	v_pk_mul_f32 v[160:161], v[160:161], v[184:185]
	v_pk_mul_f32 v[162:163], v[162:163], v[184:185]
	v_pk_mul_f32 v[164:165], v[164:165], v[184:185]
	v_pk_mul_f32 v[166:167], v[166:167], v[184:185]
	v_pk_mul_f32 v[168:169], v[168:169], v[184:185]
	v_pk_mul_f32 v[170:171], v[170:171], v[184:185]
	v_pk_mul_f32 v[172:173], v[172:173], v[184:185]
	v_pk_mul_f32 v[174:175], v[174:175], v[184:185]
	v_pk_fma_f32 v[144:145], v[160:161], v[128:129], v[144:145]
	v_pk_fma_f32 v[146:147], v[162:163], v[130:131], v[146:147]
	v_pk_fma_f32 v[148:149], v[164:165], v[132:133], v[148:149]
	v_pk_fma_f32 v[150:151], v[166:167], v[134:135], v[150:151]
	v_pk_fma_f32 v[152:153], v[168:169], v[136:137], v[152:153]
	v_pk_fma_f32 v[154:155], v[170:171], v[138:139], v[154:155]
	v_pk_fma_f32 v[156:157], v[172:173], v[140:141], v[156:157]
	v_pk_fma_f32 v[158:159], v[174:175], v[142:143], v[158:159]
	v_pk_mul_f32 v[252:253], v[144:145], v[144:145]
	v_pk_mul_f32 v[254:255], v[146:147], v[146:147]
	v_pk_fma_f32 v[252:253], v[148:149], v[148:149], v[252:253]
	v_pk_fma_f32 v[254:255], v[150:151], v[150:151], v[254:255]
	v_pk_fma_f32 v[252:253], v[152:153], v[152:153], v[252:253]
	v_pk_fma_f32 v[254:255], v[154:155], v[154:155], v[254:255]
	v_pk_fma_f32 v[252:253], v[156:157], v[156:157], v[252:253]
	v_pk_fma_f32 v[254:255], v[158:159], v[158:159], v[254:255]
	v_pk_add_f32 v[252:253], v[252:253], v[254:255]
	s_nop 0
	v_add_f32_e32 v183, v252, v253
	s_nop 1
	v_add_f32_dpp v183, v183, v183 quad_perm:[1,0,3,2] row_mask:0xf bank_mask:0xf bound_ctrl:1
	s_nop 1
	v_add_f32_dpp v183, v183, v183 quad_perm:[2,3,0,1] row_mask:0xf bank_mask:0xf bound_ctrl:1
	s_nop 1
	v_add_f32_dpp v183, v183, v183 row_half_mirror row_mask:0xf bank_mask:0xf bound_ctrl:1
	s_nop 1
	v_add_f32_dpp v183, v183, v183 row_mirror row_mask:0xf bank_mask:0xf bound_ctrl:1
	s_nop 1
	v_readlane_b32 s98, v183, 0
	v_readlane_b32 s99, v183, 16
	v_readlane_b32 s100, v183, 32
	v_readlane_b32 s101, v183, 48
	s_nop 1
	v_mov_b32_e32 v183, s98
	v_add_f32_e32 v183, s99, v183
	v_add_f32_e32 v183, s100, v183
	v_add_f32_e32 v183, s101, v183
	v_fmamk_f32 v183, v183, 0x3a800000, v182
	v_cmp_gt_f32_e32 vcc, 0x800000, v183
	v_mul_f32_e32 v181, 0x4b800000, v183
	s_nop 1
	v_cndmask_b32_e32 v183, v183, v181, vcc
	v_rsq_f32_e32 v183, v183
	s_nop 0
	v_mul_f32_e32 v181, 0x45800000, v183
	v_cndmask_b32_e32 v184, v183, v181, vcc
	v_mov_b32_e32 v185, v184
	v_cvt_pk_bf16_f32 v0, v144, v145
	v_cvt_pk_bf16_f32 v1, v146, v147
	v_cvt_pk_bf16_f32 v2, v148, v149
	v_cvt_pk_bf16_f32 v3, v150, v151
	v_cvt_pk_bf16_f32 v4, v152, v153
	v_cvt_pk_bf16_f32 v5, v154, v155
	v_cvt_pk_bf16_f32 v6, v156, v157
	v_cvt_pk_bf16_f32 v7, v158, v159
	v_add_u32_e32 v181, 0x1800000, v177
	global_store_dwordx4 v181, v[0:3], s[78:79]
	global_store_dwordx4 v181, v[4:7], s[78:79] offset:1024
	v_add_u32_e32 v236, 0x0, v237
	s_mov_b64 exec, 1
	global_store_dword v236, v184, s[78:79]
	s_mov_b64 exec, -1
	s_waitcnt vmcnt(24)
	v_lshlrev_b32_e32 v144, 16, v16
	v_and_b32_e32 v145, 0xffff0000, v16
	v_lshlrev_b32_e32 v146, 16, v17
	v_and_b32_e32 v147, 0xffff0000, v17
	v_lshlrev_b32_e32 v148, 16, v18
	v_and_b32_e32 v149, 0xffff0000, v18
	v_lshlrev_b32_e32 v150, 16, v19
	v_and_b32_e32 v151, 0xffff0000, v19
	v_lshlrev_b32_e32 v152, 16, v20
	v_and_b32_e32 v153, 0xffff0000, v20
	v_lshlrev_b32_e32 v154, 16, v21
	v_and_b32_e32 v155, 0xffff0000, v21
	v_lshlrev_b32_e32 v156, 16, v22
	v_and_b32_e32 v157, 0xffff0000, v22
	v_lshlrev_b32_e32 v158, 16, v23
	v_and_b32_e32 v159, 0xffff0000, v23
	v_lshlrev_b32_e32 v160, 16, v24
	v_and_b32_e32 v161, 0xffff0000, v24
	v_lshlrev_b32_e32 v162, 16, v25
	v_and_b32_e32 v163, 0xffff0000, v25
	v_lshlrev_b32_e32 v164, 16, v26
	v_and_b32_e32 v165, 0xffff0000, v26
	v_lshlrev_b32_e32 v166, 16, v27
	v_and_b32_e32 v167, 0xffff0000, v27
	v_lshlrev_b32_e32 v168, 16, v28
	v_and_b32_e32 v169, 0xffff0000, v28
	v_lshlrev_b32_e32 v170, 16, v29
	v_and_b32_e32 v171, 0xffff0000, v29
	v_lshlrev_b32_e32 v172, 16, v30
	v_and_b32_e32 v173, 0xffff0000, v30
	v_lshlrev_b32_e32 v174, 16, v31
	v_and_b32_e32 v175, 0xffff0000, v31
	v_pk_mul_f32 v[252:253], v[160:161], v[160:161]
	v_pk_mul_f32 v[254:255], v[162:163], v[162:163]
	v_pk_fma_f32 v[252:253], v[164:165], v[164:165], v[252:253]
	v_pk_fma_f32 v[254:255], v[166:167], v[166:167], v[254:255]
	v_pk_fma_f32 v[252:253], v[168:169], v[168:169], v[252:253]
	v_pk_fma_f32 v[254:255], v[170:171], v[170:171], v[254:255]
	v_pk_fma_f32 v[252:253], v[172:173], v[172:173], v[252:253]
	v_pk_fma_f32 v[254:255], v[174:175], v[174:175], v[254:255]
	v_pk_add_f32 v[252:253], v[252:253], v[254:255]
	s_nop 0
	v_add_f32_e32 v183, v252, v253
	s_nop 1
	v_add_f32_dpp v183, v183, v183 quad_perm:[1,0,3,2] row_mask:0xf bank_mask:0xf bound_ctrl:1
	s_nop 1
	v_add_f32_dpp v183, v183, v183 quad_perm:[2,3,0,1] row_mask:0xf bank_mask:0xf bound_ctrl:1
	s_nop 1
	v_add_f32_dpp v183, v183, v183 row_half_mirror row_mask:0xf bank_mask:0xf bound_ctrl:1
	s_nop 1
	v_add_f32_dpp v183, v183, v183 row_mirror row_mask:0xf bank_mask:0xf bound_ctrl:1
	s_nop 1
	v_readlane_b32 s98, v183, 0
	v_readlane_b32 s99, v183, 16
	v_readlane_b32 s100, v183, 32
	v_readlane_b32 s101, v183, 48
	s_nop 1
	v_mov_b32_e32 v183, s98
	v_add_f32_e32 v183, s99, v183
	v_add_f32_e32 v183, s100, v183
	v_add_f32_e32 v183, s101, v183
	v_fmamk_f32 v183, v183, 0x3a800000, v182
	v_cmp_gt_f32_e32 vcc, 0x800000, v183
	v_mul_f32_e32 v181, 0x4b800000, v183
	s_nop 1
	v_cndmask_b32_e32 v183, v183, v181, vcc
	v_rsq_f32_e32 v183, v183
	s_nop 0
	v_mul_f32_e32 v181, 0x45800000, v183
	v_cndmask_b32_e32 v184, v183, v181, vcc
	v_mov_b32_e32 v185, v184
	v_pk_mul_f32 v[160:161], v[160:161], v[184:185]
	v_pk_mul_f32 v[162:163], v[162:163], v[184:185]
	v_pk_mul_f32 v[164:165], v[164:165], v[184:185]
	v_pk_mul_f32 v[166:167], v[166:167], v[184:185]
	v_pk_mul_f32 v[168:169], v[168:169], v[184:185]
	v_pk_mul_f32 v[170:171], v[170:171], v[184:185]
	v_pk_mul_f32 v[172:173], v[172:173], v[184:185]
	v_pk_mul_f32 v[174:175], v[174:175], v[184:185]
	v_pk_fma_f32 v[144:145], v[160:161], v[128:129], v[144:145]
	v_pk_fma_f32 v[146:147], v[162:163], v[130:131], v[146:147]
	v_pk_fma_f32 v[148:149], v[164:165], v[132:133], v[148:149]
	v_pk_fma_f32 v[150:151], v[166:167], v[134:135], v[150:151]
	v_pk_fma_f32 v[152:153], v[168:169], v[136:137], v[152:153]
	v_pk_fma_f32 v[154:155], v[170:171], v[138:139], v[154:155]
	v_pk_fma_f32 v[156:157], v[172:173], v[140:141], v[156:157]
	v_pk_fma_f32 v[158:159], v[174:175], v[142:143], v[158:159]
	v_pk_mul_f32 v[252:253], v[144:145], v[144:145]
	v_pk_mul_f32 v[254:255], v[146:147], v[146:147]
	v_pk_fma_f32 v[252:253], v[148:149], v[148:149], v[252:253]
	v_pk_fma_f32 v[254:255], v[150:151], v[150:151], v[254:255]
	v_pk_fma_f32 v[252:253], v[152:153], v[152:153], v[252:253]
	v_pk_fma_f32 v[254:255], v[154:155], v[154:155], v[254:255]
	v_pk_fma_f32 v[252:253], v[156:157], v[156:157], v[252:253]
	v_pk_fma_f32 v[254:255], v[158:159], v[158:159], v[254:255]
	v_pk_add_f32 v[252:253], v[252:253], v[254:255]
	s_nop 0
	v_add_f32_e32 v183, v252, v253
	s_nop 1
	v_add_f32_dpp v183, v183, v183 quad_perm:[1,0,3,2] row_mask:0xf bank_mask:0xf bound_ctrl:1
	s_nop 1
	v_add_f32_dpp v183, v183, v183 quad_perm:[2,3,0,1] row_mask:0xf bank_mask:0xf bound_ctrl:1
	s_nop 1
	v_add_f32_dpp v183, v183, v183 row_half_mirror row_mask:0xf bank_mask:0xf bound_ctrl:1
	s_nop 1
	v_add_f32_dpp v183, v183, v183 row_mirror row_mask:0xf bank_mask:0xf bound_ctrl:1
	s_nop 1
	v_readlane_b32 s98, v183, 0
	v_readlane_b32 s99, v183, 16
	v_readlane_b32 s100, v183, 32
	v_readlane_b32 s101, v183, 48
	s_nop 1
	v_mov_b32_e32 v183, s98
	v_add_f32_e32 v183, s99, v183
	v_add_f32_e32 v183, s100, v183
	v_add_f32_e32 v183, s101, v183
	v_fmamk_f32 v183, v183, 0x3a800000, v182
	v_cmp_gt_f32_e32 vcc, 0x800000, v183
	v_mul_f32_e32 v181, 0x4b800000, v183
	s_nop 1
	v_cndmask_b32_e32 v183, v183, v181, vcc
	v_rsq_f32_e32 v183, v183
	s_nop 0
	v_mul_f32_e32 v181, 0x45800000, v183
	v_cndmask_b32_e32 v184, v183, v181, vcc
	v_mov_b32_e32 v185, v184
	v_cvt_pk_bf16_f32 v16, v144, v145
	v_cvt_pk_bf16_f32 v17, v146, v147
	v_cvt_pk_bf16_f32 v18, v148, v149
	v_cvt_pk_bf16_f32 v19, v150, v151
	v_cvt_pk_bf16_f32 v20, v152, v153
	v_cvt_pk_bf16_f32 v21, v154, v155
	v_cvt_pk_bf16_f32 v22, v156, v157
	v_cvt_pk_bf16_f32 v23, v158, v159
	v_add_u32_e32 v181, 0x1c00000, v177
	global_store_dwordx4 v181, v[16:19], s[78:79]
	global_store_dwordx4 v181, v[20:23], s[78:79] offset:1024
	v_add_u32_e32 v236, 0x2000, v237
	s_mov_b64 exec, 1
	global_store_dword v236, v184, s[78:79]
	s_mov_b64 exec, -1
	s_waitcnt vmcnt(20)
	v_lshlrev_b32_e32 v144, 16, v32
	v_and_b32_e32 v145, 0xffff0000, v32
	v_lshlrev_b32_e32 v146, 16, v33
	v_and_b32_e32 v147, 0xffff0000, v33
	v_lshlrev_b32_e32 v148, 16, v34
	v_and_b32_e32 v149, 0xffff0000, v34
	v_lshlrev_b32_e32 v150, 16, v35
	v_and_b32_e32 v151, 0xffff0000, v35
	v_lshlrev_b32_e32 v152, 16, v36
	v_and_b32_e32 v153, 0xffff0000, v36
	v_lshlrev_b32_e32 v154, 16, v37
	v_and_b32_e32 v155, 0xffff0000, v37
	v_lshlrev_b32_e32 v156, 16, v38
	v_and_b32_e32 v157, 0xffff0000, v38
	v_lshlrev_b32_e32 v158, 16, v39
	v_and_b32_e32 v159, 0xffff0000, v39
	v_lshlrev_b32_e32 v160, 16, v40
	v_and_b32_e32 v161, 0xffff0000, v40
	v_lshlrev_b32_e32 v162, 16, v41
	v_and_b32_e32 v163, 0xffff0000, v41
	v_lshlrev_b32_e32 v164, 16, v42
	v_and_b32_e32 v165, 0xffff0000, v42
	v_lshlrev_b32_e32 v166, 16, v43
	v_and_b32_e32 v167, 0xffff0000, v43
	v_lshlrev_b32_e32 v168, 16, v44
	v_and_b32_e32 v169, 0xffff0000, v44
	v_lshlrev_b32_e32 v170, 16, v45
	v_and_b32_e32 v171, 0xffff0000, v45
	v_lshlrev_b32_e32 v172, 16, v46
	v_and_b32_e32 v173, 0xffff0000, v46
	v_lshlrev_b32_e32 v174, 16, v47
	v_and_b32_e32 v175, 0xffff0000, v47
	v_pk_mul_f32 v[252:253], v[160:161], v[160:161]
	v_pk_mul_f32 v[254:255], v[162:163], v[162:163]
	v_pk_fma_f32 v[252:253], v[164:165], v[164:165], v[252:253]
	v_pk_fma_f32 v[254:255], v[166:167], v[166:167], v[254:255]
	v_pk_fma_f32 v[252:253], v[168:169], v[168:169], v[252:253]
	v_pk_fma_f32 v[254:255], v[170:171], v[170:171], v[254:255]
	v_pk_fma_f32 v[252:253], v[172:173], v[172:173], v[252:253]
	v_pk_fma_f32 v[254:255], v[174:175], v[174:175], v[254:255]
	v_pk_add_f32 v[252:253], v[252:253], v[254:255]
	s_nop 0
	v_add_f32_e32 v183, v252, v253
	s_nop 1
	v_add_f32_dpp v183, v183, v183 quad_perm:[1,0,3,2] row_mask:0xf bank_mask:0xf bound_ctrl:1
	s_nop 1
	v_add_f32_dpp v183, v183, v183 quad_perm:[2,3,0,1] row_mask:0xf bank_mask:0xf bound_ctrl:1
	s_nop 1
	v_add_f32_dpp v183, v183, v183 row_half_mirror row_mask:0xf bank_mask:0xf bound_ctrl:1
	s_nop 1
	v_add_f32_dpp v183, v183, v183 row_mirror row_mask:0xf bank_mask:0xf bound_ctrl:1
	s_nop 1
	v_readlane_b32 s98, v183, 0
	v_readlane_b32 s99, v183, 16
	v_readlane_b32 s100, v183, 32
	v_readlane_b32 s101, v183, 48
	s_nop 1
	v_mov_b32_e32 v183, s98
	v_add_f32_e32 v183, s99, v183
	v_add_f32_e32 v183, s100, v183
	v_add_f32_e32 v183, s101, v183
	v_fmamk_f32 v183, v183, 0x3a800000, v182
	v_cmp_gt_f32_e32 vcc, 0x800000, v183
	v_mul_f32_e32 v181, 0x4b800000, v183
	s_nop 1
	v_cndmask_b32_e32 v183, v183, v181, vcc
	v_rsq_f32_e32 v183, v183
	s_nop 0
	v_mul_f32_e32 v181, 0x45800000, v183
	v_cndmask_b32_e32 v184, v183, v181, vcc
	v_mov_b32_e32 v185, v184
	v_pk_mul_f32 v[160:161], v[160:161], v[184:185]
	v_pk_mul_f32 v[162:163], v[162:163], v[184:185]
	v_pk_mul_f32 v[164:165], v[164:165], v[184:185]
	v_pk_mul_f32 v[166:167], v[166:167], v[184:185]
	v_pk_mul_f32 v[168:169], v[168:169], v[184:185]
	v_pk_mul_f32 v[170:171], v[170:171], v[184:185]
	v_pk_mul_f32 v[172:173], v[172:173], v[184:185]
	v_pk_mul_f32 v[174:175], v[174:175], v[184:185]
	v_pk_fma_f32 v[144:145], v[160:161], v[128:129], v[144:145]
	v_pk_fma_f32 v[146:147], v[162:163], v[130:131], v[146:147]
	v_pk_fma_f32 v[148:149], v[164:165], v[132:133], v[148:149]
	v_pk_fma_f32 v[150:151], v[166:167], v[134:135], v[150:151]
	v_pk_fma_f32 v[152:153], v[168:169], v[136:137], v[152:153]
	v_pk_fma_f32 v[154:155], v[170:171], v[138:139], v[154:155]
	v_pk_fma_f32 v[156:157], v[172:173], v[140:141], v[156:157]
	v_pk_fma_f32 v[158:159], v[174:175], v[142:143], v[158:159]
	v_pk_mul_f32 v[252:253], v[144:145], v[144:145]
	v_pk_mul_f32 v[254:255], v[146:147], v[146:147]
	v_pk_fma_f32 v[252:253], v[148:149], v[148:149], v[252:253]
	v_pk_fma_f32 v[254:255], v[150:151], v[150:151], v[254:255]
	v_pk_fma_f32 v[252:253], v[152:153], v[152:153], v[252:253]
	v_pk_fma_f32 v[254:255], v[154:155], v[154:155], v[254:255]
	v_pk_fma_f32 v[252:253], v[156:157], v[156:157], v[252:253]
	v_pk_fma_f32 v[254:255], v[158:159], v[158:159], v[254:255]
	v_pk_add_f32 v[252:253], v[252:253], v[254:255]
	s_nop 0
	v_add_f32_e32 v183, v252, v253
	s_nop 1
	v_add_f32_dpp v183, v183, v183 quad_perm:[1,0,3,2] row_mask:0xf bank_mask:0xf bound_ctrl:1
	s_nop 1
	v_add_f32_dpp v183, v183, v183 quad_perm:[2,3,0,1] row_mask:0xf bank_mask:0xf bound_ctrl:1
	s_nop 1
	v_add_f32_dpp v183, v183, v183 row_half_mirror row_mask:0xf bank_mask:0xf bound_ctrl:1
	s_nop 1
	v_add_f32_dpp v183, v183, v183 row_mirror row_mask:0xf bank_mask:0xf bound_ctrl:1
	s_nop 1
	v_readlane_b32 s98, v183, 0
	v_readlane_b32 s99, v183, 16
	v_readlane_b32 s100, v183, 32
	v_readlane_b32 s101, v183, 48
	s_nop 1
	v_mov_b32_e32 v183, s98
	v_add_f32_e32 v183, s99, v183
	v_add_f32_e32 v183, s100, v183
	v_add_f32_e32 v183, s101, v183
	v_fmamk_f32 v183, v183, 0x3a800000, v182
	v_cmp_gt_f32_e32 vcc, 0x800000, v183
	v_mul_f32_e32 v181, 0x4b800000, v183
	s_nop 1
	v_cndmask_b32_e32 v183, v183, v181, vcc
	v_rsq_f32_e32 v183, v183
	s_nop 0
	v_mul_f32_e32 v181, 0x45800000, v183
	v_cndmask_b32_e32 v184, v183, v181, vcc
	v_mov_b32_e32 v185, v184
	v_cvt_pk_bf16_f32 v32, v144, v145
	v_cvt_pk_bf16_f32 v33, v146, v147
	v_cvt_pk_bf16_f32 v34, v148, v149
	v_cvt_pk_bf16_f32 v35, v150, v151
	v_cvt_pk_bf16_f32 v36, v152, v153
	v_cvt_pk_bf16_f32 v37, v154, v155
	v_cvt_pk_bf16_f32 v38, v156, v157
	v_cvt_pk_bf16_f32 v39, v158, v159
	v_add_u32_e32 v181, 0x2000000, v177
	global_store_dwordx4 v181, v[32:35], s[78:79]
	global_store_dwordx4 v181, v[36:39], s[78:79] offset:1024
	v_add_u32_e32 v236, 0x4000, v237
	s_mov_b64 exec, 1
	global_store_dword v236, v184, s[78:79]
	s_mov_b64 exec, -1
	s_waitcnt vmcnt(16)
	v_lshlrev_b32_e32 v144, 16, v48
	v_and_b32_e32 v145, 0xffff0000, v48
	v_lshlrev_b32_e32 v146, 16, v49
	v_and_b32_e32 v147, 0xffff0000, v49
	v_lshlrev_b32_e32 v148, 16, v50
	v_and_b32_e32 v149, 0xffff0000, v50
	v_lshlrev_b32_e32 v150, 16, v51
	v_and_b32_e32 v151, 0xffff0000, v51
	v_lshlrev_b32_e32 v152, 16, v52
	v_and_b32_e32 v153, 0xffff0000, v52
	v_lshlrev_b32_e32 v154, 16, v53
	v_and_b32_e32 v155, 0xffff0000, v53
	v_lshlrev_b32_e32 v156, 16, v54
	v_and_b32_e32 v157, 0xffff0000, v54
	v_lshlrev_b32_e32 v158, 16, v55
	v_and_b32_e32 v159, 0xffff0000, v55
	v_lshlrev_b32_e32 v160, 16, v56
	v_and_b32_e32 v161, 0xffff0000, v56
	v_lshlrev_b32_e32 v162, 16, v57
	v_and_b32_e32 v163, 0xffff0000, v57
	v_lshlrev_b32_e32 v164, 16, v58
	v_and_b32_e32 v165, 0xffff0000, v58
	v_lshlrev_b32_e32 v166, 16, v59
	v_and_b32_e32 v167, 0xffff0000, v59
	v_lshlrev_b32_e32 v168, 16, v60
	v_and_b32_e32 v169, 0xffff0000, v60
	v_lshlrev_b32_e32 v170, 16, v61
	v_and_b32_e32 v171, 0xffff0000, v61
	v_lshlrev_b32_e32 v172, 16, v62
	v_and_b32_e32 v173, 0xffff0000, v62
	v_lshlrev_b32_e32 v174, 16, v63
	v_and_b32_e32 v175, 0xffff0000, v63
	v_pk_mul_f32 v[252:253], v[160:161], v[160:161]
	v_pk_mul_f32 v[254:255], v[162:163], v[162:163]
	v_pk_fma_f32 v[252:253], v[164:165], v[164:165], v[252:253]
	v_pk_fma_f32 v[254:255], v[166:167], v[166:167], v[254:255]
	v_pk_fma_f32 v[252:253], v[168:169], v[168:169], v[252:253]
	v_pk_fma_f32 v[254:255], v[170:171], v[170:171], v[254:255]
	v_pk_fma_f32 v[252:253], v[172:173], v[172:173], v[252:253]
	v_pk_fma_f32 v[254:255], v[174:175], v[174:175], v[254:255]
	v_pk_add_f32 v[252:253], v[252:253], v[254:255]
	s_nop 0
	v_add_f32_e32 v183, v252, v253
	s_nop 1
	v_add_f32_dpp v183, v183, v183 quad_perm:[1,0,3,2] row_mask:0xf bank_mask:0xf bound_ctrl:1
	s_nop 1
	v_add_f32_dpp v183, v183, v183 quad_perm:[2,3,0,1] row_mask:0xf bank_mask:0xf bound_ctrl:1
	s_nop 1
	v_add_f32_dpp v183, v183, v183 row_half_mirror row_mask:0xf bank_mask:0xf bound_ctrl:1
	s_nop 1
	v_add_f32_dpp v183, v183, v183 row_mirror row_mask:0xf bank_mask:0xf bound_ctrl:1
	s_nop 1
	v_readlane_b32 s98, v183, 0
	v_readlane_b32 s99, v183, 16
	v_readlane_b32 s100, v183, 32
	v_readlane_b32 s101, v183, 48
	s_nop 1
	v_mov_b32_e32 v183, s98
	v_add_f32_e32 v183, s99, v183
	v_add_f32_e32 v183, s100, v183
	v_add_f32_e32 v183, s101, v183
	v_fmamk_f32 v183, v183, 0x3a800000, v182
	v_cmp_gt_f32_e32 vcc, 0x800000, v183
	v_mul_f32_e32 v181, 0x4b800000, v183
	s_nop 1
	v_cndmask_b32_e32 v183, v183, v181, vcc
	v_rsq_f32_e32 v183, v183
	s_nop 0
	v_mul_f32_e32 v181, 0x45800000, v183
	v_cndmask_b32_e32 v184, v183, v181, vcc
	v_mov_b32_e32 v185, v184
	v_pk_mul_f32 v[160:161], v[160:161], v[184:185]
	v_pk_mul_f32 v[162:163], v[162:163], v[184:185]
	v_pk_mul_f32 v[164:165], v[164:165], v[184:185]
	v_pk_mul_f32 v[166:167], v[166:167], v[184:185]
	v_pk_mul_f32 v[168:169], v[168:169], v[184:185]
	v_pk_mul_f32 v[170:171], v[170:171], v[184:185]
	v_pk_mul_f32 v[172:173], v[172:173], v[184:185]
	v_pk_mul_f32 v[174:175], v[174:175], v[184:185]
	v_pk_fma_f32 v[144:145], v[160:161], v[128:129], v[144:145]
	v_pk_fma_f32 v[146:147], v[162:163], v[130:131], v[146:147]
	v_pk_fma_f32 v[148:149], v[164:165], v[132:133], v[148:149]
	v_pk_fma_f32 v[150:151], v[166:167], v[134:135], v[150:151]
	v_pk_fma_f32 v[152:153], v[168:169], v[136:137], v[152:153]
	v_pk_fma_f32 v[154:155], v[170:171], v[138:139], v[154:155]
	v_pk_fma_f32 v[156:157], v[172:173], v[140:141], v[156:157]
	v_pk_fma_f32 v[158:159], v[174:175], v[142:143], v[158:159]
	v_pk_mul_f32 v[252:253], v[144:145], v[144:145]
	v_pk_mul_f32 v[254:255], v[146:147], v[146:147]
	v_pk_fma_f32 v[252:253], v[148:149], v[148:149], v[252:253]
	v_pk_fma_f32 v[254:255], v[150:151], v[150:151], v[254:255]
	v_pk_fma_f32 v[252:253], v[152:153], v[152:153], v[252:253]
	v_pk_fma_f32 v[254:255], v[154:155], v[154:155], v[254:255]
	v_pk_fma_f32 v[252:253], v[156:157], v[156:157], v[252:253]
	v_pk_fma_f32 v[254:255], v[158:159], v[158:159], v[254:255]
	v_pk_add_f32 v[252:253], v[252:253], v[254:255]
	s_nop 0
	v_add_f32_e32 v183, v252, v253
	s_nop 1
	v_add_f32_dpp v183, v183, v183 quad_perm:[1,0,3,2] row_mask:0xf bank_mask:0xf bound_ctrl:1
	s_nop 1
	v_add_f32_dpp v183, v183, v183 quad_perm:[2,3,0,1] row_mask:0xf bank_mask:0xf bound_ctrl:1
	s_nop 1
	v_add_f32_dpp v183, v183, v183 row_half_mirror row_mask:0xf bank_mask:0xf bound_ctrl:1
	s_nop 1
	v_add_f32_dpp v183, v183, v183 row_mirror row_mask:0xf bank_mask:0xf bound_ctrl:1
	s_nop 1
	v_readlane_b32 s98, v183, 0
	v_readlane_b32 s99, v183, 16
	v_readlane_b32 s100, v183, 32
	v_readlane_b32 s101, v183, 48
	s_nop 1
	v_mov_b32_e32 v183, s98
	v_add_f32_e32 v183, s99, v183
	v_add_f32_e32 v183, s100, v183
	v_add_f32_e32 v183, s101, v183
	v_fmamk_f32 v183, v183, 0x3a800000, v182
	v_cmp_gt_f32_e32 vcc, 0x800000, v183
	v_mul_f32_e32 v181, 0x4b800000, v183
	s_nop 1
	v_cndmask_b32_e32 v183, v183, v181, vcc
	v_rsq_f32_e32 v183, v183
	s_nop 0
	v_mul_f32_e32 v181, 0x45800000, v183
	v_cndmask_b32_e32 v184, v183, v181, vcc
	v_mov_b32_e32 v185, v184
	v_cvt_pk_bf16_f32 v48, v144, v145
	v_cvt_pk_bf16_f32 v49, v146, v147
	v_cvt_pk_bf16_f32 v50, v148, v149
	v_cvt_pk_bf16_f32 v51, v150, v151
	v_cvt_pk_bf16_f32 v52, v152, v153
	v_cvt_pk_bf16_f32 v53, v154, v155
	v_cvt_pk_bf16_f32 v54, v156, v157
	v_cvt_pk_bf16_f32 v55, v158, v159
	v_add_u32_e32 v181, 0x2400000, v177
	global_store_dwordx4 v181, v[48:51], s[78:79]
	global_store_dwordx4 v181, v[52:55], s[78:79] offset:1024
	v_add_u32_e32 v236, 0x6000, v237
	s_mov_b64 exec, 1
	global_store_dword v236, v184, s[78:79]
	s_mov_b64 exec, -1
	s_waitcnt vmcnt(12)
	v_lshlrev_b32_e32 v144, 16, v64
	v_and_b32_e32 v145, 0xffff0000, v64
	v_lshlrev_b32_e32 v146, 16, v65
	v_and_b32_e32 v147, 0xffff0000, v65
	v_lshlrev_b32_e32 v148, 16, v66
	v_and_b32_e32 v149, 0xffff0000, v66
	v_lshlrev_b32_e32 v150, 16, v67
	v_and_b32_e32 v151, 0xffff0000, v67
	v_lshlrev_b32_e32 v152, 16, v68
	v_and_b32_e32 v153, 0xffff0000, v68
	v_lshlrev_b32_e32 v154, 16, v69
	v_and_b32_e32 v155, 0xffff0000, v69
	v_lshlrev_b32_e32 v156, 16, v70
	v_and_b32_e32 v157, 0xffff0000, v70
	v_lshlrev_b32_e32 v158, 16, v71
	v_and_b32_e32 v159, 0xffff0000, v71
	v_lshlrev_b32_e32 v160, 16, v72
	v_and_b32_e32 v161, 0xffff0000, v72
	v_lshlrev_b32_e32 v162, 16, v73
	v_and_b32_e32 v163, 0xffff0000, v73
	v_lshlrev_b32_e32 v164, 16, v74
	v_and_b32_e32 v165, 0xffff0000, v74
	v_lshlrev_b32_e32 v166, 16, v75
	v_and_b32_e32 v167, 0xffff0000, v75
	v_lshlrev_b32_e32 v168, 16, v76
	v_and_b32_e32 v169, 0xffff0000, v76
	v_lshlrev_b32_e32 v170, 16, v77
	v_and_b32_e32 v171, 0xffff0000, v77
	v_lshlrev_b32_e32 v172, 16, v78
	v_and_b32_e32 v173, 0xffff0000, v78
	v_lshlrev_b32_e32 v174, 16, v79
	v_and_b32_e32 v175, 0xffff0000, v79
	v_pk_mul_f32 v[252:253], v[160:161], v[160:161]
	v_pk_mul_f32 v[254:255], v[162:163], v[162:163]
	v_pk_fma_f32 v[252:253], v[164:165], v[164:165], v[252:253]
	v_pk_fma_f32 v[254:255], v[166:167], v[166:167], v[254:255]
	v_pk_fma_f32 v[252:253], v[168:169], v[168:169], v[252:253]
	v_pk_fma_f32 v[254:255], v[170:171], v[170:171], v[254:255]
	v_pk_fma_f32 v[252:253], v[172:173], v[172:173], v[252:253]
	v_pk_fma_f32 v[254:255], v[174:175], v[174:175], v[254:255]
	v_pk_add_f32 v[252:253], v[252:253], v[254:255]
	s_nop 0
	v_add_f32_e32 v183, v252, v253
	s_nop 1
	v_add_f32_dpp v183, v183, v183 quad_perm:[1,0,3,2] row_mask:0xf bank_mask:0xf bound_ctrl:1
	s_nop 1
	v_add_f32_dpp v183, v183, v183 quad_perm:[2,3,0,1] row_mask:0xf bank_mask:0xf bound_ctrl:1
	s_nop 1
	v_add_f32_dpp v183, v183, v183 row_half_mirror row_mask:0xf bank_mask:0xf bound_ctrl:1
	s_nop 1
	v_add_f32_dpp v183, v183, v183 row_mirror row_mask:0xf bank_mask:0xf bound_ctrl:1
	s_nop 1
	v_readlane_b32 s98, v183, 0
	v_readlane_b32 s99, v183, 16
	v_readlane_b32 s100, v183, 32
	v_readlane_b32 s101, v183, 48
	s_nop 1
	v_mov_b32_e32 v183, s98
	v_add_f32_e32 v183, s99, v183
	v_add_f32_e32 v183, s100, v183
	v_add_f32_e32 v183, s101, v183
	v_fmamk_f32 v183, v183, 0x3a800000, v182
	v_cmp_gt_f32_e32 vcc, 0x800000, v183
	v_mul_f32_e32 v181, 0x4b800000, v183
	s_nop 1
	v_cndmask_b32_e32 v183, v183, v181, vcc
	v_rsq_f32_e32 v183, v183
	s_nop 0
	v_mul_f32_e32 v181, 0x45800000, v183
	v_cndmask_b32_e32 v184, v183, v181, vcc
	v_mov_b32_e32 v185, v184
	v_pk_mul_f32 v[160:161], v[160:161], v[184:185]
	v_pk_mul_f32 v[162:163], v[162:163], v[184:185]
	v_pk_mul_f32 v[164:165], v[164:165], v[184:185]
	v_pk_mul_f32 v[166:167], v[166:167], v[184:185]
	v_pk_mul_f32 v[168:169], v[168:169], v[184:185]
	v_pk_mul_f32 v[170:171], v[170:171], v[184:185]
	v_pk_mul_f32 v[172:173], v[172:173], v[184:185]
	v_pk_mul_f32 v[174:175], v[174:175], v[184:185]
	v_pk_fma_f32 v[144:145], v[160:161], v[128:129], v[144:145]
	v_pk_fma_f32 v[146:147], v[162:163], v[130:131], v[146:147]
	v_pk_fma_f32 v[148:149], v[164:165], v[132:133], v[148:149]
	v_pk_fma_f32 v[150:151], v[166:167], v[134:135], v[150:151]
	v_pk_fma_f32 v[152:153], v[168:169], v[136:137], v[152:153]
	v_pk_fma_f32 v[154:155], v[170:171], v[138:139], v[154:155]
	v_pk_fma_f32 v[156:157], v[172:173], v[140:141], v[156:157]
	v_pk_fma_f32 v[158:159], v[174:175], v[142:143], v[158:159]
	v_pk_mul_f32 v[252:253], v[144:145], v[144:145]
	v_pk_mul_f32 v[254:255], v[146:147], v[146:147]
	v_pk_fma_f32 v[252:253], v[148:149], v[148:149], v[252:253]
	v_pk_fma_f32 v[254:255], v[150:151], v[150:151], v[254:255]
	v_pk_fma_f32 v[252:253], v[152:153], v[152:153], v[252:253]
	v_pk_fma_f32 v[254:255], v[154:155], v[154:155], v[254:255]
	v_pk_fma_f32 v[252:253], v[156:157], v[156:157], v[252:253]
	v_pk_fma_f32 v[254:255], v[158:159], v[158:159], v[254:255]
	v_pk_add_f32 v[252:253], v[252:253], v[254:255]
	s_nop 0
	v_add_f32_e32 v183, v252, v253
	s_nop 1
	v_add_f32_dpp v183, v183, v183 quad_perm:[1,0,3,2] row_mask:0xf bank_mask:0xf bound_ctrl:1
	s_nop 1
	v_add_f32_dpp v183, v183, v183 quad_perm:[2,3,0,1] row_mask:0xf bank_mask:0xf bound_ctrl:1
	s_nop 1
	v_add_f32_dpp v183, v183, v183 row_half_mirror row_mask:0xf bank_mask:0xf bound_ctrl:1
	s_nop 1
	v_add_f32_dpp v183, v183, v183 row_mirror row_mask:0xf bank_mask:0xf bound_ctrl:1
	s_nop 1
	v_readlane_b32 s98, v183, 0
	v_readlane_b32 s99, v183, 16
	v_readlane_b32 s100, v183, 32
	v_readlane_b32 s101, v183, 48
	s_nop 1
	v_mov_b32_e32 v183, s98
	v_add_f32_e32 v183, s99, v183
	v_add_f32_e32 v183, s100, v183
	v_add_f32_e32 v183, s101, v183
	v_fmamk_f32 v183, v183, 0x3a800000, v182
	v_cmp_gt_f32_e32 vcc, 0x800000, v183
	v_mul_f32_e32 v181, 0x4b800000, v183
	s_nop 1
	v_cndmask_b32_e32 v183, v183, v181, vcc
	v_rsq_f32_e32 v183, v183
	s_nop 0
	v_mul_f32_e32 v181, 0x45800000, v183
	v_cndmask_b32_e32 v184, v183, v181, vcc
	v_mov_b32_e32 v185, v184
	v_cvt_pk_bf16_f32 v64, v144, v145
	v_cvt_pk_bf16_f32 v65, v146, v147
	v_cvt_pk_bf16_f32 v66, v148, v149
	v_cvt_pk_bf16_f32 v67, v150, v151
	v_cvt_pk_bf16_f32 v68, v152, v153
	v_cvt_pk_bf16_f32 v69, v154, v155
	v_cvt_pk_bf16_f32 v70, v156, v157
	v_cvt_pk_bf16_f32 v71, v158, v159
	v_add_u32_e32 v181, 0x2800000, v177
	global_store_dwordx4 v181, v[64:67], s[78:79]
	global_store_dwordx4 v181, v[68:71], s[78:79] offset:1024
	v_add_u32_e32 v236, 0x8000, v237
	s_mov_b64 exec, 1
	global_store_dword v236, v184, s[78:79]
	s_mov_b64 exec, -1
	s_waitcnt vmcnt(8)
	v_lshlrev_b32_e32 v144, 16, v80
	v_and_b32_e32 v145, 0xffff0000, v80
	v_lshlrev_b32_e32 v146, 16, v81
	v_and_b32_e32 v147, 0xffff0000, v81
	v_lshlrev_b32_e32 v148, 16, v82
	v_and_b32_e32 v149, 0xffff0000, v82
	v_lshlrev_b32_e32 v150, 16, v83
	v_and_b32_e32 v151, 0xffff0000, v83
	v_lshlrev_b32_e32 v152, 16, v84
	v_and_b32_e32 v153, 0xffff0000, v84
	v_lshlrev_b32_e32 v154, 16, v85
	v_and_b32_e32 v155, 0xffff0000, v85
	v_lshlrev_b32_e32 v156, 16, v86
	v_and_b32_e32 v157, 0xffff0000, v86
	v_lshlrev_b32_e32 v158, 16, v87
	v_and_b32_e32 v159, 0xffff0000, v87
	v_lshlrev_b32_e32 v160, 16, v88
	v_and_b32_e32 v161, 0xffff0000, v88
	v_lshlrev_b32_e32 v162, 16, v89
	v_and_b32_e32 v163, 0xffff0000, v89
	v_lshlrev_b32_e32 v164, 16, v90
	v_and_b32_e32 v165, 0xffff0000, v90
	v_lshlrev_b32_e32 v166, 16, v91
	v_and_b32_e32 v167, 0xffff0000, v91
	v_lshlrev_b32_e32 v168, 16, v92
	v_and_b32_e32 v169, 0xffff0000, v92
	v_lshlrev_b32_e32 v170, 16, v93
	v_and_b32_e32 v171, 0xffff0000, v93
	v_lshlrev_b32_e32 v172, 16, v94
	v_and_b32_e32 v173, 0xffff0000, v94
	v_lshlrev_b32_e32 v174, 16, v95
	v_and_b32_e32 v175, 0xffff0000, v95
	v_pk_mul_f32 v[252:253], v[160:161], v[160:161]
	v_pk_mul_f32 v[254:255], v[162:163], v[162:163]
	v_pk_fma_f32 v[252:253], v[164:165], v[164:165], v[252:253]
	v_pk_fma_f32 v[254:255], v[166:167], v[166:167], v[254:255]
	v_pk_fma_f32 v[252:253], v[168:169], v[168:169], v[252:253]
	v_pk_fma_f32 v[254:255], v[170:171], v[170:171], v[254:255]
	v_pk_fma_f32 v[252:253], v[172:173], v[172:173], v[252:253]
	v_pk_fma_f32 v[254:255], v[174:175], v[174:175], v[254:255]
	v_pk_add_f32 v[252:253], v[252:253], v[254:255]
	s_nop 0
	v_add_f32_e32 v183, v252, v253
	s_nop 1
	v_add_f32_dpp v183, v183, v183 quad_perm:[1,0,3,2] row_mask:0xf bank_mask:0xf bound_ctrl:1
	s_nop 1
	v_add_f32_dpp v183, v183, v183 quad_perm:[2,3,0,1] row_mask:0xf bank_mask:0xf bound_ctrl:1
	s_nop 1
	v_add_f32_dpp v183, v183, v183 row_half_mirror row_mask:0xf bank_mask:0xf bound_ctrl:1
	s_nop 1
	v_add_f32_dpp v183, v183, v183 row_mirror row_mask:0xf bank_mask:0xf bound_ctrl:1
	s_nop 1
	v_readlane_b32 s98, v183, 0
	v_readlane_b32 s99, v183, 16
	v_readlane_b32 s100, v183, 32
	v_readlane_b32 s101, v183, 48
	s_nop 1
	v_mov_b32_e32 v183, s98
	v_add_f32_e32 v183, s99, v183
	v_add_f32_e32 v183, s100, v183
	v_add_f32_e32 v183, s101, v183
	v_fmamk_f32 v183, v183, 0x3a800000, v182
	v_cmp_gt_f32_e32 vcc, 0x800000, v183
	v_mul_f32_e32 v181, 0x4b800000, v183
	s_nop 1
	v_cndmask_b32_e32 v183, v183, v181, vcc
	v_rsq_f32_e32 v183, v183
	s_nop 0
	v_mul_f32_e32 v181, 0x45800000, v183
	v_cndmask_b32_e32 v184, v183, v181, vcc
	v_mov_b32_e32 v185, v184
	v_pk_mul_f32 v[160:161], v[160:161], v[184:185]
	v_pk_mul_f32 v[162:163], v[162:163], v[184:185]
	v_pk_mul_f32 v[164:165], v[164:165], v[184:185]
	v_pk_mul_f32 v[166:167], v[166:167], v[184:185]
	v_pk_mul_f32 v[168:169], v[168:169], v[184:185]
	v_pk_mul_f32 v[170:171], v[170:171], v[184:185]
	v_pk_mul_f32 v[172:173], v[172:173], v[184:185]
	v_pk_mul_f32 v[174:175], v[174:175], v[184:185]
	v_pk_fma_f32 v[144:145], v[160:161], v[128:129], v[144:145]
	v_pk_fma_f32 v[146:147], v[162:163], v[130:131], v[146:147]
	v_pk_fma_f32 v[148:149], v[164:165], v[132:133], v[148:149]
	v_pk_fma_f32 v[150:151], v[166:167], v[134:135], v[150:151]
	v_pk_fma_f32 v[152:153], v[168:169], v[136:137], v[152:153]
	v_pk_fma_f32 v[154:155], v[170:171], v[138:139], v[154:155]
	v_pk_fma_f32 v[156:157], v[172:173], v[140:141], v[156:157]
	v_pk_fma_f32 v[158:159], v[174:175], v[142:143], v[158:159]
	v_pk_mul_f32 v[252:253], v[144:145], v[144:145]
	v_pk_mul_f32 v[254:255], v[146:147], v[146:147]
	v_pk_fma_f32 v[252:253], v[148:149], v[148:149], v[252:253]
	v_pk_fma_f32 v[254:255], v[150:151], v[150:151], v[254:255]
	v_pk_fma_f32 v[252:253], v[152:153], v[152:153], v[252:253]
	v_pk_fma_f32 v[254:255], v[154:155], v[154:155], v[254:255]
	v_pk_fma_f32 v[252:253], v[156:157], v[156:157], v[252:253]
	v_pk_fma_f32 v[254:255], v[158:159], v[158:159], v[254:255]
	v_pk_add_f32 v[252:253], v[252:253], v[254:255]
	s_nop 0
	v_add_f32_e32 v183, v252, v253
	s_nop 1
	v_add_f32_dpp v183, v183, v183 quad_perm:[1,0,3,2] row_mask:0xf bank_mask:0xf bound_ctrl:1
	s_nop 1
	v_add_f32_dpp v183, v183, v183 quad_perm:[2,3,0,1] row_mask:0xf bank_mask:0xf bound_ctrl:1
	s_nop 1
	v_add_f32_dpp v183, v183, v183 row_half_mirror row_mask:0xf bank_mask:0xf bound_ctrl:1
	s_nop 1
	v_add_f32_dpp v183, v183, v183 row_mirror row_mask:0xf bank_mask:0xf bound_ctrl:1
	s_nop 1
	v_readlane_b32 s98, v183, 0
	v_readlane_b32 s99, v183, 16
	v_readlane_b32 s100, v183, 32
	v_readlane_b32 s101, v183, 48
	s_nop 1
	v_mov_b32_e32 v183, s98
	v_add_f32_e32 v183, s99, v183
	v_add_f32_e32 v183, s100, v183
	v_add_f32_e32 v183, s101, v183
	v_fmamk_f32 v183, v183, 0x3a800000, v182
	v_cmp_gt_f32_e32 vcc, 0x800000, v183
	v_mul_f32_e32 v181, 0x4b800000, v183
	s_nop 1
	v_cndmask_b32_e32 v183, v183, v181, vcc
	v_rsq_f32_e32 v183, v183
	s_nop 0
	v_mul_f32_e32 v181, 0x45800000, v183
	v_cndmask_b32_e32 v184, v183, v181, vcc
	v_mov_b32_e32 v185, v184
	v_cvt_pk_bf16_f32 v80, v144, v145
	v_cvt_pk_bf16_f32 v81, v146, v147
	v_cvt_pk_bf16_f32 v82, v148, v149
	v_cvt_pk_bf16_f32 v83, v150, v151
	v_cvt_pk_bf16_f32 v84, v152, v153
	v_cvt_pk_bf16_f32 v85, v154, v155
	v_cvt_pk_bf16_f32 v86, v156, v157
	v_cvt_pk_bf16_f32 v87, v158, v159
	v_add_u32_e32 v181, 0x2c00000, v177
	global_store_dwordx4 v181, v[80:83], s[78:79]
	global_store_dwordx4 v181, v[84:87], s[78:79] offset:1024
	v_add_u32_e32 v236, 0xa000, v237
	s_mov_b64 exec, 1
	global_store_dword v236, v184, s[78:79]
	s_mov_b64 exec, -1
	s_waitcnt vmcnt(4)
	v_lshlrev_b32_e32 v144, 16, v96
	v_and_b32_e32 v145, 0xffff0000, v96
	v_lshlrev_b32_e32 v146, 16, v97
	v_and_b32_e32 v147, 0xffff0000, v97
	v_lshlrev_b32_e32 v148, 16, v98
	v_and_b32_e32 v149, 0xffff0000, v98
	v_lshlrev_b32_e32 v150, 16, v99
	v_and_b32_e32 v151, 0xffff0000, v99
	v_lshlrev_b32_e32 v152, 16, v100
	v_and_b32_e32 v153, 0xffff0000, v100
	v_lshlrev_b32_e32 v154, 16, v101
	v_and_b32_e32 v155, 0xffff0000, v101
	v_lshlrev_b32_e32 v156, 16, v102
	v_and_b32_e32 v157, 0xffff0000, v102
	v_lshlrev_b32_e32 v158, 16, v103
	v_and_b32_e32 v159, 0xffff0000, v103
	v_lshlrev_b32_e32 v160, 16, v104
	v_and_b32_e32 v161, 0xffff0000, v104
	v_lshlrev_b32_e32 v162, 16, v105
	v_and_b32_e32 v163, 0xffff0000, v105
	v_lshlrev_b32_e32 v164, 16, v106
	v_and_b32_e32 v165, 0xffff0000, v106
	v_lshlrev_b32_e32 v166, 16, v107
	v_and_b32_e32 v167, 0xffff0000, v107
	v_lshlrev_b32_e32 v168, 16, v108
	v_and_b32_e32 v169, 0xffff0000, v108
	v_lshlrev_b32_e32 v170, 16, v109
	v_and_b32_e32 v171, 0xffff0000, v109
	v_lshlrev_b32_e32 v172, 16, v110
	v_and_b32_e32 v173, 0xffff0000, v110
	v_lshlrev_b32_e32 v174, 16, v111
	v_and_b32_e32 v175, 0xffff0000, v111
	v_pk_mul_f32 v[252:253], v[160:161], v[160:161]
	v_pk_mul_f32 v[254:255], v[162:163], v[162:163]
	v_pk_fma_f32 v[252:253], v[164:165], v[164:165], v[252:253]
	v_pk_fma_f32 v[254:255], v[166:167], v[166:167], v[254:255]
	v_pk_fma_f32 v[252:253], v[168:169], v[168:169], v[252:253]
	v_pk_fma_f32 v[254:255], v[170:171], v[170:171], v[254:255]
	v_pk_fma_f32 v[252:253], v[172:173], v[172:173], v[252:253]
	v_pk_fma_f32 v[254:255], v[174:175], v[174:175], v[254:255]
	v_pk_add_f32 v[252:253], v[252:253], v[254:255]
	s_nop 0
	v_add_f32_e32 v183, v252, v253
	s_nop 1
	v_add_f32_dpp v183, v183, v183 quad_perm:[1,0,3,2] row_mask:0xf bank_mask:0xf bound_ctrl:1
	s_nop 1
	v_add_f32_dpp v183, v183, v183 quad_perm:[2,3,0,1] row_mask:0xf bank_mask:0xf bound_ctrl:1
	s_nop 1
	v_add_f32_dpp v183, v183, v183 row_half_mirror row_mask:0xf bank_mask:0xf bound_ctrl:1
	s_nop 1
	v_add_f32_dpp v183, v183, v183 row_mirror row_mask:0xf bank_mask:0xf bound_ctrl:1
	s_nop 1
	v_readlane_b32 s98, v183, 0
	v_readlane_b32 s99, v183, 16
	v_readlane_b32 s100, v183, 32
	v_readlane_b32 s101, v183, 48
	s_nop 1
	v_mov_b32_e32 v183, s98
	v_add_f32_e32 v183, s99, v183
	v_add_f32_e32 v183, s100, v183
	v_add_f32_e32 v183, s101, v183
	v_fmamk_f32 v183, v183, 0x3a800000, v182
	v_cmp_gt_f32_e32 vcc, 0x800000, v183
	v_mul_f32_e32 v181, 0x4b800000, v183
	s_nop 1
	v_cndmask_b32_e32 v183, v183, v181, vcc
	v_rsq_f32_e32 v183, v183
	s_nop 0
	v_mul_f32_e32 v181, 0x45800000, v183
	v_cndmask_b32_e32 v184, v183, v181, vcc
	v_mov_b32_e32 v185, v184
	v_pk_mul_f32 v[160:161], v[160:161], v[184:185]
	v_pk_mul_f32 v[162:163], v[162:163], v[184:185]
	v_pk_mul_f32 v[164:165], v[164:165], v[184:185]
	v_pk_mul_f32 v[166:167], v[166:167], v[184:185]
	v_pk_mul_f32 v[168:169], v[168:169], v[184:185]
	v_pk_mul_f32 v[170:171], v[170:171], v[184:185]
	v_pk_mul_f32 v[172:173], v[172:173], v[184:185]
	v_pk_mul_f32 v[174:175], v[174:175], v[184:185]
	v_pk_fma_f32 v[144:145], v[160:161], v[128:129], v[144:145]
	v_pk_fma_f32 v[146:147], v[162:163], v[130:131], v[146:147]
	v_pk_fma_f32 v[148:149], v[164:165], v[132:133], v[148:149]
	v_pk_fma_f32 v[150:151], v[166:167], v[134:135], v[150:151]
	v_pk_fma_f32 v[152:153], v[168:169], v[136:137], v[152:153]
	v_pk_fma_f32 v[154:155], v[170:171], v[138:139], v[154:155]
	v_pk_fma_f32 v[156:157], v[172:173], v[140:141], v[156:157]
	v_pk_fma_f32 v[158:159], v[174:175], v[142:143], v[158:159]
	v_pk_mul_f32 v[252:253], v[144:145], v[144:145]
	v_pk_mul_f32 v[254:255], v[146:147], v[146:147]
	v_pk_fma_f32 v[252:253], v[148:149], v[148:149], v[252:253]
	v_pk_fma_f32 v[254:255], v[150:151], v[150:151], v[254:255]
	v_pk_fma_f32 v[252:253], v[152:153], v[152:153], v[252:253]
	v_pk_fma_f32 v[254:255], v[154:155], v[154:155], v[254:255]
	v_pk_fma_f32 v[252:253], v[156:157], v[156:157], v[252:253]
	v_pk_fma_f32 v[254:255], v[158:159], v[158:159], v[254:255]
	v_pk_add_f32 v[252:253], v[252:253], v[254:255]
	s_nop 0
	v_add_f32_e32 v183, v252, v253
	s_nop 1
	v_add_f32_dpp v183, v183, v183 quad_perm:[1,0,3,2] row_mask:0xf bank_mask:0xf bound_ctrl:1
	s_nop 1
	v_add_f32_dpp v183, v183, v183 quad_perm:[2,3,0,1] row_mask:0xf bank_mask:0xf bound_ctrl:1
	s_nop 1
	v_add_f32_dpp v183, v183, v183 row_half_mirror row_mask:0xf bank_mask:0xf bound_ctrl:1
	s_nop 1
	v_add_f32_dpp v183, v183, v183 row_mirror row_mask:0xf bank_mask:0xf bound_ctrl:1
	s_nop 1
	v_readlane_b32 s98, v183, 0
	v_readlane_b32 s99, v183, 16
	v_readlane_b32 s100, v183, 32
	v_readlane_b32 s101, v183, 48
	s_nop 1
	v_mov_b32_e32 v183, s98
	v_add_f32_e32 v183, s99, v183
	v_add_f32_e32 v183, s100, v183
	v_add_f32_e32 v183, s101, v183
	v_fmamk_f32 v183, v183, 0x3a800000, v182
	v_cmp_gt_f32_e32 vcc, 0x800000, v183
	v_mul_f32_e32 v181, 0x4b800000, v183
	s_nop 1
	v_cndmask_b32_e32 v183, v183, v181, vcc
	v_rsq_f32_e32 v183, v183
	s_nop 0
	v_mul_f32_e32 v181, 0x45800000, v183
	v_cndmask_b32_e32 v184, v183, v181, vcc
	v_mov_b32_e32 v185, v184
	v_cvt_pk_bf16_f32 v96, v144, v145
	v_cvt_pk_bf16_f32 v97, v146, v147
	v_cvt_pk_bf16_f32 v98, v148, v149
	v_cvt_pk_bf16_f32 v99, v150, v151
	v_cvt_pk_bf16_f32 v100, v152, v153
	v_cvt_pk_bf16_f32 v101, v154, v155
	v_cvt_pk_bf16_f32 v102, v156, v157
	v_cvt_pk_bf16_f32 v103, v158, v159
	v_add_u32_e32 v181, 0x3000000, v177
	global_store_dwordx4 v181, v[96:99], s[78:79]
	global_store_dwordx4 v181, v[100:103], s[78:79] offset:1024
	v_add_u32_e32 v236, 0xc000, v237
	s_mov_b64 exec, 1
	global_store_dword v236, v184, s[78:79]
	s_mov_b64 exec, -1
	s_waitcnt vmcnt(0)
	v_lshlrev_b32_e32 v144, 16, v112
	v_and_b32_e32 v145, 0xffff0000, v112
	v_lshlrev_b32_e32 v146, 16, v113
	v_and_b32_e32 v147, 0xffff0000, v113
	v_lshlrev_b32_e32 v148, 16, v114
	v_and_b32_e32 v149, 0xffff0000, v114
	v_lshlrev_b32_e32 v150, 16, v115
	v_and_b32_e32 v151, 0xffff0000, v115
	v_lshlrev_b32_e32 v152, 16, v116
	v_and_b32_e32 v153, 0xffff0000, v116
	v_lshlrev_b32_e32 v154, 16, v117
	v_and_b32_e32 v155, 0xffff0000, v117
	v_lshlrev_b32_e32 v156, 16, v118
	v_and_b32_e32 v157, 0xffff0000, v118
	v_lshlrev_b32_e32 v158, 16, v119
	v_and_b32_e32 v159, 0xffff0000, v119
	v_lshlrev_b32_e32 v160, 16, v120
	v_and_b32_e32 v161, 0xffff0000, v120
	v_lshlrev_b32_e32 v162, 16, v121
	v_and_b32_e32 v163, 0xffff0000, v121
	v_lshlrev_b32_e32 v164, 16, v122
	v_and_b32_e32 v165, 0xffff0000, v122
	v_lshlrev_b32_e32 v166, 16, v123
	v_and_b32_e32 v167, 0xffff0000, v123
	v_lshlrev_b32_e32 v168, 16, v124
	v_and_b32_e32 v169, 0xffff0000, v124
	v_lshlrev_b32_e32 v170, 16, v125
	v_and_b32_e32 v171, 0xffff0000, v125
	v_lshlrev_b32_e32 v172, 16, v126
	v_and_b32_e32 v173, 0xffff0000, v126
	v_lshlrev_b32_e32 v174, 16, v127
	v_and_b32_e32 v175, 0xffff0000, v127
	v_pk_mul_f32 v[252:253], v[160:161], v[160:161]
	v_pk_mul_f32 v[254:255], v[162:163], v[162:163]
	v_pk_fma_f32 v[252:253], v[164:165], v[164:165], v[252:253]
	v_pk_fma_f32 v[254:255], v[166:167], v[166:167], v[254:255]
	v_pk_fma_f32 v[252:253], v[168:169], v[168:169], v[252:253]
	v_pk_fma_f32 v[254:255], v[170:171], v[170:171], v[254:255]
	v_pk_fma_f32 v[252:253], v[172:173], v[172:173], v[252:253]
	v_pk_fma_f32 v[254:255], v[174:175], v[174:175], v[254:255]
	v_pk_add_f32 v[252:253], v[252:253], v[254:255]
	s_nop 0
	v_add_f32_e32 v183, v252, v253
	s_nop 1
	v_add_f32_dpp v183, v183, v183 quad_perm:[1,0,3,2] row_mask:0xf bank_mask:0xf bound_ctrl:1
	s_nop 1
	v_add_f32_dpp v183, v183, v183 quad_perm:[2,3,0,1] row_mask:0xf bank_mask:0xf bound_ctrl:1
	s_nop 1
	v_add_f32_dpp v183, v183, v183 row_half_mirror row_mask:0xf bank_mask:0xf bound_ctrl:1
	s_nop 1
	v_add_f32_dpp v183, v183, v183 row_mirror row_mask:0xf bank_mask:0xf bound_ctrl:1
	s_nop 1
	v_readlane_b32 s98, v183, 0
	v_readlane_b32 s99, v183, 16
	v_readlane_b32 s100, v183, 32
	v_readlane_b32 s101, v183, 48
	s_nop 1
	v_mov_b32_e32 v183, s98
	v_add_f32_e32 v183, s99, v183
	v_add_f32_e32 v183, s100, v183
	v_add_f32_e32 v183, s101, v183
	v_fmamk_f32 v183, v183, 0x3a800000, v182
	v_cmp_gt_f32_e32 vcc, 0x800000, v183
	v_mul_f32_e32 v181, 0x4b800000, v183
	s_nop 1
	v_cndmask_b32_e32 v183, v183, v181, vcc
	v_rsq_f32_e32 v183, v183
	s_nop 0
	v_mul_f32_e32 v181, 0x45800000, v183
	v_cndmask_b32_e32 v184, v183, v181, vcc
	v_mov_b32_e32 v185, v184
	v_pk_mul_f32 v[160:161], v[160:161], v[184:185]
	v_pk_mul_f32 v[162:163], v[162:163], v[184:185]
	v_pk_mul_f32 v[164:165], v[164:165], v[184:185]
	v_pk_mul_f32 v[166:167], v[166:167], v[184:185]
	v_pk_mul_f32 v[168:169], v[168:169], v[184:185]
	v_pk_mul_f32 v[170:171], v[170:171], v[184:185]
	v_pk_mul_f32 v[172:173], v[172:173], v[184:185]
	v_pk_mul_f32 v[174:175], v[174:175], v[184:185]
	v_pk_fma_f32 v[144:145], v[160:161], v[128:129], v[144:145]
	v_pk_fma_f32 v[146:147], v[162:163], v[130:131], v[146:147]
	v_pk_fma_f32 v[148:149], v[164:165], v[132:133], v[148:149]
	v_pk_fma_f32 v[150:151], v[166:167], v[134:135], v[150:151]
	v_pk_fma_f32 v[152:153], v[168:169], v[136:137], v[152:153]
	v_pk_fma_f32 v[154:155], v[170:171], v[138:139], v[154:155]
	v_pk_fma_f32 v[156:157], v[172:173], v[140:141], v[156:157]
	v_pk_fma_f32 v[158:159], v[174:175], v[142:143], v[158:159]
	v_pk_mul_f32 v[252:253], v[144:145], v[144:145]
	v_pk_mul_f32 v[254:255], v[146:147], v[146:147]
	v_pk_fma_f32 v[252:253], v[148:149], v[148:149], v[252:253]
	v_pk_fma_f32 v[254:255], v[150:151], v[150:151], v[254:255]
	v_pk_fma_f32 v[252:253], v[152:153], v[152:153], v[252:253]
	v_pk_fma_f32 v[254:255], v[154:155], v[154:155], v[254:255]
	v_pk_fma_f32 v[252:253], v[156:157], v[156:157], v[252:253]
	v_pk_fma_f32 v[254:255], v[158:159], v[158:159], v[254:255]
	v_pk_add_f32 v[252:253], v[252:253], v[254:255]
	s_nop 0
	v_add_f32_e32 v183, v252, v253
	s_nop 1
	v_add_f32_dpp v183, v183, v183 quad_perm:[1,0,3,2] row_mask:0xf bank_mask:0xf bound_ctrl:1
	s_nop 1
	v_add_f32_dpp v183, v183, v183 quad_perm:[2,3,0,1] row_mask:0xf bank_mask:0xf bound_ctrl:1
	s_nop 1
	v_add_f32_dpp v183, v183, v183 row_half_mirror row_mask:0xf bank_mask:0xf bound_ctrl:1
	s_nop 1
	v_add_f32_dpp v183, v183, v183 row_mirror row_mask:0xf bank_mask:0xf bound_ctrl:1
	s_nop 1
	v_readlane_b32 s98, v183, 0
	v_readlane_b32 s99, v183, 16
	v_readlane_b32 s100, v183, 32
	v_readlane_b32 s101, v183, 48
	s_nop 1
	v_mov_b32_e32 v183, s98
	v_add_f32_e32 v183, s99, v183
	v_add_f32_e32 v183, s100, v183
	v_add_f32_e32 v183, s101, v183
	v_fmamk_f32 v183, v183, 0x3a800000, v182
	v_cmp_gt_f32_e32 vcc, 0x800000, v183
	v_mul_f32_e32 v181, 0x4b800000, v183
	s_nop 1
	v_cndmask_b32_e32 v183, v183, v181, vcc
	v_rsq_f32_e32 v183, v183
	s_nop 0
	v_mul_f32_e32 v181, 0x45800000, v183
	v_cndmask_b32_e32 v184, v183, v181, vcc
	v_mov_b32_e32 v185, v184
	v_cvt_pk_bf16_f32 v112, v144, v145
	v_cvt_pk_bf16_f32 v113, v146, v147
	v_cvt_pk_bf16_f32 v114, v148, v149
	v_cvt_pk_bf16_f32 v115, v150, v151
	v_cvt_pk_bf16_f32 v116, v152, v153
	v_cvt_pk_bf16_f32 v117, v154, v155
	v_cvt_pk_bf16_f32 v118, v156, v157
	v_cvt_pk_bf16_f32 v119, v158, v159
	v_add_u32_e32 v181, 0x3400000, v177
	global_store_dwordx4 v181, v[112:115], s[78:79]
	global_store_dwordx4 v181, v[116:119], s[78:79] offset:1024
	v_add_u32_e32 v236, 0xe000, v237
	s_mov_b64 exec, 1
	global_store_dword v236, v184, s[78:79]
	s_mov_b64 exec, -1
	v_readfirstlane_b32 s98, v179
	s_nop 3
	s_and_b32 s99, s98, 3
	s_add_i32 s100, s99, 4
	s_lshl_b32 s100, s100, 11
	s_sub_i32 s100, s100, s99
	s_lshl_b32 s101, s100, 11
	v_add_u32_e32 v177, s101, v177
	s_lshl_b32 s101, s100, 2
	v_add_u32_e32 v237, s101, v237
	v_add_u32_e32 v181, 0x1800000, v177
	global_load_dwordx4 v[0:3], v181, s[78:79]
	global_load_dwordx4 v[4:7], v181, s[78:79] offset:1024
	v_add_u32_e32 v181, 0x9e00000, v177
	global_load_dwordx4 v[8:11], v181, s[78:79]
	global_load_dwordx4 v[12:15], v181, s[78:79] offset:1024
	s_waitcnt vmcnt(0)
	v_lshlrev_b32_e32 v144, 16, v0
	v_and_b32_e32 v145, 0xffff0000, v0
	v_lshlrev_b32_e32 v146, 16, v1
	v_and_b32_e32 v147, 0xffff0000, v1
	v_lshlrev_b32_e32 v148, 16, v2
	v_and_b32_e32 v149, 0xffff0000, v2
	v_lshlrev_b32_e32 v150, 16, v3
	v_and_b32_e32 v151, 0xffff0000, v3
	v_lshlrev_b32_e32 v152, 16, v4
	v_and_b32_e32 v153, 0xffff0000, v4
	v_lshlrev_b32_e32 v154, 16, v5
	v_and_b32_e32 v155, 0xffff0000, v5
	v_lshlrev_b32_e32 v156, 16, v6
	v_and_b32_e32 v157, 0xffff0000, v6
	v_lshlrev_b32_e32 v158, 16, v7
	v_and_b32_e32 v159, 0xffff0000, v7
	v_lshlrev_b32_e32 v160, 16, v8
	v_and_b32_e32 v161, 0xffff0000, v8
	v_lshlrev_b32_e32 v162, 16, v9
	v_and_b32_e32 v163, 0xffff0000, v9
	v_lshlrev_b32_e32 v164, 16, v10
	v_and_b32_e32 v165, 0xffff0000, v10
	v_lshlrev_b32_e32 v166, 16, v11
	v_and_b32_e32 v167, 0xffff0000, v11
	v_lshlrev_b32_e32 v168, 16, v12
	v_and_b32_e32 v169, 0xffff0000, v12
	v_lshlrev_b32_e32 v170, 16, v13
	v_and_b32_e32 v171, 0xffff0000, v13
	v_lshlrev_b32_e32 v172, 16, v14
	v_and_b32_e32 v173, 0xffff0000, v14
	v_lshlrev_b32_e32 v174, 16, v15
	v_and_b32_e32 v175, 0xffff0000, v15
	v_pk_mul_f32 v[252:253], v[160:161], v[160:161]
	v_pk_mul_f32 v[254:255], v[162:163], v[162:163]
	v_pk_fma_f32 v[252:253], v[164:165], v[164:165], v[252:253]
	v_pk_fma_f32 v[254:255], v[166:167], v[166:167], v[254:255]
	v_pk_fma_f32 v[252:253], v[168:169], v[168:169], v[252:253]
	v_pk_fma_f32 v[254:255], v[170:171], v[170:171], v[254:255]
	v_pk_fma_f32 v[252:253], v[172:173], v[172:173], v[252:253]
	v_pk_fma_f32 v[254:255], v[174:175], v[174:175], v[254:255]
	v_pk_add_f32 v[252:253], v[252:253], v[254:255]
	s_nop 0
	v_add_f32_e32 v183, v252, v253
	s_nop 1
	v_add_f32_dpp v183, v183, v183 quad_perm:[1,0,3,2] row_mask:0xf bank_mask:0xf bound_ctrl:1
	s_nop 1
	v_add_f32_dpp v183, v183, v183 quad_perm:[2,3,0,1] row_mask:0xf bank_mask:0xf bound_ctrl:1
	s_nop 1
	v_add_f32_dpp v183, v183, v183 row_half_mirror row_mask:0xf bank_mask:0xf bound_ctrl:1
	s_nop 1
	v_add_f32_dpp v183, v183, v183 row_mirror row_mask:0xf bank_mask:0xf bound_ctrl:1
	s_nop 1
	v_readlane_b32 s98, v183, 0
	v_readlane_b32 s99, v183, 16
	v_readlane_b32 s100, v183, 32
	v_readlane_b32 s101, v183, 48
	s_nop 1
	v_mov_b32_e32 v183, s98
	v_add_f32_e32 v183, s99, v183
	v_add_f32_e32 v183, s100, v183
	v_add_f32_e32 v183, s101, v183
	v_fmamk_f32 v183, v183, 0x3a800000, v182
	v_cmp_gt_f32_e32 vcc, 0x800000, v183
	v_mul_f32_e32 v181, 0x4b800000, v183
	s_nop 1
	v_cndmask_b32_e32 v183, v183, v181, vcc
	v_rsq_f32_e32 v183, v183
	s_nop 0
	v_mul_f32_e32 v181, 0x45800000, v183
	v_cndmask_b32_e32 v184, v183, v181, vcc
	v_mov_b32_e32 v185, v184
	v_pk_mul_f32 v[160:161], v[160:161], v[184:185]
	v_pk_mul_f32 v[162:163], v[162:163], v[184:185]
	v_pk_mul_f32 v[164:165], v[164:165], v[184:185]
	v_pk_mul_f32 v[166:167], v[166:167], v[184:185]
	v_pk_mul_f32 v[168:169], v[168:169], v[184:185]
	v_pk_mul_f32 v[170:171], v[170:171], v[184:185]
	v_pk_mul_f32 v[172:173], v[172:173], v[184:185]
	v_pk_mul_f32 v[174:175], v[174:175], v[184:185]
	v_pk_fma_f32 v[144:145], v[160:161], v[128:129], v[144:145]
	v_pk_fma_f32 v[146:147], v[162:163], v[130:131], v[146:147]
	v_pk_fma_f32 v[148:149], v[164:165], v[132:133], v[148:149]
	v_pk_fma_f32 v[150:151], v[166:167], v[134:135], v[150:151]
	v_pk_fma_f32 v[152:153], v[168:169], v[136:137], v[152:153]
	v_pk_fma_f32 v[154:155], v[170:171], v[138:139], v[154:155]
	v_pk_fma_f32 v[156:157], v[172:173], v[140:141], v[156:157]
	v_pk_fma_f32 v[158:159], v[174:175], v[142:143], v[158:159]
	v_pk_mul_f32 v[252:253], v[144:145], v[144:145]
	v_pk_mul_f32 v[254:255], v[146:147], v[146:147]
	v_pk_fma_f32 v[252:253], v[148:149], v[148:149], v[252:253]
	v_pk_fma_f32 v[254:255], v[150:151], v[150:151], v[254:255]
	v_pk_fma_f32 v[252:253], v[152:153], v[152:153], v[252:253]
	v_pk_fma_f32 v[254:255], v[154:155], v[154:155], v[254:255]
	v_pk_fma_f32 v[252:253], v[156:157], v[156:157], v[252:253]
	v_pk_fma_f32 v[254:255], v[158:159], v[158:159], v[254:255]
	v_pk_add_f32 v[252:253], v[252:253], v[254:255]
	s_nop 0
	v_add_f32_e32 v183, v252, v253
	s_nop 1
	v_add_f32_dpp v183, v183, v183 quad_perm:[1,0,3,2] row_mask:0xf bank_mask:0xf bound_ctrl:1
	s_nop 1
	v_add_f32_dpp v183, v183, v183 quad_perm:[2,3,0,1] row_mask:0xf bank_mask:0xf bound_ctrl:1
	s_nop 1
	v_add_f32_dpp v183, v183, v183 row_half_mirror row_mask:0xf bank_mask:0xf bound_ctrl:1
	s_nop 1
	v_add_f32_dpp v183, v183, v183 row_mirror row_mask:0xf bank_mask:0xf bound_ctrl:1
	s_nop 1
	v_readlane_b32 s98, v183, 0
	v_readlane_b32 s99, v183, 16
	v_readlane_b32 s100, v183, 32
	v_readlane_b32 s101, v183, 48
	s_nop 1
	v_mov_b32_e32 v183, s98
	v_add_f32_e32 v183, s99, v183
	v_add_f32_e32 v183, s100, v183
	v_add_f32_e32 v183, s101, v183
	v_fmamk_f32 v183, v183, 0x3a800000, v182
	v_cmp_gt_f32_e32 vcc, 0x800000, v183
	v_mul_f32_e32 v181, 0x4b800000, v183
	s_nop 1
	v_cndmask_b32_e32 v183, v183, v181, vcc
	v_rsq_f32_e32 v183, v183
	s_nop 0
	v_mul_f32_e32 v181, 0x45800000, v183
	v_cndmask_b32_e32 v184, v183, v181, vcc
	v_mov_b32_e32 v185, v184
	v_cvt_pk_bf16_f32 v0, v144, v145
	v_cvt_pk_bf16_f32 v1, v146, v147
	v_cvt_pk_bf16_f32 v2, v148, v149
	v_cvt_pk_bf16_f32 v3, v150, v151
	v_cvt_pk_bf16_f32 v4, v152, v153
	v_cvt_pk_bf16_f32 v5, v154, v155
	v_cvt_pk_bf16_f32 v6, v156, v157
	v_cvt_pk_bf16_f32 v7, v158, v159
	v_add_u32_e32 v181, 0x1800000, v177
	global_store_dwordx4 v181, v[0:3], s[78:79]
	global_store_dwordx4 v181, v[4:7], s[78:79] offset:1024
	v_add_u32_e32 v236, 0x0, v237
	s_mov_b64 exec, 1
	global_store_dword v236, v184, s[78:79]
	s_mov_b64 exec, -1
	s_branch .Lmyxupd_done_3

.LBB0_1589:
	s_or_b64 exec, exec, s[8:9]
	v_cvt_f32_u32_e32 v4, v2
	s_waitcnt vmcnt(0)
	v_readfirstlane_b32 s6, v3
	v_sub_u32_e32 v3, 0, v2
	v_rcp_iflag_f32_e32 v4, v4
	v_add_u32_e32 v5, s6, v1
	v_mul_f32_e32 v4, 0x4f7ffffe, v4
	v_cvt_u32_f32_e32 v4, v4
	v_mul_lo_u32 v1, v3, v4
	v_mul_hi_u32 v1, v4, v1
	v_add_u32_e32 v1, v4, v1
	v_mul_hi_u32 v1, v5, v1
	v_mul_lo_u32 v3, v1, v2
	v_sub_u32_e32 v3, v5, v3
	v_add_u32_e32 v4, 1, v1
	v_cmp_ge_u32_e32 vcc, v3, v2
	s_nop 1
	v_cndmask_b32_e32 v1, v1, v4, vcc
	v_sub_u32_e32 v4, v3, v2
	v_cndmask_b32_e32 v3, v3, v4, vcc
	v_add_u32_e32 v4, 1, v1
	v_cmp_ge_u32_e32 vcc, v3, v2
	v_add_u32_e32 v3, 1, v5
	s_nop 0
	v_cndmask_b32_e32 v1, v1, v4, vcc
	v_mul_lo_u32 v4, v2, v1
	v_add_u32_e32 v2, v4, v2
	v_cmp_ne_u32_e32 vcc, v3, v2
	s_and_saveexec_b64 s[6:7], vcc
	s_xor_b64 s[6:7], exec, s[6:7]
	s_cbranch_execz .LBB0_1603
	s_waitcnt lgkmcnt(0)
	v_mov_b32_e32 v0, 0x3500
	global_load_dword v0, v0, s[78:79] sc1
	s_add_u32 s10, s78, 0x3500
	s_addc_u32 s11, s79, 0
	s_waitcnt vmcnt(0)
	v_cmp_eq_u32_e32 vcc, v0, v1
	s_cmp_lt_u32 s2, 16
	s_cbranch_scc0 ATB2_48733
	v_readfirstlane_b32 s100, v1
	s_mov_b64 vcc, 0
ATB2_48733:
	s_and_saveexec_b64 s[8:9], vcc
	s_cbranch_execz .LBB0_1602
	s_mov_b32 s22, 1
	s_mov_b64 s[12:13], 0
	v_mov_b32_e32 v0, 0
	s_branch .LBB0_1593

.LBB0_1606:
	s_or_b64 exec, exec, s[8:9]
	s_waitcnt vmcnt(0)
	v_readfirstlane_b32 s6, v2
	v_cvt_f32_u32_e32 v2, v0
	v_sub_u32_e32 v3, 0, v0
	v_add_u32_e32 v1, s6, v1
	s_add_u32 s6, s78, 0x3500
	v_rcp_iflag_f32_e32 v2, v2
	s_addc_u32 s7, s79, 0
	s_mov_b64 s[10:11], -1
	v_mul_f32_e32 v2, 0x4f7ffffe, v2
	v_cvt_u32_f32_e32 v2, v2
	v_mul_lo_u32 v3, v3, v2
	v_mul_hi_u32 v3, v2, v3
	v_add_u32_e32 v2, v2, v3
	v_mul_hi_u32 v2, v1, v2
	v_mul_lo_u32 v3, v2, v0
	v_sub_u32_e32 v3, v1, v3
	v_cmp_ge_u32_e32 vcc, v3, v0
	v_add_u32_e32 v4, 1, v2
	v_add_u32_e32 v1, 1, v1
	v_cndmask_b32_e32 v2, v2, v4, vcc
	v_sub_u32_e32 v4, v3, v0
	v_cndmask_b32_e32 v3, v3, v4, vcc
	v_cmp_ge_u32_e32 vcc, v3, v0
	v_add_u32_e32 v3, 1, v2
	s_nop 0
	v_cndmask_b32_e32 v2, v2, v3, vcc
	v_mul_lo_u32 v3, v0, v2
	v_add_u32_e32 v0, v3, v0
	v_cmp_ne_u32_e32 vcc, v1, v0
	v_mov_b64_e32 v[0:1], s[6:7]
	s_and_saveexec_b64 s[8:9], vcc
	s_cbranch_execz .LBB0_1618
	v_mov_b32_e32 v0, 0
	global_load_dword v1, v0, s[6:7] sc1
	s_mov_b64 s[14:15], 0
	s_waitcnt vmcnt(0)
	v_cmp_eq_u32_e32 vcc, v1, v2
	s_cmp_lt_u32 s2, 16
	s_cbranch_scc0 ATB2_48873
	v_readfirstlane_b32 s100, v2
	s_mov_b64 vcc, 0
ATB2_48873:
	s_and_saveexec_b64 s[12:13], vcc
	s_cbranch_execz .LBB0_1617
	s_add_u32 s10, s78, 0x200
	s_addc_u32 s11, s79, 0
	s_mov_b32 s24, 1
	s_branch .LBB0_1610

.LBB0_1863:
	v_readlane_b32 s0, v235, 52
	v_readlane_b32 s1, v235, 53
	s_and_b64 vcc, exec, s[0:1]
	s_waitcnt lgkmcnt(0)
	s_barrier
	v_mbcnt_lo_u32_b32 v0, -1, 0
	v_mbcnt_hi_u32_b32 v0, -1, v0
	s_cbranch_vccnz .LBB0_1883
	v_lshlrev_b32_e32 v2, 3, v0
	v_ashrrev_i32_e32 v3, 31, v2
	v_readlane_b32 s4, v235, 4
	v_lshlrev_b64 v[4:5], 1, v[2:3]
	v_lshlrev_b64 v[2:3], 2, v[2:3]
	v_readlane_b32 s14, v235, 14
	v_readlane_b32 s15, v235, 15
	v_lshl_add_u64 v[62:63], s[90:91], 0, v[2:3]
	v_readlane_b32 s5, v235, 5
	v_readlane_b32 s6, v235, 6
	v_readlane_b32 s7, v235, 7
	v_readlane_b32 s8, v235, 8
	v_readlane_b32 s9, v235, 9
	v_readlane_b32 s10, v235, 10
	v_readlane_b32 s11, v235, 11
	v_readlane_b32 s12, v235, 12
	v_readlane_b32 s13, v235, 13
	v_readlane_b32 s16, v235, 16
	v_readlane_b32 s17, v235, 17
	v_readlane_b32 s18, v235, 18
	v_readlane_b32 s19, v235, 19
	v_lshl_add_u64 v[2:3], s[14:15], 0, v[2:3]
	s_mov_b64 s[0:1], 0x2000
	v_lshl_add_u64 v[60:61], s[86:87], 0, v[4:5]
	v_lshl_add_u64 v[64:65], s[54:55], 0, v[4:5]
	v_lshl_add_u64 v[66:67], v[2:3], 0, s[0:1]
	s_mov_b32 s1, 0
	v_cmp_eq_u32_e64 s[16:17], 0, v0
	s_mov_b64 s[4:5], 0x200000
	s_mov_b64 s[6:7], 0x200800
	s_mov_b64 s[8:9], 0x400000
	s_mov_b64 s[10:11], 0x400800
	s_mov_b64 s[12:13], 0x600000
	s_mov_b64 s[14:15], 0x600800
	s_mov_b64 s[18:19], 0x800000
	s_mov_b32 s48, 0x800000
	s_mov_b64 s[20:21], 0x800800
	s_mov_b64 s[22:23], 0xa00000
	s_mov_b64 s[24:25], 0xa00800
	s_mov_b64 s[26:27], 0xc00000
	s_mov_b64 s[28:29], 0xc00800
	s_mov_b64 s[36:37], 0xe00000
	s_mov_b64 s[38:39], 0xe00800
	v_mov_b32_e32 v104, 0
	v_mov_b32_e32 v105, 0x358637bd
	v_readlane_b32 s42, v235, 61
	v_readlane_b32 s43, v235, 62
	v_mbcnt_lo_u32_b32 v176, -1, 0
	v_mbcnt_hi_u32_b32 v176, -1, v176
	v_readlane_b32 s98, v235, 49
	v_readlane_b32 s99, v235, 20
	v_readlane_b32 s100, v235, 14
	v_readlane_b32 s101, v235, 15
	s_nop 3
	s_lshr_b32 vcc_lo, s98, 3
	s_and_b32 vcc_hi, vcc_lo, 7
	s_lshr_b32 vcc_lo, vcc_lo, 3
	s_lshl_b32 vcc_lo, vcc_lo, 3
	s_add_i32 vcc_lo, vcc_lo, s99
	s_lshl_b32 s98, vcc_hi, 8
	s_add_i32 s98, s98, vcc_lo
	s_mov_b32 s99, s98
	v_mov_b32_e32 v183, s99
	v_lshlrev_b32_e32 v177, 4, v176
	s_lshl_b32 s99, s99, 11
	v_add_u32_e32 v177, s99, v177
	v_add_u32_e32 v178, 0x1800000, v177
	v_add_u32_e32 v179, 0x9e00000, v177
	v_lshlrev_b32_e32 v180, 5, v176
	v_add_u32_e32 v181, 0x2000, v180
	global_load_dwordx4 v[128:131], v181, s[100:101]
	global_load_dwordx4 v[132:135], v181, s[100:101] offset:16
	global_load_dwordx4 v[136:139], v181, s[100:101] offset:2048
	global_load_dwordx4 v[140:143], v181, s[100:101] offset:2064
	v_mov_b32_e32 v182, 0x358637bd
	s_and_b32 vcc_lo, s98, 3
	s_cmp_eq_u32 vcc_lo, 0
	s_cbranch_scc1 .Lmyxupd_heavy_4
	global_load_dwordx4 v[0:3], v178, s[78:79]
	global_load_dwordx4 v[4:7], v178, s[78:79] offset:1024
	global_load_dwordx4 v[8:11], v179, s[78:79]
	global_load_dwordx4 v[12:15], v179, s[78:79] offset:1024
	v_add_u32_e32 v178, 0x400000, v178
	v_add_u32_e32 v179, 0x400000, v179
	global_load_dwordx4 v[16:19], v178, s[78:79]
	global_load_dwordx4 v[20:23], v178, s[78:79] offset:1024
	global_load_dwordx4 v[24:27], v179, s[78:79]
	global_load_dwordx4 v[28:31], v179, s[78:79] offset:1024
	v_add_u32_e32 v178, 0x400000, v178
	v_add_u32_e32 v179, 0x400000, v179
	global_load_dwordx4 v[32:35], v178, s[78:79]
	global_load_dwordx4 v[36:39], v178, s[78:79] offset:1024
	global_load_dwordx4 v[40:43], v179, s[78:79]
	global_load_dwordx4 v[44:47], v179, s[78:79] offset:1024
	v_add_u32_e32 v178, 0x400000, v178
	v_add_u32_e32 v179, 0x400000, v179
	global_load_dwordx4 v[48:51], v178, s[78:79]
	global_load_dwordx4 v[52:55], v178, s[78:79] offset:1024
	global_load_dwordx4 v[56:59], v179, s[78:79]
	global_load_dwordx4 v[60:63], v179, s[78:79] offset:1024
	v_add_u32_e32 v178, 0x400000, v178
	v_add_u32_e32 v179, 0x400000, v179
	global_load_dwordx4 v[64:67], v178, s[78:79]
	global_load_dwordx4 v[68:71], v178, s[78:79] offset:1024
	global_load_dwordx4 v[72:75], v179, s[78:79]
	global_load_dwordx4 v[76:79], v179, s[78:79] offset:1024
	v_add_u32_e32 v178, 0x400000, v178
	v_add_u32_e32 v179, 0x400000, v179
	global_load_dwordx4 v[80:83], v178, s[78:79]
	global_load_dwordx4 v[84:87], v178, s[78:79] offset:1024
	global_load_dwordx4 v[88:91], v179, s[78:79]
	global_load_dwordx4 v[92:95], v179, s[78:79] offset:1024
	v_add_u32_e32 v178, 0x400000, v178
	v_add_u32_e32 v179, 0x400000, v179
	global_load_dwordx4 v[96:99], v178, s[78:79]
	global_load_dwordx4 v[100:103], v178, s[78:79] offset:1024
	global_load_dwordx4 v[104:107], v179, s[78:79]
	global_load_dwordx4 v[108:111], v179, s[78:79] offset:1024
	v_add_u32_e32 v178, 0x400000, v178
	v_add_u32_e32 v179, 0x400000, v179
	global_load_dwordx4 v[112:115], v178, s[78:79]
	global_load_dwordx4 v[116:119], v178, s[78:79] offset:1024
	global_load_dwordx4 v[120:123], v179, s[78:79]
	global_load_dwordx4 v[124:127], v179, s[78:79] offset:1024
	v_lshlrev_b32_e32 v237, 2, v183
	v_add_u32_e32 v237, 0x10000, v237
	v_mov_b32_e32 v179, s98
	s_waitcnt vmcnt(28)
	v_lshlrev_b32_e32 v144, 16, v0
	v_and_b32_e32 v145, 0xffff0000, v0
	v_lshlrev_b32_e32 v146, 16, v1
	v_and_b32_e32 v147, 0xffff0000, v1
	v_lshlrev_b32_e32 v148, 16, v2
	v_and_b32_e32 v149, 0xffff0000, v2
	v_lshlrev_b32_e32 v150, 16, v3
	v_and_b32_e32 v151, 0xffff0000, v3
	v_lshlrev_b32_e32 v152, 16, v4
	v_and_b32_e32 v153, 0xffff0000, v4
	v_lshlrev_b32_e32 v154, 16, v5
	v_and_b32_e32 v155, 0xffff0000, v5
	v_lshlrev_b32_e32 v156, 16, v6
	v_and_b32_e32 v157, 0xffff0000, v6
	v_lshlrev_b32_e32 v158, 16, v7
	v_and_b32_e32 v159, 0xffff0000, v7
	v_lshlrev_b32_e32 v160, 16, v8
	v_and_b32_e32 v161, 0xffff0000, v8
	v_lshlrev_b32_e32 v162, 16, v9
	v_and_b32_e32 v163, 0xffff0000, v9
	v_lshlrev_b32_e32 v164, 16, v10
	v_and_b32_e32 v165, 0xffff0000, v10
	v_lshlrev_b32_e32 v166, 16, v11
	v_and_b32_e32 v167, 0xffff0000, v11
	v_lshlrev_b32_e32 v168, 16, v12
	v_and_b32_e32 v169, 0xffff0000, v12
	v_lshlrev_b32_e32 v170, 16, v13
	v_and_b32_e32 v171, 0xffff0000, v13
	v_lshlrev_b32_e32 v172, 16, v14
	v_and_b32_e32 v173, 0xffff0000, v14
	v_lshlrev_b32_e32 v174, 16, v15
	v_and_b32_e32 v175, 0xffff0000, v15
	v_pk_mul_f32 v[252:253], v[160:161], v[160:161]
	v_pk_mul_f32 v[254:255], v[162:163], v[162:163]
	v_pk_fma_f32 v[252:253], v[164:165], v[164:165], v[252:253]
	v_pk_fma_f32 v[254:255], v[166:167], v[166:167], v[254:255]
	v_pk_fma_f32 v[252:253], v[168:169], v[168:169], v[252:253]
	v_pk_fma_f32 v[254:255], v[170:171], v[170:171], v[254:255]
	v_pk_fma_f32 v[252:253], v[172:173], v[172:173], v[252:253]
	v_pk_fma_f32 v[254:255], v[174:175], v[174:175], v[254:255]
	v_pk_add_f32 v[252:253], v[252:253], v[254:255]
	s_nop 0
	v_add_f32_e32 v183, v252, v253
	s_nop 1
	v_add_f32_dpp v183, v183, v183 quad_perm:[1,0,3,2] row_mask:0xf bank_mask:0xf bound_ctrl:1
	s_nop 1
	v_add_f32_dpp v183, v183, v183 quad_perm:[2,3,0,1] row_mask:0xf bank_mask:0xf bound_ctrl:1
	s_nop 1
	v_add_f32_dpp v183, v183, v183 row_half_mirror row_mask:0xf bank_mask:0xf bound_ctrl:1
	s_nop 1
	v_add_f32_dpp v183, v183, v183 row_mirror row_mask:0xf bank_mask:0xf bound_ctrl:1
	s_nop 1
	v_readlane_b32 s98, v183, 0
	v_readlane_b32 s99, v183, 16
	v_readlane_b32 s100, v183, 32
	v_readlane_b32 s101, v183, 48
	s_nop 1
	v_mov_b32_e32 v183, s98
	v_add_f32_e32 v183, s99, v183
	v_add_f32_e32 v183, s100, v183
	v_add_f32_e32 v183, s101, v183
	v_fmamk_f32 v183, v183, 0x3a800000, v182
	v_cmp_gt_f32_e32 vcc, 0x800000, v183
	v_mul_f32_e32 v181, 0x4b800000, v183
	s_nop 1
	v_cndmask_b32_e32 v183, v183, v181, vcc
	v_rsq_f32_e32 v183, v183
	s_nop 0
	v_mul_f32_e32 v181, 0x45800000, v183
	v_cndmask_b32_e32 v184, v183, v181, vcc
	v_mov_b32_e32 v185, v184
	v_pk_mul_f32 v[160:161], v[160:161], v[184:185]
	v_pk_mul_f32 v[162:163], v[162:163], v[184:185]
	v_pk_mul_f32 v[164:165], v[164:165], v[184:185]
	v_pk_mul_f32 v[166:167], v[166:167], v[184:185]
	v_pk_mul_f32 v[168:169], v[168:169], v[184:185]
	v_pk_mul_f32 v[170:171], v[170:171], v[184:185]
	v_pk_mul_f32 v[172:173], v[172:173], v[184:185]
	v_pk_mul_f32 v[174:175], v[174:175], v[184:185]
	v_pk_fma_f32 v[144:145], v[160:161], v[128:129], v[144:145]
	v_pk_fma_f32 v[146:147], v[162:163], v[130:131], v[146:147]
	v_pk_fma_f32 v[148:149], v[164:165], v[132:133], v[148:149]
	v_pk_fma_f32 v[150:151], v[166:167], v[134:135], v[150:151]
	v_pk_fma_f32 v[152:153], v[168:169], v[136:137], v[152:153]
	v_pk_fma_f32 v[154:155], v[170:171], v[138:139], v[154:155]
	v_pk_fma_f32 v[156:157], v[172:173], v[140:141], v[156:157]
	v_pk_fma_f32 v[158:159], v[174:175], v[142:143], v[158:159]
	v_pk_mul_f32 v[252:253], v[144:145], v[144:145]
	v_pk_mul_f32 v[254:255], v[146:147], v[146:147]
	v_pk_fma_f32 v[252:253], v[148:149], v[148:149], v[252:253]
	v_pk_fma_f32 v[254:255], v[150:151], v[150:151], v[254:255]
	v_pk_fma_f32 v[252:253], v[152:153], v[152:153], v[252:253]
	v_pk_fma_f32 v[254:255], v[154:155], v[154:155], v[254:255]
	v_pk_fma_f32 v[252:253], v[156:157], v[156:157], v[252:253]
	v_pk_fma_f32 v[254:255], v[158:159], v[158:159], v[254:255]
	v_pk_add_f32 v[252:253], v[252:253], v[254:255]
	s_nop 0
	v_add_f32_e32 v183, v252, v253
	s_nop 1
	v_add_f32_dpp v183, v183, v183 quad_perm:[1,0,3,2] row_mask:0xf bank_mask:0xf bound_ctrl:1
	s_nop 1
	v_add_f32_dpp v183, v183, v183 quad_perm:[2,3,0,1] row_mask:0xf bank_mask:0xf bound_ctrl:1
	s_nop 1
	v_add_f32_dpp v183, v183, v183 row_half_mirror row_mask:0xf bank_mask:0xf bound_ctrl:1
	s_nop 1
	v_add_f32_dpp v183, v183, v183 row_mirror row_mask:0xf bank_mask:0xf bound_ctrl:1
	s_nop 1
	v_readlane_b32 s98, v183, 0
	v_readlane_b32 s99, v183, 16
	v_readlane_b32 s100, v183, 32
	v_readlane_b32 s101, v183, 48
	s_nop 1
	v_mov_b32_e32 v183, s98
	v_add_f32_e32 v183, s99, v183
	v_add_f32_e32 v183, s100, v183
	v_add_f32_e32 v183, s101, v183
	v_fmamk_f32 v183, v183, 0x3a800000, v182
	v_cmp_gt_f32_e32 vcc, 0x800000, v183
	v_mul_f32_e32 v181, 0x4b800000, v183
	s_nop 1
	v_cndmask_b32_e32 v183, v183, v181, vcc
	v_rsq_f32_e32 v183, v183
	s_nop 0
	v_mul_f32_e32 v181, 0x45800000, v183
	v_cndmask_b32_e32 v184, v183, v181, vcc
	v_mov_b32_e32 v185, v184
	v_cvt_pk_bf16_f32 v0, v144, v145
	v_cvt_pk_bf16_f32 v1, v146, v147
	v_cvt_pk_bf16_f32 v2, v148, v149
	v_cvt_pk_bf16_f32 v3, v150, v151
	v_cvt_pk_bf16_f32 v4, v152, v153
	v_cvt_pk_bf16_f32 v5, v154, v155
	v_cvt_pk_bf16_f32 v6, v156, v157
	v_cvt_pk_bf16_f32 v7, v158, v159
	v_add_u32_e32 v181, 0x1800000, v177
	global_store_dwordx4 v181, v[0:3], s[78:79]
	global_store_dwordx4 v181, v[4:7], s[78:79] offset:1024
	v_add_u32_e32 v236, 0x0, v237
	s_mov_b64 exec, 1
	global_store_dword v236, v184, s[78:79]
	s_mov_b64 exec, -1
	s_waitcnt vmcnt(24)
	v_lshlrev_b32_e32 v144, 16, v16
	v_and_b32_e32 v145, 0xffff0000, v16
	v_lshlrev_b32_e32 v146, 16, v17
	v_and_b32_e32 v147, 0xffff0000, v17
	v_lshlrev_b32_e32 v148, 16, v18
	v_and_b32_e32 v149, 0xffff0000, v18
	v_lshlrev_b32_e32 v150, 16, v19
	v_and_b32_e32 v151, 0xffff0000, v19
	v_lshlrev_b32_e32 v152, 16, v20
	v_and_b32_e32 v153, 0xffff0000, v20
	v_lshlrev_b32_e32 v154, 16, v21
	v_and_b32_e32 v155, 0xffff0000, v21
	v_lshlrev_b32_e32 v156, 16, v22
	v_and_b32_e32 v157, 0xffff0000, v22
	v_lshlrev_b32_e32 v158, 16, v23
	v_and_b32_e32 v159, 0xffff0000, v23
	v_lshlrev_b32_e32 v160, 16, v24
	v_and_b32_e32 v161, 0xffff0000, v24
	v_lshlrev_b32_e32 v162, 16, v25
	v_and_b32_e32 v163, 0xffff0000, v25
	v_lshlrev_b32_e32 v164, 16, v26
	v_and_b32_e32 v165, 0xffff0000, v26
	v_lshlrev_b32_e32 v166, 16, v27
	v_and_b32_e32 v167, 0xffff0000, v27
	v_lshlrev_b32_e32 v168, 16, v28
	v_and_b32_e32 v169, 0xffff0000, v28
	v_lshlrev_b32_e32 v170, 16, v29
	v_and_b32_e32 v171, 0xffff0000, v29
	v_lshlrev_b32_e32 v172, 16, v30
	v_and_b32_e32 v173, 0xffff0000, v30
	v_lshlrev_b32_e32 v174, 16, v31
	v_and_b32_e32 v175, 0xffff0000, v31
	v_pk_mul_f32 v[252:253], v[160:161], v[160:161]
	v_pk_mul_f32 v[254:255], v[162:163], v[162:163]
	v_pk_fma_f32 v[252:253], v[164:165], v[164:165], v[252:253]
	v_pk_fma_f32 v[254:255], v[166:167], v[166:167], v[254:255]
	v_pk_fma_f32 v[252:253], v[168:169], v[168:169], v[252:253]
	v_pk_fma_f32 v[254:255], v[170:171], v[170:171], v[254:255]
	v_pk_fma_f32 v[252:253], v[172:173], v[172:173], v[252:253]
	v_pk_fma_f32 v[254:255], v[174:175], v[174:175], v[254:255]
	v_pk_add_f32 v[252:253], v[252:253], v[254:255]
	s_nop 0
	v_add_f32_e32 v183, v252, v253
	s_nop 1
	v_add_f32_dpp v183, v183, v183 quad_perm:[1,0,3,2] row_mask:0xf bank_mask:0xf bound_ctrl:1
	s_nop 1
	v_add_f32_dpp v183, v183, v183 quad_perm:[2,3,0,1] row_mask:0xf bank_mask:0xf bound_ctrl:1
	s_nop 1
	v_add_f32_dpp v183, v183, v183 row_half_mirror row_mask:0xf bank_mask:0xf bound_ctrl:1
	s_nop 1
	v_add_f32_dpp v183, v183, v183 row_mirror row_mask:0xf bank_mask:0xf bound_ctrl:1
	s_nop 1
	v_readlane_b32 s98, v183, 0
	v_readlane_b32 s99, v183, 16
	v_readlane_b32 s100, v183, 32
	v_readlane_b32 s101, v183, 48
	s_nop 1
	v_mov_b32_e32 v183, s98
	v_add_f32_e32 v183, s99, v183
	v_add_f32_e32 v183, s100, v183
	v_add_f32_e32 v183, s101, v183
	v_fmamk_f32 v183, v183, 0x3a800000, v182
	v_cmp_gt_f32_e32 vcc, 0x800000, v183
	v_mul_f32_e32 v181, 0x4b800000, v183
	s_nop 1
	v_cndmask_b32_e32 v183, v183, v181, vcc
	v_rsq_f32_e32 v183, v183
	s_nop 0
	v_mul_f32_e32 v181, 0x45800000, v183
	v_cndmask_b32_e32 v184, v183, v181, vcc
	v_mov_b32_e32 v185, v184
	v_pk_mul_f32 v[160:161], v[160:161], v[184:185]
	v_pk_mul_f32 v[162:163], v[162:163], v[184:185]
	v_pk_mul_f32 v[164:165], v[164:165], v[184:185]
	v_pk_mul_f32 v[166:167], v[166:167], v[184:185]
	v_pk_mul_f32 v[168:169], v[168:169], v[184:185]
	v_pk_mul_f32 v[170:171], v[170:171], v[184:185]
	v_pk_mul_f32 v[172:173], v[172:173], v[184:185]
	v_pk_mul_f32 v[174:175], v[174:175], v[184:185]
	v_pk_fma_f32 v[144:145], v[160:161], v[128:129], v[144:145]
	v_pk_fma_f32 v[146:147], v[162:163], v[130:131], v[146:147]
	v_pk_fma_f32 v[148:149], v[164:165], v[132:133], v[148:149]
	v_pk_fma_f32 v[150:151], v[166:167], v[134:135], v[150:151]
	v_pk_fma_f32 v[152:153], v[168:169], v[136:137], v[152:153]
	v_pk_fma_f32 v[154:155], v[170:171], v[138:139], v[154:155]
	v_pk_fma_f32 v[156:157], v[172:173], v[140:141], v[156:157]
	v_pk_fma_f32 v[158:159], v[174:175], v[142:143], v[158:159]
	v_pk_mul_f32 v[252:253], v[144:145], v[144:145]
	v_pk_mul_f32 v[254:255], v[146:147], v[146:147]
	v_pk_fma_f32 v[252:253], v[148:149], v[148:149], v[252:253]
	v_pk_fma_f32 v[254:255], v[150:151], v[150:151], v[254:255]
	v_pk_fma_f32 v[252:253], v[152:153], v[152:153], v[252:253]
	v_pk_fma_f32 v[254:255], v[154:155], v[154:155], v[254:255]
	v_pk_fma_f32 v[252:253], v[156:157], v[156:157], v[252:253]
	v_pk_fma_f32 v[254:255], v[158:159], v[158:159], v[254:255]
	v_pk_add_f32 v[252:253], v[252:253], v[254:255]
	s_nop 0
	v_add_f32_e32 v183, v252, v253
	s_nop 1
	v_add_f32_dpp v183, v183, v183 quad_perm:[1,0,3,2] row_mask:0xf bank_mask:0xf bound_ctrl:1
	s_nop 1
	v_add_f32_dpp v183, v183, v183 quad_perm:[2,3,0,1] row_mask:0xf bank_mask:0xf bound_ctrl:1
	s_nop 1
	v_add_f32_dpp v183, v183, v183 row_half_mirror row_mask:0xf bank_mask:0xf bound_ctrl:1
	s_nop 1
	v_add_f32_dpp v183, v183, v183 row_mirror row_mask:0xf bank_mask:0xf bound_ctrl:1
	s_nop 1
	v_readlane_b32 s98, v183, 0
	v_readlane_b32 s99, v183, 16
	v_readlane_b32 s100, v183, 32
	v_readlane_b32 s101, v183, 48
	s_nop 1
	v_mov_b32_e32 v183, s98
	v_add_f32_e32 v183, s99, v183
	v_add_f32_e32 v183, s100, v183
	v_add_f32_e32 v183, s101, v183
	v_fmamk_f32 v183, v183, 0x3a800000, v182
	v_cmp_gt_f32_e32 vcc, 0x800000, v183
	v_mul_f32_e32 v181, 0x4b800000, v183
	s_nop 1
	v_cndmask_b32_e32 v183, v183, v181, vcc
	v_rsq_f32_e32 v183, v183
	s_nop 0
	v_mul_f32_e32 v181, 0x45800000, v183
	v_cndmask_b32_e32 v184, v183, v181, vcc
	v_mov_b32_e32 v185, v184
	v_cvt_pk_bf16_f32 v16, v144, v145
	v_cvt_pk_bf16_f32 v17, v146, v147
	v_cvt_pk_bf16_f32 v18, v148, v149
	v_cvt_pk_bf16_f32 v19, v150, v151
	v_cvt_pk_bf16_f32 v20, v152, v153
	v_cvt_pk_bf16_f32 v21, v154, v155
	v_cvt_pk_bf16_f32 v22, v156, v157
	v_cvt_pk_bf16_f32 v23, v158, v159
	v_add_u32_e32 v181, 0x1c00000, v177
	global_store_dwordx4 v181, v[16:19], s[78:79]
	global_store_dwordx4 v181, v[20:23], s[78:79] offset:1024
	v_add_u32_e32 v236, 0x2000, v237
	s_mov_b64 exec, 1
	global_store_dword v236, v184, s[78:79]
	s_mov_b64 exec, -1
	s_waitcnt vmcnt(20)
	v_lshlrev_b32_e32 v144, 16, v32
	v_and_b32_e32 v145, 0xffff0000, v32
	v_lshlrev_b32_e32 v146, 16, v33
	v_and_b32_e32 v147, 0xffff0000, v33
	v_lshlrev_b32_e32 v148, 16, v34
	v_and_b32_e32 v149, 0xffff0000, v34
	v_lshlrev_b32_e32 v150, 16, v35
	v_and_b32_e32 v151, 0xffff0000, v35
	v_lshlrev_b32_e32 v152, 16, v36
	v_and_b32_e32 v153, 0xffff0000, v36
	v_lshlrev_b32_e32 v154, 16, v37
	v_and_b32_e32 v155, 0xffff0000, v37
	v_lshlrev_b32_e32 v156, 16, v38
	v_and_b32_e32 v157, 0xffff0000, v38
	v_lshlrev_b32_e32 v158, 16, v39
	v_and_b32_e32 v159, 0xffff0000, v39
	v_lshlrev_b32_e32 v160, 16, v40
	v_and_b32_e32 v161, 0xffff0000, v40
	v_lshlrev_b32_e32 v162, 16, v41
	v_and_b32_e32 v163, 0xffff0000, v41
	v_lshlrev_b32_e32 v164, 16, v42
	v_and_b32_e32 v165, 0xffff0000, v42
	v_lshlrev_b32_e32 v166, 16, v43
	v_and_b32_e32 v167, 0xffff0000, v43
	v_lshlrev_b32_e32 v168, 16, v44
	v_and_b32_e32 v169, 0xffff0000, v44
	v_lshlrev_b32_e32 v170, 16, v45
	v_and_b32_e32 v171, 0xffff0000, v45
	v_lshlrev_b32_e32 v172, 16, v46
	v_and_b32_e32 v173, 0xffff0000, v46
	v_lshlrev_b32_e32 v174, 16, v47
	v_and_b32_e32 v175, 0xffff0000, v47
	v_pk_mul_f32 v[252:253], v[160:161], v[160:161]
	v_pk_mul_f32 v[254:255], v[162:163], v[162:163]
	v_pk_fma_f32 v[252:253], v[164:165], v[164:165], v[252:253]
	v_pk_fma_f32 v[254:255], v[166:167], v[166:167], v[254:255]
	v_pk_fma_f32 v[252:253], v[168:169], v[168:169], v[252:253]
	v_pk_fma_f32 v[254:255], v[170:171], v[170:171], v[254:255]
	v_pk_fma_f32 v[252:253], v[172:173], v[172:173], v[252:253]
	v_pk_fma_f32 v[254:255], v[174:175], v[174:175], v[254:255]
	v_pk_add_f32 v[252:253], v[252:253], v[254:255]
	s_nop 0
	v_add_f32_e32 v183, v252, v253
	s_nop 1
	v_add_f32_dpp v183, v183, v183 quad_perm:[1,0,3,2] row_mask:0xf bank_mask:0xf bound_ctrl:1
	s_nop 1
	v_add_f32_dpp v183, v183, v183 quad_perm:[2,3,0,1] row_mask:0xf bank_mask:0xf bound_ctrl:1
	s_nop 1
	v_add_f32_dpp v183, v183, v183 row_half_mirror row_mask:0xf bank_mask:0xf bound_ctrl:1
	s_nop 1
	v_add_f32_dpp v183, v183, v183 row_mirror row_mask:0xf bank_mask:0xf bound_ctrl:1
	s_nop 1
	v_readlane_b32 s98, v183, 0
	v_readlane_b32 s99, v183, 16
	v_readlane_b32 s100, v183, 32
	v_readlane_b32 s101, v183, 48
	s_nop 1
	v_mov_b32_e32 v183, s98
	v_add_f32_e32 v183, s99, v183
	v_add_f32_e32 v183, s100, v183
	v_add_f32_e32 v183, s101, v183
	v_fmamk_f32 v183, v183, 0x3a800000, v182
	v_cmp_gt_f32_e32 vcc, 0x800000, v183
	v_mul_f32_e32 v181, 0x4b800000, v183
	s_nop 1
	v_cndmask_b32_e32 v183, v183, v181, vcc
	v_rsq_f32_e32 v183, v183
	s_nop 0
	v_mul_f32_e32 v181, 0x45800000, v183
	v_cndmask_b32_e32 v184, v183, v181, vcc
	v_mov_b32_e32 v185, v184
	v_pk_mul_f32 v[160:161], v[160:161], v[184:185]
	v_pk_mul_f32 v[162:163], v[162:163], v[184:185]
	v_pk_mul_f32 v[164:165], v[164:165], v[184:185]
	v_pk_mul_f32 v[166:167], v[166:167], v[184:185]
	v_pk_mul_f32 v[168:169], v[168:169], v[184:185]
	v_pk_mul_f32 v[170:171], v[170:171], v[184:185]
	v_pk_mul_f32 v[172:173], v[172:173], v[184:185]
	v_pk_mul_f32 v[174:175], v[174:175], v[184:185]
	v_pk_fma_f32 v[144:145], v[160:161], v[128:129], v[144:145]
	v_pk_fma_f32 v[146:147], v[162:163], v[130:131], v[146:147]
	v_pk_fma_f32 v[148:149], v[164:165], v[132:133], v[148:149]
	v_pk_fma_f32 v[150:151], v[166:167], v[134:135], v[150:151]
	v_pk_fma_f32 v[152:153], v[168:169], v[136:137], v[152:153]
	v_pk_fma_f32 v[154:155], v[170:171], v[138:139], v[154:155]
	v_pk_fma_f32 v[156:157], v[172:173], v[140:141], v[156:157]
	v_pk_fma_f32 v[158:159], v[174:175], v[142:143], v[158:159]
	v_pk_mul_f32 v[252:253], v[144:145], v[144:145]
	v_pk_mul_f32 v[254:255], v[146:147], v[146:147]
	v_pk_fma_f32 v[252:253], v[148:149], v[148:149], v[252:253]
	v_pk_fma_f32 v[254:255], v[150:151], v[150:151], v[254:255]
	v_pk_fma_f32 v[252:253], v[152:153], v[152:153], v[252:253]
	v_pk_fma_f32 v[254:255], v[154:155], v[154:155], v[254:255]
	v_pk_fma_f32 v[252:253], v[156:157], v[156:157], v[252:253]
	v_pk_fma_f32 v[254:255], v[158:159], v[158:159], v[254:255]
	v_pk_add_f32 v[252:253], v[252:253], v[254:255]
	s_nop 0
	v_add_f32_e32 v183, v252, v253
	s_nop 1
	v_add_f32_dpp v183, v183, v183 quad_perm:[1,0,3,2] row_mask:0xf bank_mask:0xf bound_ctrl:1
	s_nop 1
	v_add_f32_dpp v183, v183, v183 quad_perm:[2,3,0,1] row_mask:0xf bank_mask:0xf bound_ctrl:1
	s_nop 1
	v_add_f32_dpp v183, v183, v183 row_half_mirror row_mask:0xf bank_mask:0xf bound_ctrl:1
	s_nop 1
	v_add_f32_dpp v183, v183, v183 row_mirror row_mask:0xf bank_mask:0xf bound_ctrl:1
	s_nop 1
	v_readlane_b32 s98, v183, 0
	v_readlane_b32 s99, v183, 16
	v_readlane_b32 s100, v183, 32
	v_readlane_b32 s101, v183, 48
	s_nop 1
	v_mov_b32_e32 v183, s98
	v_add_f32_e32 v183, s99, v183
	v_add_f32_e32 v183, s100, v183
	v_add_f32_e32 v183, s101, v183
	v_fmamk_f32 v183, v183, 0x3a800000, v182
	v_cmp_gt_f32_e32 vcc, 0x800000, v183
	v_mul_f32_e32 v181, 0x4b800000, v183
	s_nop 1
	v_cndmask_b32_e32 v183, v183, v181, vcc
	v_rsq_f32_e32 v183, v183
	s_nop 0
	v_mul_f32_e32 v181, 0x45800000, v183
	v_cndmask_b32_e32 v184, v183, v181, vcc
	v_mov_b32_e32 v185, v184
	v_cvt_pk_bf16_f32 v32, v144, v145
	v_cvt_pk_bf16_f32 v33, v146, v147
	v_cvt_pk_bf16_f32 v34, v148, v149
	v_cvt_pk_bf16_f32 v35, v150, v151
	v_cvt_pk_bf16_f32 v36, v152, v153
	v_cvt_pk_bf16_f32 v37, v154, v155
	v_cvt_pk_bf16_f32 v38, v156, v157
	v_cvt_pk_bf16_f32 v39, v158, v159
	v_add_u32_e32 v181, 0x2000000, v177
	global_store_dwordx4 v181, v[32:35], s[78:79]
	global_store_dwordx4 v181, v[36:39], s[78:79] offset:1024
	v_add_u32_e32 v236, 0x4000, v237
	s_mov_b64 exec, 1
	global_store_dword v236, v184, s[78:79]
	s_mov_b64 exec, -1
	s_waitcnt vmcnt(16)
	v_lshlrev_b32_e32 v144, 16, v48
	v_and_b32_e32 v145, 0xffff0000, v48
	v_lshlrev_b32_e32 v146, 16, v49
	v_and_b32_e32 v147, 0xffff0000, v49
	v_lshlrev_b32_e32 v148, 16, v50
	v_and_b32_e32 v149, 0xffff0000, v50
	v_lshlrev_b32_e32 v150, 16, v51
	v_and_b32_e32 v151, 0xffff0000, v51
	v_lshlrev_b32_e32 v152, 16, v52
	v_and_b32_e32 v153, 0xffff0000, v52
	v_lshlrev_b32_e32 v154, 16, v53
	v_and_b32_e32 v155, 0xffff0000, v53
	v_lshlrev_b32_e32 v156, 16, v54
	v_and_b32_e32 v157, 0xffff0000, v54
	v_lshlrev_b32_e32 v158, 16, v55
	v_and_b32_e32 v159, 0xffff0000, v55
	v_lshlrev_b32_e32 v160, 16, v56
	v_and_b32_e32 v161, 0xffff0000, v56
	v_lshlrev_b32_e32 v162, 16, v57
	v_and_b32_e32 v163, 0xffff0000, v57
	v_lshlrev_b32_e32 v164, 16, v58
	v_and_b32_e32 v165, 0xffff0000, v58
	v_lshlrev_b32_e32 v166, 16, v59
	v_and_b32_e32 v167, 0xffff0000, v59
	v_lshlrev_b32_e32 v168, 16, v60
	v_and_b32_e32 v169, 0xffff0000, v60
	v_lshlrev_b32_e32 v170, 16, v61
	v_and_b32_e32 v171, 0xffff0000, v61
	v_lshlrev_b32_e32 v172, 16, v62
	v_and_b32_e32 v173, 0xffff0000, v62
	v_lshlrev_b32_e32 v174, 16, v63
	v_and_b32_e32 v175, 0xffff0000, v63
	v_pk_mul_f32 v[252:253], v[160:161], v[160:161]
	v_pk_mul_f32 v[254:255], v[162:163], v[162:163]
	v_pk_fma_f32 v[252:253], v[164:165], v[164:165], v[252:253]
	v_pk_fma_f32 v[254:255], v[166:167], v[166:167], v[254:255]
	v_pk_fma_f32 v[252:253], v[168:169], v[168:169], v[252:253]
	v_pk_fma_f32 v[254:255], v[170:171], v[170:171], v[254:255]
	v_pk_fma_f32 v[252:253], v[172:173], v[172:173], v[252:253]
	v_pk_fma_f32 v[254:255], v[174:175], v[174:175], v[254:255]
	v_pk_add_f32 v[252:253], v[252:253], v[254:255]
	s_nop 0
	v_add_f32_e32 v183, v252, v253
	s_nop 1
	v_add_f32_dpp v183, v183, v183 quad_perm:[1,0,3,2] row_mask:0xf bank_mask:0xf bound_ctrl:1
	s_nop 1
	v_add_f32_dpp v183, v183, v183 quad_perm:[2,3,0,1] row_mask:0xf bank_mask:0xf bound_ctrl:1
	s_nop 1
	v_add_f32_dpp v183, v183, v183 row_half_mirror row_mask:0xf bank_mask:0xf bound_ctrl:1
	s_nop 1
	v_add_f32_dpp v183, v183, v183 row_mirror row_mask:0xf bank_mask:0xf bound_ctrl:1
	s_nop 1
	v_readlane_b32 s98, v183, 0
	v_readlane_b32 s99, v183, 16
	v_readlane_b32 s100, v183, 32
	v_readlane_b32 s101, v183, 48
	s_nop 1
	v_mov_b32_e32 v183, s98
	v_add_f32_e32 v183, s99, v183
	v_add_f32_e32 v183, s100, v183
	v_add_f32_e32 v183, s101, v183
	v_fmamk_f32 v183, v183, 0x3a800000, v182
	v_cmp_gt_f32_e32 vcc, 0x800000, v183
	v_mul_f32_e32 v181, 0x4b800000, v183
	s_nop 1
	v_cndmask_b32_e32 v183, v183, v181, vcc
	v_rsq_f32_e32 v183, v183
	s_nop 0
	v_mul_f32_e32 v181, 0x45800000, v183
	v_cndmask_b32_e32 v184, v183, v181, vcc
	v_mov_b32_e32 v185, v184
	v_pk_mul_f32 v[160:161], v[160:161], v[184:185]
	v_pk_mul_f32 v[162:163], v[162:163], v[184:185]
	v_pk_mul_f32 v[164:165], v[164:165], v[184:185]
	v_pk_mul_f32 v[166:167], v[166:167], v[184:185]
	v_pk_mul_f32 v[168:169], v[168:169], v[184:185]
	v_pk_mul_f32 v[170:171], v[170:171], v[184:185]
	v_pk_mul_f32 v[172:173], v[172:173], v[184:185]
	v_pk_mul_f32 v[174:175], v[174:175], v[184:185]
	v_pk_fma_f32 v[144:145], v[160:161], v[128:129], v[144:145]
	v_pk_fma_f32 v[146:147], v[162:163], v[130:131], v[146:147]
	v_pk_fma_f32 v[148:149], v[164:165], v[132:133], v[148:149]
	v_pk_fma_f32 v[150:151], v[166:167], v[134:135], v[150:151]
	v_pk_fma_f32 v[152:153], v[168:169], v[136:137], v[152:153]
	v_pk_fma_f32 v[154:155], v[170:171], v[138:139], v[154:155]
	v_pk_fma_f32 v[156:157], v[172:173], v[140:141], v[156:157]
	v_pk_fma_f32 v[158:159], v[174:175], v[142:143], v[158:159]
	v_pk_mul_f32 v[252:253], v[144:145], v[144:145]
	v_pk_mul_f32 v[254:255], v[146:147], v[146:147]
	v_pk_fma_f32 v[252:253], v[148:149], v[148:149], v[252:253]
	v_pk_fma_f32 v[254:255], v[150:151], v[150:151], v[254:255]
	v_pk_fma_f32 v[252:253], v[152:153], v[152:153], v[252:253]
	v_pk_fma_f32 v[254:255], v[154:155], v[154:155], v[254:255]
	v_pk_fma_f32 v[252:253], v[156:157], v[156:157], v[252:253]
	v_pk_fma_f32 v[254:255], v[158:159], v[158:159], v[254:255]
	v_pk_add_f32 v[252:253], v[252:253], v[254:255]
	s_nop 0
	v_add_f32_e32 v183, v252, v253
	s_nop 1
	v_add_f32_dpp v183, v183, v183 quad_perm:[1,0,3,2] row_mask:0xf bank_mask:0xf bound_ctrl:1
	s_nop 1
	v_add_f32_dpp v183, v183, v183 quad_perm:[2,3,0,1] row_mask:0xf bank_mask:0xf bound_ctrl:1
	s_nop 1
	v_add_f32_dpp v183, v183, v183 row_half_mirror row_mask:0xf bank_mask:0xf bound_ctrl:1
	s_nop 1
	v_add_f32_dpp v183, v183, v183 row_mirror row_mask:0xf bank_mask:0xf bound_ctrl:1
	s_nop 1
	v_readlane_b32 s98, v183, 0
	v_readlane_b32 s99, v183, 16
	v_readlane_b32 s100, v183, 32
	v_readlane_b32 s101, v183, 48
	s_nop 1
	v_mov_b32_e32 v183, s98
	v_add_f32_e32 v183, s99, v183
	v_add_f32_e32 v183, s100, v183
	v_add_f32_e32 v183, s101, v183
	v_fmamk_f32 v183, v183, 0x3a800000, v182
	v_cmp_gt_f32_e32 vcc, 0x800000, v183
	v_mul_f32_e32 v181, 0x4b800000, v183
	s_nop 1
	v_cndmask_b32_e32 v183, v183, v181, vcc
	v_rsq_f32_e32 v183, v183
	s_nop 0
	v_mul_f32_e32 v181, 0x45800000, v183
	v_cndmask_b32_e32 v184, v183, v181, vcc
	v_mov_b32_e32 v185, v184
	v_cvt_pk_bf16_f32 v48, v144, v145
	v_cvt_pk_bf16_f32 v49, v146, v147
	v_cvt_pk_bf16_f32 v50, v148, v149
	v_cvt_pk_bf16_f32 v51, v150, v151
	v_cvt_pk_bf16_f32 v52, v152, v153
	v_cvt_pk_bf16_f32 v53, v154, v155
	v_cvt_pk_bf16_f32 v54, v156, v157
	v_cvt_pk_bf16_f32 v55, v158, v159
	v_add_u32_e32 v181, 0x2400000, v177
	global_store_dwordx4 v181, v[48:51], s[78:79]
	global_store_dwordx4 v181, v[52:55], s[78:79] offset:1024
	v_add_u32_e32 v236, 0x6000, v237
	s_mov_b64 exec, 1
	global_store_dword v236, v184, s[78:79]
	s_mov_b64 exec, -1
	s_waitcnt vmcnt(12)
	v_lshlrev_b32_e32 v144, 16, v64
	v_and_b32_e32 v145, 0xffff0000, v64
	v_lshlrev_b32_e32 v146, 16, v65
	v_and_b32_e32 v147, 0xffff0000, v65
	v_lshlrev_b32_e32 v148, 16, v66
	v_and_b32_e32 v149, 0xffff0000, v66
	v_lshlrev_b32_e32 v150, 16, v67
	v_and_b32_e32 v151, 0xffff0000, v67
	v_lshlrev_b32_e32 v152, 16, v68
	v_and_b32_e32 v153, 0xffff0000, v68
	v_lshlrev_b32_e32 v154, 16, v69
	v_and_b32_e32 v155, 0xffff0000, v69
	v_lshlrev_b32_e32 v156, 16, v70
	v_and_b32_e32 v157, 0xffff0000, v70
	v_lshlrev_b32_e32 v158, 16, v71
	v_and_b32_e32 v159, 0xffff0000, v71
	v_lshlrev_b32_e32 v160, 16, v72
	v_and_b32_e32 v161, 0xffff0000, v72
	v_lshlrev_b32_e32 v162, 16, v73
	v_and_b32_e32 v163, 0xffff0000, v73
	v_lshlrev_b32_e32 v164, 16, v74
	v_and_b32_e32 v165, 0xffff0000, v74
	v_lshlrev_b32_e32 v166, 16, v75
	v_and_b32_e32 v167, 0xffff0000, v75
	v_lshlrev_b32_e32 v168, 16, v76
	v_and_b32_e32 v169, 0xffff0000, v76
	v_lshlrev_b32_e32 v170, 16, v77
	v_and_b32_e32 v171, 0xffff0000, v77
	v_lshlrev_b32_e32 v172, 16, v78
	v_and_b32_e32 v173, 0xffff0000, v78
	v_lshlrev_b32_e32 v174, 16, v79
	v_and_b32_e32 v175, 0xffff0000, v79
	v_pk_mul_f32 v[252:253], v[160:161], v[160:161]
	v_pk_mul_f32 v[254:255], v[162:163], v[162:163]
	v_pk_fma_f32 v[252:253], v[164:165], v[164:165], v[252:253]
	v_pk_fma_f32 v[254:255], v[166:167], v[166:167], v[254:255]
	v_pk_fma_f32 v[252:253], v[168:169], v[168:169], v[252:253]
	v_pk_fma_f32 v[254:255], v[170:171], v[170:171], v[254:255]
	v_pk_fma_f32 v[252:253], v[172:173], v[172:173], v[252:253]
	v_pk_fma_f32 v[254:255], v[174:175], v[174:175], v[254:255]
	v_pk_add_f32 v[252:253], v[252:253], v[254:255]
	s_nop 0
	v_add_f32_e32 v183, v252, v253
	s_nop 1
	v_add_f32_dpp v183, v183, v183 quad_perm:[1,0,3,2] row_mask:0xf bank_mask:0xf bound_ctrl:1
	s_nop 1
	v_add_f32_dpp v183, v183, v183 quad_perm:[2,3,0,1] row_mask:0xf bank_mask:0xf bound_ctrl:1
	s_nop 1
	v_add_f32_dpp v183, v183, v183 row_half_mirror row_mask:0xf bank_mask:0xf bound_ctrl:1
	s_nop 1
	v_add_f32_dpp v183, v183, v183 row_mirror row_mask:0xf bank_mask:0xf bound_ctrl:1
	s_nop 1
	v_readlane_b32 s98, v183, 0
	v_readlane_b32 s99, v183, 16
	v_readlane_b32 s100, v183, 32
	v_readlane_b32 s101, v183, 48
	s_nop 1
	v_mov_b32_e32 v183, s98
	v_add_f32_e32 v183, s99, v183
	v_add_f32_e32 v183, s100, v183
	v_add_f32_e32 v183, s101, v183
	v_fmamk_f32 v183, v183, 0x3a800000, v182
	v_cmp_gt_f32_e32 vcc, 0x800000, v183
	v_mul_f32_e32 v181, 0x4b800000, v183
	s_nop 1
	v_cndmask_b32_e32 v183, v183, v181, vcc
	v_rsq_f32_e32 v183, v183
	s_nop 0
	v_mul_f32_e32 v181, 0x45800000, v183
	v_cndmask_b32_e32 v184, v183, v181, vcc
	v_mov_b32_e32 v185, v184
	v_pk_mul_f32 v[160:161], v[160:161], v[184:185]
	v_pk_mul_f32 v[162:163], v[162:163], v[184:185]
	v_pk_mul_f32 v[164:165], v[164:165], v[184:185]
	v_pk_mul_f32 v[166:167], v[166:167], v[184:185]
	v_pk_mul_f32 v[168:169], v[168:169], v[184:185]
	v_pk_mul_f32 v[170:171], v[170:171], v[184:185]
	v_pk_mul_f32 v[172:173], v[172:173], v[184:185]
	v_pk_mul_f32 v[174:175], v[174:175], v[184:185]
	v_pk_fma_f32 v[144:145], v[160:161], v[128:129], v[144:145]
	v_pk_fma_f32 v[146:147], v[162:163], v[130:131], v[146:147]
	v_pk_fma_f32 v[148:149], v[164:165], v[132:133], v[148:149]
	v_pk_fma_f32 v[150:151], v[166:167], v[134:135], v[150:151]
	v_pk_fma_f32 v[152:153], v[168:169], v[136:137], v[152:153]
	v_pk_fma_f32 v[154:155], v[170:171], v[138:139], v[154:155]
	v_pk_fma_f32 v[156:157], v[172:173], v[140:141], v[156:157]
	v_pk_fma_f32 v[158:159], v[174:175], v[142:143], v[158:159]
	v_pk_mul_f32 v[252:253], v[144:145], v[144:145]
	v_pk_mul_f32 v[254:255], v[146:147], v[146:147]
	v_pk_fma_f32 v[252:253], v[148:149], v[148:149], v[252:253]
	v_pk_fma_f32 v[254:255], v[150:151], v[150:151], v[254:255]
	v_pk_fma_f32 v[252:253], v[152:153], v[152:153], v[252:253]
	v_pk_fma_f32 v[254:255], v[154:155], v[154:155], v[254:255]
	v_pk_fma_f32 v[252:253], v[156:157], v[156:157], v[252:253]
	v_pk_fma_f32 v[254:255], v[158:159], v[158:159], v[254:255]
	v_pk_add_f32 v[252:253], v[252:253], v[254:255]
	s_nop 0
	v_add_f32_e32 v183, v252, v253
	s_nop 1
	v_add_f32_dpp v183, v183, v183 quad_perm:[1,0,3,2] row_mask:0xf bank_mask:0xf bound_ctrl:1
	s_nop 1
	v_add_f32_dpp v183, v183, v183 quad_perm:[2,3,0,1] row_mask:0xf bank_mask:0xf bound_ctrl:1
	s_nop 1
	v_add_f32_dpp v183, v183, v183 row_half_mirror row_mask:0xf bank_mask:0xf bound_ctrl:1
	s_nop 1
	v_add_f32_dpp v183, v183, v183 row_mirror row_mask:0xf bank_mask:0xf bound_ctrl:1
	s_nop 1
	v_readlane_b32 s98, v183, 0
	v_readlane_b32 s99, v183, 16
	v_readlane_b32 s100, v183, 32
	v_readlane_b32 s101, v183, 48
	s_nop 1
	v_mov_b32_e32 v183, s98
	v_add_f32_e32 v183, s99, v183
	v_add_f32_e32 v183, s100, v183
	v_add_f32_e32 v183, s101, v183
	v_fmamk_f32 v183, v183, 0x3a800000, v182
	v_cmp_gt_f32_e32 vcc, 0x800000, v183
	v_mul_f32_e32 v181, 0x4b800000, v183
	s_nop 1
	v_cndmask_b32_e32 v183, v183, v181, vcc
	v_rsq_f32_e32 v183, v183
	s_nop 0
	v_mul_f32_e32 v181, 0x45800000, v183
	v_cndmask_b32_e32 v184, v183, v181, vcc
	v_mov_b32_e32 v185, v184
	v_cvt_pk_bf16_f32 v64, v144, v145
	v_cvt_pk_bf16_f32 v65, v146, v147
	v_cvt_pk_bf16_f32 v66, v148, v149
	v_cvt_pk_bf16_f32 v67, v150, v151
	v_cvt_pk_bf16_f32 v68, v152, v153
	v_cvt_pk_bf16_f32 v69, v154, v155
	v_cvt_pk_bf16_f32 v70, v156, v157
	v_cvt_pk_bf16_f32 v71, v158, v159
	v_add_u32_e32 v181, 0x2800000, v177
	global_store_dwordx4 v181, v[64:67], s[78:79]
	global_store_dwordx4 v181, v[68:71], s[78:79] offset:1024
	v_add_u32_e32 v236, 0x8000, v237
	s_mov_b64 exec, 1
	global_store_dword v236, v184, s[78:79]
	s_mov_b64 exec, -1
	s_waitcnt vmcnt(8)
	v_lshlrev_b32_e32 v144, 16, v80
	v_and_b32_e32 v145, 0xffff0000, v80
	v_lshlrev_b32_e32 v146, 16, v81
	v_and_b32_e32 v147, 0xffff0000, v81
	v_lshlrev_b32_e32 v148, 16, v82
	v_and_b32_e32 v149, 0xffff0000, v82
	v_lshlrev_b32_e32 v150, 16, v83
	v_and_b32_e32 v151, 0xffff0000, v83
	v_lshlrev_b32_e32 v152, 16, v84
	v_and_b32_e32 v153, 0xffff0000, v84
	v_lshlrev_b32_e32 v154, 16, v85
	v_and_b32_e32 v155, 0xffff0000, v85
	v_lshlrev_b32_e32 v156, 16, v86
	v_and_b32_e32 v157, 0xffff0000, v86
	v_lshlrev_b32_e32 v158, 16, v87
	v_and_b32_e32 v159, 0xffff0000, v87
	v_lshlrev_b32_e32 v160, 16, v88
	v_and_b32_e32 v161, 0xffff0000, v88
	v_lshlrev_b32_e32 v162, 16, v89
	v_and_b32_e32 v163, 0xffff0000, v89
	v_lshlrev_b32_e32 v164, 16, v90
	v_and_b32_e32 v165, 0xffff0000, v90
	v_lshlrev_b32_e32 v166, 16, v91
	v_and_b32_e32 v167, 0xffff0000, v91
	v_lshlrev_b32_e32 v168, 16, v92
	v_and_b32_e32 v169, 0xffff0000, v92
	v_lshlrev_b32_e32 v170, 16, v93
	v_and_b32_e32 v171, 0xffff0000, v93
	v_lshlrev_b32_e32 v172, 16, v94
	v_and_b32_e32 v173, 0xffff0000, v94
	v_lshlrev_b32_e32 v174, 16, v95
	v_and_b32_e32 v175, 0xffff0000, v95
	v_pk_mul_f32 v[252:253], v[160:161], v[160:161]
	v_pk_mul_f32 v[254:255], v[162:163], v[162:163]
	v_pk_fma_f32 v[252:253], v[164:165], v[164:165], v[252:253]
	v_pk_fma_f32 v[254:255], v[166:167], v[166:167], v[254:255]
	v_pk_fma_f32 v[252:253], v[168:169], v[168:169], v[252:253]
	v_pk_fma_f32 v[254:255], v[170:171], v[170:171], v[254:255]
	v_pk_fma_f32 v[252:253], v[172:173], v[172:173], v[252:253]
	v_pk_fma_f32 v[254:255], v[174:175], v[174:175], v[254:255]
	v_pk_add_f32 v[252:253], v[252:253], v[254:255]
	s_nop 0
	v_add_f32_e32 v183, v252, v253
	s_nop 1
	v_add_f32_dpp v183, v183, v183 quad_perm:[1,0,3,2] row_mask:0xf bank_mask:0xf bound_ctrl:1
	s_nop 1
	v_add_f32_dpp v183, v183, v183 quad_perm:[2,3,0,1] row_mask:0xf bank_mask:0xf bound_ctrl:1
	s_nop 1
	v_add_f32_dpp v183, v183, v183 row_half_mirror row_mask:0xf bank_mask:0xf bound_ctrl:1
	s_nop 1
	v_add_f32_dpp v183, v183, v183 row_mirror row_mask:0xf bank_mask:0xf bound_ctrl:1
	s_nop 1
	v_readlane_b32 s98, v183, 0
	v_readlane_b32 s99, v183, 16
	v_readlane_b32 s100, v183, 32
	v_readlane_b32 s101, v183, 48
	s_nop 1
	v_mov_b32_e32 v183, s98
	v_add_f32_e32 v183, s99, v183
	v_add_f32_e32 v183, s100, v183
	v_add_f32_e32 v183, s101, v183
	v_fmamk_f32 v183, v183, 0x3a800000, v182
	v_cmp_gt_f32_e32 vcc, 0x800000, v183
	v_mul_f32_e32 v181, 0x4b800000, v183
	s_nop 1
	v_cndmask_b32_e32 v183, v183, v181, vcc
	v_rsq_f32_e32 v183, v183
	s_nop 0
	v_mul_f32_e32 v181, 0x45800000, v183
	v_cndmask_b32_e32 v184, v183, v181, vcc
	v_mov_b32_e32 v185, v184
	v_pk_mul_f32 v[160:161], v[160:161], v[184:185]
	v_pk_mul_f32 v[162:163], v[162:163], v[184:185]
	v_pk_mul_f32 v[164:165], v[164:165], v[184:185]
	v_pk_mul_f32 v[166:167], v[166:167], v[184:185]
	v_pk_mul_f32 v[168:169], v[168:169], v[184:185]
	v_pk_mul_f32 v[170:171], v[170:171], v[184:185]
	v_pk_mul_f32 v[172:173], v[172:173], v[184:185]
	v_pk_mul_f32 v[174:175], v[174:175], v[184:185]
	v_pk_fma_f32 v[144:145], v[160:161], v[128:129], v[144:145]
	v_pk_fma_f32 v[146:147], v[162:163], v[130:131], v[146:147]
	v_pk_fma_f32 v[148:149], v[164:165], v[132:133], v[148:149]
	v_pk_fma_f32 v[150:151], v[166:167], v[134:135], v[150:151]
	v_pk_fma_f32 v[152:153], v[168:169], v[136:137], v[152:153]
	v_pk_fma_f32 v[154:155], v[170:171], v[138:139], v[154:155]
	v_pk_fma_f32 v[156:157], v[172:173], v[140:141], v[156:157]
	v_pk_fma_f32 v[158:159], v[174:175], v[142:143], v[158:159]
	v_pk_mul_f32 v[252:253], v[144:145], v[144:145]
	v_pk_mul_f32 v[254:255], v[146:147], v[146:147]
	v_pk_fma_f32 v[252:253], v[148:149], v[148:149], v[252:253]
	v_pk_fma_f32 v[254:255], v[150:151], v[150:151], v[254:255]
	v_pk_fma_f32 v[252:253], v[152:153], v[152:153], v[252:253]
	v_pk_fma_f32 v[254:255], v[154:155], v[154:155], v[254:255]
	v_pk_fma_f32 v[252:253], v[156:157], v[156:157], v[252:253]
	v_pk_fma_f32 v[254:255], v[158:159], v[158:159], v[254:255]
	v_pk_add_f32 v[252:253], v[252:253], v[254:255]
	s_nop 0
	v_add_f32_e32 v183, v252, v253
	s_nop 1
	v_add_f32_dpp v183, v183, v183 quad_perm:[1,0,3,2] row_mask:0xf bank_mask:0xf bound_ctrl:1
	s_nop 1
	v_add_f32_dpp v183, v183, v183 quad_perm:[2,3,0,1] row_mask:0xf bank_mask:0xf bound_ctrl:1
	s_nop 1
	v_add_f32_dpp v183, v183, v183 row_half_mirror row_mask:0xf bank_mask:0xf bound_ctrl:1
	s_nop 1
	v_add_f32_dpp v183, v183, v183 row_mirror row_mask:0xf bank_mask:0xf bound_ctrl:1
	s_nop 1
	v_readlane_b32 s98, v183, 0
	v_readlane_b32 s99, v183, 16
	v_readlane_b32 s100, v183, 32
	v_readlane_b32 s101, v183, 48
	s_nop 1
	v_mov_b32_e32 v183, s98
	v_add_f32_e32 v183, s99, v183
	v_add_f32_e32 v183, s100, v183
	v_add_f32_e32 v183, s101, v183
	v_fmamk_f32 v183, v183, 0x3a800000, v182
	v_cmp_gt_f32_e32 vcc, 0x800000, v183
	v_mul_f32_e32 v181, 0x4b800000, v183
	s_nop 1
	v_cndmask_b32_e32 v183, v183, v181, vcc
	v_rsq_f32_e32 v183, v183
	s_nop 0
	v_mul_f32_e32 v181, 0x45800000, v183
	v_cndmask_b32_e32 v184, v183, v181, vcc
	v_mov_b32_e32 v185, v184
	v_cvt_pk_bf16_f32 v80, v144, v145
	v_cvt_pk_bf16_f32 v81, v146, v147
	v_cvt_pk_bf16_f32 v82, v148, v149
	v_cvt_pk_bf16_f32 v83, v150, v151
	v_cvt_pk_bf16_f32 v84, v152, v153
	v_cvt_pk_bf16_f32 v85, v154, v155
	v_cvt_pk_bf16_f32 v86, v156, v157
	v_cvt_pk_bf16_f32 v87, v158, v159
	v_add_u32_e32 v181, 0x2c00000, v177
	global_store_dwordx4 v181, v[80:83], s[78:79]
	global_store_dwordx4 v181, v[84:87], s[78:79] offset:1024
	v_add_u32_e32 v236, 0xa000, v237
	s_mov_b64 exec, 1
	global_store_dword v236, v184, s[78:79]
	s_mov_b64 exec, -1
	s_waitcnt vmcnt(4)
	v_lshlrev_b32_e32 v144, 16, v96
	v_and_b32_e32 v145, 0xffff0000, v96
	v_lshlrev_b32_e32 v146, 16, v97
	v_and_b32_e32 v147, 0xffff0000, v97
	v_lshlrev_b32_e32 v148, 16, v98
	v_and_b32_e32 v149, 0xffff0000, v98
	v_lshlrev_b32_e32 v150, 16, v99
	v_and_b32_e32 v151, 0xffff0000, v99
	v_lshlrev_b32_e32 v152, 16, v100
	v_and_b32_e32 v153, 0xffff0000, v100
	v_lshlrev_b32_e32 v154, 16, v101
	v_and_b32_e32 v155, 0xffff0000, v101
	v_lshlrev_b32_e32 v156, 16, v102
	v_and_b32_e32 v157, 0xffff0000, v102
	v_lshlrev_b32_e32 v158, 16, v103
	v_and_b32_e32 v159, 0xffff0000, v103
	v_lshlrev_b32_e32 v160, 16, v104
	v_and_b32_e32 v161, 0xffff0000, v104
	v_lshlrev_b32_e32 v162, 16, v105
	v_and_b32_e32 v163, 0xffff0000, v105
	v_lshlrev_b32_e32 v164, 16, v106
	v_and_b32_e32 v165, 0xffff0000, v106
	v_lshlrev_b32_e32 v166, 16, v107
	v_and_b32_e32 v167, 0xffff0000, v107
	v_lshlrev_b32_e32 v168, 16, v108
	v_and_b32_e32 v169, 0xffff0000, v108
	v_lshlrev_b32_e32 v170, 16, v109
	v_and_b32_e32 v171, 0xffff0000, v109
	v_lshlrev_b32_e32 v172, 16, v110
	v_and_b32_e32 v173, 0xffff0000, v110
	v_lshlrev_b32_e32 v174, 16, v111
	v_and_b32_e32 v175, 0xffff0000, v111
	v_pk_mul_f32 v[252:253], v[160:161], v[160:161]
	v_pk_mul_f32 v[254:255], v[162:163], v[162:163]
	v_pk_fma_f32 v[252:253], v[164:165], v[164:165], v[252:253]
	v_pk_fma_f32 v[254:255], v[166:167], v[166:167], v[254:255]
	v_pk_fma_f32 v[252:253], v[168:169], v[168:169], v[252:253]
	v_pk_fma_f32 v[254:255], v[170:171], v[170:171], v[254:255]
	v_pk_fma_f32 v[252:253], v[172:173], v[172:173], v[252:253]
	v_pk_fma_f32 v[254:255], v[174:175], v[174:175], v[254:255]
	v_pk_add_f32 v[252:253], v[252:253], v[254:255]
	s_nop 0
	v_add_f32_e32 v183, v252, v253
	s_nop 1
	v_add_f32_dpp v183, v183, v183 quad_perm:[1,0,3,2] row_mask:0xf bank_mask:0xf bound_ctrl:1
	s_nop 1
	v_add_f32_dpp v183, v183, v183 quad_perm:[2,3,0,1] row_mask:0xf bank_mask:0xf bound_ctrl:1
	s_nop 1
	v_add_f32_dpp v183, v183, v183 row_half_mirror row_mask:0xf bank_mask:0xf bound_ctrl:1
	s_nop 1
	v_add_f32_dpp v183, v183, v183 row_mirror row_mask:0xf bank_mask:0xf bound_ctrl:1
	s_nop 1
	v_readlane_b32 s98, v183, 0
	v_readlane_b32 s99, v183, 16
	v_readlane_b32 s100, v183, 32
	v_readlane_b32 s101, v183, 48
	s_nop 1
	v_mov_b32_e32 v183, s98
	v_add_f32_e32 v183, s99, v183
	v_add_f32_e32 v183, s100, v183
	v_add_f32_e32 v183, s101, v183
	v_fmamk_f32 v183, v183, 0x3a800000, v182
	v_cmp_gt_f32_e32 vcc, 0x800000, v183
	v_mul_f32_e32 v181, 0x4b800000, v183
	s_nop 1
	v_cndmask_b32_e32 v183, v183, v181, vcc
	v_rsq_f32_e32 v183, v183
	s_nop 0
	v_mul_f32_e32 v181, 0x45800000, v183
	v_cndmask_b32_e32 v184, v183, v181, vcc
	v_mov_b32_e32 v185, v184
	v_pk_mul_f32 v[160:161], v[160:161], v[184:185]
	v_pk_mul_f32 v[162:163], v[162:163], v[184:185]
	v_pk_mul_f32 v[164:165], v[164:165], v[184:185]
	v_pk_mul_f32 v[166:167], v[166:167], v[184:185]
	v_pk_mul_f32 v[168:169], v[168:169], v[184:185]
	v_pk_mul_f32 v[170:171], v[170:171], v[184:185]
	v_pk_mul_f32 v[172:173], v[172:173], v[184:185]
	v_pk_mul_f32 v[174:175], v[174:175], v[184:185]
	v_pk_fma_f32 v[144:145], v[160:161], v[128:129], v[144:145]
	v_pk_fma_f32 v[146:147], v[162:163], v[130:131], v[146:147]
	v_pk_fma_f32 v[148:149], v[164:165], v[132:133], v[148:149]
	v_pk_fma_f32 v[150:151], v[166:167], v[134:135], v[150:151]
	v_pk_fma_f32 v[152:153], v[168:169], v[136:137], v[152:153]
	v_pk_fma_f32 v[154:155], v[170:171], v[138:139], v[154:155]
	v_pk_fma_f32 v[156:157], v[172:173], v[140:141], v[156:157]
	v_pk_fma_f32 v[158:159], v[174:175], v[142:143], v[158:159]
	v_pk_mul_f32 v[252:253], v[144:145], v[144:145]
	v_pk_mul_f32 v[254:255], v[146:147], v[146:147]
	v_pk_fma_f32 v[252:253], v[148:149], v[148:149], v[252:253]
	v_pk_fma_f32 v[254:255], v[150:151], v[150:151], v[254:255]
	v_pk_fma_f32 v[252:253], v[152:153], v[152:153], v[252:253]
	v_pk_fma_f32 v[254:255], v[154:155], v[154:155], v[254:255]
	v_pk_fma_f32 v[252:253], v[156:157], v[156:157], v[252:253]
	v_pk_fma_f32 v[254:255], v[158:159], v[158:159], v[254:255]
	v_pk_add_f32 v[252:253], v[252:253], v[254:255]
	s_nop 0
	v_add_f32_e32 v183, v252, v253
	s_nop 1
	v_add_f32_dpp v183, v183, v183 quad_perm:[1,0,3,2] row_mask:0xf bank_mask:0xf bound_ctrl:1
	s_nop 1
	v_add_f32_dpp v183, v183, v183 quad_perm:[2,3,0,1] row_mask:0xf bank_mask:0xf bound_ctrl:1
	s_nop 1
	v_add_f32_dpp v183, v183, v183 row_half_mirror row_mask:0xf bank_mask:0xf bound_ctrl:1
	s_nop 1
	v_add_f32_dpp v183, v183, v183 row_mirror row_mask:0xf bank_mask:0xf bound_ctrl:1
	s_nop 1
	v_readlane_b32 s98, v183, 0
	v_readlane_b32 s99, v183, 16
	v_readlane_b32 s100, v183, 32
	v_readlane_b32 s101, v183, 48
	s_nop 1
	v_mov_b32_e32 v183, s98
	v_add_f32_e32 v183, s99, v183
	v_add_f32_e32 v183, s100, v183
	v_add_f32_e32 v183, s101, v183
	v_fmamk_f32 v183, v183, 0x3a800000, v182
	v_cmp_gt_f32_e32 vcc, 0x800000, v183
	v_mul_f32_e32 v181, 0x4b800000, v183
	s_nop 1
	v_cndmask_b32_e32 v183, v183, v181, vcc
	v_rsq_f32_e32 v183, v183
	s_nop 0
	v_mul_f32_e32 v181, 0x45800000, v183
	v_cndmask_b32_e32 v184, v183, v181, vcc
	v_mov_b32_e32 v185, v184
	v_cvt_pk_bf16_f32 v96, v144, v145
	v_cvt_pk_bf16_f32 v97, v146, v147
	v_cvt_pk_bf16_f32 v98, v148, v149
	v_cvt_pk_bf16_f32 v99, v150, v151
	v_cvt_pk_bf16_f32 v100, v152, v153
	v_cvt_pk_bf16_f32 v101, v154, v155
	v_cvt_pk_bf16_f32 v102, v156, v157
	v_cvt_pk_bf16_f32 v103, v158, v159
	v_add_u32_e32 v181, 0x3000000, v177
	global_store_dwordx4 v181, v[96:99], s[78:79]
	global_store_dwordx4 v181, v[100:103], s[78:79] offset:1024
	v_add_u32_e32 v236, 0xc000, v237
	s_mov_b64 exec, 1
	global_store_dword v236, v184, s[78:79]
	s_mov_b64 exec, -1
	s_waitcnt vmcnt(0)
	v_lshlrev_b32_e32 v144, 16, v112
	v_and_b32_e32 v145, 0xffff0000, v112
	v_lshlrev_b32_e32 v146, 16, v113
	v_and_b32_e32 v147, 0xffff0000, v113
	v_lshlrev_b32_e32 v148, 16, v114
	v_and_b32_e32 v149, 0xffff0000, v114
	v_lshlrev_b32_e32 v150, 16, v115
	v_and_b32_e32 v151, 0xffff0000, v115
	v_lshlrev_b32_e32 v152, 16, v116
	v_and_b32_e32 v153, 0xffff0000, v116
	v_lshlrev_b32_e32 v154, 16, v117
	v_and_b32_e32 v155, 0xffff0000, v117
	v_lshlrev_b32_e32 v156, 16, v118
	v_and_b32_e32 v157, 0xffff0000, v118
	v_lshlrev_b32_e32 v158, 16, v119
	v_and_b32_e32 v159, 0xffff0000, v119
	v_lshlrev_b32_e32 v160, 16, v120
	v_and_b32_e32 v161, 0xffff0000, v120
	v_lshlrev_b32_e32 v162, 16, v121
	v_and_b32_e32 v163, 0xffff0000, v121
	v_lshlrev_b32_e32 v164, 16, v122
	v_and_b32_e32 v165, 0xffff0000, v122
	v_lshlrev_b32_e32 v166, 16, v123
	v_and_b32_e32 v167, 0xffff0000, v123
	v_lshlrev_b32_e32 v168, 16, v124
	v_and_b32_e32 v169, 0xffff0000, v124
	v_lshlrev_b32_e32 v170, 16, v125
	v_and_b32_e32 v171, 0xffff0000, v125
	v_lshlrev_b32_e32 v172, 16, v126
	v_and_b32_e32 v173, 0xffff0000, v126
	v_lshlrev_b32_e32 v174, 16, v127
	v_and_b32_e32 v175, 0xffff0000, v127
	v_pk_mul_f32 v[252:253], v[160:161], v[160:161]
	v_pk_mul_f32 v[254:255], v[162:163], v[162:163]
	v_pk_fma_f32 v[252:253], v[164:165], v[164:165], v[252:253]
	v_pk_fma_f32 v[254:255], v[166:167], v[166:167], v[254:255]
	v_pk_fma_f32 v[252:253], v[168:169], v[168:169], v[252:253]
	v_pk_fma_f32 v[254:255], v[170:171], v[170:171], v[254:255]
	v_pk_fma_f32 v[252:253], v[172:173], v[172:173], v[252:253]
	v_pk_fma_f32 v[254:255], v[174:175], v[174:175], v[254:255]
	v_pk_add_f32 v[252:253], v[252:253], v[254:255]
	s_nop 0
	v_add_f32_e32 v183, v252, v253
	s_nop 1
	v_add_f32_dpp v183, v183, v183 quad_perm:[1,0,3,2] row_mask:0xf bank_mask:0xf bound_ctrl:1
	s_nop 1
	v_add_f32_dpp v183, v183, v183 quad_perm:[2,3,0,1] row_mask:0xf bank_mask:0xf bound_ctrl:1
	s_nop 1
	v_add_f32_dpp v183, v183, v183 row_half_mirror row_mask:0xf bank_mask:0xf bound_ctrl:1
	s_nop 1
	v_add_f32_dpp v183, v183, v183 row_mirror row_mask:0xf bank_mask:0xf bound_ctrl:1
	s_nop 1
	v_readlane_b32 s98, v183, 0
	v_readlane_b32 s99, v183, 16
	v_readlane_b32 s100, v183, 32
	v_readlane_b32 s101, v183, 48
	s_nop 1
	v_mov_b32_e32 v183, s98
	v_add_f32_e32 v183, s99, v183
	v_add_f32_e32 v183, s100, v183
	v_add_f32_e32 v183, s101, v183
	v_fmamk_f32 v183, v183, 0x3a800000, v182
	v_cmp_gt_f32_e32 vcc, 0x800000, v183
	v_mul_f32_e32 v181, 0x4b800000, v183
	s_nop 1
	v_cndmask_b32_e32 v183, v183, v181, vcc
	v_rsq_f32_e32 v183, v183
	s_nop 0
	v_mul_f32_e32 v181, 0x45800000, v183
	v_cndmask_b32_e32 v184, v183, v181, vcc
	v_mov_b32_e32 v185, v184
	v_pk_mul_f32 v[160:161], v[160:161], v[184:185]
	v_pk_mul_f32 v[162:163], v[162:163], v[184:185]
	v_pk_mul_f32 v[164:165], v[164:165], v[184:185]
	v_pk_mul_f32 v[166:167], v[166:167], v[184:185]
	v_pk_mul_f32 v[168:169], v[168:169], v[184:185]
	v_pk_mul_f32 v[170:171], v[170:171], v[184:185]
	v_pk_mul_f32 v[172:173], v[172:173], v[184:185]
	v_pk_mul_f32 v[174:175], v[174:175], v[184:185]
	v_pk_fma_f32 v[144:145], v[160:161], v[128:129], v[144:145]
	v_pk_fma_f32 v[146:147], v[162:163], v[130:131], v[146:147]
	v_pk_fma_f32 v[148:149], v[164:165], v[132:133], v[148:149]
	v_pk_fma_f32 v[150:151], v[166:167], v[134:135], v[150:151]
	v_pk_fma_f32 v[152:153], v[168:169], v[136:137], v[152:153]
	v_pk_fma_f32 v[154:155], v[170:171], v[138:139], v[154:155]
	v_pk_fma_f32 v[156:157], v[172:173], v[140:141], v[156:157]
	v_pk_fma_f32 v[158:159], v[174:175], v[142:143], v[158:159]
	v_pk_mul_f32 v[252:253], v[144:145], v[144:145]
	v_pk_mul_f32 v[254:255], v[146:147], v[146:147]
	v_pk_fma_f32 v[252:253], v[148:149], v[148:149], v[252:253]
	v_pk_fma_f32 v[254:255], v[150:151], v[150:151], v[254:255]
	v_pk_fma_f32 v[252:253], v[152:153], v[152:153], v[252:253]
	v_pk_fma_f32 v[254:255], v[154:155], v[154:155], v[254:255]
	v_pk_fma_f32 v[252:253], v[156:157], v[156:157], v[252:253]
	v_pk_fma_f32 v[254:255], v[158:159], v[158:159], v[254:255]
	v_pk_add_f32 v[252:253], v[252:253], v[254:255]
	s_nop 0
	v_add_f32_e32 v183, v252, v253
	s_nop 1
	v_add_f32_dpp v183, v183, v183 quad_perm:[1,0,3,2] row_mask:0xf bank_mask:0xf bound_ctrl:1
	s_nop 1
	v_add_f32_dpp v183, v183, v183 quad_perm:[2,3,0,1] row_mask:0xf bank_mask:0xf bound_ctrl:1
	s_nop 1
	v_add_f32_dpp v183, v183, v183 row_half_mirror row_mask:0xf bank_mask:0xf bound_ctrl:1
	s_nop 1
	v_add_f32_dpp v183, v183, v183 row_mirror row_mask:0xf bank_mask:0xf bound_ctrl:1
	s_nop 1
	v_readlane_b32 s98, v183, 0
	v_readlane_b32 s99, v183, 16
	v_readlane_b32 s100, v183, 32
	v_readlane_b32 s101, v183, 48
	s_nop 1
	v_mov_b32_e32 v183, s98
	v_add_f32_e32 v183, s99, v183
	v_add_f32_e32 v183, s100, v183
	v_add_f32_e32 v183, s101, v183
	v_fmamk_f32 v183, v183, 0x3a800000, v182
	v_cmp_gt_f32_e32 vcc, 0x800000, v183
	v_mul_f32_e32 v181, 0x4b800000, v183
	s_nop 1
	v_cndmask_b32_e32 v183, v183, v181, vcc
	v_rsq_f32_e32 v183, v183
	s_nop 0
	v_mul_f32_e32 v181, 0x45800000, v183
	v_cndmask_b32_e32 v184, v183, v181, vcc
	v_mov_b32_e32 v185, v184
	v_cvt_pk_bf16_f32 v112, v144, v145
	v_cvt_pk_bf16_f32 v113, v146, v147
	v_cvt_pk_bf16_f32 v114, v148, v149
	v_cvt_pk_bf16_f32 v115, v150, v151
	v_cvt_pk_bf16_f32 v116, v152, v153
	v_cvt_pk_bf16_f32 v117, v154, v155
	v_cvt_pk_bf16_f32 v118, v156, v157
	v_cvt_pk_bf16_f32 v119, v158, v159
	v_add_u32_e32 v181, 0x3400000, v177
	global_store_dwordx4 v181, v[112:115], s[78:79]
	global_store_dwordx4 v181, v[116:119], s[78:79] offset:1024
	v_add_u32_e32 v236, 0xe000, v237
	s_mov_b64 exec, 1
	global_store_dword v236, v184, s[78:79]
	s_mov_b64 exec, -1
	v_readfirstlane_b32 s98, v179
	s_nop 3
	s_and_b32 s99, s98, 3
	s_add_i32 s100, s99, 4
	s_lshl_b32 s100, s100, 11
	s_sub_i32 s100, s100, s99
	s_lshl_b32 s101, s100, 11
	v_add_u32_e32 v177, s101, v177
	s_lshl_b32 s101, s100, 2
	v_add_u32_e32 v237, s101, v237
	v_add_u32_e32 v181, 0x1800000, v177
	global_load_dwordx4 v[0:3], v181, s[78:79]
	global_load_dwordx4 v[4:7], v181, s[78:79] offset:1024
	v_add_u32_e32 v181, 0x9e00000, v177
	global_load_dwordx4 v[8:11], v181, s[78:79]
	global_load_dwordx4 v[12:15], v181, s[78:79] offset:1024
	s_waitcnt vmcnt(0)
	v_lshlrev_b32_e32 v144, 16, v0
	v_and_b32_e32 v145, 0xffff0000, v0
	v_lshlrev_b32_e32 v146, 16, v1
	v_and_b32_e32 v147, 0xffff0000, v1
	v_lshlrev_b32_e32 v148, 16, v2
	v_and_b32_e32 v149, 0xffff0000, v2
	v_lshlrev_b32_e32 v150, 16, v3
	v_and_b32_e32 v151, 0xffff0000, v3
	v_lshlrev_b32_e32 v152, 16, v4
	v_and_b32_e32 v153, 0xffff0000, v4
	v_lshlrev_b32_e32 v154, 16, v5
	v_and_b32_e32 v155, 0xffff0000, v5
	v_lshlrev_b32_e32 v156, 16, v6
	v_and_b32_e32 v157, 0xffff0000, v6
	v_lshlrev_b32_e32 v158, 16, v7
	v_and_b32_e32 v159, 0xffff0000, v7
	v_lshlrev_b32_e32 v160, 16, v8
	v_and_b32_e32 v161, 0xffff0000, v8
	v_lshlrev_b32_e32 v162, 16, v9
	v_and_b32_e32 v163, 0xffff0000, v9
	v_lshlrev_b32_e32 v164, 16, v10
	v_and_b32_e32 v165, 0xffff0000, v10
	v_lshlrev_b32_e32 v166, 16, v11
	v_and_b32_e32 v167, 0xffff0000, v11
	v_lshlrev_b32_e32 v168, 16, v12
	v_and_b32_e32 v169, 0xffff0000, v12
	v_lshlrev_b32_e32 v170, 16, v13
	v_and_b32_e32 v171, 0xffff0000, v13
	v_lshlrev_b32_e32 v172, 16, v14
	v_and_b32_e32 v173, 0xffff0000, v14
	v_lshlrev_b32_e32 v174, 16, v15
	v_and_b32_e32 v175, 0xffff0000, v15
	v_pk_mul_f32 v[252:253], v[160:161], v[160:161]
	v_pk_mul_f32 v[254:255], v[162:163], v[162:163]
	v_pk_fma_f32 v[252:253], v[164:165], v[164:165], v[252:253]
	v_pk_fma_f32 v[254:255], v[166:167], v[166:167], v[254:255]
	v_pk_fma_f32 v[252:253], v[168:169], v[168:169], v[252:253]
	v_pk_fma_f32 v[254:255], v[170:171], v[170:171], v[254:255]
	v_pk_fma_f32 v[252:253], v[172:173], v[172:173], v[252:253]
	v_pk_fma_f32 v[254:255], v[174:175], v[174:175], v[254:255]
	v_pk_add_f32 v[252:253], v[252:253], v[254:255]
	s_nop 0
	v_add_f32_e32 v183, v252, v253
	s_nop 1
	v_add_f32_dpp v183, v183, v183 quad_perm:[1,0,3,2] row_mask:0xf bank_mask:0xf bound_ctrl:1
	s_nop 1
	v_add_f32_dpp v183, v183, v183 quad_perm:[2,3,0,1] row_mask:0xf bank_mask:0xf bound_ctrl:1
	s_nop 1
	v_add_f32_dpp v183, v183, v183 row_half_mirror row_mask:0xf bank_mask:0xf bound_ctrl:1
	s_nop 1
	v_add_f32_dpp v183, v183, v183 row_mirror row_mask:0xf bank_mask:0xf bound_ctrl:1
	s_nop 1
	v_readlane_b32 s98, v183, 0
	v_readlane_b32 s99, v183, 16
	v_readlane_b32 s100, v183, 32
	v_readlane_b32 s101, v183, 48
	s_nop 1
	v_mov_b32_e32 v183, s98
	v_add_f32_e32 v183, s99, v183
	v_add_f32_e32 v183, s100, v183
	v_add_f32_e32 v183, s101, v183
	v_fmamk_f32 v183, v183, 0x3a800000, v182
	v_cmp_gt_f32_e32 vcc, 0x800000, v183
	v_mul_f32_e32 v181, 0x4b800000, v183
	s_nop 1
	v_cndmask_b32_e32 v183, v183, v181, vcc
	v_rsq_f32_e32 v183, v183
	s_nop 0
	v_mul_f32_e32 v181, 0x45800000, v183
	v_cndmask_b32_e32 v184, v183, v181, vcc
	v_mov_b32_e32 v185, v184
	v_pk_mul_f32 v[160:161], v[160:161], v[184:185]
	v_pk_mul_f32 v[162:163], v[162:163], v[184:185]
	v_pk_mul_f32 v[164:165], v[164:165], v[184:185]
	v_pk_mul_f32 v[166:167], v[166:167], v[184:185]
	v_pk_mul_f32 v[168:169], v[168:169], v[184:185]
	v_pk_mul_f32 v[170:171], v[170:171], v[184:185]
	v_pk_mul_f32 v[172:173], v[172:173], v[184:185]
	v_pk_mul_f32 v[174:175], v[174:175], v[184:185]
	v_pk_fma_f32 v[144:145], v[160:161], v[128:129], v[144:145]
	v_pk_fma_f32 v[146:147], v[162:163], v[130:131], v[146:147]
	v_pk_fma_f32 v[148:149], v[164:165], v[132:133], v[148:149]
	v_pk_fma_f32 v[150:151], v[166:167], v[134:135], v[150:151]
	v_pk_fma_f32 v[152:153], v[168:169], v[136:137], v[152:153]
	v_pk_fma_f32 v[154:155], v[170:171], v[138:139], v[154:155]
	v_pk_fma_f32 v[156:157], v[172:173], v[140:141], v[156:157]
	v_pk_fma_f32 v[158:159], v[174:175], v[142:143], v[158:159]
	v_pk_mul_f32 v[252:253], v[144:145], v[144:145]
	v_pk_mul_f32 v[254:255], v[146:147], v[146:147]
	v_pk_fma_f32 v[252:253], v[148:149], v[148:149], v[252:253]
	v_pk_fma_f32 v[254:255], v[150:151], v[150:151], v[254:255]
	v_pk_fma_f32 v[252:253], v[152:153], v[152:153], v[252:253]
	v_pk_fma_f32 v[254:255], v[154:155], v[154:155], v[254:255]
	v_pk_fma_f32 v[252:253], v[156:157], v[156:157], v[252:253]
	v_pk_fma_f32 v[254:255], v[158:159], v[158:159], v[254:255]
	v_pk_add_f32 v[252:253], v[252:253], v[254:255]
	s_nop 0
	v_add_f32_e32 v183, v252, v253
	s_nop 1
	v_add_f32_dpp v183, v183, v183 quad_perm:[1,0,3,2] row_mask:0xf bank_mask:0xf bound_ctrl:1
	s_nop 1
	v_add_f32_dpp v183, v183, v183 quad_perm:[2,3,0,1] row_mask:0xf bank_mask:0xf bound_ctrl:1
	s_nop 1
	v_add_f32_dpp v183, v183, v183 row_half_mirror row_mask:0xf bank_mask:0xf bound_ctrl:1
	s_nop 1
	v_add_f32_dpp v183, v183, v183 row_mirror row_mask:0xf bank_mask:0xf bound_ctrl:1
	s_nop 1
	v_readlane_b32 s98, v183, 0
	v_readlane_b32 s99, v183, 16
	v_readlane_b32 s100, v183, 32
	v_readlane_b32 s101, v183, 48
	s_nop 1
	v_mov_b32_e32 v183, s98
	v_add_f32_e32 v183, s99, v183
	v_add_f32_e32 v183, s100, v183
	v_add_f32_e32 v183, s101, v183
	v_fmamk_f32 v183, v183, 0x3a800000, v182
	v_cmp_gt_f32_e32 vcc, 0x800000, v183
	v_mul_f32_e32 v181, 0x4b800000, v183
	s_nop 1
	v_cndmask_b32_e32 v183, v183, v181, vcc
	v_rsq_f32_e32 v183, v183
	s_nop 0
	v_mul_f32_e32 v181, 0x45800000, v183
	v_cndmask_b32_e32 v184, v183, v181, vcc
	v_mov_b32_e32 v185, v184
	v_cvt_pk_bf16_f32 v0, v144, v145
	v_cvt_pk_bf16_f32 v1, v146, v147
	v_cvt_pk_bf16_f32 v2, v148, v149
	v_cvt_pk_bf16_f32 v3, v150, v151
	v_cvt_pk_bf16_f32 v4, v152, v153
	v_cvt_pk_bf16_f32 v5, v154, v155
	v_cvt_pk_bf16_f32 v6, v156, v157
	v_cvt_pk_bf16_f32 v7, v158, v159
	v_add_u32_e32 v181, 0x1800000, v177
	global_store_dwordx4 v181, v[0:3], s[78:79]
	global_store_dwordx4 v181, v[4:7], s[78:79] offset:1024
	v_add_u32_e32 v236, 0x0, v237
	s_mov_b64 exec, 1
	global_store_dword v236, v184, s[78:79]
	s_mov_b64 exec, -1
	s_branch .Lmyxupd_done_4

.LBB0_2139:
	v_readlane_b32 s0, v235, 52
	v_readlane_b32 s1, v235, 53
	s_and_b64 vcc, exec, s[0:1]
	s_waitcnt lgkmcnt(0)
	s_barrier
	v_mbcnt_lo_u32_b32 v0, -1, 0
	v_mbcnt_hi_u32_b32 v0, -1, v0
	s_cbranch_vccnz .LBB0_2159
	v_lshlrev_b32_e32 v2, 3, v0
	v_readlane_b32 s4, v235, 4
	v_ashrrev_i32_e32 v3, 31, v2
	v_readlane_b32 s6, v235, 6
	v_readlane_b32 s7, v235, 7
	v_lshlrev_b64 v[4:5], 1, v[2:3]
	v_lshlrev_b64 v[2:3], 2, v[2:3]
	v_readlane_b32 s5, v235, 5
	v_readlane_b32 s10, v235, 10
	v_readlane_b32 s11, v235, 11
	v_readlane_b32 s18, v235, 18
	v_readlane_b32 s19, v235, 19
	v_readlane_b32 s6, v235, 61
	v_lshl_add_u64 v[154:155], s[90:91], 0, v[2:3]
	v_readlane_b32 s8, v235, 8
	v_lshl_add_u64 v[2:3], s[18:19], 0, v[2:3]
	s_mov_b64 s[0:1], 0x2000
	v_readlane_b32 s4, v235, 0
	v_readlane_b32 s7, v235, 62
	s_mov_b32 s10, s6
	s_ashr_i32 s11, s6, 31
	v_readlane_b32 s9, v235, 9
	v_lshl_add_u64 v[158:159], v[2:3], 0, s[0:1]
	s_lshl_b32 s4, s4, 4
	s_add_i32 s0, s6, 0xffffc000
	s_lshl_b64 s[6:7], s[10:11], 2
	s_mov_b32 s8, s10
	v_readlane_b32 s12, v235, 12
	v_readlane_b32 s13, v235, 13
	v_readlane_b32 s14, v235, 14
	v_readlane_b32 s15, v235, 15
	v_readlane_b32 s16, v235, 16
	v_readlane_b32 s17, v235, 17
	v_readlane_b32 s5, v235, 1
	s_add_u32 s80, s6, 0x10000
	v_writelane_b32 v235, s8, 61
	s_addc_u32 s12, s7, 0
	s_ashr_i32 s5, s4, 31
	v_writelane_b32 v235, s9, 62
	s_lshl_b64 s[8:9], s[10:11], 11
	v_lshl_add_u64 v[152:153], s[86:87], 0, v[4:5]
	v_lshl_add_u64 v[156:157], s[54:55], 0, v[4:5]
	s_mov_b32 s1, 0
	v_cmp_eq_u32_e64 s[16:17], 0, v0
	s_lshl_b64 s[6:7], s[4:5], 2
	v_lshl_add_u64 v[160:161], s[8:9], 0, v[4:5]
	s_lshl_b64 s[8:9], s[4:5], 11
	s_mov_b64 s[20:21], 0x600000
	s_mov_b64 s[22:23], 0x600800
	s_mov_b64 s[24:25], 0x800000
	s_mov_b32 s5, 0x800000
	s_mov_b64 s[26:27], 0x800800
	s_mov_b64 s[28:29], 0xa00000
	s_mov_b64 s[36:37], 0xa00800
	s_mov_b64 s[38:39], 0xc00000
	s_mov_b64 s[40:41], 0xc00800
	s_mov_b64 s[42:43], 0xe00000
	s_mov_b64 s[44:45], 0xe00800
	s_mov_b64 s[46:47], 0x1000000
	s_mov_b32 s13, 0x1000000
	s_mov_b64 s[48:49], 0x1000800
	s_mov_b64 s[50:51], 0x1200000
	s_mov_b32 s14, 0x1200000
	s_mov_b64 s[10:11], 0x1200800
	s_mov_b64 s[82:83], 0x1400000
	s_mov_b32 s15, 0x1400000
	s_mov_b64 s[90:91], 0x1400800
	v_mov_b32_e32 v215, 0
	v_mov_b32_e32 v216, 0x358637bd
	v_mbcnt_lo_u32_b32 v176, -1, 0
	v_mbcnt_hi_u32_b32 v176, -1, v176
	v_readlane_b32 s98, v235, 49
	v_readlane_b32 s99, v235, 20
	v_readlane_b32 s100, v235, 18
	v_readlane_b32 s101, v235, 19
	s_nop 3
	s_lshr_b32 vcc_lo, s98, 3
	s_and_b32 vcc_hi, vcc_lo, 7
	s_lshr_b32 vcc_lo, vcc_lo, 3
	s_lshl_b32 vcc_lo, vcc_lo, 3
	s_add_i32 vcc_lo, vcc_lo, s99
	s_lshl_b32 s98, vcc_hi, 8
	s_add_i32 s98, s98, vcc_lo
	s_mov_b32 s99, s98
	v_mov_b32_e32 v183, s99
	v_lshlrev_b32_e32 v177, 4, v176
	s_lshl_b32 s99, s99, 11
	v_add_u32_e32 v177, s99, v177
	v_add_u32_e32 v178, 0x1800000, v177
	v_add_u32_e32 v179, 0x9e00000, v177
	v_lshlrev_b32_e32 v180, 5, v176
	v_add_u32_e32 v181, 0x2000, v180
	global_load_dwordx4 v[128:131], v181, s[100:101]
	global_load_dwordx4 v[132:135], v181, s[100:101] offset:16
	global_load_dwordx4 v[136:139], v181, s[100:101] offset:2048
	global_load_dwordx4 v[140:143], v181, s[100:101] offset:2064
	v_mov_b32_e32 v182, 0x358637bd
	s_and_b32 vcc_lo, s98, 3
	s_cmp_eq_u32 vcc_lo, 0
	s_cbranch_scc1 .Lmyxupd_heavy_5
	global_load_dwordx4 v[0:3], v178, s[78:79]
	global_load_dwordx4 v[4:7], v178, s[78:79] offset:1024
	global_load_dwordx4 v[8:11], v179, s[78:79]
	global_load_dwordx4 v[12:15], v179, s[78:79] offset:1024
	v_add_u32_e32 v178, 0x400000, v178
	v_add_u32_e32 v179, 0x400000, v179
	global_load_dwordx4 v[16:19], v178, s[78:79]
	global_load_dwordx4 v[20:23], v178, s[78:79] offset:1024
	global_load_dwordx4 v[24:27], v179, s[78:79]
	global_load_dwordx4 v[28:31], v179, s[78:79] offset:1024
	v_add_u32_e32 v178, 0x400000, v178
	v_add_u32_e32 v179, 0x400000, v179
	global_load_dwordx4 v[32:35], v178, s[78:79]
	global_load_dwordx4 v[36:39], v178, s[78:79] offset:1024
	global_load_dwordx4 v[40:43], v179, s[78:79]
	global_load_dwordx4 v[44:47], v179, s[78:79] offset:1024
	v_add_u32_e32 v178, 0x400000, v178
	v_add_u32_e32 v179, 0x400000, v179
	global_load_dwordx4 v[48:51], v178, s[78:79]
	global_load_dwordx4 v[52:55], v178, s[78:79] offset:1024
	global_load_dwordx4 v[56:59], v179, s[78:79]
	global_load_dwordx4 v[60:63], v179, s[78:79] offset:1024
	v_add_u32_e32 v178, 0x400000, v178
	v_add_u32_e32 v179, 0x400000, v179
	global_load_dwordx4 v[64:67], v178, s[78:79]
	global_load_dwordx4 v[68:71], v178, s[78:79] offset:1024
	global_load_dwordx4 v[72:75], v179, s[78:79]
	global_load_dwordx4 v[76:79], v179, s[78:79] offset:1024
	v_add_u32_e32 v178, 0x400000, v178
	v_add_u32_e32 v179, 0x400000, v179
	global_load_dwordx4 v[80:83], v178, s[78:79]
	global_load_dwordx4 v[84:87], v178, s[78:79] offset:1024
	global_load_dwordx4 v[88:91], v179, s[78:79]
	global_load_dwordx4 v[92:95], v179, s[78:79] offset:1024
	v_add_u32_e32 v178, 0x400000, v178
	v_add_u32_e32 v179, 0x400000, v179
	global_load_dwordx4 v[96:99], v178, s[78:79]
	global_load_dwordx4 v[100:103], v178, s[78:79] offset:1024
	global_load_dwordx4 v[104:107], v179, s[78:79]
	global_load_dwordx4 v[108:111], v179, s[78:79] offset:1024
	v_add_u32_e32 v178, 0x400000, v178
	v_add_u32_e32 v179, 0x400000, v179
	global_load_dwordx4 v[112:115], v178, s[78:79]
	global_load_dwordx4 v[116:119], v178, s[78:79] offset:1024
	global_load_dwordx4 v[120:123], v179, s[78:79]
	global_load_dwordx4 v[124:127], v179, s[78:79] offset:1024
	v_lshlrev_b32_e32 v237, 2, v183
	v_add_u32_e32 v237, 0x10000, v237
	v_mov_b32_e32 v179, s98
	s_waitcnt vmcnt(28)
	v_lshlrev_b32_e32 v144, 16, v0
	v_and_b32_e32 v145, 0xffff0000, v0
	v_lshlrev_b32_e32 v146, 16, v1
	v_and_b32_e32 v147, 0xffff0000, v1
	v_lshlrev_b32_e32 v148, 16, v2
	v_and_b32_e32 v149, 0xffff0000, v2
	v_lshlrev_b32_e32 v150, 16, v3
	v_and_b32_e32 v151, 0xffff0000, v3
	v_lshlrev_b32_e32 v152, 16, v4
	v_and_b32_e32 v153, 0xffff0000, v4
	v_lshlrev_b32_e32 v154, 16, v5
	v_and_b32_e32 v155, 0xffff0000, v5
	v_lshlrev_b32_e32 v156, 16, v6
	v_and_b32_e32 v157, 0xffff0000, v6
	v_lshlrev_b32_e32 v158, 16, v7
	v_and_b32_e32 v159, 0xffff0000, v7
	v_lshlrev_b32_e32 v160, 16, v8
	v_and_b32_e32 v161, 0xffff0000, v8
	v_lshlrev_b32_e32 v162, 16, v9
	v_and_b32_e32 v163, 0xffff0000, v9
	v_lshlrev_b32_e32 v164, 16, v10
	v_and_b32_e32 v165, 0xffff0000, v10
	v_lshlrev_b32_e32 v166, 16, v11
	v_and_b32_e32 v167, 0xffff0000, v11
	v_lshlrev_b32_e32 v168, 16, v12
	v_and_b32_e32 v169, 0xffff0000, v12
	v_lshlrev_b32_e32 v170, 16, v13
	v_and_b32_e32 v171, 0xffff0000, v13
	v_lshlrev_b32_e32 v172, 16, v14
	v_and_b32_e32 v173, 0xffff0000, v14
	v_lshlrev_b32_e32 v174, 16, v15
	v_and_b32_e32 v175, 0xffff0000, v15
	v_pk_mul_f32 v[252:253], v[160:161], v[160:161]
	v_pk_mul_f32 v[254:255], v[162:163], v[162:163]
	v_pk_fma_f32 v[252:253], v[164:165], v[164:165], v[252:253]
	v_pk_fma_f32 v[254:255], v[166:167], v[166:167], v[254:255]
	v_pk_fma_f32 v[252:253], v[168:169], v[168:169], v[252:253]
	v_pk_fma_f32 v[254:255], v[170:171], v[170:171], v[254:255]
	v_pk_fma_f32 v[252:253], v[172:173], v[172:173], v[252:253]
	v_pk_fma_f32 v[254:255], v[174:175], v[174:175], v[254:255]
	v_pk_add_f32 v[252:253], v[252:253], v[254:255]
	s_nop 0
	v_add_f32_e32 v183, v252, v253
	s_nop 1
	v_add_f32_dpp v183, v183, v183 quad_perm:[1,0,3,2] row_mask:0xf bank_mask:0xf bound_ctrl:1
	s_nop 1
	v_add_f32_dpp v183, v183, v183 quad_perm:[2,3,0,1] row_mask:0xf bank_mask:0xf bound_ctrl:1
	s_nop 1
	v_add_f32_dpp v183, v183, v183 row_half_mirror row_mask:0xf bank_mask:0xf bound_ctrl:1
	s_nop 1
	v_add_f32_dpp v183, v183, v183 row_mirror row_mask:0xf bank_mask:0xf bound_ctrl:1
	s_nop 1
	v_readlane_b32 s98, v183, 0
	v_readlane_b32 s99, v183, 16
	v_readlane_b32 s100, v183, 32
	v_readlane_b32 s101, v183, 48
	s_nop 1
	v_mov_b32_e32 v183, s98
	v_add_f32_e32 v183, s99, v183
	v_add_f32_e32 v183, s100, v183
	v_add_f32_e32 v183, s101, v183
	v_fmamk_f32 v183, v183, 0x3a800000, v182
	v_cmp_gt_f32_e32 vcc, 0x800000, v183
	v_mul_f32_e32 v181, 0x4b800000, v183
	s_nop 1
	v_cndmask_b32_e32 v183, v183, v181, vcc
	v_rsq_f32_e32 v183, v183
	s_nop 0
	v_mul_f32_e32 v181, 0x45800000, v183
	v_cndmask_b32_e32 v184, v183, v181, vcc
	v_mov_b32_e32 v185, v184
	v_pk_mul_f32 v[160:161], v[160:161], v[184:185]
	v_pk_mul_f32 v[162:163], v[162:163], v[184:185]
	v_pk_mul_f32 v[164:165], v[164:165], v[184:185]
	v_pk_mul_f32 v[166:167], v[166:167], v[184:185]
	v_pk_mul_f32 v[168:169], v[168:169], v[184:185]
	v_pk_mul_f32 v[170:171], v[170:171], v[184:185]
	v_pk_mul_f32 v[172:173], v[172:173], v[184:185]
	v_pk_mul_f32 v[174:175], v[174:175], v[184:185]
	v_pk_fma_f32 v[144:145], v[160:161], v[128:129], v[144:145]
	v_pk_fma_f32 v[146:147], v[162:163], v[130:131], v[146:147]
	v_pk_fma_f32 v[148:149], v[164:165], v[132:133], v[148:149]
	v_pk_fma_f32 v[150:151], v[166:167], v[134:135], v[150:151]
	v_pk_fma_f32 v[152:153], v[168:169], v[136:137], v[152:153]
	v_pk_fma_f32 v[154:155], v[170:171], v[138:139], v[154:155]
	v_pk_fma_f32 v[156:157], v[172:173], v[140:141], v[156:157]
	v_pk_fma_f32 v[158:159], v[174:175], v[142:143], v[158:159]
	v_pk_mul_f32 v[252:253], v[144:145], v[144:145]
	v_pk_mul_f32 v[254:255], v[146:147], v[146:147]
	v_pk_fma_f32 v[252:253], v[148:149], v[148:149], v[252:253]
	v_pk_fma_f32 v[254:255], v[150:151], v[150:151], v[254:255]
	v_pk_fma_f32 v[252:253], v[152:153], v[152:153], v[252:253]
	v_pk_fma_f32 v[254:255], v[154:155], v[154:155], v[254:255]
	v_pk_fma_f32 v[252:253], v[156:157], v[156:157], v[252:253]
	v_pk_fma_f32 v[254:255], v[158:159], v[158:159], v[254:255]
	v_pk_add_f32 v[252:253], v[252:253], v[254:255]
	s_nop 0
	v_add_f32_e32 v183, v252, v253
	s_nop 1
	v_add_f32_dpp v183, v183, v183 quad_perm:[1,0,3,2] row_mask:0xf bank_mask:0xf bound_ctrl:1
	s_nop 1
	v_add_f32_dpp v183, v183, v183 quad_perm:[2,3,0,1] row_mask:0xf bank_mask:0xf bound_ctrl:1
	s_nop 1
	v_add_f32_dpp v183, v183, v183 row_half_mirror row_mask:0xf bank_mask:0xf bound_ctrl:1
	s_nop 1
	v_add_f32_dpp v183, v183, v183 row_mirror row_mask:0xf bank_mask:0xf bound_ctrl:1
	s_nop 1
	v_readlane_b32 s98, v183, 0
	v_readlane_b32 s99, v183, 16
	v_readlane_b32 s100, v183, 32
	v_readlane_b32 s101, v183, 48
	s_nop 1
	v_mov_b32_e32 v183, s98
	v_add_f32_e32 v183, s99, v183
	v_add_f32_e32 v183, s100, v183
	v_add_f32_e32 v183, s101, v183
	v_fmamk_f32 v183, v183, 0x3a800000, v182
	v_cmp_gt_f32_e32 vcc, 0x800000, v183
	v_mul_f32_e32 v181, 0x4b800000, v183
	s_nop 1
	v_cndmask_b32_e32 v183, v183, v181, vcc
	v_rsq_f32_e32 v183, v183
	s_nop 0
	v_mul_f32_e32 v181, 0x45800000, v183
	v_cndmask_b32_e32 v184, v183, v181, vcc
	v_mov_b32_e32 v185, v184
	v_cvt_pk_bf16_f32 v0, v144, v145
	v_cvt_pk_bf16_f32 v1, v146, v147
	v_cvt_pk_bf16_f32 v2, v148, v149
	v_cvt_pk_bf16_f32 v3, v150, v151
	v_cvt_pk_bf16_f32 v4, v152, v153
	v_cvt_pk_bf16_f32 v5, v154, v155
	v_cvt_pk_bf16_f32 v6, v156, v157
	v_cvt_pk_bf16_f32 v7, v158, v159
	v_add_u32_e32 v181, 0x1800000, v177
	global_store_dwordx4 v181, v[0:3], s[78:79]
	global_store_dwordx4 v181, v[4:7], s[78:79] offset:1024
	v_add_u32_e32 v236, 0x0, v237
	s_mov_b64 exec, 1
	global_store_dword v236, v184, s[78:79]
	s_mov_b64 exec, -1
	s_waitcnt vmcnt(24)
	v_lshlrev_b32_e32 v144, 16, v16
	v_and_b32_e32 v145, 0xffff0000, v16
	v_lshlrev_b32_e32 v146, 16, v17
	v_and_b32_e32 v147, 0xffff0000, v17
	v_lshlrev_b32_e32 v148, 16, v18
	v_and_b32_e32 v149, 0xffff0000, v18
	v_lshlrev_b32_e32 v150, 16, v19
	v_and_b32_e32 v151, 0xffff0000, v19
	v_lshlrev_b32_e32 v152, 16, v20
	v_and_b32_e32 v153, 0xffff0000, v20
	v_lshlrev_b32_e32 v154, 16, v21
	v_and_b32_e32 v155, 0xffff0000, v21
	v_lshlrev_b32_e32 v156, 16, v22
	v_and_b32_e32 v157, 0xffff0000, v22
	v_lshlrev_b32_e32 v158, 16, v23
	v_and_b32_e32 v159, 0xffff0000, v23
	v_lshlrev_b32_e32 v160, 16, v24
	v_and_b32_e32 v161, 0xffff0000, v24
	v_lshlrev_b32_e32 v162, 16, v25
	v_and_b32_e32 v163, 0xffff0000, v25
	v_lshlrev_b32_e32 v164, 16, v26
	v_and_b32_e32 v165, 0xffff0000, v26
	v_lshlrev_b32_e32 v166, 16, v27
	v_and_b32_e32 v167, 0xffff0000, v27
	v_lshlrev_b32_e32 v168, 16, v28
	v_and_b32_e32 v169, 0xffff0000, v28
	v_lshlrev_b32_e32 v170, 16, v29
	v_and_b32_e32 v171, 0xffff0000, v29
	v_lshlrev_b32_e32 v172, 16, v30
	v_and_b32_e32 v173, 0xffff0000, v30
	v_lshlrev_b32_e32 v174, 16, v31
	v_and_b32_e32 v175, 0xffff0000, v31
	v_pk_mul_f32 v[252:253], v[160:161], v[160:161]
	v_pk_mul_f32 v[254:255], v[162:163], v[162:163]
	v_pk_fma_f32 v[252:253], v[164:165], v[164:165], v[252:253]
	v_pk_fma_f32 v[254:255], v[166:167], v[166:167], v[254:255]
	v_pk_fma_f32 v[252:253], v[168:169], v[168:169], v[252:253]
	v_pk_fma_f32 v[254:255], v[170:171], v[170:171], v[254:255]
	v_pk_fma_f32 v[252:253], v[172:173], v[172:173], v[252:253]
	v_pk_fma_f32 v[254:255], v[174:175], v[174:175], v[254:255]
	v_pk_add_f32 v[252:253], v[252:253], v[254:255]
	s_nop 0
	v_add_f32_e32 v183, v252, v253
	s_nop 1
	v_add_f32_dpp v183, v183, v183 quad_perm:[1,0,3,2] row_mask:0xf bank_mask:0xf bound_ctrl:1
	s_nop 1
	v_add_f32_dpp v183, v183, v183 quad_perm:[2,3,0,1] row_mask:0xf bank_mask:0xf bound_ctrl:1
	s_nop 1
	v_add_f32_dpp v183, v183, v183 row_half_mirror row_mask:0xf bank_mask:0xf bound_ctrl:1
	s_nop 1
	v_add_f32_dpp v183, v183, v183 row_mirror row_mask:0xf bank_mask:0xf bound_ctrl:1
	s_nop 1
	v_readlane_b32 s98, v183, 0
	v_readlane_b32 s99, v183, 16
	v_readlane_b32 s100, v183, 32
	v_readlane_b32 s101, v183, 48
	s_nop 1
	v_mov_b32_e32 v183, s98
	v_add_f32_e32 v183, s99, v183
	v_add_f32_e32 v183, s100, v183
	v_add_f32_e32 v183, s101, v183
	v_fmamk_f32 v183, v183, 0x3a800000, v182
	v_cmp_gt_f32_e32 vcc, 0x800000, v183
	v_mul_f32_e32 v181, 0x4b800000, v183
	s_nop 1
	v_cndmask_b32_e32 v183, v183, v181, vcc
	v_rsq_f32_e32 v183, v183
	s_nop 0
	v_mul_f32_e32 v181, 0x45800000, v183
	v_cndmask_b32_e32 v184, v183, v181, vcc
	v_mov_b32_e32 v185, v184
	v_pk_mul_f32 v[160:161], v[160:161], v[184:185]
	v_pk_mul_f32 v[162:163], v[162:163], v[184:185]
	v_pk_mul_f32 v[164:165], v[164:165], v[184:185]
	v_pk_mul_f32 v[166:167], v[166:167], v[184:185]
	v_pk_mul_f32 v[168:169], v[168:169], v[184:185]
	v_pk_mul_f32 v[170:171], v[170:171], v[184:185]
	v_pk_mul_f32 v[172:173], v[172:173], v[184:185]
	v_pk_mul_f32 v[174:175], v[174:175], v[184:185]
	v_pk_fma_f32 v[144:145], v[160:161], v[128:129], v[144:145]
	v_pk_fma_f32 v[146:147], v[162:163], v[130:131], v[146:147]
	v_pk_fma_f32 v[148:149], v[164:165], v[132:133], v[148:149]
	v_pk_fma_f32 v[150:151], v[166:167], v[134:135], v[150:151]
	v_pk_fma_f32 v[152:153], v[168:169], v[136:137], v[152:153]
	v_pk_fma_f32 v[154:155], v[170:171], v[138:139], v[154:155]
	v_pk_fma_f32 v[156:157], v[172:173], v[140:141], v[156:157]
	v_pk_fma_f32 v[158:159], v[174:175], v[142:143], v[158:159]
	v_pk_mul_f32 v[252:253], v[144:145], v[144:145]
	v_pk_mul_f32 v[254:255], v[146:147], v[146:147]
	v_pk_fma_f32 v[252:253], v[148:149], v[148:149], v[252:253]
	v_pk_fma_f32 v[254:255], v[150:151], v[150:151], v[254:255]
	v_pk_fma_f32 v[252:253], v[152:153], v[152:153], v[252:253]
	v_pk_fma_f32 v[254:255], v[154:155], v[154:155], v[254:255]
	v_pk_fma_f32 v[252:253], v[156:157], v[156:157], v[252:253]
	v_pk_fma_f32 v[254:255], v[158:159], v[158:159], v[254:255]
	v_pk_add_f32 v[252:253], v[252:253], v[254:255]
	s_nop 0
	v_add_f32_e32 v183, v252, v253
	s_nop 1
	v_add_f32_dpp v183, v183, v183 quad_perm:[1,0,3,2] row_mask:0xf bank_mask:0xf bound_ctrl:1
	s_nop 1
	v_add_f32_dpp v183, v183, v183 quad_perm:[2,3,0,1] row_mask:0xf bank_mask:0xf bound_ctrl:1
	s_nop 1
	v_add_f32_dpp v183, v183, v183 row_half_mirror row_mask:0xf bank_mask:0xf bound_ctrl:1
	s_nop 1
	v_add_f32_dpp v183, v183, v183 row_mirror row_mask:0xf bank_mask:0xf bound_ctrl:1
	s_nop 1
	v_readlane_b32 s98, v183, 0
	v_readlane_b32 s99, v183, 16
	v_readlane_b32 s100, v183, 32
	v_readlane_b32 s101, v183, 48
	s_nop 1
	v_mov_b32_e32 v183, s98
	v_add_f32_e32 v183, s99, v183
	v_add_f32_e32 v183, s100, v183
	v_add_f32_e32 v183, s101, v183
	v_fmamk_f32 v183, v183, 0x3a800000, v182
	v_cmp_gt_f32_e32 vcc, 0x800000, v183
	v_mul_f32_e32 v181, 0x4b800000, v183
	s_nop 1
	v_cndmask_b32_e32 v183, v183, v181, vcc
	v_rsq_f32_e32 v183, v183
	s_nop 0
	v_mul_f32_e32 v181, 0x45800000, v183
	v_cndmask_b32_e32 v184, v183, v181, vcc
	v_mov_b32_e32 v185, v184
	v_cvt_pk_bf16_f32 v16, v144, v145
	v_cvt_pk_bf16_f32 v17, v146, v147
	v_cvt_pk_bf16_f32 v18, v148, v149
	v_cvt_pk_bf16_f32 v19, v150, v151
	v_cvt_pk_bf16_f32 v20, v152, v153
	v_cvt_pk_bf16_f32 v21, v154, v155
	v_cvt_pk_bf16_f32 v22, v156, v157
	v_cvt_pk_bf16_f32 v23, v158, v159
	v_add_u32_e32 v181, 0x1c00000, v177
	global_store_dwordx4 v181, v[16:19], s[78:79]
	global_store_dwordx4 v181, v[20:23], s[78:79] offset:1024
	v_add_u32_e32 v236, 0x2000, v237
	s_mov_b64 exec, 1
	global_store_dword v236, v184, s[78:79]
	s_mov_b64 exec, -1
	s_waitcnt vmcnt(20)
	v_lshlrev_b32_e32 v144, 16, v32
	v_and_b32_e32 v145, 0xffff0000, v32
	v_lshlrev_b32_e32 v146, 16, v33
	v_and_b32_e32 v147, 0xffff0000, v33
	v_lshlrev_b32_e32 v148, 16, v34
	v_and_b32_e32 v149, 0xffff0000, v34
	v_lshlrev_b32_e32 v150, 16, v35
	v_and_b32_e32 v151, 0xffff0000, v35
	v_lshlrev_b32_e32 v152, 16, v36
	v_and_b32_e32 v153, 0xffff0000, v36
	v_lshlrev_b32_e32 v154, 16, v37
	v_and_b32_e32 v155, 0xffff0000, v37
	v_lshlrev_b32_e32 v156, 16, v38
	v_and_b32_e32 v157, 0xffff0000, v38
	v_lshlrev_b32_e32 v158, 16, v39
	v_and_b32_e32 v159, 0xffff0000, v39
	v_lshlrev_b32_e32 v160, 16, v40
	v_and_b32_e32 v161, 0xffff0000, v40
	v_lshlrev_b32_e32 v162, 16, v41
	v_and_b32_e32 v163, 0xffff0000, v41
	v_lshlrev_b32_e32 v164, 16, v42
	v_and_b32_e32 v165, 0xffff0000, v42
	v_lshlrev_b32_e32 v166, 16, v43
	v_and_b32_e32 v167, 0xffff0000, v43
	v_lshlrev_b32_e32 v168, 16, v44
	v_and_b32_e32 v169, 0xffff0000, v44
	v_lshlrev_b32_e32 v170, 16, v45
	v_and_b32_e32 v171, 0xffff0000, v45
	v_lshlrev_b32_e32 v172, 16, v46
	v_and_b32_e32 v173, 0xffff0000, v46
	v_lshlrev_b32_e32 v174, 16, v47
	v_and_b32_e32 v175, 0xffff0000, v47
	v_pk_mul_f32 v[252:253], v[160:161], v[160:161]
	v_pk_mul_f32 v[254:255], v[162:163], v[162:163]
	v_pk_fma_f32 v[252:253], v[164:165], v[164:165], v[252:253]
	v_pk_fma_f32 v[254:255], v[166:167], v[166:167], v[254:255]
	v_pk_fma_f32 v[252:253], v[168:169], v[168:169], v[252:253]
	v_pk_fma_f32 v[254:255], v[170:171], v[170:171], v[254:255]
	v_pk_fma_f32 v[252:253], v[172:173], v[172:173], v[252:253]
	v_pk_fma_f32 v[254:255], v[174:175], v[174:175], v[254:255]
	v_pk_add_f32 v[252:253], v[252:253], v[254:255]
	s_nop 0
	v_add_f32_e32 v183, v252, v253
	s_nop 1
	v_add_f32_dpp v183, v183, v183 quad_perm:[1,0,3,2] row_mask:0xf bank_mask:0xf bound_ctrl:1
	s_nop 1
	v_add_f32_dpp v183, v183, v183 quad_perm:[2,3,0,1] row_mask:0xf bank_mask:0xf bound_ctrl:1
	s_nop 1
	v_add_f32_dpp v183, v183, v183 row_half_mirror row_mask:0xf bank_mask:0xf bound_ctrl:1
	s_nop 1
	v_add_f32_dpp v183, v183, v183 row_mirror row_mask:0xf bank_mask:0xf bound_ctrl:1
	s_nop 1
	v_readlane_b32 s98, v183, 0
	v_readlane_b32 s99, v183, 16
	v_readlane_b32 s100, v183, 32
	v_readlane_b32 s101, v183, 48
	s_nop 1
	v_mov_b32_e32 v183, s98
	v_add_f32_e32 v183, s99, v183
	v_add_f32_e32 v183, s100, v183
	v_add_f32_e32 v183, s101, v183
	v_fmamk_f32 v183, v183, 0x3a800000, v182
	v_cmp_gt_f32_e32 vcc, 0x800000, v183
	v_mul_f32_e32 v181, 0x4b800000, v183
	s_nop 1
	v_cndmask_b32_e32 v183, v183, v181, vcc
	v_rsq_f32_e32 v183, v183
	s_nop 0
	v_mul_f32_e32 v181, 0x45800000, v183
	v_cndmask_b32_e32 v184, v183, v181, vcc
	v_mov_b32_e32 v185, v184
	v_pk_mul_f32 v[160:161], v[160:161], v[184:185]
	v_pk_mul_f32 v[162:163], v[162:163], v[184:185]
	v_pk_mul_f32 v[164:165], v[164:165], v[184:185]
	v_pk_mul_f32 v[166:167], v[166:167], v[184:185]
	v_pk_mul_f32 v[168:169], v[168:169], v[184:185]
	v_pk_mul_f32 v[170:171], v[170:171], v[184:185]
	v_pk_mul_f32 v[172:173], v[172:173], v[184:185]
	v_pk_mul_f32 v[174:175], v[174:175], v[184:185]
	v_pk_fma_f32 v[144:145], v[160:161], v[128:129], v[144:145]
	v_pk_fma_f32 v[146:147], v[162:163], v[130:131], v[146:147]
	v_pk_fma_f32 v[148:149], v[164:165], v[132:133], v[148:149]
	v_pk_fma_f32 v[150:151], v[166:167], v[134:135], v[150:151]
	v_pk_fma_f32 v[152:153], v[168:169], v[136:137], v[152:153]
	v_pk_fma_f32 v[154:155], v[170:171], v[138:139], v[154:155]
	v_pk_fma_f32 v[156:157], v[172:173], v[140:141], v[156:157]
	v_pk_fma_f32 v[158:159], v[174:175], v[142:143], v[158:159]
	v_pk_mul_f32 v[252:253], v[144:145], v[144:145]
	v_pk_mul_f32 v[254:255], v[146:147], v[146:147]
	v_pk_fma_f32 v[252:253], v[148:149], v[148:149], v[252:253]
	v_pk_fma_f32 v[254:255], v[150:151], v[150:151], v[254:255]
	v_pk_fma_f32 v[252:253], v[152:153], v[152:153], v[252:253]
	v_pk_fma_f32 v[254:255], v[154:155], v[154:155], v[254:255]
	v_pk_fma_f32 v[252:253], v[156:157], v[156:157], v[252:253]
	v_pk_fma_f32 v[254:255], v[158:159], v[158:159], v[254:255]
	v_pk_add_f32 v[252:253], v[252:253], v[254:255]
	s_nop 0
	v_add_f32_e32 v183, v252, v253
	s_nop 1
	v_add_f32_dpp v183, v183, v183 quad_perm:[1,0,3,2] row_mask:0xf bank_mask:0xf bound_ctrl:1
	s_nop 1
	v_add_f32_dpp v183, v183, v183 quad_perm:[2,3,0,1] row_mask:0xf bank_mask:0xf bound_ctrl:1
	s_nop 1
	v_add_f32_dpp v183, v183, v183 row_half_mirror row_mask:0xf bank_mask:0xf bound_ctrl:1
	s_nop 1
	v_add_f32_dpp v183, v183, v183 row_mirror row_mask:0xf bank_mask:0xf bound_ctrl:1
	s_nop 1
	v_readlane_b32 s98, v183, 0
	v_readlane_b32 s99, v183, 16
	v_readlane_b32 s100, v183, 32
	v_readlane_b32 s101, v183, 48
	s_nop 1
	v_mov_b32_e32 v183, s98
	v_add_f32_e32 v183, s99, v183
	v_add_f32_e32 v183, s100, v183
	v_add_f32_e32 v183, s101, v183
	v_fmamk_f32 v183, v183, 0x3a800000, v182
	v_cmp_gt_f32_e32 vcc, 0x800000, v183
	v_mul_f32_e32 v181, 0x4b800000, v183
	s_nop 1
	v_cndmask_b32_e32 v183, v183, v181, vcc
	v_rsq_f32_e32 v183, v183
	s_nop 0
	v_mul_f32_e32 v181, 0x45800000, v183
	v_cndmask_b32_e32 v184, v183, v181, vcc
	v_mov_b32_e32 v185, v184
	v_cvt_pk_bf16_f32 v32, v144, v145
	v_cvt_pk_bf16_f32 v33, v146, v147
	v_cvt_pk_bf16_f32 v34, v148, v149
	v_cvt_pk_bf16_f32 v35, v150, v151
	v_cvt_pk_bf16_f32 v36, v152, v153
	v_cvt_pk_bf16_f32 v37, v154, v155
	v_cvt_pk_bf16_f32 v38, v156, v157
	v_cvt_pk_bf16_f32 v39, v158, v159
	v_add_u32_e32 v181, 0x2000000, v177
	global_store_dwordx4 v181, v[32:35], s[78:79]
	global_store_dwordx4 v181, v[36:39], s[78:79] offset:1024
	v_add_u32_e32 v236, 0x4000, v237
	s_mov_b64 exec, 1
	global_store_dword v236, v184, s[78:79]
	s_mov_b64 exec, -1
	s_waitcnt vmcnt(16)
	v_lshlrev_b32_e32 v144, 16, v48
	v_and_b32_e32 v145, 0xffff0000, v48
	v_lshlrev_b32_e32 v146, 16, v49
	v_and_b32_e32 v147, 0xffff0000, v49
	v_lshlrev_b32_e32 v148, 16, v50
	v_and_b32_e32 v149, 0xffff0000, v50
	v_lshlrev_b32_e32 v150, 16, v51
	v_and_b32_e32 v151, 0xffff0000, v51
	v_lshlrev_b32_e32 v152, 16, v52
	v_and_b32_e32 v153, 0xffff0000, v52
	v_lshlrev_b32_e32 v154, 16, v53
	v_and_b32_e32 v155, 0xffff0000, v53
	v_lshlrev_b32_e32 v156, 16, v54
	v_and_b32_e32 v157, 0xffff0000, v54
	v_lshlrev_b32_e32 v158, 16, v55
	v_and_b32_e32 v159, 0xffff0000, v55
	v_lshlrev_b32_e32 v160, 16, v56
	v_and_b32_e32 v161, 0xffff0000, v56
	v_lshlrev_b32_e32 v162, 16, v57
	v_and_b32_e32 v163, 0xffff0000, v57
	v_lshlrev_b32_e32 v164, 16, v58
	v_and_b32_e32 v165, 0xffff0000, v58
	v_lshlrev_b32_e32 v166, 16, v59
	v_and_b32_e32 v167, 0xffff0000, v59
	v_lshlrev_b32_e32 v168, 16, v60
	v_and_b32_e32 v169, 0xffff0000, v60
	v_lshlrev_b32_e32 v170, 16, v61
	v_and_b32_e32 v171, 0xffff0000, v61
	v_lshlrev_b32_e32 v172, 16, v62
	v_and_b32_e32 v173, 0xffff0000, v62
	v_lshlrev_b32_e32 v174, 16, v63
	v_and_b32_e32 v175, 0xffff0000, v63
	v_pk_mul_f32 v[252:253], v[160:161], v[160:161]
	v_pk_mul_f32 v[254:255], v[162:163], v[162:163]
	v_pk_fma_f32 v[252:253], v[164:165], v[164:165], v[252:253]
	v_pk_fma_f32 v[254:255], v[166:167], v[166:167], v[254:255]
	v_pk_fma_f32 v[252:253], v[168:169], v[168:169], v[252:253]
	v_pk_fma_f32 v[254:255], v[170:171], v[170:171], v[254:255]
	v_pk_fma_f32 v[252:253], v[172:173], v[172:173], v[252:253]
	v_pk_fma_f32 v[254:255], v[174:175], v[174:175], v[254:255]
	v_pk_add_f32 v[252:253], v[252:253], v[254:255]
	s_nop 0
	v_add_f32_e32 v183, v252, v253
	s_nop 1
	v_add_f32_dpp v183, v183, v183 quad_perm:[1,0,3,2] row_mask:0xf bank_mask:0xf bound_ctrl:1
	s_nop 1
	v_add_f32_dpp v183, v183, v183 quad_perm:[2,3,0,1] row_mask:0xf bank_mask:0xf bound_ctrl:1
	s_nop 1
	v_add_f32_dpp v183, v183, v183 row_half_mirror row_mask:0xf bank_mask:0xf bound_ctrl:1
	s_nop 1
	v_add_f32_dpp v183, v183, v183 row_mirror row_mask:0xf bank_mask:0xf bound_ctrl:1
	s_nop 1
	v_readlane_b32 s98, v183, 0
	v_readlane_b32 s99, v183, 16
	v_readlane_b32 s100, v183, 32
	v_readlane_b32 s101, v183, 48
	s_nop 1
	v_mov_b32_e32 v183, s98
	v_add_f32_e32 v183, s99, v183
	v_add_f32_e32 v183, s100, v183
	v_add_f32_e32 v183, s101, v183
	v_fmamk_f32 v183, v183, 0x3a800000, v182
	v_cmp_gt_f32_e32 vcc, 0x800000, v183
	v_mul_f32_e32 v181, 0x4b800000, v183
	s_nop 1
	v_cndmask_b32_e32 v183, v183, v181, vcc
	v_rsq_f32_e32 v183, v183
	s_nop 0
	v_mul_f32_e32 v181, 0x45800000, v183
	v_cndmask_b32_e32 v184, v183, v181, vcc
	v_mov_b32_e32 v185, v184
	v_pk_mul_f32 v[160:161], v[160:161], v[184:185]
	v_pk_mul_f32 v[162:163], v[162:163], v[184:185]
	v_pk_mul_f32 v[164:165], v[164:165], v[184:185]
	v_pk_mul_f32 v[166:167], v[166:167], v[184:185]
	v_pk_mul_f32 v[168:169], v[168:169], v[184:185]
	v_pk_mul_f32 v[170:171], v[170:171], v[184:185]
	v_pk_mul_f32 v[172:173], v[172:173], v[184:185]
	v_pk_mul_f32 v[174:175], v[174:175], v[184:185]
	v_pk_fma_f32 v[144:145], v[160:161], v[128:129], v[144:145]
	v_pk_fma_f32 v[146:147], v[162:163], v[130:131], v[146:147]
	v_pk_fma_f32 v[148:149], v[164:165], v[132:133], v[148:149]
	v_pk_fma_f32 v[150:151], v[166:167], v[134:135], v[150:151]
	v_pk_fma_f32 v[152:153], v[168:169], v[136:137], v[152:153]
	v_pk_fma_f32 v[154:155], v[170:171], v[138:139], v[154:155]
	v_pk_fma_f32 v[156:157], v[172:173], v[140:141], v[156:157]
	v_pk_fma_f32 v[158:159], v[174:175], v[142:143], v[158:159]
	v_pk_mul_f32 v[252:253], v[144:145], v[144:145]
	v_pk_mul_f32 v[254:255], v[146:147], v[146:147]
	v_pk_fma_f32 v[252:253], v[148:149], v[148:149], v[252:253]
	v_pk_fma_f32 v[254:255], v[150:151], v[150:151], v[254:255]
	v_pk_fma_f32 v[252:253], v[152:153], v[152:153], v[252:253]
	v_pk_fma_f32 v[254:255], v[154:155], v[154:155], v[254:255]
	v_pk_fma_f32 v[252:253], v[156:157], v[156:157], v[252:253]
	v_pk_fma_f32 v[254:255], v[158:159], v[158:159], v[254:255]
	v_pk_add_f32 v[252:253], v[252:253], v[254:255]
	s_nop 0
	v_add_f32_e32 v183, v252, v253
	s_nop 1
	v_add_f32_dpp v183, v183, v183 quad_perm:[1,0,3,2] row_mask:0xf bank_mask:0xf bound_ctrl:1
	s_nop 1
	v_add_f32_dpp v183, v183, v183 quad_perm:[2,3,0,1] row_mask:0xf bank_mask:0xf bound_ctrl:1
	s_nop 1
	v_add_f32_dpp v183, v183, v183 row_half_mirror row_mask:0xf bank_mask:0xf bound_ctrl:1
	s_nop 1
	v_add_f32_dpp v183, v183, v183 row_mirror row_mask:0xf bank_mask:0xf bound_ctrl:1
	s_nop 1
	v_readlane_b32 s98, v183, 0
	v_readlane_b32 s99, v183, 16
	v_readlane_b32 s100, v183, 32
	v_readlane_b32 s101, v183, 48
	s_nop 1
	v_mov_b32_e32 v183, s98
	v_add_f32_e32 v183, s99, v183
	v_add_f32_e32 v183, s100, v183
	v_add_f32_e32 v183, s101, v183
	v_fmamk_f32 v183, v183, 0x3a800000, v182
	v_cmp_gt_f32_e32 vcc, 0x800000, v183
	v_mul_f32_e32 v181, 0x4b800000, v183
	s_nop 1
	v_cndmask_b32_e32 v183, v183, v181, vcc
	v_rsq_f32_e32 v183, v183
	s_nop 0
	v_mul_f32_e32 v181, 0x45800000, v183
	v_cndmask_b32_e32 v184, v183, v181, vcc
	v_mov_b32_e32 v185, v184
	v_cvt_pk_bf16_f32 v48, v144, v145
	v_cvt_pk_bf16_f32 v49, v146, v147
	v_cvt_pk_bf16_f32 v50, v148, v149
	v_cvt_pk_bf16_f32 v51, v150, v151
	v_cvt_pk_bf16_f32 v52, v152, v153
	v_cvt_pk_bf16_f32 v53, v154, v155
	v_cvt_pk_bf16_f32 v54, v156, v157
	v_cvt_pk_bf16_f32 v55, v158, v159
	v_add_u32_e32 v181, 0x2400000, v177
	global_store_dwordx4 v181, v[48:51], s[78:79]
	global_store_dwordx4 v181, v[52:55], s[78:79] offset:1024
	v_add_u32_e32 v236, 0x6000, v237
	s_mov_b64 exec, 1
	global_store_dword v236, v184, s[78:79]
	s_mov_b64 exec, -1
	s_waitcnt vmcnt(12)
	v_lshlrev_b32_e32 v144, 16, v64
	v_and_b32_e32 v145, 0xffff0000, v64
	v_lshlrev_b32_e32 v146, 16, v65
	v_and_b32_e32 v147, 0xffff0000, v65
	v_lshlrev_b32_e32 v148, 16, v66
	v_and_b32_e32 v149, 0xffff0000, v66
	v_lshlrev_b32_e32 v150, 16, v67
	v_and_b32_e32 v151, 0xffff0000, v67
	v_lshlrev_b32_e32 v152, 16, v68
	v_and_b32_e32 v153, 0xffff0000, v68
	v_lshlrev_b32_e32 v154, 16, v69
	v_and_b32_e32 v155, 0xffff0000, v69
	v_lshlrev_b32_e32 v156, 16, v70
	v_and_b32_e32 v157, 0xffff0000, v70
	v_lshlrev_b32_e32 v158, 16, v71
	v_and_b32_e32 v159, 0xffff0000, v71
	v_lshlrev_b32_e32 v160, 16, v72
	v_and_b32_e32 v161, 0xffff0000, v72
	v_lshlrev_b32_e32 v162, 16, v73
	v_and_b32_e32 v163, 0xffff0000, v73
	v_lshlrev_b32_e32 v164, 16, v74
	v_and_b32_e32 v165, 0xffff0000, v74
	v_lshlrev_b32_e32 v166, 16, v75
	v_and_b32_e32 v167, 0xffff0000, v75
	v_lshlrev_b32_e32 v168, 16, v76
	v_and_b32_e32 v169, 0xffff0000, v76
	v_lshlrev_b32_e32 v170, 16, v77
	v_and_b32_e32 v171, 0xffff0000, v77
	v_lshlrev_b32_e32 v172, 16, v78
	v_and_b32_e32 v173, 0xffff0000, v78
	v_lshlrev_b32_e32 v174, 16, v79
	v_and_b32_e32 v175, 0xffff0000, v79
	v_pk_mul_f32 v[252:253], v[160:161], v[160:161]
	v_pk_mul_f32 v[254:255], v[162:163], v[162:163]
	v_pk_fma_f32 v[252:253], v[164:165], v[164:165], v[252:253]
	v_pk_fma_f32 v[254:255], v[166:167], v[166:167], v[254:255]
	v_pk_fma_f32 v[252:253], v[168:169], v[168:169], v[252:253]
	v_pk_fma_f32 v[254:255], v[170:171], v[170:171], v[254:255]
	v_pk_fma_f32 v[252:253], v[172:173], v[172:173], v[252:253]
	v_pk_fma_f32 v[254:255], v[174:175], v[174:175], v[254:255]
	v_pk_add_f32 v[252:253], v[252:253], v[254:255]
	s_nop 0
	v_add_f32_e32 v183, v252, v253
	s_nop 1
	v_add_f32_dpp v183, v183, v183 quad_perm:[1,0,3,2] row_mask:0xf bank_mask:0xf bound_ctrl:1
	s_nop 1
	v_add_f32_dpp v183, v183, v183 quad_perm:[2,3,0,1] row_mask:0xf bank_mask:0xf bound_ctrl:1
	s_nop 1
	v_add_f32_dpp v183, v183, v183 row_half_mirror row_mask:0xf bank_mask:0xf bound_ctrl:1
	s_nop 1
	v_add_f32_dpp v183, v183, v183 row_mirror row_mask:0xf bank_mask:0xf bound_ctrl:1
	s_nop 1
	v_readlane_b32 s98, v183, 0
	v_readlane_b32 s99, v183, 16
	v_readlane_b32 s100, v183, 32
	v_readlane_b32 s101, v183, 48
	s_nop 1
	v_mov_b32_e32 v183, s98
	v_add_f32_e32 v183, s99, v183
	v_add_f32_e32 v183, s100, v183
	v_add_f32_e32 v183, s101, v183
	v_fmamk_f32 v183, v183, 0x3a800000, v182
	v_cmp_gt_f32_e32 vcc, 0x800000, v183
	v_mul_f32_e32 v181, 0x4b800000, v183
	s_nop 1
	v_cndmask_b32_e32 v183, v183, v181, vcc
	v_rsq_f32_e32 v183, v183
	s_nop 0
	v_mul_f32_e32 v181, 0x45800000, v183
	v_cndmask_b32_e32 v184, v183, v181, vcc
	v_mov_b32_e32 v185, v184
	v_pk_mul_f32 v[160:161], v[160:161], v[184:185]
	v_pk_mul_f32 v[162:163], v[162:163], v[184:185]
	v_pk_mul_f32 v[164:165], v[164:165], v[184:185]
	v_pk_mul_f32 v[166:167], v[166:167], v[184:185]
	v_pk_mul_f32 v[168:169], v[168:169], v[184:185]
	v_pk_mul_f32 v[170:171], v[170:171], v[184:185]
	v_pk_mul_f32 v[172:173], v[172:173], v[184:185]
	v_pk_mul_f32 v[174:175], v[174:175], v[184:185]
	v_pk_fma_f32 v[144:145], v[160:161], v[128:129], v[144:145]
	v_pk_fma_f32 v[146:147], v[162:163], v[130:131], v[146:147]
	v_pk_fma_f32 v[148:149], v[164:165], v[132:133], v[148:149]
	v_pk_fma_f32 v[150:151], v[166:167], v[134:135], v[150:151]
	v_pk_fma_f32 v[152:153], v[168:169], v[136:137], v[152:153]
	v_pk_fma_f32 v[154:155], v[170:171], v[138:139], v[154:155]
	v_pk_fma_f32 v[156:157], v[172:173], v[140:141], v[156:157]
	v_pk_fma_f32 v[158:159], v[174:175], v[142:143], v[158:159]
	v_pk_mul_f32 v[252:253], v[144:145], v[144:145]
	v_pk_mul_f32 v[254:255], v[146:147], v[146:147]
	v_pk_fma_f32 v[252:253], v[148:149], v[148:149], v[252:253]
	v_pk_fma_f32 v[254:255], v[150:151], v[150:151], v[254:255]
	v_pk_fma_f32 v[252:253], v[152:153], v[152:153], v[252:253]
	v_pk_fma_f32 v[254:255], v[154:155], v[154:155], v[254:255]
	v_pk_fma_f32 v[252:253], v[156:157], v[156:157], v[252:253]
	v_pk_fma_f32 v[254:255], v[158:159], v[158:159], v[254:255]
	v_pk_add_f32 v[252:253], v[252:253], v[254:255]
	s_nop 0
	v_add_f32_e32 v183, v252, v253
	s_nop 1
	v_add_f32_dpp v183, v183, v183 quad_perm:[1,0,3,2] row_mask:0xf bank_mask:0xf bound_ctrl:1
	s_nop 1
	v_add_f32_dpp v183, v183, v183 quad_perm:[2,3,0,1] row_mask:0xf bank_mask:0xf bound_ctrl:1
	s_nop 1
	v_add_f32_dpp v183, v183, v183 row_half_mirror row_mask:0xf bank_mask:0xf bound_ctrl:1
	s_nop 1
	v_add_f32_dpp v183, v183, v183 row_mirror row_mask:0xf bank_mask:0xf bound_ctrl:1
	s_nop 1
	v_readlane_b32 s98, v183, 0
	v_readlane_b32 s99, v183, 16
	v_readlane_b32 s100, v183, 32
	v_readlane_b32 s101, v183, 48
	s_nop 1
	v_mov_b32_e32 v183, s98
	v_add_f32_e32 v183, s99, v183
	v_add_f32_e32 v183, s100, v183
	v_add_f32_e32 v183, s101, v183
	v_fmamk_f32 v183, v183, 0x3a800000, v182
	v_cmp_gt_f32_e32 vcc, 0x800000, v183
	v_mul_f32_e32 v181, 0x4b800000, v183
	s_nop 1
	v_cndmask_b32_e32 v183, v183, v181, vcc
	v_rsq_f32_e32 v183, v183
	s_nop 0
	v_mul_f32_e32 v181, 0x45800000, v183
	v_cndmask_b32_e32 v184, v183, v181, vcc
	v_mov_b32_e32 v185, v184
	v_cvt_pk_bf16_f32 v64, v144, v145
	v_cvt_pk_bf16_f32 v65, v146, v147
	v_cvt_pk_bf16_f32 v66, v148, v149
	v_cvt_pk_bf16_f32 v67, v150, v151
	v_cvt_pk_bf16_f32 v68, v152, v153
	v_cvt_pk_bf16_f32 v69, v154, v155
	v_cvt_pk_bf16_f32 v70, v156, v157
	v_cvt_pk_bf16_f32 v71, v158, v159
	v_add_u32_e32 v181, 0x2800000, v177
	global_store_dwordx4 v181, v[64:67], s[78:79]
	global_store_dwordx4 v181, v[68:71], s[78:79] offset:1024
	v_add_u32_e32 v236, 0x8000, v237
	s_mov_b64 exec, 1
	global_store_dword v236, v184, s[78:79]
	s_mov_b64 exec, -1
	s_waitcnt vmcnt(8)
	v_lshlrev_b32_e32 v144, 16, v80
	v_and_b32_e32 v145, 0xffff0000, v80
	v_lshlrev_b32_e32 v146, 16, v81
	v_and_b32_e32 v147, 0xffff0000, v81
	v_lshlrev_b32_e32 v148, 16, v82
	v_and_b32_e32 v149, 0xffff0000, v82
	v_lshlrev_b32_e32 v150, 16, v83
	v_and_b32_e32 v151, 0xffff0000, v83
	v_lshlrev_b32_e32 v152, 16, v84
	v_and_b32_e32 v153, 0xffff0000, v84
	v_lshlrev_b32_e32 v154, 16, v85
	v_and_b32_e32 v155, 0xffff0000, v85
	v_lshlrev_b32_e32 v156, 16, v86
	v_and_b32_e32 v157, 0xffff0000, v86
	v_lshlrev_b32_e32 v158, 16, v87
	v_and_b32_e32 v159, 0xffff0000, v87
	v_lshlrev_b32_e32 v160, 16, v88
	v_and_b32_e32 v161, 0xffff0000, v88
	v_lshlrev_b32_e32 v162, 16, v89
	v_and_b32_e32 v163, 0xffff0000, v89
	v_lshlrev_b32_e32 v164, 16, v90
	v_and_b32_e32 v165, 0xffff0000, v90
	v_lshlrev_b32_e32 v166, 16, v91
	v_and_b32_e32 v167, 0xffff0000, v91
	v_lshlrev_b32_e32 v168, 16, v92
	v_and_b32_e32 v169, 0xffff0000, v92
	v_lshlrev_b32_e32 v170, 16, v93
	v_and_b32_e32 v171, 0xffff0000, v93
	v_lshlrev_b32_e32 v172, 16, v94
	v_and_b32_e32 v173, 0xffff0000, v94
	v_lshlrev_b32_e32 v174, 16, v95
	v_and_b32_e32 v175, 0xffff0000, v95
	v_pk_mul_f32 v[252:253], v[160:161], v[160:161]
	v_pk_mul_f32 v[254:255], v[162:163], v[162:163]
	v_pk_fma_f32 v[252:253], v[164:165], v[164:165], v[252:253]
	v_pk_fma_f32 v[254:255], v[166:167], v[166:167], v[254:255]
	v_pk_fma_f32 v[252:253], v[168:169], v[168:169], v[252:253]
	v_pk_fma_f32 v[254:255], v[170:171], v[170:171], v[254:255]
	v_pk_fma_f32 v[252:253], v[172:173], v[172:173], v[252:253]
	v_pk_fma_f32 v[254:255], v[174:175], v[174:175], v[254:255]
	v_pk_add_f32 v[252:253], v[252:253], v[254:255]
	s_nop 0
	v_add_f32_e32 v183, v252, v253
	s_nop 1
	v_add_f32_dpp v183, v183, v183 quad_perm:[1,0,3,2] row_mask:0xf bank_mask:0xf bound_ctrl:1
	s_nop 1
	v_add_f32_dpp v183, v183, v183 quad_perm:[2,3,0,1] row_mask:0xf bank_mask:0xf bound_ctrl:1
	s_nop 1
	v_add_f32_dpp v183, v183, v183 row_half_mirror row_mask:0xf bank_mask:0xf bound_ctrl:1
	s_nop 1
	v_add_f32_dpp v183, v183, v183 row_mirror row_mask:0xf bank_mask:0xf bound_ctrl:1
	s_nop 1
	v_readlane_b32 s98, v183, 0
	v_readlane_b32 s99, v183, 16
	v_readlane_b32 s100, v183, 32
	v_readlane_b32 s101, v183, 48
	s_nop 1
	v_mov_b32_e32 v183, s98
	v_add_f32_e32 v183, s99, v183
	v_add_f32_e32 v183, s100, v183
	v_add_f32_e32 v183, s101, v183
	v_fmamk_f32 v183, v183, 0x3a800000, v182
	v_cmp_gt_f32_e32 vcc, 0x800000, v183
	v_mul_f32_e32 v181, 0x4b800000, v183
	s_nop 1
	v_cndmask_b32_e32 v183, v183, v181, vcc
	v_rsq_f32_e32 v183, v183
	s_nop 0
	v_mul_f32_e32 v181, 0x45800000, v183
	v_cndmask_b32_e32 v184, v183, v181, vcc
	v_mov_b32_e32 v185, v184
	v_pk_mul_f32 v[160:161], v[160:161], v[184:185]
	v_pk_mul_f32 v[162:163], v[162:163], v[184:185]
	v_pk_mul_f32 v[164:165], v[164:165], v[184:185]
	v_pk_mul_f32 v[166:167], v[166:167], v[184:185]
	v_pk_mul_f32 v[168:169], v[168:169], v[184:185]
	v_pk_mul_f32 v[170:171], v[170:171], v[184:185]
	v_pk_mul_f32 v[172:173], v[172:173], v[184:185]
	v_pk_mul_f32 v[174:175], v[174:175], v[184:185]
	v_pk_fma_f32 v[144:145], v[160:161], v[128:129], v[144:145]
	v_pk_fma_f32 v[146:147], v[162:163], v[130:131], v[146:147]
	v_pk_fma_f32 v[148:149], v[164:165], v[132:133], v[148:149]
	v_pk_fma_f32 v[150:151], v[166:167], v[134:135], v[150:151]
	v_pk_fma_f32 v[152:153], v[168:169], v[136:137], v[152:153]
	v_pk_fma_f32 v[154:155], v[170:171], v[138:139], v[154:155]
	v_pk_fma_f32 v[156:157], v[172:173], v[140:141], v[156:157]
	v_pk_fma_f32 v[158:159], v[174:175], v[142:143], v[158:159]
	v_pk_mul_f32 v[252:253], v[144:145], v[144:145]
	v_pk_mul_f32 v[254:255], v[146:147], v[146:147]
	v_pk_fma_f32 v[252:253], v[148:149], v[148:149], v[252:253]
	v_pk_fma_f32 v[254:255], v[150:151], v[150:151], v[254:255]
	v_pk_fma_f32 v[252:253], v[152:153], v[152:153], v[252:253]
	v_pk_fma_f32 v[254:255], v[154:155], v[154:155], v[254:255]
	v_pk_fma_f32 v[252:253], v[156:157], v[156:157], v[252:253]
	v_pk_fma_f32 v[254:255], v[158:159], v[158:159], v[254:255]
	v_pk_add_f32 v[252:253], v[252:253], v[254:255]
	s_nop 0
	v_add_f32_e32 v183, v252, v253
	s_nop 1
	v_add_f32_dpp v183, v183, v183 quad_perm:[1,0,3,2] row_mask:0xf bank_mask:0xf bound_ctrl:1
	s_nop 1
	v_add_f32_dpp v183, v183, v183 quad_perm:[2,3,0,1] row_mask:0xf bank_mask:0xf bound_ctrl:1
	s_nop 1
	v_add_f32_dpp v183, v183, v183 row_half_mirror row_mask:0xf bank_mask:0xf bound_ctrl:1
	s_nop 1
	v_add_f32_dpp v183, v183, v183 row_mirror row_mask:0xf bank_mask:0xf bound_ctrl:1
	s_nop 1
	v_readlane_b32 s98, v183, 0
	v_readlane_b32 s99, v183, 16
	v_readlane_b32 s100, v183, 32
	v_readlane_b32 s101, v183, 48
	s_nop 1
	v_mov_b32_e32 v183, s98
	v_add_f32_e32 v183, s99, v183
	v_add_f32_e32 v183, s100, v183
	v_add_f32_e32 v183, s101, v183
	v_fmamk_f32 v183, v183, 0x3a800000, v182
	v_cmp_gt_f32_e32 vcc, 0x800000, v183
	v_mul_f32_e32 v181, 0x4b800000, v183
	s_nop 1
	v_cndmask_b32_e32 v183, v183, v181, vcc
	v_rsq_f32_e32 v183, v183
	s_nop 0
	v_mul_f32_e32 v181, 0x45800000, v183
	v_cndmask_b32_e32 v184, v183, v181, vcc
	v_mov_b32_e32 v185, v184
	v_cvt_pk_bf16_f32 v80, v144, v145
	v_cvt_pk_bf16_f32 v81, v146, v147
	v_cvt_pk_bf16_f32 v82, v148, v149
	v_cvt_pk_bf16_f32 v83, v150, v151
	v_cvt_pk_bf16_f32 v84, v152, v153
	v_cvt_pk_bf16_f32 v85, v154, v155
	v_cvt_pk_bf16_f32 v86, v156, v157
	v_cvt_pk_bf16_f32 v87, v158, v159
	v_add_u32_e32 v181, 0x2c00000, v177
	global_store_dwordx4 v181, v[80:83], s[78:79]
	global_store_dwordx4 v181, v[84:87], s[78:79] offset:1024
	v_add_u32_e32 v236, 0xa000, v237
	s_mov_b64 exec, 1
	global_store_dword v236, v184, s[78:79]
	s_mov_b64 exec, -1
	s_waitcnt vmcnt(4)
	v_lshlrev_b32_e32 v144, 16, v96
	v_and_b32_e32 v145, 0xffff0000, v96
	v_lshlrev_b32_e32 v146, 16, v97
	v_and_b32_e32 v147, 0xffff0000, v97
	v_lshlrev_b32_e32 v148, 16, v98
	v_and_b32_e32 v149, 0xffff0000, v98
	v_lshlrev_b32_e32 v150, 16, v99
	v_and_b32_e32 v151, 0xffff0000, v99
	v_lshlrev_b32_e32 v152, 16, v100
	v_and_b32_e32 v153, 0xffff0000, v100
	v_lshlrev_b32_e32 v154, 16, v101
	v_and_b32_e32 v155, 0xffff0000, v101
	v_lshlrev_b32_e32 v156, 16, v102
	v_and_b32_e32 v157, 0xffff0000, v102
	v_lshlrev_b32_e32 v158, 16, v103
	v_and_b32_e32 v159, 0xffff0000, v103
	v_lshlrev_b32_e32 v160, 16, v104
	v_and_b32_e32 v161, 0xffff0000, v104
	v_lshlrev_b32_e32 v162, 16, v105
	v_and_b32_e32 v163, 0xffff0000, v105
	v_lshlrev_b32_e32 v164, 16, v106
	v_and_b32_e32 v165, 0xffff0000, v106
	v_lshlrev_b32_e32 v166, 16, v107
	v_and_b32_e32 v167, 0xffff0000, v107
	v_lshlrev_b32_e32 v168, 16, v108
	v_and_b32_e32 v169, 0xffff0000, v108
	v_lshlrev_b32_e32 v170, 16, v109
	v_and_b32_e32 v171, 0xffff0000, v109
	v_lshlrev_b32_e32 v172, 16, v110
	v_and_b32_e32 v173, 0xffff0000, v110
	v_lshlrev_b32_e32 v174, 16, v111
	v_and_b32_e32 v175, 0xffff0000, v111
	v_pk_mul_f32 v[252:253], v[160:161], v[160:161]
	v_pk_mul_f32 v[254:255], v[162:163], v[162:163]
	v_pk_fma_f32 v[252:253], v[164:165], v[164:165], v[252:253]
	v_pk_fma_f32 v[254:255], v[166:167], v[166:167], v[254:255]
	v_pk_fma_f32 v[252:253], v[168:169], v[168:169], v[252:253]
	v_pk_fma_f32 v[254:255], v[170:171], v[170:171], v[254:255]
	v_pk_fma_f32 v[252:253], v[172:173], v[172:173], v[252:253]
	v_pk_fma_f32 v[254:255], v[174:175], v[174:175], v[254:255]
	v_pk_add_f32 v[252:253], v[252:253], v[254:255]
	s_nop 0
	v_add_f32_e32 v183, v252, v253
	s_nop 1
	v_add_f32_dpp v183, v183, v183 quad_perm:[1,0,3,2] row_mask:0xf bank_mask:0xf bound_ctrl:1
	s_nop 1
	v_add_f32_dpp v183, v183, v183 quad_perm:[2,3,0,1] row_mask:0xf bank_mask:0xf bound_ctrl:1
	s_nop 1
	v_add_f32_dpp v183, v183, v183 row_half_mirror row_mask:0xf bank_mask:0xf bound_ctrl:1
	s_nop 1
	v_add_f32_dpp v183, v183, v183 row_mirror row_mask:0xf bank_mask:0xf bound_ctrl:1
	s_nop 1
	v_readlane_b32 s98, v183, 0
	v_readlane_b32 s99, v183, 16
	v_readlane_b32 s100, v183, 32
	v_readlane_b32 s101, v183, 48
	s_nop 1
	v_mov_b32_e32 v183, s98
	v_add_f32_e32 v183, s99, v183
	v_add_f32_e32 v183, s100, v183
	v_add_f32_e32 v183, s101, v183
	v_fmamk_f32 v183, v183, 0x3a800000, v182
	v_cmp_gt_f32_e32 vcc, 0x800000, v183
	v_mul_f32_e32 v181, 0x4b800000, v183
	s_nop 1
	v_cndmask_b32_e32 v183, v183, v181, vcc
	v_rsq_f32_e32 v183, v183
	s_nop 0
	v_mul_f32_e32 v181, 0x45800000, v183
	v_cndmask_b32_e32 v184, v183, v181, vcc
	v_mov_b32_e32 v185, v184
	v_pk_mul_f32 v[160:161], v[160:161], v[184:185]
	v_pk_mul_f32 v[162:163], v[162:163], v[184:185]
	v_pk_mul_f32 v[164:165], v[164:165], v[184:185]
	v_pk_mul_f32 v[166:167], v[166:167], v[184:185]
	v_pk_mul_f32 v[168:169], v[168:169], v[184:185]
	v_pk_mul_f32 v[170:171], v[170:171], v[184:185]
	v_pk_mul_f32 v[172:173], v[172:173], v[184:185]
	v_pk_mul_f32 v[174:175], v[174:175], v[184:185]
	v_pk_fma_f32 v[144:145], v[160:161], v[128:129], v[144:145]
	v_pk_fma_f32 v[146:147], v[162:163], v[130:131], v[146:147]
	v_pk_fma_f32 v[148:149], v[164:165], v[132:133], v[148:149]
	v_pk_fma_f32 v[150:151], v[166:167], v[134:135], v[150:151]
	v_pk_fma_f32 v[152:153], v[168:169], v[136:137], v[152:153]
	v_pk_fma_f32 v[154:155], v[170:171], v[138:139], v[154:155]
	v_pk_fma_f32 v[156:157], v[172:173], v[140:141], v[156:157]
	v_pk_fma_f32 v[158:159], v[174:175], v[142:143], v[158:159]
	v_pk_mul_f32 v[252:253], v[144:145], v[144:145]
	v_pk_mul_f32 v[254:255], v[146:147], v[146:147]
	v_pk_fma_f32 v[252:253], v[148:149], v[148:149], v[252:253]
	v_pk_fma_f32 v[254:255], v[150:151], v[150:151], v[254:255]
	v_pk_fma_f32 v[252:253], v[152:153], v[152:153], v[252:253]
	v_pk_fma_f32 v[254:255], v[154:155], v[154:155], v[254:255]
	v_pk_fma_f32 v[252:253], v[156:157], v[156:157], v[252:253]
	v_pk_fma_f32 v[254:255], v[158:159], v[158:159], v[254:255]
	v_pk_add_f32 v[252:253], v[252:253], v[254:255]
	s_nop 0
	v_add_f32_e32 v183, v252, v253
	s_nop 1
	v_add_f32_dpp v183, v183, v183 quad_perm:[1,0,3,2] row_mask:0xf bank_mask:0xf bound_ctrl:1
	s_nop 1
	v_add_f32_dpp v183, v183, v183 quad_perm:[2,3,0,1] row_mask:0xf bank_mask:0xf bound_ctrl:1
	s_nop 1
	v_add_f32_dpp v183, v183, v183 row_half_mirror row_mask:0xf bank_mask:0xf bound_ctrl:1
	s_nop 1
	v_add_f32_dpp v183, v183, v183 row_mirror row_mask:0xf bank_mask:0xf bound_ctrl:1
	s_nop 1
	v_readlane_b32 s98, v183, 0
	v_readlane_b32 s99, v183, 16
	v_readlane_b32 s100, v183, 32
	v_readlane_b32 s101, v183, 48
	s_nop 1
	v_mov_b32_e32 v183, s98
	v_add_f32_e32 v183, s99, v183
	v_add_f32_e32 v183, s100, v183
	v_add_f32_e32 v183, s101, v183
	v_fmamk_f32 v183, v183, 0x3a800000, v182
	v_cmp_gt_f32_e32 vcc, 0x800000, v183
	v_mul_f32_e32 v181, 0x4b800000, v183
	s_nop 1
	v_cndmask_b32_e32 v183, v183, v181, vcc
	v_rsq_f32_e32 v183, v183
	s_nop 0
	v_mul_f32_e32 v181, 0x45800000, v183
	v_cndmask_b32_e32 v184, v183, v181, vcc
	v_mov_b32_e32 v185, v184
	v_cvt_pk_bf16_f32 v96, v144, v145
	v_cvt_pk_bf16_f32 v97, v146, v147
	v_cvt_pk_bf16_f32 v98, v148, v149
	v_cvt_pk_bf16_f32 v99, v150, v151
	v_cvt_pk_bf16_f32 v100, v152, v153
	v_cvt_pk_bf16_f32 v101, v154, v155
	v_cvt_pk_bf16_f32 v102, v156, v157
	v_cvt_pk_bf16_f32 v103, v158, v159
	v_add_u32_e32 v181, 0x3000000, v177
	global_store_dwordx4 v181, v[96:99], s[78:79]
	global_store_dwordx4 v181, v[100:103], s[78:79] offset:1024
	v_add_u32_e32 v236, 0xc000, v237
	s_mov_b64 exec, 1
	global_store_dword v236, v184, s[78:79]
	s_mov_b64 exec, -1
	s_waitcnt vmcnt(0)
	v_lshlrev_b32_e32 v144, 16, v112
	v_and_b32_e32 v145, 0xffff0000, v112
	v_lshlrev_b32_e32 v146, 16, v113
	v_and_b32_e32 v147, 0xffff0000, v113
	v_lshlrev_b32_e32 v148, 16, v114
	v_and_b32_e32 v149, 0xffff0000, v114
	v_lshlrev_b32_e32 v150, 16, v115
	v_and_b32_e32 v151, 0xffff0000, v115
	v_lshlrev_b32_e32 v152, 16, v116
	v_and_b32_e32 v153, 0xffff0000, v116
	v_lshlrev_b32_e32 v154, 16, v117
	v_and_b32_e32 v155, 0xffff0000, v117
	v_lshlrev_b32_e32 v156, 16, v118
	v_and_b32_e32 v157, 0xffff0000, v118
	v_lshlrev_b32_e32 v158, 16, v119
	v_and_b32_e32 v159, 0xffff0000, v119
	v_lshlrev_b32_e32 v160, 16, v120
	v_and_b32_e32 v161, 0xffff0000, v120
	v_lshlrev_b32_e32 v162, 16, v121
	v_and_b32_e32 v163, 0xffff0000, v121
	v_lshlrev_b32_e32 v164, 16, v122
	v_and_b32_e32 v165, 0xffff0000, v122
	v_lshlrev_b32_e32 v166, 16, v123
	v_and_b32_e32 v167, 0xffff0000, v123
	v_lshlrev_b32_e32 v168, 16, v124
	v_and_b32_e32 v169, 0xffff0000, v124
	v_lshlrev_b32_e32 v170, 16, v125
	v_and_b32_e32 v171, 0xffff0000, v125
	v_lshlrev_b32_e32 v172, 16, v126
	v_and_b32_e32 v173, 0xffff0000, v126
	v_lshlrev_b32_e32 v174, 16, v127
	v_and_b32_e32 v175, 0xffff0000, v127
	v_pk_mul_f32 v[252:253], v[160:161], v[160:161]
	v_pk_mul_f32 v[254:255], v[162:163], v[162:163]
	v_pk_fma_f32 v[252:253], v[164:165], v[164:165], v[252:253]
	v_pk_fma_f32 v[254:255], v[166:167], v[166:167], v[254:255]
	v_pk_fma_f32 v[252:253], v[168:169], v[168:169], v[252:253]
	v_pk_fma_f32 v[254:255], v[170:171], v[170:171], v[254:255]
	v_pk_fma_f32 v[252:253], v[172:173], v[172:173], v[252:253]
	v_pk_fma_f32 v[254:255], v[174:175], v[174:175], v[254:255]
	v_pk_add_f32 v[252:253], v[252:253], v[254:255]
	s_nop 0
	v_add_f32_e32 v183, v252, v253
	s_nop 1
	v_add_f32_dpp v183, v183, v183 quad_perm:[1,0,3,2] row_mask:0xf bank_mask:0xf bound_ctrl:1
	s_nop 1
	v_add_f32_dpp v183, v183, v183 quad_perm:[2,3,0,1] row_mask:0xf bank_mask:0xf bound_ctrl:1
	s_nop 1
	v_add_f32_dpp v183, v183, v183 row_half_mirror row_mask:0xf bank_mask:0xf bound_ctrl:1
	s_nop 1
	v_add_f32_dpp v183, v183, v183 row_mirror row_mask:0xf bank_mask:0xf bound_ctrl:1
	s_nop 1
	v_readlane_b32 s98, v183, 0
	v_readlane_b32 s99, v183, 16
	v_readlane_b32 s100, v183, 32
	v_readlane_b32 s101, v183, 48
	s_nop 1
	v_mov_b32_e32 v183, s98
	v_add_f32_e32 v183, s99, v183
	v_add_f32_e32 v183, s100, v183
	v_add_f32_e32 v183, s101, v183
	v_fmamk_f32 v183, v183, 0x3a800000, v182
	v_cmp_gt_f32_e32 vcc, 0x800000, v183
	v_mul_f32_e32 v181, 0x4b800000, v183
	s_nop 1
	v_cndmask_b32_e32 v183, v183, v181, vcc
	v_rsq_f32_e32 v183, v183
	s_nop 0
	v_mul_f32_e32 v181, 0x45800000, v183
	v_cndmask_b32_e32 v184, v183, v181, vcc
	v_mov_b32_e32 v185, v184
	v_pk_mul_f32 v[160:161], v[160:161], v[184:185]
	v_pk_mul_f32 v[162:163], v[162:163], v[184:185]
	v_pk_mul_f32 v[164:165], v[164:165], v[184:185]
	v_pk_mul_f32 v[166:167], v[166:167], v[184:185]
	v_pk_mul_f32 v[168:169], v[168:169], v[184:185]
	v_pk_mul_f32 v[170:171], v[170:171], v[184:185]
	v_pk_mul_f32 v[172:173], v[172:173], v[184:185]
	v_pk_mul_f32 v[174:175], v[174:175], v[184:185]
	v_pk_fma_f32 v[144:145], v[160:161], v[128:129], v[144:145]
	v_pk_fma_f32 v[146:147], v[162:163], v[130:131], v[146:147]
	v_pk_fma_f32 v[148:149], v[164:165], v[132:133], v[148:149]
	v_pk_fma_f32 v[150:151], v[166:167], v[134:135], v[150:151]
	v_pk_fma_f32 v[152:153], v[168:169], v[136:137], v[152:153]
	v_pk_fma_f32 v[154:155], v[170:171], v[138:139], v[154:155]
	v_pk_fma_f32 v[156:157], v[172:173], v[140:141], v[156:157]
	v_pk_fma_f32 v[158:159], v[174:175], v[142:143], v[158:159]
	v_pk_mul_f32 v[252:253], v[144:145], v[144:145]
	v_pk_mul_f32 v[254:255], v[146:147], v[146:147]
	v_pk_fma_f32 v[252:253], v[148:149], v[148:149], v[252:253]
	v_pk_fma_f32 v[254:255], v[150:151], v[150:151], v[254:255]
	v_pk_fma_f32 v[252:253], v[152:153], v[152:153], v[252:253]
	v_pk_fma_f32 v[254:255], v[154:155], v[154:155], v[254:255]
	v_pk_fma_f32 v[252:253], v[156:157], v[156:157], v[252:253]
	v_pk_fma_f32 v[254:255], v[158:159], v[158:159], v[254:255]
	v_pk_add_f32 v[252:253], v[252:253], v[254:255]
	s_nop 0
	v_add_f32_e32 v183, v252, v253
	s_nop 1
	v_add_f32_dpp v183, v183, v183 quad_perm:[1,0,3,2] row_mask:0xf bank_mask:0xf bound_ctrl:1
	s_nop 1
	v_add_f32_dpp v183, v183, v183 quad_perm:[2,3,0,1] row_mask:0xf bank_mask:0xf bound_ctrl:1
	s_nop 1
	v_add_f32_dpp v183, v183, v183 row_half_mirror row_mask:0xf bank_mask:0xf bound_ctrl:1
	s_nop 1
	v_add_f32_dpp v183, v183, v183 row_mirror row_mask:0xf bank_mask:0xf bound_ctrl:1
	s_nop 1
	v_readlane_b32 s98, v183, 0
	v_readlane_b32 s99, v183, 16
	v_readlane_b32 s100, v183, 32
	v_readlane_b32 s101, v183, 48
	s_nop 1
	v_mov_b32_e32 v183, s98
	v_add_f32_e32 v183, s99, v183
	v_add_f32_e32 v183, s100, v183
	v_add_f32_e32 v183, s101, v183
	v_fmamk_f32 v183, v183, 0x3a800000, v182
	v_cmp_gt_f32_e32 vcc, 0x800000, v183
	v_mul_f32_e32 v181, 0x4b800000, v183
	s_nop 1
	v_cndmask_b32_e32 v183, v183, v181, vcc
	v_rsq_f32_e32 v183, v183
	s_nop 0
	v_mul_f32_e32 v181, 0x45800000, v183
	v_cndmask_b32_e32 v184, v183, v181, vcc
	v_mov_b32_e32 v185, v184
	v_cvt_pk_bf16_f32 v112, v144, v145
	v_cvt_pk_bf16_f32 v113, v146, v147
	v_cvt_pk_bf16_f32 v114, v148, v149
	v_cvt_pk_bf16_f32 v115, v150, v151
	v_cvt_pk_bf16_f32 v116, v152, v153
	v_cvt_pk_bf16_f32 v117, v154, v155
	v_cvt_pk_bf16_f32 v118, v156, v157
	v_cvt_pk_bf16_f32 v119, v158, v159
	v_add_u32_e32 v181, 0x3400000, v177
	global_store_dwordx4 v181, v[112:115], s[78:79]
	global_store_dwordx4 v181, v[116:119], s[78:79] offset:1024
	v_add_u32_e32 v236, 0xe000, v237
	s_mov_b64 exec, 1
	global_store_dword v236, v184, s[78:79]
	s_mov_b64 exec, -1
	v_readfirstlane_b32 s98, v179
	s_nop 3
	s_and_b32 s99, s98, 3
	s_add_i32 s100, s99, 4
	s_lshl_b32 s100, s100, 11
	s_sub_i32 s100, s100, s99
	s_lshl_b32 s101, s100, 11
	v_add_u32_e32 v177, s101, v177
	s_lshl_b32 s101, s100, 2
	v_add_u32_e32 v237, s101, v237
	v_add_u32_e32 v181, 0x1800000, v177
	global_load_dwordx4 v[0:3], v181, s[78:79]
	global_load_dwordx4 v[4:7], v181, s[78:79] offset:1024
	v_add_u32_e32 v181, 0x9e00000, v177
	global_load_dwordx4 v[8:11], v181, s[78:79]
	global_load_dwordx4 v[12:15], v181, s[78:79] offset:1024
	s_waitcnt vmcnt(0)
	v_lshlrev_b32_e32 v144, 16, v0
	v_and_b32_e32 v145, 0xffff0000, v0
	v_lshlrev_b32_e32 v146, 16, v1
	v_and_b32_e32 v147, 0xffff0000, v1
	v_lshlrev_b32_e32 v148, 16, v2
	v_and_b32_e32 v149, 0xffff0000, v2
	v_lshlrev_b32_e32 v150, 16, v3
	v_and_b32_e32 v151, 0xffff0000, v3
	v_lshlrev_b32_e32 v152, 16, v4
	v_and_b32_e32 v153, 0xffff0000, v4
	v_lshlrev_b32_e32 v154, 16, v5
	v_and_b32_e32 v155, 0xffff0000, v5
	v_lshlrev_b32_e32 v156, 16, v6
	v_and_b32_e32 v157, 0xffff0000, v6
	v_lshlrev_b32_e32 v158, 16, v7
	v_and_b32_e32 v159, 0xffff0000, v7
	v_lshlrev_b32_e32 v160, 16, v8
	v_and_b32_e32 v161, 0xffff0000, v8
	v_lshlrev_b32_e32 v162, 16, v9
	v_and_b32_e32 v163, 0xffff0000, v9
	v_lshlrev_b32_e32 v164, 16, v10
	v_and_b32_e32 v165, 0xffff0000, v10
	v_lshlrev_b32_e32 v166, 16, v11
	v_and_b32_e32 v167, 0xffff0000, v11
	v_lshlrev_b32_e32 v168, 16, v12
	v_and_b32_e32 v169, 0xffff0000, v12
	v_lshlrev_b32_e32 v170, 16, v13
	v_and_b32_e32 v171, 0xffff0000, v13
	v_lshlrev_b32_e32 v172, 16, v14
	v_and_b32_e32 v173, 0xffff0000, v14
	v_lshlrev_b32_e32 v174, 16, v15
	v_and_b32_e32 v175, 0xffff0000, v15
	v_pk_mul_f32 v[252:253], v[160:161], v[160:161]
	v_pk_mul_f32 v[254:255], v[162:163], v[162:163]
	v_pk_fma_f32 v[252:253], v[164:165], v[164:165], v[252:253]
	v_pk_fma_f32 v[254:255], v[166:167], v[166:167], v[254:255]
	v_pk_fma_f32 v[252:253], v[168:169], v[168:169], v[252:253]
	v_pk_fma_f32 v[254:255], v[170:171], v[170:171], v[254:255]
	v_pk_fma_f32 v[252:253], v[172:173], v[172:173], v[252:253]
	v_pk_fma_f32 v[254:255], v[174:175], v[174:175], v[254:255]
	v_pk_add_f32 v[252:253], v[252:253], v[254:255]
	s_nop 0
	v_add_f32_e32 v183, v252, v253
	s_nop 1
	v_add_f32_dpp v183, v183, v183 quad_perm:[1,0,3,2] row_mask:0xf bank_mask:0xf bound_ctrl:1
	s_nop 1
	v_add_f32_dpp v183, v183, v183 quad_perm:[2,3,0,1] row_mask:0xf bank_mask:0xf bound_ctrl:1
	s_nop 1
	v_add_f32_dpp v183, v183, v183 row_half_mirror row_mask:0xf bank_mask:0xf bound_ctrl:1
	s_nop 1
	v_add_f32_dpp v183, v183, v183 row_mirror row_mask:0xf bank_mask:0xf bound_ctrl:1
	s_nop 1
	v_readlane_b32 s98, v183, 0
	v_readlane_b32 s99, v183, 16
	v_readlane_b32 s100, v183, 32
	v_readlane_b32 s101, v183, 48
	s_nop 1
	v_mov_b32_e32 v183, s98
	v_add_f32_e32 v183, s99, v183
	v_add_f32_e32 v183, s100, v183
	v_add_f32_e32 v183, s101, v183
	v_fmamk_f32 v183, v183, 0x3a800000, v182
	v_cmp_gt_f32_e32 vcc, 0x800000, v183
	v_mul_f32_e32 v181, 0x4b800000, v183
	s_nop 1
	v_cndmask_b32_e32 v183, v183, v181, vcc
	v_rsq_f32_e32 v183, v183
	s_nop 0
	v_mul_f32_e32 v181, 0x45800000, v183
	v_cndmask_b32_e32 v184, v183, v181, vcc
	v_mov_b32_e32 v185, v184
	v_pk_mul_f32 v[160:161], v[160:161], v[184:185]
	v_pk_mul_f32 v[162:163], v[162:163], v[184:185]
	v_pk_mul_f32 v[164:165], v[164:165], v[184:185]
	v_pk_mul_f32 v[166:167], v[166:167], v[184:185]
	v_pk_mul_f32 v[168:169], v[168:169], v[184:185]
	v_pk_mul_f32 v[170:171], v[170:171], v[184:185]
	v_pk_mul_f32 v[172:173], v[172:173], v[184:185]
	v_pk_mul_f32 v[174:175], v[174:175], v[184:185]
	v_pk_fma_f32 v[144:145], v[160:161], v[128:129], v[144:145]
	v_pk_fma_f32 v[146:147], v[162:163], v[130:131], v[146:147]
	v_pk_fma_f32 v[148:149], v[164:165], v[132:133], v[148:149]
	v_pk_fma_f32 v[150:151], v[166:167], v[134:135], v[150:151]
	v_pk_fma_f32 v[152:153], v[168:169], v[136:137], v[152:153]
	v_pk_fma_f32 v[154:155], v[170:171], v[138:139], v[154:155]
	v_pk_fma_f32 v[156:157], v[172:173], v[140:141], v[156:157]
	v_pk_fma_f32 v[158:159], v[174:175], v[142:143], v[158:159]
	v_pk_mul_f32 v[252:253], v[144:145], v[144:145]
	v_pk_mul_f32 v[254:255], v[146:147], v[146:147]
	v_pk_fma_f32 v[252:253], v[148:149], v[148:149], v[252:253]
	v_pk_fma_f32 v[254:255], v[150:151], v[150:151], v[254:255]
	v_pk_fma_f32 v[252:253], v[152:153], v[152:153], v[252:253]
	v_pk_fma_f32 v[254:255], v[154:155], v[154:155], v[254:255]
	v_pk_fma_f32 v[252:253], v[156:157], v[156:157], v[252:253]
	v_pk_fma_f32 v[254:255], v[158:159], v[158:159], v[254:255]
	v_pk_add_f32 v[252:253], v[252:253], v[254:255]
	s_nop 0
	v_add_f32_e32 v183, v252, v253
	s_nop 1
	v_add_f32_dpp v183, v183, v183 quad_perm:[1,0,3,2] row_mask:0xf bank_mask:0xf bound_ctrl:1
	s_nop 1
	v_add_f32_dpp v183, v183, v183 quad_perm:[2,3,0,1] row_mask:0xf bank_mask:0xf bound_ctrl:1
	s_nop 1
	v_add_f32_dpp v183, v183, v183 row_half_mirror row_mask:0xf bank_mask:0xf bound_ctrl:1
	s_nop 1
	v_add_f32_dpp v183, v183, v183 row_mirror row_mask:0xf bank_mask:0xf bound_ctrl:1
	s_nop 1
	v_readlane_b32 s98, v183, 0
	v_readlane_b32 s99, v183, 16
	v_readlane_b32 s100, v183, 32
	v_readlane_b32 s101, v183, 48
	s_nop 1
	v_mov_b32_e32 v183, s98
	v_add_f32_e32 v183, s99, v183
	v_add_f32_e32 v183, s100, v183
	v_add_f32_e32 v183, s101, v183
	v_fmamk_f32 v183, v183, 0x3a800000, v182
	v_cmp_gt_f32_e32 vcc, 0x800000, v183
	v_mul_f32_e32 v181, 0x4b800000, v183
	s_nop 1
	v_cndmask_b32_e32 v183, v183, v181, vcc
	v_rsq_f32_e32 v183, v183
	s_nop 0
	v_mul_f32_e32 v181, 0x45800000, v183
	v_cndmask_b32_e32 v184, v183, v181, vcc
	v_mov_b32_e32 v185, v184
	v_cvt_pk_bf16_f32 v0, v144, v145
	v_cvt_pk_bf16_f32 v1, v146, v147
	v_cvt_pk_bf16_f32 v2, v148, v149
	v_cvt_pk_bf16_f32 v3, v150, v151
	v_cvt_pk_bf16_f32 v4, v152, v153
	v_cvt_pk_bf16_f32 v5, v154, v155
	v_cvt_pk_bf16_f32 v6, v156, v157
	v_cvt_pk_bf16_f32 v7, v158, v159
	v_add_u32_e32 v181, 0x1800000, v177
	global_store_dwordx4 v181, v[0:3], s[78:79]
	global_store_dwordx4 v181, v[4:7], s[78:79] offset:1024
	v_add_u32_e32 v236, 0x0, v237
	s_mov_b64 exec, 1
	global_store_dword v236, v184, s[78:79]
	s_mov_b64 exec, -1
	s_branch .Lmyxupd_done_5

.LBB0_2298:
	s_or_b64 exec, exec, s[8:9]
	v_cvt_f32_u32_e32 v4, v2
	s_waitcnt vmcnt(0)
	v_readfirstlane_b32 s6, v3
	v_sub_u32_e32 v3, 0, v2
	v_rcp_iflag_f32_e32 v4, v4
	v_add_u32_e32 v5, s6, v1
	v_mul_f32_e32 v4, 0x4f7ffffe, v4
	v_cvt_u32_f32_e32 v4, v4
	v_mul_lo_u32 v1, v3, v4
	v_mul_hi_u32 v1, v4, v1
	v_add_u32_e32 v1, v4, v1
	v_mul_hi_u32 v1, v5, v1
	v_mul_lo_u32 v3, v1, v2
	v_sub_u32_e32 v3, v5, v3
	v_add_u32_e32 v4, 1, v1
	v_cmp_ge_u32_e32 vcc, v3, v2
	s_nop 1
	v_cndmask_b32_e32 v1, v1, v4, vcc
	v_sub_u32_e32 v4, v3, v2
	v_cndmask_b32_e32 v3, v3, v4, vcc
	v_add_u32_e32 v4, 1, v1
	v_cmp_ge_u32_e32 vcc, v3, v2
	v_add_u32_e32 v3, 1, v5
	s_nop 0
	v_cndmask_b32_e32 v1, v1, v4, vcc
	v_mul_lo_u32 v4, v2, v1
	v_add_u32_e32 v2, v4, v2
	v_cmp_ne_u32_e32 vcc, v3, v2
	s_and_saveexec_b64 s[6:7], vcc
	s_xor_b64 s[6:7], exec, s[6:7]
	s_cbranch_execz .LBB0_2312
	s_waitcnt lgkmcnt(0)
	v_mov_b32_e32 v0, 0x3500
	global_load_dword v0, v0, s[78:79] sc1
	s_add_u32 s10, s78, 0x3500
	s_addc_u32 s11, s79, 0
	s_waitcnt vmcnt(0)
	v_cmp_eq_u32_e32 vcc, v0, v1
	s_cmp_lt_u32 s2, 16
	s_cbranch_scc0 ATB3_71128
	v_readfirstlane_b32 s100, v1
	s_mov_b64 vcc, 0
ATB3_71128:
	s_and_saveexec_b64 s[8:9], vcc
	s_cbranch_execz .LBB0_2311
	s_mov_b32 s22, 1
	s_mov_b64 s[12:13], 0
	v_mov_b32_e32 v0, 0
	s_branch .LBB0_2302

.LBB0_2315:
	s_or_b64 exec, exec, s[8:9]
	v_cvt_f32_u32_e32 v3, v0
	s_waitcnt vmcnt(0)
	v_readfirstlane_b32 s6, v2
	s_add_u32 s8, s78, 0x3500
	s_addc_u32 s9, s79, 0
	v_rcp_iflag_f32_e32 v3, v3
	v_add_u32_e32 v1, s6, v1
	v_add_u32_e32 v4, 1, v1
	s_mov_b64 s[10:11], -1
	v_mul_f32_e32 v2, 0x4f7ffffe, v3
	v_cvt_u32_f32_e32 v2, v2
	v_sub_u32_e32 v3, 0, v0
	v_mul_lo_u32 v3, v3, v2
	v_mul_hi_u32 v3, v2, v3
	v_add_u32_e32 v2, v2, v3
	v_mul_hi_u32 v2, v1, v2
	v_mul_lo_u32 v3, v2, v0
	v_sub_u32_e32 v1, v1, v3
	v_add_u32_e32 v5, 1, v2
	v_cmp_ge_u32_e32 vcc, v1, v0
	v_sub_u32_e32 v3, v1, v0
	s_nop 0
	v_cndmask_b32_e32 v2, v2, v5, vcc
	v_cndmask_b32_e32 v1, v1, v3, vcc
	v_add_u32_e32 v3, 1, v2
	v_cmp_ge_u32_e32 vcc, v1, v0
	s_nop 1
	v_cndmask_b32_e32 v2, v2, v3, vcc
	v_mul_lo_u32 v1, v0, v2
	v_add_u32_e32 v0, v1, v0
	v_cmp_ne_u32_e32 vcc, v4, v0
	v_mov_b64_e32 v[0:1], s[8:9]
	s_and_saveexec_b64 s[6:7], vcc
	s_cbranch_execz .LBB0_2327
	v_mov_b32_e32 v0, 0
	global_load_dword v1, v0, s[8:9] sc1
	s_mov_b64 s[14:15], 0
	s_waitcnt vmcnt(0)
	v_cmp_eq_u32_e32 vcc, v1, v2
	s_cmp_lt_u32 s2, 16
	s_cbranch_scc0 ATB3_71269
	v_readfirstlane_b32 s100, v2
	s_mov_b64 vcc, 0
ATB3_71269:
	s_and_saveexec_b64 s[12:13], vcc
	s_cbranch_execz .LBB0_2326
	s_add_u32 s10, s78, 0x200
	s_addc_u32 s11, s79, 0
	s_mov_b32 s24, 1
	s_branch .LBB0_2319

.LBB0_2573:
	v_readlane_b32 s0, v235, 52
	v_readlane_b32 s1, v235, 53
	s_and_b64 vcc, exec, s[0:1]
	s_waitcnt lgkmcnt(0)
	s_barrier
	v_mbcnt_lo_u32_b32 v0, -1, 0
	v_mbcnt_hi_u32_b32 v0, -1, v0
	s_cbranch_vccnz .LBB0_2593
	v_lshlrev_b32_e32 v2, 3, v0
	v_ashrrev_i32_e32 v3, 31, v2
	v_readlane_b32 s4, v235, 4
	v_lshlrev_b64 v[4:5], 1, v[2:3]
	v_lshlrev_b64 v[2:3], 2, v[2:3]
	v_readlane_b32 s14, v235, 14
	v_readlane_b32 s15, v235, 15
	v_lshl_add_u64 v[62:63], s[90:91], 0, v[2:3]
	v_readlane_b32 s5, v235, 5
	v_readlane_b32 s6, v235, 6
	v_readlane_b32 s7, v235, 7
	v_readlane_b32 s8, v235, 8
	v_readlane_b32 s9, v235, 9
	v_readlane_b32 s10, v235, 10
	v_readlane_b32 s11, v235, 11
	v_readlane_b32 s12, v235, 12
	v_readlane_b32 s13, v235, 13
	v_readlane_b32 s16, v235, 16
	v_readlane_b32 s17, v235, 17
	v_readlane_b32 s18, v235, 18
	v_readlane_b32 s19, v235, 19
	v_lshl_add_u64 v[2:3], s[14:15], 0, v[2:3]
	s_mov_b64 s[0:1], 0x3000
	v_lshl_add_u64 v[60:61], s[86:87], 0, v[4:5]
	v_lshl_add_u64 v[64:65], s[54:55], 0, v[4:5]
	v_lshl_add_u64 v[66:67], v[2:3], 0, s[0:1]
	s_mov_b32 s1, 0
	v_cmp_eq_u32_e64 s[4:5], 0, v0
	s_mov_b64 s[6:7], 0x200000
	s_mov_b64 s[8:9], 0x200800
	s_mov_b64 s[10:11], 0x400000
	s_mov_b64 s[12:13], 0x400800
	s_mov_b64 s[14:15], 0x600000
	s_mov_b64 s[16:17], 0x600800
	s_mov_b64 s[18:19], 0x800000
	s_mov_b32 s48, 0x800000
	s_mov_b64 s[20:21], 0x800800
	s_mov_b64 s[22:23], 0xa00000
	s_mov_b64 s[24:25], 0xa00800
	s_mov_b64 s[26:27], 0xc00000
	s_mov_b64 s[28:29], 0xc00800
	s_mov_b64 s[30:31], 0xe00000
	s_mov_b64 s[36:37], 0xe00800
	v_mov_b32_e32 v104, 0
	v_mov_b32_e32 v105, 0x358637bd
	v_readlane_b32 s38, v235, 61
	v_readlane_b32 s39, v235, 62
	v_mbcnt_lo_u32_b32 v176, -1, 0
	v_mbcnt_hi_u32_b32 v176, -1, v176
	v_readlane_b32 s98, v235, 49
	v_readlane_b32 s99, v235, 20
	v_readlane_b32 s100, v235, 14
	v_readlane_b32 s101, v235, 15
	s_nop 3
	s_lshr_b32 vcc_lo, s98, 3
	s_and_b32 vcc_hi, vcc_lo, 7
	s_lshr_b32 vcc_lo, vcc_lo, 3
	s_lshl_b32 vcc_lo, vcc_lo, 3
	s_add_i32 vcc_lo, vcc_lo, s99
	s_lshl_b32 s98, vcc_hi, 8
	s_add_i32 s98, s98, vcc_lo
	s_mov_b32 s99, s98
	v_mov_b32_e32 v183, s99
	v_lshlrev_b32_e32 v177, 4, v176
	s_lshl_b32 s99, s99, 11
	v_add_u32_e32 v177, s99, v177
	v_add_u32_e32 v178, 0x1800000, v177
	v_add_u32_e32 v179, 0x9e00000, v177
	v_lshlrev_b32_e32 v180, 5, v176
	v_add_u32_e32 v181, 0x3000, v180
	global_load_dwordx4 v[128:131], v181, s[100:101]
	global_load_dwordx4 v[132:135], v181, s[100:101] offset:16
	global_load_dwordx4 v[136:139], v181, s[100:101] offset:2048
	global_load_dwordx4 v[140:143], v181, s[100:101] offset:2064
	v_mov_b32_e32 v182, 0x358637bd
	s_and_b32 vcc_lo, s98, 3
	s_cmp_eq_u32 vcc_lo, 0
	s_cbranch_scc1 .Lmyxupd_heavy_6
	global_load_dwordx4 v[0:3], v178, s[78:79]
	global_load_dwordx4 v[4:7], v178, s[78:79] offset:1024
	global_load_dwordx4 v[8:11], v179, s[78:79]
	global_load_dwordx4 v[12:15], v179, s[78:79] offset:1024
	v_add_u32_e32 v178, 0x400000, v178
	v_add_u32_e32 v179, 0x400000, v179
	global_load_dwordx4 v[16:19], v178, s[78:79]
	global_load_dwordx4 v[20:23], v178, s[78:79] offset:1024
	global_load_dwordx4 v[24:27], v179, s[78:79]
	global_load_dwordx4 v[28:31], v179, s[78:79] offset:1024
	v_add_u32_e32 v178, 0x400000, v178
	v_add_u32_e32 v179, 0x400000, v179
	global_load_dwordx4 v[32:35], v178, s[78:79]
	global_load_dwordx4 v[36:39], v178, s[78:79] offset:1024
	global_load_dwordx4 v[40:43], v179, s[78:79]
	global_load_dwordx4 v[44:47], v179, s[78:79] offset:1024
	v_add_u32_e32 v178, 0x400000, v178
	v_add_u32_e32 v179, 0x400000, v179
	global_load_dwordx4 v[48:51], v178, s[78:79]
	global_load_dwordx4 v[52:55], v178, s[78:79] offset:1024
	global_load_dwordx4 v[56:59], v179, s[78:79]
	global_load_dwordx4 v[60:63], v179, s[78:79] offset:1024
	v_add_u32_e32 v178, 0x400000, v178
	v_add_u32_e32 v179, 0x400000, v179
	global_load_dwordx4 v[64:67], v178, s[78:79]
	global_load_dwordx4 v[68:71], v178, s[78:79] offset:1024
	global_load_dwordx4 v[72:75], v179, s[78:79]
	global_load_dwordx4 v[76:79], v179, s[78:79] offset:1024
	v_add_u32_e32 v178, 0x400000, v178
	v_add_u32_e32 v179, 0x400000, v179
	global_load_dwordx4 v[80:83], v178, s[78:79]
	global_load_dwordx4 v[84:87], v178, s[78:79] offset:1024
	global_load_dwordx4 v[88:91], v179, s[78:79]
	global_load_dwordx4 v[92:95], v179, s[78:79] offset:1024
	v_add_u32_e32 v178, 0x400000, v178
	v_add_u32_e32 v179, 0x400000, v179
	global_load_dwordx4 v[96:99], v178, s[78:79]
	global_load_dwordx4 v[100:103], v178, s[78:79] offset:1024
	global_load_dwordx4 v[104:107], v179, s[78:79]
	global_load_dwordx4 v[108:111], v179, s[78:79] offset:1024
	v_add_u32_e32 v178, 0x400000, v178
	v_add_u32_e32 v179, 0x400000, v179
	global_load_dwordx4 v[112:115], v178, s[78:79]
	global_load_dwordx4 v[116:119], v178, s[78:79] offset:1024
	global_load_dwordx4 v[120:123], v179, s[78:79]
	global_load_dwordx4 v[124:127], v179, s[78:79] offset:1024
	v_lshlrev_b32_e32 v237, 2, v183
	v_add_u32_e32 v237, 0x10000, v237
	v_mov_b32_e32 v179, s98
	s_waitcnt vmcnt(28)
	v_lshlrev_b32_e32 v144, 16, v0
	v_and_b32_e32 v145, 0xffff0000, v0
	v_lshlrev_b32_e32 v146, 16, v1
	v_and_b32_e32 v147, 0xffff0000, v1
	v_lshlrev_b32_e32 v148, 16, v2
	v_and_b32_e32 v149, 0xffff0000, v2
	v_lshlrev_b32_e32 v150, 16, v3
	v_and_b32_e32 v151, 0xffff0000, v3
	v_lshlrev_b32_e32 v152, 16, v4
	v_and_b32_e32 v153, 0xffff0000, v4
	v_lshlrev_b32_e32 v154, 16, v5
	v_and_b32_e32 v155, 0xffff0000, v5
	v_lshlrev_b32_e32 v156, 16, v6
	v_and_b32_e32 v157, 0xffff0000, v6
	v_lshlrev_b32_e32 v158, 16, v7
	v_and_b32_e32 v159, 0xffff0000, v7
	v_lshlrev_b32_e32 v160, 16, v8
	v_and_b32_e32 v161, 0xffff0000, v8
	v_lshlrev_b32_e32 v162, 16, v9
	v_and_b32_e32 v163, 0xffff0000, v9
	v_lshlrev_b32_e32 v164, 16, v10
	v_and_b32_e32 v165, 0xffff0000, v10
	v_lshlrev_b32_e32 v166, 16, v11
	v_and_b32_e32 v167, 0xffff0000, v11
	v_lshlrev_b32_e32 v168, 16, v12
	v_and_b32_e32 v169, 0xffff0000, v12
	v_lshlrev_b32_e32 v170, 16, v13
	v_and_b32_e32 v171, 0xffff0000, v13
	v_lshlrev_b32_e32 v172, 16, v14
	v_and_b32_e32 v173, 0xffff0000, v14
	v_lshlrev_b32_e32 v174, 16, v15
	v_and_b32_e32 v175, 0xffff0000, v15
	v_pk_mul_f32 v[252:253], v[160:161], v[160:161]
	v_pk_mul_f32 v[254:255], v[162:163], v[162:163]
	v_pk_fma_f32 v[252:253], v[164:165], v[164:165], v[252:253]
	v_pk_fma_f32 v[254:255], v[166:167], v[166:167], v[254:255]
	v_pk_fma_f32 v[252:253], v[168:169], v[168:169], v[252:253]
	v_pk_fma_f32 v[254:255], v[170:171], v[170:171], v[254:255]
	v_pk_fma_f32 v[252:253], v[172:173], v[172:173], v[252:253]
	v_pk_fma_f32 v[254:255], v[174:175], v[174:175], v[254:255]
	v_pk_add_f32 v[252:253], v[252:253], v[254:255]
	s_nop 0
	v_add_f32_e32 v183, v252, v253
	s_nop 1
	v_add_f32_dpp v183, v183, v183 quad_perm:[1,0,3,2] row_mask:0xf bank_mask:0xf bound_ctrl:1
	s_nop 1
	v_add_f32_dpp v183, v183, v183 quad_perm:[2,3,0,1] row_mask:0xf bank_mask:0xf bound_ctrl:1
	s_nop 1
	v_add_f32_dpp v183, v183, v183 row_half_mirror row_mask:0xf bank_mask:0xf bound_ctrl:1
	s_nop 1
	v_add_f32_dpp v183, v183, v183 row_mirror row_mask:0xf bank_mask:0xf bound_ctrl:1
	s_nop 1
	v_readlane_b32 s98, v183, 0
	v_readlane_b32 s99, v183, 16
	v_readlane_b32 s100, v183, 32
	v_readlane_b32 s101, v183, 48
	s_nop 1
	v_mov_b32_e32 v183, s98
	v_add_f32_e32 v183, s99, v183
	v_add_f32_e32 v183, s100, v183
	v_add_f32_e32 v183, s101, v183
	v_fmamk_f32 v183, v183, 0x3a800000, v182
	v_cmp_gt_f32_e32 vcc, 0x800000, v183
	v_mul_f32_e32 v181, 0x4b800000, v183
	s_nop 1
	v_cndmask_b32_e32 v183, v183, v181, vcc
	v_rsq_f32_e32 v183, v183
	s_nop 0
	v_mul_f32_e32 v181, 0x45800000, v183
	v_cndmask_b32_e32 v184, v183, v181, vcc
	v_mov_b32_e32 v185, v184
	v_pk_mul_f32 v[160:161], v[160:161], v[184:185]
	v_pk_mul_f32 v[162:163], v[162:163], v[184:185]
	v_pk_mul_f32 v[164:165], v[164:165], v[184:185]
	v_pk_mul_f32 v[166:167], v[166:167], v[184:185]
	v_pk_mul_f32 v[168:169], v[168:169], v[184:185]
	v_pk_mul_f32 v[170:171], v[170:171], v[184:185]
	v_pk_mul_f32 v[172:173], v[172:173], v[184:185]
	v_pk_mul_f32 v[174:175], v[174:175], v[184:185]
	v_pk_fma_f32 v[144:145], v[160:161], v[128:129], v[144:145]
	v_pk_fma_f32 v[146:147], v[162:163], v[130:131], v[146:147]
	v_pk_fma_f32 v[148:149], v[164:165], v[132:133], v[148:149]
	v_pk_fma_f32 v[150:151], v[166:167], v[134:135], v[150:151]
	v_pk_fma_f32 v[152:153], v[168:169], v[136:137], v[152:153]
	v_pk_fma_f32 v[154:155], v[170:171], v[138:139], v[154:155]
	v_pk_fma_f32 v[156:157], v[172:173], v[140:141], v[156:157]
	v_pk_fma_f32 v[158:159], v[174:175], v[142:143], v[158:159]
	v_pk_mul_f32 v[252:253], v[144:145], v[144:145]
	v_pk_mul_f32 v[254:255], v[146:147], v[146:147]
	v_pk_fma_f32 v[252:253], v[148:149], v[148:149], v[252:253]
	v_pk_fma_f32 v[254:255], v[150:151], v[150:151], v[254:255]
	v_pk_fma_f32 v[252:253], v[152:153], v[152:153], v[252:253]
	v_pk_fma_f32 v[254:255], v[154:155], v[154:155], v[254:255]
	v_pk_fma_f32 v[252:253], v[156:157], v[156:157], v[252:253]
	v_pk_fma_f32 v[254:255], v[158:159], v[158:159], v[254:255]
	v_pk_add_f32 v[252:253], v[252:253], v[254:255]
	s_nop 0
	v_add_f32_e32 v183, v252, v253
	s_nop 1
	v_add_f32_dpp v183, v183, v183 quad_perm:[1,0,3,2] row_mask:0xf bank_mask:0xf bound_ctrl:1
	s_nop 1
	v_add_f32_dpp v183, v183, v183 quad_perm:[2,3,0,1] row_mask:0xf bank_mask:0xf bound_ctrl:1
	s_nop 1
	v_add_f32_dpp v183, v183, v183 row_half_mirror row_mask:0xf bank_mask:0xf bound_ctrl:1
	s_nop 1
	v_add_f32_dpp v183, v183, v183 row_mirror row_mask:0xf bank_mask:0xf bound_ctrl:1
	s_nop 1
	v_readlane_b32 s98, v183, 0
	v_readlane_b32 s99, v183, 16
	v_readlane_b32 s100, v183, 32
	v_readlane_b32 s101, v183, 48
	s_nop 1
	v_mov_b32_e32 v183, s98
	v_add_f32_e32 v183, s99, v183
	v_add_f32_e32 v183, s100, v183
	v_add_f32_e32 v183, s101, v183
	v_fmamk_f32 v183, v183, 0x3a800000, v182
	v_cmp_gt_f32_e32 vcc, 0x800000, v183
	v_mul_f32_e32 v181, 0x4b800000, v183
	s_nop 1
	v_cndmask_b32_e32 v183, v183, v181, vcc
	v_rsq_f32_e32 v183, v183
	s_nop 0
	v_mul_f32_e32 v181, 0x45800000, v183
	v_cndmask_b32_e32 v184, v183, v181, vcc
	v_mov_b32_e32 v185, v184
	v_cvt_pk_bf16_f32 v0, v144, v145
	v_cvt_pk_bf16_f32 v1, v146, v147
	v_cvt_pk_bf16_f32 v2, v148, v149
	v_cvt_pk_bf16_f32 v3, v150, v151
	v_cvt_pk_bf16_f32 v4, v152, v153
	v_cvt_pk_bf16_f32 v5, v154, v155
	v_cvt_pk_bf16_f32 v6, v156, v157
	v_cvt_pk_bf16_f32 v7, v158, v159
	v_add_u32_e32 v181, 0x1800000, v177
	global_store_dwordx4 v181, v[0:3], s[78:79]
	global_store_dwordx4 v181, v[4:7], s[78:79] offset:1024
	v_add_u32_e32 v236, 0x0, v237
	s_mov_b64 exec, 1
	global_store_dword v236, v184, s[78:79]
	s_mov_b64 exec, -1
	s_waitcnt vmcnt(24)
	v_lshlrev_b32_e32 v144, 16, v16
	v_and_b32_e32 v145, 0xffff0000, v16
	v_lshlrev_b32_e32 v146, 16, v17
	v_and_b32_e32 v147, 0xffff0000, v17
	v_lshlrev_b32_e32 v148, 16, v18
	v_and_b32_e32 v149, 0xffff0000, v18
	v_lshlrev_b32_e32 v150, 16, v19
	v_and_b32_e32 v151, 0xffff0000, v19
	v_lshlrev_b32_e32 v152, 16, v20
	v_and_b32_e32 v153, 0xffff0000, v20
	v_lshlrev_b32_e32 v154, 16, v21
	v_and_b32_e32 v155, 0xffff0000, v21
	v_lshlrev_b32_e32 v156, 16, v22
	v_and_b32_e32 v157, 0xffff0000, v22
	v_lshlrev_b32_e32 v158, 16, v23
	v_and_b32_e32 v159, 0xffff0000, v23
	v_lshlrev_b32_e32 v160, 16, v24
	v_and_b32_e32 v161, 0xffff0000, v24
	v_lshlrev_b32_e32 v162, 16, v25
	v_and_b32_e32 v163, 0xffff0000, v25
	v_lshlrev_b32_e32 v164, 16, v26
	v_and_b32_e32 v165, 0xffff0000, v26
	v_lshlrev_b32_e32 v166, 16, v27
	v_and_b32_e32 v167, 0xffff0000, v27
	v_lshlrev_b32_e32 v168, 16, v28
	v_and_b32_e32 v169, 0xffff0000, v28
	v_lshlrev_b32_e32 v170, 16, v29
	v_and_b32_e32 v171, 0xffff0000, v29
	v_lshlrev_b32_e32 v172, 16, v30
	v_and_b32_e32 v173, 0xffff0000, v30
	v_lshlrev_b32_e32 v174, 16, v31
	v_and_b32_e32 v175, 0xffff0000, v31
	v_pk_mul_f32 v[252:253], v[160:161], v[160:161]
	v_pk_mul_f32 v[254:255], v[162:163], v[162:163]
	v_pk_fma_f32 v[252:253], v[164:165], v[164:165], v[252:253]
	v_pk_fma_f32 v[254:255], v[166:167], v[166:167], v[254:255]
	v_pk_fma_f32 v[252:253], v[168:169], v[168:169], v[252:253]
	v_pk_fma_f32 v[254:255], v[170:171], v[170:171], v[254:255]
	v_pk_fma_f32 v[252:253], v[172:173], v[172:173], v[252:253]
	v_pk_fma_f32 v[254:255], v[174:175], v[174:175], v[254:255]
	v_pk_add_f32 v[252:253], v[252:253], v[254:255]
	s_nop 0
	v_add_f32_e32 v183, v252, v253
	s_nop 1
	v_add_f32_dpp v183, v183, v183 quad_perm:[1,0,3,2] row_mask:0xf bank_mask:0xf bound_ctrl:1
	s_nop 1
	v_add_f32_dpp v183, v183, v183 quad_perm:[2,3,0,1] row_mask:0xf bank_mask:0xf bound_ctrl:1
	s_nop 1
	v_add_f32_dpp v183, v183, v183 row_half_mirror row_mask:0xf bank_mask:0xf bound_ctrl:1
	s_nop 1
	v_add_f32_dpp v183, v183, v183 row_mirror row_mask:0xf bank_mask:0xf bound_ctrl:1
	s_nop 1
	v_readlane_b32 s98, v183, 0
	v_readlane_b32 s99, v183, 16
	v_readlane_b32 s100, v183, 32
	v_readlane_b32 s101, v183, 48
	s_nop 1
	v_mov_b32_e32 v183, s98
	v_add_f32_e32 v183, s99, v183
	v_add_f32_e32 v183, s100, v183
	v_add_f32_e32 v183, s101, v183
	v_fmamk_f32 v183, v183, 0x3a800000, v182
	v_cmp_gt_f32_e32 vcc, 0x800000, v183
	v_mul_f32_e32 v181, 0x4b800000, v183
	s_nop 1
	v_cndmask_b32_e32 v183, v183, v181, vcc
	v_rsq_f32_e32 v183, v183
	s_nop 0
	v_mul_f32_e32 v181, 0x45800000, v183
	v_cndmask_b32_e32 v184, v183, v181, vcc
	v_mov_b32_e32 v185, v184
	v_pk_mul_f32 v[160:161], v[160:161], v[184:185]
	v_pk_mul_f32 v[162:163], v[162:163], v[184:185]
	v_pk_mul_f32 v[164:165], v[164:165], v[184:185]
	v_pk_mul_f32 v[166:167], v[166:167], v[184:185]
	v_pk_mul_f32 v[168:169], v[168:169], v[184:185]
	v_pk_mul_f32 v[170:171], v[170:171], v[184:185]
	v_pk_mul_f32 v[172:173], v[172:173], v[184:185]
	v_pk_mul_f32 v[174:175], v[174:175], v[184:185]
	v_pk_fma_f32 v[144:145], v[160:161], v[128:129], v[144:145]
	v_pk_fma_f32 v[146:147], v[162:163], v[130:131], v[146:147]
	v_pk_fma_f32 v[148:149], v[164:165], v[132:133], v[148:149]
	v_pk_fma_f32 v[150:151], v[166:167], v[134:135], v[150:151]
	v_pk_fma_f32 v[152:153], v[168:169], v[136:137], v[152:153]
	v_pk_fma_f32 v[154:155], v[170:171], v[138:139], v[154:155]
	v_pk_fma_f32 v[156:157], v[172:173], v[140:141], v[156:157]
	v_pk_fma_f32 v[158:159], v[174:175], v[142:143], v[158:159]
	v_pk_mul_f32 v[252:253], v[144:145], v[144:145]
	v_pk_mul_f32 v[254:255], v[146:147], v[146:147]
	v_pk_fma_f32 v[252:253], v[148:149], v[148:149], v[252:253]
	v_pk_fma_f32 v[254:255], v[150:151], v[150:151], v[254:255]
	v_pk_fma_f32 v[252:253], v[152:153], v[152:153], v[252:253]
	v_pk_fma_f32 v[254:255], v[154:155], v[154:155], v[254:255]
	v_pk_fma_f32 v[252:253], v[156:157], v[156:157], v[252:253]
	v_pk_fma_f32 v[254:255], v[158:159], v[158:159], v[254:255]
	v_pk_add_f32 v[252:253], v[252:253], v[254:255]
	s_nop 0
	v_add_f32_e32 v183, v252, v253
	s_nop 1
	v_add_f32_dpp v183, v183, v183 quad_perm:[1,0,3,2] row_mask:0xf bank_mask:0xf bound_ctrl:1
	s_nop 1
	v_add_f32_dpp v183, v183, v183 quad_perm:[2,3,0,1] row_mask:0xf bank_mask:0xf bound_ctrl:1
	s_nop 1
	v_add_f32_dpp v183, v183, v183 row_half_mirror row_mask:0xf bank_mask:0xf bound_ctrl:1
	s_nop 1
	v_add_f32_dpp v183, v183, v183 row_mirror row_mask:0xf bank_mask:0xf bound_ctrl:1
	s_nop 1
	v_readlane_b32 s98, v183, 0
	v_readlane_b32 s99, v183, 16
	v_readlane_b32 s100, v183, 32
	v_readlane_b32 s101, v183, 48
	s_nop 1
	v_mov_b32_e32 v183, s98
	v_add_f32_e32 v183, s99, v183
	v_add_f32_e32 v183, s100, v183
	v_add_f32_e32 v183, s101, v183
	v_fmamk_f32 v183, v183, 0x3a800000, v182
	v_cmp_gt_f32_e32 vcc, 0x800000, v183
	v_mul_f32_e32 v181, 0x4b800000, v183
	s_nop 1
	v_cndmask_b32_e32 v183, v183, v181, vcc
	v_rsq_f32_e32 v183, v183
	s_nop 0
	v_mul_f32_e32 v181, 0x45800000, v183
	v_cndmask_b32_e32 v184, v183, v181, vcc
	v_mov_b32_e32 v185, v184
	v_cvt_pk_bf16_f32 v16, v144, v145
	v_cvt_pk_bf16_f32 v17, v146, v147
	v_cvt_pk_bf16_f32 v18, v148, v149
	v_cvt_pk_bf16_f32 v19, v150, v151
	v_cvt_pk_bf16_f32 v20, v152, v153
	v_cvt_pk_bf16_f32 v21, v154, v155
	v_cvt_pk_bf16_f32 v22, v156, v157
	v_cvt_pk_bf16_f32 v23, v158, v159
	v_add_u32_e32 v181, 0x1c00000, v177
	global_store_dwordx4 v181, v[16:19], s[78:79]
	global_store_dwordx4 v181, v[20:23], s[78:79] offset:1024
	v_add_u32_e32 v236, 0x2000, v237
	s_mov_b64 exec, 1
	global_store_dword v236, v184, s[78:79]
	s_mov_b64 exec, -1
	s_waitcnt vmcnt(20)
	v_lshlrev_b32_e32 v144, 16, v32
	v_and_b32_e32 v145, 0xffff0000, v32
	v_lshlrev_b32_e32 v146, 16, v33
	v_and_b32_e32 v147, 0xffff0000, v33
	v_lshlrev_b32_e32 v148, 16, v34
	v_and_b32_e32 v149, 0xffff0000, v34
	v_lshlrev_b32_e32 v150, 16, v35
	v_and_b32_e32 v151, 0xffff0000, v35
	v_lshlrev_b32_e32 v152, 16, v36
	v_and_b32_e32 v153, 0xffff0000, v36
	v_lshlrev_b32_e32 v154, 16, v37
	v_and_b32_e32 v155, 0xffff0000, v37
	v_lshlrev_b32_e32 v156, 16, v38
	v_and_b32_e32 v157, 0xffff0000, v38
	v_lshlrev_b32_e32 v158, 16, v39
	v_and_b32_e32 v159, 0xffff0000, v39
	v_lshlrev_b32_e32 v160, 16, v40
	v_and_b32_e32 v161, 0xffff0000, v40
	v_lshlrev_b32_e32 v162, 16, v41
	v_and_b32_e32 v163, 0xffff0000, v41
	v_lshlrev_b32_e32 v164, 16, v42
	v_and_b32_e32 v165, 0xffff0000, v42
	v_lshlrev_b32_e32 v166, 16, v43
	v_and_b32_e32 v167, 0xffff0000, v43
	v_lshlrev_b32_e32 v168, 16, v44
	v_and_b32_e32 v169, 0xffff0000, v44
	v_lshlrev_b32_e32 v170, 16, v45
	v_and_b32_e32 v171, 0xffff0000, v45
	v_lshlrev_b32_e32 v172, 16, v46
	v_and_b32_e32 v173, 0xffff0000, v46
	v_lshlrev_b32_e32 v174, 16, v47
	v_and_b32_e32 v175, 0xffff0000, v47
	v_pk_mul_f32 v[252:253], v[160:161], v[160:161]
	v_pk_mul_f32 v[254:255], v[162:163], v[162:163]
	v_pk_fma_f32 v[252:253], v[164:165], v[164:165], v[252:253]
	v_pk_fma_f32 v[254:255], v[166:167], v[166:167], v[254:255]
	v_pk_fma_f32 v[252:253], v[168:169], v[168:169], v[252:253]
	v_pk_fma_f32 v[254:255], v[170:171], v[170:171], v[254:255]
	v_pk_fma_f32 v[252:253], v[172:173], v[172:173], v[252:253]
	v_pk_fma_f32 v[254:255], v[174:175], v[174:175], v[254:255]
	v_pk_add_f32 v[252:253], v[252:253], v[254:255]
	s_nop 0
	v_add_f32_e32 v183, v252, v253
	s_nop 1
	v_add_f32_dpp v183, v183, v183 quad_perm:[1,0,3,2] row_mask:0xf bank_mask:0xf bound_ctrl:1
	s_nop 1
	v_add_f32_dpp v183, v183, v183 quad_perm:[2,3,0,1] row_mask:0xf bank_mask:0xf bound_ctrl:1
	s_nop 1
	v_add_f32_dpp v183, v183, v183 row_half_mirror row_mask:0xf bank_mask:0xf bound_ctrl:1
	s_nop 1
	v_add_f32_dpp v183, v183, v183 row_mirror row_mask:0xf bank_mask:0xf bound_ctrl:1
	s_nop 1
	v_readlane_b32 s98, v183, 0
	v_readlane_b32 s99, v183, 16
	v_readlane_b32 s100, v183, 32
	v_readlane_b32 s101, v183, 48
	s_nop 1
	v_mov_b32_e32 v183, s98
	v_add_f32_e32 v183, s99, v183
	v_add_f32_e32 v183, s100, v183
	v_add_f32_e32 v183, s101, v183
	v_fmamk_f32 v183, v183, 0x3a800000, v182
	v_cmp_gt_f32_e32 vcc, 0x800000, v183
	v_mul_f32_e32 v181, 0x4b800000, v183
	s_nop 1
	v_cndmask_b32_e32 v183, v183, v181, vcc
	v_rsq_f32_e32 v183, v183
	s_nop 0
	v_mul_f32_e32 v181, 0x45800000, v183
	v_cndmask_b32_e32 v184, v183, v181, vcc
	v_mov_b32_e32 v185, v184
	v_pk_mul_f32 v[160:161], v[160:161], v[184:185]
	v_pk_mul_f32 v[162:163], v[162:163], v[184:185]
	v_pk_mul_f32 v[164:165], v[164:165], v[184:185]
	v_pk_mul_f32 v[166:167], v[166:167], v[184:185]
	v_pk_mul_f32 v[168:169], v[168:169], v[184:185]
	v_pk_mul_f32 v[170:171], v[170:171], v[184:185]
	v_pk_mul_f32 v[172:173], v[172:173], v[184:185]
	v_pk_mul_f32 v[174:175], v[174:175], v[184:185]
	v_pk_fma_f32 v[144:145], v[160:161], v[128:129], v[144:145]
	v_pk_fma_f32 v[146:147], v[162:163], v[130:131], v[146:147]
	v_pk_fma_f32 v[148:149], v[164:165], v[132:133], v[148:149]
	v_pk_fma_f32 v[150:151], v[166:167], v[134:135], v[150:151]
	v_pk_fma_f32 v[152:153], v[168:169], v[136:137], v[152:153]
	v_pk_fma_f32 v[154:155], v[170:171], v[138:139], v[154:155]
	v_pk_fma_f32 v[156:157], v[172:173], v[140:141], v[156:157]
	v_pk_fma_f32 v[158:159], v[174:175], v[142:143], v[158:159]
	v_pk_mul_f32 v[252:253], v[144:145], v[144:145]
	v_pk_mul_f32 v[254:255], v[146:147], v[146:147]
	v_pk_fma_f32 v[252:253], v[148:149], v[148:149], v[252:253]
	v_pk_fma_f32 v[254:255], v[150:151], v[150:151], v[254:255]
	v_pk_fma_f32 v[252:253], v[152:153], v[152:153], v[252:253]
	v_pk_fma_f32 v[254:255], v[154:155], v[154:155], v[254:255]
	v_pk_fma_f32 v[252:253], v[156:157], v[156:157], v[252:253]
	v_pk_fma_f32 v[254:255], v[158:159], v[158:159], v[254:255]
	v_pk_add_f32 v[252:253], v[252:253], v[254:255]
	s_nop 0
	v_add_f32_e32 v183, v252, v253
	s_nop 1
	v_add_f32_dpp v183, v183, v183 quad_perm:[1,0,3,2] row_mask:0xf bank_mask:0xf bound_ctrl:1
	s_nop 1
	v_add_f32_dpp v183, v183, v183 quad_perm:[2,3,0,1] row_mask:0xf bank_mask:0xf bound_ctrl:1
	s_nop 1
	v_add_f32_dpp v183, v183, v183 row_half_mirror row_mask:0xf bank_mask:0xf bound_ctrl:1
	s_nop 1
	v_add_f32_dpp v183, v183, v183 row_mirror row_mask:0xf bank_mask:0xf bound_ctrl:1
	s_nop 1
	v_readlane_b32 s98, v183, 0
	v_readlane_b32 s99, v183, 16
	v_readlane_b32 s100, v183, 32
	v_readlane_b32 s101, v183, 48
	s_nop 1
	v_mov_b32_e32 v183, s98
	v_add_f32_e32 v183, s99, v183
	v_add_f32_e32 v183, s100, v183
	v_add_f32_e32 v183, s101, v183
	v_fmamk_f32 v183, v183, 0x3a800000, v182
	v_cmp_gt_f32_e32 vcc, 0x800000, v183
	v_mul_f32_e32 v181, 0x4b800000, v183
	s_nop 1
	v_cndmask_b32_e32 v183, v183, v181, vcc
	v_rsq_f32_e32 v183, v183
	s_nop 0
	v_mul_f32_e32 v181, 0x45800000, v183
	v_cndmask_b32_e32 v184, v183, v181, vcc
	v_mov_b32_e32 v185, v184
	v_cvt_pk_bf16_f32 v32, v144, v145
	v_cvt_pk_bf16_f32 v33, v146, v147
	v_cvt_pk_bf16_f32 v34, v148, v149
	v_cvt_pk_bf16_f32 v35, v150, v151
	v_cvt_pk_bf16_f32 v36, v152, v153
	v_cvt_pk_bf16_f32 v37, v154, v155
	v_cvt_pk_bf16_f32 v38, v156, v157
	v_cvt_pk_bf16_f32 v39, v158, v159
	v_add_u32_e32 v181, 0x2000000, v177
	global_store_dwordx4 v181, v[32:35], s[78:79]
	global_store_dwordx4 v181, v[36:39], s[78:79] offset:1024
	v_add_u32_e32 v236, 0x4000, v237
	s_mov_b64 exec, 1
	global_store_dword v236, v184, s[78:79]
	s_mov_b64 exec, -1
	s_waitcnt vmcnt(16)
	v_lshlrev_b32_e32 v144, 16, v48
	v_and_b32_e32 v145, 0xffff0000, v48
	v_lshlrev_b32_e32 v146, 16, v49
	v_and_b32_e32 v147, 0xffff0000, v49
	v_lshlrev_b32_e32 v148, 16, v50
	v_and_b32_e32 v149, 0xffff0000, v50
	v_lshlrev_b32_e32 v150, 16, v51
	v_and_b32_e32 v151, 0xffff0000, v51
	v_lshlrev_b32_e32 v152, 16, v52
	v_and_b32_e32 v153, 0xffff0000, v52
	v_lshlrev_b32_e32 v154, 16, v53
	v_and_b32_e32 v155, 0xffff0000, v53
	v_lshlrev_b32_e32 v156, 16, v54
	v_and_b32_e32 v157, 0xffff0000, v54
	v_lshlrev_b32_e32 v158, 16, v55
	v_and_b32_e32 v159, 0xffff0000, v55
	v_lshlrev_b32_e32 v160, 16, v56
	v_and_b32_e32 v161, 0xffff0000, v56
	v_lshlrev_b32_e32 v162, 16, v57
	v_and_b32_e32 v163, 0xffff0000, v57
	v_lshlrev_b32_e32 v164, 16, v58
	v_and_b32_e32 v165, 0xffff0000, v58
	v_lshlrev_b32_e32 v166, 16, v59
	v_and_b32_e32 v167, 0xffff0000, v59
	v_lshlrev_b32_e32 v168, 16, v60
	v_and_b32_e32 v169, 0xffff0000, v60
	v_lshlrev_b32_e32 v170, 16, v61
	v_and_b32_e32 v171, 0xffff0000, v61
	v_lshlrev_b32_e32 v172, 16, v62
	v_and_b32_e32 v173, 0xffff0000, v62
	v_lshlrev_b32_e32 v174, 16, v63
	v_and_b32_e32 v175, 0xffff0000, v63
	v_pk_mul_f32 v[252:253], v[160:161], v[160:161]
	v_pk_mul_f32 v[254:255], v[162:163], v[162:163]
	v_pk_fma_f32 v[252:253], v[164:165], v[164:165], v[252:253]
	v_pk_fma_f32 v[254:255], v[166:167], v[166:167], v[254:255]
	v_pk_fma_f32 v[252:253], v[168:169], v[168:169], v[252:253]
	v_pk_fma_f32 v[254:255], v[170:171], v[170:171], v[254:255]
	v_pk_fma_f32 v[252:253], v[172:173], v[172:173], v[252:253]
	v_pk_fma_f32 v[254:255], v[174:175], v[174:175], v[254:255]
	v_pk_add_f32 v[252:253], v[252:253], v[254:255]
	s_nop 0
	v_add_f32_e32 v183, v252, v253
	s_nop 1
	v_add_f32_dpp v183, v183, v183 quad_perm:[1,0,3,2] row_mask:0xf bank_mask:0xf bound_ctrl:1
	s_nop 1
	v_add_f32_dpp v183, v183, v183 quad_perm:[2,3,0,1] row_mask:0xf bank_mask:0xf bound_ctrl:1
	s_nop 1
	v_add_f32_dpp v183, v183, v183 row_half_mirror row_mask:0xf bank_mask:0xf bound_ctrl:1
	s_nop 1
	v_add_f32_dpp v183, v183, v183 row_mirror row_mask:0xf bank_mask:0xf bound_ctrl:1
	s_nop 1
	v_readlane_b32 s98, v183, 0
	v_readlane_b32 s99, v183, 16
	v_readlane_b32 s100, v183, 32
	v_readlane_b32 s101, v183, 48
	s_nop 1
	v_mov_b32_e32 v183, s98
	v_add_f32_e32 v183, s99, v183
	v_add_f32_e32 v183, s100, v183
	v_add_f32_e32 v183, s101, v183
	v_fmamk_f32 v183, v183, 0x3a800000, v182
	v_cmp_gt_f32_e32 vcc, 0x800000, v183
	v_mul_f32_e32 v181, 0x4b800000, v183
	s_nop 1
	v_cndmask_b32_e32 v183, v183, v181, vcc
	v_rsq_f32_e32 v183, v183
	s_nop 0
	v_mul_f32_e32 v181, 0x45800000, v183
	v_cndmask_b32_e32 v184, v183, v181, vcc
	v_mov_b32_e32 v185, v184
	v_pk_mul_f32 v[160:161], v[160:161], v[184:185]
	v_pk_mul_f32 v[162:163], v[162:163], v[184:185]
	v_pk_mul_f32 v[164:165], v[164:165], v[184:185]
	v_pk_mul_f32 v[166:167], v[166:167], v[184:185]
	v_pk_mul_f32 v[168:169], v[168:169], v[184:185]
	v_pk_mul_f32 v[170:171], v[170:171], v[184:185]
	v_pk_mul_f32 v[172:173], v[172:173], v[184:185]
	v_pk_mul_f32 v[174:175], v[174:175], v[184:185]
	v_pk_fma_f32 v[144:145], v[160:161], v[128:129], v[144:145]
	v_pk_fma_f32 v[146:147], v[162:163], v[130:131], v[146:147]
	v_pk_fma_f32 v[148:149], v[164:165], v[132:133], v[148:149]
	v_pk_fma_f32 v[150:151], v[166:167], v[134:135], v[150:151]
	v_pk_fma_f32 v[152:153], v[168:169], v[136:137], v[152:153]
	v_pk_fma_f32 v[154:155], v[170:171], v[138:139], v[154:155]
	v_pk_fma_f32 v[156:157], v[172:173], v[140:141], v[156:157]
	v_pk_fma_f32 v[158:159], v[174:175], v[142:143], v[158:159]
	v_pk_mul_f32 v[252:253], v[144:145], v[144:145]
	v_pk_mul_f32 v[254:255], v[146:147], v[146:147]
	v_pk_fma_f32 v[252:253], v[148:149], v[148:149], v[252:253]
	v_pk_fma_f32 v[254:255], v[150:151], v[150:151], v[254:255]
	v_pk_fma_f32 v[252:253], v[152:153], v[152:153], v[252:253]
	v_pk_fma_f32 v[254:255], v[154:155], v[154:155], v[254:255]
	v_pk_fma_f32 v[252:253], v[156:157], v[156:157], v[252:253]
	v_pk_fma_f32 v[254:255], v[158:159], v[158:159], v[254:255]
	v_pk_add_f32 v[252:253], v[252:253], v[254:255]
	s_nop 0
	v_add_f32_e32 v183, v252, v253
	s_nop 1
	v_add_f32_dpp v183, v183, v183 quad_perm:[1,0,3,2] row_mask:0xf bank_mask:0xf bound_ctrl:1
	s_nop 1
	v_add_f32_dpp v183, v183, v183 quad_perm:[2,3,0,1] row_mask:0xf bank_mask:0xf bound_ctrl:1
	s_nop 1
	v_add_f32_dpp v183, v183, v183 row_half_mirror row_mask:0xf bank_mask:0xf bound_ctrl:1
	s_nop 1
	v_add_f32_dpp v183, v183, v183 row_mirror row_mask:0xf bank_mask:0xf bound_ctrl:1
	s_nop 1
	v_readlane_b32 s98, v183, 0
	v_readlane_b32 s99, v183, 16
	v_readlane_b32 s100, v183, 32
	v_readlane_b32 s101, v183, 48
	s_nop 1
	v_mov_b32_e32 v183, s98
	v_add_f32_e32 v183, s99, v183
	v_add_f32_e32 v183, s100, v183
	v_add_f32_e32 v183, s101, v183
	v_fmamk_f32 v183, v183, 0x3a800000, v182
	v_cmp_gt_f32_e32 vcc, 0x800000, v183
	v_mul_f32_e32 v181, 0x4b800000, v183
	s_nop 1
	v_cndmask_b32_e32 v183, v183, v181, vcc
	v_rsq_f32_e32 v183, v183
	s_nop 0
	v_mul_f32_e32 v181, 0x45800000, v183
	v_cndmask_b32_e32 v184, v183, v181, vcc
	v_mov_b32_e32 v185, v184
	v_cvt_pk_bf16_f32 v48, v144, v145
	v_cvt_pk_bf16_f32 v49, v146, v147
	v_cvt_pk_bf16_f32 v50, v148, v149
	v_cvt_pk_bf16_f32 v51, v150, v151
	v_cvt_pk_bf16_f32 v52, v152, v153
	v_cvt_pk_bf16_f32 v53, v154, v155
	v_cvt_pk_bf16_f32 v54, v156, v157
	v_cvt_pk_bf16_f32 v55, v158, v159
	v_add_u32_e32 v181, 0x2400000, v177
	global_store_dwordx4 v181, v[48:51], s[78:79]
	global_store_dwordx4 v181, v[52:55], s[78:79] offset:1024
	v_add_u32_e32 v236, 0x6000, v237
	s_mov_b64 exec, 1
	global_store_dword v236, v184, s[78:79]
	s_mov_b64 exec, -1
	s_waitcnt vmcnt(12)
	v_lshlrev_b32_e32 v144, 16, v64
	v_and_b32_e32 v145, 0xffff0000, v64
	v_lshlrev_b32_e32 v146, 16, v65
	v_and_b32_e32 v147, 0xffff0000, v65
	v_lshlrev_b32_e32 v148, 16, v66
	v_and_b32_e32 v149, 0xffff0000, v66
	v_lshlrev_b32_e32 v150, 16, v67
	v_and_b32_e32 v151, 0xffff0000, v67
	v_lshlrev_b32_e32 v152, 16, v68
	v_and_b32_e32 v153, 0xffff0000, v68
	v_lshlrev_b32_e32 v154, 16, v69
	v_and_b32_e32 v155, 0xffff0000, v69
	v_lshlrev_b32_e32 v156, 16, v70
	v_and_b32_e32 v157, 0xffff0000, v70
	v_lshlrev_b32_e32 v158, 16, v71
	v_and_b32_e32 v159, 0xffff0000, v71
	v_lshlrev_b32_e32 v160, 16, v72
	v_and_b32_e32 v161, 0xffff0000, v72
	v_lshlrev_b32_e32 v162, 16, v73
	v_and_b32_e32 v163, 0xffff0000, v73
	v_lshlrev_b32_e32 v164, 16, v74
	v_and_b32_e32 v165, 0xffff0000, v74
	v_lshlrev_b32_e32 v166, 16, v75
	v_and_b32_e32 v167, 0xffff0000, v75
	v_lshlrev_b32_e32 v168, 16, v76
	v_and_b32_e32 v169, 0xffff0000, v76
	v_lshlrev_b32_e32 v170, 16, v77
	v_and_b32_e32 v171, 0xffff0000, v77
	v_lshlrev_b32_e32 v172, 16, v78
	v_and_b32_e32 v173, 0xffff0000, v78
	v_lshlrev_b32_e32 v174, 16, v79
	v_and_b32_e32 v175, 0xffff0000, v79
	v_pk_mul_f32 v[252:253], v[160:161], v[160:161]
	v_pk_mul_f32 v[254:255], v[162:163], v[162:163]
	v_pk_fma_f32 v[252:253], v[164:165], v[164:165], v[252:253]
	v_pk_fma_f32 v[254:255], v[166:167], v[166:167], v[254:255]
	v_pk_fma_f32 v[252:253], v[168:169], v[168:169], v[252:253]
	v_pk_fma_f32 v[254:255], v[170:171], v[170:171], v[254:255]
	v_pk_fma_f32 v[252:253], v[172:173], v[172:173], v[252:253]
	v_pk_fma_f32 v[254:255], v[174:175], v[174:175], v[254:255]
	v_pk_add_f32 v[252:253], v[252:253], v[254:255]
	s_nop 0
	v_add_f32_e32 v183, v252, v253
	s_nop 1
	v_add_f32_dpp v183, v183, v183 quad_perm:[1,0,3,2] row_mask:0xf bank_mask:0xf bound_ctrl:1
	s_nop 1
	v_add_f32_dpp v183, v183, v183 quad_perm:[2,3,0,1] row_mask:0xf bank_mask:0xf bound_ctrl:1
	s_nop 1
	v_add_f32_dpp v183, v183, v183 row_half_mirror row_mask:0xf bank_mask:0xf bound_ctrl:1
	s_nop 1
	v_add_f32_dpp v183, v183, v183 row_mirror row_mask:0xf bank_mask:0xf bound_ctrl:1
	s_nop 1
	v_readlane_b32 s98, v183, 0
	v_readlane_b32 s99, v183, 16
	v_readlane_b32 s100, v183, 32
	v_readlane_b32 s101, v183, 48
	s_nop 1
	v_mov_b32_e32 v183, s98
	v_add_f32_e32 v183, s99, v183
	v_add_f32_e32 v183, s100, v183
	v_add_f32_e32 v183, s101, v183
	v_fmamk_f32 v183, v183, 0x3a800000, v182
	v_cmp_gt_f32_e32 vcc, 0x800000, v183
	v_mul_f32_e32 v181, 0x4b800000, v183
	s_nop 1
	v_cndmask_b32_e32 v183, v183, v181, vcc
	v_rsq_f32_e32 v183, v183
	s_nop 0
	v_mul_f32_e32 v181, 0x45800000, v183
	v_cndmask_b32_e32 v184, v183, v181, vcc
	v_mov_b32_e32 v185, v184
	v_pk_mul_f32 v[160:161], v[160:161], v[184:185]
	v_pk_mul_f32 v[162:163], v[162:163], v[184:185]
	v_pk_mul_f32 v[164:165], v[164:165], v[184:185]
	v_pk_mul_f32 v[166:167], v[166:167], v[184:185]
	v_pk_mul_f32 v[168:169], v[168:169], v[184:185]
	v_pk_mul_f32 v[170:171], v[170:171], v[184:185]
	v_pk_mul_f32 v[172:173], v[172:173], v[184:185]
	v_pk_mul_f32 v[174:175], v[174:175], v[184:185]
	v_pk_fma_f32 v[144:145], v[160:161], v[128:129], v[144:145]
	v_pk_fma_f32 v[146:147], v[162:163], v[130:131], v[146:147]
	v_pk_fma_f32 v[148:149], v[164:165], v[132:133], v[148:149]
	v_pk_fma_f32 v[150:151], v[166:167], v[134:135], v[150:151]
	v_pk_fma_f32 v[152:153], v[168:169], v[136:137], v[152:153]
	v_pk_fma_f32 v[154:155], v[170:171], v[138:139], v[154:155]
	v_pk_fma_f32 v[156:157], v[172:173], v[140:141], v[156:157]
	v_pk_fma_f32 v[158:159], v[174:175], v[142:143], v[158:159]
	v_pk_mul_f32 v[252:253], v[144:145], v[144:145]
	v_pk_mul_f32 v[254:255], v[146:147], v[146:147]
	v_pk_fma_f32 v[252:253], v[148:149], v[148:149], v[252:253]
	v_pk_fma_f32 v[254:255], v[150:151], v[150:151], v[254:255]
	v_pk_fma_f32 v[252:253], v[152:153], v[152:153], v[252:253]
	v_pk_fma_f32 v[254:255], v[154:155], v[154:155], v[254:255]
	v_pk_fma_f32 v[252:253], v[156:157], v[156:157], v[252:253]
	v_pk_fma_f32 v[254:255], v[158:159], v[158:159], v[254:255]
	v_pk_add_f32 v[252:253], v[252:253], v[254:255]
	s_nop 0
	v_add_f32_e32 v183, v252, v253
	s_nop 1
	v_add_f32_dpp v183, v183, v183 quad_perm:[1,0,3,2] row_mask:0xf bank_mask:0xf bound_ctrl:1
	s_nop 1
	v_add_f32_dpp v183, v183, v183 quad_perm:[2,3,0,1] row_mask:0xf bank_mask:0xf bound_ctrl:1
	s_nop 1
	v_add_f32_dpp v183, v183, v183 row_half_mirror row_mask:0xf bank_mask:0xf bound_ctrl:1
	s_nop 1
	v_add_f32_dpp v183, v183, v183 row_mirror row_mask:0xf bank_mask:0xf bound_ctrl:1
	s_nop 1
	v_readlane_b32 s98, v183, 0
	v_readlane_b32 s99, v183, 16
	v_readlane_b32 s100, v183, 32
	v_readlane_b32 s101, v183, 48
	s_nop 1
	v_mov_b32_e32 v183, s98
	v_add_f32_e32 v183, s99, v183
	v_add_f32_e32 v183, s100, v183
	v_add_f32_e32 v183, s101, v183
	v_fmamk_f32 v183, v183, 0x3a800000, v182
	v_cmp_gt_f32_e32 vcc, 0x800000, v183
	v_mul_f32_e32 v181, 0x4b800000, v183
	s_nop 1
	v_cndmask_b32_e32 v183, v183, v181, vcc
	v_rsq_f32_e32 v183, v183
	s_nop 0
	v_mul_f32_e32 v181, 0x45800000, v183
	v_cndmask_b32_e32 v184, v183, v181, vcc
	v_mov_b32_e32 v185, v184
	v_cvt_pk_bf16_f32 v64, v144, v145
	v_cvt_pk_bf16_f32 v65, v146, v147
	v_cvt_pk_bf16_f32 v66, v148, v149
	v_cvt_pk_bf16_f32 v67, v150, v151
	v_cvt_pk_bf16_f32 v68, v152, v153
	v_cvt_pk_bf16_f32 v69, v154, v155
	v_cvt_pk_bf16_f32 v70, v156, v157
	v_cvt_pk_bf16_f32 v71, v158, v159
	v_add_u32_e32 v181, 0x2800000, v177
	global_store_dwordx4 v181, v[64:67], s[78:79]
	global_store_dwordx4 v181, v[68:71], s[78:79] offset:1024
	v_add_u32_e32 v236, 0x8000, v237
	s_mov_b64 exec, 1
	global_store_dword v236, v184, s[78:79]
	s_mov_b64 exec, -1
	s_waitcnt vmcnt(8)
	v_lshlrev_b32_e32 v144, 16, v80
	v_and_b32_e32 v145, 0xffff0000, v80
	v_lshlrev_b32_e32 v146, 16, v81
	v_and_b32_e32 v147, 0xffff0000, v81
	v_lshlrev_b32_e32 v148, 16, v82
	v_and_b32_e32 v149, 0xffff0000, v82
	v_lshlrev_b32_e32 v150, 16, v83
	v_and_b32_e32 v151, 0xffff0000, v83
	v_lshlrev_b32_e32 v152, 16, v84
	v_and_b32_e32 v153, 0xffff0000, v84
	v_lshlrev_b32_e32 v154, 16, v85
	v_and_b32_e32 v155, 0xffff0000, v85
	v_lshlrev_b32_e32 v156, 16, v86
	v_and_b32_e32 v157, 0xffff0000, v86
	v_lshlrev_b32_e32 v158, 16, v87
	v_and_b32_e32 v159, 0xffff0000, v87
	v_lshlrev_b32_e32 v160, 16, v88
	v_and_b32_e32 v161, 0xffff0000, v88
	v_lshlrev_b32_e32 v162, 16, v89
	v_and_b32_e32 v163, 0xffff0000, v89
	v_lshlrev_b32_e32 v164, 16, v90
	v_and_b32_e32 v165, 0xffff0000, v90
	v_lshlrev_b32_e32 v166, 16, v91
	v_and_b32_e32 v167, 0xffff0000, v91
	v_lshlrev_b32_e32 v168, 16, v92
	v_and_b32_e32 v169, 0xffff0000, v92
	v_lshlrev_b32_e32 v170, 16, v93
	v_and_b32_e32 v171, 0xffff0000, v93
	v_lshlrev_b32_e32 v172, 16, v94
	v_and_b32_e32 v173, 0xffff0000, v94
	v_lshlrev_b32_e32 v174, 16, v95
	v_and_b32_e32 v175, 0xffff0000, v95
	v_pk_mul_f32 v[252:253], v[160:161], v[160:161]
	v_pk_mul_f32 v[254:255], v[162:163], v[162:163]
	v_pk_fma_f32 v[252:253], v[164:165], v[164:165], v[252:253]
	v_pk_fma_f32 v[254:255], v[166:167], v[166:167], v[254:255]
	v_pk_fma_f32 v[252:253], v[168:169], v[168:169], v[252:253]
	v_pk_fma_f32 v[254:255], v[170:171], v[170:171], v[254:255]
	v_pk_fma_f32 v[252:253], v[172:173], v[172:173], v[252:253]
	v_pk_fma_f32 v[254:255], v[174:175], v[174:175], v[254:255]
	v_pk_add_f32 v[252:253], v[252:253], v[254:255]
	s_nop 0
	v_add_f32_e32 v183, v252, v253
	s_nop 1
	v_add_f32_dpp v183, v183, v183 quad_perm:[1,0,3,2] row_mask:0xf bank_mask:0xf bound_ctrl:1
	s_nop 1
	v_add_f32_dpp v183, v183, v183 quad_perm:[2,3,0,1] row_mask:0xf bank_mask:0xf bound_ctrl:1
	s_nop 1
	v_add_f32_dpp v183, v183, v183 row_half_mirror row_mask:0xf bank_mask:0xf bound_ctrl:1
	s_nop 1
	v_add_f32_dpp v183, v183, v183 row_mirror row_mask:0xf bank_mask:0xf bound_ctrl:1
	s_nop 1
	v_readlane_b32 s98, v183, 0
	v_readlane_b32 s99, v183, 16
	v_readlane_b32 s100, v183, 32
	v_readlane_b32 s101, v183, 48
	s_nop 1
	v_mov_b32_e32 v183, s98
	v_add_f32_e32 v183, s99, v183
	v_add_f32_e32 v183, s100, v183
	v_add_f32_e32 v183, s101, v183
	v_fmamk_f32 v183, v183, 0x3a800000, v182
	v_cmp_gt_f32_e32 vcc, 0x800000, v183
	v_mul_f32_e32 v181, 0x4b800000, v183
	s_nop 1
	v_cndmask_b32_e32 v183, v183, v181, vcc
	v_rsq_f32_e32 v183, v183
	s_nop 0
	v_mul_f32_e32 v181, 0x45800000, v183
	v_cndmask_b32_e32 v184, v183, v181, vcc
	v_mov_b32_e32 v185, v184
	v_pk_mul_f32 v[160:161], v[160:161], v[184:185]
	v_pk_mul_f32 v[162:163], v[162:163], v[184:185]
	v_pk_mul_f32 v[164:165], v[164:165], v[184:185]
	v_pk_mul_f32 v[166:167], v[166:167], v[184:185]
	v_pk_mul_f32 v[168:169], v[168:169], v[184:185]
	v_pk_mul_f32 v[170:171], v[170:171], v[184:185]
	v_pk_mul_f32 v[172:173], v[172:173], v[184:185]
	v_pk_mul_f32 v[174:175], v[174:175], v[184:185]
	v_pk_fma_f32 v[144:145], v[160:161], v[128:129], v[144:145]
	v_pk_fma_f32 v[146:147], v[162:163], v[130:131], v[146:147]
	v_pk_fma_f32 v[148:149], v[164:165], v[132:133], v[148:149]
	v_pk_fma_f32 v[150:151], v[166:167], v[134:135], v[150:151]
	v_pk_fma_f32 v[152:153], v[168:169], v[136:137], v[152:153]
	v_pk_fma_f32 v[154:155], v[170:171], v[138:139], v[154:155]
	v_pk_fma_f32 v[156:157], v[172:173], v[140:141], v[156:157]
	v_pk_fma_f32 v[158:159], v[174:175], v[142:143], v[158:159]
	v_pk_mul_f32 v[252:253], v[144:145], v[144:145]
	v_pk_mul_f32 v[254:255], v[146:147], v[146:147]
	v_pk_fma_f32 v[252:253], v[148:149], v[148:149], v[252:253]
	v_pk_fma_f32 v[254:255], v[150:151], v[150:151], v[254:255]
	v_pk_fma_f32 v[252:253], v[152:153], v[152:153], v[252:253]
	v_pk_fma_f32 v[254:255], v[154:155], v[154:155], v[254:255]
	v_pk_fma_f32 v[252:253], v[156:157], v[156:157], v[252:253]
	v_pk_fma_f32 v[254:255], v[158:159], v[158:159], v[254:255]
	v_pk_add_f32 v[252:253], v[252:253], v[254:255]
	s_nop 0
	v_add_f32_e32 v183, v252, v253
	s_nop 1
	v_add_f32_dpp v183, v183, v183 quad_perm:[1,0,3,2] row_mask:0xf bank_mask:0xf bound_ctrl:1
	s_nop 1
	v_add_f32_dpp v183, v183, v183 quad_perm:[2,3,0,1] row_mask:0xf bank_mask:0xf bound_ctrl:1
	s_nop 1
	v_add_f32_dpp v183, v183, v183 row_half_mirror row_mask:0xf bank_mask:0xf bound_ctrl:1
	s_nop 1
	v_add_f32_dpp v183, v183, v183 row_mirror row_mask:0xf bank_mask:0xf bound_ctrl:1
	s_nop 1
	v_readlane_b32 s98, v183, 0
	v_readlane_b32 s99, v183, 16
	v_readlane_b32 s100, v183, 32
	v_readlane_b32 s101, v183, 48
	s_nop 1
	v_mov_b32_e32 v183, s98
	v_add_f32_e32 v183, s99, v183
	v_add_f32_e32 v183, s100, v183
	v_add_f32_e32 v183, s101, v183
	v_fmamk_f32 v183, v183, 0x3a800000, v182
	v_cmp_gt_f32_e32 vcc, 0x800000, v183
	v_mul_f32_e32 v181, 0x4b800000, v183
	s_nop 1
	v_cndmask_b32_e32 v183, v183, v181, vcc
	v_rsq_f32_e32 v183, v183
	s_nop 0
	v_mul_f32_e32 v181, 0x45800000, v183
	v_cndmask_b32_e32 v184, v183, v181, vcc
	v_mov_b32_e32 v185, v184
	v_cvt_pk_bf16_f32 v80, v144, v145
	v_cvt_pk_bf16_f32 v81, v146, v147
	v_cvt_pk_bf16_f32 v82, v148, v149
	v_cvt_pk_bf16_f32 v83, v150, v151
	v_cvt_pk_bf16_f32 v84, v152, v153
	v_cvt_pk_bf16_f32 v85, v154, v155
	v_cvt_pk_bf16_f32 v86, v156, v157
	v_cvt_pk_bf16_f32 v87, v158, v159
	v_add_u32_e32 v181, 0x2c00000, v177
	global_store_dwordx4 v181, v[80:83], s[78:79]
	global_store_dwordx4 v181, v[84:87], s[78:79] offset:1024
	v_add_u32_e32 v236, 0xa000, v237
	s_mov_b64 exec, 1
	global_store_dword v236, v184, s[78:79]
	s_mov_b64 exec, -1
	s_waitcnt vmcnt(4)
	v_lshlrev_b32_e32 v144, 16, v96
	v_and_b32_e32 v145, 0xffff0000, v96
	v_lshlrev_b32_e32 v146, 16, v97
	v_and_b32_e32 v147, 0xffff0000, v97
	v_lshlrev_b32_e32 v148, 16, v98
	v_and_b32_e32 v149, 0xffff0000, v98
	v_lshlrev_b32_e32 v150, 16, v99
	v_and_b32_e32 v151, 0xffff0000, v99
	v_lshlrev_b32_e32 v152, 16, v100
	v_and_b32_e32 v153, 0xffff0000, v100
	v_lshlrev_b32_e32 v154, 16, v101
	v_and_b32_e32 v155, 0xffff0000, v101
	v_lshlrev_b32_e32 v156, 16, v102
	v_and_b32_e32 v157, 0xffff0000, v102
	v_lshlrev_b32_e32 v158, 16, v103
	v_and_b32_e32 v159, 0xffff0000, v103
	v_lshlrev_b32_e32 v160, 16, v104
	v_and_b32_e32 v161, 0xffff0000, v104
	v_lshlrev_b32_e32 v162, 16, v105
	v_and_b32_e32 v163, 0xffff0000, v105
	v_lshlrev_b32_e32 v164, 16, v106
	v_and_b32_e32 v165, 0xffff0000, v106
	v_lshlrev_b32_e32 v166, 16, v107
	v_and_b32_e32 v167, 0xffff0000, v107
	v_lshlrev_b32_e32 v168, 16, v108
	v_and_b32_e32 v169, 0xffff0000, v108
	v_lshlrev_b32_e32 v170, 16, v109
	v_and_b32_e32 v171, 0xffff0000, v109
	v_lshlrev_b32_e32 v172, 16, v110
	v_and_b32_e32 v173, 0xffff0000, v110
	v_lshlrev_b32_e32 v174, 16, v111
	v_and_b32_e32 v175, 0xffff0000, v111
	v_pk_mul_f32 v[252:253], v[160:161], v[160:161]
	v_pk_mul_f32 v[254:255], v[162:163], v[162:163]
	v_pk_fma_f32 v[252:253], v[164:165], v[164:165], v[252:253]
	v_pk_fma_f32 v[254:255], v[166:167], v[166:167], v[254:255]
	v_pk_fma_f32 v[252:253], v[168:169], v[168:169], v[252:253]
	v_pk_fma_f32 v[254:255], v[170:171], v[170:171], v[254:255]
	v_pk_fma_f32 v[252:253], v[172:173], v[172:173], v[252:253]
	v_pk_fma_f32 v[254:255], v[174:175], v[174:175], v[254:255]
	v_pk_add_f32 v[252:253], v[252:253], v[254:255]
	s_nop 0
	v_add_f32_e32 v183, v252, v253
	s_nop 1
	v_add_f32_dpp v183, v183, v183 quad_perm:[1,0,3,2] row_mask:0xf bank_mask:0xf bound_ctrl:1
	s_nop 1
	v_add_f32_dpp v183, v183, v183 quad_perm:[2,3,0,1] row_mask:0xf bank_mask:0xf bound_ctrl:1
	s_nop 1
	v_add_f32_dpp v183, v183, v183 row_half_mirror row_mask:0xf bank_mask:0xf bound_ctrl:1
	s_nop 1
	v_add_f32_dpp v183, v183, v183 row_mirror row_mask:0xf bank_mask:0xf bound_ctrl:1
	s_nop 1
	v_readlane_b32 s98, v183, 0
	v_readlane_b32 s99, v183, 16
	v_readlane_b32 s100, v183, 32
	v_readlane_b32 s101, v183, 48
	s_nop 1
	v_mov_b32_e32 v183, s98
	v_add_f32_e32 v183, s99, v183
	v_add_f32_e32 v183, s100, v183
	v_add_f32_e32 v183, s101, v183
	v_fmamk_f32 v183, v183, 0x3a800000, v182
	v_cmp_gt_f32_e32 vcc, 0x800000, v183
	v_mul_f32_e32 v181, 0x4b800000, v183
	s_nop 1
	v_cndmask_b32_e32 v183, v183, v181, vcc
	v_rsq_f32_e32 v183, v183
	s_nop 0
	v_mul_f32_e32 v181, 0x45800000, v183
	v_cndmask_b32_e32 v184, v183, v181, vcc
	v_mov_b32_e32 v185, v184
	v_pk_mul_f32 v[160:161], v[160:161], v[184:185]
	v_pk_mul_f32 v[162:163], v[162:163], v[184:185]
	v_pk_mul_f32 v[164:165], v[164:165], v[184:185]
	v_pk_mul_f32 v[166:167], v[166:167], v[184:185]
	v_pk_mul_f32 v[168:169], v[168:169], v[184:185]
	v_pk_mul_f32 v[170:171], v[170:171], v[184:185]
	v_pk_mul_f32 v[172:173], v[172:173], v[184:185]
	v_pk_mul_f32 v[174:175], v[174:175], v[184:185]
	v_pk_fma_f32 v[144:145], v[160:161], v[128:129], v[144:145]
	v_pk_fma_f32 v[146:147], v[162:163], v[130:131], v[146:147]
	v_pk_fma_f32 v[148:149], v[164:165], v[132:133], v[148:149]
	v_pk_fma_f32 v[150:151], v[166:167], v[134:135], v[150:151]
	v_pk_fma_f32 v[152:153], v[168:169], v[136:137], v[152:153]
	v_pk_fma_f32 v[154:155], v[170:171], v[138:139], v[154:155]
	v_pk_fma_f32 v[156:157], v[172:173], v[140:141], v[156:157]
	v_pk_fma_f32 v[158:159], v[174:175], v[142:143], v[158:159]
	v_pk_mul_f32 v[252:253], v[144:145], v[144:145]
	v_pk_mul_f32 v[254:255], v[146:147], v[146:147]
	v_pk_fma_f32 v[252:253], v[148:149], v[148:149], v[252:253]
	v_pk_fma_f32 v[254:255], v[150:151], v[150:151], v[254:255]
	v_pk_fma_f32 v[252:253], v[152:153], v[152:153], v[252:253]
	v_pk_fma_f32 v[254:255], v[154:155], v[154:155], v[254:255]
	v_pk_fma_f32 v[252:253], v[156:157], v[156:157], v[252:253]
	v_pk_fma_f32 v[254:255], v[158:159], v[158:159], v[254:255]
	v_pk_add_f32 v[252:253], v[252:253], v[254:255]
	s_nop 0
	v_add_f32_e32 v183, v252, v253
	s_nop 1
	v_add_f32_dpp v183, v183, v183 quad_perm:[1,0,3,2] row_mask:0xf bank_mask:0xf bound_ctrl:1
	s_nop 1
	v_add_f32_dpp v183, v183, v183 quad_perm:[2,3,0,1] row_mask:0xf bank_mask:0xf bound_ctrl:1
	s_nop 1
	v_add_f32_dpp v183, v183, v183 row_half_mirror row_mask:0xf bank_mask:0xf bound_ctrl:1
	s_nop 1
	v_add_f32_dpp v183, v183, v183 row_mirror row_mask:0xf bank_mask:0xf bound_ctrl:1
	s_nop 1
	v_readlane_b32 s98, v183, 0
	v_readlane_b32 s99, v183, 16
	v_readlane_b32 s100, v183, 32
	v_readlane_b32 s101, v183, 48
	s_nop 1
	v_mov_b32_e32 v183, s98
	v_add_f32_e32 v183, s99, v183
	v_add_f32_e32 v183, s100, v183
	v_add_f32_e32 v183, s101, v183
	v_fmamk_f32 v183, v183, 0x3a800000, v182
	v_cmp_gt_f32_e32 vcc, 0x800000, v183
	v_mul_f32_e32 v181, 0x4b800000, v183
	s_nop 1
	v_cndmask_b32_e32 v183, v183, v181, vcc
	v_rsq_f32_e32 v183, v183
	s_nop 0
	v_mul_f32_e32 v181, 0x45800000, v183
	v_cndmask_b32_e32 v184, v183, v181, vcc
	v_mov_b32_e32 v185, v184
	v_cvt_pk_bf16_f32 v96, v144, v145
	v_cvt_pk_bf16_f32 v97, v146, v147
	v_cvt_pk_bf16_f32 v98, v148, v149
	v_cvt_pk_bf16_f32 v99, v150, v151
	v_cvt_pk_bf16_f32 v100, v152, v153
	v_cvt_pk_bf16_f32 v101, v154, v155
	v_cvt_pk_bf16_f32 v102, v156, v157
	v_cvt_pk_bf16_f32 v103, v158, v159
	v_add_u32_e32 v181, 0x3000000, v177
	global_store_dwordx4 v181, v[96:99], s[78:79]
	global_store_dwordx4 v181, v[100:103], s[78:79] offset:1024
	v_add_u32_e32 v236, 0xc000, v237
	s_mov_b64 exec, 1
	global_store_dword v236, v184, s[78:79]
	s_mov_b64 exec, -1
	s_waitcnt vmcnt(0)
	v_lshlrev_b32_e32 v144, 16, v112
	v_and_b32_e32 v145, 0xffff0000, v112
	v_lshlrev_b32_e32 v146, 16, v113
	v_and_b32_e32 v147, 0xffff0000, v113
	v_lshlrev_b32_e32 v148, 16, v114
	v_and_b32_e32 v149, 0xffff0000, v114
	v_lshlrev_b32_e32 v150, 16, v115
	v_and_b32_e32 v151, 0xffff0000, v115
	v_lshlrev_b32_e32 v152, 16, v116
	v_and_b32_e32 v153, 0xffff0000, v116
	v_lshlrev_b32_e32 v154, 16, v117
	v_and_b32_e32 v155, 0xffff0000, v117
	v_lshlrev_b32_e32 v156, 16, v118
	v_and_b32_e32 v157, 0xffff0000, v118
	v_lshlrev_b32_e32 v158, 16, v119
	v_and_b32_e32 v159, 0xffff0000, v119
	v_lshlrev_b32_e32 v160, 16, v120
	v_and_b32_e32 v161, 0xffff0000, v120
	v_lshlrev_b32_e32 v162, 16, v121
	v_and_b32_e32 v163, 0xffff0000, v121
	v_lshlrev_b32_e32 v164, 16, v122
	v_and_b32_e32 v165, 0xffff0000, v122
	v_lshlrev_b32_e32 v166, 16, v123
	v_and_b32_e32 v167, 0xffff0000, v123
	v_lshlrev_b32_e32 v168, 16, v124
	v_and_b32_e32 v169, 0xffff0000, v124
	v_lshlrev_b32_e32 v170, 16, v125
	v_and_b32_e32 v171, 0xffff0000, v125
	v_lshlrev_b32_e32 v172, 16, v126
	v_and_b32_e32 v173, 0xffff0000, v126
	v_lshlrev_b32_e32 v174, 16, v127
	v_and_b32_e32 v175, 0xffff0000, v127
	v_pk_mul_f32 v[252:253], v[160:161], v[160:161]
	v_pk_mul_f32 v[254:255], v[162:163], v[162:163]
	v_pk_fma_f32 v[252:253], v[164:165], v[164:165], v[252:253]
	v_pk_fma_f32 v[254:255], v[166:167], v[166:167], v[254:255]
	v_pk_fma_f32 v[252:253], v[168:169], v[168:169], v[252:253]
	v_pk_fma_f32 v[254:255], v[170:171], v[170:171], v[254:255]
	v_pk_fma_f32 v[252:253], v[172:173], v[172:173], v[252:253]
	v_pk_fma_f32 v[254:255], v[174:175], v[174:175], v[254:255]
	v_pk_add_f32 v[252:253], v[252:253], v[254:255]
	s_nop 0
	v_add_f32_e32 v183, v252, v253
	s_nop 1
	v_add_f32_dpp v183, v183, v183 quad_perm:[1,0,3,2] row_mask:0xf bank_mask:0xf bound_ctrl:1
	s_nop 1
	v_add_f32_dpp v183, v183, v183 quad_perm:[2,3,0,1] row_mask:0xf bank_mask:0xf bound_ctrl:1
	s_nop 1
	v_add_f32_dpp v183, v183, v183 row_half_mirror row_mask:0xf bank_mask:0xf bound_ctrl:1
	s_nop 1
	v_add_f32_dpp v183, v183, v183 row_mirror row_mask:0xf bank_mask:0xf bound_ctrl:1
	s_nop 1
	v_readlane_b32 s98, v183, 0
	v_readlane_b32 s99, v183, 16
	v_readlane_b32 s100, v183, 32
	v_readlane_b32 s101, v183, 48
	s_nop 1
	v_mov_b32_e32 v183, s98
	v_add_f32_e32 v183, s99, v183
	v_add_f32_e32 v183, s100, v183
	v_add_f32_e32 v183, s101, v183
	v_fmamk_f32 v183, v183, 0x3a800000, v182
	v_cmp_gt_f32_e32 vcc, 0x800000, v183
	v_mul_f32_e32 v181, 0x4b800000, v183
	s_nop 1
	v_cndmask_b32_e32 v183, v183, v181, vcc
	v_rsq_f32_e32 v183, v183
	s_nop 0
	v_mul_f32_e32 v181, 0x45800000, v183
	v_cndmask_b32_e32 v184, v183, v181, vcc
	v_mov_b32_e32 v185, v184
	v_pk_mul_f32 v[160:161], v[160:161], v[184:185]
	v_pk_mul_f32 v[162:163], v[162:163], v[184:185]
	v_pk_mul_f32 v[164:165], v[164:165], v[184:185]
	v_pk_mul_f32 v[166:167], v[166:167], v[184:185]
	v_pk_mul_f32 v[168:169], v[168:169], v[184:185]
	v_pk_mul_f32 v[170:171], v[170:171], v[184:185]
	v_pk_mul_f32 v[172:173], v[172:173], v[184:185]
	v_pk_mul_f32 v[174:175], v[174:175], v[184:185]
	v_pk_fma_f32 v[144:145], v[160:161], v[128:129], v[144:145]
	v_pk_fma_f32 v[146:147], v[162:163], v[130:131], v[146:147]
	v_pk_fma_f32 v[148:149], v[164:165], v[132:133], v[148:149]
	v_pk_fma_f32 v[150:151], v[166:167], v[134:135], v[150:151]
	v_pk_fma_f32 v[152:153], v[168:169], v[136:137], v[152:153]
	v_pk_fma_f32 v[154:155], v[170:171], v[138:139], v[154:155]
	v_pk_fma_f32 v[156:157], v[172:173], v[140:141], v[156:157]
	v_pk_fma_f32 v[158:159], v[174:175], v[142:143], v[158:159]
	v_pk_mul_f32 v[252:253], v[144:145], v[144:145]
	v_pk_mul_f32 v[254:255], v[146:147], v[146:147]
	v_pk_fma_f32 v[252:253], v[148:149], v[148:149], v[252:253]
	v_pk_fma_f32 v[254:255], v[150:151], v[150:151], v[254:255]
	v_pk_fma_f32 v[252:253], v[152:153], v[152:153], v[252:253]
	v_pk_fma_f32 v[254:255], v[154:155], v[154:155], v[254:255]
	v_pk_fma_f32 v[252:253], v[156:157], v[156:157], v[252:253]
	v_pk_fma_f32 v[254:255], v[158:159], v[158:159], v[254:255]
	v_pk_add_f32 v[252:253], v[252:253], v[254:255]
	s_nop 0
	v_add_f32_e32 v183, v252, v253
	s_nop 1
	v_add_f32_dpp v183, v183, v183 quad_perm:[1,0,3,2] row_mask:0xf bank_mask:0xf bound_ctrl:1
	s_nop 1
	v_add_f32_dpp v183, v183, v183 quad_perm:[2,3,0,1] row_mask:0xf bank_mask:0xf bound_ctrl:1
	s_nop 1
	v_add_f32_dpp v183, v183, v183 row_half_mirror row_mask:0xf bank_mask:0xf bound_ctrl:1
	s_nop 1
	v_add_f32_dpp v183, v183, v183 row_mirror row_mask:0xf bank_mask:0xf bound_ctrl:1
	s_nop 1
	v_readlane_b32 s98, v183, 0
	v_readlane_b32 s99, v183, 16
	v_readlane_b32 s100, v183, 32
	v_readlane_b32 s101, v183, 48
	s_nop 1
	v_mov_b32_e32 v183, s98
	v_add_f32_e32 v183, s99, v183
	v_add_f32_e32 v183, s100, v183
	v_add_f32_e32 v183, s101, v183
	v_fmamk_f32 v183, v183, 0x3a800000, v182
	v_cmp_gt_f32_e32 vcc, 0x800000, v183
	v_mul_f32_e32 v181, 0x4b800000, v183
	s_nop 1
	v_cndmask_b32_e32 v183, v183, v181, vcc
	v_rsq_f32_e32 v183, v183
	s_nop 0
	v_mul_f32_e32 v181, 0x45800000, v183
	v_cndmask_b32_e32 v184, v183, v181, vcc
	v_mov_b32_e32 v185, v184
	v_cvt_pk_bf16_f32 v112, v144, v145
	v_cvt_pk_bf16_f32 v113, v146, v147
	v_cvt_pk_bf16_f32 v114, v148, v149
	v_cvt_pk_bf16_f32 v115, v150, v151
	v_cvt_pk_bf16_f32 v116, v152, v153
	v_cvt_pk_bf16_f32 v117, v154, v155
	v_cvt_pk_bf16_f32 v118, v156, v157
	v_cvt_pk_bf16_f32 v119, v158, v159
	v_add_u32_e32 v181, 0x3400000, v177
	global_store_dwordx4 v181, v[112:115], s[78:79]
	global_store_dwordx4 v181, v[116:119], s[78:79] offset:1024
	v_add_u32_e32 v236, 0xe000, v237
	s_mov_b64 exec, 1
	global_store_dword v236, v184, s[78:79]
	s_mov_b64 exec, -1
	v_readfirstlane_b32 s98, v179
	s_nop 3
	s_and_b32 s99, s98, 3
	s_add_i32 s100, s99, 4
	s_lshl_b32 s100, s100, 11
	s_sub_i32 s100, s100, s99
	s_lshl_b32 s101, s100, 11
	v_add_u32_e32 v177, s101, v177
	s_lshl_b32 s101, s100, 2
	v_add_u32_e32 v237, s101, v237
	v_add_u32_e32 v181, 0x1800000, v177
	global_load_dwordx4 v[0:3], v181, s[78:79]
	global_load_dwordx4 v[4:7], v181, s[78:79] offset:1024
	v_add_u32_e32 v181, 0x9e00000, v177
	global_load_dwordx4 v[8:11], v181, s[78:79]
	global_load_dwordx4 v[12:15], v181, s[78:79] offset:1024
	s_waitcnt vmcnt(0)
	v_lshlrev_b32_e32 v144, 16, v0
	v_and_b32_e32 v145, 0xffff0000, v0
	v_lshlrev_b32_e32 v146, 16, v1
	v_and_b32_e32 v147, 0xffff0000, v1
	v_lshlrev_b32_e32 v148, 16, v2
	v_and_b32_e32 v149, 0xffff0000, v2
	v_lshlrev_b32_e32 v150, 16, v3
	v_and_b32_e32 v151, 0xffff0000, v3
	v_lshlrev_b32_e32 v152, 16, v4
	v_and_b32_e32 v153, 0xffff0000, v4
	v_lshlrev_b32_e32 v154, 16, v5
	v_and_b32_e32 v155, 0xffff0000, v5
	v_lshlrev_b32_e32 v156, 16, v6
	v_and_b32_e32 v157, 0xffff0000, v6
	v_lshlrev_b32_e32 v158, 16, v7
	v_and_b32_e32 v159, 0xffff0000, v7
	v_lshlrev_b32_e32 v160, 16, v8
	v_and_b32_e32 v161, 0xffff0000, v8
	v_lshlrev_b32_e32 v162, 16, v9
	v_and_b32_e32 v163, 0xffff0000, v9
	v_lshlrev_b32_e32 v164, 16, v10
	v_and_b32_e32 v165, 0xffff0000, v10
	v_lshlrev_b32_e32 v166, 16, v11
	v_and_b32_e32 v167, 0xffff0000, v11
	v_lshlrev_b32_e32 v168, 16, v12
	v_and_b32_e32 v169, 0xffff0000, v12
	v_lshlrev_b32_e32 v170, 16, v13
	v_and_b32_e32 v171, 0xffff0000, v13
	v_lshlrev_b32_e32 v172, 16, v14
	v_and_b32_e32 v173, 0xffff0000, v14
	v_lshlrev_b32_e32 v174, 16, v15
	v_and_b32_e32 v175, 0xffff0000, v15
	v_pk_mul_f32 v[252:253], v[160:161], v[160:161]
	v_pk_mul_f32 v[254:255], v[162:163], v[162:163]
	v_pk_fma_f32 v[252:253], v[164:165], v[164:165], v[252:253]
	v_pk_fma_f32 v[254:255], v[166:167], v[166:167], v[254:255]
	v_pk_fma_f32 v[252:253], v[168:169], v[168:169], v[252:253]
	v_pk_fma_f32 v[254:255], v[170:171], v[170:171], v[254:255]
	v_pk_fma_f32 v[252:253], v[172:173], v[172:173], v[252:253]
	v_pk_fma_f32 v[254:255], v[174:175], v[174:175], v[254:255]
	v_pk_add_f32 v[252:253], v[252:253], v[254:255]
	s_nop 0
	v_add_f32_e32 v183, v252, v253
	s_nop 1
	v_add_f32_dpp v183, v183, v183 quad_perm:[1,0,3,2] row_mask:0xf bank_mask:0xf bound_ctrl:1
	s_nop 1
	v_add_f32_dpp v183, v183, v183 quad_perm:[2,3,0,1] row_mask:0xf bank_mask:0xf bound_ctrl:1
	s_nop 1
	v_add_f32_dpp v183, v183, v183 row_half_mirror row_mask:0xf bank_mask:0xf bound_ctrl:1
	s_nop 1
	v_add_f32_dpp v183, v183, v183 row_mirror row_mask:0xf bank_mask:0xf bound_ctrl:1
	s_nop 1
	v_readlane_b32 s98, v183, 0
	v_readlane_b32 s99, v183, 16
	v_readlane_b32 s100, v183, 32
	v_readlane_b32 s101, v183, 48
	s_nop 1
	v_mov_b32_e32 v183, s98
	v_add_f32_e32 v183, s99, v183
	v_add_f32_e32 v183, s100, v183
	v_add_f32_e32 v183, s101, v183
	v_fmamk_f32 v183, v183, 0x3a800000, v182
	v_cmp_gt_f32_e32 vcc, 0x800000, v183
	v_mul_f32_e32 v181, 0x4b800000, v183
	s_nop 1
	v_cndmask_b32_e32 v183, v183, v181, vcc
	v_rsq_f32_e32 v183, v183
	s_nop 0
	v_mul_f32_e32 v181, 0x45800000, v183
	v_cndmask_b32_e32 v184, v183, v181, vcc
	v_mov_b32_e32 v185, v184
	v_pk_mul_f32 v[160:161], v[160:161], v[184:185]
	v_pk_mul_f32 v[162:163], v[162:163], v[184:185]
	v_pk_mul_f32 v[164:165], v[164:165], v[184:185]
	v_pk_mul_f32 v[166:167], v[166:167], v[184:185]
	v_pk_mul_f32 v[168:169], v[168:169], v[184:185]
	v_pk_mul_f32 v[170:171], v[170:171], v[184:185]
	v_pk_mul_f32 v[172:173], v[172:173], v[184:185]
	v_pk_mul_f32 v[174:175], v[174:175], v[184:185]
	v_pk_fma_f32 v[144:145], v[160:161], v[128:129], v[144:145]
	v_pk_fma_f32 v[146:147], v[162:163], v[130:131], v[146:147]
	v_pk_fma_f32 v[148:149], v[164:165], v[132:133], v[148:149]
	v_pk_fma_f32 v[150:151], v[166:167], v[134:135], v[150:151]
	v_pk_fma_f32 v[152:153], v[168:169], v[136:137], v[152:153]
	v_pk_fma_f32 v[154:155], v[170:171], v[138:139], v[154:155]
	v_pk_fma_f32 v[156:157], v[172:173], v[140:141], v[156:157]
	v_pk_fma_f32 v[158:159], v[174:175], v[142:143], v[158:159]
	v_pk_mul_f32 v[252:253], v[144:145], v[144:145]
	v_pk_mul_f32 v[254:255], v[146:147], v[146:147]
	v_pk_fma_f32 v[252:253], v[148:149], v[148:149], v[252:253]
	v_pk_fma_f32 v[254:255], v[150:151], v[150:151], v[254:255]
	v_pk_fma_f32 v[252:253], v[152:153], v[152:153], v[252:253]
	v_pk_fma_f32 v[254:255], v[154:155], v[154:155], v[254:255]
	v_pk_fma_f32 v[252:253], v[156:157], v[156:157], v[252:253]
	v_pk_fma_f32 v[254:255], v[158:159], v[158:159], v[254:255]
	v_pk_add_f32 v[252:253], v[252:253], v[254:255]
	s_nop 0
	v_add_f32_e32 v183, v252, v253
	s_nop 1
	v_add_f32_dpp v183, v183, v183 quad_perm:[1,0,3,2] row_mask:0xf bank_mask:0xf bound_ctrl:1
	s_nop 1
	v_add_f32_dpp v183, v183, v183 quad_perm:[2,3,0,1] row_mask:0xf bank_mask:0xf bound_ctrl:1
	s_nop 1
	v_add_f32_dpp v183, v183, v183 row_half_mirror row_mask:0xf bank_mask:0xf bound_ctrl:1
	s_nop 1
	v_add_f32_dpp v183, v183, v183 row_mirror row_mask:0xf bank_mask:0xf bound_ctrl:1
	s_nop 1
	v_readlane_b32 s98, v183, 0
	v_readlane_b32 s99, v183, 16
	v_readlane_b32 s100, v183, 32
	v_readlane_b32 s101, v183, 48
	s_nop 1
	v_mov_b32_e32 v183, s98
	v_add_f32_e32 v183, s99, v183
	v_add_f32_e32 v183, s100, v183
	v_add_f32_e32 v183, s101, v183
	v_fmamk_f32 v183, v183, 0x3a800000, v182
	v_cmp_gt_f32_e32 vcc, 0x800000, v183
	v_mul_f32_e32 v181, 0x4b800000, v183
	s_nop 1
	v_cndmask_b32_e32 v183, v183, v181, vcc
	v_rsq_f32_e32 v183, v183
	s_nop 0
	v_mul_f32_e32 v181, 0x45800000, v183
	v_cndmask_b32_e32 v184, v183, v181, vcc
	v_mov_b32_e32 v185, v184
	v_cvt_pk_bf16_f32 v0, v144, v145
	v_cvt_pk_bf16_f32 v1, v146, v147
	v_cvt_pk_bf16_f32 v2, v148, v149
	v_cvt_pk_bf16_f32 v3, v150, v151
	v_cvt_pk_bf16_f32 v4, v152, v153
	v_cvt_pk_bf16_f32 v5, v154, v155
	v_cvt_pk_bf16_f32 v6, v156, v157
	v_cvt_pk_bf16_f32 v7, v158, v159
	v_add_u32_e32 v181, 0x1800000, v177
	global_store_dwordx4 v181, v[0:3], s[78:79]
	global_store_dwordx4 v181, v[4:7], s[78:79] offset:1024
	v_add_u32_e32 v236, 0x0, v237
	s_mov_b64 exec, 1
	global_store_dword v236, v184, s[78:79]
	s_mov_b64 exec, -1
	s_branch .Lmyxupd_done_6

.LBB0_2849:
	v_readlane_b32 s0, v235, 52
	v_readlane_b32 s1, v235, 53
	s_and_b64 vcc, exec, s[0:1]
	s_waitcnt lgkmcnt(0)
	s_barrier
	v_mbcnt_lo_u32_b32 v0, -1, 0
	v_mbcnt_hi_u32_b32 v0, -1, v0
	s_cbranch_vccnz .LBB0_2864
	v_lshlrev_b32_e32 v0, 3, v0
	v_ashrrev_i32_e32 v1, 31, v0
	v_readlane_b32 s0, v235, 4
	v_lshlrev_b64 v[2:3], 1, v[0:1]
	v_lshlrev_b64 v[0:1], 2, v[0:1]
	v_readlane_b32 s1, v235, 5
	v_readlane_b32 s14, v235, 18
	v_readlane_b32 s15, v235, 19
	s_mov_b64 s[0:1], 0x3000
	v_readlane_b32 s2, v235, 6
	v_lshl_add_u64 v[4:5], s[14:15], 0, v[0:1]
	v_readlane_b32 s4, v235, 8
	v_readlane_b32 s5, v235, 9
	v_lshl_add_u64 v[50:51], v[4:5], 0, s[0:1]
	v_readlane_b32 s0, v235, 0
	s_ashr_i32 s25, s24, 31
	s_lshl_b32 s0, s0, 4
	s_add_i32 s2, s24, 0xffffc000
	s_lshl_b64 s[4:5], s[24:25], 11
	s_add_u32 s4, s78, s4
	v_readlane_b32 s1, v235, 1
	s_addc_u32 s5, s79, s5
	v_lshl_add_u64 v[44:45], s[86:87], 0, v[2:3]
	v_lshl_add_u64 v[48:49], s[54:55], 0, v[2:3]
	v_readlane_b32 s6, v235, 10
	v_readlane_b32 s7, v235, 11
	v_lshl_add_u64 v[2:3], s[4:5], 0, v[2:3]
	s_mov_b64 s[4:5], 0x9e00000
	s_ashr_i32 s1, s0, 31
	v_lshl_add_u64 v[56:57], v[2:3], 0, s[4:5]
	s_lshl_b64 s[4:5], s[0:1], 11
	s_lshl_b64 s[6:7], s[24:25], 12
	s_add_u32 s6, s76, s6
	s_addc_u32 s7, s77, s7
	v_lshl_add_u64 v[46:47], s[90:91], 0, v[0:1]
	v_readlane_b32 s3, v235, 7
	v_readlane_b32 s8, v235, 12
	v_readlane_b32 s9, v235, 13
	v_readlane_b32 s10, v235, 14
	v_readlane_b32 s11, v235, 15
	v_readlane_b32 s12, v235, 16
	v_readlane_b32 s13, v235, 17
	v_lshl_add_u64 v[52:53], s[74:75], 0, v[0:1]
	v_lshl_add_u64 v[54:55], s[76:77], 0, v[0:1]
	v_lshl_add_u64 v[0:1], s[6:7], 0, v[0:1]
	s_mov_b64 s[6:7], 0x810
	v_lshl_add_u64 v[58:59], v[0:1], 0, s[6:7]
	s_lshl_b64 s[6:7], s[0:1], 12
	s_mov_b32 s3, 0
	s_mov_b64 s[8:9], 0x200000
	s_mov_b64 s[10:11], 0x200800
	s_mov_b64 s[12:13], 0x400000
	s_mov_b64 s[14:15], 0x400800
	s_mov_b64 s[16:17], 0x600000
	s_mov_b64 s[18:19], 0x600800
	s_mov_b64 s[20:21], 0x800000
	s_mov_b32 s1, 0x800000
	s_mov_b64 s[22:23], 0x800800
	s_mov_b64 s[24:25], 0xa00000
	s_mov_b64 s[26:27], 0xa00800
	s_mov_b64 s[28:29], 0xc00000
	s_mov_b64 s[30:31], 0xc00800
	s_mov_b64 s[34:35], 0xe00000
	s_mov_b64 s[36:37], 0xe00800
	s_mov_b64 s[38:39], 0x1000000
	s_mov_b32 s60, 0x1000000
	s_mov_b64 s[40:41], 0x1000800
	s_mov_b64 s[42:43], 0x1200000
	s_mov_b32 s61, 0x1200000
	s_mov_b64 s[44:45], 0x1200800
	s_mov_b64 s[46:47], 0x1400000
	s_mov_b32 s62, 0x1400000
	s_mov_b64 s[48:49], 0x1400800
	v_mov_b32_e32 v100, 0x358637bd
	v_mbcnt_lo_u32_b32 v176, -1, 0
	v_mbcnt_hi_u32_b32 v176, -1, v176
	v_readlane_b32 s98, v235, 49
	v_readlane_b32 s99, v235, 20
	v_readlane_b32 s100, v235, 18
	v_readlane_b32 s101, v235, 19
	s_nop 3
	s_lshr_b32 vcc_lo, s98, 3
	s_and_b32 vcc_hi, vcc_lo, 7
	s_lshr_b32 vcc_lo, vcc_lo, 3
	s_lshl_b32 vcc_lo, vcc_lo, 3
	s_add_i32 vcc_lo, vcc_lo, s99
	s_lshl_b32 s98, vcc_hi, 8
	s_add_i32 s98, s98, vcc_lo
	s_mov_b32 s99, s98
	v_mov_b32_e32 v183, s99
	v_lshlrev_b32_e32 v177, 4, v176
	s_lshl_b32 s99, s99, 11
	v_add_u32_e32 v177, s99, v177
	v_add_u32_e32 v178, 0x1800000, v177
	v_add_u32_e32 v179, 0x9e00000, v177
	v_lshlrev_b32_e32 v180, 5, v176
	v_add_u32_e32 v181, 0x3000, v180
	global_load_dwordx4 v[128:131], v181, s[100:101]
	global_load_dwordx4 v[132:135], v181, s[100:101] offset:16
	global_load_dwordx4 v[136:139], v181, s[100:101] offset:2048
	global_load_dwordx4 v[140:143], v181, s[100:101] offset:2064
	global_load_dwordx4 v[236:239], v180, s[74:75]
	global_load_dwordx4 v[240:243], v180, s[74:75] offset:16
	global_load_dwordx4 v[244:247], v180, s[74:75] offset:2048
	global_load_dwordx4 v[248:251], v180, s[74:75] offset:2064
	v_mov_b32_e32 v182, 0x358637bd
	s_and_b32 vcc_lo, s98, 3
	s_cmp_eq_u32 vcc_lo, 0
	s_cbranch_scc1 .Lmyxupd_heavy_7
	global_load_dwordx4 v[0:3], v178, s[78:79]
	global_load_dwordx4 v[4:7], v178, s[78:79] offset:1024
	global_load_dwordx4 v[8:11], v179, s[78:79]
	global_load_dwordx4 v[12:15], v179, s[78:79] offset:1024
	v_add_u32_e32 v178, 0x400000, v178
	v_add_u32_e32 v179, 0x400000, v179
	global_load_dwordx4 v[16:19], v178, s[78:79]
	global_load_dwordx4 v[20:23], v178, s[78:79] offset:1024
	global_load_dwordx4 v[24:27], v179, s[78:79]
	global_load_dwordx4 v[28:31], v179, s[78:79] offset:1024
	v_add_u32_e32 v178, 0x400000, v178
	v_add_u32_e32 v179, 0x400000, v179
	global_load_dwordx4 v[32:35], v178, s[78:79]
	global_load_dwordx4 v[36:39], v178, s[78:79] offset:1024
	global_load_dwordx4 v[40:43], v179, s[78:79]
	global_load_dwordx4 v[44:47], v179, s[78:79] offset:1024
	v_add_u32_e32 v178, 0x400000, v178
	v_add_u32_e32 v179, 0x400000, v179
	global_load_dwordx4 v[48:51], v178, s[78:79]
	global_load_dwordx4 v[52:55], v178, s[78:79] offset:1024
	global_load_dwordx4 v[56:59], v179, s[78:79]
	global_load_dwordx4 v[60:63], v179, s[78:79] offset:1024
	v_add_u32_e32 v178, 0x400000, v178
	v_add_u32_e32 v179, 0x400000, v179
	global_load_dwordx4 v[64:67], v178, s[78:79]
	global_load_dwordx4 v[68:71], v178, s[78:79] offset:1024
	global_load_dwordx4 v[72:75], v179, s[78:79]
	global_load_dwordx4 v[76:79], v179, s[78:79] offset:1024
	v_add_u32_e32 v178, 0x400000, v178
	v_add_u32_e32 v179, 0x400000, v179
	global_load_dwordx4 v[80:83], v178, s[78:79]
	global_load_dwordx4 v[84:87], v178, s[78:79] offset:1024
	global_load_dwordx4 v[88:91], v179, s[78:79]
	global_load_dwordx4 v[92:95], v179, s[78:79] offset:1024
	v_add_u32_e32 v178, 0x400000, v178
	v_add_u32_e32 v179, 0x400000, v179
	global_load_dwordx4 v[96:99], v178, s[78:79]
	global_load_dwordx4 v[100:103], v178, s[78:79] offset:1024
	global_load_dwordx4 v[104:107], v179, s[78:79]
	global_load_dwordx4 v[108:111], v179, s[78:79] offset:1024
	v_add_u32_e32 v178, 0x400000, v178
	v_add_u32_e32 v179, 0x400000, v179
	global_load_dwordx4 v[112:115], v178, s[78:79]
	global_load_dwordx4 v[116:119], v178, s[78:79] offset:1024
	global_load_dwordx4 v[120:123], v179, s[78:79]
	global_load_dwordx4 v[124:127], v179, s[78:79] offset:1024
	v_lshl_add_u32 v178, v183, 12, v180
	v_mov_b32_e32 v179, s98
	s_waitcnt vmcnt(28)
	v_lshlrev_b32_e32 v144, 16, v0
	v_and_b32_e32 v145, 0xffff0000, v0
	v_lshlrev_b32_e32 v146, 16, v1
	v_and_b32_e32 v147, 0xffff0000, v1
	v_lshlrev_b32_e32 v148, 16, v2
	v_and_b32_e32 v149, 0xffff0000, v2
	v_lshlrev_b32_e32 v150, 16, v3
	v_and_b32_e32 v151, 0xffff0000, v3
	v_lshlrev_b32_e32 v152, 16, v4
	v_and_b32_e32 v153, 0xffff0000, v4
	v_lshlrev_b32_e32 v154, 16, v5
	v_and_b32_e32 v155, 0xffff0000, v5
	v_lshlrev_b32_e32 v156, 16, v6
	v_and_b32_e32 v157, 0xffff0000, v6
	v_lshlrev_b32_e32 v158, 16, v7
	v_and_b32_e32 v159, 0xffff0000, v7
	v_lshlrev_b32_e32 v160, 16, v8
	v_and_b32_e32 v161, 0xffff0000, v8
	v_lshlrev_b32_e32 v162, 16, v9
	v_and_b32_e32 v163, 0xffff0000, v9
	v_lshlrev_b32_e32 v164, 16, v10
	v_and_b32_e32 v165, 0xffff0000, v10
	v_lshlrev_b32_e32 v166, 16, v11
	v_and_b32_e32 v167, 0xffff0000, v11
	v_lshlrev_b32_e32 v168, 16, v12
	v_and_b32_e32 v169, 0xffff0000, v12
	v_lshlrev_b32_e32 v170, 16, v13
	v_and_b32_e32 v171, 0xffff0000, v13
	v_lshlrev_b32_e32 v172, 16, v14
	v_and_b32_e32 v173, 0xffff0000, v14
	v_lshlrev_b32_e32 v174, 16, v15
	v_and_b32_e32 v175, 0xffff0000, v15
	v_pk_mul_f32 v[252:253], v[160:161], v[160:161]
	v_pk_mul_f32 v[254:255], v[162:163], v[162:163]
	v_pk_fma_f32 v[252:253], v[164:165], v[164:165], v[252:253]
	v_pk_fma_f32 v[254:255], v[166:167], v[166:167], v[254:255]
	v_pk_fma_f32 v[252:253], v[168:169], v[168:169], v[252:253]
	v_pk_fma_f32 v[254:255], v[170:171], v[170:171], v[254:255]
	v_pk_fma_f32 v[252:253], v[172:173], v[172:173], v[252:253]
	v_pk_fma_f32 v[254:255], v[174:175], v[174:175], v[254:255]
	v_pk_add_f32 v[252:253], v[252:253], v[254:255]
	s_nop 0
	v_add_f32_e32 v183, v252, v253
	s_nop 1
	v_add_f32_dpp v183, v183, v183 quad_perm:[1,0,3,2] row_mask:0xf bank_mask:0xf bound_ctrl:1
	s_nop 1
	v_add_f32_dpp v183, v183, v183 quad_perm:[2,3,0,1] row_mask:0xf bank_mask:0xf bound_ctrl:1
	s_nop 1
	v_add_f32_dpp v183, v183, v183 row_half_mirror row_mask:0xf bank_mask:0xf bound_ctrl:1
	s_nop 1
	v_add_f32_dpp v183, v183, v183 row_mirror row_mask:0xf bank_mask:0xf bound_ctrl:1
	s_nop 1
	v_readlane_b32 s98, v183, 0
	v_readlane_b32 s99, v183, 16
	v_readlane_b32 s100, v183, 32
	v_readlane_b32 s101, v183, 48
	s_nop 1
	v_mov_b32_e32 v183, s98
	v_add_f32_e32 v183, s99, v183
	v_add_f32_e32 v183, s100, v183
	v_add_f32_e32 v183, s101, v183
	v_fmamk_f32 v183, v183, 0x3a800000, v182
	v_cmp_gt_f32_e32 vcc, 0x800000, v183
	v_mul_f32_e32 v181, 0x4b800000, v183
	s_nop 1
	v_cndmask_b32_e32 v183, v183, v181, vcc
	v_rsq_f32_e32 v183, v183
	s_nop 0
	v_mul_f32_e32 v181, 0x45800000, v183
	v_cndmask_b32_e32 v184, v183, v181, vcc
	v_mov_b32_e32 v185, v184
	v_pk_mul_f32 v[160:161], v[160:161], v[184:185]
	v_pk_mul_f32 v[162:163], v[162:163], v[184:185]
	v_pk_mul_f32 v[164:165], v[164:165], v[184:185]
	v_pk_mul_f32 v[166:167], v[166:167], v[184:185]
	v_pk_mul_f32 v[168:169], v[168:169], v[184:185]
	v_pk_mul_f32 v[170:171], v[170:171], v[184:185]
	v_pk_mul_f32 v[172:173], v[172:173], v[184:185]
	v_pk_mul_f32 v[174:175], v[174:175], v[184:185]
	v_pk_fma_f32 v[144:145], v[160:161], v[128:129], v[144:145]
	v_pk_fma_f32 v[146:147], v[162:163], v[130:131], v[146:147]
	v_pk_fma_f32 v[148:149], v[164:165], v[132:133], v[148:149]
	v_pk_fma_f32 v[150:151], v[166:167], v[134:135], v[150:151]
	v_pk_fma_f32 v[152:153], v[168:169], v[136:137], v[152:153]
	v_pk_fma_f32 v[154:155], v[170:171], v[138:139], v[154:155]
	v_pk_fma_f32 v[156:157], v[172:173], v[140:141], v[156:157]
	v_pk_fma_f32 v[158:159], v[174:175], v[142:143], v[158:159]
	v_pk_mul_f32 v[252:253], v[144:145], v[144:145]
	v_pk_mul_f32 v[254:255], v[146:147], v[146:147]
	v_pk_fma_f32 v[252:253], v[148:149], v[148:149], v[252:253]
	v_pk_fma_f32 v[254:255], v[150:151], v[150:151], v[254:255]
	v_pk_fma_f32 v[252:253], v[152:153], v[152:153], v[252:253]
	v_pk_fma_f32 v[254:255], v[154:155], v[154:155], v[254:255]
	v_pk_fma_f32 v[252:253], v[156:157], v[156:157], v[252:253]
	v_pk_fma_f32 v[254:255], v[158:159], v[158:159], v[254:255]
	v_pk_add_f32 v[252:253], v[252:253], v[254:255]
	s_nop 0
	v_add_f32_e32 v183, v252, v253
	s_nop 1
	v_add_f32_dpp v183, v183, v183 quad_perm:[1,0,3,2] row_mask:0xf bank_mask:0xf bound_ctrl:1
	s_nop 1
	v_add_f32_dpp v183, v183, v183 quad_perm:[2,3,0,1] row_mask:0xf bank_mask:0xf bound_ctrl:1
	s_nop 1
	v_add_f32_dpp v183, v183, v183 row_half_mirror row_mask:0xf bank_mask:0xf bound_ctrl:1
	s_nop 1
	v_add_f32_dpp v183, v183, v183 row_mirror row_mask:0xf bank_mask:0xf bound_ctrl:1
	s_nop 1
	v_readlane_b32 s98, v183, 0
	v_readlane_b32 s99, v183, 16
	v_readlane_b32 s100, v183, 32
	v_readlane_b32 s101, v183, 48
	s_nop 1
	v_mov_b32_e32 v183, s98
	v_add_f32_e32 v183, s99, v183
	v_add_f32_e32 v183, s100, v183
	v_add_f32_e32 v183, s101, v183
	v_fmamk_f32 v183, v183, 0x3a800000, v182
	v_cmp_gt_f32_e32 vcc, 0x800000, v183
	v_mul_f32_e32 v181, 0x4b800000, v183
	s_nop 1
	v_cndmask_b32_e32 v183, v183, v181, vcc
	v_rsq_f32_e32 v183, v183
	s_nop 0
	v_mul_f32_e32 v181, 0x45800000, v183
	v_cndmask_b32_e32 v184, v183, v181, vcc
	v_mov_b32_e32 v185, v184
	v_pk_mul_f32 v[144:145], v[144:145], v[184:185]
	v_pk_mul_f32 v[146:147], v[146:147], v[184:185]
	v_pk_mul_f32 v[148:149], v[148:149], v[184:185]
	v_pk_mul_f32 v[150:151], v[150:151], v[184:185]
	v_pk_mul_f32 v[152:153], v[152:153], v[184:185]
	v_pk_mul_f32 v[154:155], v[154:155], v[184:185]
	v_pk_mul_f32 v[156:157], v[156:157], v[184:185]
	v_pk_mul_f32 v[158:159], v[158:159], v[184:185]
	v_pk_mul_f32 v[144:145], v[144:145], v[236:237]
	v_pk_mul_f32 v[146:147], v[146:147], v[238:239]
	v_pk_mul_f32 v[148:149], v[148:149], v[240:241]
	v_pk_mul_f32 v[150:151], v[150:151], v[242:243]
	v_pk_mul_f32 v[152:153], v[152:153], v[244:245]
	v_pk_mul_f32 v[154:155], v[154:155], v[246:247]
	v_pk_mul_f32 v[156:157], v[156:157], v[248:249]
	v_pk_mul_f32 v[158:159], v[158:159], v[250:251]
	v_add_u32_e32 v181, 0x0, v178
	global_store_dwordx4 v181, v[144:147], s[76:77]
	global_store_dwordx4 v181, v[148:151], s[76:77] offset:16
	global_store_dwordx4 v181, v[152:155], s[76:77] offset:2048
	global_store_dwordx4 v181, v[156:159], s[76:77] offset:2064
	s_nop 1
	s_waitcnt vmcnt(24)
	v_lshlrev_b32_e32 v144, 16, v16
	v_and_b32_e32 v145, 0xffff0000, v16
	v_lshlrev_b32_e32 v146, 16, v17
	v_and_b32_e32 v147, 0xffff0000, v17
	v_lshlrev_b32_e32 v148, 16, v18
	v_and_b32_e32 v149, 0xffff0000, v18
	v_lshlrev_b32_e32 v150, 16, v19
	v_and_b32_e32 v151, 0xffff0000, v19
	v_lshlrev_b32_e32 v152, 16, v20
	v_and_b32_e32 v153, 0xffff0000, v20
	v_lshlrev_b32_e32 v154, 16, v21
	v_and_b32_e32 v155, 0xffff0000, v21
	v_lshlrev_b32_e32 v156, 16, v22
	v_and_b32_e32 v157, 0xffff0000, v22
	v_lshlrev_b32_e32 v158, 16, v23
	v_and_b32_e32 v159, 0xffff0000, v23
	v_lshlrev_b32_e32 v160, 16, v24
	v_and_b32_e32 v161, 0xffff0000, v24
	v_lshlrev_b32_e32 v162, 16, v25
	v_and_b32_e32 v163, 0xffff0000, v25
	v_lshlrev_b32_e32 v164, 16, v26
	v_and_b32_e32 v165, 0xffff0000, v26
	v_lshlrev_b32_e32 v166, 16, v27
	v_and_b32_e32 v167, 0xffff0000, v27
	v_lshlrev_b32_e32 v168, 16, v28
	v_and_b32_e32 v169, 0xffff0000, v28
	v_lshlrev_b32_e32 v170, 16, v29
	v_and_b32_e32 v171, 0xffff0000, v29
	v_lshlrev_b32_e32 v172, 16, v30
	v_and_b32_e32 v173, 0xffff0000, v30
	v_lshlrev_b32_e32 v174, 16, v31
	v_and_b32_e32 v175, 0xffff0000, v31
	v_pk_mul_f32 v[252:253], v[160:161], v[160:161]
	v_pk_mul_f32 v[254:255], v[162:163], v[162:163]
	v_pk_fma_f32 v[252:253], v[164:165], v[164:165], v[252:253]
	v_pk_fma_f32 v[254:255], v[166:167], v[166:167], v[254:255]
	v_pk_fma_f32 v[252:253], v[168:169], v[168:169], v[252:253]
	v_pk_fma_f32 v[254:255], v[170:171], v[170:171], v[254:255]
	v_pk_fma_f32 v[252:253], v[172:173], v[172:173], v[252:253]
	v_pk_fma_f32 v[254:255], v[174:175], v[174:175], v[254:255]
	v_pk_add_f32 v[252:253], v[252:253], v[254:255]
	s_nop 0
	v_add_f32_e32 v183, v252, v253
	s_nop 1
	v_add_f32_dpp v183, v183, v183 quad_perm:[1,0,3,2] row_mask:0xf bank_mask:0xf bound_ctrl:1
	s_nop 1
	v_add_f32_dpp v183, v183, v183 quad_perm:[2,3,0,1] row_mask:0xf bank_mask:0xf bound_ctrl:1
	s_nop 1
	v_add_f32_dpp v183, v183, v183 row_half_mirror row_mask:0xf bank_mask:0xf bound_ctrl:1
	s_nop 1
	v_add_f32_dpp v183, v183, v183 row_mirror row_mask:0xf bank_mask:0xf bound_ctrl:1
	s_nop 1
	v_readlane_b32 s98, v183, 0
	v_readlane_b32 s99, v183, 16
	v_readlane_b32 s100, v183, 32
	v_readlane_b32 s101, v183, 48
	s_nop 1
	v_mov_b32_e32 v183, s98
	v_add_f32_e32 v183, s99, v183
	v_add_f32_e32 v183, s100, v183
	v_add_f32_e32 v183, s101, v183
	v_fmamk_f32 v183, v183, 0x3a800000, v182
	v_cmp_gt_f32_e32 vcc, 0x800000, v183
	v_mul_f32_e32 v181, 0x4b800000, v183
	s_nop 1
	v_cndmask_b32_e32 v183, v183, v181, vcc
	v_rsq_f32_e32 v183, v183
	s_nop 0
	v_mul_f32_e32 v181, 0x45800000, v183
	v_cndmask_b32_e32 v184, v183, v181, vcc
	v_mov_b32_e32 v185, v184
	v_pk_mul_f32 v[160:161], v[160:161], v[184:185]
	v_pk_mul_f32 v[162:163], v[162:163], v[184:185]
	v_pk_mul_f32 v[164:165], v[164:165], v[184:185]
	v_pk_mul_f32 v[166:167], v[166:167], v[184:185]
	v_pk_mul_f32 v[168:169], v[168:169], v[184:185]
	v_pk_mul_f32 v[170:171], v[170:171], v[184:185]
	v_pk_mul_f32 v[172:173], v[172:173], v[184:185]
	v_pk_mul_f32 v[174:175], v[174:175], v[184:185]
	v_pk_fma_f32 v[144:145], v[160:161], v[128:129], v[144:145]
	v_pk_fma_f32 v[146:147], v[162:163], v[130:131], v[146:147]
	v_pk_fma_f32 v[148:149], v[164:165], v[132:133], v[148:149]
	v_pk_fma_f32 v[150:151], v[166:167], v[134:135], v[150:151]
	v_pk_fma_f32 v[152:153], v[168:169], v[136:137], v[152:153]
	v_pk_fma_f32 v[154:155], v[170:171], v[138:139], v[154:155]
	v_pk_fma_f32 v[156:157], v[172:173], v[140:141], v[156:157]
	v_pk_fma_f32 v[158:159], v[174:175], v[142:143], v[158:159]
	v_pk_mul_f32 v[252:253], v[144:145], v[144:145]
	v_pk_mul_f32 v[254:255], v[146:147], v[146:147]
	v_pk_fma_f32 v[252:253], v[148:149], v[148:149], v[252:253]
	v_pk_fma_f32 v[254:255], v[150:151], v[150:151], v[254:255]
	v_pk_fma_f32 v[252:253], v[152:153], v[152:153], v[252:253]
	v_pk_fma_f32 v[254:255], v[154:155], v[154:155], v[254:255]
	v_pk_fma_f32 v[252:253], v[156:157], v[156:157], v[252:253]
	v_pk_fma_f32 v[254:255], v[158:159], v[158:159], v[254:255]
	v_pk_add_f32 v[252:253], v[252:253], v[254:255]
	s_nop 0
	v_add_f32_e32 v183, v252, v253
	s_nop 1
	v_add_f32_dpp v183, v183, v183 quad_perm:[1,0,3,2] row_mask:0xf bank_mask:0xf bound_ctrl:1
	s_nop 1
	v_add_f32_dpp v183, v183, v183 quad_perm:[2,3,0,1] row_mask:0xf bank_mask:0xf bound_ctrl:1
	s_nop 1
	v_add_f32_dpp v183, v183, v183 row_half_mirror row_mask:0xf bank_mask:0xf bound_ctrl:1
	s_nop 1
	v_add_f32_dpp v183, v183, v183 row_mirror row_mask:0xf bank_mask:0xf bound_ctrl:1
	s_nop 1
	v_readlane_b32 s98, v183, 0
	v_readlane_b32 s99, v183, 16
	v_readlane_b32 s100, v183, 32
	v_readlane_b32 s101, v183, 48
	s_nop 1
	v_mov_b32_e32 v183, s98
	v_add_f32_e32 v183, s99, v183
	v_add_f32_e32 v183, s100, v183
	v_add_f32_e32 v183, s101, v183
	v_fmamk_f32 v183, v183, 0x3a800000, v182
	v_cmp_gt_f32_e32 vcc, 0x800000, v183
	v_mul_f32_e32 v181, 0x4b800000, v183
	s_nop 1
	v_cndmask_b32_e32 v183, v183, v181, vcc
	v_rsq_f32_e32 v183, v183
	s_nop 0
	v_mul_f32_e32 v181, 0x45800000, v183
	v_cndmask_b32_e32 v184, v183, v181, vcc
	v_mov_b32_e32 v185, v184
	v_pk_mul_f32 v[144:145], v[144:145], v[184:185]
	v_pk_mul_f32 v[146:147], v[146:147], v[184:185]
	v_pk_mul_f32 v[148:149], v[148:149], v[184:185]
	v_pk_mul_f32 v[150:151], v[150:151], v[184:185]
	v_pk_mul_f32 v[152:153], v[152:153], v[184:185]
	v_pk_mul_f32 v[154:155], v[154:155], v[184:185]
	v_pk_mul_f32 v[156:157], v[156:157], v[184:185]
	v_pk_mul_f32 v[158:159], v[158:159], v[184:185]
	v_pk_mul_f32 v[144:145], v[144:145], v[236:237]
	v_pk_mul_f32 v[146:147], v[146:147], v[238:239]
	v_pk_mul_f32 v[148:149], v[148:149], v[240:241]
	v_pk_mul_f32 v[150:151], v[150:151], v[242:243]
	v_pk_mul_f32 v[152:153], v[152:153], v[244:245]
	v_pk_mul_f32 v[154:155], v[154:155], v[246:247]
	v_pk_mul_f32 v[156:157], v[156:157], v[248:249]
	v_pk_mul_f32 v[158:159], v[158:159], v[250:251]
	v_add_u32_e32 v181, 0x800000, v178
	global_store_dwordx4 v181, v[144:147], s[76:77]
	global_store_dwordx4 v181, v[148:151], s[76:77] offset:16
	global_store_dwordx4 v181, v[152:155], s[76:77] offset:2048
	global_store_dwordx4 v181, v[156:159], s[76:77] offset:2064
	s_nop 1
	s_waitcnt vmcnt(20)
	v_lshlrev_b32_e32 v144, 16, v32
	v_and_b32_e32 v145, 0xffff0000, v32
	v_lshlrev_b32_e32 v146, 16, v33
	v_and_b32_e32 v147, 0xffff0000, v33
	v_lshlrev_b32_e32 v148, 16, v34
	v_and_b32_e32 v149, 0xffff0000, v34
	v_lshlrev_b32_e32 v150, 16, v35
	v_and_b32_e32 v151, 0xffff0000, v35
	v_lshlrev_b32_e32 v152, 16, v36
	v_and_b32_e32 v153, 0xffff0000, v36
	v_lshlrev_b32_e32 v154, 16, v37
	v_and_b32_e32 v155, 0xffff0000, v37
	v_lshlrev_b32_e32 v156, 16, v38
	v_and_b32_e32 v157, 0xffff0000, v38
	v_lshlrev_b32_e32 v158, 16, v39
	v_and_b32_e32 v159, 0xffff0000, v39
	v_lshlrev_b32_e32 v160, 16, v40
	v_and_b32_e32 v161, 0xffff0000, v40
	v_lshlrev_b32_e32 v162, 16, v41
	v_and_b32_e32 v163, 0xffff0000, v41
	v_lshlrev_b32_e32 v164, 16, v42
	v_and_b32_e32 v165, 0xffff0000, v42
	v_lshlrev_b32_e32 v166, 16, v43
	v_and_b32_e32 v167, 0xffff0000, v43
	v_lshlrev_b32_e32 v168, 16, v44
	v_and_b32_e32 v169, 0xffff0000, v44
	v_lshlrev_b32_e32 v170, 16, v45
	v_and_b32_e32 v171, 0xffff0000, v45
	v_lshlrev_b32_e32 v172, 16, v46
	v_and_b32_e32 v173, 0xffff0000, v46
	v_lshlrev_b32_e32 v174, 16, v47
	v_and_b32_e32 v175, 0xffff0000, v47
	v_pk_mul_f32 v[252:253], v[160:161], v[160:161]
	v_pk_mul_f32 v[254:255], v[162:163], v[162:163]
	v_pk_fma_f32 v[252:253], v[164:165], v[164:165], v[252:253]
	v_pk_fma_f32 v[254:255], v[166:167], v[166:167], v[254:255]
	v_pk_fma_f32 v[252:253], v[168:169], v[168:169], v[252:253]
	v_pk_fma_f32 v[254:255], v[170:171], v[170:171], v[254:255]
	v_pk_fma_f32 v[252:253], v[172:173], v[172:173], v[252:253]
	v_pk_fma_f32 v[254:255], v[174:175], v[174:175], v[254:255]
	v_pk_add_f32 v[252:253], v[252:253], v[254:255]
	s_nop 0
	v_add_f32_e32 v183, v252, v253
	s_nop 1
	v_add_f32_dpp v183, v183, v183 quad_perm:[1,0,3,2] row_mask:0xf bank_mask:0xf bound_ctrl:1
	s_nop 1
	v_add_f32_dpp v183, v183, v183 quad_perm:[2,3,0,1] row_mask:0xf bank_mask:0xf bound_ctrl:1
	s_nop 1
	v_add_f32_dpp v183, v183, v183 row_half_mirror row_mask:0xf bank_mask:0xf bound_ctrl:1
	s_nop 1
	v_add_f32_dpp v183, v183, v183 row_mirror row_mask:0xf bank_mask:0xf bound_ctrl:1
	s_nop 1
	v_readlane_b32 s98, v183, 0
	v_readlane_b32 s99, v183, 16
	v_readlane_b32 s100, v183, 32
	v_readlane_b32 s101, v183, 48
	s_nop 1
	v_mov_b32_e32 v183, s98
	v_add_f32_e32 v183, s99, v183
	v_add_f32_e32 v183, s100, v183
	v_add_f32_e32 v183, s101, v183
	v_fmamk_f32 v183, v183, 0x3a800000, v182
	v_cmp_gt_f32_e32 vcc, 0x800000, v183
	v_mul_f32_e32 v181, 0x4b800000, v183
	s_nop 1
	v_cndmask_b32_e32 v183, v183, v181, vcc
	v_rsq_f32_e32 v183, v183
	s_nop 0
	v_mul_f32_e32 v181, 0x45800000, v183
	v_cndmask_b32_e32 v184, v183, v181, vcc
	v_mov_b32_e32 v185, v184
	v_pk_mul_f32 v[160:161], v[160:161], v[184:185]
	v_pk_mul_f32 v[162:163], v[162:163], v[184:185]
	v_pk_mul_f32 v[164:165], v[164:165], v[184:185]
	v_pk_mul_f32 v[166:167], v[166:167], v[184:185]
	v_pk_mul_f32 v[168:169], v[168:169], v[184:185]
	v_pk_mul_f32 v[170:171], v[170:171], v[184:185]
	v_pk_mul_f32 v[172:173], v[172:173], v[184:185]
	v_pk_mul_f32 v[174:175], v[174:175], v[184:185]
	v_pk_fma_f32 v[144:145], v[160:161], v[128:129], v[144:145]
	v_pk_fma_f32 v[146:147], v[162:163], v[130:131], v[146:147]
	v_pk_fma_f32 v[148:149], v[164:165], v[132:133], v[148:149]
	v_pk_fma_f32 v[150:151], v[166:167], v[134:135], v[150:151]
	v_pk_fma_f32 v[152:153], v[168:169], v[136:137], v[152:153]
	v_pk_fma_f32 v[154:155], v[170:171], v[138:139], v[154:155]
	v_pk_fma_f32 v[156:157], v[172:173], v[140:141], v[156:157]
	v_pk_fma_f32 v[158:159], v[174:175], v[142:143], v[158:159]
	v_pk_mul_f32 v[252:253], v[144:145], v[144:145]
	v_pk_mul_f32 v[254:255], v[146:147], v[146:147]
	v_pk_fma_f32 v[252:253], v[148:149], v[148:149], v[252:253]
	v_pk_fma_f32 v[254:255], v[150:151], v[150:151], v[254:255]
	v_pk_fma_f32 v[252:253], v[152:153], v[152:153], v[252:253]
	v_pk_fma_f32 v[254:255], v[154:155], v[154:155], v[254:255]
	v_pk_fma_f32 v[252:253], v[156:157], v[156:157], v[252:253]
	v_pk_fma_f32 v[254:255], v[158:159], v[158:159], v[254:255]
	v_pk_add_f32 v[252:253], v[252:253], v[254:255]
	s_nop 0
	v_add_f32_e32 v183, v252, v253
	s_nop 1
	v_add_f32_dpp v183, v183, v183 quad_perm:[1,0,3,2] row_mask:0xf bank_mask:0xf bound_ctrl:1
	s_nop 1
	v_add_f32_dpp v183, v183, v183 quad_perm:[2,3,0,1] row_mask:0xf bank_mask:0xf bound_ctrl:1
	s_nop 1
	v_add_f32_dpp v183, v183, v183 row_half_mirror row_mask:0xf bank_mask:0xf bound_ctrl:1
	s_nop 1
	v_add_f32_dpp v183, v183, v183 row_mirror row_mask:0xf bank_mask:0xf bound_ctrl:1
	s_nop 1
	v_readlane_b32 s98, v183, 0
	v_readlane_b32 s99, v183, 16
	v_readlane_b32 s100, v183, 32
	v_readlane_b32 s101, v183, 48
	s_nop 1
	v_mov_b32_e32 v183, s98
	v_add_f32_e32 v183, s99, v183
	v_add_f32_e32 v183, s100, v183
	v_add_f32_e32 v183, s101, v183
	v_fmamk_f32 v183, v183, 0x3a800000, v182
	v_cmp_gt_f32_e32 vcc, 0x800000, v183
	v_mul_f32_e32 v181, 0x4b800000, v183
	s_nop 1
	v_cndmask_b32_e32 v183, v183, v181, vcc
	v_rsq_f32_e32 v183, v183
	s_nop 0
	v_mul_f32_e32 v181, 0x45800000, v183
	v_cndmask_b32_e32 v184, v183, v181, vcc
	v_mov_b32_e32 v185, v184
	v_pk_mul_f32 v[144:145], v[144:145], v[184:185]
	v_pk_mul_f32 v[146:147], v[146:147], v[184:185]
	v_pk_mul_f32 v[148:149], v[148:149], v[184:185]
	v_pk_mul_f32 v[150:151], v[150:151], v[184:185]
	v_pk_mul_f32 v[152:153], v[152:153], v[184:185]
	v_pk_mul_f32 v[154:155], v[154:155], v[184:185]
	v_pk_mul_f32 v[156:157], v[156:157], v[184:185]
	v_pk_mul_f32 v[158:159], v[158:159], v[184:185]
	v_pk_mul_f32 v[144:145], v[144:145], v[236:237]
	v_pk_mul_f32 v[146:147], v[146:147], v[238:239]
	v_pk_mul_f32 v[148:149], v[148:149], v[240:241]
	v_pk_mul_f32 v[150:151], v[150:151], v[242:243]
	v_pk_mul_f32 v[152:153], v[152:153], v[244:245]
	v_pk_mul_f32 v[154:155], v[154:155], v[246:247]
	v_pk_mul_f32 v[156:157], v[156:157], v[248:249]
	v_pk_mul_f32 v[158:159], v[158:159], v[250:251]
	v_add_u32_e32 v181, 0x1000000, v178
	global_store_dwordx4 v181, v[144:147], s[76:77]
	global_store_dwordx4 v181, v[148:151], s[76:77] offset:16
	global_store_dwordx4 v181, v[152:155], s[76:77] offset:2048
	global_store_dwordx4 v181, v[156:159], s[76:77] offset:2064
	s_nop 1
	s_waitcnt vmcnt(16)
	v_lshlrev_b32_e32 v144, 16, v48
	v_and_b32_e32 v145, 0xffff0000, v48
	v_lshlrev_b32_e32 v146, 16, v49
	v_and_b32_e32 v147, 0xffff0000, v49
	v_lshlrev_b32_e32 v148, 16, v50
	v_and_b32_e32 v149, 0xffff0000, v50
	v_lshlrev_b32_e32 v150, 16, v51
	v_and_b32_e32 v151, 0xffff0000, v51
	v_lshlrev_b32_e32 v152, 16, v52
	v_and_b32_e32 v153, 0xffff0000, v52
	v_lshlrev_b32_e32 v154, 16, v53
	v_and_b32_e32 v155, 0xffff0000, v53
	v_lshlrev_b32_e32 v156, 16, v54
	v_and_b32_e32 v157, 0xffff0000, v54
	v_lshlrev_b32_e32 v158, 16, v55
	v_and_b32_e32 v159, 0xffff0000, v55
	v_lshlrev_b32_e32 v160, 16, v56
	v_and_b32_e32 v161, 0xffff0000, v56
	v_lshlrev_b32_e32 v162, 16, v57
	v_and_b32_e32 v163, 0xffff0000, v57
	v_lshlrev_b32_e32 v164, 16, v58
	v_and_b32_e32 v165, 0xffff0000, v58
	v_lshlrev_b32_e32 v166, 16, v59
	v_and_b32_e32 v167, 0xffff0000, v59
	v_lshlrev_b32_e32 v168, 16, v60
	v_and_b32_e32 v169, 0xffff0000, v60
	v_lshlrev_b32_e32 v170, 16, v61
	v_and_b32_e32 v171, 0xffff0000, v61
	v_lshlrev_b32_e32 v172, 16, v62
	v_and_b32_e32 v173, 0xffff0000, v62
	v_lshlrev_b32_e32 v174, 16, v63
	v_and_b32_e32 v175, 0xffff0000, v63
	v_pk_mul_f32 v[252:253], v[160:161], v[160:161]
	v_pk_mul_f32 v[254:255], v[162:163], v[162:163]
	v_pk_fma_f32 v[252:253], v[164:165], v[164:165], v[252:253]
	v_pk_fma_f32 v[254:255], v[166:167], v[166:167], v[254:255]
	v_pk_fma_f32 v[252:253], v[168:169], v[168:169], v[252:253]
	v_pk_fma_f32 v[254:255], v[170:171], v[170:171], v[254:255]
	v_pk_fma_f32 v[252:253], v[172:173], v[172:173], v[252:253]
	v_pk_fma_f32 v[254:255], v[174:175], v[174:175], v[254:255]
	v_pk_add_f32 v[252:253], v[252:253], v[254:255]
	s_nop 0
	v_add_f32_e32 v183, v252, v253
	s_nop 1
	v_add_f32_dpp v183, v183, v183 quad_perm:[1,0,3,2] row_mask:0xf bank_mask:0xf bound_ctrl:1
	s_nop 1
	v_add_f32_dpp v183, v183, v183 quad_perm:[2,3,0,1] row_mask:0xf bank_mask:0xf bound_ctrl:1
	s_nop 1
	v_add_f32_dpp v183, v183, v183 row_half_mirror row_mask:0xf bank_mask:0xf bound_ctrl:1
	s_nop 1
	v_add_f32_dpp v183, v183, v183 row_mirror row_mask:0xf bank_mask:0xf bound_ctrl:1
	s_nop 1
	v_readlane_b32 s98, v183, 0
	v_readlane_b32 s99, v183, 16
	v_readlane_b32 s100, v183, 32
	v_readlane_b32 s101, v183, 48
	s_nop 1
	v_mov_b32_e32 v183, s98
	v_add_f32_e32 v183, s99, v183
	v_add_f32_e32 v183, s100, v183
	v_add_f32_e32 v183, s101, v183
	v_fmamk_f32 v183, v183, 0x3a800000, v182
	v_cmp_gt_f32_e32 vcc, 0x800000, v183
	v_mul_f32_e32 v181, 0x4b800000, v183
	s_nop 1
	v_cndmask_b32_e32 v183, v183, v181, vcc
	v_rsq_f32_e32 v183, v183
	s_nop 0
	v_mul_f32_e32 v181, 0x45800000, v183
	v_cndmask_b32_e32 v184, v183, v181, vcc
	v_mov_b32_e32 v185, v184
	v_pk_mul_f32 v[160:161], v[160:161], v[184:185]
	v_pk_mul_f32 v[162:163], v[162:163], v[184:185]
	v_pk_mul_f32 v[164:165], v[164:165], v[184:185]
	v_pk_mul_f32 v[166:167], v[166:167], v[184:185]
	v_pk_mul_f32 v[168:169], v[168:169], v[184:185]
	v_pk_mul_f32 v[170:171], v[170:171], v[184:185]
	v_pk_mul_f32 v[172:173], v[172:173], v[184:185]
	v_pk_mul_f32 v[174:175], v[174:175], v[184:185]
	v_pk_fma_f32 v[144:145], v[160:161], v[128:129], v[144:145]
	v_pk_fma_f32 v[146:147], v[162:163], v[130:131], v[146:147]
	v_pk_fma_f32 v[148:149], v[164:165], v[132:133], v[148:149]
	v_pk_fma_f32 v[150:151], v[166:167], v[134:135], v[150:151]
	v_pk_fma_f32 v[152:153], v[168:169], v[136:137], v[152:153]
	v_pk_fma_f32 v[154:155], v[170:171], v[138:139], v[154:155]
	v_pk_fma_f32 v[156:157], v[172:173], v[140:141], v[156:157]
	v_pk_fma_f32 v[158:159], v[174:175], v[142:143], v[158:159]
	v_pk_mul_f32 v[252:253], v[144:145], v[144:145]
	v_pk_mul_f32 v[254:255], v[146:147], v[146:147]
	v_pk_fma_f32 v[252:253], v[148:149], v[148:149], v[252:253]
	v_pk_fma_f32 v[254:255], v[150:151], v[150:151], v[254:255]
	v_pk_fma_f32 v[252:253], v[152:153], v[152:153], v[252:253]
	v_pk_fma_f32 v[254:255], v[154:155], v[154:155], v[254:255]
	v_pk_fma_f32 v[252:253], v[156:157], v[156:157], v[252:253]
	v_pk_fma_f32 v[254:255], v[158:159], v[158:159], v[254:255]
	v_pk_add_f32 v[252:253], v[252:253], v[254:255]
	s_nop 0
	v_add_f32_e32 v183, v252, v253
	s_nop 1
	v_add_f32_dpp v183, v183, v183 quad_perm:[1,0,3,2] row_mask:0xf bank_mask:0xf bound_ctrl:1
	s_nop 1
	v_add_f32_dpp v183, v183, v183 quad_perm:[2,3,0,1] row_mask:0xf bank_mask:0xf bound_ctrl:1
	s_nop 1
	v_add_f32_dpp v183, v183, v183 row_half_mirror row_mask:0xf bank_mask:0xf bound_ctrl:1
	s_nop 1
	v_add_f32_dpp v183, v183, v183 row_mirror row_mask:0xf bank_mask:0xf bound_ctrl:1
	s_nop 1
	v_readlane_b32 s98, v183, 0
	v_readlane_b32 s99, v183, 16
	v_readlane_b32 s100, v183, 32
	v_readlane_b32 s101, v183, 48
	s_nop 1
	v_mov_b32_e32 v183, s98
	v_add_f32_e32 v183, s99, v183
	v_add_f32_e32 v183, s100, v183
	v_add_f32_e32 v183, s101, v183
	v_fmamk_f32 v183, v183, 0x3a800000, v182
	v_cmp_gt_f32_e32 vcc, 0x800000, v183
	v_mul_f32_e32 v181, 0x4b800000, v183
	s_nop 1
	v_cndmask_b32_e32 v183, v183, v181, vcc
	v_rsq_f32_e32 v183, v183
	s_nop 0
	v_mul_f32_e32 v181, 0x45800000, v183
	v_cndmask_b32_e32 v184, v183, v181, vcc
	v_mov_b32_e32 v185, v184
	v_pk_mul_f32 v[144:145], v[144:145], v[184:185]
	v_pk_mul_f32 v[146:147], v[146:147], v[184:185]
	v_pk_mul_f32 v[148:149], v[148:149], v[184:185]
	v_pk_mul_f32 v[150:151], v[150:151], v[184:185]
	v_pk_mul_f32 v[152:153], v[152:153], v[184:185]
	v_pk_mul_f32 v[154:155], v[154:155], v[184:185]
	v_pk_mul_f32 v[156:157], v[156:157], v[184:185]
	v_pk_mul_f32 v[158:159], v[158:159], v[184:185]
	v_pk_mul_f32 v[144:145], v[144:145], v[236:237]
	v_pk_mul_f32 v[146:147], v[146:147], v[238:239]
	v_pk_mul_f32 v[148:149], v[148:149], v[240:241]
	v_pk_mul_f32 v[150:151], v[150:151], v[242:243]
	v_pk_mul_f32 v[152:153], v[152:153], v[244:245]
	v_pk_mul_f32 v[154:155], v[154:155], v[246:247]
	v_pk_mul_f32 v[156:157], v[156:157], v[248:249]
	v_pk_mul_f32 v[158:159], v[158:159], v[250:251]
	v_add_u32_e32 v181, 0x1800000, v178
	global_store_dwordx4 v181, v[144:147], s[76:77]
	global_store_dwordx4 v181, v[148:151], s[76:77] offset:16
	global_store_dwordx4 v181, v[152:155], s[76:77] offset:2048
	global_store_dwordx4 v181, v[156:159], s[76:77] offset:2064
	s_nop 1
	s_waitcnt vmcnt(12)
	v_lshlrev_b32_e32 v144, 16, v64
	v_and_b32_e32 v145, 0xffff0000, v64
	v_lshlrev_b32_e32 v146, 16, v65
	v_and_b32_e32 v147, 0xffff0000, v65
	v_lshlrev_b32_e32 v148, 16, v66
	v_and_b32_e32 v149, 0xffff0000, v66
	v_lshlrev_b32_e32 v150, 16, v67
	v_and_b32_e32 v151, 0xffff0000, v67
	v_lshlrev_b32_e32 v152, 16, v68
	v_and_b32_e32 v153, 0xffff0000, v68
	v_lshlrev_b32_e32 v154, 16, v69
	v_and_b32_e32 v155, 0xffff0000, v69
	v_lshlrev_b32_e32 v156, 16, v70
	v_and_b32_e32 v157, 0xffff0000, v70
	v_lshlrev_b32_e32 v158, 16, v71
	v_and_b32_e32 v159, 0xffff0000, v71
	v_lshlrev_b32_e32 v160, 16, v72
	v_and_b32_e32 v161, 0xffff0000, v72
	v_lshlrev_b32_e32 v162, 16, v73
	v_and_b32_e32 v163, 0xffff0000, v73
	v_lshlrev_b32_e32 v164, 16, v74
	v_and_b32_e32 v165, 0xffff0000, v74
	v_lshlrev_b32_e32 v166, 16, v75
	v_and_b32_e32 v167, 0xffff0000, v75
	v_lshlrev_b32_e32 v168, 16, v76
	v_and_b32_e32 v169, 0xffff0000, v76
	v_lshlrev_b32_e32 v170, 16, v77
	v_and_b32_e32 v171, 0xffff0000, v77
	v_lshlrev_b32_e32 v172, 16, v78
	v_and_b32_e32 v173, 0xffff0000, v78
	v_lshlrev_b32_e32 v174, 16, v79
	v_and_b32_e32 v175, 0xffff0000, v79
	v_pk_mul_f32 v[252:253], v[160:161], v[160:161]
	v_pk_mul_f32 v[254:255], v[162:163], v[162:163]
	v_pk_fma_f32 v[252:253], v[164:165], v[164:165], v[252:253]
	v_pk_fma_f32 v[254:255], v[166:167], v[166:167], v[254:255]
	v_pk_fma_f32 v[252:253], v[168:169], v[168:169], v[252:253]
	v_pk_fma_f32 v[254:255], v[170:171], v[170:171], v[254:255]
	v_pk_fma_f32 v[252:253], v[172:173], v[172:173], v[252:253]
	v_pk_fma_f32 v[254:255], v[174:175], v[174:175], v[254:255]
	v_pk_add_f32 v[252:253], v[252:253], v[254:255]
	s_nop 0
	v_add_f32_e32 v183, v252, v253
	s_nop 1
	v_add_f32_dpp v183, v183, v183 quad_perm:[1,0,3,2] row_mask:0xf bank_mask:0xf bound_ctrl:1
	s_nop 1
	v_add_f32_dpp v183, v183, v183 quad_perm:[2,3,0,1] row_mask:0xf bank_mask:0xf bound_ctrl:1
	s_nop 1
	v_add_f32_dpp v183, v183, v183 row_half_mirror row_mask:0xf bank_mask:0xf bound_ctrl:1
	s_nop 1
	v_add_f32_dpp v183, v183, v183 row_mirror row_mask:0xf bank_mask:0xf bound_ctrl:1
	s_nop 1
	v_readlane_b32 s98, v183, 0
	v_readlane_b32 s99, v183, 16
	v_readlane_b32 s100, v183, 32
	v_readlane_b32 s101, v183, 48
	s_nop 1
	v_mov_b32_e32 v183, s98
	v_add_f32_e32 v183, s99, v183
	v_add_f32_e32 v183, s100, v183
	v_add_f32_e32 v183, s101, v183
	v_fmamk_f32 v183, v183, 0x3a800000, v182
	v_cmp_gt_f32_e32 vcc, 0x800000, v183
	v_mul_f32_e32 v181, 0x4b800000, v183
	s_nop 1
	v_cndmask_b32_e32 v183, v183, v181, vcc
	v_rsq_f32_e32 v183, v183
	s_nop 0
	v_mul_f32_e32 v181, 0x45800000, v183
	v_cndmask_b32_e32 v184, v183, v181, vcc
	v_mov_b32_e32 v185, v184
	v_pk_mul_f32 v[160:161], v[160:161], v[184:185]
	v_pk_mul_f32 v[162:163], v[162:163], v[184:185]
	v_pk_mul_f32 v[164:165], v[164:165], v[184:185]
	v_pk_mul_f32 v[166:167], v[166:167], v[184:185]
	v_pk_mul_f32 v[168:169], v[168:169], v[184:185]
	v_pk_mul_f32 v[170:171], v[170:171], v[184:185]
	v_pk_mul_f32 v[172:173], v[172:173], v[184:185]
	v_pk_mul_f32 v[174:175], v[174:175], v[184:185]
	v_pk_fma_f32 v[144:145], v[160:161], v[128:129], v[144:145]
	v_pk_fma_f32 v[146:147], v[162:163], v[130:131], v[146:147]
	v_pk_fma_f32 v[148:149], v[164:165], v[132:133], v[148:149]
	v_pk_fma_f32 v[150:151], v[166:167], v[134:135], v[150:151]
	v_pk_fma_f32 v[152:153], v[168:169], v[136:137], v[152:153]
	v_pk_fma_f32 v[154:155], v[170:171], v[138:139], v[154:155]
	v_pk_fma_f32 v[156:157], v[172:173], v[140:141], v[156:157]
	v_pk_fma_f32 v[158:159], v[174:175], v[142:143], v[158:159]
	v_pk_mul_f32 v[252:253], v[144:145], v[144:145]
	v_pk_mul_f32 v[254:255], v[146:147], v[146:147]
	v_pk_fma_f32 v[252:253], v[148:149], v[148:149], v[252:253]
	v_pk_fma_f32 v[254:255], v[150:151], v[150:151], v[254:255]
	v_pk_fma_f32 v[252:253], v[152:153], v[152:153], v[252:253]
	v_pk_fma_f32 v[254:255], v[154:155], v[154:155], v[254:255]
	v_pk_fma_f32 v[252:253], v[156:157], v[156:157], v[252:253]
	v_pk_fma_f32 v[254:255], v[158:159], v[158:159], v[254:255]
	v_pk_add_f32 v[252:253], v[252:253], v[254:255]
	s_nop 0
	v_add_f32_e32 v183, v252, v253
	s_nop 1
	v_add_f32_dpp v183, v183, v183 quad_perm:[1,0,3,2] row_mask:0xf bank_mask:0xf bound_ctrl:1
	s_nop 1
	v_add_f32_dpp v183, v183, v183 quad_perm:[2,3,0,1] row_mask:0xf bank_mask:0xf bound_ctrl:1
	s_nop 1
	v_add_f32_dpp v183, v183, v183 row_half_mirror row_mask:0xf bank_mask:0xf bound_ctrl:1
	s_nop 1
	v_add_f32_dpp v183, v183, v183 row_mirror row_mask:0xf bank_mask:0xf bound_ctrl:1
	s_nop 1
	v_readlane_b32 s98, v183, 0
	v_readlane_b32 s99, v183, 16
	v_readlane_b32 s100, v183, 32
	v_readlane_b32 s101, v183, 48
	s_nop 1
	v_mov_b32_e32 v183, s98
	v_add_f32_e32 v183, s99, v183
	v_add_f32_e32 v183, s100, v183
	v_add_f32_e32 v183, s101, v183
	v_fmamk_f32 v183, v183, 0x3a800000, v182
	v_cmp_gt_f32_e32 vcc, 0x800000, v183
	v_mul_f32_e32 v181, 0x4b800000, v183
	s_nop 1
	v_cndmask_b32_e32 v183, v183, v181, vcc
	v_rsq_f32_e32 v183, v183
	s_nop 0
	v_mul_f32_e32 v181, 0x45800000, v183
	v_cndmask_b32_e32 v184, v183, v181, vcc
	v_mov_b32_e32 v185, v184
	v_pk_mul_f32 v[144:145], v[144:145], v[184:185]
	v_pk_mul_f32 v[146:147], v[146:147], v[184:185]
	v_pk_mul_f32 v[148:149], v[148:149], v[184:185]
	v_pk_mul_f32 v[150:151], v[150:151], v[184:185]
	v_pk_mul_f32 v[152:153], v[152:153], v[184:185]
	v_pk_mul_f32 v[154:155], v[154:155], v[184:185]
	v_pk_mul_f32 v[156:157], v[156:157], v[184:185]
	v_pk_mul_f32 v[158:159], v[158:159], v[184:185]
	v_pk_mul_f32 v[144:145], v[144:145], v[236:237]
	v_pk_mul_f32 v[146:147], v[146:147], v[238:239]
	v_pk_mul_f32 v[148:149], v[148:149], v[240:241]
	v_pk_mul_f32 v[150:151], v[150:151], v[242:243]
	v_pk_mul_f32 v[152:153], v[152:153], v[244:245]
	v_pk_mul_f32 v[154:155], v[154:155], v[246:247]
	v_pk_mul_f32 v[156:157], v[156:157], v[248:249]
	v_pk_mul_f32 v[158:159], v[158:159], v[250:251]
	v_add_u32_e32 v181, 0x2000000, v178
	global_store_dwordx4 v181, v[144:147], s[76:77]
	global_store_dwordx4 v181, v[148:151], s[76:77] offset:16
	global_store_dwordx4 v181, v[152:155], s[76:77] offset:2048
	global_store_dwordx4 v181, v[156:159], s[76:77] offset:2064
	s_nop 1
	s_waitcnt vmcnt(8)
	v_lshlrev_b32_e32 v144, 16, v80
	v_and_b32_e32 v145, 0xffff0000, v80
	v_lshlrev_b32_e32 v146, 16, v81
	v_and_b32_e32 v147, 0xffff0000, v81
	v_lshlrev_b32_e32 v148, 16, v82
	v_and_b32_e32 v149, 0xffff0000, v82
	v_lshlrev_b32_e32 v150, 16, v83
	v_and_b32_e32 v151, 0xffff0000, v83
	v_lshlrev_b32_e32 v152, 16, v84
	v_and_b32_e32 v153, 0xffff0000, v84
	v_lshlrev_b32_e32 v154, 16, v85
	v_and_b32_e32 v155, 0xffff0000, v85
	v_lshlrev_b32_e32 v156, 16, v86
	v_and_b32_e32 v157, 0xffff0000, v86
	v_lshlrev_b32_e32 v158, 16, v87
	v_and_b32_e32 v159, 0xffff0000, v87
	v_lshlrev_b32_e32 v160, 16, v88
	v_and_b32_e32 v161, 0xffff0000, v88
	v_lshlrev_b32_e32 v162, 16, v89
	v_and_b32_e32 v163, 0xffff0000, v89
	v_lshlrev_b32_e32 v164, 16, v90
	v_and_b32_e32 v165, 0xffff0000, v90
	v_lshlrev_b32_e32 v166, 16, v91
	v_and_b32_e32 v167, 0xffff0000, v91
	v_lshlrev_b32_e32 v168, 16, v92
	v_and_b32_e32 v169, 0xffff0000, v92
	v_lshlrev_b32_e32 v170, 16, v93
	v_and_b32_e32 v171, 0xffff0000, v93
	v_lshlrev_b32_e32 v172, 16, v94
	v_and_b32_e32 v173, 0xffff0000, v94
	v_lshlrev_b32_e32 v174, 16, v95
	v_and_b32_e32 v175, 0xffff0000, v95
	v_pk_mul_f32 v[252:253], v[160:161], v[160:161]
	v_pk_mul_f32 v[254:255], v[162:163], v[162:163]
	v_pk_fma_f32 v[252:253], v[164:165], v[164:165], v[252:253]
	v_pk_fma_f32 v[254:255], v[166:167], v[166:167], v[254:255]
	v_pk_fma_f32 v[252:253], v[168:169], v[168:169], v[252:253]
	v_pk_fma_f32 v[254:255], v[170:171], v[170:171], v[254:255]
	v_pk_fma_f32 v[252:253], v[172:173], v[172:173], v[252:253]
	v_pk_fma_f32 v[254:255], v[174:175], v[174:175], v[254:255]
	v_pk_add_f32 v[252:253], v[252:253], v[254:255]
	s_nop 0
	v_add_f32_e32 v183, v252, v253
	s_nop 1
	v_add_f32_dpp v183, v183, v183 quad_perm:[1,0,3,2] row_mask:0xf bank_mask:0xf bound_ctrl:1
	s_nop 1
	v_add_f32_dpp v183, v183, v183 quad_perm:[2,3,0,1] row_mask:0xf bank_mask:0xf bound_ctrl:1
	s_nop 1
	v_add_f32_dpp v183, v183, v183 row_half_mirror row_mask:0xf bank_mask:0xf bound_ctrl:1
	s_nop 1
	v_add_f32_dpp v183, v183, v183 row_mirror row_mask:0xf bank_mask:0xf bound_ctrl:1
	s_nop 1
	v_readlane_b32 s98, v183, 0
	v_readlane_b32 s99, v183, 16
	v_readlane_b32 s100, v183, 32
	v_readlane_b32 s101, v183, 48
	s_nop 1
	v_mov_b32_e32 v183, s98
	v_add_f32_e32 v183, s99, v183
	v_add_f32_e32 v183, s100, v183
	v_add_f32_e32 v183, s101, v183
	v_fmamk_f32 v183, v183, 0x3a800000, v182
	v_cmp_gt_f32_e32 vcc, 0x800000, v183
	v_mul_f32_e32 v181, 0x4b800000, v183
	s_nop 1
	v_cndmask_b32_e32 v183, v183, v181, vcc
	v_rsq_f32_e32 v183, v183
	s_nop 0
	v_mul_f32_e32 v181, 0x45800000, v183
	v_cndmask_b32_e32 v184, v183, v181, vcc
	v_mov_b32_e32 v185, v184
	v_pk_mul_f32 v[160:161], v[160:161], v[184:185]
	v_pk_mul_f32 v[162:163], v[162:163], v[184:185]
	v_pk_mul_f32 v[164:165], v[164:165], v[184:185]
	v_pk_mul_f32 v[166:167], v[166:167], v[184:185]
	v_pk_mul_f32 v[168:169], v[168:169], v[184:185]
	v_pk_mul_f32 v[170:171], v[170:171], v[184:185]
	v_pk_mul_f32 v[172:173], v[172:173], v[184:185]
	v_pk_mul_f32 v[174:175], v[174:175], v[184:185]
	v_pk_fma_f32 v[144:145], v[160:161], v[128:129], v[144:145]
	v_pk_fma_f32 v[146:147], v[162:163], v[130:131], v[146:147]
	v_pk_fma_f32 v[148:149], v[164:165], v[132:133], v[148:149]
	v_pk_fma_f32 v[150:151], v[166:167], v[134:135], v[150:151]
	v_pk_fma_f32 v[152:153], v[168:169], v[136:137], v[152:153]
	v_pk_fma_f32 v[154:155], v[170:171], v[138:139], v[154:155]
	v_pk_fma_f32 v[156:157], v[172:173], v[140:141], v[156:157]
	v_pk_fma_f32 v[158:159], v[174:175], v[142:143], v[158:159]
	v_pk_mul_f32 v[252:253], v[144:145], v[144:145]
	v_pk_mul_f32 v[254:255], v[146:147], v[146:147]
	v_pk_fma_f32 v[252:253], v[148:149], v[148:149], v[252:253]
	v_pk_fma_f32 v[254:255], v[150:151], v[150:151], v[254:255]
	v_pk_fma_f32 v[252:253], v[152:153], v[152:153], v[252:253]
	v_pk_fma_f32 v[254:255], v[154:155], v[154:155], v[254:255]
	v_pk_fma_f32 v[252:253], v[156:157], v[156:157], v[252:253]
	v_pk_fma_f32 v[254:255], v[158:159], v[158:159], v[254:255]
	v_pk_add_f32 v[252:253], v[252:253], v[254:255]
	s_nop 0
	v_add_f32_e32 v183, v252, v253
	s_nop 1
	v_add_f32_dpp v183, v183, v183 quad_perm:[1,0,3,2] row_mask:0xf bank_mask:0xf bound_ctrl:1
	s_nop 1
	v_add_f32_dpp v183, v183, v183 quad_perm:[2,3,0,1] row_mask:0xf bank_mask:0xf bound_ctrl:1
	s_nop 1
	v_add_f32_dpp v183, v183, v183 row_half_mirror row_mask:0xf bank_mask:0xf bound_ctrl:1
	s_nop 1
	v_add_f32_dpp v183, v183, v183 row_mirror row_mask:0xf bank_mask:0xf bound_ctrl:1
	s_nop 1
	v_readlane_b32 s98, v183, 0
	v_readlane_b32 s99, v183, 16
	v_readlane_b32 s100, v183, 32
	v_readlane_b32 s101, v183, 48
	s_nop 1
	v_mov_b32_e32 v183, s98
	v_add_f32_e32 v183, s99, v183
	v_add_f32_e32 v183, s100, v183
	v_add_f32_e32 v183, s101, v183
	v_fmamk_f32 v183, v183, 0x3a800000, v182
	v_cmp_gt_f32_e32 vcc, 0x800000, v183
	v_mul_f32_e32 v181, 0x4b800000, v183
	s_nop 1
	v_cndmask_b32_e32 v183, v183, v181, vcc
	v_rsq_f32_e32 v183, v183
	s_nop 0
	v_mul_f32_e32 v181, 0x45800000, v183
	v_cndmask_b32_e32 v184, v183, v181, vcc
	v_mov_b32_e32 v185, v184
	v_pk_mul_f32 v[144:145], v[144:145], v[184:185]
	v_pk_mul_f32 v[146:147], v[146:147], v[184:185]
	v_pk_mul_f32 v[148:149], v[148:149], v[184:185]
	v_pk_mul_f32 v[150:151], v[150:151], v[184:185]
	v_pk_mul_f32 v[152:153], v[152:153], v[184:185]
	v_pk_mul_f32 v[154:155], v[154:155], v[184:185]
	v_pk_mul_f32 v[156:157], v[156:157], v[184:185]
	v_pk_mul_f32 v[158:159], v[158:159], v[184:185]
	v_pk_mul_f32 v[144:145], v[144:145], v[236:237]
	v_pk_mul_f32 v[146:147], v[146:147], v[238:239]
	v_pk_mul_f32 v[148:149], v[148:149], v[240:241]
	v_pk_mul_f32 v[150:151], v[150:151], v[242:243]
	v_pk_mul_f32 v[152:153], v[152:153], v[244:245]
	v_pk_mul_f32 v[154:155], v[154:155], v[246:247]
	v_pk_mul_f32 v[156:157], v[156:157], v[248:249]
	v_pk_mul_f32 v[158:159], v[158:159], v[250:251]
	v_add_u32_e32 v181, 0x2800000, v178
	global_store_dwordx4 v181, v[144:147], s[76:77]
	global_store_dwordx4 v181, v[148:151], s[76:77] offset:16
	global_store_dwordx4 v181, v[152:155], s[76:77] offset:2048
	global_store_dwordx4 v181, v[156:159], s[76:77] offset:2064
	s_nop 1
	s_waitcnt vmcnt(4)
	v_lshlrev_b32_e32 v144, 16, v96
	v_and_b32_e32 v145, 0xffff0000, v96
	v_lshlrev_b32_e32 v146, 16, v97
	v_and_b32_e32 v147, 0xffff0000, v97
	v_lshlrev_b32_e32 v148, 16, v98
	v_and_b32_e32 v149, 0xffff0000, v98
	v_lshlrev_b32_e32 v150, 16, v99
	v_and_b32_e32 v151, 0xffff0000, v99
	v_lshlrev_b32_e32 v152, 16, v100
	v_and_b32_e32 v153, 0xffff0000, v100
	v_lshlrev_b32_e32 v154, 16, v101
	v_and_b32_e32 v155, 0xffff0000, v101
	v_lshlrev_b32_e32 v156, 16, v102
	v_and_b32_e32 v157, 0xffff0000, v102
	v_lshlrev_b32_e32 v158, 16, v103
	v_and_b32_e32 v159, 0xffff0000, v103
	v_lshlrev_b32_e32 v160, 16, v104
	v_and_b32_e32 v161, 0xffff0000, v104
	v_lshlrev_b32_e32 v162, 16, v105
	v_and_b32_e32 v163, 0xffff0000, v105
	v_lshlrev_b32_e32 v164, 16, v106
	v_and_b32_e32 v165, 0xffff0000, v106
	v_lshlrev_b32_e32 v166, 16, v107
	v_and_b32_e32 v167, 0xffff0000, v107
	v_lshlrev_b32_e32 v168, 16, v108
	v_and_b32_e32 v169, 0xffff0000, v108
	v_lshlrev_b32_e32 v170, 16, v109
	v_and_b32_e32 v171, 0xffff0000, v109
	v_lshlrev_b32_e32 v172, 16, v110
	v_and_b32_e32 v173, 0xffff0000, v110
	v_lshlrev_b32_e32 v174, 16, v111
	v_and_b32_e32 v175, 0xffff0000, v111
	v_pk_mul_f32 v[252:253], v[160:161], v[160:161]
	v_pk_mul_f32 v[254:255], v[162:163], v[162:163]
	v_pk_fma_f32 v[252:253], v[164:165], v[164:165], v[252:253]
	v_pk_fma_f32 v[254:255], v[166:167], v[166:167], v[254:255]
	v_pk_fma_f32 v[252:253], v[168:169], v[168:169], v[252:253]
	v_pk_fma_f32 v[254:255], v[170:171], v[170:171], v[254:255]
	v_pk_fma_f32 v[252:253], v[172:173], v[172:173], v[252:253]
	v_pk_fma_f32 v[254:255], v[174:175], v[174:175], v[254:255]
	v_pk_add_f32 v[252:253], v[252:253], v[254:255]
	s_nop 0
	v_add_f32_e32 v183, v252, v253
	s_nop 1
	v_add_f32_dpp v183, v183, v183 quad_perm:[1,0,3,2] row_mask:0xf bank_mask:0xf bound_ctrl:1
	s_nop 1
	v_add_f32_dpp v183, v183, v183 quad_perm:[2,3,0,1] row_mask:0xf bank_mask:0xf bound_ctrl:1
	s_nop 1
	v_add_f32_dpp v183, v183, v183 row_half_mirror row_mask:0xf bank_mask:0xf bound_ctrl:1
	s_nop 1
	v_add_f32_dpp v183, v183, v183 row_mirror row_mask:0xf bank_mask:0xf bound_ctrl:1
	s_nop 1
	v_readlane_b32 s98, v183, 0
	v_readlane_b32 s99, v183, 16
	v_readlane_b32 s100, v183, 32
	v_readlane_b32 s101, v183, 48
	s_nop 1
	v_mov_b32_e32 v183, s98
	v_add_f32_e32 v183, s99, v183
	v_add_f32_e32 v183, s100, v183
	v_add_f32_e32 v183, s101, v183
	v_fmamk_f32 v183, v183, 0x3a800000, v182
	v_cmp_gt_f32_e32 vcc, 0x800000, v183
	v_mul_f32_e32 v181, 0x4b800000, v183
	s_nop 1
	v_cndmask_b32_e32 v183, v183, v181, vcc
	v_rsq_f32_e32 v183, v183
	s_nop 0
	v_mul_f32_e32 v181, 0x45800000, v183
	v_cndmask_b32_e32 v184, v183, v181, vcc
	v_mov_b32_e32 v185, v184
	v_pk_mul_f32 v[160:161], v[160:161], v[184:185]
	v_pk_mul_f32 v[162:163], v[162:163], v[184:185]
	v_pk_mul_f32 v[164:165], v[164:165], v[184:185]
	v_pk_mul_f32 v[166:167], v[166:167], v[184:185]
	v_pk_mul_f32 v[168:169], v[168:169], v[184:185]
	v_pk_mul_f32 v[170:171], v[170:171], v[184:185]
	v_pk_mul_f32 v[172:173], v[172:173], v[184:185]
	v_pk_mul_f32 v[174:175], v[174:175], v[184:185]
	v_pk_fma_f32 v[144:145], v[160:161], v[128:129], v[144:145]
	v_pk_fma_f32 v[146:147], v[162:163], v[130:131], v[146:147]
	v_pk_fma_f32 v[148:149], v[164:165], v[132:133], v[148:149]
	v_pk_fma_f32 v[150:151], v[166:167], v[134:135], v[150:151]
	v_pk_fma_f32 v[152:153], v[168:169], v[136:137], v[152:153]
	v_pk_fma_f32 v[154:155], v[170:171], v[138:139], v[154:155]
	v_pk_fma_f32 v[156:157], v[172:173], v[140:141], v[156:157]
	v_pk_fma_f32 v[158:159], v[174:175], v[142:143], v[158:159]
	v_pk_mul_f32 v[252:253], v[144:145], v[144:145]
	v_pk_mul_f32 v[254:255], v[146:147], v[146:147]
	v_pk_fma_f32 v[252:253], v[148:149], v[148:149], v[252:253]
	v_pk_fma_f32 v[254:255], v[150:151], v[150:151], v[254:255]
	v_pk_fma_f32 v[252:253], v[152:153], v[152:153], v[252:253]
	v_pk_fma_f32 v[254:255], v[154:155], v[154:155], v[254:255]
	v_pk_fma_f32 v[252:253], v[156:157], v[156:157], v[252:253]
	v_pk_fma_f32 v[254:255], v[158:159], v[158:159], v[254:255]
	v_pk_add_f32 v[252:253], v[252:253], v[254:255]
	s_nop 0
	v_add_f32_e32 v183, v252, v253
	s_nop 1
	v_add_f32_dpp v183, v183, v183 quad_perm:[1,0,3,2] row_mask:0xf bank_mask:0xf bound_ctrl:1
	s_nop 1
	v_add_f32_dpp v183, v183, v183 quad_perm:[2,3,0,1] row_mask:0xf bank_mask:0xf bound_ctrl:1
	s_nop 1
	v_add_f32_dpp v183, v183, v183 row_half_mirror row_mask:0xf bank_mask:0xf bound_ctrl:1
	s_nop 1
	v_add_f32_dpp v183, v183, v183 row_mirror row_mask:0xf bank_mask:0xf bound_ctrl:1
	s_nop 1
	v_readlane_b32 s98, v183, 0
	v_readlane_b32 s99, v183, 16
	v_readlane_b32 s100, v183, 32
	v_readlane_b32 s101, v183, 48
	s_nop 1
	v_mov_b32_e32 v183, s98
	v_add_f32_e32 v183, s99, v183
	v_add_f32_e32 v183, s100, v183
	v_add_f32_e32 v183, s101, v183
	v_fmamk_f32 v183, v183, 0x3a800000, v182
	v_cmp_gt_f32_e32 vcc, 0x800000, v183
	v_mul_f32_e32 v181, 0x4b800000, v183
	s_nop 1
	v_cndmask_b32_e32 v183, v183, v181, vcc
	v_rsq_f32_e32 v183, v183
	s_nop 0
	v_mul_f32_e32 v181, 0x45800000, v183
	v_cndmask_b32_e32 v184, v183, v181, vcc
	v_mov_b32_e32 v185, v184
	v_pk_mul_f32 v[144:145], v[144:145], v[184:185]
	v_pk_mul_f32 v[146:147], v[146:147], v[184:185]
	v_pk_mul_f32 v[148:149], v[148:149], v[184:185]
	v_pk_mul_f32 v[150:151], v[150:151], v[184:185]
	v_pk_mul_f32 v[152:153], v[152:153], v[184:185]
	v_pk_mul_f32 v[154:155], v[154:155], v[184:185]
	v_pk_mul_f32 v[156:157], v[156:157], v[184:185]
	v_pk_mul_f32 v[158:159], v[158:159], v[184:185]
	v_pk_mul_f32 v[144:145], v[144:145], v[236:237]
	v_pk_mul_f32 v[146:147], v[146:147], v[238:239]
	v_pk_mul_f32 v[148:149], v[148:149], v[240:241]
	v_pk_mul_f32 v[150:151], v[150:151], v[242:243]
	v_pk_mul_f32 v[152:153], v[152:153], v[244:245]
	v_pk_mul_f32 v[154:155], v[154:155], v[246:247]
	v_pk_mul_f32 v[156:157], v[156:157], v[248:249]
	v_pk_mul_f32 v[158:159], v[158:159], v[250:251]
	v_add_u32_e32 v181, 0x3000000, v178
	global_store_dwordx4 v181, v[144:147], s[76:77]
	global_store_dwordx4 v181, v[148:151], s[76:77] offset:16
	global_store_dwordx4 v181, v[152:155], s[76:77] offset:2048
	global_store_dwordx4 v181, v[156:159], s[76:77] offset:2064
	s_nop 1
	s_waitcnt vmcnt(0)
	v_lshlrev_b32_e32 v144, 16, v112
	v_and_b32_e32 v145, 0xffff0000, v112
	v_lshlrev_b32_e32 v146, 16, v113
	v_and_b32_e32 v147, 0xffff0000, v113
	v_lshlrev_b32_e32 v148, 16, v114
	v_and_b32_e32 v149, 0xffff0000, v114
	v_lshlrev_b32_e32 v150, 16, v115
	v_and_b32_e32 v151, 0xffff0000, v115
	v_lshlrev_b32_e32 v152, 16, v116
	v_and_b32_e32 v153, 0xffff0000, v116
	v_lshlrev_b32_e32 v154, 16, v117
	v_and_b32_e32 v155, 0xffff0000, v117
	v_lshlrev_b32_e32 v156, 16, v118
	v_and_b32_e32 v157, 0xffff0000, v118
	v_lshlrev_b32_e32 v158, 16, v119
	v_and_b32_e32 v159, 0xffff0000, v119
	v_lshlrev_b32_e32 v160, 16, v120
	v_and_b32_e32 v161, 0xffff0000, v120
	v_lshlrev_b32_e32 v162, 16, v121
	v_and_b32_e32 v163, 0xffff0000, v121
	v_lshlrev_b32_e32 v164, 16, v122
	v_and_b32_e32 v165, 0xffff0000, v122
	v_lshlrev_b32_e32 v166, 16, v123
	v_and_b32_e32 v167, 0xffff0000, v123
	v_lshlrev_b32_e32 v168, 16, v124
	v_and_b32_e32 v169, 0xffff0000, v124
	v_lshlrev_b32_e32 v170, 16, v125
	v_and_b32_e32 v171, 0xffff0000, v125
	v_lshlrev_b32_e32 v172, 16, v126
	v_and_b32_e32 v173, 0xffff0000, v126
	v_lshlrev_b32_e32 v174, 16, v127
	v_and_b32_e32 v175, 0xffff0000, v127
	v_pk_mul_f32 v[252:253], v[160:161], v[160:161]
	v_pk_mul_f32 v[254:255], v[162:163], v[162:163]
	v_pk_fma_f32 v[252:253], v[164:165], v[164:165], v[252:253]
	v_pk_fma_f32 v[254:255], v[166:167], v[166:167], v[254:255]
	v_pk_fma_f32 v[252:253], v[168:169], v[168:169], v[252:253]
	v_pk_fma_f32 v[254:255], v[170:171], v[170:171], v[254:255]
	v_pk_fma_f32 v[252:253], v[172:173], v[172:173], v[252:253]
	v_pk_fma_f32 v[254:255], v[174:175], v[174:175], v[254:255]
	v_pk_add_f32 v[252:253], v[252:253], v[254:255]
	s_nop 0
	v_add_f32_e32 v183, v252, v253
	s_nop 1
	v_add_f32_dpp v183, v183, v183 quad_perm:[1,0,3,2] row_mask:0xf bank_mask:0xf bound_ctrl:1
	s_nop 1
	v_add_f32_dpp v183, v183, v183 quad_perm:[2,3,0,1] row_mask:0xf bank_mask:0xf bound_ctrl:1
	s_nop 1
	v_add_f32_dpp v183, v183, v183 row_half_mirror row_mask:0xf bank_mask:0xf bound_ctrl:1
	s_nop 1
	v_add_f32_dpp v183, v183, v183 row_mirror row_mask:0xf bank_mask:0xf bound_ctrl:1
	s_nop 1
	v_readlane_b32 s98, v183, 0
	v_readlane_b32 s99, v183, 16
	v_readlane_b32 s100, v183, 32
	v_readlane_b32 s101, v183, 48
	s_nop 1
	v_mov_b32_e32 v183, s98
	v_add_f32_e32 v183, s99, v183
	v_add_f32_e32 v183, s100, v183
	v_add_f32_e32 v183, s101, v183
	v_fmamk_f32 v183, v183, 0x3a800000, v182
	v_cmp_gt_f32_e32 vcc, 0x800000, v183
	v_mul_f32_e32 v181, 0x4b800000, v183
	s_nop 1
	v_cndmask_b32_e32 v183, v183, v181, vcc
	v_rsq_f32_e32 v183, v183
	s_nop 0
	v_mul_f32_e32 v181, 0x45800000, v183
	v_cndmask_b32_e32 v184, v183, v181, vcc
	v_mov_b32_e32 v185, v184
	v_pk_mul_f32 v[160:161], v[160:161], v[184:185]
	v_pk_mul_f32 v[162:163], v[162:163], v[184:185]
	v_pk_mul_f32 v[164:165], v[164:165], v[184:185]
	v_pk_mul_f32 v[166:167], v[166:167], v[184:185]
	v_pk_mul_f32 v[168:169], v[168:169], v[184:185]
	v_pk_mul_f32 v[170:171], v[170:171], v[184:185]
	v_pk_mul_f32 v[172:173], v[172:173], v[184:185]
	v_pk_mul_f32 v[174:175], v[174:175], v[184:185]
	v_pk_fma_f32 v[144:145], v[160:161], v[128:129], v[144:145]
	v_pk_fma_f32 v[146:147], v[162:163], v[130:131], v[146:147]
	v_pk_fma_f32 v[148:149], v[164:165], v[132:133], v[148:149]
	v_pk_fma_f32 v[150:151], v[166:167], v[134:135], v[150:151]
	v_pk_fma_f32 v[152:153], v[168:169], v[136:137], v[152:153]
	v_pk_fma_f32 v[154:155], v[170:171], v[138:139], v[154:155]
	v_pk_fma_f32 v[156:157], v[172:173], v[140:141], v[156:157]
	v_pk_fma_f32 v[158:159], v[174:175], v[142:143], v[158:159]
	v_pk_mul_f32 v[252:253], v[144:145], v[144:145]
	v_pk_mul_f32 v[254:255], v[146:147], v[146:147]
	v_pk_fma_f32 v[252:253], v[148:149], v[148:149], v[252:253]
	v_pk_fma_f32 v[254:255], v[150:151], v[150:151], v[254:255]
	v_pk_fma_f32 v[252:253], v[152:153], v[152:153], v[252:253]
	v_pk_fma_f32 v[254:255], v[154:155], v[154:155], v[254:255]
	v_pk_fma_f32 v[252:253], v[156:157], v[156:157], v[252:253]
	v_pk_fma_f32 v[254:255], v[158:159], v[158:159], v[254:255]
	v_pk_add_f32 v[252:253], v[252:253], v[254:255]
	s_nop 0
	v_add_f32_e32 v183, v252, v253
	s_nop 1
	v_add_f32_dpp v183, v183, v183 quad_perm:[1,0,3,2] row_mask:0xf bank_mask:0xf bound_ctrl:1
	s_nop 1
	v_add_f32_dpp v183, v183, v183 quad_perm:[2,3,0,1] row_mask:0xf bank_mask:0xf bound_ctrl:1
	s_nop 1
	v_add_f32_dpp v183, v183, v183 row_half_mirror row_mask:0xf bank_mask:0xf bound_ctrl:1
	s_nop 1
	v_add_f32_dpp v183, v183, v183 row_mirror row_mask:0xf bank_mask:0xf bound_ctrl:1
	s_nop 1
	v_readlane_b32 s98, v183, 0
	v_readlane_b32 s99, v183, 16
	v_readlane_b32 s100, v183, 32
	v_readlane_b32 s101, v183, 48
	s_nop 1
	v_mov_b32_e32 v183, s98
	v_add_f32_e32 v183, s99, v183
	v_add_f32_e32 v183, s100, v183
	v_add_f32_e32 v183, s101, v183
	v_fmamk_f32 v183, v183, 0x3a800000, v182
	v_cmp_gt_f32_e32 vcc, 0x800000, v183
	v_mul_f32_e32 v181, 0x4b800000, v183
	s_nop 1
	v_cndmask_b32_e32 v183, v183, v181, vcc
	v_rsq_f32_e32 v183, v183
	s_nop 0
	v_mul_f32_e32 v181, 0x45800000, v183
	v_cndmask_b32_e32 v184, v183, v181, vcc
	v_mov_b32_e32 v185, v184
	v_pk_mul_f32 v[144:145], v[144:145], v[184:185]
	v_pk_mul_f32 v[146:147], v[146:147], v[184:185]
	v_pk_mul_f32 v[148:149], v[148:149], v[184:185]
	v_pk_mul_f32 v[150:151], v[150:151], v[184:185]
	v_pk_mul_f32 v[152:153], v[152:153], v[184:185]
	v_pk_mul_f32 v[154:155], v[154:155], v[184:185]
	v_pk_mul_f32 v[156:157], v[156:157], v[184:185]
	v_pk_mul_f32 v[158:159], v[158:159], v[184:185]
	v_pk_mul_f32 v[144:145], v[144:145], v[236:237]
	v_pk_mul_f32 v[146:147], v[146:147], v[238:239]
	v_pk_mul_f32 v[148:149], v[148:149], v[240:241]
	v_pk_mul_f32 v[150:151], v[150:151], v[242:243]
	v_pk_mul_f32 v[152:153], v[152:153], v[244:245]
	v_pk_mul_f32 v[154:155], v[154:155], v[246:247]
	v_pk_mul_f32 v[156:157], v[156:157], v[248:249]
	v_pk_mul_f32 v[158:159], v[158:159], v[250:251]
	v_add_u32_e32 v181, 0x3800000, v178
	global_store_dwordx4 v181, v[144:147], s[76:77]
	global_store_dwordx4 v181, v[148:151], s[76:77] offset:16
	global_store_dwordx4 v181, v[152:155], s[76:77] offset:2048
	global_store_dwordx4 v181, v[156:159], s[76:77] offset:2064
	s_nop 1
	v_readfirstlane_b32 s98, v179
	s_nop 3
	s_and_b32 s99, s98, 3
	s_add_i32 s100, s99, 4
	s_lshl_b32 s100, s100, 11
	s_sub_i32 s100, s100, s99
	s_lshl_b32 s101, s100, 11
	v_add_u32_e32 v177, s101, v177
	s_lshl_b32 s101, s100, 12
	v_add_u32_e32 v178, s101, v178
	v_add_u32_e32 v181, 0x1800000, v177
	global_load_dwordx4 v[0:3], v181, s[78:79]
	global_load_dwordx4 v[4:7], v181, s[78:79] offset:1024
	v_add_u32_e32 v181, 0x9e00000, v177
	global_load_dwordx4 v[8:11], v181, s[78:79]
	global_load_dwordx4 v[12:15], v181, s[78:79] offset:1024
	s_waitcnt vmcnt(0)
	v_lshlrev_b32_e32 v144, 16, v0
	v_and_b32_e32 v145, 0xffff0000, v0
	v_lshlrev_b32_e32 v146, 16, v1
	v_and_b32_e32 v147, 0xffff0000, v1
	v_lshlrev_b32_e32 v148, 16, v2
	v_and_b32_e32 v149, 0xffff0000, v2
	v_lshlrev_b32_e32 v150, 16, v3
	v_and_b32_e32 v151, 0xffff0000, v3
	v_lshlrev_b32_e32 v152, 16, v4
	v_and_b32_e32 v153, 0xffff0000, v4
	v_lshlrev_b32_e32 v154, 16, v5
	v_and_b32_e32 v155, 0xffff0000, v5
	v_lshlrev_b32_e32 v156, 16, v6
	v_and_b32_e32 v157, 0xffff0000, v6
	v_lshlrev_b32_e32 v158, 16, v7
	v_and_b32_e32 v159, 0xffff0000, v7
	v_lshlrev_b32_e32 v160, 16, v8
	v_and_b32_e32 v161, 0xffff0000, v8
	v_lshlrev_b32_e32 v162, 16, v9
	v_and_b32_e32 v163, 0xffff0000, v9
	v_lshlrev_b32_e32 v164, 16, v10
	v_and_b32_e32 v165, 0xffff0000, v10
	v_lshlrev_b32_e32 v166, 16, v11
	v_and_b32_e32 v167, 0xffff0000, v11
	v_lshlrev_b32_e32 v168, 16, v12
	v_and_b32_e32 v169, 0xffff0000, v12
	v_lshlrev_b32_e32 v170, 16, v13
	v_and_b32_e32 v171, 0xffff0000, v13
	v_lshlrev_b32_e32 v172, 16, v14
	v_and_b32_e32 v173, 0xffff0000, v14
	v_lshlrev_b32_e32 v174, 16, v15
	v_and_b32_e32 v175, 0xffff0000, v15
	v_pk_mul_f32 v[252:253], v[160:161], v[160:161]
	v_pk_mul_f32 v[254:255], v[162:163], v[162:163]
	v_pk_fma_f32 v[252:253], v[164:165], v[164:165], v[252:253]
	v_pk_fma_f32 v[254:255], v[166:167], v[166:167], v[254:255]
	v_pk_fma_f32 v[252:253], v[168:169], v[168:169], v[252:253]
	v_pk_fma_f32 v[254:255], v[170:171], v[170:171], v[254:255]
	v_pk_fma_f32 v[252:253], v[172:173], v[172:173], v[252:253]
	v_pk_fma_f32 v[254:255], v[174:175], v[174:175], v[254:255]
	v_pk_add_f32 v[252:253], v[252:253], v[254:255]
	s_nop 0
	v_add_f32_e32 v183, v252, v253
	s_nop 1
	v_add_f32_dpp v183, v183, v183 quad_perm:[1,0,3,2] row_mask:0xf bank_mask:0xf bound_ctrl:1
	s_nop 1
	v_add_f32_dpp v183, v183, v183 quad_perm:[2,3,0,1] row_mask:0xf bank_mask:0xf bound_ctrl:1
	s_nop 1
	v_add_f32_dpp v183, v183, v183 row_half_mirror row_mask:0xf bank_mask:0xf bound_ctrl:1
	s_nop 1
	v_add_f32_dpp v183, v183, v183 row_mirror row_mask:0xf bank_mask:0xf bound_ctrl:1
	s_nop 1
	v_readlane_b32 s98, v183, 0
	v_readlane_b32 s99, v183, 16
	v_readlane_b32 s100, v183, 32
	v_readlane_b32 s101, v183, 48
	s_nop 1
	v_mov_b32_e32 v183, s98
	v_add_f32_e32 v183, s99, v183
	v_add_f32_e32 v183, s100, v183
	v_add_f32_e32 v183, s101, v183
	v_fmamk_f32 v183, v183, 0x3a800000, v182
	v_cmp_gt_f32_e32 vcc, 0x800000, v183
	v_mul_f32_e32 v181, 0x4b800000, v183
	s_nop 1
	v_cndmask_b32_e32 v183, v183, v181, vcc
	v_rsq_f32_e32 v183, v183
	s_nop 0
	v_mul_f32_e32 v181, 0x45800000, v183
	v_cndmask_b32_e32 v184, v183, v181, vcc
	v_mov_b32_e32 v185, v184
	v_pk_mul_f32 v[160:161], v[160:161], v[184:185]
	v_pk_mul_f32 v[162:163], v[162:163], v[184:185]
	v_pk_mul_f32 v[164:165], v[164:165], v[184:185]
	v_pk_mul_f32 v[166:167], v[166:167], v[184:185]
	v_pk_mul_f32 v[168:169], v[168:169], v[184:185]
	v_pk_mul_f32 v[170:171], v[170:171], v[184:185]
	v_pk_mul_f32 v[172:173], v[172:173], v[184:185]
	v_pk_mul_f32 v[174:175], v[174:175], v[184:185]
	v_pk_fma_f32 v[144:145], v[160:161], v[128:129], v[144:145]
	v_pk_fma_f32 v[146:147], v[162:163], v[130:131], v[146:147]
	v_pk_fma_f32 v[148:149], v[164:165], v[132:133], v[148:149]
	v_pk_fma_f32 v[150:151], v[166:167], v[134:135], v[150:151]
	v_pk_fma_f32 v[152:153], v[168:169], v[136:137], v[152:153]
	v_pk_fma_f32 v[154:155], v[170:171], v[138:139], v[154:155]
	v_pk_fma_f32 v[156:157], v[172:173], v[140:141], v[156:157]
	v_pk_fma_f32 v[158:159], v[174:175], v[142:143], v[158:159]
	v_pk_mul_f32 v[252:253], v[144:145], v[144:145]
	v_pk_mul_f32 v[254:255], v[146:147], v[146:147]
	v_pk_fma_f32 v[252:253], v[148:149], v[148:149], v[252:253]
	v_pk_fma_f32 v[254:255], v[150:151], v[150:151], v[254:255]
	v_pk_fma_f32 v[252:253], v[152:153], v[152:153], v[252:253]
	v_pk_fma_f32 v[254:255], v[154:155], v[154:155], v[254:255]
	v_pk_fma_f32 v[252:253], v[156:157], v[156:157], v[252:253]
	v_pk_fma_f32 v[254:255], v[158:159], v[158:159], v[254:255]
	v_pk_add_f32 v[252:253], v[252:253], v[254:255]
	s_nop 0
	v_add_f32_e32 v183, v252, v253
	s_nop 1
	v_add_f32_dpp v183, v183, v183 quad_perm:[1,0,3,2] row_mask:0xf bank_mask:0xf bound_ctrl:1
	s_nop 1
	v_add_f32_dpp v183, v183, v183 quad_perm:[2,3,0,1] row_mask:0xf bank_mask:0xf bound_ctrl:1
	s_nop 1
	v_add_f32_dpp v183, v183, v183 row_half_mirror row_mask:0xf bank_mask:0xf bound_ctrl:1
	s_nop 1
	v_add_f32_dpp v183, v183, v183 row_mirror row_mask:0xf bank_mask:0xf bound_ctrl:1
	s_nop 1
	v_readlane_b32 s98, v183, 0
	v_readlane_b32 s99, v183, 16
	v_readlane_b32 s100, v183, 32
	v_readlane_b32 s101, v183, 48
	s_nop 1
	v_mov_b32_e32 v183, s98
	v_add_f32_e32 v183, s99, v183
	v_add_f32_e32 v183, s100, v183
	v_add_f32_e32 v183, s101, v183
	v_fmamk_f32 v183, v183, 0x3a800000, v182
	v_cmp_gt_f32_e32 vcc, 0x800000, v183
	v_mul_f32_e32 v181, 0x4b800000, v183
	s_nop 1
	v_cndmask_b32_e32 v183, v183, v181, vcc
	v_rsq_f32_e32 v183, v183
	s_nop 0
	v_mul_f32_e32 v181, 0x45800000, v183
	v_cndmask_b32_e32 v184, v183, v181, vcc
	v_mov_b32_e32 v185, v184
	v_pk_mul_f32 v[144:145], v[144:145], v[184:185]
	v_pk_mul_f32 v[146:147], v[146:147], v[184:185]
	v_pk_mul_f32 v[148:149], v[148:149], v[184:185]
	v_pk_mul_f32 v[150:151], v[150:151], v[184:185]
	v_pk_mul_f32 v[152:153], v[152:153], v[184:185]
	v_pk_mul_f32 v[154:155], v[154:155], v[184:185]
	v_pk_mul_f32 v[156:157], v[156:157], v[184:185]
	v_pk_mul_f32 v[158:159], v[158:159], v[184:185]
	v_pk_mul_f32 v[144:145], v[144:145], v[236:237]
	v_pk_mul_f32 v[146:147], v[146:147], v[238:239]
	v_pk_mul_f32 v[148:149], v[148:149], v[240:241]
	v_pk_mul_f32 v[150:151], v[150:151], v[242:243]
	v_pk_mul_f32 v[152:153], v[152:153], v[244:245]
	v_pk_mul_f32 v[154:155], v[154:155], v[246:247]
	v_pk_mul_f32 v[156:157], v[156:157], v[248:249]
	v_pk_mul_f32 v[158:159], v[158:159], v[250:251]
	v_add_u32_e32 v181, 0x0, v178
	global_store_dwordx4 v181, v[144:147], s[76:77]
	global_store_dwordx4 v181, v[148:151], s[76:77] offset:16
	global_store_dwordx4 v181, v[152:155], s[76:77] offset:2048
	global_store_dwordx4 v181, v[156:159], s[76:77] offset:2064
	s_nop 1
	s_branch .Lmyxupd_done_7
.Lmyxupd_heavy_7:
	global_load_dwordx4 v[0:3], v178, s[78:79]
	global_load_dwordx4 v[4:7], v178, s[78:79] offset:1024
	global_load_dwordx4 v[8:11], v179, s[78:79]
	global_load_dwordx4 v[12:15], v179, s[78:79] offset:1024
	v_add_u32_e32 v178, 0x400000, v178
	v_add_u32_e32 v179, 0x400000, v179
	global_load_dwordx4 v[16:19], v178, s[78:79]
	global_load_dwordx4 v[20:23], v178, s[78:79] offset:1024
	global_load_dwordx4 v[24:27], v179, s[78:79]
	global_load_dwordx4 v[28:31], v179, s[78:79] offset:1024
	v_add_u32_e32 v178, 0x400000, v178
	v_add_u32_e32 v179, 0x400000, v179
	global_load_dwordx4 v[32:35], v178, s[78:79]
	global_load_dwordx4 v[36:39], v178, s[78:79] offset:1024
	global_load_dwordx4 v[40:43], v179, s[78:79]
	global_load_dwordx4 v[44:47], v179, s[78:79] offset:1024
	v_add_u32_e32 v178, 0x400000, v178
	v_add_u32_e32 v179, 0x400000, v179
	global_load_dwordx4 v[48:51], v178, s[78:79]
	global_load_dwordx4 v[52:55], v178, s[78:79] offset:1024
	global_load_dwordx4 v[56:59], v179, s[78:79]
	global_load_dwordx4 v[60:63], v179, s[78:79] offset:1024
	v_add_u32_e32 v178, 0x400000, v178
	v_add_u32_e32 v179, 0x400000, v179
	global_load_dwordx4 v[64:67], v178, s[78:79]
	global_load_dwordx4 v[68:71], v178, s[78:79] offset:1024
	global_load_dwordx4 v[72:75], v179, s[78:79]
	global_load_dwordx4 v[76:79], v179, s[78:79] offset:1024
	v_lshl_add_u32 v178, v183, 12, v180
	v_mov_b32_e32 v179, s98
	s_waitcnt vmcnt(16)
	v_lshlrev_b32_e32 v144, 16, v0
	v_and_b32_e32 v145, 0xffff0000, v0
	v_lshlrev_b32_e32 v146, 16, v1
	v_and_b32_e32 v147, 0xffff0000, v1
	v_lshlrev_b32_e32 v148, 16, v2
	v_and_b32_e32 v149, 0xffff0000, v2
	v_lshlrev_b32_e32 v150, 16, v3
	v_and_b32_e32 v151, 0xffff0000, v3
	v_lshlrev_b32_e32 v152, 16, v4
	v_and_b32_e32 v153, 0xffff0000, v4
	v_lshlrev_b32_e32 v154, 16, v5
	v_and_b32_e32 v155, 0xffff0000, v5
	v_lshlrev_b32_e32 v156, 16, v6
	v_and_b32_e32 v157, 0xffff0000, v6
	v_lshlrev_b32_e32 v158, 16, v7
	v_and_b32_e32 v159, 0xffff0000, v7
	v_lshlrev_b32_e32 v160, 16, v8
	v_and_b32_e32 v161, 0xffff0000, v8
	v_lshlrev_b32_e32 v162, 16, v9
	v_and_b32_e32 v163, 0xffff0000, v9
	v_lshlrev_b32_e32 v164, 16, v10
	v_and_b32_e32 v165, 0xffff0000, v10
	v_lshlrev_b32_e32 v166, 16, v11
	v_and_b32_e32 v167, 0xffff0000, v11
	v_lshlrev_b32_e32 v168, 16, v12
	v_and_b32_e32 v169, 0xffff0000, v12
	v_lshlrev_b32_e32 v170, 16, v13
	v_and_b32_e32 v171, 0xffff0000, v13
	v_lshlrev_b32_e32 v172, 16, v14
	v_and_b32_e32 v173, 0xffff0000, v14
	v_lshlrev_b32_e32 v174, 16, v15
	v_and_b32_e32 v175, 0xffff0000, v15
	v_pk_mul_f32 v[252:253], v[160:161], v[160:161]
	v_pk_mul_f32 v[254:255], v[162:163], v[162:163]
	v_pk_fma_f32 v[252:253], v[164:165], v[164:165], v[252:253]
	v_pk_fma_f32 v[254:255], v[166:167], v[166:167], v[254:255]
	v_pk_fma_f32 v[252:253], v[168:169], v[168:169], v[252:253]
	v_pk_fma_f32 v[254:255], v[170:171], v[170:171], v[254:255]
	v_pk_fma_f32 v[252:253], v[172:173], v[172:173], v[252:253]
	v_pk_fma_f32 v[254:255], v[174:175], v[174:175], v[254:255]
	v_pk_add_f32 v[252:253], v[252:253], v[254:255]
	s_nop 0
	v_add_f32_e32 v183, v252, v253
	s_nop 1
	v_add_f32_dpp v183, v183, v183 quad_perm:[1,0,3,2] row_mask:0xf bank_mask:0xf bound_ctrl:1
	s_nop 1
	v_add_f32_dpp v183, v183, v183 quad_perm:[2,3,0,1] row_mask:0xf bank_mask:0xf bound_ctrl:1
	s_nop 1
	v_add_f32_dpp v183, v183, v183 row_half_mirror row_mask:0xf bank_mask:0xf bound_ctrl:1
	s_nop 1
	v_add_f32_dpp v183, v183, v183 row_mirror row_mask:0xf bank_mask:0xf bound_ctrl:1
	s_nop 1
	v_readlane_b32 s98, v183, 0
	v_readlane_b32 s99, v183, 16
	v_readlane_b32 s100, v183, 32
	v_readlane_b32 s101, v183, 48
	s_nop 1
	v_mov_b32_e32 v183, s98
	v_add_f32_e32 v183, s99, v183
	v_add_f32_e32 v183, s100, v183
	v_add_f32_e32 v183, s101, v183
	v_fmamk_f32 v183, v183, 0x3a800000, v182
	v_cmp_gt_f32_e32 vcc, 0x800000, v183
	v_mul_f32_e32 v181, 0x4b800000, v183
	s_nop 1
	v_cndmask_b32_e32 v183, v183, v181, vcc
	v_rsq_f32_e32 v183, v183
	s_nop 0
	v_mul_f32_e32 v181, 0x45800000, v183
	v_cndmask_b32_e32 v184, v183, v181, vcc
	v_mov_b32_e32 v185, v184
	v_pk_mul_f32 v[160:161], v[160:161], v[184:185]
	v_pk_mul_f32 v[162:163], v[162:163], v[184:185]
	v_pk_mul_f32 v[164:165], v[164:165], v[184:185]
	v_pk_mul_f32 v[166:167], v[166:167], v[184:185]
	v_pk_mul_f32 v[168:169], v[168:169], v[184:185]
	v_pk_mul_f32 v[170:171], v[170:171], v[184:185]
	v_pk_mul_f32 v[172:173], v[172:173], v[184:185]
	v_pk_mul_f32 v[174:175], v[174:175], v[184:185]
	v_pk_fma_f32 v[144:145], v[160:161], v[128:129], v[144:145]
	v_pk_fma_f32 v[146:147], v[162:163], v[130:131], v[146:147]
	v_pk_fma_f32 v[148:149], v[164:165], v[132:133], v[148:149]
	v_pk_fma_f32 v[150:151], v[166:167], v[134:135], v[150:151]
	v_pk_fma_f32 v[152:153], v[168:169], v[136:137], v[152:153]
	v_pk_fma_f32 v[154:155], v[170:171], v[138:139], v[154:155]
	v_pk_fma_f32 v[156:157], v[172:173], v[140:141], v[156:157]
	v_pk_fma_f32 v[158:159], v[174:175], v[142:143], v[158:159]
	v_pk_mul_f32 v[252:253], v[144:145], v[144:145]
	v_pk_mul_f32 v[254:255], v[146:147], v[146:147]
	v_pk_fma_f32 v[252:253], v[148:149], v[148:149], v[252:253]
	v_pk_fma_f32 v[254:255], v[150:151], v[150:151], v[254:255]
	v_pk_fma_f32 v[252:253], v[152:153], v[152:153], v[252:253]
	v_pk_fma_f32 v[254:255], v[154:155], v[154:155], v[254:255]
	v_pk_fma_f32 v[252:253], v[156:157], v[156:157], v[252:253]
	v_pk_fma_f32 v[254:255], v[158:159], v[158:159], v[254:255]
	v_pk_add_f32 v[252:253], v[252:253], v[254:255]
	s_nop 0
	v_add_f32_e32 v183, v252, v253
	s_nop 1
	v_add_f32_dpp v183, v183, v183 quad_perm:[1,0,3,2] row_mask:0xf bank_mask:0xf bound_ctrl:1
	s_nop 1
	v_add_f32_dpp v183, v183, v183 quad_perm:[2,3,0,1] row_mask:0xf bank_mask:0xf bound_ctrl:1
	s_nop 1
	v_add_f32_dpp v183, v183, v183 row_half_mirror row_mask:0xf bank_mask:0xf bound_ctrl:1
	s_nop 1
	v_add_f32_dpp v183, v183, v183 row_mirror row_mask:0xf bank_mask:0xf bound_ctrl:1
	s_nop 1
	v_readlane_b32 s98, v183, 0
	v_readlane_b32 s99, v183, 16
	v_readlane_b32 s100, v183, 32
	v_readlane_b32 s101, v183, 48
	s_nop 1
	v_mov_b32_e32 v183, s98
	v_add_f32_e32 v183, s99, v183
	v_add_f32_e32 v183, s100, v183
	v_add_f32_e32 v183, s101, v183
	v_fmamk_f32 v183, v183, 0x3a800000, v182
	v_cmp_gt_f32_e32 vcc, 0x800000, v183
	v_mul_f32_e32 v181, 0x4b800000, v183
	s_nop 1
	v_cndmask_b32_e32 v183, v183, v181, vcc
	v_rsq_f32_e32 v183, v183
	s_nop 0
	v_mul_f32_e32 v181, 0x45800000, v183
	v_cndmask_b32_e32 v184, v183, v181, vcc
	v_mov_b32_e32 v185, v184
	v_pk_mul_f32 v[144:145], v[144:145], v[184:185]
	v_pk_mul_f32 v[146:147], v[146:147], v[184:185]
	v_pk_mul_f32 v[148:149], v[148:149], v[184:185]
	v_pk_mul_f32 v[150:151], v[150:151], v[184:185]
	v_pk_mul_f32 v[152:153], v[152:153], v[184:185]
	v_pk_mul_f32 v[154:155], v[154:155], v[184:185]
	v_pk_mul_f32 v[156:157], v[156:157], v[184:185]
	v_pk_mul_f32 v[158:159], v[158:159], v[184:185]
	v_pk_mul_f32 v[144:145], v[144:145], v[236:237]
	v_pk_mul_f32 v[146:147], v[146:147], v[238:239]
	v_pk_mul_f32 v[148:149], v[148:149], v[240:241]
	v_pk_mul_f32 v[150:151], v[150:151], v[242:243]
	v_pk_mul_f32 v[152:153], v[152:153], v[244:245]
	v_pk_mul_f32 v[154:155], v[154:155], v[246:247]
	v_pk_mul_f32 v[156:157], v[156:157], v[248:249]
	v_pk_mul_f32 v[158:159], v[158:159], v[250:251]
	v_add_u32_e32 v181, 0x0, v178
	global_store_dwordx4 v181, v[144:147], s[76:77]
	global_store_dwordx4 v181, v[148:151], s[76:77] offset:16
	global_store_dwordx4 v181, v[152:155], s[76:77] offset:2048
	global_store_dwordx4 v181, v[156:159], s[76:77] offset:2064
	s_nop 1
	s_waitcnt vmcnt(12)
	v_lshlrev_b32_e32 v144, 16, v16
	v_and_b32_e32 v145, 0xffff0000, v16
	v_lshlrev_b32_e32 v146, 16, v17
	v_and_b32_e32 v147, 0xffff0000, v17
	v_lshlrev_b32_e32 v148, 16, v18
	v_and_b32_e32 v149, 0xffff0000, v18
	v_lshlrev_b32_e32 v150, 16, v19
	v_and_b32_e32 v151, 0xffff0000, v19
	v_lshlrev_b32_e32 v152, 16, v20
	v_and_b32_e32 v153, 0xffff0000, v20
	v_lshlrev_b32_e32 v154, 16, v21
	v_and_b32_e32 v155, 0xffff0000, v21
	v_lshlrev_b32_e32 v156, 16, v22
	v_and_b32_e32 v157, 0xffff0000, v22
	v_lshlrev_b32_e32 v158, 16, v23
	v_and_b32_e32 v159, 0xffff0000, v23
	v_lshlrev_b32_e32 v160, 16, v24
	v_and_b32_e32 v161, 0xffff0000, v24
	v_lshlrev_b32_e32 v162, 16, v25
	v_and_b32_e32 v163, 0xffff0000, v25
	v_lshlrev_b32_e32 v164, 16, v26
	v_and_b32_e32 v165, 0xffff0000, v26
	v_lshlrev_b32_e32 v166, 16, v27
	v_and_b32_e32 v167, 0xffff0000, v27
	v_lshlrev_b32_e32 v168, 16, v28
	v_and_b32_e32 v169, 0xffff0000, v28
	v_lshlrev_b32_e32 v170, 16, v29
	v_and_b32_e32 v171, 0xffff0000, v29
	v_lshlrev_b32_e32 v172, 16, v30
	v_and_b32_e32 v173, 0xffff0000, v30
	v_lshlrev_b32_e32 v174, 16, v31
	v_and_b32_e32 v175, 0xffff0000, v31
	v_pk_mul_f32 v[252:253], v[160:161], v[160:161]
	v_pk_mul_f32 v[254:255], v[162:163], v[162:163]
	v_pk_fma_f32 v[252:253], v[164:165], v[164:165], v[252:253]
	v_pk_fma_f32 v[254:255], v[166:167], v[166:167], v[254:255]
	v_pk_fma_f32 v[252:253], v[168:169], v[168:169], v[252:253]
	v_pk_fma_f32 v[254:255], v[170:171], v[170:171], v[254:255]
	v_pk_fma_f32 v[252:253], v[172:173], v[172:173], v[252:253]
	v_pk_fma_f32 v[254:255], v[174:175], v[174:175], v[254:255]
	v_pk_add_f32 v[252:253], v[252:253], v[254:255]
	s_nop 0
	v_add_f32_e32 v183, v252, v253
	s_nop 1
	v_add_f32_dpp v183, v183, v183 quad_perm:[1,0,3,2] row_mask:0xf bank_mask:0xf bound_ctrl:1
	s_nop 1
	v_add_f32_dpp v183, v183, v183 quad_perm:[2,3,0,1] row_mask:0xf bank_mask:0xf bound_ctrl:1
	s_nop 1
	v_add_f32_dpp v183, v183, v183 row_half_mirror row_mask:0xf bank_mask:0xf bound_ctrl:1
	s_nop 1
	v_add_f32_dpp v183, v183, v183 row_mirror row_mask:0xf bank_mask:0xf bound_ctrl:1
	s_nop 1
	v_readlane_b32 s98, v183, 0
	v_readlane_b32 s99, v183, 16
	v_readlane_b32 s100, v183, 32
	v_readlane_b32 s101, v183, 48
	s_nop 1
	v_mov_b32_e32 v183, s98
	v_add_f32_e32 v183, s99, v183
	v_add_f32_e32 v183, s100, v183
	v_add_f32_e32 v183, s101, v183
	v_fmamk_f32 v183, v183, 0x3a800000, v182
	v_cmp_gt_f32_e32 vcc, 0x800000, v183
	v_mul_f32_e32 v181, 0x4b800000, v183
	s_nop 1
	v_cndmask_b32_e32 v183, v183, v181, vcc
	v_rsq_f32_e32 v183, v183
	s_nop 0
	v_mul_f32_e32 v181, 0x45800000, v183
	v_cndmask_b32_e32 v184, v183, v181, vcc
	v_mov_b32_e32 v185, v184
	v_pk_mul_f32 v[160:161], v[160:161], v[184:185]
	v_pk_mul_f32 v[162:163], v[162:163], v[184:185]
	v_pk_mul_f32 v[164:165], v[164:165], v[184:185]
	v_pk_mul_f32 v[166:167], v[166:167], v[184:185]
	v_pk_mul_f32 v[168:169], v[168:169], v[184:185]
	v_pk_mul_f32 v[170:171], v[170:171], v[184:185]
	v_pk_mul_f32 v[172:173], v[172:173], v[184:185]
	v_pk_mul_f32 v[174:175], v[174:175], v[184:185]
	v_pk_fma_f32 v[144:145], v[160:161], v[128:129], v[144:145]
	v_pk_fma_f32 v[146:147], v[162:163], v[130:131], v[146:147]
	v_pk_fma_f32 v[148:149], v[164:165], v[132:133], v[148:149]
	v_pk_fma_f32 v[150:151], v[166:167], v[134:135], v[150:151]
	v_pk_fma_f32 v[152:153], v[168:169], v[136:137], v[152:153]
	v_pk_fma_f32 v[154:155], v[170:171], v[138:139], v[154:155]
	v_pk_fma_f32 v[156:157], v[172:173], v[140:141], v[156:157]
	v_pk_fma_f32 v[158:159], v[174:175], v[142:143], v[158:159]
	v_pk_mul_f32 v[252:253], v[144:145], v[144:145]
	v_pk_mul_f32 v[254:255], v[146:147], v[146:147]
	v_pk_fma_f32 v[252:253], v[148:149], v[148:149], v[252:253]
	v_pk_fma_f32 v[254:255], v[150:151], v[150:151], v[254:255]
	v_pk_fma_f32 v[252:253], v[152:153], v[152:153], v[252:253]
	v_pk_fma_f32 v[254:255], v[154:155], v[154:155], v[254:255]
	v_pk_fma_f32 v[252:253], v[156:157], v[156:157], v[252:253]
	v_pk_fma_f32 v[254:255], v[158:159], v[158:159], v[254:255]
	v_pk_add_f32 v[252:253], v[252:253], v[254:255]
	s_nop 0
	v_add_f32_e32 v183, v252, v253
	s_nop 1
	v_add_f32_dpp v183, v183, v183 quad_perm:[1,0,3,2] row_mask:0xf bank_mask:0xf bound_ctrl:1
	s_nop 1
	v_add_f32_dpp v183, v183, v183 quad_perm:[2,3,0,1] row_mask:0xf bank_mask:0xf bound_ctrl:1
	s_nop 1
	v_add_f32_dpp v183, v183, v183 row_half_mirror row_mask:0xf bank_mask:0xf bound_ctrl:1
	s_nop 1
	v_add_f32_dpp v183, v183, v183 row_mirror row_mask:0xf bank_mask:0xf bound_ctrl:1
	s_nop 1
	v_readlane_b32 s98, v183, 0
	v_readlane_b32 s99, v183, 16
	v_readlane_b32 s100, v183, 32
	v_readlane_b32 s101, v183, 48
	s_nop 1
	v_mov_b32_e32 v183, s98
	v_add_f32_e32 v183, s99, v183
	v_add_f32_e32 v183, s100, v183
	v_add_f32_e32 v183, s101, v183
	v_fmamk_f32 v183, v183, 0x3a800000, v182
	v_cmp_gt_f32_e32 vcc, 0x800000, v183
	v_mul_f32_e32 v181, 0x4b800000, v183
	s_nop 1
	v_cndmask_b32_e32 v183, v183, v181, vcc
	v_rsq_f32_e32 v183, v183
	s_nop 0
	v_mul_f32_e32 v181, 0x45800000, v183
	v_cndmask_b32_e32 v184, v183, v181, vcc
	v_mov_b32_e32 v185, v184
	v_pk_mul_f32 v[144:145], v[144:145], v[184:185]
	v_pk_mul_f32 v[146:147], v[146:147], v[184:185]
	v_pk_mul_f32 v[148:149], v[148:149], v[184:185]
	v_pk_mul_f32 v[150:151], v[150:151], v[184:185]
	v_pk_mul_f32 v[152:153], v[152:153], v[184:185]
	v_pk_mul_f32 v[154:155], v[154:155], v[184:185]
	v_pk_mul_f32 v[156:157], v[156:157], v[184:185]
	v_pk_mul_f32 v[158:159], v[158:159], v[184:185]
	v_pk_mul_f32 v[144:145], v[144:145], v[236:237]
	v_pk_mul_f32 v[146:147], v[146:147], v[238:239]
	v_pk_mul_f32 v[148:149], v[148:149], v[240:241]
	v_pk_mul_f32 v[150:151], v[150:151], v[242:243]
	v_pk_mul_f32 v[152:153], v[152:153], v[244:245]
	v_pk_mul_f32 v[154:155], v[154:155], v[246:247]
	v_pk_mul_f32 v[156:157], v[156:157], v[248:249]
	v_pk_mul_f32 v[158:159], v[158:159], v[250:251]
	v_add_u32_e32 v181, 0x800000, v178
	global_store_dwordx4 v181, v[144:147], s[76:77]
	global_store_dwordx4 v181, v[148:151], s[76:77] offset:16
	global_store_dwordx4 v181, v[152:155], s[76:77] offset:2048
	global_store_dwordx4 v181, v[156:159], s[76:77] offset:2064
	s_nop 1
	s_waitcnt vmcnt(8)
	v_lshlrev_b32_e32 v144, 16, v32
	v_and_b32_e32 v145, 0xffff0000, v32
	v_lshlrev_b32_e32 v146, 16, v33
	v_and_b32_e32 v147, 0xffff0000, v33
	v_lshlrev_b32_e32 v148, 16, v34
	v_and_b32_e32 v149, 0xffff0000, v34
	v_lshlrev_b32_e32 v150, 16, v35
	v_and_b32_e32 v151, 0xffff0000, v35
	v_lshlrev_b32_e32 v152, 16, v36
	v_and_b32_e32 v153, 0xffff0000, v36
	v_lshlrev_b32_e32 v154, 16, v37
	v_and_b32_e32 v155, 0xffff0000, v37
	v_lshlrev_b32_e32 v156, 16, v38
	v_and_b32_e32 v157, 0xffff0000, v38
	v_lshlrev_b32_e32 v158, 16, v39
	v_and_b32_e32 v159, 0xffff0000, v39
	v_lshlrev_b32_e32 v160, 16, v40
	v_and_b32_e32 v161, 0xffff0000, v40
	v_lshlrev_b32_e32 v162, 16, v41
	v_and_b32_e32 v163, 0xffff0000, v41
	v_lshlrev_b32_e32 v164, 16, v42
	v_and_b32_e32 v165, 0xffff0000, v42
	v_lshlrev_b32_e32 v166, 16, v43
	v_and_b32_e32 v167, 0xffff0000, v43
	v_lshlrev_b32_e32 v168, 16, v44
	v_and_b32_e32 v169, 0xffff0000, v44
	v_lshlrev_b32_e32 v170, 16, v45
	v_and_b32_e32 v171, 0xffff0000, v45
	v_lshlrev_b32_e32 v172, 16, v46
	v_and_b32_e32 v173, 0xffff0000, v46
	v_lshlrev_b32_e32 v174, 16, v47
	v_and_b32_e32 v175, 0xffff0000, v47
	v_pk_mul_f32 v[252:253], v[160:161], v[160:161]
	v_pk_mul_f32 v[254:255], v[162:163], v[162:163]
	v_pk_fma_f32 v[252:253], v[164:165], v[164:165], v[252:253]
	v_pk_fma_f32 v[254:255], v[166:167], v[166:167], v[254:255]
	v_pk_fma_f32 v[252:253], v[168:169], v[168:169], v[252:253]
	v_pk_fma_f32 v[254:255], v[170:171], v[170:171], v[254:255]
	v_pk_fma_f32 v[252:253], v[172:173], v[172:173], v[252:253]
	v_pk_fma_f32 v[254:255], v[174:175], v[174:175], v[254:255]
	v_pk_add_f32 v[252:253], v[252:253], v[254:255]
	s_nop 0
	v_add_f32_e32 v183, v252, v253
	s_nop 1
	v_add_f32_dpp v183, v183, v183 quad_perm:[1,0,3,2] row_mask:0xf bank_mask:0xf bound_ctrl:1
	s_nop 1
	v_add_f32_dpp v183, v183, v183 quad_perm:[2,3,0,1] row_mask:0xf bank_mask:0xf bound_ctrl:1
	s_nop 1
	v_add_f32_dpp v183, v183, v183 row_half_mirror row_mask:0xf bank_mask:0xf bound_ctrl:1
	s_nop 1
	v_add_f32_dpp v183, v183, v183 row_mirror row_mask:0xf bank_mask:0xf bound_ctrl:1
	s_nop 1
	v_readlane_b32 s98, v183, 0
	v_readlane_b32 s99, v183, 16
	v_readlane_b32 s100, v183, 32
	v_readlane_b32 s101, v183, 48
	s_nop 1
	v_mov_b32_e32 v183, s98
	v_add_f32_e32 v183, s99, v183
	v_add_f32_e32 v183, s100, v183
	v_add_f32_e32 v183, s101, v183
	v_fmamk_f32 v183, v183, 0x3a800000, v182
	v_cmp_gt_f32_e32 vcc, 0x800000, v183
	v_mul_f32_e32 v181, 0x4b800000, v183
	s_nop 1
	v_cndmask_b32_e32 v183, v183, v181, vcc
	v_rsq_f32_e32 v183, v183
	s_nop 0
	v_mul_f32_e32 v181, 0x45800000, v183
	v_cndmask_b32_e32 v184, v183, v181, vcc
	v_mov_b32_e32 v185, v184
	v_pk_mul_f32 v[160:161], v[160:161], v[184:185]
	v_pk_mul_f32 v[162:163], v[162:163], v[184:185]
	v_pk_mul_f32 v[164:165], v[164:165], v[184:185]
	v_pk_mul_f32 v[166:167], v[166:167], v[184:185]
	v_pk_mul_f32 v[168:169], v[168:169], v[184:185]
	v_pk_mul_f32 v[170:171], v[170:171], v[184:185]
	v_pk_mul_f32 v[172:173], v[172:173], v[184:185]
	v_pk_mul_f32 v[174:175], v[174:175], v[184:185]
	v_pk_fma_f32 v[144:145], v[160:161], v[128:129], v[144:145]
	v_pk_fma_f32 v[146:147], v[162:163], v[130:131], v[146:147]
	v_pk_fma_f32 v[148:149], v[164:165], v[132:133], v[148:149]
	v_pk_fma_f32 v[150:151], v[166:167], v[134:135], v[150:151]
	v_pk_fma_f32 v[152:153], v[168:169], v[136:137], v[152:153]
	v_pk_fma_f32 v[154:155], v[170:171], v[138:139], v[154:155]
	v_pk_fma_f32 v[156:157], v[172:173], v[140:141], v[156:157]
	v_pk_fma_f32 v[158:159], v[174:175], v[142:143], v[158:159]
	v_pk_mul_f32 v[252:253], v[144:145], v[144:145]
	v_pk_mul_f32 v[254:255], v[146:147], v[146:147]
	v_pk_fma_f32 v[252:253], v[148:149], v[148:149], v[252:253]
	v_pk_fma_f32 v[254:255], v[150:151], v[150:151], v[254:255]
	v_pk_fma_f32 v[252:253], v[152:153], v[152:153], v[252:253]
	v_pk_fma_f32 v[254:255], v[154:155], v[154:155], v[254:255]
	v_pk_fma_f32 v[252:253], v[156:157], v[156:157], v[252:253]
	v_pk_fma_f32 v[254:255], v[158:159], v[158:159], v[254:255]
	v_pk_add_f32 v[252:253], v[252:253], v[254:255]
	s_nop 0
	v_add_f32_e32 v183, v252, v253
	s_nop 1
	v_add_f32_dpp v183, v183, v183 quad_perm:[1,0,3,2] row_mask:0xf bank_mask:0xf bound_ctrl:1
	s_nop 1
	v_add_f32_dpp v183, v183, v183 quad_perm:[2,3,0,1] row_mask:0xf bank_mask:0xf bound_ctrl:1
	s_nop 1
	v_add_f32_dpp v183, v183, v183 row_half_mirror row_mask:0xf bank_mask:0xf bound_ctrl:1
	s_nop 1
	v_add_f32_dpp v183, v183, v183 row_mirror row_mask:0xf bank_mask:0xf bound_ctrl:1
	s_nop 1
	v_readlane_b32 s98, v183, 0
	v_readlane_b32 s99, v183, 16
	v_readlane_b32 s100, v183, 32
	v_readlane_b32 s101, v183, 48
	s_nop 1
	v_mov_b32_e32 v183, s98
	v_add_f32_e32 v183, s99, v183
	v_add_f32_e32 v183, s100, v183
	v_add_f32_e32 v183, s101, v183
	v_fmamk_f32 v183, v183, 0x3a800000, v182
	v_cmp_gt_f32_e32 vcc, 0x800000, v183
	v_mul_f32_e32 v181, 0x4b800000, v183
	s_nop 1
	v_cndmask_b32_e32 v183, v183, v181, vcc
	v_rsq_f32_e32 v183, v183
	s_nop 0
	v_mul_f32_e32 v181, 0x45800000, v183
	v_cndmask_b32_e32 v184, v183, v181, vcc
	v_mov_b32_e32 v185, v184
	v_pk_mul_f32 v[144:145], v[144:145], v[184:185]
	v_pk_mul_f32 v[146:147], v[146:147], v[184:185]
	v_pk_mul_f32 v[148:149], v[148:149], v[184:185]
	v_pk_mul_f32 v[150:151], v[150:151], v[184:185]
	v_pk_mul_f32 v[152:153], v[152:153], v[184:185]
	v_pk_mul_f32 v[154:155], v[154:155], v[184:185]
	v_pk_mul_f32 v[156:157], v[156:157], v[184:185]
	v_pk_mul_f32 v[158:159], v[158:159], v[184:185]
	v_pk_mul_f32 v[144:145], v[144:145], v[236:237]
	v_pk_mul_f32 v[146:147], v[146:147], v[238:239]
	v_pk_mul_f32 v[148:149], v[148:149], v[240:241]
	v_pk_mul_f32 v[150:151], v[150:151], v[242:243]
	v_pk_mul_f32 v[152:153], v[152:153], v[244:245]
	v_pk_mul_f32 v[154:155], v[154:155], v[246:247]
	v_pk_mul_f32 v[156:157], v[156:157], v[248:249]
	v_pk_mul_f32 v[158:159], v[158:159], v[250:251]
	v_add_u32_e32 v181, 0x1000000, v178
	global_store_dwordx4 v181, v[144:147], s[76:77]
	global_store_dwordx4 v181, v[148:151], s[76:77] offset:16
	global_store_dwordx4 v181, v[152:155], s[76:77] offset:2048
	global_store_dwordx4 v181, v[156:159], s[76:77] offset:2064
	s_nop 1
	s_waitcnt vmcnt(4)
	v_lshlrev_b32_e32 v144, 16, v48
	v_and_b32_e32 v145, 0xffff0000, v48
	v_lshlrev_b32_e32 v146, 16, v49
	v_and_b32_e32 v147, 0xffff0000, v49
	v_lshlrev_b32_e32 v148, 16, v50
	v_and_b32_e32 v149, 0xffff0000, v50
	v_lshlrev_b32_e32 v150, 16, v51
	v_and_b32_e32 v151, 0xffff0000, v51
	v_lshlrev_b32_e32 v152, 16, v52
	v_and_b32_e32 v153, 0xffff0000, v52
	v_lshlrev_b32_e32 v154, 16, v53
	v_and_b32_e32 v155, 0xffff0000, v53
	v_lshlrev_b32_e32 v156, 16, v54
	v_and_b32_e32 v157, 0xffff0000, v54
	v_lshlrev_b32_e32 v158, 16, v55
	v_and_b32_e32 v159, 0xffff0000, v55
	v_lshlrev_b32_e32 v160, 16, v56
	v_and_b32_e32 v161, 0xffff0000, v56
	v_lshlrev_b32_e32 v162, 16, v57
	v_and_b32_e32 v163, 0xffff0000, v57
	v_lshlrev_b32_e32 v164, 16, v58
	v_and_b32_e32 v165, 0xffff0000, v58
	v_lshlrev_b32_e32 v166, 16, v59
	v_and_b32_e32 v167, 0xffff0000, v59
	v_lshlrev_b32_e32 v168, 16, v60
	v_and_b32_e32 v169, 0xffff0000, v60
	v_lshlrev_b32_e32 v170, 16, v61
	v_and_b32_e32 v171, 0xffff0000, v61
	v_lshlrev_b32_e32 v172, 16, v62
	v_and_b32_e32 v173, 0xffff0000, v62
	v_lshlrev_b32_e32 v174, 16, v63
	v_and_b32_e32 v175, 0xffff0000, v63
	v_pk_mul_f32 v[252:253], v[160:161], v[160:161]
	v_pk_mul_f32 v[254:255], v[162:163], v[162:163]
	v_pk_fma_f32 v[252:253], v[164:165], v[164:165], v[252:253]
	v_pk_fma_f32 v[254:255], v[166:167], v[166:167], v[254:255]
	v_pk_fma_f32 v[252:253], v[168:169], v[168:169], v[252:253]
	v_pk_fma_f32 v[254:255], v[170:171], v[170:171], v[254:255]
	v_pk_fma_f32 v[252:253], v[172:173], v[172:173], v[252:253]
	v_pk_fma_f32 v[254:255], v[174:175], v[174:175], v[254:255]
	v_pk_add_f32 v[252:253], v[252:253], v[254:255]
	s_nop 0
	v_add_f32_e32 v183, v252, v253
	s_nop 1
	v_add_f32_dpp v183, v183, v183 quad_perm:[1,0,3,2] row_mask:0xf bank_mask:0xf bound_ctrl:1
	s_nop 1
	v_add_f32_dpp v183, v183, v183 quad_perm:[2,3,0,1] row_mask:0xf bank_mask:0xf bound_ctrl:1
	s_nop 1
	v_add_f32_dpp v183, v183, v183 row_half_mirror row_mask:0xf bank_mask:0xf bound_ctrl:1
	s_nop 1
	v_add_f32_dpp v183, v183, v183 row_mirror row_mask:0xf bank_mask:0xf bound_ctrl:1
	s_nop 1
	v_readlane_b32 s98, v183, 0
	v_readlane_b32 s99, v183, 16
	v_readlane_b32 s100, v183, 32
	v_readlane_b32 s101, v183, 48
	s_nop 1
	v_mov_b32_e32 v183, s98
	v_add_f32_e32 v183, s99, v183
	v_add_f32_e32 v183, s100, v183
	v_add_f32_e32 v183, s101, v183
	v_fmamk_f32 v183, v183, 0x3a800000, v182
	v_cmp_gt_f32_e32 vcc, 0x800000, v183
	v_mul_f32_e32 v181, 0x4b800000, v183
	s_nop 1
	v_cndmask_b32_e32 v183, v183, v181, vcc
	v_rsq_f32_e32 v183, v183
	s_nop 0
	v_mul_f32_e32 v181, 0x45800000, v183
	v_cndmask_b32_e32 v184, v183, v181, vcc
	v_mov_b32_e32 v185, v184
	v_pk_mul_f32 v[160:161], v[160:161], v[184:185]
	v_pk_mul_f32 v[162:163], v[162:163], v[184:185]
	v_pk_mul_f32 v[164:165], v[164:165], v[184:185]
	v_pk_mul_f32 v[166:167], v[166:167], v[184:185]
	v_pk_mul_f32 v[168:169], v[168:169], v[184:185]
	v_pk_mul_f32 v[170:171], v[170:171], v[184:185]
	v_pk_mul_f32 v[172:173], v[172:173], v[184:185]
	v_pk_mul_f32 v[174:175], v[174:175], v[184:185]
	v_pk_fma_f32 v[144:145], v[160:161], v[128:129], v[144:145]
	v_pk_fma_f32 v[146:147], v[162:163], v[130:131], v[146:147]
	v_pk_fma_f32 v[148:149], v[164:165], v[132:133], v[148:149]
	v_pk_fma_f32 v[150:151], v[166:167], v[134:135], v[150:151]
	v_pk_fma_f32 v[152:153], v[168:169], v[136:137], v[152:153]
	v_pk_fma_f32 v[154:155], v[170:171], v[138:139], v[154:155]
	v_pk_fma_f32 v[156:157], v[172:173], v[140:141], v[156:157]
	v_pk_fma_f32 v[158:159], v[174:175], v[142:143], v[158:159]
	v_pk_mul_f32 v[252:253], v[144:145], v[144:145]
	v_pk_mul_f32 v[254:255], v[146:147], v[146:147]
	v_pk_fma_f32 v[252:253], v[148:149], v[148:149], v[252:253]
	v_pk_fma_f32 v[254:255], v[150:151], v[150:151], v[254:255]
	v_pk_fma_f32 v[252:253], v[152:153], v[152:153], v[252:253]
	v_pk_fma_f32 v[254:255], v[154:155], v[154:155], v[254:255]
	v_pk_fma_f32 v[252:253], v[156:157], v[156:157], v[252:253]
	v_pk_fma_f32 v[254:255], v[158:159], v[158:159], v[254:255]
	v_pk_add_f32 v[252:253], v[252:253], v[254:255]
	s_nop 0
	v_add_f32_e32 v183, v252, v253
	s_nop 1
	v_add_f32_dpp v183, v183, v183 quad_perm:[1,0,3,2] row_mask:0xf bank_mask:0xf bound_ctrl:1
	s_nop 1
	v_add_f32_dpp v183, v183, v183 quad_perm:[2,3,0,1] row_mask:0xf bank_mask:0xf bound_ctrl:1
	s_nop 1
	v_add_f32_dpp v183, v183, v183 row_half_mirror row_mask:0xf bank_mask:0xf bound_ctrl:1
	s_nop 1
	v_add_f32_dpp v183, v183, v183 row_mirror row_mask:0xf bank_mask:0xf bound_ctrl:1
	s_nop 1
	v_readlane_b32 s98, v183, 0
	v_readlane_b32 s99, v183, 16
	v_readlane_b32 s100, v183, 32
	v_readlane_b32 s101, v183, 48
	s_nop 1
	v_mov_b32_e32 v183, s98
	v_add_f32_e32 v183, s99, v183
	v_add_f32_e32 v183, s100, v183
	v_add_f32_e32 v183, s101, v183
	v_fmamk_f32 v183, v183, 0x3a800000, v182
	v_cmp_gt_f32_e32 vcc, 0x800000, v183
	v_mul_f32_e32 v181, 0x4b800000, v183
	s_nop 1
	v_cndmask_b32_e32 v183, v183, v181, vcc
	v_rsq_f32_e32 v183, v183
	s_nop 0
	v_mul_f32_e32 v181, 0x45800000, v183
	v_cndmask_b32_e32 v184, v183, v181, vcc
	v_mov_b32_e32 v185, v184
	v_pk_mul_f32 v[144:145], v[144:145], v[184:185]
	v_pk_mul_f32 v[146:147], v[146:147], v[184:185]
	v_pk_mul_f32 v[148:149], v[148:149], v[184:185]
	v_pk_mul_f32 v[150:151], v[150:151], v[184:185]
	v_pk_mul_f32 v[152:153], v[152:153], v[184:185]
	v_pk_mul_f32 v[154:155], v[154:155], v[184:185]
	v_pk_mul_f32 v[156:157], v[156:157], v[184:185]
	v_pk_mul_f32 v[158:159], v[158:159], v[184:185]
	v_pk_mul_f32 v[144:145], v[144:145], v[236:237]
	v_pk_mul_f32 v[146:147], v[146:147], v[238:239]
	v_pk_mul_f32 v[148:149], v[148:149], v[240:241]
	v_pk_mul_f32 v[150:151], v[150:151], v[242:243]
	v_pk_mul_f32 v[152:153], v[152:153], v[244:245]
	v_pk_mul_f32 v[154:155], v[154:155], v[246:247]
	v_pk_mul_f32 v[156:157], v[156:157], v[248:249]
	v_pk_mul_f32 v[158:159], v[158:159], v[250:251]
	v_add_u32_e32 v181, 0x1800000, v178
	global_store_dwordx4 v181, v[144:147], s[76:77]
	global_store_dwordx4 v181, v[148:151], s[76:77] offset:16
	global_store_dwordx4 v181, v[152:155], s[76:77] offset:2048
	global_store_dwordx4 v181, v[156:159], s[76:77] offset:2064
	s_nop 1
	s_waitcnt vmcnt(0)
	v_lshlrev_b32_e32 v144, 16, v64
	v_and_b32_e32 v145, 0xffff0000, v64
	v_lshlrev_b32_e32 v146, 16, v65
	v_and_b32_e32 v147, 0xffff0000, v65
	v_lshlrev_b32_e32 v148, 16, v66
	v_and_b32_e32 v149, 0xffff0000, v66
	v_lshlrev_b32_e32 v150, 16, v67
	v_and_b32_e32 v151, 0xffff0000, v67
	v_lshlrev_b32_e32 v152, 16, v68
	v_and_b32_e32 v153, 0xffff0000, v68
	v_lshlrev_b32_e32 v154, 16, v69
	v_and_b32_e32 v155, 0xffff0000, v69
	v_lshlrev_b32_e32 v156, 16, v70
	v_and_b32_e32 v157, 0xffff0000, v70
	v_lshlrev_b32_e32 v158, 16, v71
	v_and_b32_e32 v159, 0xffff0000, v71
	v_lshlrev_b32_e32 v160, 16, v72
	v_and_b32_e32 v161, 0xffff0000, v72
	v_lshlrev_b32_e32 v162, 16, v73
	v_and_b32_e32 v163, 0xffff0000, v73
	v_lshlrev_b32_e32 v164, 16, v74
	v_and_b32_e32 v165, 0xffff0000, v74
	v_lshlrev_b32_e32 v166, 16, v75
	v_and_b32_e32 v167, 0xffff0000, v75
	v_lshlrev_b32_e32 v168, 16, v76
	v_and_b32_e32 v169, 0xffff0000, v76
	v_lshlrev_b32_e32 v170, 16, v77
	v_and_b32_e32 v171, 0xffff0000, v77
	v_lshlrev_b32_e32 v172, 16, v78
	v_and_b32_e32 v173, 0xffff0000, v78
	v_lshlrev_b32_e32 v174, 16, v79
	v_and_b32_e32 v175, 0xffff0000, v79
	v_pk_mul_f32 v[252:253], v[160:161], v[160:161]
	v_pk_mul_f32 v[254:255], v[162:163], v[162:163]
	v_pk_fma_f32 v[252:253], v[164:165], v[164:165], v[252:253]
	v_pk_fma_f32 v[254:255], v[166:167], v[166:167], v[254:255]
	v_pk_fma_f32 v[252:253], v[168:169], v[168:169], v[252:253]
	v_pk_fma_f32 v[254:255], v[170:171], v[170:171], v[254:255]
	v_pk_fma_f32 v[252:253], v[172:173], v[172:173], v[252:253]
	v_pk_fma_f32 v[254:255], v[174:175], v[174:175], v[254:255]
	v_pk_add_f32 v[252:253], v[252:253], v[254:255]
	s_nop 0
	v_add_f32_e32 v183, v252, v253
	s_nop 1
	v_add_f32_dpp v183, v183, v183 quad_perm:[1,0,3,2] row_mask:0xf bank_mask:0xf bound_ctrl:1
	s_nop 1
	v_add_f32_dpp v183, v183, v183 quad_perm:[2,3,0,1] row_mask:0xf bank_mask:0xf bound_ctrl:1
	s_nop 1
	v_add_f32_dpp v183, v183, v183 row_half_mirror row_mask:0xf bank_mask:0xf bound_ctrl:1
	s_nop 1
	v_add_f32_dpp v183, v183, v183 row_mirror row_mask:0xf bank_mask:0xf bound_ctrl:1
	s_nop 1
	v_readlane_b32 s98, v183, 0
	v_readlane_b32 s99, v183, 16
	v_readlane_b32 s100, v183, 32
	v_readlane_b32 s101, v183, 48
	s_nop 1
	v_mov_b32_e32 v183, s98
	v_add_f32_e32 v183, s99, v183
	v_add_f32_e32 v183, s100, v183
	v_add_f32_e32 v183, s101, v183
	v_fmamk_f32 v183, v183, 0x3a800000, v182
	v_cmp_gt_f32_e32 vcc, 0x800000, v183
	v_mul_f32_e32 v181, 0x4b800000, v183
	s_nop 1
	v_cndmask_b32_e32 v183, v183, v181, vcc
	v_rsq_f32_e32 v183, v183
	s_nop 0
	v_mul_f32_e32 v181, 0x45800000, v183
	v_cndmask_b32_e32 v184, v183, v181, vcc
	v_mov_b32_e32 v185, v184
	v_pk_mul_f32 v[160:161], v[160:161], v[184:185]
	v_pk_mul_f32 v[162:163], v[162:163], v[184:185]
	v_pk_mul_f32 v[164:165], v[164:165], v[184:185]
	v_pk_mul_f32 v[166:167], v[166:167], v[184:185]
	v_pk_mul_f32 v[168:169], v[168:169], v[184:185]
	v_pk_mul_f32 v[170:171], v[170:171], v[184:185]
	v_pk_mul_f32 v[172:173], v[172:173], v[184:185]
	v_pk_mul_f32 v[174:175], v[174:175], v[184:185]
	v_pk_fma_f32 v[144:145], v[160:161], v[128:129], v[144:145]
	v_pk_fma_f32 v[146:147], v[162:163], v[130:131], v[146:147]
	v_pk_fma_f32 v[148:149], v[164:165], v[132:133], v[148:149]
	v_pk_fma_f32 v[150:151], v[166:167], v[134:135], v[150:151]
	v_pk_fma_f32 v[152:153], v[168:169], v[136:137], v[152:153]
	v_pk_fma_f32 v[154:155], v[170:171], v[138:139], v[154:155]
	v_pk_fma_f32 v[156:157], v[172:173], v[140:141], v[156:157]
	v_pk_fma_f32 v[158:159], v[174:175], v[142:143], v[158:159]
	v_pk_mul_f32 v[252:253], v[144:145], v[144:145]
	v_pk_mul_f32 v[254:255], v[146:147], v[146:147]
	v_pk_fma_f32 v[252:253], v[148:149], v[148:149], v[252:253]
	v_pk_fma_f32 v[254:255], v[150:151], v[150:151], v[254:255]
	v_pk_fma_f32 v[252:253], v[152:153], v[152:153], v[252:253]
	v_pk_fma_f32 v[254:255], v[154:155], v[154:155], v[254:255]
	v_pk_fma_f32 v[252:253], v[156:157], v[156:157], v[252:253]
	v_pk_fma_f32 v[254:255], v[158:159], v[158:159], v[254:255]
	v_pk_add_f32 v[252:253], v[252:253], v[254:255]
	s_nop 0
	v_add_f32_e32 v183, v252, v253
	s_nop 1
	v_add_f32_dpp v183, v183, v183 quad_perm:[1,0,3,2] row_mask:0xf bank_mask:0xf bound_ctrl:1
	s_nop 1
	v_add_f32_dpp v183, v183, v183 quad_perm:[2,3,0,1] row_mask:0xf bank_mask:0xf bound_ctrl:1
	s_nop 1
	v_add_f32_dpp v183, v183, v183 row_half_mirror row_mask:0xf bank_mask:0xf bound_ctrl:1
	s_nop 1
	v_add_f32_dpp v183, v183, v183 row_mirror row_mask:0xf bank_mask:0xf bound_ctrl:1
	s_nop 1
	v_readlane_b32 s98, v183, 0
	v_readlane_b32 s99, v183, 16
	v_readlane_b32 s100, v183, 32
	v_readlane_b32 s101, v183, 48
	s_nop 1
	v_mov_b32_e32 v183, s98
	v_add_f32_e32 v183, s99, v183
	v_add_f32_e32 v183, s100, v183
	v_add_f32_e32 v183, s101, v183
	v_fmamk_f32 v183, v183, 0x3a800000, v182
	v_cmp_gt_f32_e32 vcc, 0x800000, v183
	v_mul_f32_e32 v181, 0x4b800000, v183
	s_nop 1
	v_cndmask_b32_e32 v183, v183, v181, vcc
	v_rsq_f32_e32 v183, v183
	s_nop 0
	v_mul_f32_e32 v181, 0x45800000, v183
	v_cndmask_b32_e32 v184, v183, v181, vcc
	v_mov_b32_e32 v185, v184
	v_pk_mul_f32 v[144:145], v[144:145], v[184:185]
	v_pk_mul_f32 v[146:147], v[146:147], v[184:185]
	v_pk_mul_f32 v[148:149], v[148:149], v[184:185]
	v_pk_mul_f32 v[150:151], v[150:151], v[184:185]
	v_pk_mul_f32 v[152:153], v[152:153], v[184:185]
	v_pk_mul_f32 v[154:155], v[154:155], v[184:185]
	v_pk_mul_f32 v[156:157], v[156:157], v[184:185]
	v_pk_mul_f32 v[158:159], v[158:159], v[184:185]
	v_pk_mul_f32 v[144:145], v[144:145], v[236:237]
	v_pk_mul_f32 v[146:147], v[146:147], v[238:239]
	v_pk_mul_f32 v[148:149], v[148:149], v[240:241]
	v_pk_mul_f32 v[150:151], v[150:151], v[242:243]
	v_pk_mul_f32 v[152:153], v[152:153], v[244:245]
	v_pk_mul_f32 v[154:155], v[154:155], v[246:247]
	v_pk_mul_f32 v[156:157], v[156:157], v[248:249]
	v_pk_mul_f32 v[158:159], v[158:159], v[250:251]
	v_add_u32_e32 v181, 0x2000000, v178
	global_store_dwordx4 v181, v[144:147], s[76:77]
	global_store_dwordx4 v181, v[148:151], s[76:77] offset:16
	global_store_dwordx4 v181, v[152:155], s[76:77] offset:2048
	global_store_dwordx4 v181, v[156:159], s[76:77] offset:2064
	s_nop 1
	v_readfirstlane_b32 s98, v179
	s_nop 3
	s_and_b32 s99, s98, 3
	s_cmp_lg_u32 s99, 0
	s_cbranch_scc1 .Lmyxupd_done_7
	v_lshrrev_b32_e32 v179, 2, v179
	v_lshlrev_b32_e32 v177, 4, v176
	v_lshl_add_u32 v177, v179, 11, v177
	v_lshl_add_u32 v178, v179, 12, v180
	v_add_u32_e32 v181, 0x3800000, v177
	global_load_dwordx4 v[194:197], v181, s[78:79]
	global_load_dwordx4 v[198:201], v181, s[78:79] offset:1024
	v_lshl_add_u32 v183, v179, 12, v180
	v_add_u32_e32 v183, 0xbf00000, v183
	v_add_u32_e32 v181, 0x0, v183
	global_load_dwordx4 v[0:3], v181, s[78:79]
	global_load_dwordx4 v[4:7], v181, s[78:79] offset:16
	global_load_dwordx4 v[8:11], v181, s[78:79] offset:2048
	global_load_dwordx4 v[12:15], v181, s[78:79] offset:2064
	v_add_u32_e32 v181, 0x200000, v183
	global_load_dwordx4 v[16:19], v181, s[78:79]
	global_load_dwordx4 v[20:23], v181, s[78:79] offset:16
	global_load_dwordx4 v[24:27], v181, s[78:79] offset:2048
	global_load_dwordx4 v[28:31], v181, s[78:79] offset:2064
	v_add_u32_e32 v181, 0x400000, v183
	global_load_dwordx4 v[32:35], v181, s[78:79]
	global_load_dwordx4 v[36:39], v181, s[78:79] offset:16
	global_load_dwordx4 v[40:43], v181, s[78:79] offset:2048
	global_load_dwordx4 v[44:47], v181, s[78:79] offset:2064
	v_add_u32_e32 v181, 0x600000, v183
	global_load_dwordx4 v[48:51], v181, s[78:79]
	global_load_dwordx4 v[52:55], v181, s[78:79] offset:16
	global_load_dwordx4 v[56:59], v181, s[78:79] offset:2048
	global_load_dwordx4 v[60:63], v181, s[78:79] offset:2064
	v_add_u32_e32 v181, 0x800000, v183
	global_load_dwordx4 v[64:67], v181, s[78:79]
	global_load_dwordx4 v[68:71], v181, s[78:79] offset:16
	global_load_dwordx4 v[72:75], v181, s[78:79] offset:2048
	global_load_dwordx4 v[76:79], v181, s[78:79] offset:2064
	v_add_u32_e32 v181, 0xa00000, v183
	global_load_dwordx4 v[80:83], v181, s[78:79]
	global_load_dwordx4 v[84:87], v181, s[78:79] offset:16
	global_load_dwordx4 v[88:91], v181, s[78:79] offset:2048
	global_load_dwordx4 v[92:95], v181, s[78:79] offset:2064
	v_add_u32_e32 v181, 0xc00000, v183
	global_load_dwordx4 v[96:99], v181, s[78:79]
	global_load_dwordx4 v[100:103], v181, s[78:79] offset:16
	global_load_dwordx4 v[104:107], v181, s[78:79] offset:2048
	global_load_dwordx4 v[108:111], v181, s[78:79] offset:2064
	v_add_u32_e32 v181, 0xe00000, v183
	global_load_dwordx4 v[112:115], v181, s[78:79]
	global_load_dwordx4 v[116:119], v181, s[78:79] offset:16
	global_load_dwordx4 v[120:123], v181, s[78:79] offset:2048
	global_load_dwordx4 v[124:127], v181, s[78:79] offset:2064
	s_waitcnt vmcnt(28)
	v_pk_add_f32 v[160:161], v[0:1], 0 op_sel_hi:[1,0]
	v_pk_add_f32 v[162:163], v[2:3], 0 op_sel_hi:[1,0]
	v_pk_add_f32 v[164:165], v[4:5], 0 op_sel_hi:[1,0]
	v_pk_add_f32 v[166:167], v[6:7], 0 op_sel_hi:[1,0]
	v_pk_add_f32 v[168:169], v[8:9], 0 op_sel_hi:[1,0]
	v_pk_add_f32 v[170:171], v[10:11], 0 op_sel_hi:[1,0]
	v_pk_add_f32 v[172:173], v[12:13], 0 op_sel_hi:[1,0]
	v_pk_add_f32 v[174:175], v[14:15], 0 op_sel_hi:[1,0]
	s_waitcnt vmcnt(24)
	v_pk_add_f32 v[160:161], v[160:161], v[16:17]
	v_pk_add_f32 v[162:163], v[162:163], v[18:19]
	v_pk_add_f32 v[164:165], v[164:165], v[20:21]
	v_pk_add_f32 v[166:167], v[166:167], v[22:23]
	v_pk_add_f32 v[168:169], v[168:169], v[24:25]
	v_pk_add_f32 v[170:171], v[170:171], v[26:27]
	v_pk_add_f32 v[172:173], v[172:173], v[28:29]
	v_pk_add_f32 v[174:175], v[174:175], v[30:31]
	s_waitcnt vmcnt(20)
	v_pk_add_f32 v[160:161], v[160:161], v[32:33]
	v_pk_add_f32 v[162:163], v[162:163], v[34:35]
	v_pk_add_f32 v[164:165], v[164:165], v[36:37]
	v_pk_add_f32 v[166:167], v[166:167], v[38:39]
	v_pk_add_f32 v[168:169], v[168:169], v[40:41]
	v_pk_add_f32 v[170:171], v[170:171], v[42:43]
	v_pk_add_f32 v[172:173], v[172:173], v[44:45]
	v_pk_add_f32 v[174:175], v[174:175], v[46:47]
	v_add_u32_e32 v181, 0x1000000, v183
	global_load_dwordx4 v[0:3], v181, s[78:79]
	global_load_dwordx4 v[4:7], v181, s[78:79] offset:16
	global_load_dwordx4 v[8:11], v181, s[78:79] offset:2048
	global_load_dwordx4 v[12:15], v181, s[78:79] offset:2064
	v_add_u32_e32 v181, 0x1200000, v183
	global_load_dwordx4 v[16:19], v181, s[78:79]
	global_load_dwordx4 v[20:23], v181, s[78:79] offset:16
	global_load_dwordx4 v[24:27], v181, s[78:79] offset:2048
	global_load_dwordx4 v[28:31], v181, s[78:79] offset:2064
	v_add_u32_e32 v181, 0x1400000, v183
	global_load_dwordx4 v[32:35], v181, s[78:79]
	global_load_dwordx4 v[36:39], v181, s[78:79] offset:16
	global_load_dwordx4 v[40:43], v181, s[78:79] offset:2048
	global_load_dwordx4 v[44:47], v181, s[78:79] offset:2064
	s_waitcnt vmcnt(28)
	v_pk_add_f32 v[160:161], v[160:161], v[48:49]
	v_pk_add_f32 v[162:163], v[162:163], v[50:51]
	v_pk_add_f32 v[164:165], v[164:165], v[52:53]
	v_pk_add_f32 v[166:167], v[166:167], v[54:55]
	v_pk_add_f32 v[168:169], v[168:169], v[56:57]
	v_pk_add_f32 v[170:171], v[170:171], v[58:59]
	v_pk_add_f32 v[172:173], v[172:173], v[60:61]
	v_pk_add_f32 v[174:175], v[174:175], v[62:63]
	s_waitcnt vmcnt(24)
	v_pk_add_f32 v[160:161], v[160:161], v[64:65]
	v_pk_add_f32 v[162:163], v[162:163], v[66:67]
	v_pk_add_f32 v[164:165], v[164:165], v[68:69]
	v_pk_add_f32 v[166:167], v[166:167], v[70:71]
	v_pk_add_f32 v[168:169], v[168:169], v[72:73]
	v_pk_add_f32 v[170:171], v[170:171], v[74:75]
	v_pk_add_f32 v[172:173], v[172:173], v[76:77]
	v_pk_add_f32 v[174:175], v[174:175], v[78:79]
	s_waitcnt vmcnt(20)
	v_pk_add_f32 v[160:161], v[160:161], v[80:81]
	v_pk_add_f32 v[162:163], v[162:163], v[82:83]
	v_pk_add_f32 v[164:165], v[164:165], v[84:85]
	v_pk_add_f32 v[166:167], v[166:167], v[86:87]
	v_pk_add_f32 v[168:169], v[168:169], v[88:89]
	v_pk_add_f32 v[170:171], v[170:171], v[90:91]
	v_pk_add_f32 v[172:173], v[172:173], v[92:93]
	v_pk_add_f32 v[174:175], v[174:175], v[94:95]
	s_waitcnt vmcnt(16)
	v_pk_add_f32 v[160:161], v[160:161], v[96:97]
	v_pk_add_f32 v[162:163], v[162:163], v[98:99]
	v_pk_add_f32 v[164:165], v[164:165], v[100:101]
	v_pk_add_f32 v[166:167], v[166:167], v[102:103]
	v_pk_add_f32 v[168:169], v[168:169], v[104:105]
	v_pk_add_f32 v[170:171], v[170:171], v[106:107]
	v_pk_add_f32 v[172:173], v[172:173], v[108:109]
	v_pk_add_f32 v[174:175], v[174:175], v[110:111]
	s_waitcnt vmcnt(12)
	v_pk_add_f32 v[160:161], v[160:161], v[112:113]
	v_pk_add_f32 v[162:163], v[162:163], v[114:115]
	v_pk_add_f32 v[164:165], v[164:165], v[116:117]
	v_pk_add_f32 v[166:167], v[166:167], v[118:119]
	v_pk_add_f32 v[168:169], v[168:169], v[120:121]
	v_pk_add_f32 v[170:171], v[170:171], v[122:123]
	v_pk_add_f32 v[172:173], v[172:173], v[124:125]
	v_pk_add_f32 v[174:175], v[174:175], v[126:127]
	v_lshlrev_b32_e32 v144, 16, v194
	v_and_b32_e32 v145, 0xffff0000, v194
	v_lshlrev_b32_e32 v146, 16, v195
	v_and_b32_e32 v147, 0xffff0000, v195
	v_lshlrev_b32_e32 v148, 16, v196
	v_and_b32_e32 v149, 0xffff0000, v196
	v_lshlrev_b32_e32 v150, 16, v197
	v_and_b32_e32 v151, 0xffff0000, v197
	v_lshlrev_b32_e32 v152, 16, v198
	v_and_b32_e32 v153, 0xffff0000, v198
	v_lshlrev_b32_e32 v154, 16, v199
	v_and_b32_e32 v155, 0xffff0000, v199
	v_lshlrev_b32_e32 v156, 16, v200
	v_and_b32_e32 v157, 0xffff0000, v200
	v_lshlrev_b32_e32 v158, 16, v201
	v_and_b32_e32 v159, 0xffff0000, v201
	s_waitcnt vmcnt(8)
	v_pk_add_f32 v[160:161], v[160:161], v[0:1]
	v_pk_add_f32 v[162:163], v[162:163], v[2:3]
	v_pk_add_f32 v[164:165], v[164:165], v[4:5]
	v_pk_add_f32 v[166:167], v[166:167], v[6:7]
	v_pk_add_f32 v[168:169], v[168:169], v[8:9]
	v_pk_add_f32 v[170:171], v[170:171], v[10:11]
	v_pk_add_f32 v[172:173], v[172:173], v[12:13]
	v_pk_add_f32 v[174:175], v[174:175], v[14:15]
	s_waitcnt vmcnt(4)
	v_pk_add_f32 v[160:161], v[160:161], v[16:17]
	v_pk_add_f32 v[162:163], v[162:163], v[18:19]
	v_pk_add_f32 v[164:165], v[164:165], v[20:21]
	v_pk_add_f32 v[166:167], v[166:167], v[22:23]
	v_pk_add_f32 v[168:169], v[168:169], v[24:25]
	v_pk_add_f32 v[170:171], v[170:171], v[26:27]
	v_pk_add_f32 v[172:173], v[172:173], v[28:29]
	v_pk_add_f32 v[174:175], v[174:175], v[30:31]
	s_waitcnt vmcnt(0)
	v_pk_add_f32 v[160:161], v[160:161], v[32:33]
	v_pk_add_f32 v[162:163], v[162:163], v[34:35]
	v_pk_add_f32 v[164:165], v[164:165], v[36:37]
	v_pk_add_f32 v[166:167], v[166:167], v[38:39]
	v_pk_add_f32 v[168:169], v[168:169], v[40:41]
	v_pk_add_f32 v[170:171], v[170:171], v[42:43]
	v_pk_add_f32 v[172:173], v[172:173], v[44:45]
	v_pk_add_f32 v[174:175], v[174:175], v[46:47]
	v_pk_mul_f32 v[252:253], v[160:161], v[160:161]
	v_pk_mul_f32 v[254:255], v[162:163], v[162:163]
	v_pk_fma_f32 v[252:253], v[164:165], v[164:165], v[252:253]
	v_pk_fma_f32 v[254:255], v[166:167], v[166:167], v[254:255]
	v_pk_fma_f32 v[252:253], v[168:169], v[168:169], v[252:253]
	v_pk_fma_f32 v[254:255], v[170:171], v[170:171], v[254:255]
	v_pk_fma_f32 v[252:253], v[172:173], v[172:173], v[252:253]
	v_pk_fma_f32 v[254:255], v[174:175], v[174:175], v[254:255]
	v_pk_add_f32 v[252:253], v[252:253], v[254:255]
	s_nop 0
	v_add_f32_e32 v183, v252, v253
	s_nop 1
	v_add_f32_dpp v183, v183, v183 quad_perm:[1,0,3,2] row_mask:0xf bank_mask:0xf bound_ctrl:1
	s_nop 1
	v_add_f32_dpp v183, v183, v183 quad_perm:[2,3,0,1] row_mask:0xf bank_mask:0xf bound_ctrl:1
	s_nop 1
	v_add_f32_dpp v183, v183, v183 row_half_mirror row_mask:0xf bank_mask:0xf bound_ctrl:1
	s_nop 1
	v_add_f32_dpp v183, v183, v183 row_mirror row_mask:0xf bank_mask:0xf bound_ctrl:1
	s_nop 1
	v_readlane_b32 s98, v183, 0
	v_readlane_b32 s99, v183, 16
	v_readlane_b32 s100, v183, 32
	v_readlane_b32 s101, v183, 48
	s_nop 1
	v_mov_b32_e32 v183, s98
	v_add_f32_e32 v183, s99, v183
	v_add_f32_e32 v183, s100, v183
	v_add_f32_e32 v183, s101, v183
	v_fmamk_f32 v183, v183, 0x3a800000, v182
	v_cmp_gt_f32_e32 vcc, 0x800000, v183
	v_mul_f32_e32 v181, 0x4b800000, v183
	s_nop 1
	v_cndmask_b32_e32 v183, v183, v181, vcc
	v_rsq_f32_e32 v183, v183
	s_nop 0
	v_mul_f32_e32 v181, 0x45800000, v183
	v_cndmask_b32_e32 v184, v183, v181, vcc
	v_mov_b32_e32 v185, v184
	v_pk_mul_f32 v[160:161], v[160:161], v[184:185]
	v_pk_mul_f32 v[162:163], v[162:163], v[184:185]
	v_pk_mul_f32 v[164:165], v[164:165], v[184:185]
	v_pk_mul_f32 v[166:167], v[166:167], v[184:185]
	v_pk_mul_f32 v[168:169], v[168:169], v[184:185]
	v_pk_mul_f32 v[170:171], v[170:171], v[184:185]
	v_pk_mul_f32 v[172:173], v[172:173], v[184:185]
	v_pk_mul_f32 v[174:175], v[174:175], v[184:185]
	v_pk_fma_f32 v[144:145], v[160:161], v[128:129], v[144:145]
	v_pk_fma_f32 v[146:147], v[162:163], v[130:131], v[146:147]
	v_pk_fma_f32 v[148:149], v[164:165], v[132:133], v[148:149]
	v_pk_fma_f32 v[150:151], v[166:167], v[134:135], v[150:151]
	v_pk_fma_f32 v[152:153], v[168:169], v[136:137], v[152:153]
	v_pk_fma_f32 v[154:155], v[170:171], v[138:139], v[154:155]
	v_pk_fma_f32 v[156:157], v[172:173], v[140:141], v[156:157]
	v_pk_fma_f32 v[158:159], v[174:175], v[142:143], v[158:159]
	v_pk_mul_f32 v[252:253], v[144:145], v[144:145]
	v_pk_mul_f32 v[254:255], v[146:147], v[146:147]
	v_pk_fma_f32 v[252:253], v[148:149], v[148:149], v[252:253]
	v_pk_fma_f32 v[254:255], v[150:151], v[150:151], v[254:255]
	v_pk_fma_f32 v[252:253], v[152:153], v[152:153], v[252:253]
	v_pk_fma_f32 v[254:255], v[154:155], v[154:155], v[254:255]
	v_pk_fma_f32 v[252:253], v[156:157], v[156:157], v[252:253]
	v_pk_fma_f32 v[254:255], v[158:159], v[158:159], v[254:255]
	v_pk_add_f32 v[252:253], v[252:253], v[254:255]
	s_nop 0
	v_add_f32_e32 v183, v252, v253
	s_nop 1
	v_add_f32_dpp v183, v183, v183 quad_perm:[1,0,3,2] row_mask:0xf bank_mask:0xf bound_ctrl:1
	s_nop 1
	v_add_f32_dpp v183, v183, v183 quad_perm:[2,3,0,1] row_mask:0xf bank_mask:0xf bound_ctrl:1
	s_nop 1
	v_add_f32_dpp v183, v183, v183 row_half_mirror row_mask:0xf bank_mask:0xf bound_ctrl:1
	s_nop 1
	v_add_f32_dpp v183, v183, v183 row_mirror row_mask:0xf bank_mask:0xf bound_ctrl:1
	s_nop 1
	v_readlane_b32 s98, v183, 0
	v_readlane_b32 s99, v183, 16
	v_readlane_b32 s100, v183, 32
	v_readlane_b32 s101, v183, 48
	s_nop 1
	v_mov_b32_e32 v183, s98
	v_add_f32_e32 v183, s99, v183
	v_add_f32_e32 v183, s100, v183
	v_add_f32_e32 v183, s101, v183
	v_fmamk_f32 v183, v183, 0x3a800000, v182
	v_cmp_gt_f32_e32 vcc, 0x800000, v183
	v_mul_f32_e32 v181, 0x4b800000, v183
	s_nop 1
	v_cndmask_b32_e32 v183, v183, v181, vcc
	v_rsq_f32_e32 v183, v183
	s_nop 0
	v_mul_f32_e32 v181, 0x45800000, v183
	v_cndmask_b32_e32 v184, v183, v181, vcc
	v_mov_b32_e32 v185, v184
	v_pk_mul_f32 v[144:145], v[144:145], v[184:185]
	v_pk_mul_f32 v[146:147], v[146:147], v[184:185]
	v_pk_mul_f32 v[148:149], v[148:149], v[184:185]
	v_pk_mul_f32 v[150:151], v[150:151], v[184:185]
	v_pk_mul_f32 v[152:153], v[152:153], v[184:185]
	v_pk_mul_f32 v[154:155], v[154:155], v[184:185]
	v_pk_mul_f32 v[156:157], v[156:157], v[184:185]
	v_pk_mul_f32 v[158:159], v[158:159], v[184:185]
	v_pk_mul_f32 v[144:145], v[144:145], v[236:237]
	v_pk_mul_f32 v[146:147], v[146:147], v[238:239]
	v_pk_mul_f32 v[148:149], v[148:149], v[240:241]
	v_pk_mul_f32 v[150:151], v[150:151], v[242:243]
	v_pk_mul_f32 v[152:153], v[152:153], v[244:245]
	v_pk_mul_f32 v[154:155], v[154:155], v[246:247]
	v_pk_mul_f32 v[156:157], v[156:157], v[248:249]
	v_pk_mul_f32 v[158:159], v[158:159], v[250:251]
	v_add_u32_e32 v181, 0x4000000, v178
	global_store_dwordx4 v181, v[144:147], s[76:77]
	global_store_dwordx4 v181, v[148:151], s[76:77] offset:16
	global_store_dwordx4 v181, v[152:155], s[76:77] offset:2048
	global_store_dwordx4 v181, v[156:159], s[76:77] offset:2064
	s_nop 1
